# pipelined dil loop: exps split 4 before the global-load wait, 4 before the LDS wait, 2 between each QK MFMA
# speedup vs baseline: 1.0037x; 1.0037x over previous
; #define LAS __attribute__((address_space(3)))
; #define GAS __attribute__((address_space(1)))
; __device__ __forceinline__ void dil_unit(LAS unsigned char* lds, bf16_t* proj, int seq, int hd, int T0, int rho) {
;     int tid_ = threadIdx.x; asm volatile("" : "+v"(tid_));
;     const int tid = tid_, lane = tid & 63, r32 = lane & 31, hi = lane >> 5, wid = __builtin_amdgcn_readfirstlane(tid >> 6);
;     bf16_t* base = proj + (size_t)seq * SEQ * NIN;
;     LAS unsigned char* wbuf = lds + wid * 4096;
;     const LAS unsigned char* vp = wbuf + ((lane >> 4) & 1) * 32 + (lane & 3) * 8 + (4 * hi + ((lane & 15) >> 2)) * 64;
;     const int P0 = T0 + rho;
;     bf16x8 qr[4];
; #pragma unroll
;     for (int ks = 0; ks < 4; ++ks) qr[ks] = *(const GAS bf16x8*)(base + (size_t)(P0 + 16 * r32) * NIN + PC_LQ + hd * 64 + 16 * ks + 8 * hi);
;     f32x16 o0 = {}, o1 = {}; float l = 0.f;
;     const bool bound = (T0 < 1024) || (T0 >= 15360);
; __device__ __forceinline__ void attn_phase(unsigned char* ws, int l, LAS unsigned char* lds, int G) {
;     ...
;     for (int bu = vb; bu < 1152; bu += G) {
;         const int sh = bu >> 6, rem = bu & 63, T0 = (rem >> 1) * 512, rho = (rem & 1) * 8 + wid;
;         dil_unit(lds, proj, sh / 6, sh % 6, T0, rho);
.LBB0_554:
	s_lshr_b32 s82, s33, 8
	s_mul_i32 s82, s82, 13
	s_add_i32 s82, s82, s33
	s_ashr_i32 s2, s33, 6
	s_mul_hi_i32 s7, s2, 0x2aaaaaab
	s_lshl_b32 s3, s82, 8
	s_lshr_b32 s8, s7, 31
	s_and_b32 s6, s3, 0x3e00
	s_lshl_b32 s3, s82, 3
	s_add_i32 s7, s7, s8
	s_and_b32 s3, s3, 8
	s_mul_i32 s8, s7, 6
	s_add_i32 s3, s3, s64
	s_sub_i32 s8, s2, s8
	s_mul_hi_i32 s2, s7, 0x6000000
	s_mul_i32 s7, s7, 0x6000000
	v_mov_b32_e32 v2, v154
	s_add_u32 s56, s48, s7
	s_addc_u32 s57, s49, s2
	v_and_b32_e32 v105, 31, v2
	s_add_i32 s76, s3, s6
	v_lshl_add_u32 v3, v105, 4, s76
	v_mov_b64_e32 v[0:1], s[56:57]
	s_lshl_b32 s58, s8, 6
	v_bfe_u32 v106, v2, 5, 1
	v_mad_u64_u32 v[0:1], s[2:3], v3, s65, v[0:1]
	s_ashr_i32 s59, s58, 31
	v_lshl_add_u64 v[0:1], s[58:59], 1, v[0:1]
	v_lshlrev_b32_e32 v80, 4, v106
	v_lshl_add_u64 v[0:1], v[0:1], 0, v[80:81]
	global_load_dwordx4 v[48:51], v[0:1], off offset:1280
	global_load_dwordx4 v[52:55], v[0:1], off offset:1312
	global_load_dwordx4 v[56:59], v[0:1], off offset:1344
	global_load_dwordx4 v[60:63], v[0:1], off offset:1376
	v_readfirstlane_b32 s2, v2
	s_lshl_b32 s2, s2, 6
	s_and_b32 s2, s2, 0xfffff000
	v_lshlrev_b32_e32 v0, 1, v2
	v_lshlrev_b32_e32 v104, 3, v2
	v_lshlrev_b32_e32 v107, 2, v106
	v_lshrrev_b32_e32 v1, 2, v2
	v_and_b32_e32 v103, 63, v2
	v_and_b32_e32 v0, 32, v0
	v_and_b32_e32 v98, 24, v104
	v_and_or_b32 v1, v1, 3, v107
	s_add_i32 s77, s2, 0
	v_lshlrev_b32_e32 v108, 6, v1
	v_lshlrev_b32_e32 v1, 3, v106
	v_add3_u32 v109, s77, v0, v98
	s_addk_i32 s6, 0xc400
	v_lshrrev_b32_e32 v110, 2, v103
	v_lshlrev_b32_e32 v0, 4, v103
	s_mov_b64 s[2:3], -1
	s_cmp_gt_u32 s6, 0xffffc7ff
	v_lshlrev_b32_e32 v100, 1, v98
	s_mul_i32 s6, s8, 0x1c00
	v_lshlrev_b32_e32 v82, 1, v1
	v_or_b32_e32 v111, 16, v110
	v_add_u32_e32 v112, s77, v0
	s_cbranch_scc0 .LBB0_558
	s_movk_i32 s100, 0x1800
	s_add_i32 s101, s6, 0x15c00
	s_lshl_b32 s90, s58, 1
	s_add_u32 s82, s56, s90
	s_addc_u32 s83, s57, 0
	s_add_u32 s82, s82, 0x1200
	s_addc_u32 s83, s83, 0
	s_sub_i32 s90, s76, 64
	s_mul_i32 s90, s90, 0x1800
	s_add_u32 s84, s82, s90
	s_addc_u32 s85, s83, 0
	s_sub_i32 s90, s76, 256
	s_mul_i32 s90, s90, 0x1800
	s_add_u32 s86, s82, s90
	s_addc_u32 s87, s83, 0
	s_sub_i32 s90, s76, 1024
	s_mul_i32 s90, s90, 0x1800
	s_add_u32 s88, s82, s90
	s_addc_u32 s89, s83, 0
	v_lshlrev_b32_e32 v153, 1, v98
	v_mad_u32_u24 v80, v105, s100, v82
	v_mad_u32_u24 v100, v110, s100, v153
	v_add_u32_e32 v149, 0x18000, v100
	v_lshlrev_b32_e32 v83, 2, v105
	v_mad_u32_u24 v83, v83, s100, v82
	v_lshlrev_b32_e32 v101, 2, v110
	v_mad_u32_u24 v101, v101, s100, v153
	v_add_u32_e32 v150, 0x60000, v101
	v_lshlrev_b32_e32 v99, 4, v105
	v_mad_u32_u24 v99, v99, s100, v82
	v_lshlrev_b32_e32 v148, 4, v110
	v_mad_u32_u24 v148, v148, s100, v153
	v_add_u32_e32 v151, 0x180000, v148
	v_lshrrev_b32_e32 v249, 3, v103
	v_and_b32_e32 v250, 7, v103
	v_lshlrev_b32_e32 v250, 4, v250
	v_add_u32_e32 v235, 0, v249
	v_mad_u32_u24 v235, v235, s100, v250
	v_add_u32_e32 v236, 8, v249
	v_mad_u32_u24 v236, v236, s100, v250
	v_add_u32_e32 v237, 16, v249
	v_mad_u32_u24 v237, v237, s100, v250
	v_add_u32_e32 v238, 24, v249
	v_mad_u32_u24 v238, v238, s100, v250
	v_add_u32_e32 v239, 0, v249
	v_lshlrev_b32_e32 v239, 2, v239
	v_mad_u32_u24 v239, v239, s100, v250
	v_add_u32_e32 v240, 8, v249
	v_lshlrev_b32_e32 v240, 2, v240
	v_mad_u32_u24 v240, v240, s100, v250
	v_add_u32_e32 v241, 16, v249
	v_lshlrev_b32_e32 v241, 2, v241
	v_mad_u32_u24 v241, v241, s100, v250
	v_add_u32_e32 v242, 24, v249
	v_lshlrev_b32_e32 v242, 2, v242
	v_mad_u32_u24 v242, v242, s100, v250
	v_add_u32_e32 v243, 0, v249
	v_lshlrev_b32_e32 v243, 4, v243
	v_mad_u32_u24 v243, v243, s100, v250
	v_add_u32_e32 v244, 8, v249
	v_lshlrev_b32_e32 v244, 4, v244
	v_mad_u32_u24 v244, v244, s100, v250
	v_add_u32_e32 v245, 16, v249
	v_lshlrev_b32_e32 v245, 4, v245
	v_mad_u32_u24 v245, v245, s100, v250
	v_add_u32_e32 v246, 24, v249
	v_lshlrev_b32_e32 v246, 4, v246
	v_mad_u32_u24 v246, v246, s100, v250
	v_and_b32_e32 v247, 7, v249
	v_lshlrev_b32_e32 v247, 4, v247
	v_xor_b32_e32 v247, v247, v112
	v_and_b32_e32 v153, 7, v105
	v_or_b32_e32 v248, 0, v106
	v_xor_b32_e32 v248, v248, v153
	v_lshlrev_b32_e32 v248, 4, v248
	v_lshl_add_u32 v248, v105, 7, v248
	v_add_u32_e32 v248, s77, v248
	v_or_b32_e32 v249, 2, v106
	v_xor_b32_e32 v249, v249, v153
	v_lshlrev_b32_e32 v249, 4, v249
	v_lshl_add_u32 v249, v105, 7, v249
	v_add_u32_e32 v249, s77, v249
	v_or_b32_e32 v250, 4, v106
	v_xor_b32_e32 v250, v250, v153
	v_lshlrev_b32_e32 v250, 4, v250
	v_lshl_add_u32 v250, v105, 7, v250
	v_add_u32_e32 v250, s77, v250
	v_or_b32_e32 v251, 6, v106
	v_xor_b32_e32 v251, v251, v153
	v_lshlrev_b32_e32 v251, 4, v251
	v_lshl_add_u32 v251, v105, 7, v251
	v_add_u32_e32 v251, s77, v251
	v_lshlrev_b32_e32 v153, 1, v98
	v_mul_u32_u24_e32 v228, 17, v105
	v_sub_u32_e32 v228, v107, v228
	s_mul_i32 s90, s58, 153
	s_lshr_b32 s90, s90, 1
	s_add_i32 s90, s90, 34876
	v_lshl_add_u32 v228, v228, 2, s90
	v_lshlrev_b32_e32 v229, 2, v105
	v_sub_u32_e32 v229, v107, v229
	s_add_i32 s90, s101, 5104
	v_lshl_add_u32 v229, v229, 2, s90
	v_sub_u32_e32 v230, v107, v105
	s_add_i32 s90, s101, 6364
	v_lshl_add_u32 v230, v230, 2, s90
	v_add_u32_e32 v231, v109, v108
	v_mov_b64_e32 v[232:233], 0
	v_mov_b64_e32 v[0:1], 0
	v_mov_b64_e32 v[2:3], 0
	v_mov_b64_e32 v[4:5], 0
	v_mov_b64_e32 v[6:7], 0
	v_mov_b64_e32 v[8:9], 0
	v_mov_b64_e32 v[10:11], 0
	v_mov_b64_e32 v[12:13], 0
	v_mov_b64_e32 v[14:15], 0
	v_mov_b64_e32 v[16:17], 0
	v_mov_b64_e32 v[18:19], 0
	v_mov_b64_e32 v[20:21], 0
	v_mov_b64_e32 v[22:23], 0
	v_mov_b64_e32 v[24:25], 0
	v_mov_b64_e32 v[26:27], 0
	v_mov_b64_e32 v[28:29], 0
	v_mov_b64_e32 v[30:31], 0
	global_load_dwordx4 v[116:119], v235, s[84:85]
	global_load_dwordx4 v[120:123], v236, s[84:85]
	global_load_dwordx4 v[124:127], v237, s[84:85]
	global_load_dwordx4 v[128:131], v238, s[84:85]
	global_load_dwordx4 v[132:135], v100, s[84:85] offset:768
	global_load_dwordx4 v[136:139], v149, s[84:85] offset:768
	global_load_dwordx4 v[140:143], v100, s[84:85] offset:832
	global_load_dwordx4 v[144:147], v149, s[84:85] offset:832
	s_add_u32 s84, s84, 0x30000
	s_addc_u32 s85, s85, 0
	global_load_dwordx4 v[156:159], v235, s[84:85]
	global_load_dwordx4 v[160:163], v236, s[84:85]
	global_load_dwordx4 v[164:167], v237, s[84:85]
	global_load_dwordx4 v[168:171], v238, s[84:85]
	global_load_dwordx4 v[172:175], v100, s[84:85] offset:768
	global_load_dwordx4 v[176:179], v149, s[84:85] offset:768
	global_load_dwordx4 v[180:183], v100, s[84:85] offset:832
	global_load_dwordx4 v[184:187], v149, s[84:85] offset:832
	s_add_u32 s84, s84, 0x30000
	s_addc_u32 s85, s85, 0
	v_mov_b32_e32 v115, v228
	ds_read2_b32 v[32:33], v115 offset0:0 offset1:1
	ds_read2_b32 v[34:35], v115 offset0:2 offset1:3
	ds_read2_b32 v[36:37], v115 offset0:8 offset1:9
	ds_read2_b32 v[38:39], v115 offset0:10 offset1:11
	ds_read2_b32 v[40:41], v115 offset0:17 offset1:18
	ds_read2_b32 v[42:43], v115 offset0:19 offset1:20
	ds_read2_b32 v[44:45], v115 offset0:25 offset1:26
	ds_read2_b32 v[46:47], v115 offset0:27 offset1:28
	s_waitcnt vmcnt(8)
	ds_write_b128 v247, v[116:119]
	ds_write_b128 v247, v[120:123] offset:1024
	ds_write_b128 v247, v[124:127] offset:2048
	ds_write_b128 v247, v[128:131] offset:3072
	ds_read_b128 v[116:119], v248
	ds_read_b128 v[120:123], v249
	ds_read_b128 v[124:127], v250
	ds_read_b128 v[128:131], v251
	ds_write_b128 v112, v[132:135]
	ds_write_b128 v112, v[136:139] offset:1024
	ds_write_b128 v112, v[140:143] offset:2048
	ds_write_b128 v112, v[144:147] offset:3072
	s_waitcnt lgkmcnt(4)
	v_mfma_f32_32x32x16_bf16 v[32:47], v[116:119], v[48:51], v[32:47]
	v_mfma_f32_32x32x16_bf16 v[32:47], v[120:123], v[52:55], v[32:47]
	v_mfma_f32_32x32x16_bf16 v[32:47], v[124:127], v[56:59], v[32:47]
	v_mfma_f32_32x32x16_bf16 v[32:47], v[128:131], v[60:63], v[32:47]
	ds_read2_b32 v[188:189], v115 offset0:34 offset1:35
	ds_read2_b32 v[190:191], v115 offset0:36 offset1:37
	ds_read2_b32 v[192:193], v115 offset0:42 offset1:43
	ds_read2_b32 v[194:195], v115 offset0:44 offset1:45
	ds_read2_b32 v[196:197], v115 offset0:51 offset1:52
	ds_read2_b32 v[198:199], v115 offset0:53 offset1:54
	ds_read2_b32 v[200:201], v115 offset0:59 offset1:60
	ds_read2_b32 v[202:203], v115 offset0:61 offset1:62
	global_load_dwordx4 v[116:119], v235, s[84:85]
	global_load_dwordx4 v[120:123], v236, s[84:85]
	global_load_dwordx4 v[124:127], v237, s[84:85]
	global_load_dwordx4 v[128:131], v238, s[84:85]
	global_load_dwordx4 v[132:135], v100, s[84:85] offset:768
	global_load_dwordx4 v[136:139], v149, s[84:85] offset:768
	global_load_dwordx4 v[140:143], v100, s[84:85] offset:832
	global_load_dwordx4 v[144:147], v149, s[84:85] offset:832
	s_add_u32 s84, s84, 0x30000
	s_addc_u32 s85, s85, 0
	ds_read_b64_tr_b16 v[72:73], v231
	ds_read_b64_tr_b16 v[74:75], v231 offset:512
	ds_read_b64_tr_b16 v[76:77], v231 offset:2048
	ds_read_b64_tr_b16 v[78:79], v231 offset:2560
	ds_read_b64_tr_b16 v[220:221], v231 offset:1024
	ds_read_b64_tr_b16 v[222:223], v231 offset:1536
	ds_read_b64_tr_b16 v[224:225], v231 offset:3072
	ds_read_b64_tr_b16 v[226:227], v231 offset:3584
	v_exp_f32_e32 v32, v32
	v_exp_f32_e32 v33, v33
	v_exp_f32_e32 v34, v34
	v_exp_f32_e32 v35, v35
	s_waitcnt vmcnt(8)
	ds_write_b128 v247, v[156:159]
	ds_write_b128 v247, v[160:163] offset:1024
	ds_write_b128 v247, v[164:167] offset:2048
	ds_write_b128 v247, v[168:171] offset:3072
	ds_read_b128 v[156:159], v248
	ds_read_b128 v[160:163], v249
	ds_read_b128 v[164:167], v250
	ds_read_b128 v[168:171], v251
	ds_write_b128 v112, v[172:175]
	ds_write_b128 v112, v[176:179] offset:1024
	ds_write_b128 v112, v[180:183] offset:2048
	ds_write_b128 v112, v[184:187] offset:3072
	v_exp_f32_e32 v36, v36
	v_exp_f32_e32 v37, v37
	v_exp_f32_e32 v38, v38
	v_exp_f32_e32 v39, v39
	s_waitcnt lgkmcnt(4)
	v_mfma_f32_32x32x16_bf16 v[188:203], v[156:159], v[48:51], v[188:203]
	v_exp_f32_e32 v40, v40
	v_exp_f32_e32 v41, v41
	v_mfma_f32_32x32x16_bf16 v[188:203], v[160:163], v[52:55], v[188:203]
	v_exp_f32_e32 v42, v42
	v_exp_f32_e32 v43, v43
	v_mfma_f32_32x32x16_bf16 v[188:203], v[164:167], v[56:59], v[188:203]
	v_exp_f32_e32 v44, v44
	v_exp_f32_e32 v45, v45
	v_mfma_f32_32x32x16_bf16 v[188:203], v[168:171], v[60:63], v[188:203]
	v_exp_f32_e32 v46, v46
	v_exp_f32_e32 v47, v47
	v_cvt_pk_bf16_f32 v64, v32, v33
	v_cvt_pk_bf16_f32 v65, v34, v35
	v_cvt_pk_bf16_f32 v66, v36, v37
	v_cvt_pk_bf16_f32 v67, v38, v39
	v_cvt_pk_bf16_f32 v68, v40, v41
	v_cvt_pk_bf16_f32 v69, v42, v43
	v_cvt_pk_bf16_f32 v70, v44, v45
	v_cvt_pk_bf16_f32 v71, v46, v47
	v_pk_add_f32 v[232:233], v[232:233], v[32:33]
	v_pk_add_f32 v[232:233], v[232:233], v[34:35]
	v_pk_add_f32 v[232:233], v[232:233], v[36:37]
	v_pk_add_f32 v[232:233], v[232:233], v[38:39]
	v_pk_add_f32 v[232:233], v[232:233], v[40:41]
	v_pk_add_f32 v[232:233], v[232:233], v[42:43]
	v_pk_add_f32 v[232:233], v[232:233], v[44:45]
	v_pk_add_f32 v[232:233], v[232:233], v[46:47]
	ds_read2_b32 v[32:33], v115 offset0:68 offset1:69
	ds_read2_b32 v[34:35], v115 offset0:70 offset1:71
	ds_read2_b32 v[36:37], v115 offset0:76 offset1:77
	ds_read2_b32 v[38:39], v115 offset0:78 offset1:79
	ds_read2_b32 v[40:41], v115 offset0:85 offset1:86
	ds_read2_b32 v[42:43], v115 offset0:87 offset1:88
	ds_read2_b32 v[44:45], v115 offset0:93 offset1:94
	ds_read2_b32 v[46:47], v115 offset0:95 offset1:96
	v_mfma_f32_32x32x16_bf16 v[0:15], v[64:67], v[72:75], v[0:15]
	v_mfma_f32_32x32x16_bf16 v[16:31], v[64:67], v[76:79], v[16:31]
	v_mfma_f32_32x32x16_bf16 v[0:15], v[68:71], v[220:223], v[0:15]
	v_mfma_f32_32x32x16_bf16 v[16:31], v[68:71], v[224:227], v[16:31]
	global_load_dwordx4 v[156:159], v235, s[84:85]
	global_load_dwordx4 v[160:163], v236, s[84:85]
	global_load_dwordx4 v[164:167], v237, s[84:85]
	global_load_dwordx4 v[168:171], v238, s[84:85]
	global_load_dwordx4 v[172:175], v100, s[84:85] offset:768
	global_load_dwordx4 v[176:179], v149, s[84:85] offset:768
	global_load_dwordx4 v[180:183], v100, s[84:85] offset:832
	global_load_dwordx4 v[184:187], v149, s[84:85] offset:832
	s_add_u32 s84, s84, 0x30000
	s_addc_u32 s85, s85, 0
	ds_read_b64_tr_b16 v[72:73], v231
	ds_read_b64_tr_b16 v[74:75], v231 offset:512
	ds_read_b64_tr_b16 v[76:77], v231 offset:2048
	ds_read_b64_tr_b16 v[78:79], v231 offset:2560
	ds_read_b64_tr_b16 v[220:221], v231 offset:1024
	ds_read_b64_tr_b16 v[222:223], v231 offset:1536
	ds_read_b64_tr_b16 v[224:225], v231 offset:3072
	ds_read_b64_tr_b16 v[226:227], v231 offset:3584
	v_exp_f32_e32 v188, v188
	v_exp_f32_e32 v189, v189
	v_exp_f32_e32 v190, v190
	v_exp_f32_e32 v191, v191
	s_waitcnt vmcnt(8)
	ds_write_b128 v247, v[116:119]
	ds_write_b128 v247, v[120:123] offset:1024
	ds_write_b128 v247, v[124:127] offset:2048
	ds_write_b128 v247, v[128:131] offset:3072
	ds_read_b128 v[116:119], v248
	ds_read_b128 v[120:123], v249
	ds_read_b128 v[124:127], v250
	ds_read_b128 v[128:131], v251
	ds_write_b128 v112, v[132:135]
	ds_write_b128 v112, v[136:139] offset:1024
	ds_write_b128 v112, v[140:143] offset:2048
	ds_write_b128 v112, v[144:147] offset:3072
	v_exp_f32_e32 v192, v192
	v_exp_f32_e32 v193, v193
	v_exp_f32_e32 v194, v194
	v_exp_f32_e32 v195, v195
	s_waitcnt lgkmcnt(4)
	v_mfma_f32_32x32x16_bf16 v[32:47], v[116:119], v[48:51], v[32:47]
	v_exp_f32_e32 v196, v196
	v_exp_f32_e32 v197, v197
	v_mfma_f32_32x32x16_bf16 v[32:47], v[120:123], v[52:55], v[32:47]
	v_exp_f32_e32 v198, v198
	v_exp_f32_e32 v199, v199
	v_mfma_f32_32x32x16_bf16 v[32:47], v[124:127], v[56:59], v[32:47]
	v_exp_f32_e32 v200, v200
	v_exp_f32_e32 v201, v201
	v_mfma_f32_32x32x16_bf16 v[32:47], v[128:131], v[60:63], v[32:47]
	v_exp_f32_e32 v202, v202
	v_exp_f32_e32 v203, v203
	v_cvt_pk_bf16_f32 v64, v188, v189
	v_cvt_pk_bf16_f32 v65, v190, v191
	v_cvt_pk_bf16_f32 v66, v192, v193
	v_cvt_pk_bf16_f32 v67, v194, v195
	v_cvt_pk_bf16_f32 v68, v196, v197
	v_cvt_pk_bf16_f32 v69, v198, v199
	v_cvt_pk_bf16_f32 v70, v200, v201
	v_cvt_pk_bf16_f32 v71, v202, v203
	v_pk_add_f32 v[232:233], v[232:233], v[188:189]
	v_pk_add_f32 v[232:233], v[232:233], v[190:191]
	v_pk_add_f32 v[232:233], v[232:233], v[192:193]
	v_pk_add_f32 v[232:233], v[232:233], v[194:195]
	v_pk_add_f32 v[232:233], v[232:233], v[196:197]
	v_pk_add_f32 v[232:233], v[232:233], v[198:199]
	v_pk_add_f32 v[232:233], v[232:233], v[200:201]
	v_pk_add_f32 v[232:233], v[232:233], v[202:203]
	ds_read2_b32 v[188:189], v115 offset0:102 offset1:103
	ds_read2_b32 v[190:191], v115 offset0:104 offset1:105
	ds_read2_b32 v[192:193], v115 offset0:110 offset1:111
	ds_read2_b32 v[194:195], v115 offset0:112 offset1:113
	ds_read2_b32 v[196:197], v115 offset0:119 offset1:120
	ds_read2_b32 v[198:199], v115 offset0:121 offset1:122
	ds_read2_b32 v[200:201], v115 offset0:127 offset1:128
	ds_read2_b32 v[202:203], v115 offset0:129 offset1:130
	v_mfma_f32_32x32x16_bf16 v[0:15], v[64:67], v[72:75], v[0:15]
	v_mfma_f32_32x32x16_bf16 v[16:31], v[64:67], v[76:79], v[16:31]
	v_mfma_f32_32x32x16_bf16 v[0:15], v[68:71], v[220:223], v[0:15]
	v_mfma_f32_32x32x16_bf16 v[16:31], v[68:71], v[224:227], v[16:31]
	global_load_dwordx4 v[116:119], v235, s[84:85]
	global_load_dwordx4 v[120:123], v236, s[84:85]
	global_load_dwordx4 v[124:127], v237, s[84:85]
	global_load_dwordx4 v[128:131], v238, s[84:85]
	global_load_dwordx4 v[132:135], v100, s[84:85] offset:768
	global_load_dwordx4 v[136:139], v149, s[84:85] offset:768
	global_load_dwordx4 v[140:143], v100, s[84:85] offset:832
	global_load_dwordx4 v[144:147], v149, s[84:85] offset:832
	s_add_u32 s84, s84, 0x30000
	s_addc_u32 s85, s85, 0
	ds_read_b64_tr_b16 v[72:73], v231
	ds_read_b64_tr_b16 v[74:75], v231 offset:512
	ds_read_b64_tr_b16 v[76:77], v231 offset:2048
	ds_read_b64_tr_b16 v[78:79], v231 offset:2560
	ds_read_b64_tr_b16 v[220:221], v231 offset:1024
	ds_read_b64_tr_b16 v[222:223], v231 offset:1536
	ds_read_b64_tr_b16 v[224:225], v231 offset:3072
	ds_read_b64_tr_b16 v[226:227], v231 offset:3584
	v_exp_f32_e32 v32, v32
	v_exp_f32_e32 v33, v33
	v_exp_f32_e32 v34, v34
	v_exp_f32_e32 v35, v35
	s_waitcnt vmcnt(8)
	ds_write_b128 v247, v[156:159]
	ds_write_b128 v247, v[160:163] offset:1024
	ds_write_b128 v247, v[164:167] offset:2048
	ds_write_b128 v247, v[168:171] offset:3072
	ds_read_b128 v[156:159], v248
	ds_read_b128 v[160:163], v249
	ds_read_b128 v[164:167], v250
	ds_read_b128 v[168:171], v251
	ds_write_b128 v112, v[172:175]
	ds_write_b128 v112, v[176:179] offset:1024
	ds_write_b128 v112, v[180:183] offset:2048
	ds_write_b128 v112, v[184:187] offset:3072
	v_exp_f32_e32 v36, v36
	v_exp_f32_e32 v37, v37
	v_exp_f32_e32 v38, v38
	v_exp_f32_e32 v39, v39
	s_waitcnt lgkmcnt(4)
	v_mfma_f32_32x32x16_bf16 v[188:203], v[156:159], v[48:51], v[188:203]
	v_exp_f32_e32 v40, v40
	v_exp_f32_e32 v41, v41
	v_mfma_f32_32x32x16_bf16 v[188:203], v[160:163], v[52:55], v[188:203]
	v_exp_f32_e32 v42, v42
	v_exp_f32_e32 v43, v43
	v_mfma_f32_32x32x16_bf16 v[188:203], v[164:167], v[56:59], v[188:203]
	v_exp_f32_e32 v44, v44
	v_exp_f32_e32 v45, v45
	v_mfma_f32_32x32x16_bf16 v[188:203], v[168:171], v[60:63], v[188:203]
	v_exp_f32_e32 v46, v46
	v_exp_f32_e32 v47, v47
	v_cvt_pk_bf16_f32 v64, v32, v33
	v_cvt_pk_bf16_f32 v65, v34, v35
	v_cvt_pk_bf16_f32 v66, v36, v37
	v_cvt_pk_bf16_f32 v67, v38, v39
	v_cvt_pk_bf16_f32 v68, v40, v41
	v_cvt_pk_bf16_f32 v69, v42, v43
	v_cvt_pk_bf16_f32 v70, v44, v45
	v_cvt_pk_bf16_f32 v71, v46, v47
	v_pk_add_f32 v[232:233], v[232:233], v[32:33]
	v_pk_add_f32 v[232:233], v[232:233], v[34:35]
	v_pk_add_f32 v[232:233], v[232:233], v[36:37]
	v_pk_add_f32 v[232:233], v[232:233], v[38:39]
	v_pk_add_f32 v[232:233], v[232:233], v[40:41]
	v_pk_add_f32 v[232:233], v[232:233], v[42:43]
	v_pk_add_f32 v[232:233], v[232:233], v[44:45]
	v_pk_add_f32 v[232:233], v[232:233], v[46:47]
	ds_read2_b32 v[32:33], v115 offset0:136 offset1:137
	ds_read2_b32 v[34:35], v115 offset0:138 offset1:139
	ds_read2_b32 v[36:37], v115 offset0:144 offset1:145
	ds_read2_b32 v[38:39], v115 offset0:146 offset1:147
	ds_read2_b32 v[40:41], v115 offset0:153 offset1:154
	ds_read2_b32 v[42:43], v115 offset0:155 offset1:156
	ds_read2_b32 v[44:45], v115 offset0:161 offset1:162
	ds_read2_b32 v[46:47], v115 offset0:163 offset1:164
	v_mfma_f32_32x32x16_bf16 v[0:15], v[64:67], v[72:75], v[0:15]
	v_mfma_f32_32x32x16_bf16 v[16:31], v[64:67], v[76:79], v[16:31]
	v_mfma_f32_32x32x16_bf16 v[0:15], v[68:71], v[220:223], v[0:15]
	v_mfma_f32_32x32x16_bf16 v[16:31], v[68:71], v[224:227], v[16:31]
	global_load_dwordx4 v[156:159], v235, s[84:85]
	global_load_dwordx4 v[160:163], v236, s[84:85]
	global_load_dwordx4 v[164:167], v237, s[84:85]
	global_load_dwordx4 v[168:171], v238, s[84:85]
	global_load_dwordx4 v[172:175], v100, s[84:85] offset:768
	global_load_dwordx4 v[176:179], v149, s[84:85] offset:768
	global_load_dwordx4 v[180:183], v100, s[84:85] offset:832
	global_load_dwordx4 v[184:187], v149, s[84:85] offset:832
	s_add_u32 s84, s84, 0x30000
	s_addc_u32 s85, s85, 0
	ds_read_b64_tr_b16 v[72:73], v231
	ds_read_b64_tr_b16 v[74:75], v231 offset:512
	ds_read_b64_tr_b16 v[76:77], v231 offset:2048
	ds_read_b64_tr_b16 v[78:79], v231 offset:2560
	ds_read_b64_tr_b16 v[220:221], v231 offset:1024
	ds_read_b64_tr_b16 v[222:223], v231 offset:1536
	ds_read_b64_tr_b16 v[224:225], v231 offset:3072
	ds_read_b64_tr_b16 v[226:227], v231 offset:3584
	v_exp_f32_e32 v188, v188
	v_exp_f32_e32 v189, v189
	v_exp_f32_e32 v190, v190
	v_exp_f32_e32 v191, v191
	s_waitcnt vmcnt(8)
	ds_write_b128 v247, v[116:119]
	ds_write_b128 v247, v[120:123] offset:1024
	ds_write_b128 v247, v[124:127] offset:2048
	ds_write_b128 v247, v[128:131] offset:3072
	ds_read_b128 v[116:119], v248
	ds_read_b128 v[120:123], v249
	ds_read_b128 v[124:127], v250
	ds_read_b128 v[128:131], v251
	ds_write_b128 v112, v[132:135]
	ds_write_b128 v112, v[136:139] offset:1024
	ds_write_b128 v112, v[140:143] offset:2048
	ds_write_b128 v112, v[144:147] offset:3072
	v_exp_f32_e32 v192, v192
	v_exp_f32_e32 v193, v193
	v_exp_f32_e32 v194, v194
	v_exp_f32_e32 v195, v195
	s_waitcnt lgkmcnt(4)
	v_mfma_f32_32x32x16_bf16 v[32:47], v[116:119], v[48:51], v[32:47]
	v_exp_f32_e32 v196, v196
	v_exp_f32_e32 v197, v197
	v_mfma_f32_32x32x16_bf16 v[32:47], v[120:123], v[52:55], v[32:47]
	v_exp_f32_e32 v198, v198
	v_exp_f32_e32 v199, v199
	v_mfma_f32_32x32x16_bf16 v[32:47], v[124:127], v[56:59], v[32:47]
	v_exp_f32_e32 v200, v200
	v_exp_f32_e32 v201, v201
	v_mfma_f32_32x32x16_bf16 v[32:47], v[128:131], v[60:63], v[32:47]
	v_exp_f32_e32 v202, v202
	v_exp_f32_e32 v203, v203
	v_cvt_pk_bf16_f32 v64, v188, v189
	v_cvt_pk_bf16_f32 v65, v190, v191
	v_cvt_pk_bf16_f32 v66, v192, v193
	v_cvt_pk_bf16_f32 v67, v194, v195
	v_cvt_pk_bf16_f32 v68, v196, v197
	v_cvt_pk_bf16_f32 v69, v198, v199
	v_cvt_pk_bf16_f32 v70, v200, v201
	v_cvt_pk_bf16_f32 v71, v202, v203
	v_pk_add_f32 v[232:233], v[232:233], v[188:189]
	v_pk_add_f32 v[232:233], v[232:233], v[190:191]
	v_pk_add_f32 v[232:233], v[232:233], v[192:193]
	v_pk_add_f32 v[232:233], v[232:233], v[194:195]
	v_pk_add_f32 v[232:233], v[232:233], v[196:197]
	v_pk_add_f32 v[232:233], v[232:233], v[198:199]
	v_pk_add_f32 v[232:233], v[232:233], v[200:201]
	v_pk_add_f32 v[232:233], v[232:233], v[202:203]
	ds_read2_b32 v[188:189], v115 offset0:170 offset1:171
	ds_read2_b32 v[190:191], v115 offset0:172 offset1:173
	ds_read2_b32 v[192:193], v115 offset0:178 offset1:179
	ds_read2_b32 v[194:195], v115 offset0:180 offset1:181
	ds_read2_b32 v[196:197], v115 offset0:187 offset1:188
	ds_read2_b32 v[198:199], v115 offset0:189 offset1:190
	ds_read2_b32 v[200:201], v115 offset0:195 offset1:196
	ds_read2_b32 v[202:203], v115 offset0:197 offset1:198
	v_mfma_f32_32x32x16_bf16 v[0:15], v[64:67], v[72:75], v[0:15]
	v_mfma_f32_32x32x16_bf16 v[16:31], v[64:67], v[76:79], v[16:31]
	v_mfma_f32_32x32x16_bf16 v[0:15], v[68:71], v[220:223], v[0:15]
	v_mfma_f32_32x32x16_bf16 v[16:31], v[68:71], v[224:227], v[16:31]
	global_load_dwordx4 v[116:119], v235, s[84:85]
	global_load_dwordx4 v[120:123], v236, s[84:85]
	global_load_dwordx4 v[124:127], v237, s[84:85]
	global_load_dwordx4 v[128:131], v238, s[84:85]
	global_load_dwordx4 v[132:135], v100, s[84:85] offset:768
	global_load_dwordx4 v[136:139], v149, s[84:85] offset:768
	global_load_dwordx4 v[140:143], v100, s[84:85] offset:832
	global_load_dwordx4 v[144:147], v149, s[84:85] offset:832
	s_add_u32 s84, s84, 0x30000
	s_addc_u32 s85, s85, 0
	ds_read_b64_tr_b16 v[72:73], v231
	ds_read_b64_tr_b16 v[74:75], v231 offset:512
	ds_read_b64_tr_b16 v[76:77], v231 offset:2048
	ds_read_b64_tr_b16 v[78:79], v231 offset:2560
	ds_read_b64_tr_b16 v[220:221], v231 offset:1024
	ds_read_b64_tr_b16 v[222:223], v231 offset:1536
	ds_read_b64_tr_b16 v[224:225], v231 offset:3072
	ds_read_b64_tr_b16 v[226:227], v231 offset:3584
	v_exp_f32_e32 v32, v32
	v_exp_f32_e32 v33, v33
	v_exp_f32_e32 v34, v34
	v_exp_f32_e32 v35, v35
	s_waitcnt vmcnt(8)
	ds_write_b128 v247, v[156:159]
	ds_write_b128 v247, v[160:163] offset:1024
	ds_write_b128 v247, v[164:167] offset:2048
	ds_write_b128 v247, v[168:171] offset:3072
	ds_read_b128 v[156:159], v248
	ds_read_b128 v[160:163], v249
	ds_read_b128 v[164:167], v250
	ds_read_b128 v[168:171], v251
	ds_write_b128 v112, v[172:175]
	ds_write_b128 v112, v[176:179] offset:1024
	ds_write_b128 v112, v[180:183] offset:2048
	ds_write_b128 v112, v[184:187] offset:3072
	v_exp_f32_e32 v36, v36
	v_exp_f32_e32 v37, v37
	v_exp_f32_e32 v38, v38
	v_exp_f32_e32 v39, v39
	s_waitcnt lgkmcnt(4)
	v_mfma_f32_32x32x16_bf16 v[188:203], v[156:159], v[48:51], v[188:203]
	v_exp_f32_e32 v40, v40
	v_exp_f32_e32 v41, v41
	v_mfma_f32_32x32x16_bf16 v[188:203], v[160:163], v[52:55], v[188:203]
	v_exp_f32_e32 v42, v42
	v_exp_f32_e32 v43, v43
	v_mfma_f32_32x32x16_bf16 v[188:203], v[164:167], v[56:59], v[188:203]
	v_exp_f32_e32 v44, v44
	v_exp_f32_e32 v45, v45
	v_mfma_f32_32x32x16_bf16 v[188:203], v[168:171], v[60:63], v[188:203]
	v_exp_f32_e32 v46, v46
	v_exp_f32_e32 v47, v47
	v_cvt_pk_bf16_f32 v64, v32, v33
	v_cvt_pk_bf16_f32 v65, v34, v35
	v_cvt_pk_bf16_f32 v66, v36, v37
	v_cvt_pk_bf16_f32 v67, v38, v39
	v_cvt_pk_bf16_f32 v68, v40, v41
	v_cvt_pk_bf16_f32 v69, v42, v43
	v_cvt_pk_bf16_f32 v70, v44, v45
	v_cvt_pk_bf16_f32 v71, v46, v47
	v_pk_add_f32 v[232:233], v[232:233], v[32:33]
	v_pk_add_f32 v[232:233], v[232:233], v[34:35]
	v_pk_add_f32 v[232:233], v[232:233], v[36:37]
	v_pk_add_f32 v[232:233], v[232:233], v[38:39]
	v_pk_add_f32 v[232:233], v[232:233], v[40:41]
	v_pk_add_f32 v[232:233], v[232:233], v[42:43]
	v_pk_add_f32 v[232:233], v[232:233], v[44:45]
	v_pk_add_f32 v[232:233], v[232:233], v[46:47]
	ds_read2_b32 v[32:33], v115 offset0:204 offset1:205
	ds_read2_b32 v[34:35], v115 offset0:206 offset1:207
	ds_read2_b32 v[36:37], v115 offset0:212 offset1:213
	ds_read2_b32 v[38:39], v115 offset0:214 offset1:215
	ds_read2_b32 v[40:41], v115 offset0:221 offset1:222
	ds_read2_b32 v[42:43], v115 offset0:223 offset1:224
	ds_read2_b32 v[44:45], v115 offset0:229 offset1:230
	ds_read2_b32 v[46:47], v115 offset0:231 offset1:232
	v_mfma_f32_32x32x16_bf16 v[0:15], v[64:67], v[72:75], v[0:15]
	v_mfma_f32_32x32x16_bf16 v[16:31], v[64:67], v[76:79], v[16:31]
	v_mfma_f32_32x32x16_bf16 v[0:15], v[68:71], v[220:223], v[0:15]
	v_mfma_f32_32x32x16_bf16 v[16:31], v[68:71], v[224:227], v[16:31]
	global_load_dwordx4 v[156:159], v235, s[84:85]
	global_load_dwordx4 v[160:163], v236, s[84:85]
	global_load_dwordx4 v[164:167], v237, s[84:85]
	global_load_dwordx4 v[168:171], v238, s[84:85]
	global_load_dwordx4 v[172:175], v100, s[84:85] offset:768
	global_load_dwordx4 v[176:179], v149, s[84:85] offset:768
	global_load_dwordx4 v[180:183], v100, s[84:85] offset:832
	global_load_dwordx4 v[184:187], v149, s[84:85] offset:832
	s_add_u32 s84, s84, 0x30000
	s_addc_u32 s85, s85, 0
	ds_read_b64_tr_b16 v[72:73], v231
	ds_read_b64_tr_b16 v[74:75], v231 offset:512
	ds_read_b64_tr_b16 v[76:77], v231 offset:2048
	ds_read_b64_tr_b16 v[78:79], v231 offset:2560
	ds_read_b64_tr_b16 v[220:221], v231 offset:1024
	ds_read_b64_tr_b16 v[222:223], v231 offset:1536
	ds_read_b64_tr_b16 v[224:225], v231 offset:3072
	ds_read_b64_tr_b16 v[226:227], v231 offset:3584
	v_exp_f32_e32 v188, v188
	v_exp_f32_e32 v189, v189
	v_exp_f32_e32 v190, v190
	v_exp_f32_e32 v191, v191
	s_waitcnt vmcnt(8)
	ds_write_b128 v247, v[116:119]
	ds_write_b128 v247, v[120:123] offset:1024
	ds_write_b128 v247, v[124:127] offset:2048
	ds_write_b128 v247, v[128:131] offset:3072
	ds_read_b128 v[116:119], v248
	ds_read_b128 v[120:123], v249
	ds_read_b128 v[124:127], v250
	ds_read_b128 v[128:131], v251
	ds_write_b128 v112, v[132:135]
	ds_write_b128 v112, v[136:139] offset:1024
	ds_write_b128 v112, v[140:143] offset:2048
	ds_write_b128 v112, v[144:147] offset:3072
	v_exp_f32_e32 v192, v192
	v_exp_f32_e32 v193, v193
	v_exp_f32_e32 v194, v194
	v_exp_f32_e32 v195, v195
	s_waitcnt lgkmcnt(4)
	v_mfma_f32_32x32x16_bf16 v[32:47], v[116:119], v[48:51], v[32:47]
	v_exp_f32_e32 v196, v196
	v_exp_f32_e32 v197, v197
	v_mfma_f32_32x32x16_bf16 v[32:47], v[120:123], v[52:55], v[32:47]
	v_exp_f32_e32 v198, v198
	v_exp_f32_e32 v199, v199
	v_mfma_f32_32x32x16_bf16 v[32:47], v[124:127], v[56:59], v[32:47]
	v_exp_f32_e32 v200, v200
	v_exp_f32_e32 v201, v201
	v_mfma_f32_32x32x16_bf16 v[32:47], v[128:131], v[60:63], v[32:47]
	v_exp_f32_e32 v202, v202
	v_exp_f32_e32 v203, v203
	v_cvt_pk_bf16_f32 v64, v188, v189
	v_cvt_pk_bf16_f32 v65, v190, v191
	v_cvt_pk_bf16_f32 v66, v192, v193
	v_cvt_pk_bf16_f32 v67, v194, v195
	v_cvt_pk_bf16_f32 v68, v196, v197
	v_cvt_pk_bf16_f32 v69, v198, v199
	v_cvt_pk_bf16_f32 v70, v200, v201
	v_cvt_pk_bf16_f32 v71, v202, v203
	v_pk_add_f32 v[232:233], v[232:233], v[188:189]
	v_pk_add_f32 v[232:233], v[232:233], v[190:191]
	v_pk_add_f32 v[232:233], v[232:233], v[192:193]
	v_pk_add_f32 v[232:233], v[232:233], v[194:195]
	v_pk_add_f32 v[232:233], v[232:233], v[196:197]
	v_pk_add_f32 v[232:233], v[232:233], v[198:199]
	v_pk_add_f32 v[232:233], v[232:233], v[200:201]
	v_pk_add_f32 v[232:233], v[232:233], v[202:203]
	v_add_u32_e32 v115, 952, v115
	ds_read2_b32 v[188:189], v115 offset0:0 offset1:1
	ds_read2_b32 v[190:191], v115 offset0:2 offset1:3
	ds_read2_b32 v[192:193], v115 offset0:8 offset1:9
	ds_read2_b32 v[194:195], v115 offset0:10 offset1:11
	ds_read2_b32 v[196:197], v115 offset0:17 offset1:18
	ds_read2_b32 v[198:199], v115 offset0:19 offset1:20
	ds_read2_b32 v[200:201], v115 offset0:25 offset1:26
	ds_read2_b32 v[202:203], v115 offset0:27 offset1:28
	v_mfma_f32_32x32x16_bf16 v[0:15], v[64:67], v[72:75], v[0:15]
	v_mfma_f32_32x32x16_bf16 v[16:31], v[64:67], v[76:79], v[16:31]
	v_mfma_f32_32x32x16_bf16 v[0:15], v[68:71], v[220:223], v[0:15]
	v_mfma_f32_32x32x16_bf16 v[16:31], v[68:71], v[224:227], v[16:31]
	global_load_dwordx4 v[116:119], v235, s[84:85]
	global_load_dwordx4 v[120:123], v236, s[84:85]
	global_load_dwordx4 v[124:127], v237, s[84:85]
	global_load_dwordx4 v[128:131], v238, s[84:85]
	global_load_dwordx4 v[132:135], v100, s[84:85] offset:768
	global_load_dwordx4 v[136:139], v149, s[84:85] offset:768
	global_load_dwordx4 v[140:143], v100, s[84:85] offset:832
	global_load_dwordx4 v[144:147], v149, s[84:85] offset:832
	s_add_u32 s84, s84, 0x30000
	s_addc_u32 s85, s85, 0
	ds_read_b64_tr_b16 v[72:73], v231
	ds_read_b64_tr_b16 v[74:75], v231 offset:512
	ds_read_b64_tr_b16 v[76:77], v231 offset:2048
	ds_read_b64_tr_b16 v[78:79], v231 offset:2560
	ds_read_b64_tr_b16 v[220:221], v231 offset:1024
	ds_read_b64_tr_b16 v[222:223], v231 offset:1536
	ds_read_b64_tr_b16 v[224:225], v231 offset:3072
	ds_read_b64_tr_b16 v[226:227], v231 offset:3584
	v_exp_f32_e32 v32, v32
	v_exp_f32_e32 v33, v33
	v_exp_f32_e32 v34, v34
	v_exp_f32_e32 v35, v35
	s_waitcnt vmcnt(8)
	ds_write_b128 v247, v[156:159]
	ds_write_b128 v247, v[160:163] offset:1024
	ds_write_b128 v247, v[164:167] offset:2048
	ds_write_b128 v247, v[168:171] offset:3072
	ds_read_b128 v[156:159], v248
	ds_read_b128 v[160:163], v249
	ds_read_b128 v[164:167], v250
	ds_read_b128 v[168:171], v251
	ds_write_b128 v112, v[172:175]
	ds_write_b128 v112, v[176:179] offset:1024
	ds_write_b128 v112, v[180:183] offset:2048
	ds_write_b128 v112, v[184:187] offset:3072
	v_exp_f32_e32 v36, v36
	v_exp_f32_e32 v37, v37
	v_exp_f32_e32 v38, v38
	v_exp_f32_e32 v39, v39
	s_waitcnt lgkmcnt(4)
	v_mfma_f32_32x32x16_bf16 v[188:203], v[156:159], v[48:51], v[188:203]
	v_exp_f32_e32 v40, v40
	v_exp_f32_e32 v41, v41
	v_mfma_f32_32x32x16_bf16 v[188:203], v[160:163], v[52:55], v[188:203]
	v_exp_f32_e32 v42, v42
	v_exp_f32_e32 v43, v43
	v_mfma_f32_32x32x16_bf16 v[188:203], v[164:167], v[56:59], v[188:203]
	v_exp_f32_e32 v44, v44
	v_exp_f32_e32 v45, v45
	v_mfma_f32_32x32x16_bf16 v[188:203], v[168:171], v[60:63], v[188:203]
	v_exp_f32_e32 v46, v46
	v_exp_f32_e32 v47, v47
	v_cvt_pk_bf16_f32 v64, v32, v33
	v_cvt_pk_bf16_f32 v65, v34, v35
	v_cvt_pk_bf16_f32 v66, v36, v37
	v_cvt_pk_bf16_f32 v67, v38, v39
	v_cvt_pk_bf16_f32 v68, v40, v41
	v_cvt_pk_bf16_f32 v69, v42, v43
	v_cvt_pk_bf16_f32 v70, v44, v45
	v_cvt_pk_bf16_f32 v71, v46, v47
	v_pk_add_f32 v[232:233], v[232:233], v[32:33]
	v_pk_add_f32 v[232:233], v[232:233], v[34:35]
	v_pk_add_f32 v[232:233], v[232:233], v[36:37]
	v_pk_add_f32 v[232:233], v[232:233], v[38:39]
	v_pk_add_f32 v[232:233], v[232:233], v[40:41]
	v_pk_add_f32 v[232:233], v[232:233], v[42:43]
	v_pk_add_f32 v[232:233], v[232:233], v[44:45]
	v_pk_add_f32 v[232:233], v[232:233], v[46:47]
	ds_read2_b32 v[32:33], v115 offset0:34 offset1:35
	ds_read2_b32 v[34:35], v115 offset0:36 offset1:37
	ds_read2_b32 v[36:37], v115 offset0:42 offset1:43
	ds_read2_b32 v[38:39], v115 offset0:44 offset1:45
	ds_read2_b32 v[40:41], v115 offset0:51 offset1:52
	ds_read2_b32 v[42:43], v115 offset0:53 offset1:54
	ds_read2_b32 v[44:45], v115 offset0:59 offset1:60
	ds_read2_b32 v[46:47], v115 offset0:61 offset1:62
	v_mfma_f32_32x32x16_bf16 v[0:15], v[64:67], v[72:75], v[0:15]
	v_mfma_f32_32x32x16_bf16 v[16:31], v[64:67], v[76:79], v[16:31]
	v_mfma_f32_32x32x16_bf16 v[0:15], v[68:71], v[220:223], v[0:15]
	v_mfma_f32_32x32x16_bf16 v[16:31], v[68:71], v[224:227], v[16:31]
	global_load_dwordx4 v[156:159], v235, s[84:85]
	global_load_dwordx4 v[160:163], v236, s[84:85]
	global_load_dwordx4 v[164:167], v237, s[84:85]
	global_load_dwordx4 v[168:171], v238, s[84:85]
	global_load_dwordx4 v[172:175], v100, s[84:85] offset:768
	global_load_dwordx4 v[176:179], v149, s[84:85] offset:768
	global_load_dwordx4 v[180:183], v100, s[84:85] offset:832
	global_load_dwordx4 v[184:187], v149, s[84:85] offset:832
	s_add_u32 s84, s84, 0x30000
	s_addc_u32 s85, s85, 0
	ds_read_b64_tr_b16 v[72:73], v231
	ds_read_b64_tr_b16 v[74:75], v231 offset:512
	ds_read_b64_tr_b16 v[76:77], v231 offset:2048
	ds_read_b64_tr_b16 v[78:79], v231 offset:2560
	ds_read_b64_tr_b16 v[220:221], v231 offset:1024
	ds_read_b64_tr_b16 v[222:223], v231 offset:1536
	ds_read_b64_tr_b16 v[224:225], v231 offset:3072
	ds_read_b64_tr_b16 v[226:227], v231 offset:3584
	v_exp_f32_e32 v188, v188
	v_exp_f32_e32 v189, v189
	v_exp_f32_e32 v190, v190
	v_exp_f32_e32 v191, v191
	s_waitcnt vmcnt(8)
	ds_write_b128 v247, v[116:119]
	ds_write_b128 v247, v[120:123] offset:1024
	ds_write_b128 v247, v[124:127] offset:2048
	ds_write_b128 v247, v[128:131] offset:3072
	ds_read_b128 v[116:119], v248
	ds_read_b128 v[120:123], v249
	ds_read_b128 v[124:127], v250
	ds_read_b128 v[128:131], v251
	ds_write_b128 v112, v[132:135]
	ds_write_b128 v112, v[136:139] offset:1024
	ds_write_b128 v112, v[140:143] offset:2048
	ds_write_b128 v112, v[144:147] offset:3072
	v_exp_f32_e32 v192, v192
	v_exp_f32_e32 v193, v193
	v_exp_f32_e32 v194, v194
	v_exp_f32_e32 v195, v195
	s_waitcnt lgkmcnt(4)
	v_mfma_f32_32x32x16_bf16 v[32:47], v[116:119], v[48:51], v[32:47]
	v_exp_f32_e32 v196, v196
	v_exp_f32_e32 v197, v197
	v_mfma_f32_32x32x16_bf16 v[32:47], v[120:123], v[52:55], v[32:47]
	v_exp_f32_e32 v198, v198
	v_exp_f32_e32 v199, v199
	v_mfma_f32_32x32x16_bf16 v[32:47], v[124:127], v[56:59], v[32:47]
	v_exp_f32_e32 v200, v200
	v_exp_f32_e32 v201, v201
	v_mfma_f32_32x32x16_bf16 v[32:47], v[128:131], v[60:63], v[32:47]
	v_exp_f32_e32 v202, v202
	v_exp_f32_e32 v203, v203
	v_cvt_pk_bf16_f32 v64, v188, v189
	v_cvt_pk_bf16_f32 v65, v190, v191
	v_cvt_pk_bf16_f32 v66, v192, v193
	v_cvt_pk_bf16_f32 v67, v194, v195
	v_cvt_pk_bf16_f32 v68, v196, v197
	v_cvt_pk_bf16_f32 v69, v198, v199
	v_cvt_pk_bf16_f32 v70, v200, v201
	v_cvt_pk_bf16_f32 v71, v202, v203
	v_pk_add_f32 v[232:233], v[232:233], v[188:189]
	v_pk_add_f32 v[232:233], v[232:233], v[190:191]
	v_pk_add_f32 v[232:233], v[232:233], v[192:193]
	v_pk_add_f32 v[232:233], v[232:233], v[194:195]
	v_pk_add_f32 v[232:233], v[232:233], v[196:197]
	v_pk_add_f32 v[232:233], v[232:233], v[198:199]
	v_pk_add_f32 v[232:233], v[232:233], v[200:201]
	v_pk_add_f32 v[232:233], v[232:233], v[202:203]
	ds_read2_b32 v[188:189], v115 offset0:68 offset1:69
	ds_read2_b32 v[190:191], v115 offset0:70 offset1:71
	ds_read2_b32 v[192:193], v115 offset0:76 offset1:77
	ds_read2_b32 v[194:195], v115 offset0:78 offset1:79
	ds_read2_b32 v[196:197], v115 offset0:85 offset1:86
	ds_read2_b32 v[198:199], v115 offset0:87 offset1:88
	ds_read2_b32 v[200:201], v115 offset0:93 offset1:94
	ds_read2_b32 v[202:203], v115 offset0:95 offset1:96
	v_mfma_f32_32x32x16_bf16 v[0:15], v[64:67], v[72:75], v[0:15]
	v_mfma_f32_32x32x16_bf16 v[16:31], v[64:67], v[76:79], v[16:31]
	v_mfma_f32_32x32x16_bf16 v[0:15], v[68:71], v[220:223], v[0:15]
	v_mfma_f32_32x32x16_bf16 v[16:31], v[68:71], v[224:227], v[16:31]
	global_load_dwordx4 v[116:119], v235, s[84:85]
	global_load_dwordx4 v[120:123], v236, s[84:85]
	global_load_dwordx4 v[124:127], v237, s[84:85]
	global_load_dwordx4 v[128:131], v238, s[84:85]
	global_load_dwordx4 v[132:135], v100, s[84:85] offset:768
	global_load_dwordx4 v[136:139], v149, s[84:85] offset:768
	global_load_dwordx4 v[140:143], v100, s[84:85] offset:832
	global_load_dwordx4 v[144:147], v149, s[84:85] offset:832
	s_add_u32 s84, s84, 0x30000
	s_addc_u32 s85, s85, 0
	ds_read_b64_tr_b16 v[72:73], v231
	ds_read_b64_tr_b16 v[74:75], v231 offset:512
	ds_read_b64_tr_b16 v[76:77], v231 offset:2048
	ds_read_b64_tr_b16 v[78:79], v231 offset:2560
	ds_read_b64_tr_b16 v[220:221], v231 offset:1024
	ds_read_b64_tr_b16 v[222:223], v231 offset:1536
	ds_read_b64_tr_b16 v[224:225], v231 offset:3072
	ds_read_b64_tr_b16 v[226:227], v231 offset:3584
	v_exp_f32_e32 v32, v32
	v_exp_f32_e32 v33, v33
	v_exp_f32_e32 v34, v34
	v_exp_f32_e32 v35, v35
	s_waitcnt vmcnt(8)
	ds_write_b128 v247, v[156:159]
	ds_write_b128 v247, v[160:163] offset:1024
	ds_write_b128 v247, v[164:167] offset:2048
	ds_write_b128 v247, v[168:171] offset:3072
	ds_read_b128 v[156:159], v248
	ds_read_b128 v[160:163], v249
	ds_read_b128 v[164:167], v250
	ds_read_b128 v[168:171], v251
	ds_write_b128 v112, v[172:175]
	ds_write_b128 v112, v[176:179] offset:1024
	ds_write_b128 v112, v[180:183] offset:2048
	ds_write_b128 v112, v[184:187] offset:3072
	v_exp_f32_e32 v36, v36
	v_exp_f32_e32 v37, v37
	v_exp_f32_e32 v38, v38
	v_exp_f32_e32 v39, v39
	s_waitcnt lgkmcnt(4)
	v_mfma_f32_32x32x16_bf16 v[188:203], v[156:159], v[48:51], v[188:203]
	v_exp_f32_e32 v40, v40
	v_exp_f32_e32 v41, v41
	v_mfma_f32_32x32x16_bf16 v[188:203], v[160:163], v[52:55], v[188:203]
	v_exp_f32_e32 v42, v42
	v_exp_f32_e32 v43, v43
	v_mfma_f32_32x32x16_bf16 v[188:203], v[164:167], v[56:59], v[188:203]
	v_exp_f32_e32 v44, v44
	v_exp_f32_e32 v45, v45
	v_mfma_f32_32x32x16_bf16 v[188:203], v[168:171], v[60:63], v[188:203]
	v_exp_f32_e32 v46, v46
	v_exp_f32_e32 v47, v47
	v_cvt_pk_bf16_f32 v64, v32, v33
	v_cvt_pk_bf16_f32 v65, v34, v35
	v_cvt_pk_bf16_f32 v66, v36, v37
	v_cvt_pk_bf16_f32 v67, v38, v39
	v_cvt_pk_bf16_f32 v68, v40, v41
	v_cvt_pk_bf16_f32 v69, v42, v43
	v_cvt_pk_bf16_f32 v70, v44, v45
	v_cvt_pk_bf16_f32 v71, v46, v47
	v_pk_add_f32 v[232:233], v[232:233], v[32:33]
	v_pk_add_f32 v[232:233], v[232:233], v[34:35]
	v_pk_add_f32 v[232:233], v[232:233], v[36:37]
	v_pk_add_f32 v[232:233], v[232:233], v[38:39]
	v_pk_add_f32 v[232:233], v[232:233], v[40:41]
	v_pk_add_f32 v[232:233], v[232:233], v[42:43]
	v_pk_add_f32 v[232:233], v[232:233], v[44:45]
	v_pk_add_f32 v[232:233], v[232:233], v[46:47]
	ds_read2_b32 v[32:33], v115 offset0:102 offset1:103
	ds_read2_b32 v[34:35], v115 offset0:104 offset1:105
	ds_read2_b32 v[36:37], v115 offset0:110 offset1:111
	ds_read2_b32 v[38:39], v115 offset0:112 offset1:113
	ds_read2_b32 v[40:41], v115 offset0:119 offset1:120
	ds_read2_b32 v[42:43], v115 offset0:121 offset1:122
	ds_read2_b32 v[44:45], v115 offset0:127 offset1:128
	ds_read2_b32 v[46:47], v115 offset0:129 offset1:130
	v_mfma_f32_32x32x16_bf16 v[0:15], v[64:67], v[72:75], v[0:15]
	v_mfma_f32_32x32x16_bf16 v[16:31], v[64:67], v[76:79], v[16:31]
	v_mfma_f32_32x32x16_bf16 v[0:15], v[68:71], v[220:223], v[0:15]
	v_mfma_f32_32x32x16_bf16 v[16:31], v[68:71], v[224:227], v[16:31]
	global_load_dwordx4 v[156:159], v235, s[84:85]
	global_load_dwordx4 v[160:163], v236, s[84:85]
	global_load_dwordx4 v[164:167], v237, s[84:85]
	global_load_dwordx4 v[168:171], v238, s[84:85]
	global_load_dwordx4 v[172:175], v100, s[84:85] offset:768
	global_load_dwordx4 v[176:179], v149, s[84:85] offset:768
	global_load_dwordx4 v[180:183], v100, s[84:85] offset:832
	global_load_dwordx4 v[184:187], v149, s[84:85] offset:832
	s_add_u32 s84, s84, 0x30000
	s_addc_u32 s85, s85, 0
	ds_read_b64_tr_b16 v[72:73], v231
	ds_read_b64_tr_b16 v[74:75], v231 offset:512
	ds_read_b64_tr_b16 v[76:77], v231 offset:2048
	ds_read_b64_tr_b16 v[78:79], v231 offset:2560
	ds_read_b64_tr_b16 v[220:221], v231 offset:1024
	ds_read_b64_tr_b16 v[222:223], v231 offset:1536
	ds_read_b64_tr_b16 v[224:225], v231 offset:3072
	ds_read_b64_tr_b16 v[226:227], v231 offset:3584
	v_exp_f32_e32 v188, v188
	v_exp_f32_e32 v189, v189
	v_exp_f32_e32 v190, v190
	v_exp_f32_e32 v191, v191
	s_waitcnt vmcnt(8)
	ds_write_b128 v247, v[116:119]
	ds_write_b128 v247, v[120:123] offset:1024
	ds_write_b128 v247, v[124:127] offset:2048
	ds_write_b128 v247, v[128:131] offset:3072
	ds_read_b128 v[116:119], v248
	ds_read_b128 v[120:123], v249
	ds_read_b128 v[124:127], v250
	ds_read_b128 v[128:131], v251
	ds_write_b128 v112, v[132:135]
	ds_write_b128 v112, v[136:139] offset:1024
	ds_write_b128 v112, v[140:143] offset:2048
	ds_write_b128 v112, v[144:147] offset:3072
	v_exp_f32_e32 v192, v192
	v_exp_f32_e32 v193, v193
	v_exp_f32_e32 v194, v194
	v_exp_f32_e32 v195, v195
	s_waitcnt lgkmcnt(4)
	v_mfma_f32_32x32x16_bf16 v[32:47], v[116:119], v[48:51], v[32:47]
	v_exp_f32_e32 v196, v196
	v_exp_f32_e32 v197, v197
	v_mfma_f32_32x32x16_bf16 v[32:47], v[120:123], v[52:55], v[32:47]
	v_exp_f32_e32 v198, v198
	v_exp_f32_e32 v199, v199
	v_mfma_f32_32x32x16_bf16 v[32:47], v[124:127], v[56:59], v[32:47]
	v_exp_f32_e32 v200, v200
	v_exp_f32_e32 v201, v201
	v_mfma_f32_32x32x16_bf16 v[32:47], v[128:131], v[60:63], v[32:47]
	v_exp_f32_e32 v202, v202
	v_exp_f32_e32 v203, v203
	v_cvt_pk_bf16_f32 v64, v188, v189
	v_cvt_pk_bf16_f32 v65, v190, v191
	v_cvt_pk_bf16_f32 v66, v192, v193
	v_cvt_pk_bf16_f32 v67, v194, v195
	v_cvt_pk_bf16_f32 v68, v196, v197
	v_cvt_pk_bf16_f32 v69, v198, v199
	v_cvt_pk_bf16_f32 v70, v200, v201
	v_cvt_pk_bf16_f32 v71, v202, v203
	v_pk_add_f32 v[232:233], v[232:233], v[188:189]
	v_pk_add_f32 v[232:233], v[232:233], v[190:191]
	v_pk_add_f32 v[232:233], v[232:233], v[192:193]
	v_pk_add_f32 v[232:233], v[232:233], v[194:195]
	v_pk_add_f32 v[232:233], v[232:233], v[196:197]
	v_pk_add_f32 v[232:233], v[232:233], v[198:199]
	v_pk_add_f32 v[232:233], v[232:233], v[200:201]
	v_pk_add_f32 v[232:233], v[232:233], v[202:203]
	ds_read2_b32 v[188:189], v115 offset0:136 offset1:137
	ds_read2_b32 v[190:191], v115 offset0:138 offset1:139
	ds_read2_b32 v[192:193], v115 offset0:144 offset1:145
	ds_read2_b32 v[194:195], v115 offset0:146 offset1:147
	ds_read2_b32 v[196:197], v115 offset0:153 offset1:154
	ds_read2_b32 v[198:199], v115 offset0:155 offset1:156
	ds_read2_b32 v[200:201], v115 offset0:161 offset1:162
	ds_read2_b32 v[202:203], v115 offset0:163 offset1:164
	v_mfma_f32_32x32x16_bf16 v[0:15], v[64:67], v[72:75], v[0:15]
	v_mfma_f32_32x32x16_bf16 v[16:31], v[64:67], v[76:79], v[16:31]
	v_mfma_f32_32x32x16_bf16 v[0:15], v[68:71], v[220:223], v[0:15]
	v_mfma_f32_32x32x16_bf16 v[16:31], v[68:71], v[224:227], v[16:31]
	global_load_dwordx4 v[116:119], v235, s[84:85]
	global_load_dwordx4 v[120:123], v236, s[84:85]
	global_load_dwordx4 v[124:127], v237, s[84:85]
	global_load_dwordx4 v[128:131], v238, s[84:85]
	global_load_dwordx4 v[132:135], v100, s[84:85] offset:768
	global_load_dwordx4 v[136:139], v149, s[84:85] offset:768
	global_load_dwordx4 v[140:143], v100, s[84:85] offset:832
	global_load_dwordx4 v[144:147], v149, s[84:85] offset:832
	s_add_u32 s84, s84, 0x30000
	s_addc_u32 s85, s85, 0
	ds_read_b64_tr_b16 v[72:73], v231
	ds_read_b64_tr_b16 v[74:75], v231 offset:512
	ds_read_b64_tr_b16 v[76:77], v231 offset:2048
	ds_read_b64_tr_b16 v[78:79], v231 offset:2560
	ds_read_b64_tr_b16 v[220:221], v231 offset:1024
	ds_read_b64_tr_b16 v[222:223], v231 offset:1536
	ds_read_b64_tr_b16 v[224:225], v231 offset:3072
	ds_read_b64_tr_b16 v[226:227], v231 offset:3584
	v_exp_f32_e32 v32, v32
	v_exp_f32_e32 v33, v33
	v_exp_f32_e32 v34, v34
	v_exp_f32_e32 v35, v35
	s_waitcnt vmcnt(8)
	ds_write_b128 v247, v[156:159]
	ds_write_b128 v247, v[160:163] offset:1024
	ds_write_b128 v247, v[164:167] offset:2048
	ds_write_b128 v247, v[168:171] offset:3072
	ds_read_b128 v[156:159], v248
	ds_read_b128 v[160:163], v249
	ds_read_b128 v[164:167], v250
	ds_read_b128 v[168:171], v251
	ds_write_b128 v112, v[172:175]
	ds_write_b128 v112, v[176:179] offset:1024
	ds_write_b128 v112, v[180:183] offset:2048
	ds_write_b128 v112, v[184:187] offset:3072
	v_exp_f32_e32 v36, v36
	v_exp_f32_e32 v37, v37
	v_exp_f32_e32 v38, v38
	v_exp_f32_e32 v39, v39
	s_waitcnt lgkmcnt(4)
	v_mfma_f32_32x32x16_bf16 v[188:203], v[156:159], v[48:51], v[188:203]
	v_exp_f32_e32 v40, v40
	v_exp_f32_e32 v41, v41
	v_mfma_f32_32x32x16_bf16 v[188:203], v[160:163], v[52:55], v[188:203]
	v_exp_f32_e32 v42, v42
	v_exp_f32_e32 v43, v43
	v_mfma_f32_32x32x16_bf16 v[188:203], v[164:167], v[56:59], v[188:203]
	v_exp_f32_e32 v44, v44
	v_exp_f32_e32 v45, v45
	v_mfma_f32_32x32x16_bf16 v[188:203], v[168:171], v[60:63], v[188:203]
	v_exp_f32_e32 v46, v46
	v_exp_f32_e32 v47, v47
	v_cvt_pk_bf16_f32 v64, v32, v33
	v_cvt_pk_bf16_f32 v65, v34, v35
	v_cvt_pk_bf16_f32 v66, v36, v37
	v_cvt_pk_bf16_f32 v67, v38, v39
	v_cvt_pk_bf16_f32 v68, v40, v41
	v_cvt_pk_bf16_f32 v69, v42, v43
	v_cvt_pk_bf16_f32 v70, v44, v45
	v_cvt_pk_bf16_f32 v71, v46, v47
	v_pk_add_f32 v[232:233], v[232:233], v[32:33]
	v_pk_add_f32 v[232:233], v[232:233], v[34:35]
	v_pk_add_f32 v[232:233], v[232:233], v[36:37]
	v_pk_add_f32 v[232:233], v[232:233], v[38:39]
	v_pk_add_f32 v[232:233], v[232:233], v[40:41]
	v_pk_add_f32 v[232:233], v[232:233], v[42:43]
	v_pk_add_f32 v[232:233], v[232:233], v[44:45]
	v_pk_add_f32 v[232:233], v[232:233], v[46:47]
	ds_read2_b32 v[32:33], v115 offset0:170 offset1:171
	ds_read2_b32 v[34:35], v115 offset0:172 offset1:173
	ds_read2_b32 v[36:37], v115 offset0:178 offset1:179
	ds_read2_b32 v[38:39], v115 offset0:180 offset1:181
	ds_read2_b32 v[40:41], v115 offset0:187 offset1:188
	ds_read2_b32 v[42:43], v115 offset0:189 offset1:190
	ds_read2_b32 v[44:45], v115 offset0:195 offset1:196
	ds_read2_b32 v[46:47], v115 offset0:197 offset1:198
	v_mfma_f32_32x32x16_bf16 v[0:15], v[64:67], v[72:75], v[0:15]
	v_mfma_f32_32x32x16_bf16 v[16:31], v[64:67], v[76:79], v[16:31]
	v_mfma_f32_32x32x16_bf16 v[0:15], v[68:71], v[220:223], v[0:15]
	v_mfma_f32_32x32x16_bf16 v[16:31], v[68:71], v[224:227], v[16:31]
	global_load_dwordx4 v[156:159], v235, s[84:85]
	global_load_dwordx4 v[160:163], v236, s[84:85]
	global_load_dwordx4 v[164:167], v237, s[84:85]
	global_load_dwordx4 v[168:171], v238, s[84:85]
	global_load_dwordx4 v[172:175], v100, s[84:85] offset:768
	global_load_dwordx4 v[176:179], v149, s[84:85] offset:768
	global_load_dwordx4 v[180:183], v100, s[84:85] offset:832
	global_load_dwordx4 v[184:187], v149, s[84:85] offset:832
	s_add_u32 s84, s84, 0x30000
	s_addc_u32 s85, s85, 0
	ds_read_b64_tr_b16 v[72:73], v231
	ds_read_b64_tr_b16 v[74:75], v231 offset:512
	ds_read_b64_tr_b16 v[76:77], v231 offset:2048
	ds_read_b64_tr_b16 v[78:79], v231 offset:2560
	ds_read_b64_tr_b16 v[220:221], v231 offset:1024
	ds_read_b64_tr_b16 v[222:223], v231 offset:1536
	ds_read_b64_tr_b16 v[224:225], v231 offset:3072
	ds_read_b64_tr_b16 v[226:227], v231 offset:3584
	v_exp_f32_e32 v188, v188
	v_exp_f32_e32 v189, v189
	v_exp_f32_e32 v190, v190
	v_exp_f32_e32 v191, v191
	s_waitcnt vmcnt(8)
	ds_write_b128 v247, v[116:119]
	ds_write_b128 v247, v[120:123] offset:1024
	ds_write_b128 v247, v[124:127] offset:2048
	ds_write_b128 v247, v[128:131] offset:3072
	ds_read_b128 v[116:119], v248
	ds_read_b128 v[120:123], v249
	ds_read_b128 v[124:127], v250
	ds_read_b128 v[128:131], v251
	ds_write_b128 v112, v[132:135]
	ds_write_b128 v112, v[136:139] offset:1024
	ds_write_b128 v112, v[140:143] offset:2048
	ds_write_b128 v112, v[144:147] offset:3072
	v_exp_f32_e32 v192, v192
	v_exp_f32_e32 v193, v193
	v_exp_f32_e32 v194, v194
	v_exp_f32_e32 v195, v195
	s_waitcnt lgkmcnt(4)
	v_mfma_f32_32x32x16_bf16 v[32:47], v[116:119], v[48:51], v[32:47]
	v_exp_f32_e32 v196, v196
	v_exp_f32_e32 v197, v197
	v_mfma_f32_32x32x16_bf16 v[32:47], v[120:123], v[52:55], v[32:47]
	v_exp_f32_e32 v198, v198
	v_exp_f32_e32 v199, v199
	v_mfma_f32_32x32x16_bf16 v[32:47], v[124:127], v[56:59], v[32:47]
	v_exp_f32_e32 v200, v200
	v_exp_f32_e32 v201, v201
	v_mfma_f32_32x32x16_bf16 v[32:47], v[128:131], v[60:63], v[32:47]
	v_exp_f32_e32 v202, v202
	v_exp_f32_e32 v203, v203
	v_cvt_pk_bf16_f32 v64, v188, v189
	v_cvt_pk_bf16_f32 v65, v190, v191
	v_cvt_pk_bf16_f32 v66, v192, v193
	v_cvt_pk_bf16_f32 v67, v194, v195
	v_cvt_pk_bf16_f32 v68, v196, v197
	v_cvt_pk_bf16_f32 v69, v198, v199
	v_cvt_pk_bf16_f32 v70, v200, v201
	v_cvt_pk_bf16_f32 v71, v202, v203
	v_pk_add_f32 v[232:233], v[232:233], v[188:189]
	v_pk_add_f32 v[232:233], v[232:233], v[190:191]
	v_pk_add_f32 v[232:233], v[232:233], v[192:193]
	v_pk_add_f32 v[232:233], v[232:233], v[194:195]
	v_pk_add_f32 v[232:233], v[232:233], v[196:197]
	v_pk_add_f32 v[232:233], v[232:233], v[198:199]
	v_pk_add_f32 v[232:233], v[232:233], v[200:201]
	v_pk_add_f32 v[232:233], v[232:233], v[202:203]
	ds_read2_b32 v[188:189], v115 offset0:204 offset1:205
	ds_read2_b32 v[190:191], v115 offset0:206 offset1:207
	ds_read2_b32 v[192:193], v115 offset0:212 offset1:213
	ds_read2_b32 v[194:195], v115 offset0:214 offset1:215
	ds_read2_b32 v[196:197], v115 offset0:221 offset1:222
	ds_read2_b32 v[198:199], v115 offset0:223 offset1:224
	ds_read2_b32 v[200:201], v115 offset0:229 offset1:230
	ds_read2_b32 v[202:203], v115 offset0:231 offset1:232
	v_mfma_f32_32x32x16_bf16 v[0:15], v[64:67], v[72:75], v[0:15]
	v_mfma_f32_32x32x16_bf16 v[16:31], v[64:67], v[76:79], v[16:31]
	v_mfma_f32_32x32x16_bf16 v[0:15], v[68:71], v[220:223], v[0:15]
	v_mfma_f32_32x32x16_bf16 v[16:31], v[68:71], v[224:227], v[16:31]
	global_load_dwordx4 v[116:119], v235, s[84:85]
	global_load_dwordx4 v[120:123], v236, s[84:85]
	global_load_dwordx4 v[124:127], v237, s[84:85]
	global_load_dwordx4 v[128:131], v238, s[84:85]
	global_load_dwordx4 v[132:135], v100, s[84:85] offset:768
	global_load_dwordx4 v[136:139], v149, s[84:85] offset:768
	global_load_dwordx4 v[140:143], v100, s[84:85] offset:832
	global_load_dwordx4 v[144:147], v149, s[84:85] offset:832
	s_add_u32 s84, s84, 0x30000
	s_addc_u32 s85, s85, 0
	ds_read_b64_tr_b16 v[72:73], v231
	ds_read_b64_tr_b16 v[74:75], v231 offset:512
	ds_read_b64_tr_b16 v[76:77], v231 offset:2048
	ds_read_b64_tr_b16 v[78:79], v231 offset:2560
	ds_read_b64_tr_b16 v[220:221], v231 offset:1024
	ds_read_b64_tr_b16 v[222:223], v231 offset:1536
	ds_read_b64_tr_b16 v[224:225], v231 offset:3072
	ds_read_b64_tr_b16 v[226:227], v231 offset:3584
	v_exp_f32_e32 v32, v32
	v_exp_f32_e32 v33, v33
	v_exp_f32_e32 v34, v34
	v_exp_f32_e32 v35, v35
	s_waitcnt vmcnt(8)
	ds_write_b128 v247, v[156:159]
	ds_write_b128 v247, v[160:163] offset:1024
	ds_write_b128 v247, v[164:167] offset:2048
	ds_write_b128 v247, v[168:171] offset:3072
	ds_read_b128 v[156:159], v248
	ds_read_b128 v[160:163], v249
	ds_read_b128 v[164:167], v250
	ds_read_b128 v[168:171], v251
	ds_write_b128 v112, v[172:175]
	ds_write_b128 v112, v[176:179] offset:1024
	ds_write_b128 v112, v[180:183] offset:2048
	ds_write_b128 v112, v[184:187] offset:3072
	v_exp_f32_e32 v36, v36
	v_exp_f32_e32 v37, v37
	v_exp_f32_e32 v38, v38
	v_exp_f32_e32 v39, v39
	s_waitcnt lgkmcnt(4)
	v_mfma_f32_32x32x16_bf16 v[188:203], v[156:159], v[48:51], v[188:203]
	v_exp_f32_e32 v40, v40
	v_exp_f32_e32 v41, v41
	v_mfma_f32_32x32x16_bf16 v[188:203], v[160:163], v[52:55], v[188:203]
	v_exp_f32_e32 v42, v42
	v_exp_f32_e32 v43, v43
	v_mfma_f32_32x32x16_bf16 v[188:203], v[164:167], v[56:59], v[188:203]
	v_exp_f32_e32 v44, v44
	v_exp_f32_e32 v45, v45
	v_mfma_f32_32x32x16_bf16 v[188:203], v[168:171], v[60:63], v[188:203]
	v_exp_f32_e32 v46, v46
	v_exp_f32_e32 v47, v47
	v_cvt_pk_bf16_f32 v64, v32, v33
	v_cvt_pk_bf16_f32 v65, v34, v35
	v_cvt_pk_bf16_f32 v66, v36, v37
	v_cvt_pk_bf16_f32 v67, v38, v39
	v_cvt_pk_bf16_f32 v68, v40, v41
	v_cvt_pk_bf16_f32 v69, v42, v43
	v_cvt_pk_bf16_f32 v70, v44, v45
	v_cvt_pk_bf16_f32 v71, v46, v47
	v_pk_add_f32 v[232:233], v[232:233], v[32:33]
	v_pk_add_f32 v[232:233], v[232:233], v[34:35]
	v_pk_add_f32 v[232:233], v[232:233], v[36:37]
	v_pk_add_f32 v[232:233], v[232:233], v[38:39]
	v_pk_add_f32 v[232:233], v[232:233], v[40:41]
	v_pk_add_f32 v[232:233], v[232:233], v[42:43]
	v_pk_add_f32 v[232:233], v[232:233], v[44:45]
	v_pk_add_f32 v[232:233], v[232:233], v[46:47]
	v_add_u32_e32 v115, 952, v115
	ds_read2_b32 v[32:33], v115 offset0:0 offset1:1
	ds_read2_b32 v[34:35], v115 offset0:2 offset1:3
	ds_read2_b32 v[36:37], v115 offset0:8 offset1:9
	ds_read2_b32 v[38:39], v115 offset0:10 offset1:11
	ds_read2_b32 v[40:41], v115 offset0:17 offset1:18
	ds_read2_b32 v[42:43], v115 offset0:19 offset1:20
	ds_read2_b32 v[44:45], v115 offset0:25 offset1:26
	ds_read2_b32 v[46:47], v115 offset0:27 offset1:28
	v_mfma_f32_32x32x16_bf16 v[0:15], v[64:67], v[72:75], v[0:15]
	v_mfma_f32_32x32x16_bf16 v[16:31], v[64:67], v[76:79], v[16:31]
	v_mfma_f32_32x32x16_bf16 v[0:15], v[68:71], v[220:223], v[0:15]
	v_mfma_f32_32x32x16_bf16 v[16:31], v[68:71], v[224:227], v[16:31]
	global_load_dwordx4 v[156:159], v235, s[84:85]
	global_load_dwordx4 v[160:163], v236, s[84:85]
	global_load_dwordx4 v[164:167], v237, s[84:85]
	global_load_dwordx4 v[168:171], v238, s[84:85]
	global_load_dwordx4 v[172:175], v100, s[84:85] offset:768
	global_load_dwordx4 v[176:179], v149, s[84:85] offset:768
	global_load_dwordx4 v[180:183], v100, s[84:85] offset:832
	global_load_dwordx4 v[184:187], v149, s[84:85] offset:832
	s_add_u32 s84, s84, 0x30000
	s_addc_u32 s85, s85, 0
	ds_read_b64_tr_b16 v[72:73], v231
	ds_read_b64_tr_b16 v[74:75], v231 offset:512
	ds_read_b64_tr_b16 v[76:77], v231 offset:2048
	ds_read_b64_tr_b16 v[78:79], v231 offset:2560
	ds_read_b64_tr_b16 v[220:221], v231 offset:1024
	ds_read_b64_tr_b16 v[222:223], v231 offset:1536
	ds_read_b64_tr_b16 v[224:225], v231 offset:3072
	ds_read_b64_tr_b16 v[226:227], v231 offset:3584
	v_exp_f32_e32 v188, v188
	v_exp_f32_e32 v189, v189
	v_exp_f32_e32 v190, v190
	v_exp_f32_e32 v191, v191
	s_waitcnt vmcnt(8)
	ds_write_b128 v247, v[116:119]
	ds_write_b128 v247, v[120:123] offset:1024
	ds_write_b128 v247, v[124:127] offset:2048
	ds_write_b128 v247, v[128:131] offset:3072
	ds_read_b128 v[116:119], v248
	ds_read_b128 v[120:123], v249
	ds_read_b128 v[124:127], v250
	ds_read_b128 v[128:131], v251
	ds_write_b128 v112, v[132:135]
	ds_write_b128 v112, v[136:139] offset:1024
	ds_write_b128 v112, v[140:143] offset:2048
	ds_write_b128 v112, v[144:147] offset:3072
	v_exp_f32_e32 v192, v192
	v_exp_f32_e32 v193, v193
	v_exp_f32_e32 v194, v194
	v_exp_f32_e32 v195, v195
	s_waitcnt lgkmcnt(4)
	v_mfma_f32_32x32x16_bf16 v[32:47], v[116:119], v[48:51], v[32:47]
	v_exp_f32_e32 v196, v196
	v_exp_f32_e32 v197, v197
	v_mfma_f32_32x32x16_bf16 v[32:47], v[120:123], v[52:55], v[32:47]
	v_exp_f32_e32 v198, v198
	v_exp_f32_e32 v199, v199
	v_mfma_f32_32x32x16_bf16 v[32:47], v[124:127], v[56:59], v[32:47]
	v_exp_f32_e32 v200, v200
	v_exp_f32_e32 v201, v201
	v_mfma_f32_32x32x16_bf16 v[32:47], v[128:131], v[60:63], v[32:47]
	v_exp_f32_e32 v202, v202
	v_exp_f32_e32 v203, v203
	v_cvt_pk_bf16_f32 v64, v188, v189
	v_cvt_pk_bf16_f32 v65, v190, v191
	v_cvt_pk_bf16_f32 v66, v192, v193
	v_cvt_pk_bf16_f32 v67, v194, v195
	v_cvt_pk_bf16_f32 v68, v196, v197
	v_cvt_pk_bf16_f32 v69, v198, v199
	v_cvt_pk_bf16_f32 v70, v200, v201
	v_cvt_pk_bf16_f32 v71, v202, v203
	v_pk_add_f32 v[232:233], v[232:233], v[188:189]
	v_pk_add_f32 v[232:233], v[232:233], v[190:191]
	v_pk_add_f32 v[232:233], v[232:233], v[192:193]
	v_pk_add_f32 v[232:233], v[232:233], v[194:195]
	v_pk_add_f32 v[232:233], v[232:233], v[196:197]
	v_pk_add_f32 v[232:233], v[232:233], v[198:199]
	v_pk_add_f32 v[232:233], v[232:233], v[200:201]
	v_pk_add_f32 v[232:233], v[232:233], v[202:203]
	ds_read2_b32 v[188:189], v115 offset0:34 offset1:35
	ds_read2_b32 v[190:191], v115 offset0:36 offset1:37
	ds_read2_b32 v[192:193], v115 offset0:42 offset1:43
	ds_read2_b32 v[194:195], v115 offset0:44 offset1:45
	ds_read2_b32 v[196:197], v115 offset0:51 offset1:52
	ds_read2_b32 v[198:199], v115 offset0:53 offset1:54
	ds_read2_b32 v[200:201], v115 offset0:59 offset1:60
	ds_read2_b32 v[202:203], v115 offset0:61 offset1:62
	v_mfma_f32_32x32x16_bf16 v[0:15], v[64:67], v[72:75], v[0:15]
	v_mfma_f32_32x32x16_bf16 v[16:31], v[64:67], v[76:79], v[16:31]
	v_mfma_f32_32x32x16_bf16 v[0:15], v[68:71], v[220:223], v[0:15]
	v_mfma_f32_32x32x16_bf16 v[16:31], v[68:71], v[224:227], v[16:31]
	global_load_dwordx4 v[116:119], v235, s[84:85]
	global_load_dwordx4 v[120:123], v236, s[84:85]
	global_load_dwordx4 v[124:127], v237, s[84:85]
	global_load_dwordx4 v[128:131], v238, s[84:85]
	global_load_dwordx4 v[132:135], v100, s[84:85] offset:768
	global_load_dwordx4 v[136:139], v149, s[84:85] offset:768
	global_load_dwordx4 v[140:143], v100, s[84:85] offset:832
	global_load_dwordx4 v[144:147], v149, s[84:85] offset:832
	s_add_u32 s84, s84, 0x30000
	s_addc_u32 s85, s85, 0
	ds_read_b64_tr_b16 v[72:73], v231
	ds_read_b64_tr_b16 v[74:75], v231 offset:512
	ds_read_b64_tr_b16 v[76:77], v231 offset:2048
	ds_read_b64_tr_b16 v[78:79], v231 offset:2560
	ds_read_b64_tr_b16 v[220:221], v231 offset:1024
	ds_read_b64_tr_b16 v[222:223], v231 offset:1536
	ds_read_b64_tr_b16 v[224:225], v231 offset:3072
	ds_read_b64_tr_b16 v[226:227], v231 offset:3584
	v_exp_f32_e32 v32, v32
	v_exp_f32_e32 v33, v33
	v_exp_f32_e32 v34, v34
	v_exp_f32_e32 v35, v35
	s_waitcnt vmcnt(8)
	ds_write_b128 v247, v[156:159]
	ds_write_b128 v247, v[160:163] offset:1024
	ds_write_b128 v247, v[164:167] offset:2048
	ds_write_b128 v247, v[168:171] offset:3072
	ds_read_b128 v[156:159], v248
	ds_read_b128 v[160:163], v249
	ds_read_b128 v[164:167], v250
	ds_read_b128 v[168:171], v251
	ds_write_b128 v112, v[172:175]
	ds_write_b128 v112, v[176:179] offset:1024
	ds_write_b128 v112, v[180:183] offset:2048
	ds_write_b128 v112, v[184:187] offset:3072
	v_exp_f32_e32 v36, v36
	v_exp_f32_e32 v37, v37
	v_exp_f32_e32 v38, v38
	v_exp_f32_e32 v39, v39
	s_waitcnt lgkmcnt(4)
	v_mfma_f32_32x32x16_bf16 v[188:203], v[156:159], v[48:51], v[188:203]
	v_exp_f32_e32 v40, v40
	v_exp_f32_e32 v41, v41
	v_mfma_f32_32x32x16_bf16 v[188:203], v[160:163], v[52:55], v[188:203]
	v_exp_f32_e32 v42, v42
	v_exp_f32_e32 v43, v43
	v_mfma_f32_32x32x16_bf16 v[188:203], v[164:167], v[56:59], v[188:203]
	v_exp_f32_e32 v44, v44
	v_exp_f32_e32 v45, v45
	v_mfma_f32_32x32x16_bf16 v[188:203], v[168:171], v[60:63], v[188:203]
	v_exp_f32_e32 v46, v46
	v_exp_f32_e32 v47, v47
	v_cvt_pk_bf16_f32 v64, v32, v33
	v_cvt_pk_bf16_f32 v65, v34, v35
	v_cvt_pk_bf16_f32 v66, v36, v37
	v_cvt_pk_bf16_f32 v67, v38, v39
	v_cvt_pk_bf16_f32 v68, v40, v41
	v_cvt_pk_bf16_f32 v69, v42, v43
	v_cvt_pk_bf16_f32 v70, v44, v45
	v_cvt_pk_bf16_f32 v71, v46, v47
	v_pk_add_f32 v[232:233], v[232:233], v[32:33]
	v_pk_add_f32 v[232:233], v[232:233], v[34:35]
	v_pk_add_f32 v[232:233], v[232:233], v[36:37]
	v_pk_add_f32 v[232:233], v[232:233], v[38:39]
	v_pk_add_f32 v[232:233], v[232:233], v[40:41]
	v_pk_add_f32 v[232:233], v[232:233], v[42:43]
	v_pk_add_f32 v[232:233], v[232:233], v[44:45]
	v_pk_add_f32 v[232:233], v[232:233], v[46:47]
	ds_read2_b32 v[32:33], v115 offset0:68 offset1:69
	ds_read2_b32 v[34:35], v115 offset0:70 offset1:71
	ds_read2_b32 v[36:37], v115 offset0:76 offset1:77
	ds_read2_b32 v[38:39], v115 offset0:78 offset1:79
	ds_read2_b32 v[40:41], v115 offset0:85 offset1:86
	ds_read2_b32 v[42:43], v115 offset0:87 offset1:88
	ds_read2_b32 v[44:45], v115 offset0:93 offset1:94
	ds_read2_b32 v[46:47], v115 offset0:95 offset1:96
	v_mfma_f32_32x32x16_bf16 v[0:15], v[64:67], v[72:75], v[0:15]
	v_mfma_f32_32x32x16_bf16 v[16:31], v[64:67], v[76:79], v[16:31]
	v_mfma_f32_32x32x16_bf16 v[0:15], v[68:71], v[220:223], v[0:15]
	v_mfma_f32_32x32x16_bf16 v[16:31], v[68:71], v[224:227], v[16:31]
	global_load_dwordx4 v[156:159], v235, s[84:85]
	global_load_dwordx4 v[160:163], v236, s[84:85]
	global_load_dwordx4 v[164:167], v237, s[84:85]
	global_load_dwordx4 v[168:171], v238, s[84:85]
	global_load_dwordx4 v[172:175], v100, s[84:85] offset:768
	global_load_dwordx4 v[176:179], v149, s[84:85] offset:768
	global_load_dwordx4 v[180:183], v100, s[84:85] offset:832
	global_load_dwordx4 v[184:187], v149, s[84:85] offset:832
	s_add_u32 s84, s84, 0x30000
	s_addc_u32 s85, s85, 0
	ds_read_b64_tr_b16 v[72:73], v231
	ds_read_b64_tr_b16 v[74:75], v231 offset:512
	ds_read_b64_tr_b16 v[76:77], v231 offset:2048
	ds_read_b64_tr_b16 v[78:79], v231 offset:2560
	ds_read_b64_tr_b16 v[220:221], v231 offset:1024
	ds_read_b64_tr_b16 v[222:223], v231 offset:1536
	ds_read_b64_tr_b16 v[224:225], v231 offset:3072
	ds_read_b64_tr_b16 v[226:227], v231 offset:3584
	v_exp_f32_e32 v188, v188
	v_exp_f32_e32 v189, v189
	v_exp_f32_e32 v190, v190
	v_exp_f32_e32 v191, v191
	s_waitcnt vmcnt(8)
	ds_write_b128 v247, v[116:119]
	ds_write_b128 v247, v[120:123] offset:1024
	ds_write_b128 v247, v[124:127] offset:2048
	ds_write_b128 v247, v[128:131] offset:3072
	ds_read_b128 v[116:119], v248
	ds_read_b128 v[120:123], v249
	ds_read_b128 v[124:127], v250
	ds_read_b128 v[128:131], v251
	ds_write_b128 v112, v[132:135]
	ds_write_b128 v112, v[136:139] offset:1024
	ds_write_b128 v112, v[140:143] offset:2048
	ds_write_b128 v112, v[144:147] offset:3072
	v_exp_f32_e32 v192, v192
	v_exp_f32_e32 v193, v193
	v_exp_f32_e32 v194, v194
	v_exp_f32_e32 v195, v195
	s_waitcnt lgkmcnt(4)
	v_mfma_f32_32x32x16_bf16 v[32:47], v[116:119], v[48:51], v[32:47]
	v_exp_f32_e32 v196, v196
	v_exp_f32_e32 v197, v197
	v_mfma_f32_32x32x16_bf16 v[32:47], v[120:123], v[52:55], v[32:47]
	v_exp_f32_e32 v198, v198
	v_exp_f32_e32 v199, v199
	v_mfma_f32_32x32x16_bf16 v[32:47], v[124:127], v[56:59], v[32:47]
	v_exp_f32_e32 v200, v200
	v_exp_f32_e32 v201, v201
	v_mfma_f32_32x32x16_bf16 v[32:47], v[128:131], v[60:63], v[32:47]
	v_exp_f32_e32 v202, v202
	v_exp_f32_e32 v203, v203
	v_cvt_pk_bf16_f32 v64, v188, v189
	v_cvt_pk_bf16_f32 v65, v190, v191
	v_cvt_pk_bf16_f32 v66, v192, v193
	v_cvt_pk_bf16_f32 v67, v194, v195
	v_cvt_pk_bf16_f32 v68, v196, v197
	v_cvt_pk_bf16_f32 v69, v198, v199
	v_cvt_pk_bf16_f32 v70, v200, v201
	v_cvt_pk_bf16_f32 v71, v202, v203
	v_pk_add_f32 v[232:233], v[232:233], v[188:189]
	v_pk_add_f32 v[232:233], v[232:233], v[190:191]
	v_pk_add_f32 v[232:233], v[232:233], v[192:193]
	v_pk_add_f32 v[232:233], v[232:233], v[194:195]
	v_pk_add_f32 v[232:233], v[232:233], v[196:197]
	v_pk_add_f32 v[232:233], v[232:233], v[198:199]
	v_pk_add_f32 v[232:233], v[232:233], v[200:201]
	v_pk_add_f32 v[232:233], v[232:233], v[202:203]
	ds_read2_b32 v[188:189], v115 offset0:102 offset1:103
	ds_read2_b32 v[190:191], v115 offset0:104 offset1:105
	ds_read2_b32 v[192:193], v115 offset0:110 offset1:111
	ds_read2_b32 v[194:195], v115 offset0:112 offset1:113
	ds_read2_b32 v[196:197], v115 offset0:119 offset1:120
	ds_read2_b32 v[198:199], v115 offset0:121 offset1:122
	ds_read2_b32 v[200:201], v115 offset0:127 offset1:128
	ds_read2_b32 v[202:203], v115 offset0:129 offset1:130
	v_mfma_f32_32x32x16_bf16 v[0:15], v[64:67], v[72:75], v[0:15]
	v_mfma_f32_32x32x16_bf16 v[16:31], v[64:67], v[76:79], v[16:31]
	v_mfma_f32_32x32x16_bf16 v[0:15], v[68:71], v[220:223], v[0:15]
	v_mfma_f32_32x32x16_bf16 v[16:31], v[68:71], v[224:227], v[16:31]
	global_load_dwordx4 v[116:119], v235, s[84:85]
	global_load_dwordx4 v[120:123], v236, s[84:85]
	global_load_dwordx4 v[124:127], v237, s[84:85]
	global_load_dwordx4 v[128:131], v238, s[84:85]
	global_load_dwordx4 v[132:135], v100, s[84:85] offset:768
	global_load_dwordx4 v[136:139], v149, s[84:85] offset:768
	global_load_dwordx4 v[140:143], v100, s[84:85] offset:832
	global_load_dwordx4 v[144:147], v149, s[84:85] offset:832
	s_add_u32 s84, s84, 0x30000
	s_addc_u32 s85, s85, 0
	ds_read_b64_tr_b16 v[72:73], v231
	ds_read_b64_tr_b16 v[74:75], v231 offset:512
	ds_read_b64_tr_b16 v[76:77], v231 offset:2048
	ds_read_b64_tr_b16 v[78:79], v231 offset:2560
	ds_read_b64_tr_b16 v[220:221], v231 offset:1024
	ds_read_b64_tr_b16 v[222:223], v231 offset:1536
	ds_read_b64_tr_b16 v[224:225], v231 offset:3072
	ds_read_b64_tr_b16 v[226:227], v231 offset:3584
	v_exp_f32_e32 v32, v32
	v_exp_f32_e32 v33, v33
	v_exp_f32_e32 v34, v34
	v_exp_f32_e32 v35, v35
	s_waitcnt vmcnt(8)
	ds_write_b128 v247, v[156:159]
	ds_write_b128 v247, v[160:163] offset:1024
	ds_write_b128 v247, v[164:167] offset:2048
	ds_write_b128 v247, v[168:171] offset:3072
	ds_read_b128 v[156:159], v248
	ds_read_b128 v[160:163], v249
	ds_read_b128 v[164:167], v250
	ds_read_b128 v[168:171], v251
	ds_write_b128 v112, v[172:175]
	ds_write_b128 v112, v[176:179] offset:1024
	ds_write_b128 v112, v[180:183] offset:2048
	ds_write_b128 v112, v[184:187] offset:3072
	v_exp_f32_e32 v36, v36
	v_exp_f32_e32 v37, v37
	v_exp_f32_e32 v38, v38
	v_exp_f32_e32 v39, v39
	s_waitcnt lgkmcnt(4)
	v_mfma_f32_32x32x16_bf16 v[188:203], v[156:159], v[48:51], v[188:203]
	v_exp_f32_e32 v40, v40
	v_exp_f32_e32 v41, v41
	v_mfma_f32_32x32x16_bf16 v[188:203], v[160:163], v[52:55], v[188:203]
	v_exp_f32_e32 v42, v42
	v_exp_f32_e32 v43, v43
	v_mfma_f32_32x32x16_bf16 v[188:203], v[164:167], v[56:59], v[188:203]
	v_exp_f32_e32 v44, v44
	v_exp_f32_e32 v45, v45
	v_mfma_f32_32x32x16_bf16 v[188:203], v[168:171], v[60:63], v[188:203]
	v_exp_f32_e32 v46, v46
	v_exp_f32_e32 v47, v47
	v_cvt_pk_bf16_f32 v64, v32, v33
	v_cvt_pk_bf16_f32 v65, v34, v35
	v_cvt_pk_bf16_f32 v66, v36, v37
	v_cvt_pk_bf16_f32 v67, v38, v39
	v_cvt_pk_bf16_f32 v68, v40, v41
	v_cvt_pk_bf16_f32 v69, v42, v43
	v_cvt_pk_bf16_f32 v70, v44, v45
	v_cvt_pk_bf16_f32 v71, v46, v47
	v_pk_add_f32 v[232:233], v[232:233], v[32:33]
	v_pk_add_f32 v[232:233], v[232:233], v[34:35]
	v_pk_add_f32 v[232:233], v[232:233], v[36:37]
	v_pk_add_f32 v[232:233], v[232:233], v[38:39]
	v_pk_add_f32 v[232:233], v[232:233], v[40:41]
	v_pk_add_f32 v[232:233], v[232:233], v[42:43]
	v_pk_add_f32 v[232:233], v[232:233], v[44:45]
	v_pk_add_f32 v[232:233], v[232:233], v[46:47]
	ds_read2_b32 v[32:33], v115 offset0:136 offset1:137
	ds_read2_b32 v[34:35], v115 offset0:138 offset1:139
	ds_read2_b32 v[36:37], v115 offset0:144 offset1:145
	ds_read2_b32 v[38:39], v115 offset0:146 offset1:147
	ds_read2_b32 v[40:41], v115 offset0:153 offset1:154
	ds_read2_b32 v[42:43], v115 offset0:155 offset1:156
	ds_read2_b32 v[44:45], v115 offset0:161 offset1:162
	ds_read2_b32 v[46:47], v115 offset0:163 offset1:164
	v_mfma_f32_32x32x16_bf16 v[0:15], v[64:67], v[72:75], v[0:15]
	v_mfma_f32_32x32x16_bf16 v[16:31], v[64:67], v[76:79], v[16:31]
	v_mfma_f32_32x32x16_bf16 v[0:15], v[68:71], v[220:223], v[0:15]
	v_mfma_f32_32x32x16_bf16 v[16:31], v[68:71], v[224:227], v[16:31]
	global_load_dwordx4 v[156:159], v235, s[84:85]
	global_load_dwordx4 v[160:163], v236, s[84:85]
	global_load_dwordx4 v[164:167], v237, s[84:85]
	global_load_dwordx4 v[168:171], v238, s[84:85]
	global_load_dwordx4 v[172:175], v100, s[84:85] offset:768
	global_load_dwordx4 v[176:179], v149, s[84:85] offset:768
	global_load_dwordx4 v[180:183], v100, s[84:85] offset:832
	global_load_dwordx4 v[184:187], v149, s[84:85] offset:832
	ds_read_b64_tr_b16 v[72:73], v231
	ds_read_b64_tr_b16 v[74:75], v231 offset:512
	ds_read_b64_tr_b16 v[76:77], v231 offset:2048
	ds_read_b64_tr_b16 v[78:79], v231 offset:2560
	ds_read_b64_tr_b16 v[220:221], v231 offset:1024
	ds_read_b64_tr_b16 v[222:223], v231 offset:1536
	ds_read_b64_tr_b16 v[224:225], v231 offset:3072
	ds_read_b64_tr_b16 v[226:227], v231 offset:3584
	v_exp_f32_e32 v188, v188
	v_exp_f32_e32 v189, v189
	v_exp_f32_e32 v190, v190
	v_exp_f32_e32 v191, v191
	s_waitcnt vmcnt(8)
	ds_write_b128 v247, v[116:119]
	ds_write_b128 v247, v[120:123] offset:1024
	ds_write_b128 v247, v[124:127] offset:2048
	ds_write_b128 v247, v[128:131] offset:3072
	ds_read_b128 v[116:119], v248
	ds_read_b128 v[120:123], v249
	ds_read_b128 v[124:127], v250
	ds_read_b128 v[128:131], v251
	ds_write_b128 v112, v[132:135]
	ds_write_b128 v112, v[136:139] offset:1024
	ds_write_b128 v112, v[140:143] offset:2048
	ds_write_b128 v112, v[144:147] offset:3072
	v_exp_f32_e32 v192, v192
	v_exp_f32_e32 v193, v193
	v_exp_f32_e32 v194, v194
	v_exp_f32_e32 v195, v195
	s_waitcnt lgkmcnt(4)
	v_mfma_f32_32x32x16_bf16 v[32:47], v[116:119], v[48:51], v[32:47]
	v_exp_f32_e32 v196, v196
	v_exp_f32_e32 v197, v197
	v_mfma_f32_32x32x16_bf16 v[32:47], v[120:123], v[52:55], v[32:47]
	v_exp_f32_e32 v198, v198
	v_exp_f32_e32 v199, v199
	v_mfma_f32_32x32x16_bf16 v[32:47], v[124:127], v[56:59], v[32:47]
	v_exp_f32_e32 v200, v200
	v_exp_f32_e32 v201, v201
	v_mfma_f32_32x32x16_bf16 v[32:47], v[128:131], v[60:63], v[32:47]
	v_exp_f32_e32 v202, v202
	v_exp_f32_e32 v203, v203
	v_cvt_pk_bf16_f32 v64, v188, v189
	v_cvt_pk_bf16_f32 v65, v190, v191
	v_cvt_pk_bf16_f32 v66, v192, v193
	v_cvt_pk_bf16_f32 v67, v194, v195
	v_cvt_pk_bf16_f32 v68, v196, v197
	v_cvt_pk_bf16_f32 v69, v198, v199
	v_cvt_pk_bf16_f32 v70, v200, v201
	v_cvt_pk_bf16_f32 v71, v202, v203
	v_pk_add_f32 v[232:233], v[232:233], v[188:189]
	v_pk_add_f32 v[232:233], v[232:233], v[190:191]
	v_pk_add_f32 v[232:233], v[232:233], v[192:193]
	v_pk_add_f32 v[232:233], v[232:233], v[194:195]
	v_pk_add_f32 v[232:233], v[232:233], v[196:197]
	v_pk_add_f32 v[232:233], v[232:233], v[198:199]
	v_pk_add_f32 v[232:233], v[232:233], v[200:201]
	v_pk_add_f32 v[232:233], v[232:233], v[202:203]
	ds_read2_b32 v[188:189], v115 offset0:170 offset1:171
	ds_read2_b32 v[190:191], v115 offset0:172 offset1:173
	ds_read2_b32 v[192:193], v115 offset0:178 offset1:179
	ds_read2_b32 v[194:195], v115 offset0:180 offset1:181
	ds_read2_b32 v[196:197], v115 offset0:187 offset1:188
	ds_read2_b32 v[198:199], v115 offset0:189 offset1:190
	ds_read2_b32 v[200:201], v115 offset0:195 offset1:196
	ds_read2_b32 v[202:203], v115 offset0:197 offset1:198
	v_mfma_f32_32x32x16_bf16 v[0:15], v[64:67], v[72:75], v[0:15]
	v_mfma_f32_32x32x16_bf16 v[16:31], v[64:67], v[76:79], v[16:31]
	v_mfma_f32_32x32x16_bf16 v[0:15], v[68:71], v[220:223], v[0:15]
	v_mfma_f32_32x32x16_bf16 v[16:31], v[68:71], v[224:227], v[16:31]
	global_load_dwordx4 v[116:119], v239, s[86:87]
	global_load_dwordx4 v[120:123], v240, s[86:87]
	global_load_dwordx4 v[124:127], v241, s[86:87]
	global_load_dwordx4 v[128:131], v242, s[86:87]
	global_load_dwordx4 v[132:135], v101, s[86:87] offset:768
	global_load_dwordx4 v[136:139], v150, s[86:87] offset:768
	global_load_dwordx4 v[140:143], v101, s[86:87] offset:832
	global_load_dwordx4 v[144:147], v150, s[86:87] offset:832
	s_add_u32 s86, s86, 0xc0000
	s_addc_u32 s87, s87, 0
	ds_read_b64_tr_b16 v[72:73], v231
	ds_read_b64_tr_b16 v[74:75], v231 offset:512
	ds_read_b64_tr_b16 v[76:77], v231 offset:2048
	ds_read_b64_tr_b16 v[78:79], v231 offset:2560
	ds_read_b64_tr_b16 v[220:221], v231 offset:1024
	ds_read_b64_tr_b16 v[222:223], v231 offset:1536
	ds_read_b64_tr_b16 v[224:225], v231 offset:3072
	ds_read_b64_tr_b16 v[226:227], v231 offset:3584
	v_exp_f32_e32 v32, v32
	v_exp_f32_e32 v33, v33
	v_exp_f32_e32 v34, v34
	v_exp_f32_e32 v35, v35
	s_waitcnt vmcnt(8)
	ds_write_b128 v247, v[156:159]
	ds_write_b128 v247, v[160:163] offset:1024
	ds_write_b128 v247, v[164:167] offset:2048
	ds_write_b128 v247, v[168:171] offset:3072
	ds_read_b128 v[156:159], v248
	ds_read_b128 v[160:163], v249
	ds_read_b128 v[164:167], v250
	ds_read_b128 v[168:171], v251
	ds_write_b128 v112, v[172:175]
	ds_write_b128 v112, v[176:179] offset:1024
	ds_write_b128 v112, v[180:183] offset:2048
	ds_write_b128 v112, v[184:187] offset:3072
	v_exp_f32_e32 v36, v36
	v_exp_f32_e32 v37, v37
	v_exp_f32_e32 v38, v38
	v_exp_f32_e32 v39, v39
	s_waitcnt lgkmcnt(4)
	v_mfma_f32_32x32x16_bf16 v[188:203], v[156:159], v[48:51], v[188:203]
	v_exp_f32_e32 v40, v40
	v_exp_f32_e32 v41, v41
	v_mfma_f32_32x32x16_bf16 v[188:203], v[160:163], v[52:55], v[188:203]
	v_exp_f32_e32 v42, v42
	v_exp_f32_e32 v43, v43
	v_mfma_f32_32x32x16_bf16 v[188:203], v[164:167], v[56:59], v[188:203]
	v_exp_f32_e32 v44, v44
	v_exp_f32_e32 v45, v45
	v_mfma_f32_32x32x16_bf16 v[188:203], v[168:171], v[60:63], v[188:203]
	v_exp_f32_e32 v46, v46
	v_exp_f32_e32 v47, v47
	v_cvt_pk_bf16_f32 v64, v32, v33
	v_cvt_pk_bf16_f32 v65, v34, v35
	v_cvt_pk_bf16_f32 v66, v36, v37
	v_cvt_pk_bf16_f32 v67, v38, v39
	v_cvt_pk_bf16_f32 v68, v40, v41
	v_cvt_pk_bf16_f32 v69, v42, v43
	v_cvt_pk_bf16_f32 v70, v44, v45
	v_cvt_pk_bf16_f32 v71, v46, v47
	v_pk_add_f32 v[232:233], v[232:233], v[32:33]
	v_pk_add_f32 v[232:233], v[232:233], v[34:35]
	v_pk_add_f32 v[232:233], v[232:233], v[36:37]
	v_pk_add_f32 v[232:233], v[232:233], v[38:39]
	v_pk_add_f32 v[232:233], v[232:233], v[40:41]
	v_pk_add_f32 v[232:233], v[232:233], v[42:43]
	v_pk_add_f32 v[232:233], v[232:233], v[44:45]
	v_pk_add_f32 v[232:233], v[232:233], v[46:47]
	v_mov_b32_e32 v115, v229
	ds_read2_b32 v[32:33], v115 offset0:0 offset1:1
	ds_read2_b32 v[34:35], v115 offset0:2 offset1:3
	ds_read2_b32 v[36:37], v115 offset0:8 offset1:9
	ds_read2_b32 v[38:39], v115 offset0:10 offset1:11
	ds_read2_b32 v[40:41], v115 offset0:16 offset1:17
	ds_read2_b32 v[42:43], v115 offset0:18 offset1:19
	ds_read2_b32 v[44:45], v115 offset0:24 offset1:25
	ds_read2_b32 v[46:47], v115 offset0:26 offset1:27
	v_mfma_f32_32x32x16_bf16 v[0:15], v[64:67], v[72:75], v[0:15]
	v_mfma_f32_32x32x16_bf16 v[16:31], v[64:67], v[76:79], v[16:31]
	v_mfma_f32_32x32x16_bf16 v[0:15], v[68:71], v[220:223], v[0:15]
	v_mfma_f32_32x32x16_bf16 v[16:31], v[68:71], v[224:227], v[16:31]
	global_load_dwordx4 v[156:159], v239, s[86:87]
	global_load_dwordx4 v[160:163], v240, s[86:87]
	global_load_dwordx4 v[164:167], v241, s[86:87]
	global_load_dwordx4 v[168:171], v242, s[86:87]
	global_load_dwordx4 v[172:175], v101, s[86:87] offset:768
	global_load_dwordx4 v[176:179], v150, s[86:87] offset:768
	global_load_dwordx4 v[180:183], v101, s[86:87] offset:832
	global_load_dwordx4 v[184:187], v150, s[86:87] offset:832
	s_add_u32 s86, s86, 0xc0000
	s_addc_u32 s87, s87, 0
	ds_read_b64_tr_b16 v[72:73], v231
	ds_read_b64_tr_b16 v[74:75], v231 offset:512
	ds_read_b64_tr_b16 v[76:77], v231 offset:2048
	ds_read_b64_tr_b16 v[78:79], v231 offset:2560
	ds_read_b64_tr_b16 v[220:221], v231 offset:1024
	ds_read_b64_tr_b16 v[222:223], v231 offset:1536
	ds_read_b64_tr_b16 v[224:225], v231 offset:3072
	ds_read_b64_tr_b16 v[226:227], v231 offset:3584
	v_exp_f32_e32 v188, v188
	v_exp_f32_e32 v189, v189
	v_exp_f32_e32 v190, v190
	v_exp_f32_e32 v191, v191
	s_waitcnt vmcnt(8)
	ds_write_b128 v247, v[116:119]
	ds_write_b128 v247, v[120:123] offset:1024
	ds_write_b128 v247, v[124:127] offset:2048
	ds_write_b128 v247, v[128:131] offset:3072
	ds_read_b128 v[116:119], v248
	ds_read_b128 v[120:123], v249
	ds_read_b128 v[124:127], v250
	ds_read_b128 v[128:131], v251
	ds_write_b128 v112, v[132:135]
	ds_write_b128 v112, v[136:139] offset:1024
	ds_write_b128 v112, v[140:143] offset:2048
	ds_write_b128 v112, v[144:147] offset:3072
	v_exp_f32_e32 v192, v192
	v_exp_f32_e32 v193, v193
	v_exp_f32_e32 v194, v194
	v_exp_f32_e32 v195, v195
	s_waitcnt lgkmcnt(4)
	v_mfma_f32_32x32x16_bf16 v[32:47], v[116:119], v[48:51], v[32:47]
	v_exp_f32_e32 v196, v196
	v_exp_f32_e32 v197, v197
	v_mfma_f32_32x32x16_bf16 v[32:47], v[120:123], v[52:55], v[32:47]
	v_exp_f32_e32 v198, v198
	v_exp_f32_e32 v199, v199
	v_mfma_f32_32x32x16_bf16 v[32:47], v[124:127], v[56:59], v[32:47]
	v_exp_f32_e32 v200, v200
	v_exp_f32_e32 v201, v201
	v_mfma_f32_32x32x16_bf16 v[32:47], v[128:131], v[60:63], v[32:47]
	v_exp_f32_e32 v202, v202
	v_exp_f32_e32 v203, v203
	v_cvt_pk_bf16_f32 v64, v188, v189
	v_cvt_pk_bf16_f32 v65, v190, v191
	v_cvt_pk_bf16_f32 v66, v192, v193
	v_cvt_pk_bf16_f32 v67, v194, v195
	v_cvt_pk_bf16_f32 v68, v196, v197
	v_cvt_pk_bf16_f32 v69, v198, v199
	v_cvt_pk_bf16_f32 v70, v200, v201
	v_cvt_pk_bf16_f32 v71, v202, v203
	v_pk_add_f32 v[232:233], v[232:233], v[188:189]
	v_pk_add_f32 v[232:233], v[232:233], v[190:191]
	v_pk_add_f32 v[232:233], v[232:233], v[192:193]
	v_pk_add_f32 v[232:233], v[232:233], v[194:195]
	v_pk_add_f32 v[232:233], v[232:233], v[196:197]
	v_pk_add_f32 v[232:233], v[232:233], v[198:199]
	v_pk_add_f32 v[232:233], v[232:233], v[200:201]
	v_pk_add_f32 v[232:233], v[232:233], v[202:203]
	ds_read2_b32 v[188:189], v115 offset0:32 offset1:33
	ds_read2_b32 v[190:191], v115 offset0:34 offset1:35
	ds_read2_b32 v[192:193], v115 offset0:40 offset1:41
	ds_read2_b32 v[194:195], v115 offset0:42 offset1:43
	ds_read2_b32 v[196:197], v115 offset0:48 offset1:49
	ds_read2_b32 v[198:199], v115 offset0:50 offset1:51
	ds_read2_b32 v[200:201], v115 offset0:56 offset1:57
	ds_read2_b32 v[202:203], v115 offset0:58 offset1:59
	v_mfma_f32_32x32x16_bf16 v[0:15], v[64:67], v[72:75], v[0:15]
	v_mfma_f32_32x32x16_bf16 v[16:31], v[64:67], v[76:79], v[16:31]
	v_mfma_f32_32x32x16_bf16 v[0:15], v[68:71], v[220:223], v[0:15]
	v_mfma_f32_32x32x16_bf16 v[16:31], v[68:71], v[224:227], v[16:31]
	global_load_dwordx4 v[116:119], v239, s[86:87]
	global_load_dwordx4 v[120:123], v240, s[86:87]
	global_load_dwordx4 v[124:127], v241, s[86:87]
	global_load_dwordx4 v[128:131], v242, s[86:87]
	global_load_dwordx4 v[132:135], v101, s[86:87] offset:768
	global_load_dwordx4 v[136:139], v150, s[86:87] offset:768
	global_load_dwordx4 v[140:143], v101, s[86:87] offset:832
	global_load_dwordx4 v[144:147], v150, s[86:87] offset:832
	s_add_u32 s86, s86, 0xc0000
	s_addc_u32 s87, s87, 0
	ds_read_b64_tr_b16 v[72:73], v231
	ds_read_b64_tr_b16 v[74:75], v231 offset:512
	ds_read_b64_tr_b16 v[76:77], v231 offset:2048
	ds_read_b64_tr_b16 v[78:79], v231 offset:2560
	ds_read_b64_tr_b16 v[220:221], v231 offset:1024
	ds_read_b64_tr_b16 v[222:223], v231 offset:1536
	ds_read_b64_tr_b16 v[224:225], v231 offset:3072
	ds_read_b64_tr_b16 v[226:227], v231 offset:3584
	v_exp_f32_e32 v32, v32
	v_exp_f32_e32 v33, v33
	v_exp_f32_e32 v34, v34
	v_exp_f32_e32 v35, v35
	s_waitcnt vmcnt(8)
	ds_write_b128 v247, v[156:159]
	ds_write_b128 v247, v[160:163] offset:1024
	ds_write_b128 v247, v[164:167] offset:2048
	ds_write_b128 v247, v[168:171] offset:3072
	ds_read_b128 v[156:159], v248
	ds_read_b128 v[160:163], v249
	ds_read_b128 v[164:167], v250
	ds_read_b128 v[168:171], v251
	ds_write_b128 v112, v[172:175]
	ds_write_b128 v112, v[176:179] offset:1024
	ds_write_b128 v112, v[180:183] offset:2048
	ds_write_b128 v112, v[184:187] offset:3072
	v_exp_f32_e32 v36, v36
	v_exp_f32_e32 v37, v37
	v_exp_f32_e32 v38, v38
	v_exp_f32_e32 v39, v39
	s_waitcnt lgkmcnt(4)
	v_mfma_f32_32x32x16_bf16 v[188:203], v[156:159], v[48:51], v[188:203]
	v_exp_f32_e32 v40, v40
	v_exp_f32_e32 v41, v41
	v_mfma_f32_32x32x16_bf16 v[188:203], v[160:163], v[52:55], v[188:203]
	v_exp_f32_e32 v42, v42
	v_exp_f32_e32 v43, v43
	v_mfma_f32_32x32x16_bf16 v[188:203], v[164:167], v[56:59], v[188:203]
	v_exp_f32_e32 v44, v44
	v_exp_f32_e32 v45, v45
	v_mfma_f32_32x32x16_bf16 v[188:203], v[168:171], v[60:63], v[188:203]
	v_exp_f32_e32 v46, v46
	v_exp_f32_e32 v47, v47
	v_cvt_pk_bf16_f32 v64, v32, v33
	v_cvt_pk_bf16_f32 v65, v34, v35
	v_cvt_pk_bf16_f32 v66, v36, v37
	v_cvt_pk_bf16_f32 v67, v38, v39
	v_cvt_pk_bf16_f32 v68, v40, v41
	v_cvt_pk_bf16_f32 v69, v42, v43
	v_cvt_pk_bf16_f32 v70, v44, v45
	v_cvt_pk_bf16_f32 v71, v46, v47
	v_pk_add_f32 v[232:233], v[232:233], v[32:33]
	v_pk_add_f32 v[232:233], v[232:233], v[34:35]
	v_pk_add_f32 v[232:233], v[232:233], v[36:37]
	v_pk_add_f32 v[232:233], v[232:233], v[38:39]
	v_pk_add_f32 v[232:233], v[232:233], v[40:41]
	v_pk_add_f32 v[232:233], v[232:233], v[42:43]
	v_pk_add_f32 v[232:233], v[232:233], v[44:45]
	v_pk_add_f32 v[232:233], v[232:233], v[46:47]
	ds_read2_b32 v[32:33], v115 offset0:64 offset1:65
	ds_read2_b32 v[34:35], v115 offset0:66 offset1:67
	ds_read2_b32 v[36:37], v115 offset0:72 offset1:73
	ds_read2_b32 v[38:39], v115 offset0:74 offset1:75
	ds_read2_b32 v[40:41], v115 offset0:80 offset1:81
	ds_read2_b32 v[42:43], v115 offset0:82 offset1:83
	ds_read2_b32 v[44:45], v115 offset0:88 offset1:89
	ds_read2_b32 v[46:47], v115 offset0:90 offset1:91
	v_mfma_f32_32x32x16_bf16 v[0:15], v[64:67], v[72:75], v[0:15]
	v_mfma_f32_32x32x16_bf16 v[16:31], v[64:67], v[76:79], v[16:31]
	v_mfma_f32_32x32x16_bf16 v[0:15], v[68:71], v[220:223], v[0:15]
	v_mfma_f32_32x32x16_bf16 v[16:31], v[68:71], v[224:227], v[16:31]
	global_load_dwordx4 v[156:159], v239, s[86:87]
	global_load_dwordx4 v[160:163], v240, s[86:87]
	global_load_dwordx4 v[164:167], v241, s[86:87]
	global_load_dwordx4 v[168:171], v242, s[86:87]
	global_load_dwordx4 v[172:175], v101, s[86:87] offset:768
	global_load_dwordx4 v[176:179], v150, s[86:87] offset:768
	global_load_dwordx4 v[180:183], v101, s[86:87] offset:832
	global_load_dwordx4 v[184:187], v150, s[86:87] offset:832
	s_add_u32 s86, s86, 0xc0000
	s_addc_u32 s87, s87, 0
	ds_read_b64_tr_b16 v[72:73], v231
	ds_read_b64_tr_b16 v[74:75], v231 offset:512
	ds_read_b64_tr_b16 v[76:77], v231 offset:2048
	ds_read_b64_tr_b16 v[78:79], v231 offset:2560
	ds_read_b64_tr_b16 v[220:221], v231 offset:1024
	ds_read_b64_tr_b16 v[222:223], v231 offset:1536
	ds_read_b64_tr_b16 v[224:225], v231 offset:3072
	ds_read_b64_tr_b16 v[226:227], v231 offset:3584
	v_exp_f32_e32 v188, v188
	v_exp_f32_e32 v189, v189
	v_exp_f32_e32 v190, v190
	v_exp_f32_e32 v191, v191
	s_waitcnt vmcnt(8)
	ds_write_b128 v247, v[116:119]
	ds_write_b128 v247, v[120:123] offset:1024
	ds_write_b128 v247, v[124:127] offset:2048
	ds_write_b128 v247, v[128:131] offset:3072
	ds_read_b128 v[116:119], v248
	ds_read_b128 v[120:123], v249
	ds_read_b128 v[124:127], v250
	ds_read_b128 v[128:131], v251
	ds_write_b128 v112, v[132:135]
	ds_write_b128 v112, v[136:139] offset:1024
	ds_write_b128 v112, v[140:143] offset:2048
	ds_write_b128 v112, v[144:147] offset:3072
	v_exp_f32_e32 v192, v192
	v_exp_f32_e32 v193, v193
	v_exp_f32_e32 v194, v194
	v_exp_f32_e32 v195, v195
	s_waitcnt lgkmcnt(4)
	v_mfma_f32_32x32x16_bf16 v[32:47], v[116:119], v[48:51], v[32:47]
	v_exp_f32_e32 v196, v196
	v_exp_f32_e32 v197, v197
	v_mfma_f32_32x32x16_bf16 v[32:47], v[120:123], v[52:55], v[32:47]
	v_exp_f32_e32 v198, v198
	v_exp_f32_e32 v199, v199
	v_mfma_f32_32x32x16_bf16 v[32:47], v[124:127], v[56:59], v[32:47]
	v_exp_f32_e32 v200, v200
	v_exp_f32_e32 v201, v201
	v_mfma_f32_32x32x16_bf16 v[32:47], v[128:131], v[60:63], v[32:47]
	v_exp_f32_e32 v202, v202
	v_exp_f32_e32 v203, v203
	v_cvt_pk_bf16_f32 v64, v188, v189
	v_cvt_pk_bf16_f32 v65, v190, v191
	v_cvt_pk_bf16_f32 v66, v192, v193
	v_cvt_pk_bf16_f32 v67, v194, v195
	v_cvt_pk_bf16_f32 v68, v196, v197
	v_cvt_pk_bf16_f32 v69, v198, v199
	v_cvt_pk_bf16_f32 v70, v200, v201
	v_cvt_pk_bf16_f32 v71, v202, v203
	v_pk_add_f32 v[232:233], v[232:233], v[188:189]
	v_pk_add_f32 v[232:233], v[232:233], v[190:191]
	v_pk_add_f32 v[232:233], v[232:233], v[192:193]
	v_pk_add_f32 v[232:233], v[232:233], v[194:195]
	v_pk_add_f32 v[232:233], v[232:233], v[196:197]
	v_pk_add_f32 v[232:233], v[232:233], v[198:199]
	v_pk_add_f32 v[232:233], v[232:233], v[200:201]
	v_pk_add_f32 v[232:233], v[232:233], v[202:203]
	ds_read2_b32 v[188:189], v115 offset0:96 offset1:97
	ds_read2_b32 v[190:191], v115 offset0:98 offset1:99
	ds_read2_b32 v[192:193], v115 offset0:104 offset1:105
	ds_read2_b32 v[194:195], v115 offset0:106 offset1:107
	ds_read2_b32 v[196:197], v115 offset0:112 offset1:113
	ds_read2_b32 v[198:199], v115 offset0:114 offset1:115
	ds_read2_b32 v[200:201], v115 offset0:120 offset1:121
	ds_read2_b32 v[202:203], v115 offset0:122 offset1:123
	v_mfma_f32_32x32x16_bf16 v[0:15], v[64:67], v[72:75], v[0:15]
	v_mfma_f32_32x32x16_bf16 v[16:31], v[64:67], v[76:79], v[16:31]
	v_mfma_f32_32x32x16_bf16 v[0:15], v[68:71], v[220:223], v[0:15]
	v_mfma_f32_32x32x16_bf16 v[16:31], v[68:71], v[224:227], v[16:31]
	global_load_dwordx4 v[116:119], v239, s[86:87]
	global_load_dwordx4 v[120:123], v240, s[86:87]
	global_load_dwordx4 v[124:127], v241, s[86:87]
	global_load_dwordx4 v[128:131], v242, s[86:87]
	global_load_dwordx4 v[132:135], v101, s[86:87] offset:768
	global_load_dwordx4 v[136:139], v150, s[86:87] offset:768
	global_load_dwordx4 v[140:143], v101, s[86:87] offset:832
	global_load_dwordx4 v[144:147], v150, s[86:87] offset:832
	s_add_u32 s86, s86, 0xc0000
	s_addc_u32 s87, s87, 0
	ds_read_b64_tr_b16 v[72:73], v231
	ds_read_b64_tr_b16 v[74:75], v231 offset:512
	ds_read_b64_tr_b16 v[76:77], v231 offset:2048
	ds_read_b64_tr_b16 v[78:79], v231 offset:2560
	ds_read_b64_tr_b16 v[220:221], v231 offset:1024
	ds_read_b64_tr_b16 v[222:223], v231 offset:1536
	ds_read_b64_tr_b16 v[224:225], v231 offset:3072
	ds_read_b64_tr_b16 v[226:227], v231 offset:3584
	v_exp_f32_e32 v32, v32
	v_exp_f32_e32 v33, v33
	v_exp_f32_e32 v34, v34
	v_exp_f32_e32 v35, v35
	s_waitcnt vmcnt(8)
	ds_write_b128 v247, v[156:159]
	ds_write_b128 v247, v[160:163] offset:1024
	ds_write_b128 v247, v[164:167] offset:2048
	ds_write_b128 v247, v[168:171] offset:3072
	ds_read_b128 v[156:159], v248
	ds_read_b128 v[160:163], v249
	ds_read_b128 v[164:167], v250
	ds_read_b128 v[168:171], v251
	ds_write_b128 v112, v[172:175]
	ds_write_b128 v112, v[176:179] offset:1024
	ds_write_b128 v112, v[180:183] offset:2048
	ds_write_b128 v112, v[184:187] offset:3072
	v_exp_f32_e32 v36, v36
	v_exp_f32_e32 v37, v37
	v_exp_f32_e32 v38, v38
	v_exp_f32_e32 v39, v39
	s_waitcnt lgkmcnt(4)
	v_mfma_f32_32x32x16_bf16 v[188:203], v[156:159], v[48:51], v[188:203]
	v_exp_f32_e32 v40, v40
	v_exp_f32_e32 v41, v41
	v_mfma_f32_32x32x16_bf16 v[188:203], v[160:163], v[52:55], v[188:203]
	v_exp_f32_e32 v42, v42
	v_exp_f32_e32 v43, v43
	v_mfma_f32_32x32x16_bf16 v[188:203], v[164:167], v[56:59], v[188:203]
	v_exp_f32_e32 v44, v44
	v_exp_f32_e32 v45, v45
	v_mfma_f32_32x32x16_bf16 v[188:203], v[168:171], v[60:63], v[188:203]
	v_exp_f32_e32 v46, v46
	v_exp_f32_e32 v47, v47
	v_cvt_pk_bf16_f32 v64, v32, v33
	v_cvt_pk_bf16_f32 v65, v34, v35
	v_cvt_pk_bf16_f32 v66, v36, v37
	v_cvt_pk_bf16_f32 v67, v38, v39
	v_cvt_pk_bf16_f32 v68, v40, v41
	v_cvt_pk_bf16_f32 v69, v42, v43
	v_cvt_pk_bf16_f32 v70, v44, v45
	v_cvt_pk_bf16_f32 v71, v46, v47
	v_pk_add_f32 v[232:233], v[232:233], v[32:33]
	v_pk_add_f32 v[232:233], v[232:233], v[34:35]
	v_pk_add_f32 v[232:233], v[232:233], v[36:37]
	v_pk_add_f32 v[232:233], v[232:233], v[38:39]
	v_pk_add_f32 v[232:233], v[232:233], v[40:41]
	v_pk_add_f32 v[232:233], v[232:233], v[42:43]
	v_pk_add_f32 v[232:233], v[232:233], v[44:45]
	v_pk_add_f32 v[232:233], v[232:233], v[46:47]
	ds_read2_b32 v[32:33], v115 offset0:128 offset1:129
	ds_read2_b32 v[34:35], v115 offset0:130 offset1:131
	ds_read2_b32 v[36:37], v115 offset0:136 offset1:137
	ds_read2_b32 v[38:39], v115 offset0:138 offset1:139
	ds_read2_b32 v[40:41], v115 offset0:144 offset1:145
	ds_read2_b32 v[42:43], v115 offset0:146 offset1:147
	ds_read2_b32 v[44:45], v115 offset0:152 offset1:153
	ds_read2_b32 v[46:47], v115 offset0:154 offset1:155
	v_mfma_f32_32x32x16_bf16 v[0:15], v[64:67], v[72:75], v[0:15]
	v_mfma_f32_32x32x16_bf16 v[16:31], v[64:67], v[76:79], v[16:31]
	v_mfma_f32_32x32x16_bf16 v[0:15], v[68:71], v[220:223], v[0:15]
	v_mfma_f32_32x32x16_bf16 v[16:31], v[68:71], v[224:227], v[16:31]
	global_load_dwordx4 v[156:159], v239, s[86:87]
	global_load_dwordx4 v[160:163], v240, s[86:87]
	global_load_dwordx4 v[164:167], v241, s[86:87]
	global_load_dwordx4 v[168:171], v242, s[86:87]
	global_load_dwordx4 v[172:175], v101, s[86:87] offset:768
	global_load_dwordx4 v[176:179], v150, s[86:87] offset:768
	global_load_dwordx4 v[180:183], v101, s[86:87] offset:832
	global_load_dwordx4 v[184:187], v150, s[86:87] offset:832
	s_add_u32 s86, s86, 0xc0000
	s_addc_u32 s87, s87, 0
	ds_read_b64_tr_b16 v[72:73], v231
	ds_read_b64_tr_b16 v[74:75], v231 offset:512
	ds_read_b64_tr_b16 v[76:77], v231 offset:2048
	ds_read_b64_tr_b16 v[78:79], v231 offset:2560
	ds_read_b64_tr_b16 v[220:221], v231 offset:1024
	ds_read_b64_tr_b16 v[222:223], v231 offset:1536
	ds_read_b64_tr_b16 v[224:225], v231 offset:3072
	ds_read_b64_tr_b16 v[226:227], v231 offset:3584
	v_exp_f32_e32 v188, v188
	v_exp_f32_e32 v189, v189
	v_exp_f32_e32 v190, v190
	v_exp_f32_e32 v191, v191
	s_waitcnt vmcnt(8)
	ds_write_b128 v247, v[116:119]
	ds_write_b128 v247, v[120:123] offset:1024
	ds_write_b128 v247, v[124:127] offset:2048
	ds_write_b128 v247, v[128:131] offset:3072
	ds_read_b128 v[116:119], v248
	ds_read_b128 v[120:123], v249
	ds_read_b128 v[124:127], v250
	ds_read_b128 v[128:131], v251
	ds_write_b128 v112, v[132:135]
	ds_write_b128 v112, v[136:139] offset:1024
	ds_write_b128 v112, v[140:143] offset:2048
	ds_write_b128 v112, v[144:147] offset:3072
	v_exp_f32_e32 v192, v192
	v_exp_f32_e32 v193, v193
	v_exp_f32_e32 v194, v194
	v_exp_f32_e32 v195, v195
	s_waitcnt lgkmcnt(4)
	v_mfma_f32_32x32x16_bf16 v[32:47], v[116:119], v[48:51], v[32:47]
	v_exp_f32_e32 v196, v196
	v_exp_f32_e32 v197, v197
	v_mfma_f32_32x32x16_bf16 v[32:47], v[120:123], v[52:55], v[32:47]
	v_exp_f32_e32 v198, v198
	v_exp_f32_e32 v199, v199
	v_mfma_f32_32x32x16_bf16 v[32:47], v[124:127], v[56:59], v[32:47]
	v_exp_f32_e32 v200, v200
	v_exp_f32_e32 v201, v201
	v_mfma_f32_32x32x16_bf16 v[32:47], v[128:131], v[60:63], v[32:47]
	v_exp_f32_e32 v202, v202
	v_exp_f32_e32 v203, v203
	v_cvt_pk_bf16_f32 v64, v188, v189
	v_cvt_pk_bf16_f32 v65, v190, v191
	v_cvt_pk_bf16_f32 v66, v192, v193
	v_cvt_pk_bf16_f32 v67, v194, v195
	v_cvt_pk_bf16_f32 v68, v196, v197
	v_cvt_pk_bf16_f32 v69, v198, v199
	v_cvt_pk_bf16_f32 v70, v200, v201
	v_cvt_pk_bf16_f32 v71, v202, v203
	v_pk_add_f32 v[232:233], v[232:233], v[188:189]
	v_pk_add_f32 v[232:233], v[232:233], v[190:191]
	v_pk_add_f32 v[232:233], v[232:233], v[192:193]
	v_pk_add_f32 v[232:233], v[232:233], v[194:195]
	v_pk_add_f32 v[232:233], v[232:233], v[196:197]
	v_pk_add_f32 v[232:233], v[232:233], v[198:199]
	v_pk_add_f32 v[232:233], v[232:233], v[200:201]
	v_pk_add_f32 v[232:233], v[232:233], v[202:203]
	ds_read2_b32 v[188:189], v115 offset0:160 offset1:161
	ds_read2_b32 v[190:191], v115 offset0:162 offset1:163
	ds_read2_b32 v[192:193], v115 offset0:168 offset1:169
	ds_read2_b32 v[194:195], v115 offset0:170 offset1:171
	ds_read2_b32 v[196:197], v115 offset0:176 offset1:177
	ds_read2_b32 v[198:199], v115 offset0:178 offset1:179
	ds_read2_b32 v[200:201], v115 offset0:184 offset1:185
	ds_read2_b32 v[202:203], v115 offset0:186 offset1:187
	v_mfma_f32_32x32x16_bf16 v[0:15], v[64:67], v[72:75], v[0:15]
	v_mfma_f32_32x32x16_bf16 v[16:31], v[64:67], v[76:79], v[16:31]
	v_mfma_f32_32x32x16_bf16 v[0:15], v[68:71], v[220:223], v[0:15]
	v_mfma_f32_32x32x16_bf16 v[16:31], v[68:71], v[224:227], v[16:31]
	global_load_dwordx4 v[116:119], v239, s[86:87]
	global_load_dwordx4 v[120:123], v240, s[86:87]
	global_load_dwordx4 v[124:127], v241, s[86:87]
	global_load_dwordx4 v[128:131], v242, s[86:87]
	global_load_dwordx4 v[132:135], v101, s[86:87] offset:768
	global_load_dwordx4 v[136:139], v150, s[86:87] offset:768
	global_load_dwordx4 v[140:143], v101, s[86:87] offset:832
	global_load_dwordx4 v[144:147], v150, s[86:87] offset:832
	s_add_u32 s86, s86, 0xc0000
	s_addc_u32 s87, s87, 0
	ds_read_b64_tr_b16 v[72:73], v231
	ds_read_b64_tr_b16 v[74:75], v231 offset:512
	ds_read_b64_tr_b16 v[76:77], v231 offset:2048
	ds_read_b64_tr_b16 v[78:79], v231 offset:2560
	ds_read_b64_tr_b16 v[220:221], v231 offset:1024
	ds_read_b64_tr_b16 v[222:223], v231 offset:1536
	ds_read_b64_tr_b16 v[224:225], v231 offset:3072
	ds_read_b64_tr_b16 v[226:227], v231 offset:3584
	v_exp_f32_e32 v32, v32
	v_exp_f32_e32 v33, v33
	v_exp_f32_e32 v34, v34
	v_exp_f32_e32 v35, v35
	s_waitcnt vmcnt(8)
	ds_write_b128 v247, v[156:159]
	ds_write_b128 v247, v[160:163] offset:1024
	ds_write_b128 v247, v[164:167] offset:2048
	ds_write_b128 v247, v[168:171] offset:3072
	ds_read_b128 v[156:159], v248
	ds_read_b128 v[160:163], v249
	ds_read_b128 v[164:167], v250
	ds_read_b128 v[168:171], v251
	ds_write_b128 v112, v[172:175]
	ds_write_b128 v112, v[176:179] offset:1024
	ds_write_b128 v112, v[180:183] offset:2048
	ds_write_b128 v112, v[184:187] offset:3072
	v_exp_f32_e32 v36, v36
	v_exp_f32_e32 v37, v37
	v_exp_f32_e32 v38, v38
	v_exp_f32_e32 v39, v39
	s_waitcnt lgkmcnt(4)
	v_mfma_f32_32x32x16_bf16 v[188:203], v[156:159], v[48:51], v[188:203]
	v_exp_f32_e32 v40, v40
	v_exp_f32_e32 v41, v41
	v_mfma_f32_32x32x16_bf16 v[188:203], v[160:163], v[52:55], v[188:203]
	v_exp_f32_e32 v42, v42
	v_exp_f32_e32 v43, v43
	v_mfma_f32_32x32x16_bf16 v[188:203], v[164:167], v[56:59], v[188:203]
	v_exp_f32_e32 v44, v44
	v_exp_f32_e32 v45, v45
	v_mfma_f32_32x32x16_bf16 v[188:203], v[168:171], v[60:63], v[188:203]
	v_exp_f32_e32 v46, v46
	v_exp_f32_e32 v47, v47
	v_cvt_pk_bf16_f32 v64, v32, v33
	v_cvt_pk_bf16_f32 v65, v34, v35
	v_cvt_pk_bf16_f32 v66, v36, v37
	v_cvt_pk_bf16_f32 v67, v38, v39
	v_cvt_pk_bf16_f32 v68, v40, v41
	v_cvt_pk_bf16_f32 v69, v42, v43
	v_cvt_pk_bf16_f32 v70, v44, v45
	v_cvt_pk_bf16_f32 v71, v46, v47
	v_pk_add_f32 v[232:233], v[232:233], v[32:33]
	v_pk_add_f32 v[232:233], v[232:233], v[34:35]
	v_pk_add_f32 v[232:233], v[232:233], v[36:37]
	v_pk_add_f32 v[232:233], v[232:233], v[38:39]
	v_pk_add_f32 v[232:233], v[232:233], v[40:41]
	v_pk_add_f32 v[232:233], v[232:233], v[42:43]
	v_pk_add_f32 v[232:233], v[232:233], v[44:45]
	v_pk_add_f32 v[232:233], v[232:233], v[46:47]
	ds_read2_b32 v[32:33], v115 offset0:192 offset1:193
	ds_read2_b32 v[34:35], v115 offset0:194 offset1:195
	ds_read2_b32 v[36:37], v115 offset0:200 offset1:201
	ds_read2_b32 v[38:39], v115 offset0:202 offset1:203
	ds_read2_b32 v[40:41], v115 offset0:208 offset1:209
	ds_read2_b32 v[42:43], v115 offset0:210 offset1:211
	ds_read2_b32 v[44:45], v115 offset0:216 offset1:217
	ds_read2_b32 v[46:47], v115 offset0:218 offset1:219
	v_mfma_f32_32x32x16_bf16 v[0:15], v[64:67], v[72:75], v[0:15]
	v_mfma_f32_32x32x16_bf16 v[16:31], v[64:67], v[76:79], v[16:31]
	v_mfma_f32_32x32x16_bf16 v[0:15], v[68:71], v[220:223], v[0:15]
	v_mfma_f32_32x32x16_bf16 v[16:31], v[68:71], v[224:227], v[16:31]
	global_load_dwordx4 v[156:159], v239, s[86:87]
	global_load_dwordx4 v[160:163], v240, s[86:87]
	global_load_dwordx4 v[164:167], v241, s[86:87]
	global_load_dwordx4 v[168:171], v242, s[86:87]
	global_load_dwordx4 v[172:175], v101, s[86:87] offset:768
	global_load_dwordx4 v[176:179], v150, s[86:87] offset:768
	global_load_dwordx4 v[180:183], v101, s[86:87] offset:832
	global_load_dwordx4 v[184:187], v150, s[86:87] offset:832
	ds_read_b64_tr_b16 v[72:73], v231
	ds_read_b64_tr_b16 v[74:75], v231 offset:512
	ds_read_b64_tr_b16 v[76:77], v231 offset:2048
	ds_read_b64_tr_b16 v[78:79], v231 offset:2560
	ds_read_b64_tr_b16 v[220:221], v231 offset:1024
	ds_read_b64_tr_b16 v[222:223], v231 offset:1536
	ds_read_b64_tr_b16 v[224:225], v231 offset:3072
	ds_read_b64_tr_b16 v[226:227], v231 offset:3584
	v_exp_f32_e32 v188, v188
	v_exp_f32_e32 v189, v189
	v_exp_f32_e32 v190, v190
	v_exp_f32_e32 v191, v191
	s_waitcnt vmcnt(8)
	ds_write_b128 v247, v[116:119]
	ds_write_b128 v247, v[120:123] offset:1024
	ds_write_b128 v247, v[124:127] offset:2048
	ds_write_b128 v247, v[128:131] offset:3072
	ds_read_b128 v[116:119], v248
	ds_read_b128 v[120:123], v249
	ds_read_b128 v[124:127], v250
	ds_read_b128 v[128:131], v251
	ds_write_b128 v112, v[132:135]
	ds_write_b128 v112, v[136:139] offset:1024
	ds_write_b128 v112, v[140:143] offset:2048
	ds_write_b128 v112, v[144:147] offset:3072
	v_exp_f32_e32 v192, v192
	v_exp_f32_e32 v193, v193
	v_exp_f32_e32 v194, v194
	v_exp_f32_e32 v195, v195
	s_waitcnt lgkmcnt(4)
	v_mfma_f32_32x32x16_bf16 v[32:47], v[116:119], v[48:51], v[32:47]
	v_exp_f32_e32 v196, v196
	v_exp_f32_e32 v197, v197
	v_mfma_f32_32x32x16_bf16 v[32:47], v[120:123], v[52:55], v[32:47]
	v_exp_f32_e32 v198, v198
	v_exp_f32_e32 v199, v199
	v_mfma_f32_32x32x16_bf16 v[32:47], v[124:127], v[56:59], v[32:47]
	v_exp_f32_e32 v200, v200
	v_exp_f32_e32 v201, v201
	v_mfma_f32_32x32x16_bf16 v[32:47], v[128:131], v[60:63], v[32:47]
	v_exp_f32_e32 v202, v202
	v_exp_f32_e32 v203, v203
	v_cvt_pk_bf16_f32 v64, v188, v189
	v_cvt_pk_bf16_f32 v65, v190, v191
	v_cvt_pk_bf16_f32 v66, v192, v193
	v_cvt_pk_bf16_f32 v67, v194, v195
	v_cvt_pk_bf16_f32 v68, v196, v197
	v_cvt_pk_bf16_f32 v69, v198, v199
	v_cvt_pk_bf16_f32 v70, v200, v201
	v_cvt_pk_bf16_f32 v71, v202, v203
	v_pk_add_f32 v[232:233], v[232:233], v[188:189]
	v_pk_add_f32 v[232:233], v[232:233], v[190:191]
	v_pk_add_f32 v[232:233], v[232:233], v[192:193]
	v_pk_add_f32 v[232:233], v[232:233], v[194:195]
	v_pk_add_f32 v[232:233], v[232:233], v[196:197]
	v_pk_add_f32 v[232:233], v[232:233], v[198:199]
	v_pk_add_f32 v[232:233], v[232:233], v[200:201]
	v_pk_add_f32 v[232:233], v[232:233], v[202:203]
	ds_read2_b32 v[188:189], v115 offset0:224 offset1:225
	ds_read2_b32 v[190:191], v115 offset0:226 offset1:227
	ds_read2_b32 v[192:193], v115 offset0:232 offset1:233
	ds_read2_b32 v[194:195], v115 offset0:234 offset1:235
	ds_read2_b32 v[196:197], v115 offset0:240 offset1:241
	ds_read2_b32 v[198:199], v115 offset0:242 offset1:243
	ds_read2_b32 v[200:201], v115 offset0:248 offset1:249
	ds_read2_b32 v[202:203], v115 offset0:250 offset1:251
	v_mfma_f32_32x32x16_bf16 v[0:15], v[64:67], v[72:75], v[0:15]
	v_mfma_f32_32x32x16_bf16 v[16:31], v[64:67], v[76:79], v[16:31]
	v_mfma_f32_32x32x16_bf16 v[0:15], v[68:71], v[220:223], v[0:15]
	v_mfma_f32_32x32x16_bf16 v[16:31], v[68:71], v[224:227], v[16:31]
	global_load_dwordx4 v[116:119], v243, s[88:89]
	global_load_dwordx4 v[120:123], v244, s[88:89]
	global_load_dwordx4 v[124:127], v245, s[88:89]
	global_load_dwordx4 v[128:131], v246, s[88:89]
	global_load_dwordx4 v[132:135], v148, s[88:89] offset:768
	global_load_dwordx4 v[136:139], v151, s[88:89] offset:768
	global_load_dwordx4 v[140:143], v148, s[88:89] offset:832
	global_load_dwordx4 v[144:147], v151, s[88:89] offset:832
	s_add_u32 s88, s88, 0x300000
	s_addc_u32 s89, s89, 0
	ds_read_b64_tr_b16 v[72:73], v231
	ds_read_b64_tr_b16 v[74:75], v231 offset:512
	ds_read_b64_tr_b16 v[76:77], v231 offset:2048
	ds_read_b64_tr_b16 v[78:79], v231 offset:2560
	ds_read_b64_tr_b16 v[220:221], v231 offset:1024
	ds_read_b64_tr_b16 v[222:223], v231 offset:1536
	ds_read_b64_tr_b16 v[224:225], v231 offset:3072
	ds_read_b64_tr_b16 v[226:227], v231 offset:3584
	v_exp_f32_e32 v32, v32
	v_exp_f32_e32 v33, v33
	v_exp_f32_e32 v34, v34
	v_exp_f32_e32 v35, v35
	s_waitcnt vmcnt(8)
	ds_write_b128 v247, v[156:159]
	ds_write_b128 v247, v[160:163] offset:1024
	ds_write_b128 v247, v[164:167] offset:2048
	ds_write_b128 v247, v[168:171] offset:3072
	ds_read_b128 v[156:159], v248
	ds_read_b128 v[160:163], v249
	ds_read_b128 v[164:167], v250
	ds_read_b128 v[168:171], v251
	ds_write_b128 v112, v[172:175]
	ds_write_b128 v112, v[176:179] offset:1024
	ds_write_b128 v112, v[180:183] offset:2048
	ds_write_b128 v112, v[184:187] offset:3072
	v_exp_f32_e32 v36, v36
	v_exp_f32_e32 v37, v37
	v_exp_f32_e32 v38, v38
	v_exp_f32_e32 v39, v39
	s_waitcnt lgkmcnt(4)
	v_mfma_f32_32x32x16_bf16 v[188:203], v[156:159], v[48:51], v[188:203]
	v_exp_f32_e32 v40, v40
	v_exp_f32_e32 v41, v41
	v_mfma_f32_32x32x16_bf16 v[188:203], v[160:163], v[52:55], v[188:203]
	v_exp_f32_e32 v42, v42
	v_exp_f32_e32 v43, v43
	v_mfma_f32_32x32x16_bf16 v[188:203], v[164:167], v[56:59], v[188:203]
	v_exp_f32_e32 v44, v44
	v_exp_f32_e32 v45, v45
	v_mfma_f32_32x32x16_bf16 v[188:203], v[168:171], v[60:63], v[188:203]
	v_exp_f32_e32 v46, v46
	v_exp_f32_e32 v47, v47
	v_cvt_pk_bf16_f32 v64, v32, v33
	v_cvt_pk_bf16_f32 v65, v34, v35
	v_cvt_pk_bf16_f32 v66, v36, v37
	v_cvt_pk_bf16_f32 v67, v38, v39
	v_cvt_pk_bf16_f32 v68, v40, v41
	v_cvt_pk_bf16_f32 v69, v42, v43
	v_cvt_pk_bf16_f32 v70, v44, v45
	v_cvt_pk_bf16_f32 v71, v46, v47
	v_pk_add_f32 v[232:233], v[232:233], v[32:33]
	v_pk_add_f32 v[232:233], v[232:233], v[34:35]
	v_pk_add_f32 v[232:233], v[232:233], v[36:37]
	v_pk_add_f32 v[232:233], v[232:233], v[38:39]
	v_pk_add_f32 v[232:233], v[232:233], v[40:41]
	v_pk_add_f32 v[232:233], v[232:233], v[42:43]
	v_pk_add_f32 v[232:233], v[232:233], v[44:45]
	v_pk_add_f32 v[232:233], v[232:233], v[46:47]
	v_mov_b32_e32 v115, v230
	ds_read2_b32 v[32:33], v115 offset0:0 offset1:1
	ds_read2_b32 v[34:35], v115 offset0:2 offset1:3
	ds_read2_b32 v[36:37], v115 offset0:8 offset1:9
	ds_read2_b32 v[38:39], v115 offset0:10 offset1:11
	ds_read2_b32 v[40:41], v115 offset0:16 offset1:17
	ds_read2_b32 v[42:43], v115 offset0:18 offset1:19
	ds_read2_b32 v[44:45], v115 offset0:24 offset1:25
	ds_read2_b32 v[46:47], v115 offset0:26 offset1:27
	v_mfma_f32_32x32x16_bf16 v[0:15], v[64:67], v[72:75], v[0:15]
	v_mfma_f32_32x32x16_bf16 v[16:31], v[64:67], v[76:79], v[16:31]
	v_mfma_f32_32x32x16_bf16 v[0:15], v[68:71], v[220:223], v[0:15]
	v_mfma_f32_32x32x16_bf16 v[16:31], v[68:71], v[224:227], v[16:31]
	global_load_dwordx4 v[156:159], v243, s[88:89]
	global_load_dwordx4 v[160:163], v244, s[88:89]
	global_load_dwordx4 v[164:167], v245, s[88:89]
	global_load_dwordx4 v[168:171], v246, s[88:89]
	global_load_dwordx4 v[172:175], v148, s[88:89] offset:768
	global_load_dwordx4 v[176:179], v151, s[88:89] offset:768
	global_load_dwordx4 v[180:183], v148, s[88:89] offset:832
	global_load_dwordx4 v[184:187], v151, s[88:89] offset:832
	s_add_u32 s88, s88, 0x300000
	s_addc_u32 s89, s89, 0
	ds_read_b64_tr_b16 v[72:73], v231
	ds_read_b64_tr_b16 v[74:75], v231 offset:512
	ds_read_b64_tr_b16 v[76:77], v231 offset:2048
	ds_read_b64_tr_b16 v[78:79], v231 offset:2560
	ds_read_b64_tr_b16 v[220:221], v231 offset:1024
	ds_read_b64_tr_b16 v[222:223], v231 offset:1536
	ds_read_b64_tr_b16 v[224:225], v231 offset:3072
	ds_read_b64_tr_b16 v[226:227], v231 offset:3584
	v_exp_f32_e32 v188, v188
	v_exp_f32_e32 v189, v189
	v_exp_f32_e32 v190, v190
	v_exp_f32_e32 v191, v191
	s_waitcnt vmcnt(8)
	ds_write_b128 v247, v[116:119]
	ds_write_b128 v247, v[120:123] offset:1024
	ds_write_b128 v247, v[124:127] offset:2048
	ds_write_b128 v247, v[128:131] offset:3072
	ds_read_b128 v[116:119], v248
	ds_read_b128 v[120:123], v249
	ds_read_b128 v[124:127], v250
	ds_read_b128 v[128:131], v251
	ds_write_b128 v112, v[132:135]
	ds_write_b128 v112, v[136:139] offset:1024
	ds_write_b128 v112, v[140:143] offset:2048
	ds_write_b128 v112, v[144:147] offset:3072
	v_exp_f32_e32 v192, v192
	v_exp_f32_e32 v193, v193
	v_exp_f32_e32 v194, v194
	v_exp_f32_e32 v195, v195
	s_waitcnt lgkmcnt(4)
	v_mfma_f32_32x32x16_bf16 v[32:47], v[116:119], v[48:51], v[32:47]
	v_exp_f32_e32 v196, v196
	v_exp_f32_e32 v197, v197
	v_mfma_f32_32x32x16_bf16 v[32:47], v[120:123], v[52:55], v[32:47]
	v_exp_f32_e32 v198, v198
	v_exp_f32_e32 v199, v199
	v_mfma_f32_32x32x16_bf16 v[32:47], v[124:127], v[56:59], v[32:47]
	v_exp_f32_e32 v200, v200
	v_exp_f32_e32 v201, v201
	v_mfma_f32_32x32x16_bf16 v[32:47], v[128:131], v[60:63], v[32:47]
	v_exp_f32_e32 v202, v202
	v_exp_f32_e32 v203, v203
	v_cvt_pk_bf16_f32 v64, v188, v189
	v_cvt_pk_bf16_f32 v65, v190, v191
	v_cvt_pk_bf16_f32 v66, v192, v193
	v_cvt_pk_bf16_f32 v67, v194, v195
	v_cvt_pk_bf16_f32 v68, v196, v197
	v_cvt_pk_bf16_f32 v69, v198, v199
	v_cvt_pk_bf16_f32 v70, v200, v201
	v_cvt_pk_bf16_f32 v71, v202, v203
	v_pk_add_f32 v[232:233], v[232:233], v[188:189]
	v_pk_add_f32 v[232:233], v[232:233], v[190:191]
	v_pk_add_f32 v[232:233], v[232:233], v[192:193]
	v_pk_add_f32 v[232:233], v[232:233], v[194:195]
	v_pk_add_f32 v[232:233], v[232:233], v[196:197]
	v_pk_add_f32 v[232:233], v[232:233], v[198:199]
	v_pk_add_f32 v[232:233], v[232:233], v[200:201]
	v_pk_add_f32 v[232:233], v[232:233], v[202:203]
	ds_read2_b32 v[188:189], v115 offset0:32 offset1:33
	ds_read2_b32 v[190:191], v115 offset0:34 offset1:35
	ds_read2_b32 v[192:193], v115 offset0:40 offset1:41
	ds_read2_b32 v[194:195], v115 offset0:42 offset1:43
	ds_read2_b32 v[196:197], v115 offset0:48 offset1:49
	ds_read2_b32 v[198:199], v115 offset0:50 offset1:51
	ds_read2_b32 v[200:201], v115 offset0:56 offset1:57
	ds_read2_b32 v[202:203], v115 offset0:58 offset1:59
	v_mfma_f32_32x32x16_bf16 v[0:15], v[64:67], v[72:75], v[0:15]
	v_mfma_f32_32x32x16_bf16 v[16:31], v[64:67], v[76:79], v[16:31]
	v_mfma_f32_32x32x16_bf16 v[0:15], v[68:71], v[220:223], v[0:15]
	v_mfma_f32_32x32x16_bf16 v[16:31], v[68:71], v[224:227], v[16:31]
	global_load_dwordx4 v[116:119], v243, s[88:89]
	global_load_dwordx4 v[120:123], v244, s[88:89]
	global_load_dwordx4 v[124:127], v245, s[88:89]
	global_load_dwordx4 v[128:131], v246, s[88:89]
	global_load_dwordx4 v[132:135], v148, s[88:89] offset:768
	global_load_dwordx4 v[136:139], v151, s[88:89] offset:768
	global_load_dwordx4 v[140:143], v148, s[88:89] offset:832
	global_load_dwordx4 v[144:147], v151, s[88:89] offset:832
	s_add_u32 s88, s88, 0x300000
	s_addc_u32 s89, s89, 0
	ds_read_b64_tr_b16 v[72:73], v231
	ds_read_b64_tr_b16 v[74:75], v231 offset:512
	ds_read_b64_tr_b16 v[76:77], v231 offset:2048
	ds_read_b64_tr_b16 v[78:79], v231 offset:2560
	ds_read_b64_tr_b16 v[220:221], v231 offset:1024
	ds_read_b64_tr_b16 v[222:223], v231 offset:1536
	ds_read_b64_tr_b16 v[224:225], v231 offset:3072
	ds_read_b64_tr_b16 v[226:227], v231 offset:3584
	v_exp_f32_e32 v32, v32
	v_exp_f32_e32 v33, v33
	v_exp_f32_e32 v34, v34
	v_exp_f32_e32 v35, v35
	s_waitcnt vmcnt(8)
	ds_write_b128 v247, v[156:159]
	ds_write_b128 v247, v[160:163] offset:1024
	ds_write_b128 v247, v[164:167] offset:2048
	ds_write_b128 v247, v[168:171] offset:3072
	ds_read_b128 v[156:159], v248
	ds_read_b128 v[160:163], v249
	ds_read_b128 v[164:167], v250
	ds_read_b128 v[168:171], v251
	ds_write_b128 v112, v[172:175]
	ds_write_b128 v112, v[176:179] offset:1024
	ds_write_b128 v112, v[180:183] offset:2048
	ds_write_b128 v112, v[184:187] offset:3072
	v_exp_f32_e32 v36, v36
	v_exp_f32_e32 v37, v37
	v_exp_f32_e32 v38, v38
	v_exp_f32_e32 v39, v39
	s_waitcnt lgkmcnt(4)
	v_mfma_f32_32x32x16_bf16 v[188:203], v[156:159], v[48:51], v[188:203]
	v_exp_f32_e32 v40, v40
	v_exp_f32_e32 v41, v41
	v_mfma_f32_32x32x16_bf16 v[188:203], v[160:163], v[52:55], v[188:203]
	v_exp_f32_e32 v42, v42
	v_exp_f32_e32 v43, v43
	v_mfma_f32_32x32x16_bf16 v[188:203], v[164:167], v[56:59], v[188:203]
	v_exp_f32_e32 v44, v44
	v_exp_f32_e32 v45, v45
	v_mfma_f32_32x32x16_bf16 v[188:203], v[168:171], v[60:63], v[188:203]
	v_exp_f32_e32 v46, v46
	v_exp_f32_e32 v47, v47
	v_cvt_pk_bf16_f32 v64, v32, v33
	v_cvt_pk_bf16_f32 v65, v34, v35
	v_cvt_pk_bf16_f32 v66, v36, v37
	v_cvt_pk_bf16_f32 v67, v38, v39
	v_cvt_pk_bf16_f32 v68, v40, v41
	v_cvt_pk_bf16_f32 v69, v42, v43
	v_cvt_pk_bf16_f32 v70, v44, v45
	v_cvt_pk_bf16_f32 v71, v46, v47
	v_pk_add_f32 v[232:233], v[232:233], v[32:33]
	v_pk_add_f32 v[232:233], v[232:233], v[34:35]
	v_pk_add_f32 v[232:233], v[232:233], v[36:37]
	v_pk_add_f32 v[232:233], v[232:233], v[38:39]
	v_pk_add_f32 v[232:233], v[232:233], v[40:41]
	v_pk_add_f32 v[232:233], v[232:233], v[42:43]
	v_pk_add_f32 v[232:233], v[232:233], v[44:45]
	v_pk_add_f32 v[232:233], v[232:233], v[46:47]
	ds_read2_b32 v[32:33], v115 offset0:64 offset1:65
	ds_read2_b32 v[34:35], v115 offset0:66 offset1:67
	ds_read2_b32 v[36:37], v115 offset0:72 offset1:73
	ds_read2_b32 v[38:39], v115 offset0:74 offset1:75
	ds_read2_b32 v[40:41], v115 offset0:80 offset1:81
	ds_read2_b32 v[42:43], v115 offset0:82 offset1:83
	ds_read2_b32 v[44:45], v115 offset0:88 offset1:89
	ds_read2_b32 v[46:47], v115 offset0:90 offset1:91
	v_mfma_f32_32x32x16_bf16 v[0:15], v[64:67], v[72:75], v[0:15]
	v_mfma_f32_32x32x16_bf16 v[16:31], v[64:67], v[76:79], v[16:31]
	v_mfma_f32_32x32x16_bf16 v[0:15], v[68:71], v[220:223], v[0:15]
	v_mfma_f32_32x32x16_bf16 v[16:31], v[68:71], v[224:227], v[16:31]
	global_load_dwordx4 v[156:159], v243, s[88:89]
	global_load_dwordx4 v[160:163], v244, s[88:89]
	global_load_dwordx4 v[164:167], v245, s[88:89]
	global_load_dwordx4 v[168:171], v246, s[88:89]
	global_load_dwordx4 v[172:175], v148, s[88:89] offset:768
	global_load_dwordx4 v[176:179], v151, s[88:89] offset:768
	global_load_dwordx4 v[180:183], v148, s[88:89] offset:832
	global_load_dwordx4 v[184:187], v151, s[88:89] offset:832
	s_add_u32 s88, s88, 0x300000
	s_addc_u32 s89, s89, 0
	ds_read_b64_tr_b16 v[72:73], v231
	ds_read_b64_tr_b16 v[74:75], v231 offset:512
	ds_read_b64_tr_b16 v[76:77], v231 offset:2048
	ds_read_b64_tr_b16 v[78:79], v231 offset:2560
	ds_read_b64_tr_b16 v[220:221], v231 offset:1024
	ds_read_b64_tr_b16 v[222:223], v231 offset:1536
	ds_read_b64_tr_b16 v[224:225], v231 offset:3072
	ds_read_b64_tr_b16 v[226:227], v231 offset:3584
	v_exp_f32_e32 v188, v188
	v_exp_f32_e32 v189, v189
	v_exp_f32_e32 v190, v190
	v_exp_f32_e32 v191, v191
	s_waitcnt vmcnt(8)
	ds_write_b128 v247, v[116:119]
	ds_write_b128 v247, v[120:123] offset:1024
	ds_write_b128 v247, v[124:127] offset:2048
	ds_write_b128 v247, v[128:131] offset:3072
	ds_read_b128 v[116:119], v248
	ds_read_b128 v[120:123], v249
	ds_read_b128 v[124:127], v250
	ds_read_b128 v[128:131], v251
	ds_write_b128 v112, v[132:135]
	ds_write_b128 v112, v[136:139] offset:1024
	ds_write_b128 v112, v[140:143] offset:2048
	ds_write_b128 v112, v[144:147] offset:3072
	v_exp_f32_e32 v192, v192
	v_exp_f32_e32 v193, v193
	v_exp_f32_e32 v194, v194
	v_exp_f32_e32 v195, v195
	s_waitcnt lgkmcnt(4)
	v_mfma_f32_32x32x16_bf16 v[32:47], v[116:119], v[48:51], v[32:47]
	v_exp_f32_e32 v196, v196
	v_exp_f32_e32 v197, v197
	v_mfma_f32_32x32x16_bf16 v[32:47], v[120:123], v[52:55], v[32:47]
	v_exp_f32_e32 v198, v198
	v_exp_f32_e32 v199, v199
	v_mfma_f32_32x32x16_bf16 v[32:47], v[124:127], v[56:59], v[32:47]
	v_exp_f32_e32 v200, v200
	v_exp_f32_e32 v201, v201
	v_mfma_f32_32x32x16_bf16 v[32:47], v[128:131], v[60:63], v[32:47]
	v_exp_f32_e32 v202, v202
	v_exp_f32_e32 v203, v203
	v_cvt_pk_bf16_f32 v64, v188, v189
	v_cvt_pk_bf16_f32 v65, v190, v191
	v_cvt_pk_bf16_f32 v66, v192, v193
	v_cvt_pk_bf16_f32 v67, v194, v195
	v_cvt_pk_bf16_f32 v68, v196, v197
	v_cvt_pk_bf16_f32 v69, v198, v199
	v_cvt_pk_bf16_f32 v70, v200, v201
	v_cvt_pk_bf16_f32 v71, v202, v203
	v_pk_add_f32 v[232:233], v[232:233], v[188:189]
	v_pk_add_f32 v[232:233], v[232:233], v[190:191]
	v_pk_add_f32 v[232:233], v[232:233], v[192:193]
	v_pk_add_f32 v[232:233], v[232:233], v[194:195]
	v_pk_add_f32 v[232:233], v[232:233], v[196:197]
	v_pk_add_f32 v[232:233], v[232:233], v[198:199]
	v_pk_add_f32 v[232:233], v[232:233], v[200:201]
	v_pk_add_f32 v[232:233], v[232:233], v[202:203]
	ds_read2_b32 v[188:189], v115 offset0:96 offset1:97
	ds_read2_b32 v[190:191], v115 offset0:98 offset1:99
	ds_read2_b32 v[192:193], v115 offset0:104 offset1:105
	ds_read2_b32 v[194:195], v115 offset0:106 offset1:107
	ds_read2_b32 v[196:197], v115 offset0:112 offset1:113
	ds_read2_b32 v[198:199], v115 offset0:114 offset1:115
	ds_read2_b32 v[200:201], v115 offset0:120 offset1:121
	ds_read2_b32 v[202:203], v115 offset0:122 offset1:123
	v_mfma_f32_32x32x16_bf16 v[0:15], v[64:67], v[72:75], v[0:15]
	v_mfma_f32_32x32x16_bf16 v[16:31], v[64:67], v[76:79], v[16:31]
	v_mfma_f32_32x32x16_bf16 v[0:15], v[68:71], v[220:223], v[0:15]
	v_mfma_f32_32x32x16_bf16 v[16:31], v[68:71], v[224:227], v[16:31]
	global_load_dwordx4 v[116:119], v243, s[88:89]
	global_load_dwordx4 v[120:123], v244, s[88:89]
	global_load_dwordx4 v[124:127], v245, s[88:89]
	global_load_dwordx4 v[128:131], v246, s[88:89]
	global_load_dwordx4 v[132:135], v148, s[88:89] offset:768
	global_load_dwordx4 v[136:139], v151, s[88:89] offset:768
	global_load_dwordx4 v[140:143], v148, s[88:89] offset:832
	global_load_dwordx4 v[144:147], v151, s[88:89] offset:832
	ds_read_b64_tr_b16 v[72:73], v231
	ds_read_b64_tr_b16 v[74:75], v231 offset:512
	ds_read_b64_tr_b16 v[76:77], v231 offset:2048
	ds_read_b64_tr_b16 v[78:79], v231 offset:2560
	ds_read_b64_tr_b16 v[220:221], v231 offset:1024
	ds_read_b64_tr_b16 v[222:223], v231 offset:1536
	ds_read_b64_tr_b16 v[224:225], v231 offset:3072
	ds_read_b64_tr_b16 v[226:227], v231 offset:3584
	v_exp_f32_e32 v32, v32
	v_exp_f32_e32 v33, v33
	v_exp_f32_e32 v34, v34
	v_exp_f32_e32 v35, v35
	s_waitcnt vmcnt(8)
	ds_write_b128 v247, v[156:159]
	ds_write_b128 v247, v[160:163] offset:1024
	ds_write_b128 v247, v[164:167] offset:2048
	ds_write_b128 v247, v[168:171] offset:3072
	ds_read_b128 v[156:159], v248
	ds_read_b128 v[160:163], v249
	ds_read_b128 v[164:167], v250
	ds_read_b128 v[168:171], v251
	ds_write_b128 v112, v[172:175]
	ds_write_b128 v112, v[176:179] offset:1024
	ds_write_b128 v112, v[180:183] offset:2048
	ds_write_b128 v112, v[184:187] offset:3072
	v_exp_f32_e32 v36, v36
	v_exp_f32_e32 v37, v37
	v_exp_f32_e32 v38, v38
	v_exp_f32_e32 v39, v39
	s_waitcnt lgkmcnt(4)
	v_mfma_f32_32x32x16_bf16 v[188:203], v[156:159], v[48:51], v[188:203]
	v_exp_f32_e32 v40, v40
	v_exp_f32_e32 v41, v41
	v_mfma_f32_32x32x16_bf16 v[188:203], v[160:163], v[52:55], v[188:203]
	v_exp_f32_e32 v42, v42
	v_exp_f32_e32 v43, v43
	v_mfma_f32_32x32x16_bf16 v[188:203], v[164:167], v[56:59], v[188:203]
	v_exp_f32_e32 v44, v44
	v_exp_f32_e32 v45, v45
	v_mfma_f32_32x32x16_bf16 v[188:203], v[168:171], v[60:63], v[188:203]
	v_exp_f32_e32 v46, v46
	v_exp_f32_e32 v47, v47
	v_cvt_pk_bf16_f32 v64, v32, v33
	v_cvt_pk_bf16_f32 v65, v34, v35
	v_cvt_pk_bf16_f32 v66, v36, v37
	v_cvt_pk_bf16_f32 v67, v38, v39
	v_cvt_pk_bf16_f32 v68, v40, v41
	v_cvt_pk_bf16_f32 v69, v42, v43
	v_cvt_pk_bf16_f32 v70, v44, v45
	v_cvt_pk_bf16_f32 v71, v46, v47
	v_pk_add_f32 v[232:233], v[232:233], v[32:33]
	v_pk_add_f32 v[232:233], v[232:233], v[34:35]
	v_pk_add_f32 v[232:233], v[232:233], v[36:37]
	v_pk_add_f32 v[232:233], v[232:233], v[38:39]
	v_pk_add_f32 v[232:233], v[232:233], v[40:41]
	v_pk_add_f32 v[232:233], v[232:233], v[42:43]
	v_pk_add_f32 v[232:233], v[232:233], v[44:45]
	v_pk_add_f32 v[232:233], v[232:233], v[46:47]
	ds_read2_b32 v[32:33], v115 offset0:128 offset1:129
	ds_read2_b32 v[34:35], v115 offset0:130 offset1:131
	ds_read2_b32 v[36:37], v115 offset0:136 offset1:137
	ds_read2_b32 v[38:39], v115 offset0:138 offset1:139
	ds_read2_b32 v[40:41], v115 offset0:144 offset1:145
	ds_read2_b32 v[42:43], v115 offset0:146 offset1:147
	ds_read2_b32 v[44:45], v115 offset0:152 offset1:153
	ds_read2_b32 v[46:47], v115 offset0:154 offset1:155
	v_mfma_f32_32x32x16_bf16 v[0:15], v[64:67], v[72:75], v[0:15]
	v_mfma_f32_32x32x16_bf16 v[16:31], v[64:67], v[76:79], v[16:31]
	v_mfma_f32_32x32x16_bf16 v[0:15], v[68:71], v[220:223], v[0:15]
	v_mfma_f32_32x32x16_bf16 v[16:31], v[68:71], v[224:227], v[16:31]
	ds_read_b64_tr_b16 v[72:73], v231
	ds_read_b64_tr_b16 v[74:75], v231 offset:512
	ds_read_b64_tr_b16 v[76:77], v231 offset:2048
	ds_read_b64_tr_b16 v[78:79], v231 offset:2560
	ds_read_b64_tr_b16 v[220:221], v231 offset:1024
	ds_read_b64_tr_b16 v[222:223], v231 offset:1536
	ds_read_b64_tr_b16 v[224:225], v231 offset:3072
	ds_read_b64_tr_b16 v[226:227], v231 offset:3584
	v_exp_f32_e32 v188, v188
	v_exp_f32_e32 v189, v189
	v_exp_f32_e32 v190, v190
	v_exp_f32_e32 v191, v191
	s_waitcnt vmcnt(0)
; __device__ __forceinline__ int crow(int r, int hi) { return (r & 3) + 8 * (r >> 2) + 4 * hi; }
; __device__ __forceinline__ void dil_unit(LAS unsigned char* lds, bf16_t* proj, int seq, int hd, int T0, int rho) {
;     ...
;     l += __shfl_xor(l, 32);
; #pragma unroll
;     for (int rr = 0; rr < 16; ++rr) {
;         const int j = crow(rr, hi);
	ds_write_b128 v247, v[116:119]
	ds_write_b128 v247, v[120:123] offset:1024
	ds_write_b128 v247, v[124:127] offset:2048
	ds_write_b128 v247, v[128:131] offset:3072
	ds_read_b128 v[116:119], v248
	ds_read_b128 v[120:123], v249
	ds_read_b128 v[124:127], v250
	ds_read_b128 v[128:131], v251
	ds_write_b128 v112, v[132:135]
	ds_write_b128 v112, v[136:139] offset:1024
	ds_write_b128 v112, v[140:143] offset:2048
	ds_write_b128 v112, v[144:147] offset:3072
	v_exp_f32_e32 v192, v192
	v_exp_f32_e32 v193, v193
	v_exp_f32_e32 v194, v194
	v_exp_f32_e32 v195, v195
	s_waitcnt lgkmcnt(4)
	v_mfma_f32_32x32x16_bf16 v[32:47], v[116:119], v[48:51], v[32:47]
	v_exp_f32_e32 v196, v196
	v_exp_f32_e32 v197, v197
	v_mfma_f32_32x32x16_bf16 v[32:47], v[120:123], v[52:55], v[32:47]
	v_exp_f32_e32 v198, v198
	v_exp_f32_e32 v199, v199
	v_mfma_f32_32x32x16_bf16 v[32:47], v[124:127], v[56:59], v[32:47]
	v_exp_f32_e32 v200, v200
	v_exp_f32_e32 v201, v201
	v_mfma_f32_32x32x16_bf16 v[32:47], v[128:131], v[60:63], v[32:47]
	v_exp_f32_e32 v202, v202
	v_exp_f32_e32 v203, v203
	v_cvt_pk_bf16_f32 v64, v188, v189
	v_cvt_pk_bf16_f32 v65, v190, v191
	v_cvt_pk_bf16_f32 v66, v192, v193
	v_cvt_pk_bf16_f32 v67, v194, v195
	v_cvt_pk_bf16_f32 v68, v196, v197
	v_cvt_pk_bf16_f32 v69, v198, v199
	v_cvt_pk_bf16_f32 v70, v200, v201
	v_cvt_pk_bf16_f32 v71, v202, v203
	v_pk_add_f32 v[232:233], v[232:233], v[188:189]
	v_pk_add_f32 v[232:233], v[232:233], v[190:191]
	v_pk_add_f32 v[232:233], v[232:233], v[192:193]
	v_pk_add_f32 v[232:233], v[232:233], v[194:195]
	v_pk_add_f32 v[232:233], v[232:233], v[196:197]
	v_pk_add_f32 v[232:233], v[232:233], v[198:199]
	v_pk_add_f32 v[232:233], v[232:233], v[200:201]
	v_pk_add_f32 v[232:233], v[232:233], v[202:203]
	v_mfma_f32_32x32x16_bf16 v[0:15], v[64:67], v[72:75], v[0:15]
	v_mfma_f32_32x32x16_bf16 v[16:31], v[64:67], v[76:79], v[16:31]
	v_mfma_f32_32x32x16_bf16 v[0:15], v[68:71], v[220:223], v[0:15]
	v_mfma_f32_32x32x16_bf16 v[16:31], v[68:71], v[224:227], v[16:31]
	ds_read_b64_tr_b16 v[72:73], v231
	ds_read_b64_tr_b16 v[74:75], v231 offset:512
	ds_read_b64_tr_b16 v[76:77], v231 offset:2048
	ds_read_b64_tr_b16 v[78:79], v231 offset:2560
	ds_read_b64_tr_b16 v[220:221], v231 offset:1024
	ds_read_b64_tr_b16 v[222:223], v231 offset:1536
	ds_read_b64_tr_b16 v[224:225], v231 offset:3072
	ds_read_b64_tr_b16 v[226:227], v231 offset:3584
	s_waitcnt lgkmcnt(0)
	v_exp_f32_e32 v32, v32
	v_exp_f32_e32 v33, v33
	v_exp_f32_e32 v34, v34
	v_exp_f32_e32 v35, v35
	v_exp_f32_e32 v36, v36
	v_exp_f32_e32 v37, v37
	v_exp_f32_e32 v38, v38
	v_exp_f32_e32 v39, v39
	v_exp_f32_e32 v40, v40
	v_exp_f32_e32 v41, v41
	v_exp_f32_e32 v42, v42
	v_exp_f32_e32 v43, v43
	v_exp_f32_e32 v44, v44
	v_exp_f32_e32 v45, v45
	v_exp_f32_e32 v46, v46
	v_exp_f32_e32 v47, v47
	v_cvt_pk_bf16_f32 v64, v32, v33
	v_cvt_pk_bf16_f32 v65, v34, v35
	v_cvt_pk_bf16_f32 v66, v36, v37
	v_cvt_pk_bf16_f32 v67, v38, v39
	v_cvt_pk_bf16_f32 v68, v40, v41
	v_cvt_pk_bf16_f32 v69, v42, v43
	v_cvt_pk_bf16_f32 v70, v44, v45
	v_cvt_pk_bf16_f32 v71, v46, v47
	v_pk_add_f32 v[232:233], v[232:233], v[32:33]
	v_pk_add_f32 v[232:233], v[232:233], v[34:35]
	v_pk_add_f32 v[232:233], v[232:233], v[36:37]
	v_pk_add_f32 v[232:233], v[232:233], v[38:39]
	v_pk_add_f32 v[232:233], v[232:233], v[40:41]
	v_pk_add_f32 v[232:233], v[232:233], v[42:43]
	v_pk_add_f32 v[232:233], v[232:233], v[44:45]
	v_pk_add_f32 v[232:233], v[232:233], v[46:47]
	v_mfma_f32_32x32x16_bf16 v[0:15], v[64:67], v[72:75], v[0:15]
	v_mfma_f32_32x32x16_bf16 v[16:31], v[64:67], v[76:79], v[16:31]
	v_mfma_f32_32x32x16_bf16 v[0:15], v[68:71], v[220:223], v[0:15]
	v_mfma_f32_32x32x16_bf16 v[16:31], v[68:71], v[224:227], v[16:31]
	v_add_f32_e32 v113, v232, v233
	v_or_b32_e32 v114, 1, v107
	v_or_b32_e32 v97, 2, v107
	v_or_b32_e32 v96, 3, v107
	v_or_b32_e32 v95, 8, v107
	v_or_b32_e32 v94, 9, v107
	v_or_b32_e32 v93, 10, v107
	v_or_b32_e32 v92, 11, v107
	v_or_b32_e32 v91, 16, v107
	v_or_b32_e32 v90, 17, v107
	v_or_b32_e32 v89, 18, v107
	v_or_b32_e32 v88, 19, v107
	v_or_b32_e32 v87, 24, v107
	v_or_b32_e32 v86, 25, v107
	v_or_b32_e32 v85, 26, v107
	v_or_b32_e32 v84, 27, v107
	s_nop 11
	s_branch .LBB0_553
.LBB0_558:
	s_movk_i32 s100, 0x1800
	s_add_i32 s101, s6, 0x15c00
	s_lshl_b32 s90, s58, 1
	s_add_u32 s82, s56, s90
	s_addc_u32 s83, s57, 0
	s_add_u32 s82, s82, 0x1200
	s_addc_u32 s83, s83, 0
	s_sub_i32 s90, s76, 64
	s_mul_i32 s90, s90, 0x1800
	s_add_u32 s84, s82, s90
	s_addc_u32 s85, s83, 0
	s_sub_i32 s90, s76, 256
	s_mul_i32 s90, s90, 0x1800
	s_add_u32 s86, s82, s90
	s_addc_u32 s87, s83, 0
	s_sub_i32 s90, s76, 1024
	s_mul_i32 s90, s90, 0x1800
	s_add_u32 s88, s82, s90
	s_addc_u32 s89, s83, 0
	v_lshlrev_b32_e32 v153, 1, v98
	v_mad_u32_u24 v80, v105, s100, v82
	v_mad_u32_u24 v100, v110, s100, v153
	v_add_u32_e32 v149, 0x18000, v100
	v_lshlrev_b32_e32 v83, 2, v105
	v_mad_u32_u24 v83, v83, s100, v82
	v_lshlrev_b32_e32 v101, 2, v110
	v_mad_u32_u24 v101, v101, s100, v153
	v_add_u32_e32 v150, 0x60000, v101
	v_lshlrev_b32_e32 v99, 4, v105
	v_mad_u32_u24 v99, v99, s100, v82
	v_lshlrev_b32_e32 v148, 4, v110
	v_mad_u32_u24 v148, v148, s100, v153
	v_add_u32_e32 v151, 0x180000, v148
	v_lshrrev_b32_e32 v249, 3, v103
	v_and_b32_e32 v250, 7, v103
	v_lshlrev_b32_e32 v250, 4, v250
	v_add_u32_e32 v235, 0, v249
	v_add_u32_e32 v236, 8, v249
	v_add_u32_e32 v237, 16, v249
	v_add_u32_e32 v238, 24, v249
	v_add_u32_e32 v239, 0, v249
	v_lshlrev_b32_e32 v239, 2, v239
	v_add_u32_e32 v240, 8, v249
	v_lshlrev_b32_e32 v240, 2, v240
	v_add_u32_e32 v241, 16, v249
	v_lshlrev_b32_e32 v241, 2, v241
	v_add_u32_e32 v242, 24, v249
	v_lshlrev_b32_e32 v242, 2, v242
	v_add_u32_e32 v243, 0, v249
	v_lshlrev_b32_e32 v243, 4, v243
; #define LAS __attribute__((address_space(3)))
; #define GAS __attribute__((address_space(1)))
; __device__ __forceinline__ void dil_unit(LAS unsigned char* lds, bf16_t* proj, int seq, int hd, int T0, int rho) {
;     ...
;     LAS unsigned char* wbuf = lds + wid * 4096;
;     const LAS unsigned char* vp = wbuf + ((lane >> 4) & 1) * 32 + (lane & 3) * 8 + (4 * hi + ((lane & 15) >> 2)) * 64;
;     const int P0 = T0 + rho;
;     bf16x8 qr[4];
; #pragma unroll
;     for (int ks = 0; ks < 4; ++ks) qr[ks] = *(const GAS bf16x8*)(base + (size_t)(P0 + 16 * r32) * NIN + PC_LQ + hd * 64 + 16 * ks + 8 * hi);
;     f32x16 o0 = {}, o1 = {}; float l = 0.f;
;     const bool bound = (T0 < 1024) || (T0 >= 15360);
	v_add_u32_e32 v244, 8, v249
	v_lshlrev_b32_e32 v244, 4, v244
	v_add_u32_e32 v245, 16, v249
	v_lshlrev_b32_e32 v245, 4, v245
	v_add_u32_e32 v246, 24, v249
	v_lshlrev_b32_e32 v246, 4, v246
	v_mov_b32_e32 v252, v250
	v_mov_b32_e32 v100, v110
	v_add_u32_e32 v149, 16, v100
	v_lshlrev_b32_e32 v101, 2, v110
	v_add_u32_e32 v150, 64, v101
	v_lshlrev_b32_e32 v148, 4, v110
	v_add_u32_e32 v151, 256, v148
	s_mov_b32 s98, 0x4000
	s_mov_b32 s99, 0x3fff
	v_and_b32_e32 v247, 7, v249
	v_lshlrev_b32_e32 v247, 4, v247
	v_xor_b32_e32 v247, v247, v112
	v_and_b32_e32 v153, 7, v105
	v_or_b32_e32 v248, 0, v106
	v_xor_b32_e32 v248, v248, v153
	v_lshlrev_b32_e32 v248, 4, v248
	v_lshl_add_u32 v248, v105, 7, v248
	v_add_u32_e32 v248, s77, v248
	v_or_b32_e32 v249, 2, v106
	v_xor_b32_e32 v249, v249, v153
	v_lshlrev_b32_e32 v249, 4, v249
	v_lshl_add_u32 v249, v105, 7, v249
	v_add_u32_e32 v249, s77, v249
	v_or_b32_e32 v250, 4, v106
	v_xor_b32_e32 v250, v250, v153
	v_lshlrev_b32_e32 v250, 4, v250
	v_lshl_add_u32 v250, v105, 7, v250
	v_add_u32_e32 v250, s77, v250
	v_or_b32_e32 v251, 6, v106
	v_xor_b32_e32 v251, v251, v153
	v_lshlrev_b32_e32 v251, 4, v251
	v_lshl_add_u32 v251, v105, 7, v251
	v_add_u32_e32 v251, s77, v251
	v_lshlrev_b32_e32 v153, 1, v98
	v_mul_u32_u24_e32 v228, 17, v105
	v_sub_u32_e32 v228, v107, v228
	s_mul_i32 s90, s58, 153
	s_lshr_b32 s90, s90, 1
	s_add_i32 s90, s90, 34876
	v_lshl_add_u32 v228, v228, 2, s90
	v_lshlrev_b32_e32 v229, 2, v105
	v_sub_u32_e32 v229, v107, v229
	s_add_i32 s90, s101, 5104
	v_lshl_add_u32 v229, v229, 2, s90
	v_sub_u32_e32 v230, v107, v105
	s_add_i32 s90, s101, 6364
	v_lshl_add_u32 v230, v230, 2, s90
	v_add_u32_e32 v231, v109, v108
	v_mov_b64_e32 v[232:233], 0
	v_mov_b64_e32 v[0:1], 0
	v_mov_b64_e32 v[2:3], 0
	v_mov_b64_e32 v[4:5], 0
	v_mov_b64_e32 v[6:7], 0
	v_mov_b64_e32 v[8:9], 0
	v_mov_b64_e32 v[10:11], 0
	v_mov_b64_e32 v[12:13], 0
	v_mov_b64_e32 v[14:15], 0
	v_mov_b64_e32 v[16:17], 0
	v_mov_b64_e32 v[18:19], 0
	v_mov_b64_e32 v[20:21], 0
	v_mov_b64_e32 v[22:23], 0
	v_mov_b64_e32 v[24:25], 0
	v_mov_b64_e32 v[26:27], 0
	v_mov_b64_e32 v[28:29], 0
	v_mov_b64_e32 v[30:31], 0
	s_add_i32 s90, s76, -64
	v_add_u32_e32 v80, s90, v235
	v_add_u32_e32 v83, s90, v236
	v_add_u32_e32 v99, s90, v237
	v_add_u32_e32 v253, s90, v238
	v_add_u32_e32 v254, s90, v100
	v_add_u32_e32 v255, s90, v149
	v_med3_i32 v80, v80, 0, s99
	v_med3_i32 v83, v83, 0, s99
	v_med3_i32 v99, v99, 0, s99
	v_med3_i32 v253, v253, 0, s99
	v_med3_i32 v254, v254, 0, s99
	v_med3_i32 v255, v255, 0, s99
	v_mad_u32_u24 v80, v80, s100, v252
	v_mad_u32_u24 v83, v83, s100, v252
	v_mad_u32_u24 v99, v99, s100, v252
	v_mad_u32_u24 v253, v253, s100, v252
	v_mad_u32_u24 v254, v254, s100, v153
	v_mad_u32_u24 v255, v255, s100, v153
	global_load_dwordx4 v[116:119], v80, s[82:83]
	global_load_dwordx4 v[120:123], v83, s[82:83]
	global_load_dwordx4 v[124:127], v99, s[82:83]
	global_load_dwordx4 v[128:131], v253, s[82:83]
	global_load_dwordx4 v[132:135], v254, s[82:83] offset:768
	global_load_dwordx4 v[136:139], v255, s[82:83] offset:768
	global_load_dwordx4 v[140:143], v254, s[82:83] offset:832
	global_load_dwordx4 v[144:147], v255, s[82:83] offset:832
	s_add_i32 s90, s76, -32
	v_add_u32_e32 v80, s90, v235
	v_add_u32_e32 v83, s90, v236
	v_add_u32_e32 v99, s90, v237
	v_add_u32_e32 v253, s90, v238
	v_add_u32_e32 v254, s90, v100
	v_add_u32_e32 v255, s90, v149
	v_med3_i32 v80, v80, 0, s99
	v_med3_i32 v83, v83, 0, s99
	v_med3_i32 v99, v99, 0, s99
	v_med3_i32 v253, v253, 0, s99
	v_med3_i32 v254, v254, 0, s99
	v_med3_i32 v255, v255, 0, s99
	v_mad_u32_u24 v80, v80, s100, v252
	v_mad_u32_u24 v83, v83, s100, v252
	v_mad_u32_u24 v99, v99, s100, v252
	v_mad_u32_u24 v253, v253, s100, v252
	v_mad_u32_u24 v254, v254, s100, v153
	v_mad_u32_u24 v255, v255, s100, v153
	global_load_dwordx4 v[156:159], v80, s[82:83]
	global_load_dwordx4 v[160:163], v83, s[82:83]
	global_load_dwordx4 v[164:167], v99, s[82:83]
	global_load_dwordx4 v[168:171], v253, s[82:83]
	global_load_dwordx4 v[172:175], v254, s[82:83] offset:768
	global_load_dwordx4 v[176:179], v255, s[82:83] offset:768
	global_load_dwordx4 v[180:183], v254, s[82:83] offset:832
	global_load_dwordx4 v[184:187], v255, s[82:83] offset:832
	v_mov_b32_e32 v115, v228
	ds_read2_b32 v[32:33], v115 offset0:0 offset1:1
	ds_read2_b32 v[34:35], v115 offset0:2 offset1:3
	ds_read2_b32 v[36:37], v115 offset0:8 offset1:9
	ds_read2_b32 v[38:39], v115 offset0:10 offset1:11
	ds_read2_b32 v[40:41], v115 offset0:17 offset1:18
	ds_read2_b32 v[42:43], v115 offset0:19 offset1:20
	ds_read2_b32 v[44:45], v115 offset0:25 offset1:26
	ds_read2_b32 v[46:47], v115 offset0:27 offset1:28
	s_waitcnt vmcnt(8)
	ds_write_b128 v247, v[116:119]
	ds_write_b128 v247, v[120:123] offset:1024
	ds_write_b128 v247, v[124:127] offset:2048
	ds_write_b128 v247, v[128:131] offset:3072
	ds_read_b128 v[116:119], v248
	ds_read_b128 v[120:123], v249
	ds_read_b128 v[124:127], v250
	ds_read_b128 v[128:131], v251
	ds_write_b128 v112, v[132:135]
	ds_write_b128 v112, v[136:139] offset:1024
	ds_write_b128 v112, v[140:143] offset:2048
	ds_write_b128 v112, v[144:147] offset:3072
	s_waitcnt lgkmcnt(4)
	v_mfma_f32_32x32x16_bf16 v[32:47], v[116:119], v[48:51], v[32:47]
	v_mfma_f32_32x32x16_bf16 v[32:47], v[120:123], v[52:55], v[32:47]
	v_mfma_f32_32x32x16_bf16 v[32:47], v[124:127], v[56:59], v[32:47]
	v_mfma_f32_32x32x16_bf16 v[32:47], v[128:131], v[60:63], v[32:47]
	ds_read2_b32 v[188:189], v115 offset0:34 offset1:35
	ds_read2_b32 v[190:191], v115 offset0:36 offset1:37
	ds_read2_b32 v[192:193], v115 offset0:42 offset1:43
	ds_read2_b32 v[194:195], v115 offset0:44 offset1:45
	ds_read2_b32 v[196:197], v115 offset0:51 offset1:52
	ds_read2_b32 v[198:199], v115 offset0:53 offset1:54
	ds_read2_b32 v[200:201], v115 offset0:59 offset1:60
	ds_read2_b32 v[202:203], v115 offset0:61 offset1:62
	s_add_i32 s90, s76, 0
	v_add_u32_e32 v80, s90, v235
	v_add_u32_e32 v83, s90, v236
	v_add_u32_e32 v99, s90, v237
	v_add_u32_e32 v253, s90, v238
	v_add_u32_e32 v254, s90, v100
	v_add_u32_e32 v255, s90, v149
	v_med3_i32 v80, v80, 0, s99
	v_med3_i32 v83, v83, 0, s99
	v_med3_i32 v99, v99, 0, s99
	v_med3_i32 v253, v253, 0, s99
	v_med3_i32 v254, v254, 0, s99
	v_med3_i32 v255, v255, 0, s99
	v_mad_u32_u24 v80, v80, s100, v252
	v_mad_u32_u24 v83, v83, s100, v252
	v_mad_u32_u24 v99, v99, s100, v252
	v_mad_u32_u24 v253, v253, s100, v252
	v_mad_u32_u24 v254, v254, s100, v153
	v_mad_u32_u24 v255, v255, s100, v153
	global_load_dwordx4 v[116:119], v80, s[82:83]
	global_load_dwordx4 v[120:123], v83, s[82:83]
	global_load_dwordx4 v[124:127], v99, s[82:83]
	global_load_dwordx4 v[128:131], v253, s[82:83]
	global_load_dwordx4 v[132:135], v254, s[82:83] offset:768
	global_load_dwordx4 v[136:139], v255, s[82:83] offset:768
	global_load_dwordx4 v[140:143], v254, s[82:83] offset:832
	global_load_dwordx4 v[144:147], v255, s[82:83] offset:832
	ds_read_b64_tr_b16 v[72:73], v231
	ds_read_b64_tr_b16 v[74:75], v231 offset:512
	ds_read_b64_tr_b16 v[76:77], v231 offset:2048
	ds_read_b64_tr_b16 v[78:79], v231 offset:2560
	ds_read_b64_tr_b16 v[220:221], v231 offset:1024
	ds_read_b64_tr_b16 v[222:223], v231 offset:1536
	ds_read_b64_tr_b16 v[224:225], v231 offset:3072
	ds_read_b64_tr_b16 v[226:227], v231 offset:3584
	v_exp_f32_e32 v32, v32
	v_exp_f32_e32 v33, v33
	v_exp_f32_e32 v34, v34
	v_exp_f32_e32 v35, v35
	s_waitcnt vmcnt(8)
	ds_write_b128 v247, v[156:159]
	ds_write_b128 v247, v[160:163] offset:1024
	ds_write_b128 v247, v[164:167] offset:2048
	ds_write_b128 v247, v[168:171] offset:3072
	ds_read_b128 v[156:159], v248
	ds_read_b128 v[160:163], v249
	ds_read_b128 v[164:167], v250
	ds_read_b128 v[168:171], v251
	ds_write_b128 v112, v[172:175]
	ds_write_b128 v112, v[176:179] offset:1024
	ds_write_b128 v112, v[180:183] offset:2048
	ds_write_b128 v112, v[184:187] offset:3072
	v_exp_f32_e32 v36, v36
	v_exp_f32_e32 v37, v37
	v_exp_f32_e32 v38, v38
	v_exp_f32_e32 v39, v39
	s_waitcnt lgkmcnt(4)
	v_mfma_f32_32x32x16_bf16 v[188:203], v[156:159], v[48:51], v[188:203]
	v_exp_f32_e32 v40, v40
	v_exp_f32_e32 v41, v41
	v_mfma_f32_32x32x16_bf16 v[188:203], v[160:163], v[52:55], v[188:203]
	v_exp_f32_e32 v42, v42
	v_exp_f32_e32 v43, v43
	v_mfma_f32_32x32x16_bf16 v[188:203], v[164:167], v[56:59], v[188:203]
	v_exp_f32_e32 v44, v44
	v_exp_f32_e32 v45, v45
	v_mfma_f32_32x32x16_bf16 v[188:203], v[168:171], v[60:63], v[188:203]
	v_exp_f32_e32 v46, v46
	v_exp_f32_e32 v47, v47
	s_add_i32 s90, s76, -64
	v_add_u32_e32 v84, s90, v107
	v_add_u32_e32 v85, 0, v84
	v_add_u32_e32 v86, 1, v84
	v_add_u32_e32 v87, 2, v84
	v_add_u32_e32 v88, 3, v84
	v_cmp_gt_u32_e64 s[30:31], s98, v85
	v_cmp_gt_u32_e64 s[36:37], s98, v86
	v_cmp_gt_u32_e64 s[78:79], s98, v87
	v_cmp_gt_u32_e64 s[50:51], s98, v88
	v_cndmask_b32_e64 v32, 0, v32, s[30:31]
	v_add_u32_e32 v85, 8, v84
	v_cmp_gt_u32_e64 s[30:31], s98, v85
	v_cndmask_b32_e64 v33, 0, v33, s[36:37]
	v_add_u32_e32 v86, 9, v84
	v_cmp_gt_u32_e64 s[36:37], s98, v86
	v_cndmask_b32_e64 v34, 0, v34, s[78:79]
	v_add_u32_e32 v87, 10, v84
	v_cmp_gt_u32_e64 s[78:79], s98, v87
	v_cndmask_b32_e64 v35, 0, v35, s[50:51]
	v_add_u32_e32 v88, 11, v84
	v_cmp_gt_u32_e64 s[50:51], s98, v88
	v_cndmask_b32_e64 v36, 0, v36, s[30:31]
	v_add_u32_e32 v85, 16, v84
	v_cmp_gt_u32_e64 s[30:31], s98, v85
	v_cndmask_b32_e64 v37, 0, v37, s[36:37]
	v_add_u32_e32 v86, 17, v84
	v_cmp_gt_u32_e64 s[36:37], s98, v86
	v_cndmask_b32_e64 v38, 0, v38, s[78:79]
	v_add_u32_e32 v87, 18, v84
	v_cmp_gt_u32_e64 s[78:79], s98, v87
	v_cndmask_b32_e64 v39, 0, v39, s[50:51]
	v_add_u32_e32 v88, 19, v84
	v_cmp_gt_u32_e64 s[50:51], s98, v88
	v_cndmask_b32_e64 v40, 0, v40, s[30:31]
	v_add_u32_e32 v85, 24, v84
	v_cmp_gt_u32_e64 s[30:31], s98, v85
	v_cndmask_b32_e64 v41, 0, v41, s[36:37]
	v_add_u32_e32 v86, 25, v84
	v_cmp_gt_u32_e64 s[36:37], s98, v86
	v_cndmask_b32_e64 v42, 0, v42, s[78:79]
	v_add_u32_e32 v87, 26, v84
	v_cmp_gt_u32_e64 s[78:79], s98, v87
	v_cndmask_b32_e64 v43, 0, v43, s[50:51]
	v_add_u32_e32 v88, 27, v84
	v_cmp_gt_u32_e64 s[50:51], s98, v88
	v_nop
	v_cndmask_b32_e64 v44, 0, v44, s[30:31]
	v_cndmask_b32_e64 v45, 0, v45, s[36:37]
	v_cndmask_b32_e64 v46, 0, v46, s[78:79]
	v_cndmask_b32_e64 v47, 0, v47, s[50:51]
	v_cvt_pk_bf16_f32 v64, v32, v33
	v_cvt_pk_bf16_f32 v65, v34, v35
	v_cvt_pk_bf16_f32 v66, v36, v37
	v_cvt_pk_bf16_f32 v67, v38, v39
	v_cvt_pk_bf16_f32 v68, v40, v41
	v_cvt_pk_bf16_f32 v69, v42, v43
	v_cvt_pk_bf16_f32 v70, v44, v45
	v_cvt_pk_bf16_f32 v71, v46, v47
	v_pk_add_f32 v[232:233], v[232:233], v[32:33]
	v_pk_add_f32 v[232:233], v[232:233], v[34:35]
	v_pk_add_f32 v[232:233], v[232:233], v[36:37]
	v_pk_add_f32 v[232:233], v[232:233], v[38:39]
	v_pk_add_f32 v[232:233], v[232:233], v[40:41]
	v_pk_add_f32 v[232:233], v[232:233], v[42:43]
	v_pk_add_f32 v[232:233], v[232:233], v[44:45]
	v_pk_add_f32 v[232:233], v[232:233], v[46:47]
	ds_read2_b32 v[32:33], v115 offset0:68 offset1:69
	ds_read2_b32 v[34:35], v115 offset0:70 offset1:71
	ds_read2_b32 v[36:37], v115 offset0:76 offset1:77
	ds_read2_b32 v[38:39], v115 offset0:78 offset1:79
	ds_read2_b32 v[40:41], v115 offset0:85 offset1:86
	ds_read2_b32 v[42:43], v115 offset0:87 offset1:88
	ds_read2_b32 v[44:45], v115 offset0:93 offset1:94
	ds_read2_b32 v[46:47], v115 offset0:95 offset1:96
	v_mfma_f32_32x32x16_bf16 v[0:15], v[64:67], v[72:75], v[0:15]
	v_mfma_f32_32x32x16_bf16 v[16:31], v[64:67], v[76:79], v[16:31]
	v_mfma_f32_32x32x16_bf16 v[0:15], v[68:71], v[220:223], v[0:15]
	v_mfma_f32_32x32x16_bf16 v[16:31], v[68:71], v[224:227], v[16:31]
	s_add_i32 s90, s76, 32
	v_add_u32_e32 v80, s90, v235
	v_add_u32_e32 v83, s90, v236
	v_add_u32_e32 v99, s90, v237
	v_add_u32_e32 v253, s90, v238
	v_add_u32_e32 v254, s90, v100
	v_add_u32_e32 v255, s90, v149
	v_med3_i32 v80, v80, 0, s99
	v_med3_i32 v83, v83, 0, s99
	v_med3_i32 v99, v99, 0, s99
	v_med3_i32 v253, v253, 0, s99
	v_med3_i32 v254, v254, 0, s99
	v_med3_i32 v255, v255, 0, s99
	v_mad_u32_u24 v80, v80, s100, v252
	v_mad_u32_u24 v83, v83, s100, v252
	v_mad_u32_u24 v99, v99, s100, v252
	v_mad_u32_u24 v253, v253, s100, v252
	v_mad_u32_u24 v254, v254, s100, v153
	v_mad_u32_u24 v255, v255, s100, v153
	global_load_dwordx4 v[156:159], v80, s[82:83]
	global_load_dwordx4 v[160:163], v83, s[82:83]
	global_load_dwordx4 v[164:167], v99, s[82:83]
	global_load_dwordx4 v[168:171], v253, s[82:83]
	global_load_dwordx4 v[172:175], v254, s[82:83] offset:768
	global_load_dwordx4 v[176:179], v255, s[82:83] offset:768
	global_load_dwordx4 v[180:183], v254, s[82:83] offset:832
	global_load_dwordx4 v[184:187], v255, s[82:83] offset:832
	ds_read_b64_tr_b16 v[72:73], v231
	ds_read_b64_tr_b16 v[74:75], v231 offset:512
	ds_read_b64_tr_b16 v[76:77], v231 offset:2048
	ds_read_b64_tr_b16 v[78:79], v231 offset:2560
	ds_read_b64_tr_b16 v[220:221], v231 offset:1024
	ds_read_b64_tr_b16 v[222:223], v231 offset:1536
	ds_read_b64_tr_b16 v[224:225], v231 offset:3072
	ds_read_b64_tr_b16 v[226:227], v231 offset:3584
	v_exp_f32_e32 v188, v188
	v_exp_f32_e32 v189, v189
	v_exp_f32_e32 v190, v190
	v_exp_f32_e32 v191, v191
	s_waitcnt vmcnt(8)
	ds_write_b128 v247, v[116:119]
	ds_write_b128 v247, v[120:123] offset:1024
	ds_write_b128 v247, v[124:127] offset:2048
	ds_write_b128 v247, v[128:131] offset:3072
	ds_read_b128 v[116:119], v248
	ds_read_b128 v[120:123], v249
	ds_read_b128 v[124:127], v250
	ds_read_b128 v[128:131], v251
	ds_write_b128 v112, v[132:135]
	ds_write_b128 v112, v[136:139] offset:1024
	ds_write_b128 v112, v[140:143] offset:2048
	ds_write_b128 v112, v[144:147] offset:3072
	v_exp_f32_e32 v192, v192
	v_exp_f32_e32 v193, v193
	v_exp_f32_e32 v194, v194
	v_exp_f32_e32 v195, v195
	s_waitcnt lgkmcnt(4)
	v_mfma_f32_32x32x16_bf16 v[32:47], v[116:119], v[48:51], v[32:47]
	v_exp_f32_e32 v196, v196
	v_exp_f32_e32 v197, v197
	v_mfma_f32_32x32x16_bf16 v[32:47], v[120:123], v[52:55], v[32:47]
	v_exp_f32_e32 v198, v198
	v_exp_f32_e32 v199, v199
	v_mfma_f32_32x32x16_bf16 v[32:47], v[124:127], v[56:59], v[32:47]
	v_exp_f32_e32 v200, v200
	v_exp_f32_e32 v201, v201
	v_mfma_f32_32x32x16_bf16 v[32:47], v[128:131], v[60:63], v[32:47]
	v_exp_f32_e32 v202, v202
	v_exp_f32_e32 v203, v203
	s_add_i32 s90, s76, -32
	v_add_u32_e32 v84, s90, v107
	v_add_u32_e32 v85, 0, v84
	v_add_u32_e32 v86, 1, v84
	v_add_u32_e32 v87, 2, v84
	v_add_u32_e32 v88, 3, v84
	v_cmp_gt_u32_e64 s[30:31], s98, v85
	v_cmp_gt_u32_e64 s[36:37], s98, v86
	v_cmp_gt_u32_e64 s[78:79], s98, v87
	v_cmp_gt_u32_e64 s[50:51], s98, v88
	v_cndmask_b32_e64 v188, 0, v188, s[30:31]
	v_add_u32_e32 v85, 8, v84
	v_cmp_gt_u32_e64 s[30:31], s98, v85
	v_cndmask_b32_e64 v189, 0, v189, s[36:37]
	v_add_u32_e32 v86, 9, v84
	v_cmp_gt_u32_e64 s[36:37], s98, v86
	v_cndmask_b32_e64 v190, 0, v190, s[78:79]
	v_add_u32_e32 v87, 10, v84
	v_cmp_gt_u32_e64 s[78:79], s98, v87
	v_cndmask_b32_e64 v191, 0, v191, s[50:51]
	v_add_u32_e32 v88, 11, v84
	v_cmp_gt_u32_e64 s[50:51], s98, v88
	v_cndmask_b32_e64 v192, 0, v192, s[30:31]
	v_add_u32_e32 v85, 16, v84
	v_cmp_gt_u32_e64 s[30:31], s98, v85
	v_cndmask_b32_e64 v193, 0, v193, s[36:37]
	v_add_u32_e32 v86, 17, v84
	v_cmp_gt_u32_e64 s[36:37], s98, v86
	v_cndmask_b32_e64 v194, 0, v194, s[78:79]
	v_add_u32_e32 v87, 18, v84
	v_cmp_gt_u32_e64 s[78:79], s98, v87
	v_cndmask_b32_e64 v195, 0, v195, s[50:51]
	v_add_u32_e32 v88, 19, v84
	v_cmp_gt_u32_e64 s[50:51], s98, v88
	v_cndmask_b32_e64 v196, 0, v196, s[30:31]
	v_add_u32_e32 v85, 24, v84
	v_cmp_gt_u32_e64 s[30:31], s98, v85
	v_cndmask_b32_e64 v197, 0, v197, s[36:37]
	v_add_u32_e32 v86, 25, v84
	v_cmp_gt_u32_e64 s[36:37], s98, v86
	v_cndmask_b32_e64 v198, 0, v198, s[78:79]
	v_add_u32_e32 v87, 26, v84
	v_cmp_gt_u32_e64 s[78:79], s98, v87
	v_cndmask_b32_e64 v199, 0, v199, s[50:51]
	v_add_u32_e32 v88, 27, v84
	v_cmp_gt_u32_e64 s[50:51], s98, v88
	v_nop
	v_cndmask_b32_e64 v200, 0, v200, s[30:31]
	v_cndmask_b32_e64 v201, 0, v201, s[36:37]
	v_cndmask_b32_e64 v202, 0, v202, s[78:79]
	v_cndmask_b32_e64 v203, 0, v203, s[50:51]
	v_cvt_pk_bf16_f32 v64, v188, v189
	v_cvt_pk_bf16_f32 v65, v190, v191
	v_cvt_pk_bf16_f32 v66, v192, v193
	v_cvt_pk_bf16_f32 v67, v194, v195
	v_cvt_pk_bf16_f32 v68, v196, v197
	v_cvt_pk_bf16_f32 v69, v198, v199
	v_cvt_pk_bf16_f32 v70, v200, v201
	v_cvt_pk_bf16_f32 v71, v202, v203
	v_pk_add_f32 v[232:233], v[232:233], v[188:189]
	v_pk_add_f32 v[232:233], v[232:233], v[190:191]
	v_pk_add_f32 v[232:233], v[232:233], v[192:193]
	v_pk_add_f32 v[232:233], v[232:233], v[194:195]
	v_pk_add_f32 v[232:233], v[232:233], v[196:197]
	v_pk_add_f32 v[232:233], v[232:233], v[198:199]
	v_pk_add_f32 v[232:233], v[232:233], v[200:201]
	v_pk_add_f32 v[232:233], v[232:233], v[202:203]
	ds_read2_b32 v[188:189], v115 offset0:102 offset1:103
	ds_read2_b32 v[190:191], v115 offset0:104 offset1:105
	ds_read2_b32 v[192:193], v115 offset0:110 offset1:111
	ds_read2_b32 v[194:195], v115 offset0:112 offset1:113
	ds_read2_b32 v[196:197], v115 offset0:119 offset1:120
	ds_read2_b32 v[198:199], v115 offset0:121 offset1:122
	ds_read2_b32 v[200:201], v115 offset0:127 offset1:128
	ds_read2_b32 v[202:203], v115 offset0:129 offset1:130
	v_mfma_f32_32x32x16_bf16 v[0:15], v[64:67], v[72:75], v[0:15]
	v_mfma_f32_32x32x16_bf16 v[16:31], v[64:67], v[76:79], v[16:31]
	v_mfma_f32_32x32x16_bf16 v[0:15], v[68:71], v[220:223], v[0:15]
	v_mfma_f32_32x32x16_bf16 v[16:31], v[68:71], v[224:227], v[16:31]
	s_add_i32 s90, s76, 64
	v_add_u32_e32 v80, s90, v235
	v_add_u32_e32 v83, s90, v236
	v_add_u32_e32 v99, s90, v237
	v_add_u32_e32 v253, s90, v238
	v_add_u32_e32 v254, s90, v100
	v_add_u32_e32 v255, s90, v149
	v_med3_i32 v80, v80, 0, s99
	v_med3_i32 v83, v83, 0, s99
	v_med3_i32 v99, v99, 0, s99
	v_med3_i32 v253, v253, 0, s99
	v_med3_i32 v254, v254, 0, s99
	v_med3_i32 v255, v255, 0, s99
	v_mad_u32_u24 v80, v80, s100, v252
	v_mad_u32_u24 v83, v83, s100, v252
	v_mad_u32_u24 v99, v99, s100, v252
	v_mad_u32_u24 v253, v253, s100, v252
	v_mad_u32_u24 v254, v254, s100, v153
	v_mad_u32_u24 v255, v255, s100, v153
	global_load_dwordx4 v[116:119], v80, s[82:83]
	global_load_dwordx4 v[120:123], v83, s[82:83]
	global_load_dwordx4 v[124:127], v99, s[82:83]
	global_load_dwordx4 v[128:131], v253, s[82:83]
	global_load_dwordx4 v[132:135], v254, s[82:83] offset:768
	global_load_dwordx4 v[136:139], v255, s[82:83] offset:768
	global_load_dwordx4 v[140:143], v254, s[82:83] offset:832
	global_load_dwordx4 v[144:147], v255, s[82:83] offset:832
	ds_read_b64_tr_b16 v[72:73], v231
	ds_read_b64_tr_b16 v[74:75], v231 offset:512
	ds_read_b64_tr_b16 v[76:77], v231 offset:2048
	ds_read_b64_tr_b16 v[78:79], v231 offset:2560
	ds_read_b64_tr_b16 v[220:221], v231 offset:1024
	ds_read_b64_tr_b16 v[222:223], v231 offset:1536
	ds_read_b64_tr_b16 v[224:225], v231 offset:3072
	ds_read_b64_tr_b16 v[226:227], v231 offset:3584
	v_exp_f32_e32 v32, v32
	v_exp_f32_e32 v33, v33
	v_exp_f32_e32 v34, v34
	v_exp_f32_e32 v35, v35
	s_waitcnt vmcnt(8)
	ds_write_b128 v247, v[156:159]
	ds_write_b128 v247, v[160:163] offset:1024
	ds_write_b128 v247, v[164:167] offset:2048
	ds_write_b128 v247, v[168:171] offset:3072
	ds_read_b128 v[156:159], v248
	ds_read_b128 v[160:163], v249
	ds_read_b128 v[164:167], v250
	ds_read_b128 v[168:171], v251
	ds_write_b128 v112, v[172:175]
	ds_write_b128 v112, v[176:179] offset:1024
	ds_write_b128 v112, v[180:183] offset:2048
	ds_write_b128 v112, v[184:187] offset:3072
	v_exp_f32_e32 v36, v36
	v_exp_f32_e32 v37, v37
	v_exp_f32_e32 v38, v38
	v_exp_f32_e32 v39, v39
	s_waitcnt lgkmcnt(4)
	v_mfma_f32_32x32x16_bf16 v[188:203], v[156:159], v[48:51], v[188:203]
	v_exp_f32_e32 v40, v40
	v_exp_f32_e32 v41, v41
	v_mfma_f32_32x32x16_bf16 v[188:203], v[160:163], v[52:55], v[188:203]
	v_exp_f32_e32 v42, v42
	v_exp_f32_e32 v43, v43
	v_mfma_f32_32x32x16_bf16 v[188:203], v[164:167], v[56:59], v[188:203]
	v_exp_f32_e32 v44, v44
	v_exp_f32_e32 v45, v45
	v_mfma_f32_32x32x16_bf16 v[188:203], v[168:171], v[60:63], v[188:203]
	v_exp_f32_e32 v46, v46
	v_exp_f32_e32 v47, v47
	s_add_i32 s90, s76, 0
	v_add_u32_e32 v84, s90, v107
	v_add_u32_e32 v85, 0, v84
	v_add_u32_e32 v86, 1, v84
	v_add_u32_e32 v87, 2, v84
	v_add_u32_e32 v88, 3, v84
	v_cmp_gt_u32_e64 s[30:31], s98, v85
	v_cmp_gt_u32_e64 s[36:37], s98, v86
	v_cmp_gt_u32_e64 s[78:79], s98, v87
	v_cmp_gt_u32_e64 s[50:51], s98, v88
	v_cndmask_b32_e64 v32, 0, v32, s[30:31]
	v_add_u32_e32 v85, 8, v84
	v_cmp_gt_u32_e64 s[30:31], s98, v85
	v_cndmask_b32_e64 v33, 0, v33, s[36:37]
	v_add_u32_e32 v86, 9, v84
	v_cmp_gt_u32_e64 s[36:37], s98, v86
	v_cndmask_b32_e64 v34, 0, v34, s[78:79]
	v_add_u32_e32 v87, 10, v84
	v_cmp_gt_u32_e64 s[78:79], s98, v87
	v_cndmask_b32_e64 v35, 0, v35, s[50:51]
	v_add_u32_e32 v88, 11, v84
	v_cmp_gt_u32_e64 s[50:51], s98, v88
	v_cndmask_b32_e64 v36, 0, v36, s[30:31]
	v_add_u32_e32 v85, 16, v84
	v_cmp_gt_u32_e64 s[30:31], s98, v85
	v_cndmask_b32_e64 v37, 0, v37, s[36:37]
	v_add_u32_e32 v86, 17, v84
	v_cmp_gt_u32_e64 s[36:37], s98, v86
	v_cndmask_b32_e64 v38, 0, v38, s[78:79]
	v_add_u32_e32 v87, 18, v84
	v_cmp_gt_u32_e64 s[78:79], s98, v87
	v_cndmask_b32_e64 v39, 0, v39, s[50:51]
	v_add_u32_e32 v88, 19, v84
	v_cmp_gt_u32_e64 s[50:51], s98, v88
	v_cndmask_b32_e64 v40, 0, v40, s[30:31]
	v_add_u32_e32 v85, 24, v84
	v_cmp_gt_u32_e64 s[30:31], s98, v85
	v_cndmask_b32_e64 v41, 0, v41, s[36:37]
	v_add_u32_e32 v86, 25, v84
	v_cmp_gt_u32_e64 s[36:37], s98, v86
	v_cndmask_b32_e64 v42, 0, v42, s[78:79]
	v_add_u32_e32 v87, 26, v84
	v_cmp_gt_u32_e64 s[78:79], s98, v87
	v_cndmask_b32_e64 v43, 0, v43, s[50:51]
	v_add_u32_e32 v88, 27, v84
	v_cmp_gt_u32_e64 s[50:51], s98, v88
	v_nop
	v_cndmask_b32_e64 v44, 0, v44, s[30:31]
	v_cndmask_b32_e64 v45, 0, v45, s[36:37]
	v_cndmask_b32_e64 v46, 0, v46, s[78:79]
	v_cndmask_b32_e64 v47, 0, v47, s[50:51]
	v_cvt_pk_bf16_f32 v64, v32, v33
	v_cvt_pk_bf16_f32 v65, v34, v35
	v_cvt_pk_bf16_f32 v66, v36, v37
	v_cvt_pk_bf16_f32 v67, v38, v39
	v_cvt_pk_bf16_f32 v68, v40, v41
	v_cvt_pk_bf16_f32 v69, v42, v43
	v_cvt_pk_bf16_f32 v70, v44, v45
	v_cvt_pk_bf16_f32 v71, v46, v47
	v_pk_add_f32 v[232:233], v[232:233], v[32:33]
	v_pk_add_f32 v[232:233], v[232:233], v[34:35]
	v_pk_add_f32 v[232:233], v[232:233], v[36:37]
	v_pk_add_f32 v[232:233], v[232:233], v[38:39]
	v_pk_add_f32 v[232:233], v[232:233], v[40:41]
	v_pk_add_f32 v[232:233], v[232:233], v[42:43]
	v_pk_add_f32 v[232:233], v[232:233], v[44:45]
	v_pk_add_f32 v[232:233], v[232:233], v[46:47]
	ds_read2_b32 v[32:33], v115 offset0:136 offset1:137
	ds_read2_b32 v[34:35], v115 offset0:138 offset1:139
	ds_read2_b32 v[36:37], v115 offset0:144 offset1:145
	ds_read2_b32 v[38:39], v115 offset0:146 offset1:147
	ds_read2_b32 v[40:41], v115 offset0:153 offset1:154
	ds_read2_b32 v[42:43], v115 offset0:155 offset1:156
	ds_read2_b32 v[44:45], v115 offset0:161 offset1:162
	ds_read2_b32 v[46:47], v115 offset0:163 offset1:164
	v_mfma_f32_32x32x16_bf16 v[0:15], v[64:67], v[72:75], v[0:15]
	v_mfma_f32_32x32x16_bf16 v[16:31], v[64:67], v[76:79], v[16:31]
	v_mfma_f32_32x32x16_bf16 v[0:15], v[68:71], v[220:223], v[0:15]
	v_mfma_f32_32x32x16_bf16 v[16:31], v[68:71], v[224:227], v[16:31]
	s_add_i32 s90, s76, 96
	v_add_u32_e32 v80, s90, v235
	v_add_u32_e32 v83, s90, v236
	v_add_u32_e32 v99, s90, v237
	v_add_u32_e32 v253, s90, v238
	v_add_u32_e32 v254, s90, v100
	v_add_u32_e32 v255, s90, v149
	v_med3_i32 v80, v80, 0, s99
	v_med3_i32 v83, v83, 0, s99
	v_med3_i32 v99, v99, 0, s99
	v_med3_i32 v253, v253, 0, s99
	v_med3_i32 v254, v254, 0, s99
	v_med3_i32 v255, v255, 0, s99
	v_mad_u32_u24 v80, v80, s100, v252
	v_mad_u32_u24 v83, v83, s100, v252
	v_mad_u32_u24 v99, v99, s100, v252
	v_mad_u32_u24 v253, v253, s100, v252
	v_mad_u32_u24 v254, v254, s100, v153
	v_mad_u32_u24 v255, v255, s100, v153
	global_load_dwordx4 v[156:159], v80, s[82:83]
	global_load_dwordx4 v[160:163], v83, s[82:83]
	global_load_dwordx4 v[164:167], v99, s[82:83]
	global_load_dwordx4 v[168:171], v253, s[82:83]
	global_load_dwordx4 v[172:175], v254, s[82:83] offset:768
	global_load_dwordx4 v[176:179], v255, s[82:83] offset:768
	global_load_dwordx4 v[180:183], v254, s[82:83] offset:832
	global_load_dwordx4 v[184:187], v255, s[82:83] offset:832
	ds_read_b64_tr_b16 v[72:73], v231
	ds_read_b64_tr_b16 v[74:75], v231 offset:512
	ds_read_b64_tr_b16 v[76:77], v231 offset:2048
	ds_read_b64_tr_b16 v[78:79], v231 offset:2560
	ds_read_b64_tr_b16 v[220:221], v231 offset:1024
	ds_read_b64_tr_b16 v[222:223], v231 offset:1536
	ds_read_b64_tr_b16 v[224:225], v231 offset:3072
	ds_read_b64_tr_b16 v[226:227], v231 offset:3584
	v_exp_f32_e32 v188, v188
	v_exp_f32_e32 v189, v189
	v_exp_f32_e32 v190, v190
	v_exp_f32_e32 v191, v191
	s_waitcnt vmcnt(8)
	ds_write_b128 v247, v[116:119]
	ds_write_b128 v247, v[120:123] offset:1024
	ds_write_b128 v247, v[124:127] offset:2048
	ds_write_b128 v247, v[128:131] offset:3072
	ds_read_b128 v[116:119], v248
	ds_read_b128 v[120:123], v249
	ds_read_b128 v[124:127], v250
	ds_read_b128 v[128:131], v251
	ds_write_b128 v112, v[132:135]
	ds_write_b128 v112, v[136:139] offset:1024
	ds_write_b128 v112, v[140:143] offset:2048
	ds_write_b128 v112, v[144:147] offset:3072
	v_exp_f32_e32 v192, v192
	v_exp_f32_e32 v193, v193
	v_exp_f32_e32 v194, v194
	v_exp_f32_e32 v195, v195
	s_waitcnt lgkmcnt(4)
	v_mfma_f32_32x32x16_bf16 v[32:47], v[116:119], v[48:51], v[32:47]
	v_exp_f32_e32 v196, v196
	v_exp_f32_e32 v197, v197
	v_mfma_f32_32x32x16_bf16 v[32:47], v[120:123], v[52:55], v[32:47]
	v_exp_f32_e32 v198, v198
	v_exp_f32_e32 v199, v199
	v_mfma_f32_32x32x16_bf16 v[32:47], v[124:127], v[56:59], v[32:47]
	v_exp_f32_e32 v200, v200
	v_exp_f32_e32 v201, v201
	v_mfma_f32_32x32x16_bf16 v[32:47], v[128:131], v[60:63], v[32:47]
	v_exp_f32_e32 v202, v202
	v_exp_f32_e32 v203, v203
	s_add_i32 s90, s76, 32
	v_add_u32_e32 v84, s90, v107
	v_add_u32_e32 v85, 0, v84
	v_add_u32_e32 v86, 1, v84
	v_add_u32_e32 v87, 2, v84
	v_add_u32_e32 v88, 3, v84
	v_cmp_gt_u32_e64 s[30:31], s98, v85
	v_cmp_gt_u32_e64 s[36:37], s98, v86
	v_cmp_gt_u32_e64 s[78:79], s98, v87
	v_cmp_gt_u32_e64 s[50:51], s98, v88
	v_cndmask_b32_e64 v188, 0, v188, s[30:31]
	v_add_u32_e32 v85, 8, v84
	v_cmp_gt_u32_e64 s[30:31], s98, v85
	v_cndmask_b32_e64 v189, 0, v189, s[36:37]
	v_add_u32_e32 v86, 9, v84
	v_cmp_gt_u32_e64 s[36:37], s98, v86
	v_cndmask_b32_e64 v190, 0, v190, s[78:79]
	v_add_u32_e32 v87, 10, v84
	v_cmp_gt_u32_e64 s[78:79], s98, v87
	v_cndmask_b32_e64 v191, 0, v191, s[50:51]
	v_add_u32_e32 v88, 11, v84
	v_cmp_gt_u32_e64 s[50:51], s98, v88
	v_cndmask_b32_e64 v192, 0, v192, s[30:31]
	v_add_u32_e32 v85, 16, v84
	v_cmp_gt_u32_e64 s[30:31], s98, v85
	v_cndmask_b32_e64 v193, 0, v193, s[36:37]
	v_add_u32_e32 v86, 17, v84
	v_cmp_gt_u32_e64 s[36:37], s98, v86
	v_cndmask_b32_e64 v194, 0, v194, s[78:79]
	v_add_u32_e32 v87, 18, v84
	v_cmp_gt_u32_e64 s[78:79], s98, v87
	v_cndmask_b32_e64 v195, 0, v195, s[50:51]
	v_add_u32_e32 v88, 19, v84
	v_cmp_gt_u32_e64 s[50:51], s98, v88
	v_cndmask_b32_e64 v196, 0, v196, s[30:31]
	v_add_u32_e32 v85, 24, v84
	v_cmp_gt_u32_e64 s[30:31], s98, v85
	v_cndmask_b32_e64 v197, 0, v197, s[36:37]
	v_add_u32_e32 v86, 25, v84
	v_cmp_gt_u32_e64 s[36:37], s98, v86
	v_cndmask_b32_e64 v198, 0, v198, s[78:79]
	v_add_u32_e32 v87, 26, v84
	v_cmp_gt_u32_e64 s[78:79], s98, v87
	v_cndmask_b32_e64 v199, 0, v199, s[50:51]
	v_add_u32_e32 v88, 27, v84
	v_cmp_gt_u32_e64 s[50:51], s98, v88
	v_nop
	v_cndmask_b32_e64 v200, 0, v200, s[30:31]
	v_cndmask_b32_e64 v201, 0, v201, s[36:37]
	v_cndmask_b32_e64 v202, 0, v202, s[78:79]
	v_cndmask_b32_e64 v203, 0, v203, s[50:51]
	v_cvt_pk_bf16_f32 v64, v188, v189
	v_cvt_pk_bf16_f32 v65, v190, v191
	v_cvt_pk_bf16_f32 v66, v192, v193
	v_cvt_pk_bf16_f32 v67, v194, v195
	v_cvt_pk_bf16_f32 v68, v196, v197
	v_cvt_pk_bf16_f32 v69, v198, v199
	v_cvt_pk_bf16_f32 v70, v200, v201
	v_cvt_pk_bf16_f32 v71, v202, v203
	v_pk_add_f32 v[232:233], v[232:233], v[188:189]
	v_pk_add_f32 v[232:233], v[232:233], v[190:191]
	v_pk_add_f32 v[232:233], v[232:233], v[192:193]
	v_pk_add_f32 v[232:233], v[232:233], v[194:195]
	v_pk_add_f32 v[232:233], v[232:233], v[196:197]
	v_pk_add_f32 v[232:233], v[232:233], v[198:199]
	v_pk_add_f32 v[232:233], v[232:233], v[200:201]
	v_pk_add_f32 v[232:233], v[232:233], v[202:203]
	ds_read2_b32 v[188:189], v115 offset0:170 offset1:171
	ds_read2_b32 v[190:191], v115 offset0:172 offset1:173
	ds_read2_b32 v[192:193], v115 offset0:178 offset1:179
	ds_read2_b32 v[194:195], v115 offset0:180 offset1:181
	ds_read2_b32 v[196:197], v115 offset0:187 offset1:188
	ds_read2_b32 v[198:199], v115 offset0:189 offset1:190
	ds_read2_b32 v[200:201], v115 offset0:195 offset1:196
	ds_read2_b32 v[202:203], v115 offset0:197 offset1:198
	v_mfma_f32_32x32x16_bf16 v[0:15], v[64:67], v[72:75], v[0:15]
	v_mfma_f32_32x32x16_bf16 v[16:31], v[64:67], v[76:79], v[16:31]
	v_mfma_f32_32x32x16_bf16 v[0:15], v[68:71], v[220:223], v[0:15]
	v_mfma_f32_32x32x16_bf16 v[16:31], v[68:71], v[224:227], v[16:31]
	s_add_i32 s90, s76, 128
	v_add_u32_e32 v80, s90, v235
	v_add_u32_e32 v83, s90, v236
	v_add_u32_e32 v99, s90, v237
	v_add_u32_e32 v253, s90, v238
	v_add_u32_e32 v254, s90, v100
	v_add_u32_e32 v255, s90, v149
	v_med3_i32 v80, v80, 0, s99
	v_med3_i32 v83, v83, 0, s99
	v_med3_i32 v99, v99, 0, s99
	v_med3_i32 v253, v253, 0, s99
	v_med3_i32 v254, v254, 0, s99
	v_med3_i32 v255, v255, 0, s99
	v_mad_u32_u24 v80, v80, s100, v252
	v_mad_u32_u24 v83, v83, s100, v252
	v_mad_u32_u24 v99, v99, s100, v252
	v_mad_u32_u24 v253, v253, s100, v252
	v_mad_u32_u24 v254, v254, s100, v153
	v_mad_u32_u24 v255, v255, s100, v153
	global_load_dwordx4 v[116:119], v80, s[82:83]
	global_load_dwordx4 v[120:123], v83, s[82:83]
	global_load_dwordx4 v[124:127], v99, s[82:83]
	global_load_dwordx4 v[128:131], v253, s[82:83]
	global_load_dwordx4 v[132:135], v254, s[82:83] offset:768
	global_load_dwordx4 v[136:139], v255, s[82:83] offset:768
	global_load_dwordx4 v[140:143], v254, s[82:83] offset:832
	global_load_dwordx4 v[144:147], v255, s[82:83] offset:832
	ds_read_b64_tr_b16 v[72:73], v231
	ds_read_b64_tr_b16 v[74:75], v231 offset:512
	ds_read_b64_tr_b16 v[76:77], v231 offset:2048
	ds_read_b64_tr_b16 v[78:79], v231 offset:2560
	ds_read_b64_tr_b16 v[220:221], v231 offset:1024
	ds_read_b64_tr_b16 v[222:223], v231 offset:1536
	ds_read_b64_tr_b16 v[224:225], v231 offset:3072
	ds_read_b64_tr_b16 v[226:227], v231 offset:3584
	v_exp_f32_e32 v32, v32
	v_exp_f32_e32 v33, v33
	v_exp_f32_e32 v34, v34
	v_exp_f32_e32 v35, v35
	s_waitcnt vmcnt(8)
	ds_write_b128 v247, v[156:159]
	ds_write_b128 v247, v[160:163] offset:1024
	ds_write_b128 v247, v[164:167] offset:2048
	ds_write_b128 v247, v[168:171] offset:3072
	ds_read_b128 v[156:159], v248
	ds_read_b128 v[160:163], v249
	ds_read_b128 v[164:167], v250
	ds_read_b128 v[168:171], v251
	ds_write_b128 v112, v[172:175]
	ds_write_b128 v112, v[176:179] offset:1024
	ds_write_b128 v112, v[180:183] offset:2048
	ds_write_b128 v112, v[184:187] offset:3072
	v_exp_f32_e32 v36, v36
	v_exp_f32_e32 v37, v37
	v_exp_f32_e32 v38, v38
	v_exp_f32_e32 v39, v39
	s_waitcnt lgkmcnt(4)
	v_mfma_f32_32x32x16_bf16 v[188:203], v[156:159], v[48:51], v[188:203]
	v_exp_f32_e32 v40, v40
	v_exp_f32_e32 v41, v41
	v_mfma_f32_32x32x16_bf16 v[188:203], v[160:163], v[52:55], v[188:203]
	v_exp_f32_e32 v42, v42
	v_exp_f32_e32 v43, v43
	v_mfma_f32_32x32x16_bf16 v[188:203], v[164:167], v[56:59], v[188:203]
	v_exp_f32_e32 v44, v44
	v_exp_f32_e32 v45, v45
	v_mfma_f32_32x32x16_bf16 v[188:203], v[168:171], v[60:63], v[188:203]
	v_exp_f32_e32 v46, v46
	v_exp_f32_e32 v47, v47
	s_add_i32 s90, s76, 64
	v_add_u32_e32 v84, s90, v107
	v_add_u32_e32 v85, 0, v84
	v_add_u32_e32 v86, 1, v84
	v_add_u32_e32 v87, 2, v84
	v_add_u32_e32 v88, 3, v84
	v_cmp_gt_u32_e64 s[30:31], s98, v85
	v_cmp_gt_u32_e64 s[36:37], s98, v86
	v_cmp_gt_u32_e64 s[78:79], s98, v87
	v_cmp_gt_u32_e64 s[50:51], s98, v88
	v_cndmask_b32_e64 v32, 0, v32, s[30:31]
	v_add_u32_e32 v85, 8, v84
	v_cmp_gt_u32_e64 s[30:31], s98, v85
	v_cndmask_b32_e64 v33, 0, v33, s[36:37]
	v_add_u32_e32 v86, 9, v84
	v_cmp_gt_u32_e64 s[36:37], s98, v86
	v_cndmask_b32_e64 v34, 0, v34, s[78:79]
	v_add_u32_e32 v87, 10, v84
	v_cmp_gt_u32_e64 s[78:79], s98, v87
	v_cndmask_b32_e64 v35, 0, v35, s[50:51]
	v_add_u32_e32 v88, 11, v84
	v_cmp_gt_u32_e64 s[50:51], s98, v88
	v_cndmask_b32_e64 v36, 0, v36, s[30:31]
	v_add_u32_e32 v85, 16, v84
	v_cmp_gt_u32_e64 s[30:31], s98, v85
	v_cndmask_b32_e64 v37, 0, v37, s[36:37]
	v_add_u32_e32 v86, 17, v84
	v_cmp_gt_u32_e64 s[36:37], s98, v86
	v_cndmask_b32_e64 v38, 0, v38, s[78:79]
	v_add_u32_e32 v87, 18, v84
	v_cmp_gt_u32_e64 s[78:79], s98, v87
	v_cndmask_b32_e64 v39, 0, v39, s[50:51]
	v_add_u32_e32 v88, 19, v84
	v_cmp_gt_u32_e64 s[50:51], s98, v88
	v_cndmask_b32_e64 v40, 0, v40, s[30:31]
	v_add_u32_e32 v85, 24, v84
	v_cmp_gt_u32_e64 s[30:31], s98, v85
	v_cndmask_b32_e64 v41, 0, v41, s[36:37]
	v_add_u32_e32 v86, 25, v84
	v_cmp_gt_u32_e64 s[36:37], s98, v86
	v_cndmask_b32_e64 v42, 0, v42, s[78:79]
	v_add_u32_e32 v87, 26, v84
	v_cmp_gt_u32_e64 s[78:79], s98, v87
	v_cndmask_b32_e64 v43, 0, v43, s[50:51]
	v_add_u32_e32 v88, 27, v84
	v_cmp_gt_u32_e64 s[50:51], s98, v88
	v_nop
	v_cndmask_b32_e64 v44, 0, v44, s[30:31]
	v_cndmask_b32_e64 v45, 0, v45, s[36:37]
	v_cndmask_b32_e64 v46, 0, v46, s[78:79]
	v_cndmask_b32_e64 v47, 0, v47, s[50:51]
	v_cvt_pk_bf16_f32 v64, v32, v33
	v_cvt_pk_bf16_f32 v65, v34, v35
	v_cvt_pk_bf16_f32 v66, v36, v37
	v_cvt_pk_bf16_f32 v67, v38, v39
	v_cvt_pk_bf16_f32 v68, v40, v41
	v_cvt_pk_bf16_f32 v69, v42, v43
	v_cvt_pk_bf16_f32 v70, v44, v45
	v_cvt_pk_bf16_f32 v71, v46, v47
	v_pk_add_f32 v[232:233], v[232:233], v[32:33]
	v_pk_add_f32 v[232:233], v[232:233], v[34:35]
	v_pk_add_f32 v[232:233], v[232:233], v[36:37]
	v_pk_add_f32 v[232:233], v[232:233], v[38:39]
	v_pk_add_f32 v[232:233], v[232:233], v[40:41]
	v_pk_add_f32 v[232:233], v[232:233], v[42:43]
	v_pk_add_f32 v[232:233], v[232:233], v[44:45]
	v_pk_add_f32 v[232:233], v[232:233], v[46:47]
	ds_read2_b32 v[32:33], v115 offset0:204 offset1:205
	ds_read2_b32 v[34:35], v115 offset0:206 offset1:207
	ds_read2_b32 v[36:37], v115 offset0:212 offset1:213
	ds_read2_b32 v[38:39], v115 offset0:214 offset1:215
	ds_read2_b32 v[40:41], v115 offset0:221 offset1:222
	ds_read2_b32 v[42:43], v115 offset0:223 offset1:224
	ds_read2_b32 v[44:45], v115 offset0:229 offset1:230
	ds_read2_b32 v[46:47], v115 offset0:231 offset1:232
	v_mfma_f32_32x32x16_bf16 v[0:15], v[64:67], v[72:75], v[0:15]
	v_mfma_f32_32x32x16_bf16 v[16:31], v[64:67], v[76:79], v[16:31]
	v_mfma_f32_32x32x16_bf16 v[0:15], v[68:71], v[220:223], v[0:15]
	v_mfma_f32_32x32x16_bf16 v[16:31], v[68:71], v[224:227], v[16:31]
	s_add_i32 s90, s76, 160
	v_add_u32_e32 v80, s90, v235
	v_add_u32_e32 v83, s90, v236
	v_add_u32_e32 v99, s90, v237
	v_add_u32_e32 v253, s90, v238
	v_add_u32_e32 v254, s90, v100
	v_add_u32_e32 v255, s90, v149
	v_med3_i32 v80, v80, 0, s99
	v_med3_i32 v83, v83, 0, s99
	v_med3_i32 v99, v99, 0, s99
	v_med3_i32 v253, v253, 0, s99
	v_med3_i32 v254, v254, 0, s99
	v_med3_i32 v255, v255, 0, s99
	v_mad_u32_u24 v80, v80, s100, v252
	v_mad_u32_u24 v83, v83, s100, v252
	v_mad_u32_u24 v99, v99, s100, v252
	v_mad_u32_u24 v253, v253, s100, v252
	v_mad_u32_u24 v254, v254, s100, v153
	v_mad_u32_u24 v255, v255, s100, v153
	global_load_dwordx4 v[156:159], v80, s[82:83]
	global_load_dwordx4 v[160:163], v83, s[82:83]
	global_load_dwordx4 v[164:167], v99, s[82:83]
	global_load_dwordx4 v[168:171], v253, s[82:83]
	global_load_dwordx4 v[172:175], v254, s[82:83] offset:768
	global_load_dwordx4 v[176:179], v255, s[82:83] offset:768
	global_load_dwordx4 v[180:183], v254, s[82:83] offset:832
	global_load_dwordx4 v[184:187], v255, s[82:83] offset:832
	ds_read_b64_tr_b16 v[72:73], v231
	ds_read_b64_tr_b16 v[74:75], v231 offset:512
	ds_read_b64_tr_b16 v[76:77], v231 offset:2048
	ds_read_b64_tr_b16 v[78:79], v231 offset:2560
	ds_read_b64_tr_b16 v[220:221], v231 offset:1024
	ds_read_b64_tr_b16 v[222:223], v231 offset:1536
	ds_read_b64_tr_b16 v[224:225], v231 offset:3072
	ds_read_b64_tr_b16 v[226:227], v231 offset:3584
	v_exp_f32_e32 v188, v188
	v_exp_f32_e32 v189, v189
	v_exp_f32_e32 v190, v190
	v_exp_f32_e32 v191, v191
	s_waitcnt vmcnt(8)
	ds_write_b128 v247, v[116:119]
	ds_write_b128 v247, v[120:123] offset:1024
	ds_write_b128 v247, v[124:127] offset:2048
	ds_write_b128 v247, v[128:131] offset:3072
	ds_read_b128 v[116:119], v248
	ds_read_b128 v[120:123], v249
	ds_read_b128 v[124:127], v250
	ds_read_b128 v[128:131], v251
	ds_write_b128 v112, v[132:135]
	ds_write_b128 v112, v[136:139] offset:1024
	ds_write_b128 v112, v[140:143] offset:2048
	ds_write_b128 v112, v[144:147] offset:3072
	v_exp_f32_e32 v192, v192
	v_exp_f32_e32 v193, v193
	v_exp_f32_e32 v194, v194
	v_exp_f32_e32 v195, v195
	s_waitcnt lgkmcnt(4)
	v_mfma_f32_32x32x16_bf16 v[32:47], v[116:119], v[48:51], v[32:47]
	v_exp_f32_e32 v196, v196
	v_exp_f32_e32 v197, v197
	v_mfma_f32_32x32x16_bf16 v[32:47], v[120:123], v[52:55], v[32:47]
	v_exp_f32_e32 v198, v198
	v_exp_f32_e32 v199, v199
	v_mfma_f32_32x32x16_bf16 v[32:47], v[124:127], v[56:59], v[32:47]
	v_exp_f32_e32 v200, v200
	v_exp_f32_e32 v201, v201
	v_mfma_f32_32x32x16_bf16 v[32:47], v[128:131], v[60:63], v[32:47]
	v_exp_f32_e32 v202, v202
	v_exp_f32_e32 v203, v203
	s_add_i32 s90, s76, 96
	v_add_u32_e32 v84, s90, v107
	v_add_u32_e32 v85, 0, v84
	v_add_u32_e32 v86, 1, v84
	v_add_u32_e32 v87, 2, v84
	v_add_u32_e32 v88, 3, v84
	v_cmp_gt_u32_e64 s[30:31], s98, v85
	v_cmp_gt_u32_e64 s[36:37], s98, v86
	v_cmp_gt_u32_e64 s[78:79], s98, v87
	v_cmp_gt_u32_e64 s[50:51], s98, v88
	v_cndmask_b32_e64 v188, 0, v188, s[30:31]
	v_add_u32_e32 v85, 8, v84
	v_cmp_gt_u32_e64 s[30:31], s98, v85
	v_cndmask_b32_e64 v189, 0, v189, s[36:37]
	v_add_u32_e32 v86, 9, v84
	v_cmp_gt_u32_e64 s[36:37], s98, v86
	v_cndmask_b32_e64 v190, 0, v190, s[78:79]
	v_add_u32_e32 v87, 10, v84
	v_cmp_gt_u32_e64 s[78:79], s98, v87
	v_cndmask_b32_e64 v191, 0, v191, s[50:51]
	v_add_u32_e32 v88, 11, v84
	v_cmp_gt_u32_e64 s[50:51], s98, v88
	v_cndmask_b32_e64 v192, 0, v192, s[30:31]
	v_add_u32_e32 v85, 16, v84
	v_cmp_gt_u32_e64 s[30:31], s98, v85
	v_cndmask_b32_e64 v193, 0, v193, s[36:37]
	v_add_u32_e32 v86, 17, v84
	v_cmp_gt_u32_e64 s[36:37], s98, v86
	v_cndmask_b32_e64 v194, 0, v194, s[78:79]
	v_add_u32_e32 v87, 18, v84
	v_cmp_gt_u32_e64 s[78:79], s98, v87
	v_cndmask_b32_e64 v195, 0, v195, s[50:51]
	v_add_u32_e32 v88, 19, v84
	v_cmp_gt_u32_e64 s[50:51], s98, v88
	v_cndmask_b32_e64 v196, 0, v196, s[30:31]
	v_add_u32_e32 v85, 24, v84
	v_cmp_gt_u32_e64 s[30:31], s98, v85
	v_cndmask_b32_e64 v197, 0, v197, s[36:37]
	v_add_u32_e32 v86, 25, v84
	v_cmp_gt_u32_e64 s[36:37], s98, v86
	v_cndmask_b32_e64 v198, 0, v198, s[78:79]
	v_add_u32_e32 v87, 26, v84
	v_cmp_gt_u32_e64 s[78:79], s98, v87
	v_cndmask_b32_e64 v199, 0, v199, s[50:51]
	v_add_u32_e32 v88, 27, v84
	v_cmp_gt_u32_e64 s[50:51], s98, v88
	v_nop
	v_cndmask_b32_e64 v200, 0, v200, s[30:31]
	v_cndmask_b32_e64 v201, 0, v201, s[36:37]
	v_cndmask_b32_e64 v202, 0, v202, s[78:79]
	v_cndmask_b32_e64 v203, 0, v203, s[50:51]
	v_cvt_pk_bf16_f32 v64, v188, v189
	v_cvt_pk_bf16_f32 v65, v190, v191
	v_cvt_pk_bf16_f32 v66, v192, v193
	v_cvt_pk_bf16_f32 v67, v194, v195
	v_cvt_pk_bf16_f32 v68, v196, v197
	v_cvt_pk_bf16_f32 v69, v198, v199
	v_cvt_pk_bf16_f32 v70, v200, v201
	v_cvt_pk_bf16_f32 v71, v202, v203
	v_pk_add_f32 v[232:233], v[232:233], v[188:189]
	v_pk_add_f32 v[232:233], v[232:233], v[190:191]
	v_pk_add_f32 v[232:233], v[232:233], v[192:193]
	v_pk_add_f32 v[232:233], v[232:233], v[194:195]
	v_pk_add_f32 v[232:233], v[232:233], v[196:197]
	v_pk_add_f32 v[232:233], v[232:233], v[198:199]
	v_pk_add_f32 v[232:233], v[232:233], v[200:201]
	v_pk_add_f32 v[232:233], v[232:233], v[202:203]
	v_add_u32_e32 v115, 952, v115
	ds_read2_b32 v[188:189], v115 offset0:0 offset1:1
	ds_read2_b32 v[190:191], v115 offset0:2 offset1:3
	ds_read2_b32 v[192:193], v115 offset0:8 offset1:9
	ds_read2_b32 v[194:195], v115 offset0:10 offset1:11
	ds_read2_b32 v[196:197], v115 offset0:17 offset1:18
	ds_read2_b32 v[198:199], v115 offset0:19 offset1:20
	ds_read2_b32 v[200:201], v115 offset0:25 offset1:26
	ds_read2_b32 v[202:203], v115 offset0:27 offset1:28
	v_mfma_f32_32x32x16_bf16 v[0:15], v[64:67], v[72:75], v[0:15]
	v_mfma_f32_32x32x16_bf16 v[16:31], v[64:67], v[76:79], v[16:31]
	v_mfma_f32_32x32x16_bf16 v[0:15], v[68:71], v[220:223], v[0:15]
	v_mfma_f32_32x32x16_bf16 v[16:31], v[68:71], v[224:227], v[16:31]
	s_add_i32 s90, s76, 192
	v_add_u32_e32 v80, s90, v235
	v_add_u32_e32 v83, s90, v236
	v_add_u32_e32 v99, s90, v237
	v_add_u32_e32 v253, s90, v238
	v_add_u32_e32 v254, s90, v100
	v_add_u32_e32 v255, s90, v149
	v_med3_i32 v80, v80, 0, s99
	v_med3_i32 v83, v83, 0, s99
	v_med3_i32 v99, v99, 0, s99
	v_med3_i32 v253, v253, 0, s99
	v_med3_i32 v254, v254, 0, s99
	v_med3_i32 v255, v255, 0, s99
	v_mad_u32_u24 v80, v80, s100, v252
	v_mad_u32_u24 v83, v83, s100, v252
	v_mad_u32_u24 v99, v99, s100, v252
	v_mad_u32_u24 v253, v253, s100, v252
	v_mad_u32_u24 v254, v254, s100, v153
	v_mad_u32_u24 v255, v255, s100, v153
	global_load_dwordx4 v[116:119], v80, s[82:83]
	global_load_dwordx4 v[120:123], v83, s[82:83]
	global_load_dwordx4 v[124:127], v99, s[82:83]
	global_load_dwordx4 v[128:131], v253, s[82:83]
	global_load_dwordx4 v[132:135], v254, s[82:83] offset:768
	global_load_dwordx4 v[136:139], v255, s[82:83] offset:768
	global_load_dwordx4 v[140:143], v254, s[82:83] offset:832
	global_load_dwordx4 v[144:147], v255, s[82:83] offset:832
	ds_read_b64_tr_b16 v[72:73], v231
	ds_read_b64_tr_b16 v[74:75], v231 offset:512
	ds_read_b64_tr_b16 v[76:77], v231 offset:2048
	ds_read_b64_tr_b16 v[78:79], v231 offset:2560
	ds_read_b64_tr_b16 v[220:221], v231 offset:1024
	ds_read_b64_tr_b16 v[222:223], v231 offset:1536
	ds_read_b64_tr_b16 v[224:225], v231 offset:3072
	ds_read_b64_tr_b16 v[226:227], v231 offset:3584
	v_exp_f32_e32 v32, v32
	v_exp_f32_e32 v33, v33
	v_exp_f32_e32 v34, v34
	v_exp_f32_e32 v35, v35
	s_waitcnt vmcnt(8)
	ds_write_b128 v247, v[156:159]
	ds_write_b128 v247, v[160:163] offset:1024
	ds_write_b128 v247, v[164:167] offset:2048
	ds_write_b128 v247, v[168:171] offset:3072
	ds_read_b128 v[156:159], v248
	ds_read_b128 v[160:163], v249
	ds_read_b128 v[164:167], v250
	ds_read_b128 v[168:171], v251
	ds_write_b128 v112, v[172:175]
	ds_write_b128 v112, v[176:179] offset:1024
	ds_write_b128 v112, v[180:183] offset:2048
	ds_write_b128 v112, v[184:187] offset:3072
	v_exp_f32_e32 v36, v36
	v_exp_f32_e32 v37, v37
	v_exp_f32_e32 v38, v38
	v_exp_f32_e32 v39, v39
	s_waitcnt lgkmcnt(4)
	v_mfma_f32_32x32x16_bf16 v[188:203], v[156:159], v[48:51], v[188:203]
	v_exp_f32_e32 v40, v40
	v_exp_f32_e32 v41, v41
	v_mfma_f32_32x32x16_bf16 v[188:203], v[160:163], v[52:55], v[188:203]
	v_exp_f32_e32 v42, v42
	v_exp_f32_e32 v43, v43
	v_mfma_f32_32x32x16_bf16 v[188:203], v[164:167], v[56:59], v[188:203]
	v_exp_f32_e32 v44, v44
	v_exp_f32_e32 v45, v45
	v_mfma_f32_32x32x16_bf16 v[188:203], v[168:171], v[60:63], v[188:203]
	v_exp_f32_e32 v46, v46
	v_exp_f32_e32 v47, v47
	s_add_i32 s90, s76, 128
	v_add_u32_e32 v84, s90, v107
	v_add_u32_e32 v85, 0, v84
	v_add_u32_e32 v86, 1, v84
	v_add_u32_e32 v87, 2, v84
	v_add_u32_e32 v88, 3, v84
	v_cmp_gt_u32_e64 s[30:31], s98, v85
	v_cmp_gt_u32_e64 s[36:37], s98, v86
	v_cmp_gt_u32_e64 s[78:79], s98, v87
	v_cmp_gt_u32_e64 s[50:51], s98, v88
	v_cndmask_b32_e64 v32, 0, v32, s[30:31]
	v_add_u32_e32 v85, 8, v84
	v_cmp_gt_u32_e64 s[30:31], s98, v85
	v_cndmask_b32_e64 v33, 0, v33, s[36:37]
	v_add_u32_e32 v86, 9, v84
	v_cmp_gt_u32_e64 s[36:37], s98, v86
	v_cndmask_b32_e64 v34, 0, v34, s[78:79]
	v_add_u32_e32 v87, 10, v84
	v_cmp_gt_u32_e64 s[78:79], s98, v87
	v_cndmask_b32_e64 v35, 0, v35, s[50:51]
	v_add_u32_e32 v88, 11, v84
	v_cmp_gt_u32_e64 s[50:51], s98, v88
	v_cndmask_b32_e64 v36, 0, v36, s[30:31]
	v_add_u32_e32 v85, 16, v84
	v_cmp_gt_u32_e64 s[30:31], s98, v85
	v_cndmask_b32_e64 v37, 0, v37, s[36:37]
	v_add_u32_e32 v86, 17, v84
	v_cmp_gt_u32_e64 s[36:37], s98, v86
	v_cndmask_b32_e64 v38, 0, v38, s[78:79]
	v_add_u32_e32 v87, 18, v84
	v_cmp_gt_u32_e64 s[78:79], s98, v87
	v_cndmask_b32_e64 v39, 0, v39, s[50:51]
	v_add_u32_e32 v88, 19, v84
	v_cmp_gt_u32_e64 s[50:51], s98, v88
	v_cndmask_b32_e64 v40, 0, v40, s[30:31]
	v_add_u32_e32 v85, 24, v84
	v_cmp_gt_u32_e64 s[30:31], s98, v85
	v_cndmask_b32_e64 v41, 0, v41, s[36:37]
	v_add_u32_e32 v86, 25, v84
	v_cmp_gt_u32_e64 s[36:37], s98, v86
	v_cndmask_b32_e64 v42, 0, v42, s[78:79]
	v_add_u32_e32 v87, 26, v84
	v_cmp_gt_u32_e64 s[78:79], s98, v87
	v_cndmask_b32_e64 v43, 0, v43, s[50:51]
	v_add_u32_e32 v88, 27, v84
	v_cmp_gt_u32_e64 s[50:51], s98, v88
	v_nop
	v_cndmask_b32_e64 v44, 0, v44, s[30:31]
	v_cndmask_b32_e64 v45, 0, v45, s[36:37]
	v_cndmask_b32_e64 v46, 0, v46, s[78:79]
	v_cndmask_b32_e64 v47, 0, v47, s[50:51]
	v_cvt_pk_bf16_f32 v64, v32, v33
	v_cvt_pk_bf16_f32 v65, v34, v35
	v_cvt_pk_bf16_f32 v66, v36, v37
	v_cvt_pk_bf16_f32 v67, v38, v39
	v_cvt_pk_bf16_f32 v68, v40, v41
	v_cvt_pk_bf16_f32 v69, v42, v43
	v_cvt_pk_bf16_f32 v70, v44, v45
	v_cvt_pk_bf16_f32 v71, v46, v47
	v_pk_add_f32 v[232:233], v[232:233], v[32:33]
	v_pk_add_f32 v[232:233], v[232:233], v[34:35]
	v_pk_add_f32 v[232:233], v[232:233], v[36:37]
	v_pk_add_f32 v[232:233], v[232:233], v[38:39]
	v_pk_add_f32 v[232:233], v[232:233], v[40:41]
	v_pk_add_f32 v[232:233], v[232:233], v[42:43]
	v_pk_add_f32 v[232:233], v[232:233], v[44:45]
	v_pk_add_f32 v[232:233], v[232:233], v[46:47]
	ds_read2_b32 v[32:33], v115 offset0:34 offset1:35
	ds_read2_b32 v[34:35], v115 offset0:36 offset1:37
	ds_read2_b32 v[36:37], v115 offset0:42 offset1:43
	ds_read2_b32 v[38:39], v115 offset0:44 offset1:45
	ds_read2_b32 v[40:41], v115 offset0:51 offset1:52
	ds_read2_b32 v[42:43], v115 offset0:53 offset1:54
	ds_read2_b32 v[44:45], v115 offset0:59 offset1:60
	ds_read2_b32 v[46:47], v115 offset0:61 offset1:62
	v_mfma_f32_32x32x16_bf16 v[0:15], v[64:67], v[72:75], v[0:15]
	v_mfma_f32_32x32x16_bf16 v[16:31], v[64:67], v[76:79], v[16:31]
	v_mfma_f32_32x32x16_bf16 v[0:15], v[68:71], v[220:223], v[0:15]
	v_mfma_f32_32x32x16_bf16 v[16:31], v[68:71], v[224:227], v[16:31]
	s_add_i32 s90, s76, 224
	v_add_u32_e32 v80, s90, v235
	v_add_u32_e32 v83, s90, v236
	v_add_u32_e32 v99, s90, v237
	v_add_u32_e32 v253, s90, v238
	v_add_u32_e32 v254, s90, v100
	v_add_u32_e32 v255, s90, v149
	v_med3_i32 v80, v80, 0, s99
	v_med3_i32 v83, v83, 0, s99
	v_med3_i32 v99, v99, 0, s99
	v_med3_i32 v253, v253, 0, s99
	v_med3_i32 v254, v254, 0, s99
	v_med3_i32 v255, v255, 0, s99
	v_mad_u32_u24 v80, v80, s100, v252
	v_mad_u32_u24 v83, v83, s100, v252
	v_mad_u32_u24 v99, v99, s100, v252
	v_mad_u32_u24 v253, v253, s100, v252
	v_mad_u32_u24 v254, v254, s100, v153
	v_mad_u32_u24 v255, v255, s100, v153
	global_load_dwordx4 v[156:159], v80, s[82:83]
	global_load_dwordx4 v[160:163], v83, s[82:83]
	global_load_dwordx4 v[164:167], v99, s[82:83]
	global_load_dwordx4 v[168:171], v253, s[82:83]
	global_load_dwordx4 v[172:175], v254, s[82:83] offset:768
	global_load_dwordx4 v[176:179], v255, s[82:83] offset:768
	global_load_dwordx4 v[180:183], v254, s[82:83] offset:832
	global_load_dwordx4 v[184:187], v255, s[82:83] offset:832
	ds_read_b64_tr_b16 v[72:73], v231
	ds_read_b64_tr_b16 v[74:75], v231 offset:512
	ds_read_b64_tr_b16 v[76:77], v231 offset:2048
	ds_read_b64_tr_b16 v[78:79], v231 offset:2560
	ds_read_b64_tr_b16 v[220:221], v231 offset:1024
	ds_read_b64_tr_b16 v[222:223], v231 offset:1536
	ds_read_b64_tr_b16 v[224:225], v231 offset:3072
	ds_read_b64_tr_b16 v[226:227], v231 offset:3584
	v_exp_f32_e32 v188, v188
	v_exp_f32_e32 v189, v189
	v_exp_f32_e32 v190, v190
	v_exp_f32_e32 v191, v191
	s_waitcnt vmcnt(8)
	ds_write_b128 v247, v[116:119]
	ds_write_b128 v247, v[120:123] offset:1024
	ds_write_b128 v247, v[124:127] offset:2048
	ds_write_b128 v247, v[128:131] offset:3072
	ds_read_b128 v[116:119], v248
	ds_read_b128 v[120:123], v249
	ds_read_b128 v[124:127], v250
	ds_read_b128 v[128:131], v251
	ds_write_b128 v112, v[132:135]
	ds_write_b128 v112, v[136:139] offset:1024
	ds_write_b128 v112, v[140:143] offset:2048
	ds_write_b128 v112, v[144:147] offset:3072
	v_exp_f32_e32 v192, v192
	v_exp_f32_e32 v193, v193
	v_exp_f32_e32 v194, v194
	v_exp_f32_e32 v195, v195
	s_waitcnt lgkmcnt(4)
	v_mfma_f32_32x32x16_bf16 v[32:47], v[116:119], v[48:51], v[32:47]
	v_exp_f32_e32 v196, v196
	v_exp_f32_e32 v197, v197
	v_mfma_f32_32x32x16_bf16 v[32:47], v[120:123], v[52:55], v[32:47]
	v_exp_f32_e32 v198, v198
	v_exp_f32_e32 v199, v199
	v_mfma_f32_32x32x16_bf16 v[32:47], v[124:127], v[56:59], v[32:47]
	v_exp_f32_e32 v200, v200
	v_exp_f32_e32 v201, v201
	v_mfma_f32_32x32x16_bf16 v[32:47], v[128:131], v[60:63], v[32:47]
	v_exp_f32_e32 v202, v202
	v_exp_f32_e32 v203, v203
	s_add_i32 s90, s76, 160
	v_add_u32_e32 v84, s90, v107
	v_add_u32_e32 v85, 0, v84
	v_add_u32_e32 v86, 1, v84
	v_add_u32_e32 v87, 2, v84
	v_add_u32_e32 v88, 3, v84
	v_cmp_gt_u32_e64 s[30:31], s98, v85
	v_cmp_gt_u32_e64 s[36:37], s98, v86
	v_cmp_gt_u32_e64 s[78:79], s98, v87
	v_cmp_gt_u32_e64 s[50:51], s98, v88
	v_cndmask_b32_e64 v188, 0, v188, s[30:31]
	v_add_u32_e32 v85, 8, v84
	v_cmp_gt_u32_e64 s[30:31], s98, v85
	v_cndmask_b32_e64 v189, 0, v189, s[36:37]
	v_add_u32_e32 v86, 9, v84
	v_cmp_gt_u32_e64 s[36:37], s98, v86
	v_cndmask_b32_e64 v190, 0, v190, s[78:79]
	v_add_u32_e32 v87, 10, v84
	v_cmp_gt_u32_e64 s[78:79], s98, v87
	v_cndmask_b32_e64 v191, 0, v191, s[50:51]
	v_add_u32_e32 v88, 11, v84
	v_cmp_gt_u32_e64 s[50:51], s98, v88
	v_cndmask_b32_e64 v192, 0, v192, s[30:31]
	v_add_u32_e32 v85, 16, v84
	v_cmp_gt_u32_e64 s[30:31], s98, v85
	v_cndmask_b32_e64 v193, 0, v193, s[36:37]
	v_add_u32_e32 v86, 17, v84
	v_cmp_gt_u32_e64 s[36:37], s98, v86
	v_cndmask_b32_e64 v194, 0, v194, s[78:79]
	v_add_u32_e32 v87, 18, v84
	v_cmp_gt_u32_e64 s[78:79], s98, v87
	v_cndmask_b32_e64 v195, 0, v195, s[50:51]
	v_add_u32_e32 v88, 19, v84
	v_cmp_gt_u32_e64 s[50:51], s98, v88
	v_cndmask_b32_e64 v196, 0, v196, s[30:31]
	v_add_u32_e32 v85, 24, v84
	v_cmp_gt_u32_e64 s[30:31], s98, v85
	v_cndmask_b32_e64 v197, 0, v197, s[36:37]
	v_add_u32_e32 v86, 25, v84
	v_cmp_gt_u32_e64 s[36:37], s98, v86
	v_cndmask_b32_e64 v198, 0, v198, s[78:79]
	v_add_u32_e32 v87, 26, v84
	v_cmp_gt_u32_e64 s[78:79], s98, v87
	v_cndmask_b32_e64 v199, 0, v199, s[50:51]
	v_add_u32_e32 v88, 27, v84
	v_cmp_gt_u32_e64 s[50:51], s98, v88
	v_nop
	v_cndmask_b32_e64 v200, 0, v200, s[30:31]
	v_cndmask_b32_e64 v201, 0, v201, s[36:37]
	v_cndmask_b32_e64 v202, 0, v202, s[78:79]
	v_cndmask_b32_e64 v203, 0, v203, s[50:51]
	v_cvt_pk_bf16_f32 v64, v188, v189
	v_cvt_pk_bf16_f32 v65, v190, v191
	v_cvt_pk_bf16_f32 v66, v192, v193
	v_cvt_pk_bf16_f32 v67, v194, v195
	v_cvt_pk_bf16_f32 v68, v196, v197
	v_cvt_pk_bf16_f32 v69, v198, v199
	v_cvt_pk_bf16_f32 v70, v200, v201
	v_cvt_pk_bf16_f32 v71, v202, v203
	v_pk_add_f32 v[232:233], v[232:233], v[188:189]
	v_pk_add_f32 v[232:233], v[232:233], v[190:191]
	v_pk_add_f32 v[232:233], v[232:233], v[192:193]
	v_pk_add_f32 v[232:233], v[232:233], v[194:195]
	v_pk_add_f32 v[232:233], v[232:233], v[196:197]
	v_pk_add_f32 v[232:233], v[232:233], v[198:199]
	v_pk_add_f32 v[232:233], v[232:233], v[200:201]
	v_pk_add_f32 v[232:233], v[232:233], v[202:203]
	ds_read2_b32 v[188:189], v115 offset0:68 offset1:69
	ds_read2_b32 v[190:191], v115 offset0:70 offset1:71
	ds_read2_b32 v[192:193], v115 offset0:76 offset1:77
	ds_read2_b32 v[194:195], v115 offset0:78 offset1:79
	ds_read2_b32 v[196:197], v115 offset0:85 offset1:86
	ds_read2_b32 v[198:199], v115 offset0:87 offset1:88
	ds_read2_b32 v[200:201], v115 offset0:93 offset1:94
	ds_read2_b32 v[202:203], v115 offset0:95 offset1:96
	v_mfma_f32_32x32x16_bf16 v[0:15], v[64:67], v[72:75], v[0:15]
	v_mfma_f32_32x32x16_bf16 v[16:31], v[64:67], v[76:79], v[16:31]
	v_mfma_f32_32x32x16_bf16 v[0:15], v[68:71], v[220:223], v[0:15]
	v_mfma_f32_32x32x16_bf16 v[16:31], v[68:71], v[224:227], v[16:31]
	s_add_i32 s90, s76, 256
	v_add_u32_e32 v80, s90, v235
	v_add_u32_e32 v83, s90, v236
	v_add_u32_e32 v99, s90, v237
	v_add_u32_e32 v253, s90, v238
	v_add_u32_e32 v254, s90, v100
	v_add_u32_e32 v255, s90, v149
	v_med3_i32 v80, v80, 0, s99
	v_med3_i32 v83, v83, 0, s99
	v_med3_i32 v99, v99, 0, s99
	v_med3_i32 v253, v253, 0, s99
	v_med3_i32 v254, v254, 0, s99
	v_med3_i32 v255, v255, 0, s99
	v_mad_u32_u24 v80, v80, s100, v252
	v_mad_u32_u24 v83, v83, s100, v252
	v_mad_u32_u24 v99, v99, s100, v252
	v_mad_u32_u24 v253, v253, s100, v252
	v_mad_u32_u24 v254, v254, s100, v153
	v_mad_u32_u24 v255, v255, s100, v153
	global_load_dwordx4 v[116:119], v80, s[82:83]
	global_load_dwordx4 v[120:123], v83, s[82:83]
	global_load_dwordx4 v[124:127], v99, s[82:83]
	global_load_dwordx4 v[128:131], v253, s[82:83]
	global_load_dwordx4 v[132:135], v254, s[82:83] offset:768
	global_load_dwordx4 v[136:139], v255, s[82:83] offset:768
	global_load_dwordx4 v[140:143], v254, s[82:83] offset:832
	global_load_dwordx4 v[144:147], v255, s[82:83] offset:832
	ds_read_b64_tr_b16 v[72:73], v231
	ds_read_b64_tr_b16 v[74:75], v231 offset:512
	ds_read_b64_tr_b16 v[76:77], v231 offset:2048
	ds_read_b64_tr_b16 v[78:79], v231 offset:2560
	ds_read_b64_tr_b16 v[220:221], v231 offset:1024
	ds_read_b64_tr_b16 v[222:223], v231 offset:1536
	ds_read_b64_tr_b16 v[224:225], v231 offset:3072
	ds_read_b64_tr_b16 v[226:227], v231 offset:3584
	v_exp_f32_e32 v32, v32
	v_exp_f32_e32 v33, v33
	v_exp_f32_e32 v34, v34
	v_exp_f32_e32 v35, v35
	s_waitcnt vmcnt(8)
	ds_write_b128 v247, v[156:159]
	ds_write_b128 v247, v[160:163] offset:1024
	ds_write_b128 v247, v[164:167] offset:2048
	ds_write_b128 v247, v[168:171] offset:3072
	ds_read_b128 v[156:159], v248
	ds_read_b128 v[160:163], v249
	ds_read_b128 v[164:167], v250
	ds_read_b128 v[168:171], v251
	ds_write_b128 v112, v[172:175]
	ds_write_b128 v112, v[176:179] offset:1024
	ds_write_b128 v112, v[180:183] offset:2048
	ds_write_b128 v112, v[184:187] offset:3072
	v_exp_f32_e32 v36, v36
	v_exp_f32_e32 v37, v37
	v_exp_f32_e32 v38, v38
	v_exp_f32_e32 v39, v39
	s_waitcnt lgkmcnt(4)
	v_mfma_f32_32x32x16_bf16 v[188:203], v[156:159], v[48:51], v[188:203]
	v_exp_f32_e32 v40, v40
	v_exp_f32_e32 v41, v41
	v_mfma_f32_32x32x16_bf16 v[188:203], v[160:163], v[52:55], v[188:203]
	v_exp_f32_e32 v42, v42
	v_exp_f32_e32 v43, v43
	v_mfma_f32_32x32x16_bf16 v[188:203], v[164:167], v[56:59], v[188:203]
	v_exp_f32_e32 v44, v44
	v_exp_f32_e32 v45, v45
	v_mfma_f32_32x32x16_bf16 v[188:203], v[168:171], v[60:63], v[188:203]
	v_exp_f32_e32 v46, v46
	v_exp_f32_e32 v47, v47
	s_add_i32 s90, s76, 192
	v_add_u32_e32 v84, s90, v107
	v_add_u32_e32 v85, 0, v84
	v_add_u32_e32 v86, 1, v84
	v_add_u32_e32 v87, 2, v84
	v_add_u32_e32 v88, 3, v84
	v_cmp_gt_u32_e64 s[30:31], s98, v85
	v_cmp_gt_u32_e64 s[36:37], s98, v86
	v_cmp_gt_u32_e64 s[78:79], s98, v87
	v_cmp_gt_u32_e64 s[50:51], s98, v88
	v_cndmask_b32_e64 v32, 0, v32, s[30:31]
	v_add_u32_e32 v85, 8, v84
	v_cmp_gt_u32_e64 s[30:31], s98, v85
	v_cndmask_b32_e64 v33, 0, v33, s[36:37]
	v_add_u32_e32 v86, 9, v84
	v_cmp_gt_u32_e64 s[36:37], s98, v86
	v_cndmask_b32_e64 v34, 0, v34, s[78:79]
	v_add_u32_e32 v87, 10, v84
	v_cmp_gt_u32_e64 s[78:79], s98, v87
	v_cndmask_b32_e64 v35, 0, v35, s[50:51]
	v_add_u32_e32 v88, 11, v84
	v_cmp_gt_u32_e64 s[50:51], s98, v88
	v_cndmask_b32_e64 v36, 0, v36, s[30:31]
	v_add_u32_e32 v85, 16, v84
	v_cmp_gt_u32_e64 s[30:31], s98, v85
	v_cndmask_b32_e64 v37, 0, v37, s[36:37]
	v_add_u32_e32 v86, 17, v84
	v_cmp_gt_u32_e64 s[36:37], s98, v86
	v_cndmask_b32_e64 v38, 0, v38, s[78:79]
	v_add_u32_e32 v87, 18, v84
	v_cmp_gt_u32_e64 s[78:79], s98, v87
	v_cndmask_b32_e64 v39, 0, v39, s[50:51]
	v_add_u32_e32 v88, 19, v84
	v_cmp_gt_u32_e64 s[50:51], s98, v88
	v_cndmask_b32_e64 v40, 0, v40, s[30:31]
	v_add_u32_e32 v85, 24, v84
	v_cmp_gt_u32_e64 s[30:31], s98, v85
	v_cndmask_b32_e64 v41, 0, v41, s[36:37]
	v_add_u32_e32 v86, 25, v84
	v_cmp_gt_u32_e64 s[36:37], s98, v86
	v_cndmask_b32_e64 v42, 0, v42, s[78:79]
	v_add_u32_e32 v87, 26, v84
	v_cmp_gt_u32_e64 s[78:79], s98, v87
	v_cndmask_b32_e64 v43, 0, v43, s[50:51]
	v_add_u32_e32 v88, 27, v84
	v_cmp_gt_u32_e64 s[50:51], s98, v88
	v_nop
	v_cndmask_b32_e64 v44, 0, v44, s[30:31]
	v_cndmask_b32_e64 v45, 0, v45, s[36:37]
	v_cndmask_b32_e64 v46, 0, v46, s[78:79]
	v_cndmask_b32_e64 v47, 0, v47, s[50:51]
	v_cvt_pk_bf16_f32 v64, v32, v33
	v_cvt_pk_bf16_f32 v65, v34, v35
	v_cvt_pk_bf16_f32 v66, v36, v37
	v_cvt_pk_bf16_f32 v67, v38, v39
	v_cvt_pk_bf16_f32 v68, v40, v41
	v_cvt_pk_bf16_f32 v69, v42, v43
	v_cvt_pk_bf16_f32 v70, v44, v45
	v_cvt_pk_bf16_f32 v71, v46, v47
	v_pk_add_f32 v[232:233], v[232:233], v[32:33]
	v_pk_add_f32 v[232:233], v[232:233], v[34:35]
	v_pk_add_f32 v[232:233], v[232:233], v[36:37]
	v_pk_add_f32 v[232:233], v[232:233], v[38:39]
	v_pk_add_f32 v[232:233], v[232:233], v[40:41]
	v_pk_add_f32 v[232:233], v[232:233], v[42:43]
	v_pk_add_f32 v[232:233], v[232:233], v[44:45]
	v_pk_add_f32 v[232:233], v[232:233], v[46:47]
	ds_read2_b32 v[32:33], v115 offset0:102 offset1:103
	ds_read2_b32 v[34:35], v115 offset0:104 offset1:105
	ds_read2_b32 v[36:37], v115 offset0:110 offset1:111
	ds_read2_b32 v[38:39], v115 offset0:112 offset1:113
	ds_read2_b32 v[40:41], v115 offset0:119 offset1:120
	ds_read2_b32 v[42:43], v115 offset0:121 offset1:122
	ds_read2_b32 v[44:45], v115 offset0:127 offset1:128
	ds_read2_b32 v[46:47], v115 offset0:129 offset1:130
	v_mfma_f32_32x32x16_bf16 v[0:15], v[64:67], v[72:75], v[0:15]
	v_mfma_f32_32x32x16_bf16 v[16:31], v[64:67], v[76:79], v[16:31]
	v_mfma_f32_32x32x16_bf16 v[0:15], v[68:71], v[220:223], v[0:15]
	v_mfma_f32_32x32x16_bf16 v[16:31], v[68:71], v[224:227], v[16:31]
	s_add_i32 s90, s76, 288
	v_add_u32_e32 v80, s90, v235
	v_add_u32_e32 v83, s90, v236
	v_add_u32_e32 v99, s90, v237
	v_add_u32_e32 v253, s90, v238
	v_add_u32_e32 v254, s90, v100
	v_add_u32_e32 v255, s90, v149
	v_med3_i32 v80, v80, 0, s99
	v_med3_i32 v83, v83, 0, s99
	v_med3_i32 v99, v99, 0, s99
	v_med3_i32 v253, v253, 0, s99
	v_med3_i32 v254, v254, 0, s99
	v_med3_i32 v255, v255, 0, s99
	v_mad_u32_u24 v80, v80, s100, v252
	v_mad_u32_u24 v83, v83, s100, v252
	v_mad_u32_u24 v99, v99, s100, v252
	v_mad_u32_u24 v253, v253, s100, v252
	v_mad_u32_u24 v254, v254, s100, v153
	v_mad_u32_u24 v255, v255, s100, v153
	global_load_dwordx4 v[156:159], v80, s[82:83]
	global_load_dwordx4 v[160:163], v83, s[82:83]
	global_load_dwordx4 v[164:167], v99, s[82:83]
	global_load_dwordx4 v[168:171], v253, s[82:83]
	global_load_dwordx4 v[172:175], v254, s[82:83] offset:768
	global_load_dwordx4 v[176:179], v255, s[82:83] offset:768
	global_load_dwordx4 v[180:183], v254, s[82:83] offset:832
	global_load_dwordx4 v[184:187], v255, s[82:83] offset:832
	ds_read_b64_tr_b16 v[72:73], v231
	ds_read_b64_tr_b16 v[74:75], v231 offset:512
	ds_read_b64_tr_b16 v[76:77], v231 offset:2048
	ds_read_b64_tr_b16 v[78:79], v231 offset:2560
	ds_read_b64_tr_b16 v[220:221], v231 offset:1024
	ds_read_b64_tr_b16 v[222:223], v231 offset:1536
	ds_read_b64_tr_b16 v[224:225], v231 offset:3072
	ds_read_b64_tr_b16 v[226:227], v231 offset:3584
	v_exp_f32_e32 v188, v188
	v_exp_f32_e32 v189, v189
	v_exp_f32_e32 v190, v190
	v_exp_f32_e32 v191, v191
	s_waitcnt vmcnt(8)
	ds_write_b128 v247, v[116:119]
	ds_write_b128 v247, v[120:123] offset:1024
	ds_write_b128 v247, v[124:127] offset:2048
	ds_write_b128 v247, v[128:131] offset:3072
	ds_read_b128 v[116:119], v248
	ds_read_b128 v[120:123], v249
	ds_read_b128 v[124:127], v250
	ds_read_b128 v[128:131], v251
	ds_write_b128 v112, v[132:135]
	ds_write_b128 v112, v[136:139] offset:1024
	ds_write_b128 v112, v[140:143] offset:2048
	ds_write_b128 v112, v[144:147] offset:3072
	v_exp_f32_e32 v192, v192
	v_exp_f32_e32 v193, v193
	v_exp_f32_e32 v194, v194
	v_exp_f32_e32 v195, v195
	s_waitcnt lgkmcnt(4)
	v_mfma_f32_32x32x16_bf16 v[32:47], v[116:119], v[48:51], v[32:47]
	v_exp_f32_e32 v196, v196
	v_exp_f32_e32 v197, v197
	v_mfma_f32_32x32x16_bf16 v[32:47], v[120:123], v[52:55], v[32:47]
	v_exp_f32_e32 v198, v198
	v_exp_f32_e32 v199, v199
	v_mfma_f32_32x32x16_bf16 v[32:47], v[124:127], v[56:59], v[32:47]
	v_exp_f32_e32 v200, v200
	v_exp_f32_e32 v201, v201
	v_mfma_f32_32x32x16_bf16 v[32:47], v[128:131], v[60:63], v[32:47]
	v_exp_f32_e32 v202, v202
	v_exp_f32_e32 v203, v203
	s_add_i32 s90, s76, 224
	v_add_u32_e32 v84, s90, v107
	v_add_u32_e32 v85, 0, v84
	v_add_u32_e32 v86, 1, v84
	v_add_u32_e32 v87, 2, v84
	v_add_u32_e32 v88, 3, v84
	v_cmp_gt_u32_e64 s[30:31], s98, v85
	v_cmp_gt_u32_e64 s[36:37], s98, v86
	v_cmp_gt_u32_e64 s[78:79], s98, v87
	v_cmp_gt_u32_e64 s[50:51], s98, v88
	v_cndmask_b32_e64 v188, 0, v188, s[30:31]
	v_add_u32_e32 v85, 8, v84
	v_cmp_gt_u32_e64 s[30:31], s98, v85
	v_cndmask_b32_e64 v189, 0, v189, s[36:37]
	v_add_u32_e32 v86, 9, v84
	v_cmp_gt_u32_e64 s[36:37], s98, v86
	v_cndmask_b32_e64 v190, 0, v190, s[78:79]
	v_add_u32_e32 v87, 10, v84
	v_cmp_gt_u32_e64 s[78:79], s98, v87
	v_cndmask_b32_e64 v191, 0, v191, s[50:51]
	v_add_u32_e32 v88, 11, v84
	v_cmp_gt_u32_e64 s[50:51], s98, v88
	v_cndmask_b32_e64 v192, 0, v192, s[30:31]
	v_add_u32_e32 v85, 16, v84
	v_cmp_gt_u32_e64 s[30:31], s98, v85
	v_cndmask_b32_e64 v193, 0, v193, s[36:37]
	v_add_u32_e32 v86, 17, v84
	v_cmp_gt_u32_e64 s[36:37], s98, v86
	v_cndmask_b32_e64 v194, 0, v194, s[78:79]
	v_add_u32_e32 v87, 18, v84
	v_cmp_gt_u32_e64 s[78:79], s98, v87
	v_cndmask_b32_e64 v195, 0, v195, s[50:51]
	v_add_u32_e32 v88, 19, v84
	v_cmp_gt_u32_e64 s[50:51], s98, v88
	v_cndmask_b32_e64 v196, 0, v196, s[30:31]
	v_add_u32_e32 v85, 24, v84
	v_cmp_gt_u32_e64 s[30:31], s98, v85
	v_cndmask_b32_e64 v197, 0, v197, s[36:37]
	v_add_u32_e32 v86, 25, v84
	v_cmp_gt_u32_e64 s[36:37], s98, v86
	v_cndmask_b32_e64 v198, 0, v198, s[78:79]
	v_add_u32_e32 v87, 26, v84
	v_cmp_gt_u32_e64 s[78:79], s98, v87
	v_cndmask_b32_e64 v199, 0, v199, s[50:51]
	v_add_u32_e32 v88, 27, v84
	v_cmp_gt_u32_e64 s[50:51], s98, v88
	v_nop
	v_cndmask_b32_e64 v200, 0, v200, s[30:31]
	v_cndmask_b32_e64 v201, 0, v201, s[36:37]
	v_cndmask_b32_e64 v202, 0, v202, s[78:79]
	v_cndmask_b32_e64 v203, 0, v203, s[50:51]
	v_cvt_pk_bf16_f32 v64, v188, v189
	v_cvt_pk_bf16_f32 v65, v190, v191
	v_cvt_pk_bf16_f32 v66, v192, v193
	v_cvt_pk_bf16_f32 v67, v194, v195
	v_cvt_pk_bf16_f32 v68, v196, v197
	v_cvt_pk_bf16_f32 v69, v198, v199
	v_cvt_pk_bf16_f32 v70, v200, v201
	v_cvt_pk_bf16_f32 v71, v202, v203
	v_pk_add_f32 v[232:233], v[232:233], v[188:189]
	v_pk_add_f32 v[232:233], v[232:233], v[190:191]
	v_pk_add_f32 v[232:233], v[232:233], v[192:193]
	v_pk_add_f32 v[232:233], v[232:233], v[194:195]
	v_pk_add_f32 v[232:233], v[232:233], v[196:197]
	v_pk_add_f32 v[232:233], v[232:233], v[198:199]
	v_pk_add_f32 v[232:233], v[232:233], v[200:201]
	v_pk_add_f32 v[232:233], v[232:233], v[202:203]
	ds_read2_b32 v[188:189], v115 offset0:136 offset1:137
	ds_read2_b32 v[190:191], v115 offset0:138 offset1:139
	ds_read2_b32 v[192:193], v115 offset0:144 offset1:145
	ds_read2_b32 v[194:195], v115 offset0:146 offset1:147
	ds_read2_b32 v[196:197], v115 offset0:153 offset1:154
	ds_read2_b32 v[198:199], v115 offset0:155 offset1:156
	ds_read2_b32 v[200:201], v115 offset0:161 offset1:162
	ds_read2_b32 v[202:203], v115 offset0:163 offset1:164
	v_mfma_f32_32x32x16_bf16 v[0:15], v[64:67], v[72:75], v[0:15]
	v_mfma_f32_32x32x16_bf16 v[16:31], v[64:67], v[76:79], v[16:31]
	v_mfma_f32_32x32x16_bf16 v[0:15], v[68:71], v[220:223], v[0:15]
	v_mfma_f32_32x32x16_bf16 v[16:31], v[68:71], v[224:227], v[16:31]
	s_add_i32 s90, s76, 320
	v_add_u32_e32 v80, s90, v235
	v_add_u32_e32 v83, s90, v236
	v_add_u32_e32 v99, s90, v237
	v_add_u32_e32 v253, s90, v238
	v_add_u32_e32 v254, s90, v100
	v_add_u32_e32 v255, s90, v149
	v_med3_i32 v80, v80, 0, s99
	v_med3_i32 v83, v83, 0, s99
	v_med3_i32 v99, v99, 0, s99
	v_med3_i32 v253, v253, 0, s99
	v_med3_i32 v254, v254, 0, s99
	v_med3_i32 v255, v255, 0, s99
	v_mad_u32_u24 v80, v80, s100, v252
	v_mad_u32_u24 v83, v83, s100, v252
	v_mad_u32_u24 v99, v99, s100, v252
	v_mad_u32_u24 v253, v253, s100, v252
	v_mad_u32_u24 v254, v254, s100, v153
	v_mad_u32_u24 v255, v255, s100, v153
	global_load_dwordx4 v[116:119], v80, s[82:83]
	global_load_dwordx4 v[120:123], v83, s[82:83]
	global_load_dwordx4 v[124:127], v99, s[82:83]
	global_load_dwordx4 v[128:131], v253, s[82:83]
	global_load_dwordx4 v[132:135], v254, s[82:83] offset:768
	global_load_dwordx4 v[136:139], v255, s[82:83] offset:768
	global_load_dwordx4 v[140:143], v254, s[82:83] offset:832
	global_load_dwordx4 v[144:147], v255, s[82:83] offset:832
	ds_read_b64_tr_b16 v[72:73], v231
	ds_read_b64_tr_b16 v[74:75], v231 offset:512
	ds_read_b64_tr_b16 v[76:77], v231 offset:2048
	ds_read_b64_tr_b16 v[78:79], v231 offset:2560
	ds_read_b64_tr_b16 v[220:221], v231 offset:1024
	ds_read_b64_tr_b16 v[222:223], v231 offset:1536
	ds_read_b64_tr_b16 v[224:225], v231 offset:3072
	ds_read_b64_tr_b16 v[226:227], v231 offset:3584
	v_exp_f32_e32 v32, v32
	v_exp_f32_e32 v33, v33
	v_exp_f32_e32 v34, v34
	v_exp_f32_e32 v35, v35
	s_waitcnt vmcnt(8)
	ds_write_b128 v247, v[156:159]
	ds_write_b128 v247, v[160:163] offset:1024
	ds_write_b128 v247, v[164:167] offset:2048
	ds_write_b128 v247, v[168:171] offset:3072
	ds_read_b128 v[156:159], v248
	ds_read_b128 v[160:163], v249
	ds_read_b128 v[164:167], v250
	ds_read_b128 v[168:171], v251
	ds_write_b128 v112, v[172:175]
	ds_write_b128 v112, v[176:179] offset:1024
	ds_write_b128 v112, v[180:183] offset:2048
	ds_write_b128 v112, v[184:187] offset:3072
	v_exp_f32_e32 v36, v36
	v_exp_f32_e32 v37, v37
	v_exp_f32_e32 v38, v38
	v_exp_f32_e32 v39, v39
	s_waitcnt lgkmcnt(4)
	v_mfma_f32_32x32x16_bf16 v[188:203], v[156:159], v[48:51], v[188:203]
	v_exp_f32_e32 v40, v40
	v_exp_f32_e32 v41, v41
	v_mfma_f32_32x32x16_bf16 v[188:203], v[160:163], v[52:55], v[188:203]
	v_exp_f32_e32 v42, v42
	v_exp_f32_e32 v43, v43
	v_mfma_f32_32x32x16_bf16 v[188:203], v[164:167], v[56:59], v[188:203]
	v_exp_f32_e32 v44, v44
	v_exp_f32_e32 v45, v45
	v_mfma_f32_32x32x16_bf16 v[188:203], v[168:171], v[60:63], v[188:203]
	v_exp_f32_e32 v46, v46
	v_exp_f32_e32 v47, v47
	s_add_i32 s90, s76, 256
	v_add_u32_e32 v84, s90, v107
	v_add_u32_e32 v85, 0, v84
	v_add_u32_e32 v86, 1, v84
	v_add_u32_e32 v87, 2, v84
	v_add_u32_e32 v88, 3, v84
	v_cmp_gt_u32_e64 s[30:31], s98, v85
	v_cmp_gt_u32_e64 s[36:37], s98, v86
	v_cmp_gt_u32_e64 s[78:79], s98, v87
	v_cmp_gt_u32_e64 s[50:51], s98, v88
	v_cndmask_b32_e64 v32, 0, v32, s[30:31]
	v_add_u32_e32 v85, 8, v84
	v_cmp_gt_u32_e64 s[30:31], s98, v85
	v_cndmask_b32_e64 v33, 0, v33, s[36:37]
	v_add_u32_e32 v86, 9, v84
	v_cmp_gt_u32_e64 s[36:37], s98, v86
	v_cndmask_b32_e64 v34, 0, v34, s[78:79]
	v_add_u32_e32 v87, 10, v84
	v_cmp_gt_u32_e64 s[78:79], s98, v87
	v_cndmask_b32_e64 v35, 0, v35, s[50:51]
	v_add_u32_e32 v88, 11, v84
	v_cmp_gt_u32_e64 s[50:51], s98, v88
	v_cndmask_b32_e64 v36, 0, v36, s[30:31]
	v_add_u32_e32 v85, 16, v84
	v_cmp_gt_u32_e64 s[30:31], s98, v85
	v_cndmask_b32_e64 v37, 0, v37, s[36:37]
	v_add_u32_e32 v86, 17, v84
	v_cmp_gt_u32_e64 s[36:37], s98, v86
	v_cndmask_b32_e64 v38, 0, v38, s[78:79]
	v_add_u32_e32 v87, 18, v84
	v_cmp_gt_u32_e64 s[78:79], s98, v87
	v_cndmask_b32_e64 v39, 0, v39, s[50:51]
	v_add_u32_e32 v88, 19, v84
	v_cmp_gt_u32_e64 s[50:51], s98, v88
	v_cndmask_b32_e64 v40, 0, v40, s[30:31]
	v_add_u32_e32 v85, 24, v84
	v_cmp_gt_u32_e64 s[30:31], s98, v85
	v_cndmask_b32_e64 v41, 0, v41, s[36:37]
	v_add_u32_e32 v86, 25, v84
	v_cmp_gt_u32_e64 s[36:37], s98, v86
	v_cndmask_b32_e64 v42, 0, v42, s[78:79]
	v_add_u32_e32 v87, 26, v84
	v_cmp_gt_u32_e64 s[78:79], s98, v87
	v_cndmask_b32_e64 v43, 0, v43, s[50:51]
	v_add_u32_e32 v88, 27, v84
	v_cmp_gt_u32_e64 s[50:51], s98, v88
	v_nop
	v_cndmask_b32_e64 v44, 0, v44, s[30:31]
	v_cndmask_b32_e64 v45, 0, v45, s[36:37]
	v_cndmask_b32_e64 v46, 0, v46, s[78:79]
	v_cndmask_b32_e64 v47, 0, v47, s[50:51]
	v_cvt_pk_bf16_f32 v64, v32, v33
	v_cvt_pk_bf16_f32 v65, v34, v35
	v_cvt_pk_bf16_f32 v66, v36, v37
	v_cvt_pk_bf16_f32 v67, v38, v39
	v_cvt_pk_bf16_f32 v68, v40, v41
	v_cvt_pk_bf16_f32 v69, v42, v43
	v_cvt_pk_bf16_f32 v70, v44, v45
	v_cvt_pk_bf16_f32 v71, v46, v47
	v_pk_add_f32 v[232:233], v[232:233], v[32:33]
	v_pk_add_f32 v[232:233], v[232:233], v[34:35]
	v_pk_add_f32 v[232:233], v[232:233], v[36:37]
	v_pk_add_f32 v[232:233], v[232:233], v[38:39]
	v_pk_add_f32 v[232:233], v[232:233], v[40:41]
	v_pk_add_f32 v[232:233], v[232:233], v[42:43]
	v_pk_add_f32 v[232:233], v[232:233], v[44:45]
	v_pk_add_f32 v[232:233], v[232:233], v[46:47]
	ds_read2_b32 v[32:33], v115 offset0:170 offset1:171
	ds_read2_b32 v[34:35], v115 offset0:172 offset1:173
	ds_read2_b32 v[36:37], v115 offset0:178 offset1:179
	ds_read2_b32 v[38:39], v115 offset0:180 offset1:181
	ds_read2_b32 v[40:41], v115 offset0:187 offset1:188
	ds_read2_b32 v[42:43], v115 offset0:189 offset1:190
	ds_read2_b32 v[44:45], v115 offset0:195 offset1:196
	ds_read2_b32 v[46:47], v115 offset0:197 offset1:198
	v_mfma_f32_32x32x16_bf16 v[0:15], v[64:67], v[72:75], v[0:15]
	v_mfma_f32_32x32x16_bf16 v[16:31], v[64:67], v[76:79], v[16:31]
	v_mfma_f32_32x32x16_bf16 v[0:15], v[68:71], v[220:223], v[0:15]
	v_mfma_f32_32x32x16_bf16 v[16:31], v[68:71], v[224:227], v[16:31]
	s_add_i32 s90, s76, 352
	v_add_u32_e32 v80, s90, v235
	v_add_u32_e32 v83, s90, v236
	v_add_u32_e32 v99, s90, v237
	v_add_u32_e32 v253, s90, v238
	v_add_u32_e32 v254, s90, v100
	v_add_u32_e32 v255, s90, v149
	v_med3_i32 v80, v80, 0, s99
	v_med3_i32 v83, v83, 0, s99
	v_med3_i32 v99, v99, 0, s99
	v_med3_i32 v253, v253, 0, s99
	v_med3_i32 v254, v254, 0, s99
	v_med3_i32 v255, v255, 0, s99
	v_mad_u32_u24 v80, v80, s100, v252
	v_mad_u32_u24 v83, v83, s100, v252
	v_mad_u32_u24 v99, v99, s100, v252
	v_mad_u32_u24 v253, v253, s100, v252
	v_mad_u32_u24 v254, v254, s100, v153
	v_mad_u32_u24 v255, v255, s100, v153
	global_load_dwordx4 v[156:159], v80, s[82:83]
	global_load_dwordx4 v[160:163], v83, s[82:83]
	global_load_dwordx4 v[164:167], v99, s[82:83]
	global_load_dwordx4 v[168:171], v253, s[82:83]
	global_load_dwordx4 v[172:175], v254, s[82:83] offset:768
	global_load_dwordx4 v[176:179], v255, s[82:83] offset:768
	global_load_dwordx4 v[180:183], v254, s[82:83] offset:832
	global_load_dwordx4 v[184:187], v255, s[82:83] offset:832
	ds_read_b64_tr_b16 v[72:73], v231
	ds_read_b64_tr_b16 v[74:75], v231 offset:512
	ds_read_b64_tr_b16 v[76:77], v231 offset:2048
	ds_read_b64_tr_b16 v[78:79], v231 offset:2560
	ds_read_b64_tr_b16 v[220:221], v231 offset:1024
	ds_read_b64_tr_b16 v[222:223], v231 offset:1536
	ds_read_b64_tr_b16 v[224:225], v231 offset:3072
	ds_read_b64_tr_b16 v[226:227], v231 offset:3584
	v_exp_f32_e32 v188, v188
	v_exp_f32_e32 v189, v189
	v_exp_f32_e32 v190, v190
	v_exp_f32_e32 v191, v191
	s_waitcnt vmcnt(8)
	ds_write_b128 v247, v[116:119]
	ds_write_b128 v247, v[120:123] offset:1024
	ds_write_b128 v247, v[124:127] offset:2048
	ds_write_b128 v247, v[128:131] offset:3072
	ds_read_b128 v[116:119], v248
	ds_read_b128 v[120:123], v249
	ds_read_b128 v[124:127], v250
	ds_read_b128 v[128:131], v251
	ds_write_b128 v112, v[132:135]
	ds_write_b128 v112, v[136:139] offset:1024
	ds_write_b128 v112, v[140:143] offset:2048
	ds_write_b128 v112, v[144:147] offset:3072
	v_exp_f32_e32 v192, v192
	v_exp_f32_e32 v193, v193
	v_exp_f32_e32 v194, v194
	v_exp_f32_e32 v195, v195
	s_waitcnt lgkmcnt(4)
	v_mfma_f32_32x32x16_bf16 v[32:47], v[116:119], v[48:51], v[32:47]
	v_exp_f32_e32 v196, v196
	v_exp_f32_e32 v197, v197
	v_mfma_f32_32x32x16_bf16 v[32:47], v[120:123], v[52:55], v[32:47]
	v_exp_f32_e32 v198, v198
	v_exp_f32_e32 v199, v199
	v_mfma_f32_32x32x16_bf16 v[32:47], v[124:127], v[56:59], v[32:47]
	v_exp_f32_e32 v200, v200
	v_exp_f32_e32 v201, v201
	v_mfma_f32_32x32x16_bf16 v[32:47], v[128:131], v[60:63], v[32:47]
	v_exp_f32_e32 v202, v202
	v_exp_f32_e32 v203, v203
	s_add_i32 s90, s76, 288
	v_add_u32_e32 v84, s90, v107
	v_add_u32_e32 v85, 0, v84
	v_add_u32_e32 v86, 1, v84
	v_add_u32_e32 v87, 2, v84
	v_add_u32_e32 v88, 3, v84
	v_cmp_gt_u32_e64 s[30:31], s98, v85
	v_cmp_gt_u32_e64 s[36:37], s98, v86
	v_cmp_gt_u32_e64 s[78:79], s98, v87
	v_cmp_gt_u32_e64 s[50:51], s98, v88
	v_cndmask_b32_e64 v188, 0, v188, s[30:31]
	v_add_u32_e32 v85, 8, v84
	v_cmp_gt_u32_e64 s[30:31], s98, v85
	v_cndmask_b32_e64 v189, 0, v189, s[36:37]
	v_add_u32_e32 v86, 9, v84
	v_cmp_gt_u32_e64 s[36:37], s98, v86
	v_cndmask_b32_e64 v190, 0, v190, s[78:79]
	v_add_u32_e32 v87, 10, v84
	v_cmp_gt_u32_e64 s[78:79], s98, v87
	v_cndmask_b32_e64 v191, 0, v191, s[50:51]
	v_add_u32_e32 v88, 11, v84
	v_cmp_gt_u32_e64 s[50:51], s98, v88
	v_cndmask_b32_e64 v192, 0, v192, s[30:31]
	v_add_u32_e32 v85, 16, v84
	v_cmp_gt_u32_e64 s[30:31], s98, v85
	v_cndmask_b32_e64 v193, 0, v193, s[36:37]
	v_add_u32_e32 v86, 17, v84
	v_cmp_gt_u32_e64 s[36:37], s98, v86
	v_cndmask_b32_e64 v194, 0, v194, s[78:79]
	v_add_u32_e32 v87, 18, v84
	v_cmp_gt_u32_e64 s[78:79], s98, v87
	v_cndmask_b32_e64 v195, 0, v195, s[50:51]
	v_add_u32_e32 v88, 19, v84
	v_cmp_gt_u32_e64 s[50:51], s98, v88
	v_cndmask_b32_e64 v196, 0, v196, s[30:31]
	v_add_u32_e32 v85, 24, v84
	v_cmp_gt_u32_e64 s[30:31], s98, v85
	v_cndmask_b32_e64 v197, 0, v197, s[36:37]
	v_add_u32_e32 v86, 25, v84
	v_cmp_gt_u32_e64 s[36:37], s98, v86
	v_cndmask_b32_e64 v198, 0, v198, s[78:79]
	v_add_u32_e32 v87, 26, v84
	v_cmp_gt_u32_e64 s[78:79], s98, v87
	v_cndmask_b32_e64 v199, 0, v199, s[50:51]
	v_add_u32_e32 v88, 27, v84
	v_cmp_gt_u32_e64 s[50:51], s98, v88
	v_nop
	v_cndmask_b32_e64 v200, 0, v200, s[30:31]
	v_cndmask_b32_e64 v201, 0, v201, s[36:37]
	v_cndmask_b32_e64 v202, 0, v202, s[78:79]
	v_cndmask_b32_e64 v203, 0, v203, s[50:51]
	v_cvt_pk_bf16_f32 v64, v188, v189
	v_cvt_pk_bf16_f32 v65, v190, v191
	v_cvt_pk_bf16_f32 v66, v192, v193
	v_cvt_pk_bf16_f32 v67, v194, v195
	v_cvt_pk_bf16_f32 v68, v196, v197
	v_cvt_pk_bf16_f32 v69, v198, v199
	v_cvt_pk_bf16_f32 v70, v200, v201
	v_cvt_pk_bf16_f32 v71, v202, v203
	v_pk_add_f32 v[232:233], v[232:233], v[188:189]
	v_pk_add_f32 v[232:233], v[232:233], v[190:191]
	v_pk_add_f32 v[232:233], v[232:233], v[192:193]
	v_pk_add_f32 v[232:233], v[232:233], v[194:195]
	v_pk_add_f32 v[232:233], v[232:233], v[196:197]
	v_pk_add_f32 v[232:233], v[232:233], v[198:199]
	v_pk_add_f32 v[232:233], v[232:233], v[200:201]
	v_pk_add_f32 v[232:233], v[232:233], v[202:203]
	ds_read2_b32 v[188:189], v115 offset0:204 offset1:205
	ds_read2_b32 v[190:191], v115 offset0:206 offset1:207
	ds_read2_b32 v[192:193], v115 offset0:212 offset1:213
	ds_read2_b32 v[194:195], v115 offset0:214 offset1:215
	ds_read2_b32 v[196:197], v115 offset0:221 offset1:222
	ds_read2_b32 v[198:199], v115 offset0:223 offset1:224
	ds_read2_b32 v[200:201], v115 offset0:229 offset1:230
	ds_read2_b32 v[202:203], v115 offset0:231 offset1:232
	v_mfma_f32_32x32x16_bf16 v[0:15], v[64:67], v[72:75], v[0:15]
	v_mfma_f32_32x32x16_bf16 v[16:31], v[64:67], v[76:79], v[16:31]
	v_mfma_f32_32x32x16_bf16 v[0:15], v[68:71], v[220:223], v[0:15]
	v_mfma_f32_32x32x16_bf16 v[16:31], v[68:71], v[224:227], v[16:31]
	s_add_i32 s90, s76, 384
	v_add_u32_e32 v80, s90, v235
	v_add_u32_e32 v83, s90, v236
	v_add_u32_e32 v99, s90, v237
	v_add_u32_e32 v253, s90, v238
	v_add_u32_e32 v254, s90, v100
	v_add_u32_e32 v255, s90, v149
	v_med3_i32 v80, v80, 0, s99
	v_med3_i32 v83, v83, 0, s99
	v_med3_i32 v99, v99, 0, s99
	v_med3_i32 v253, v253, 0, s99
	v_med3_i32 v254, v254, 0, s99
	v_med3_i32 v255, v255, 0, s99
	v_mad_u32_u24 v80, v80, s100, v252
	v_mad_u32_u24 v83, v83, s100, v252
	v_mad_u32_u24 v99, v99, s100, v252
	v_mad_u32_u24 v253, v253, s100, v252
	v_mad_u32_u24 v254, v254, s100, v153
	v_mad_u32_u24 v255, v255, s100, v153
	global_load_dwordx4 v[116:119], v80, s[82:83]
	global_load_dwordx4 v[120:123], v83, s[82:83]
	global_load_dwordx4 v[124:127], v99, s[82:83]
	global_load_dwordx4 v[128:131], v253, s[82:83]
	global_load_dwordx4 v[132:135], v254, s[82:83] offset:768
	global_load_dwordx4 v[136:139], v255, s[82:83] offset:768
	global_load_dwordx4 v[140:143], v254, s[82:83] offset:832
	global_load_dwordx4 v[144:147], v255, s[82:83] offset:832
	ds_read_b64_tr_b16 v[72:73], v231
	ds_read_b64_tr_b16 v[74:75], v231 offset:512
	ds_read_b64_tr_b16 v[76:77], v231 offset:2048
	ds_read_b64_tr_b16 v[78:79], v231 offset:2560
	ds_read_b64_tr_b16 v[220:221], v231 offset:1024
	ds_read_b64_tr_b16 v[222:223], v231 offset:1536
	ds_read_b64_tr_b16 v[224:225], v231 offset:3072
	ds_read_b64_tr_b16 v[226:227], v231 offset:3584
	v_exp_f32_e32 v32, v32
	v_exp_f32_e32 v33, v33
	v_exp_f32_e32 v34, v34
	v_exp_f32_e32 v35, v35
	s_waitcnt vmcnt(8)
	ds_write_b128 v247, v[156:159]
	ds_write_b128 v247, v[160:163] offset:1024
	ds_write_b128 v247, v[164:167] offset:2048
	ds_write_b128 v247, v[168:171] offset:3072
	ds_read_b128 v[156:159], v248
	ds_read_b128 v[160:163], v249
	ds_read_b128 v[164:167], v250
	ds_read_b128 v[168:171], v251
	ds_write_b128 v112, v[172:175]
	ds_write_b128 v112, v[176:179] offset:1024
	ds_write_b128 v112, v[180:183] offset:2048
	ds_write_b128 v112, v[184:187] offset:3072
	v_exp_f32_e32 v36, v36
	v_exp_f32_e32 v37, v37
	v_exp_f32_e32 v38, v38
	v_exp_f32_e32 v39, v39
	s_waitcnt lgkmcnt(4)
	v_mfma_f32_32x32x16_bf16 v[188:203], v[156:159], v[48:51], v[188:203]
	v_exp_f32_e32 v40, v40
	v_exp_f32_e32 v41, v41
	v_mfma_f32_32x32x16_bf16 v[188:203], v[160:163], v[52:55], v[188:203]
	v_exp_f32_e32 v42, v42
	v_exp_f32_e32 v43, v43
	v_mfma_f32_32x32x16_bf16 v[188:203], v[164:167], v[56:59], v[188:203]
	v_exp_f32_e32 v44, v44
	v_exp_f32_e32 v45, v45
	v_mfma_f32_32x32x16_bf16 v[188:203], v[168:171], v[60:63], v[188:203]
	v_exp_f32_e32 v46, v46
	v_exp_f32_e32 v47, v47
	s_add_i32 s90, s76, 320
	v_add_u32_e32 v84, s90, v107
	v_add_u32_e32 v85, 0, v84
	v_add_u32_e32 v86, 1, v84
	v_add_u32_e32 v87, 2, v84
	v_add_u32_e32 v88, 3, v84
	v_cmp_gt_u32_e64 s[30:31], s98, v85
	v_cmp_gt_u32_e64 s[36:37], s98, v86
	v_cmp_gt_u32_e64 s[78:79], s98, v87
	v_cmp_gt_u32_e64 s[50:51], s98, v88
	v_cndmask_b32_e64 v32, 0, v32, s[30:31]
	v_add_u32_e32 v85, 8, v84
	v_cmp_gt_u32_e64 s[30:31], s98, v85
	v_cndmask_b32_e64 v33, 0, v33, s[36:37]
	v_add_u32_e32 v86, 9, v84
	v_cmp_gt_u32_e64 s[36:37], s98, v86
	v_cndmask_b32_e64 v34, 0, v34, s[78:79]
	v_add_u32_e32 v87, 10, v84
	v_cmp_gt_u32_e64 s[78:79], s98, v87
	v_cndmask_b32_e64 v35, 0, v35, s[50:51]
	v_add_u32_e32 v88, 11, v84
	v_cmp_gt_u32_e64 s[50:51], s98, v88
	v_cndmask_b32_e64 v36, 0, v36, s[30:31]
	v_add_u32_e32 v85, 16, v84
	v_cmp_gt_u32_e64 s[30:31], s98, v85
	v_cndmask_b32_e64 v37, 0, v37, s[36:37]
	v_add_u32_e32 v86, 17, v84
	v_cmp_gt_u32_e64 s[36:37], s98, v86
	v_cndmask_b32_e64 v38, 0, v38, s[78:79]
	v_add_u32_e32 v87, 18, v84
	v_cmp_gt_u32_e64 s[78:79], s98, v87
	v_cndmask_b32_e64 v39, 0, v39, s[50:51]
	v_add_u32_e32 v88, 19, v84
	v_cmp_gt_u32_e64 s[50:51], s98, v88
	v_cndmask_b32_e64 v40, 0, v40, s[30:31]
	v_add_u32_e32 v85, 24, v84
	v_cmp_gt_u32_e64 s[30:31], s98, v85
	v_cndmask_b32_e64 v41, 0, v41, s[36:37]
	v_add_u32_e32 v86, 25, v84
	v_cmp_gt_u32_e64 s[36:37], s98, v86
	v_cndmask_b32_e64 v42, 0, v42, s[78:79]
	v_add_u32_e32 v87, 26, v84
	v_cmp_gt_u32_e64 s[78:79], s98, v87
	v_cndmask_b32_e64 v43, 0, v43, s[50:51]
	v_add_u32_e32 v88, 27, v84
	v_cmp_gt_u32_e64 s[50:51], s98, v88
	v_nop
	v_cndmask_b32_e64 v44, 0, v44, s[30:31]
	v_cndmask_b32_e64 v45, 0, v45, s[36:37]
	v_cndmask_b32_e64 v46, 0, v46, s[78:79]
	v_cndmask_b32_e64 v47, 0, v47, s[50:51]
	v_cvt_pk_bf16_f32 v64, v32, v33
	v_cvt_pk_bf16_f32 v65, v34, v35
	v_cvt_pk_bf16_f32 v66, v36, v37
	v_cvt_pk_bf16_f32 v67, v38, v39
	v_cvt_pk_bf16_f32 v68, v40, v41
	v_cvt_pk_bf16_f32 v69, v42, v43
	v_cvt_pk_bf16_f32 v70, v44, v45
	v_cvt_pk_bf16_f32 v71, v46, v47
	v_pk_add_f32 v[232:233], v[232:233], v[32:33]
	v_pk_add_f32 v[232:233], v[232:233], v[34:35]
	v_pk_add_f32 v[232:233], v[232:233], v[36:37]
	v_pk_add_f32 v[232:233], v[232:233], v[38:39]
	v_pk_add_f32 v[232:233], v[232:233], v[40:41]
	v_pk_add_f32 v[232:233], v[232:233], v[42:43]
	v_pk_add_f32 v[232:233], v[232:233], v[44:45]
	v_pk_add_f32 v[232:233], v[232:233], v[46:47]
	v_add_u32_e32 v115, 952, v115
	ds_read2_b32 v[32:33], v115 offset0:0 offset1:1
	ds_read2_b32 v[34:35], v115 offset0:2 offset1:3
	ds_read2_b32 v[36:37], v115 offset0:8 offset1:9
	ds_read2_b32 v[38:39], v115 offset0:10 offset1:11
	ds_read2_b32 v[40:41], v115 offset0:17 offset1:18
	ds_read2_b32 v[42:43], v115 offset0:19 offset1:20
	ds_read2_b32 v[44:45], v115 offset0:25 offset1:26
	ds_read2_b32 v[46:47], v115 offset0:27 offset1:28
	v_mfma_f32_32x32x16_bf16 v[0:15], v[64:67], v[72:75], v[0:15]
	v_mfma_f32_32x32x16_bf16 v[16:31], v[64:67], v[76:79], v[16:31]
	v_mfma_f32_32x32x16_bf16 v[0:15], v[68:71], v[220:223], v[0:15]
	v_mfma_f32_32x32x16_bf16 v[16:31], v[68:71], v[224:227], v[16:31]
	s_add_i32 s90, s76, 416
	v_add_u32_e32 v80, s90, v235
	v_add_u32_e32 v83, s90, v236
	v_add_u32_e32 v99, s90, v237
	v_add_u32_e32 v253, s90, v238
	v_add_u32_e32 v254, s90, v100
	v_add_u32_e32 v255, s90, v149
	v_med3_i32 v80, v80, 0, s99
	v_med3_i32 v83, v83, 0, s99
	v_med3_i32 v99, v99, 0, s99
	v_med3_i32 v253, v253, 0, s99
	v_med3_i32 v254, v254, 0, s99
	v_med3_i32 v255, v255, 0, s99
	v_mad_u32_u24 v80, v80, s100, v252
	v_mad_u32_u24 v83, v83, s100, v252
	v_mad_u32_u24 v99, v99, s100, v252
	v_mad_u32_u24 v253, v253, s100, v252
	v_mad_u32_u24 v254, v254, s100, v153
	v_mad_u32_u24 v255, v255, s100, v153
	global_load_dwordx4 v[156:159], v80, s[82:83]
	global_load_dwordx4 v[160:163], v83, s[82:83]
	global_load_dwordx4 v[164:167], v99, s[82:83]
	global_load_dwordx4 v[168:171], v253, s[82:83]
	global_load_dwordx4 v[172:175], v254, s[82:83] offset:768
	global_load_dwordx4 v[176:179], v255, s[82:83] offset:768
	global_load_dwordx4 v[180:183], v254, s[82:83] offset:832
	global_load_dwordx4 v[184:187], v255, s[82:83] offset:832
	ds_read_b64_tr_b16 v[72:73], v231
	ds_read_b64_tr_b16 v[74:75], v231 offset:512
	ds_read_b64_tr_b16 v[76:77], v231 offset:2048
	ds_read_b64_tr_b16 v[78:79], v231 offset:2560
	ds_read_b64_tr_b16 v[220:221], v231 offset:1024
	ds_read_b64_tr_b16 v[222:223], v231 offset:1536
	ds_read_b64_tr_b16 v[224:225], v231 offset:3072
	ds_read_b64_tr_b16 v[226:227], v231 offset:3584
	v_exp_f32_e32 v188, v188
	v_exp_f32_e32 v189, v189
	v_exp_f32_e32 v190, v190
	v_exp_f32_e32 v191, v191
	s_waitcnt vmcnt(8)
	ds_write_b128 v247, v[116:119]
	ds_write_b128 v247, v[120:123] offset:1024
	ds_write_b128 v247, v[124:127] offset:2048
	ds_write_b128 v247, v[128:131] offset:3072
	ds_read_b128 v[116:119], v248
	ds_read_b128 v[120:123], v249
	ds_read_b128 v[124:127], v250
	ds_read_b128 v[128:131], v251
	ds_write_b128 v112, v[132:135]
	ds_write_b128 v112, v[136:139] offset:1024
	ds_write_b128 v112, v[140:143] offset:2048
	ds_write_b128 v112, v[144:147] offset:3072
	v_exp_f32_e32 v192, v192
	v_exp_f32_e32 v193, v193
	v_exp_f32_e32 v194, v194
	v_exp_f32_e32 v195, v195
	s_waitcnt lgkmcnt(4)
	v_mfma_f32_32x32x16_bf16 v[32:47], v[116:119], v[48:51], v[32:47]
	v_exp_f32_e32 v196, v196
	v_exp_f32_e32 v197, v197
	v_mfma_f32_32x32x16_bf16 v[32:47], v[120:123], v[52:55], v[32:47]
	v_exp_f32_e32 v198, v198
	v_exp_f32_e32 v199, v199
	v_mfma_f32_32x32x16_bf16 v[32:47], v[124:127], v[56:59], v[32:47]
	v_exp_f32_e32 v200, v200
	v_exp_f32_e32 v201, v201
	v_mfma_f32_32x32x16_bf16 v[32:47], v[128:131], v[60:63], v[32:47]
	v_exp_f32_e32 v202, v202
	v_exp_f32_e32 v203, v203
	s_add_i32 s90, s76, 352
	v_add_u32_e32 v84, s90, v107
	v_add_u32_e32 v85, 0, v84
	v_add_u32_e32 v86, 1, v84
	v_add_u32_e32 v87, 2, v84
	v_add_u32_e32 v88, 3, v84
	v_cmp_gt_u32_e64 s[30:31], s98, v85
	v_cmp_gt_u32_e64 s[36:37], s98, v86
	v_cmp_gt_u32_e64 s[78:79], s98, v87
	v_cmp_gt_u32_e64 s[50:51], s98, v88
	v_cndmask_b32_e64 v188, 0, v188, s[30:31]
	v_add_u32_e32 v85, 8, v84
	v_cmp_gt_u32_e64 s[30:31], s98, v85
	v_cndmask_b32_e64 v189, 0, v189, s[36:37]
	v_add_u32_e32 v86, 9, v84
	v_cmp_gt_u32_e64 s[36:37], s98, v86
	v_cndmask_b32_e64 v190, 0, v190, s[78:79]
	v_add_u32_e32 v87, 10, v84
	v_cmp_gt_u32_e64 s[78:79], s98, v87
	v_cndmask_b32_e64 v191, 0, v191, s[50:51]
	v_add_u32_e32 v88, 11, v84
	v_cmp_gt_u32_e64 s[50:51], s98, v88
	v_cndmask_b32_e64 v192, 0, v192, s[30:31]
	v_add_u32_e32 v85, 16, v84
	v_cmp_gt_u32_e64 s[30:31], s98, v85
	v_cndmask_b32_e64 v193, 0, v193, s[36:37]
	v_add_u32_e32 v86, 17, v84
	v_cmp_gt_u32_e64 s[36:37], s98, v86
	v_cndmask_b32_e64 v194, 0, v194, s[78:79]
	v_add_u32_e32 v87, 18, v84
	v_cmp_gt_u32_e64 s[78:79], s98, v87
	v_cndmask_b32_e64 v195, 0, v195, s[50:51]
	v_add_u32_e32 v88, 19, v84
	v_cmp_gt_u32_e64 s[50:51], s98, v88
	v_cndmask_b32_e64 v196, 0, v196, s[30:31]
	v_add_u32_e32 v85, 24, v84
	v_cmp_gt_u32_e64 s[30:31], s98, v85
	v_cndmask_b32_e64 v197, 0, v197, s[36:37]
	v_add_u32_e32 v86, 25, v84
	v_cmp_gt_u32_e64 s[36:37], s98, v86
	v_cndmask_b32_e64 v198, 0, v198, s[78:79]
	v_add_u32_e32 v87, 26, v84
	v_cmp_gt_u32_e64 s[78:79], s98, v87
	v_cndmask_b32_e64 v199, 0, v199, s[50:51]
	v_add_u32_e32 v88, 27, v84
	v_cmp_gt_u32_e64 s[50:51], s98, v88
	v_nop
	v_cndmask_b32_e64 v200, 0, v200, s[30:31]
	v_cndmask_b32_e64 v201, 0, v201, s[36:37]
	v_cndmask_b32_e64 v202, 0, v202, s[78:79]
	v_cndmask_b32_e64 v203, 0, v203, s[50:51]
	v_cvt_pk_bf16_f32 v64, v188, v189
	v_cvt_pk_bf16_f32 v65, v190, v191
	v_cvt_pk_bf16_f32 v66, v192, v193
	v_cvt_pk_bf16_f32 v67, v194, v195
	v_cvt_pk_bf16_f32 v68, v196, v197
	v_cvt_pk_bf16_f32 v69, v198, v199
	v_cvt_pk_bf16_f32 v70, v200, v201
	v_cvt_pk_bf16_f32 v71, v202, v203
	v_pk_add_f32 v[232:233], v[232:233], v[188:189]
	v_pk_add_f32 v[232:233], v[232:233], v[190:191]
	v_pk_add_f32 v[232:233], v[232:233], v[192:193]
	v_pk_add_f32 v[232:233], v[232:233], v[194:195]
	v_pk_add_f32 v[232:233], v[232:233], v[196:197]
	v_pk_add_f32 v[232:233], v[232:233], v[198:199]
	v_pk_add_f32 v[232:233], v[232:233], v[200:201]
	v_pk_add_f32 v[232:233], v[232:233], v[202:203]
	ds_read2_b32 v[188:189], v115 offset0:34 offset1:35
	ds_read2_b32 v[190:191], v115 offset0:36 offset1:37
	ds_read2_b32 v[192:193], v115 offset0:42 offset1:43
	ds_read2_b32 v[194:195], v115 offset0:44 offset1:45
	ds_read2_b32 v[196:197], v115 offset0:51 offset1:52
	ds_read2_b32 v[198:199], v115 offset0:53 offset1:54
	ds_read2_b32 v[200:201], v115 offset0:59 offset1:60
	ds_read2_b32 v[202:203], v115 offset0:61 offset1:62
	v_mfma_f32_32x32x16_bf16 v[0:15], v[64:67], v[72:75], v[0:15]
	v_mfma_f32_32x32x16_bf16 v[16:31], v[64:67], v[76:79], v[16:31]
	v_mfma_f32_32x32x16_bf16 v[0:15], v[68:71], v[220:223], v[0:15]
	v_mfma_f32_32x32x16_bf16 v[16:31], v[68:71], v[224:227], v[16:31]
	s_add_i32 s90, s76, 448
	v_add_u32_e32 v80, s90, v235
	v_add_u32_e32 v83, s90, v236
	v_add_u32_e32 v99, s90, v237
	v_add_u32_e32 v253, s90, v238
	v_add_u32_e32 v254, s90, v100
	v_add_u32_e32 v255, s90, v149
	v_med3_i32 v80, v80, 0, s99
	v_med3_i32 v83, v83, 0, s99
	v_med3_i32 v99, v99, 0, s99
	v_med3_i32 v253, v253, 0, s99
	v_med3_i32 v254, v254, 0, s99
	v_med3_i32 v255, v255, 0, s99
	v_mad_u32_u24 v80, v80, s100, v252
	v_mad_u32_u24 v83, v83, s100, v252
	v_mad_u32_u24 v99, v99, s100, v252
	v_mad_u32_u24 v253, v253, s100, v252
	v_mad_u32_u24 v254, v254, s100, v153
	v_mad_u32_u24 v255, v255, s100, v153
	global_load_dwordx4 v[116:119], v80, s[82:83]
	global_load_dwordx4 v[120:123], v83, s[82:83]
	global_load_dwordx4 v[124:127], v99, s[82:83]
	global_load_dwordx4 v[128:131], v253, s[82:83]
	global_load_dwordx4 v[132:135], v254, s[82:83] offset:768
	global_load_dwordx4 v[136:139], v255, s[82:83] offset:768
	global_load_dwordx4 v[140:143], v254, s[82:83] offset:832
	global_load_dwordx4 v[144:147], v255, s[82:83] offset:832
	ds_read_b64_tr_b16 v[72:73], v231
	ds_read_b64_tr_b16 v[74:75], v231 offset:512
	ds_read_b64_tr_b16 v[76:77], v231 offset:2048
	ds_read_b64_tr_b16 v[78:79], v231 offset:2560
	ds_read_b64_tr_b16 v[220:221], v231 offset:1024
	ds_read_b64_tr_b16 v[222:223], v231 offset:1536
	ds_read_b64_tr_b16 v[224:225], v231 offset:3072
	ds_read_b64_tr_b16 v[226:227], v231 offset:3584
	v_exp_f32_e32 v32, v32
	v_exp_f32_e32 v33, v33
	v_exp_f32_e32 v34, v34
	v_exp_f32_e32 v35, v35
	s_waitcnt vmcnt(8)
	ds_write_b128 v247, v[156:159]
	ds_write_b128 v247, v[160:163] offset:1024
	ds_write_b128 v247, v[164:167] offset:2048
	ds_write_b128 v247, v[168:171] offset:3072
	ds_read_b128 v[156:159], v248
	ds_read_b128 v[160:163], v249
	ds_read_b128 v[164:167], v250
	ds_read_b128 v[168:171], v251
	ds_write_b128 v112, v[172:175]
	ds_write_b128 v112, v[176:179] offset:1024
	ds_write_b128 v112, v[180:183] offset:2048
	ds_write_b128 v112, v[184:187] offset:3072
	v_exp_f32_e32 v36, v36
	v_exp_f32_e32 v37, v37
	v_exp_f32_e32 v38, v38
	v_exp_f32_e32 v39, v39
	s_waitcnt lgkmcnt(4)
	v_mfma_f32_32x32x16_bf16 v[188:203], v[156:159], v[48:51], v[188:203]
	v_exp_f32_e32 v40, v40
	v_exp_f32_e32 v41, v41
	v_mfma_f32_32x32x16_bf16 v[188:203], v[160:163], v[52:55], v[188:203]
	v_exp_f32_e32 v42, v42
	v_exp_f32_e32 v43, v43
	v_mfma_f32_32x32x16_bf16 v[188:203], v[164:167], v[56:59], v[188:203]
	v_exp_f32_e32 v44, v44
	v_exp_f32_e32 v45, v45
	v_mfma_f32_32x32x16_bf16 v[188:203], v[168:171], v[60:63], v[188:203]
	v_exp_f32_e32 v46, v46
	v_exp_f32_e32 v47, v47
	s_add_i32 s90, s76, 384
	v_add_u32_e32 v84, s90, v107
	v_add_u32_e32 v85, 0, v84
	v_add_u32_e32 v86, 1, v84
	v_add_u32_e32 v87, 2, v84
	v_add_u32_e32 v88, 3, v84
	v_cmp_gt_u32_e64 s[30:31], s98, v85
	v_cmp_gt_u32_e64 s[36:37], s98, v86
	v_cmp_gt_u32_e64 s[78:79], s98, v87
	v_cmp_gt_u32_e64 s[50:51], s98, v88
	v_cndmask_b32_e64 v32, 0, v32, s[30:31]
	v_add_u32_e32 v85, 8, v84
	v_cmp_gt_u32_e64 s[30:31], s98, v85
	v_cndmask_b32_e64 v33, 0, v33, s[36:37]
	v_add_u32_e32 v86, 9, v84
	v_cmp_gt_u32_e64 s[36:37], s98, v86
	v_cndmask_b32_e64 v34, 0, v34, s[78:79]
	v_add_u32_e32 v87, 10, v84
	v_cmp_gt_u32_e64 s[78:79], s98, v87
	v_cndmask_b32_e64 v35, 0, v35, s[50:51]
	v_add_u32_e32 v88, 11, v84
	v_cmp_gt_u32_e64 s[50:51], s98, v88
	v_cndmask_b32_e64 v36, 0, v36, s[30:31]
	v_add_u32_e32 v85, 16, v84
	v_cmp_gt_u32_e64 s[30:31], s98, v85
	v_cndmask_b32_e64 v37, 0, v37, s[36:37]
	v_add_u32_e32 v86, 17, v84
	v_cmp_gt_u32_e64 s[36:37], s98, v86
	v_cndmask_b32_e64 v38, 0, v38, s[78:79]
	v_add_u32_e32 v87, 18, v84
	v_cmp_gt_u32_e64 s[78:79], s98, v87
	v_cndmask_b32_e64 v39, 0, v39, s[50:51]
	v_add_u32_e32 v88, 19, v84
	v_cmp_gt_u32_e64 s[50:51], s98, v88
	v_cndmask_b32_e64 v40, 0, v40, s[30:31]
	v_add_u32_e32 v85, 24, v84
	v_cmp_gt_u32_e64 s[30:31], s98, v85
	v_cndmask_b32_e64 v41, 0, v41, s[36:37]
	v_add_u32_e32 v86, 25, v84
	v_cmp_gt_u32_e64 s[36:37], s98, v86
	v_cndmask_b32_e64 v42, 0, v42, s[78:79]
	v_add_u32_e32 v87, 26, v84
	v_cmp_gt_u32_e64 s[78:79], s98, v87
	v_cndmask_b32_e64 v43, 0, v43, s[50:51]
	v_add_u32_e32 v88, 27, v84
	v_cmp_gt_u32_e64 s[50:51], s98, v88
	v_nop
	v_cndmask_b32_e64 v44, 0, v44, s[30:31]
	v_cndmask_b32_e64 v45, 0, v45, s[36:37]
	v_cndmask_b32_e64 v46, 0, v46, s[78:79]
	v_cndmask_b32_e64 v47, 0, v47, s[50:51]
	v_cvt_pk_bf16_f32 v64, v32, v33
	v_cvt_pk_bf16_f32 v65, v34, v35
	v_cvt_pk_bf16_f32 v66, v36, v37
	v_cvt_pk_bf16_f32 v67, v38, v39
	v_cvt_pk_bf16_f32 v68, v40, v41
	v_cvt_pk_bf16_f32 v69, v42, v43
	v_cvt_pk_bf16_f32 v70, v44, v45
	v_cvt_pk_bf16_f32 v71, v46, v47
	v_pk_add_f32 v[232:233], v[232:233], v[32:33]
	v_pk_add_f32 v[232:233], v[232:233], v[34:35]
	v_pk_add_f32 v[232:233], v[232:233], v[36:37]
	v_pk_add_f32 v[232:233], v[232:233], v[38:39]
	v_pk_add_f32 v[232:233], v[232:233], v[40:41]
	v_pk_add_f32 v[232:233], v[232:233], v[42:43]
	v_pk_add_f32 v[232:233], v[232:233], v[44:45]
	v_pk_add_f32 v[232:233], v[232:233], v[46:47]
	ds_read2_b32 v[32:33], v115 offset0:68 offset1:69
	ds_read2_b32 v[34:35], v115 offset0:70 offset1:71
	ds_read2_b32 v[36:37], v115 offset0:76 offset1:77
	ds_read2_b32 v[38:39], v115 offset0:78 offset1:79
	ds_read2_b32 v[40:41], v115 offset0:85 offset1:86
	ds_read2_b32 v[42:43], v115 offset0:87 offset1:88
	ds_read2_b32 v[44:45], v115 offset0:93 offset1:94
	ds_read2_b32 v[46:47], v115 offset0:95 offset1:96
	v_mfma_f32_32x32x16_bf16 v[0:15], v[64:67], v[72:75], v[0:15]
	v_mfma_f32_32x32x16_bf16 v[16:31], v[64:67], v[76:79], v[16:31]
	v_mfma_f32_32x32x16_bf16 v[0:15], v[68:71], v[220:223], v[0:15]
	v_mfma_f32_32x32x16_bf16 v[16:31], v[68:71], v[224:227], v[16:31]
	s_add_i32 s90, s76, 480
	v_add_u32_e32 v80, s90, v235
	v_add_u32_e32 v83, s90, v236
	v_add_u32_e32 v99, s90, v237
	v_add_u32_e32 v253, s90, v238
	v_add_u32_e32 v254, s90, v100
	v_add_u32_e32 v255, s90, v149
	v_med3_i32 v80, v80, 0, s99
	v_med3_i32 v83, v83, 0, s99
	v_med3_i32 v99, v99, 0, s99
	v_med3_i32 v253, v253, 0, s99
	v_med3_i32 v254, v254, 0, s99
	v_med3_i32 v255, v255, 0, s99
	v_mad_u32_u24 v80, v80, s100, v252
	v_mad_u32_u24 v83, v83, s100, v252
	v_mad_u32_u24 v99, v99, s100, v252
	v_mad_u32_u24 v253, v253, s100, v252
	v_mad_u32_u24 v254, v254, s100, v153
	v_mad_u32_u24 v255, v255, s100, v153
	global_load_dwordx4 v[156:159], v80, s[82:83]
	global_load_dwordx4 v[160:163], v83, s[82:83]
	global_load_dwordx4 v[164:167], v99, s[82:83]
	global_load_dwordx4 v[168:171], v253, s[82:83]
	global_load_dwordx4 v[172:175], v254, s[82:83] offset:768
	global_load_dwordx4 v[176:179], v255, s[82:83] offset:768
	global_load_dwordx4 v[180:183], v254, s[82:83] offset:832
	global_load_dwordx4 v[184:187], v255, s[82:83] offset:832
	ds_read_b64_tr_b16 v[72:73], v231
	ds_read_b64_tr_b16 v[74:75], v231 offset:512
	ds_read_b64_tr_b16 v[76:77], v231 offset:2048
	ds_read_b64_tr_b16 v[78:79], v231 offset:2560
	ds_read_b64_tr_b16 v[220:221], v231 offset:1024
	ds_read_b64_tr_b16 v[222:223], v231 offset:1536
	ds_read_b64_tr_b16 v[224:225], v231 offset:3072
	ds_read_b64_tr_b16 v[226:227], v231 offset:3584
	v_exp_f32_e32 v188, v188
	v_exp_f32_e32 v189, v189
	v_exp_f32_e32 v190, v190
	v_exp_f32_e32 v191, v191
	s_waitcnt vmcnt(8)
	ds_write_b128 v247, v[116:119]
	ds_write_b128 v247, v[120:123] offset:1024
	ds_write_b128 v247, v[124:127] offset:2048
	ds_write_b128 v247, v[128:131] offset:3072
	ds_read_b128 v[116:119], v248
	ds_read_b128 v[120:123], v249
	ds_read_b128 v[124:127], v250
	ds_read_b128 v[128:131], v251
	ds_write_b128 v112, v[132:135]
	ds_write_b128 v112, v[136:139] offset:1024
	ds_write_b128 v112, v[140:143] offset:2048
	ds_write_b128 v112, v[144:147] offset:3072
	v_exp_f32_e32 v192, v192
	v_exp_f32_e32 v193, v193
	v_exp_f32_e32 v194, v194
	v_exp_f32_e32 v195, v195
	s_waitcnt lgkmcnt(4)
	v_mfma_f32_32x32x16_bf16 v[32:47], v[116:119], v[48:51], v[32:47]
	v_exp_f32_e32 v196, v196
	v_exp_f32_e32 v197, v197
	v_mfma_f32_32x32x16_bf16 v[32:47], v[120:123], v[52:55], v[32:47]
	v_exp_f32_e32 v198, v198
	v_exp_f32_e32 v199, v199
	v_mfma_f32_32x32x16_bf16 v[32:47], v[124:127], v[56:59], v[32:47]
	v_exp_f32_e32 v200, v200
	v_exp_f32_e32 v201, v201
	v_mfma_f32_32x32x16_bf16 v[32:47], v[128:131], v[60:63], v[32:47]
	v_exp_f32_e32 v202, v202
	v_exp_f32_e32 v203, v203
	s_add_i32 s90, s76, 416
	v_add_u32_e32 v84, s90, v107
	v_add_u32_e32 v85, 0, v84
	v_add_u32_e32 v86, 1, v84
	v_add_u32_e32 v87, 2, v84
	v_add_u32_e32 v88, 3, v84
	v_cmp_gt_u32_e64 s[30:31], s98, v85
	v_cmp_gt_u32_e64 s[36:37], s98, v86
	v_cmp_gt_u32_e64 s[78:79], s98, v87
	v_cmp_gt_u32_e64 s[50:51], s98, v88
	v_cndmask_b32_e64 v188, 0, v188, s[30:31]
	v_add_u32_e32 v85, 8, v84
	v_cmp_gt_u32_e64 s[30:31], s98, v85
	v_cndmask_b32_e64 v189, 0, v189, s[36:37]
	v_add_u32_e32 v86, 9, v84
	v_cmp_gt_u32_e64 s[36:37], s98, v86
	v_cndmask_b32_e64 v190, 0, v190, s[78:79]
	v_add_u32_e32 v87, 10, v84
	v_cmp_gt_u32_e64 s[78:79], s98, v87
	v_cndmask_b32_e64 v191, 0, v191, s[50:51]
	v_add_u32_e32 v88, 11, v84
	v_cmp_gt_u32_e64 s[50:51], s98, v88
	v_cndmask_b32_e64 v192, 0, v192, s[30:31]
	v_add_u32_e32 v85, 16, v84
	v_cmp_gt_u32_e64 s[30:31], s98, v85
	v_cndmask_b32_e64 v193, 0, v193, s[36:37]
	v_add_u32_e32 v86, 17, v84
	v_cmp_gt_u32_e64 s[36:37], s98, v86
	v_cndmask_b32_e64 v194, 0, v194, s[78:79]
	v_add_u32_e32 v87, 18, v84
	v_cmp_gt_u32_e64 s[78:79], s98, v87
	v_cndmask_b32_e64 v195, 0, v195, s[50:51]
	v_add_u32_e32 v88, 19, v84
	v_cmp_gt_u32_e64 s[50:51], s98, v88
	v_cndmask_b32_e64 v196, 0, v196, s[30:31]
	v_add_u32_e32 v85, 24, v84
	v_cmp_gt_u32_e64 s[30:31], s98, v85
	v_cndmask_b32_e64 v197, 0, v197, s[36:37]
	v_add_u32_e32 v86, 25, v84
	v_cmp_gt_u32_e64 s[36:37], s98, v86
	v_cndmask_b32_e64 v198, 0, v198, s[78:79]
	v_add_u32_e32 v87, 26, v84
	v_cmp_gt_u32_e64 s[78:79], s98, v87
	v_cndmask_b32_e64 v199, 0, v199, s[50:51]
	v_add_u32_e32 v88, 27, v84
	v_cmp_gt_u32_e64 s[50:51], s98, v88
	v_nop
	v_cndmask_b32_e64 v200, 0, v200, s[30:31]
	v_cndmask_b32_e64 v201, 0, v201, s[36:37]
	v_cndmask_b32_e64 v202, 0, v202, s[78:79]
	v_cndmask_b32_e64 v203, 0, v203, s[50:51]
	v_cvt_pk_bf16_f32 v64, v188, v189
	v_cvt_pk_bf16_f32 v65, v190, v191
	v_cvt_pk_bf16_f32 v66, v192, v193
	v_cvt_pk_bf16_f32 v67, v194, v195
	v_cvt_pk_bf16_f32 v68, v196, v197
	v_cvt_pk_bf16_f32 v69, v198, v199
	v_cvt_pk_bf16_f32 v70, v200, v201
	v_cvt_pk_bf16_f32 v71, v202, v203
	v_pk_add_f32 v[232:233], v[232:233], v[188:189]
	v_pk_add_f32 v[232:233], v[232:233], v[190:191]
	v_pk_add_f32 v[232:233], v[232:233], v[192:193]
	v_pk_add_f32 v[232:233], v[232:233], v[194:195]
	v_pk_add_f32 v[232:233], v[232:233], v[196:197]
	v_pk_add_f32 v[232:233], v[232:233], v[198:199]
	v_pk_add_f32 v[232:233], v[232:233], v[200:201]
	v_pk_add_f32 v[232:233], v[232:233], v[202:203]
	ds_read2_b32 v[188:189], v115 offset0:102 offset1:103
	ds_read2_b32 v[190:191], v115 offset0:104 offset1:105
	ds_read2_b32 v[192:193], v115 offset0:110 offset1:111
	ds_read2_b32 v[194:195], v115 offset0:112 offset1:113
	ds_read2_b32 v[196:197], v115 offset0:119 offset1:120
	ds_read2_b32 v[198:199], v115 offset0:121 offset1:122
	ds_read2_b32 v[200:201], v115 offset0:127 offset1:128
	ds_read2_b32 v[202:203], v115 offset0:129 offset1:130
	v_mfma_f32_32x32x16_bf16 v[0:15], v[64:67], v[72:75], v[0:15]
	v_mfma_f32_32x32x16_bf16 v[16:31], v[64:67], v[76:79], v[16:31]
	v_mfma_f32_32x32x16_bf16 v[0:15], v[68:71], v[220:223], v[0:15]
	v_mfma_f32_32x32x16_bf16 v[16:31], v[68:71], v[224:227], v[16:31]
	s_add_i32 s90, s76, 512
	v_add_u32_e32 v80, s90, v235
	v_add_u32_e32 v83, s90, v236
	v_add_u32_e32 v99, s90, v237
	v_add_u32_e32 v253, s90, v238
	v_add_u32_e32 v254, s90, v100
	v_add_u32_e32 v255, s90, v149
	v_med3_i32 v80, v80, 0, s99
	v_med3_i32 v83, v83, 0, s99
	v_med3_i32 v99, v99, 0, s99
	v_med3_i32 v253, v253, 0, s99
	v_med3_i32 v254, v254, 0, s99
	v_med3_i32 v255, v255, 0, s99
	v_mad_u32_u24 v80, v80, s100, v252
	v_mad_u32_u24 v83, v83, s100, v252
	v_mad_u32_u24 v99, v99, s100, v252
	v_mad_u32_u24 v253, v253, s100, v252
	v_mad_u32_u24 v254, v254, s100, v153
	v_mad_u32_u24 v255, v255, s100, v153
	global_load_dwordx4 v[116:119], v80, s[82:83]
	global_load_dwordx4 v[120:123], v83, s[82:83]
	global_load_dwordx4 v[124:127], v99, s[82:83]
	global_load_dwordx4 v[128:131], v253, s[82:83]
	global_load_dwordx4 v[132:135], v254, s[82:83] offset:768
	global_load_dwordx4 v[136:139], v255, s[82:83] offset:768
	global_load_dwordx4 v[140:143], v254, s[82:83] offset:832
	global_load_dwordx4 v[144:147], v255, s[82:83] offset:832
	ds_read_b64_tr_b16 v[72:73], v231
	ds_read_b64_tr_b16 v[74:75], v231 offset:512
	ds_read_b64_tr_b16 v[76:77], v231 offset:2048
	ds_read_b64_tr_b16 v[78:79], v231 offset:2560
	ds_read_b64_tr_b16 v[220:221], v231 offset:1024
	ds_read_b64_tr_b16 v[222:223], v231 offset:1536
	ds_read_b64_tr_b16 v[224:225], v231 offset:3072
	ds_read_b64_tr_b16 v[226:227], v231 offset:3584
	v_exp_f32_e32 v32, v32
	v_exp_f32_e32 v33, v33
	v_exp_f32_e32 v34, v34
	v_exp_f32_e32 v35, v35
	s_waitcnt vmcnt(8)
	ds_write_b128 v247, v[156:159]
	ds_write_b128 v247, v[160:163] offset:1024
	ds_write_b128 v247, v[164:167] offset:2048
	ds_write_b128 v247, v[168:171] offset:3072
	ds_read_b128 v[156:159], v248
	ds_read_b128 v[160:163], v249
	ds_read_b128 v[164:167], v250
	ds_read_b128 v[168:171], v251
	ds_write_b128 v112, v[172:175]
	ds_write_b128 v112, v[176:179] offset:1024
	ds_write_b128 v112, v[180:183] offset:2048
	ds_write_b128 v112, v[184:187] offset:3072
	v_exp_f32_e32 v36, v36
	v_exp_f32_e32 v37, v37
	v_exp_f32_e32 v38, v38
	v_exp_f32_e32 v39, v39
	s_waitcnt lgkmcnt(4)
	v_mfma_f32_32x32x16_bf16 v[188:203], v[156:159], v[48:51], v[188:203]
	v_exp_f32_e32 v40, v40
	v_exp_f32_e32 v41, v41
	v_mfma_f32_32x32x16_bf16 v[188:203], v[160:163], v[52:55], v[188:203]
	v_exp_f32_e32 v42, v42
	v_exp_f32_e32 v43, v43
	v_mfma_f32_32x32x16_bf16 v[188:203], v[164:167], v[56:59], v[188:203]
	v_exp_f32_e32 v44, v44
	v_exp_f32_e32 v45, v45
	v_mfma_f32_32x32x16_bf16 v[188:203], v[168:171], v[60:63], v[188:203]
	v_exp_f32_e32 v46, v46
	v_exp_f32_e32 v47, v47
	s_add_i32 s90, s76, 448
	v_add_u32_e32 v84, s90, v107
	v_add_u32_e32 v85, 0, v84
	v_add_u32_e32 v86, 1, v84
	v_add_u32_e32 v87, 2, v84
	v_add_u32_e32 v88, 3, v84
	v_cmp_gt_u32_e64 s[30:31], s98, v85
	v_cmp_gt_u32_e64 s[36:37], s98, v86
	v_cmp_gt_u32_e64 s[78:79], s98, v87
	v_cmp_gt_u32_e64 s[50:51], s98, v88
	v_cndmask_b32_e64 v32, 0, v32, s[30:31]
	v_add_u32_e32 v85, 8, v84
	v_cmp_gt_u32_e64 s[30:31], s98, v85
	v_cndmask_b32_e64 v33, 0, v33, s[36:37]
	v_add_u32_e32 v86, 9, v84
	v_cmp_gt_u32_e64 s[36:37], s98, v86
	v_cndmask_b32_e64 v34, 0, v34, s[78:79]
	v_add_u32_e32 v87, 10, v84
	v_cmp_gt_u32_e64 s[78:79], s98, v87
	v_cndmask_b32_e64 v35, 0, v35, s[50:51]
	v_add_u32_e32 v88, 11, v84
	v_cmp_gt_u32_e64 s[50:51], s98, v88
	v_cndmask_b32_e64 v36, 0, v36, s[30:31]
	v_add_u32_e32 v85, 16, v84
	v_cmp_gt_u32_e64 s[30:31], s98, v85
	v_cndmask_b32_e64 v37, 0, v37, s[36:37]
	v_add_u32_e32 v86, 17, v84
	v_cmp_gt_u32_e64 s[36:37], s98, v86
	v_cndmask_b32_e64 v38, 0, v38, s[78:79]
	v_add_u32_e32 v87, 18, v84
	v_cmp_gt_u32_e64 s[78:79], s98, v87
	v_cndmask_b32_e64 v39, 0, v39, s[50:51]
	v_add_u32_e32 v88, 19, v84
	v_cmp_gt_u32_e64 s[50:51], s98, v88
	v_cndmask_b32_e64 v40, 0, v40, s[30:31]
	v_add_u32_e32 v85, 24, v84
	v_cmp_gt_u32_e64 s[30:31], s98, v85
	v_cndmask_b32_e64 v41, 0, v41, s[36:37]
	v_add_u32_e32 v86, 25, v84
	v_cmp_gt_u32_e64 s[36:37], s98, v86
	v_cndmask_b32_e64 v42, 0, v42, s[78:79]
	v_add_u32_e32 v87, 26, v84
	v_cmp_gt_u32_e64 s[78:79], s98, v87
	v_cndmask_b32_e64 v43, 0, v43, s[50:51]
	v_add_u32_e32 v88, 27, v84
	v_cmp_gt_u32_e64 s[50:51], s98, v88
	v_nop
	v_cndmask_b32_e64 v44, 0, v44, s[30:31]
	v_cndmask_b32_e64 v45, 0, v45, s[36:37]
	v_cndmask_b32_e64 v46, 0, v46, s[78:79]
	v_cndmask_b32_e64 v47, 0, v47, s[50:51]
	v_cvt_pk_bf16_f32 v64, v32, v33
	v_cvt_pk_bf16_f32 v65, v34, v35
	v_cvt_pk_bf16_f32 v66, v36, v37
	v_cvt_pk_bf16_f32 v67, v38, v39
	v_cvt_pk_bf16_f32 v68, v40, v41
	v_cvt_pk_bf16_f32 v69, v42, v43
	v_cvt_pk_bf16_f32 v70, v44, v45
	v_cvt_pk_bf16_f32 v71, v46, v47
	v_pk_add_f32 v[232:233], v[232:233], v[32:33]
	v_pk_add_f32 v[232:233], v[232:233], v[34:35]
	v_pk_add_f32 v[232:233], v[232:233], v[36:37]
	v_pk_add_f32 v[232:233], v[232:233], v[38:39]
	v_pk_add_f32 v[232:233], v[232:233], v[40:41]
	v_pk_add_f32 v[232:233], v[232:233], v[42:43]
	v_pk_add_f32 v[232:233], v[232:233], v[44:45]
	v_pk_add_f32 v[232:233], v[232:233], v[46:47]
	ds_read2_b32 v[32:33], v115 offset0:136 offset1:137
	ds_read2_b32 v[34:35], v115 offset0:138 offset1:139
	ds_read2_b32 v[36:37], v115 offset0:144 offset1:145
	ds_read2_b32 v[38:39], v115 offset0:146 offset1:147
	ds_read2_b32 v[40:41], v115 offset0:153 offset1:154
	ds_read2_b32 v[42:43], v115 offset0:155 offset1:156
	ds_read2_b32 v[44:45], v115 offset0:161 offset1:162
	ds_read2_b32 v[46:47], v115 offset0:163 offset1:164
	v_mfma_f32_32x32x16_bf16 v[0:15], v[64:67], v[72:75], v[0:15]
	v_mfma_f32_32x32x16_bf16 v[16:31], v[64:67], v[76:79], v[16:31]
	v_mfma_f32_32x32x16_bf16 v[0:15], v[68:71], v[220:223], v[0:15]
	v_mfma_f32_32x32x16_bf16 v[16:31], v[68:71], v[224:227], v[16:31]
	s_add_i32 s90, s76, 544
	v_add_u32_e32 v80, s90, v235
	v_add_u32_e32 v83, s90, v236
	v_add_u32_e32 v99, s90, v237
	v_add_u32_e32 v253, s90, v238
	v_add_u32_e32 v254, s90, v100
	v_add_u32_e32 v255, s90, v149
	v_med3_i32 v80, v80, 0, s99
	v_med3_i32 v83, v83, 0, s99
	v_med3_i32 v99, v99, 0, s99
	v_med3_i32 v253, v253, 0, s99
	v_med3_i32 v254, v254, 0, s99
	v_med3_i32 v255, v255, 0, s99
	v_mad_u32_u24 v80, v80, s100, v252
	v_mad_u32_u24 v83, v83, s100, v252
	v_mad_u32_u24 v99, v99, s100, v252
	v_mad_u32_u24 v253, v253, s100, v252
	v_mad_u32_u24 v254, v254, s100, v153
	v_mad_u32_u24 v255, v255, s100, v153
	global_load_dwordx4 v[156:159], v80, s[82:83]
	global_load_dwordx4 v[160:163], v83, s[82:83]
	global_load_dwordx4 v[164:167], v99, s[82:83]
	global_load_dwordx4 v[168:171], v253, s[82:83]
	global_load_dwordx4 v[172:175], v254, s[82:83] offset:768
	global_load_dwordx4 v[176:179], v255, s[82:83] offset:768
	global_load_dwordx4 v[180:183], v254, s[82:83] offset:832
	global_load_dwordx4 v[184:187], v255, s[82:83] offset:832
	ds_read_b64_tr_b16 v[72:73], v231
	ds_read_b64_tr_b16 v[74:75], v231 offset:512
	ds_read_b64_tr_b16 v[76:77], v231 offset:2048
	ds_read_b64_tr_b16 v[78:79], v231 offset:2560
	ds_read_b64_tr_b16 v[220:221], v231 offset:1024
	ds_read_b64_tr_b16 v[222:223], v231 offset:1536
	ds_read_b64_tr_b16 v[224:225], v231 offset:3072
	ds_read_b64_tr_b16 v[226:227], v231 offset:3584
	v_exp_f32_e32 v188, v188
	v_exp_f32_e32 v189, v189
	v_exp_f32_e32 v190, v190
	v_exp_f32_e32 v191, v191
	s_waitcnt vmcnt(8)
	ds_write_b128 v247, v[116:119]
	ds_write_b128 v247, v[120:123] offset:1024
	ds_write_b128 v247, v[124:127] offset:2048
	ds_write_b128 v247, v[128:131] offset:3072
	ds_read_b128 v[116:119], v248
	ds_read_b128 v[120:123], v249
	ds_read_b128 v[124:127], v250
	ds_read_b128 v[128:131], v251
	ds_write_b128 v112, v[132:135]
	ds_write_b128 v112, v[136:139] offset:1024
	ds_write_b128 v112, v[140:143] offset:2048
	ds_write_b128 v112, v[144:147] offset:3072
	v_exp_f32_e32 v192, v192
	v_exp_f32_e32 v193, v193
	v_exp_f32_e32 v194, v194
	v_exp_f32_e32 v195, v195
	s_waitcnt lgkmcnt(4)
	v_mfma_f32_32x32x16_bf16 v[32:47], v[116:119], v[48:51], v[32:47]
	v_exp_f32_e32 v196, v196
	v_exp_f32_e32 v197, v197
	v_mfma_f32_32x32x16_bf16 v[32:47], v[120:123], v[52:55], v[32:47]
	v_exp_f32_e32 v198, v198
	v_exp_f32_e32 v199, v199
	v_mfma_f32_32x32x16_bf16 v[32:47], v[124:127], v[56:59], v[32:47]
	v_exp_f32_e32 v200, v200
	v_exp_f32_e32 v201, v201
	v_mfma_f32_32x32x16_bf16 v[32:47], v[128:131], v[60:63], v[32:47]
	v_exp_f32_e32 v202, v202
	v_exp_f32_e32 v203, v203
	s_add_i32 s90, s76, 480
	v_add_u32_e32 v84, s90, v107
	v_add_u32_e32 v85, 0, v84
	v_add_u32_e32 v86, 1, v84
	v_add_u32_e32 v87, 2, v84
	v_add_u32_e32 v88, 3, v84
	v_cmp_gt_u32_e64 s[30:31], s98, v85
	v_cmp_gt_u32_e64 s[36:37], s98, v86
	v_cmp_gt_u32_e64 s[78:79], s98, v87
	v_cmp_gt_u32_e64 s[50:51], s98, v88
	v_cndmask_b32_e64 v188, 0, v188, s[30:31]
	v_add_u32_e32 v85, 8, v84
	v_cmp_gt_u32_e64 s[30:31], s98, v85
	v_cndmask_b32_e64 v189, 0, v189, s[36:37]
	v_add_u32_e32 v86, 9, v84
	v_cmp_gt_u32_e64 s[36:37], s98, v86
	v_cndmask_b32_e64 v190, 0, v190, s[78:79]
	v_add_u32_e32 v87, 10, v84
	v_cmp_gt_u32_e64 s[78:79], s98, v87
	v_cndmask_b32_e64 v191, 0, v191, s[50:51]
	v_add_u32_e32 v88, 11, v84
	v_cmp_gt_u32_e64 s[50:51], s98, v88
	v_cndmask_b32_e64 v192, 0, v192, s[30:31]
	v_add_u32_e32 v85, 16, v84
	v_cmp_gt_u32_e64 s[30:31], s98, v85
	v_cndmask_b32_e64 v193, 0, v193, s[36:37]
	v_add_u32_e32 v86, 17, v84
	v_cmp_gt_u32_e64 s[36:37], s98, v86
	v_cndmask_b32_e64 v194, 0, v194, s[78:79]
	v_add_u32_e32 v87, 18, v84
	v_cmp_gt_u32_e64 s[78:79], s98, v87
	v_cndmask_b32_e64 v195, 0, v195, s[50:51]
	v_add_u32_e32 v88, 19, v84
	v_cmp_gt_u32_e64 s[50:51], s98, v88
	v_cndmask_b32_e64 v196, 0, v196, s[30:31]
	v_add_u32_e32 v85, 24, v84
	v_cmp_gt_u32_e64 s[30:31], s98, v85
	v_cndmask_b32_e64 v197, 0, v197, s[36:37]
	v_add_u32_e32 v86, 25, v84
	v_cmp_gt_u32_e64 s[36:37], s98, v86
	v_cndmask_b32_e64 v198, 0, v198, s[78:79]
	v_add_u32_e32 v87, 26, v84
	v_cmp_gt_u32_e64 s[78:79], s98, v87
	v_cndmask_b32_e64 v199, 0, v199, s[50:51]
	v_add_u32_e32 v88, 27, v84
	v_cmp_gt_u32_e64 s[50:51], s98, v88
	v_nop
	v_cndmask_b32_e64 v200, 0, v200, s[30:31]
	v_cndmask_b32_e64 v201, 0, v201, s[36:37]
	v_cndmask_b32_e64 v202, 0, v202, s[78:79]
	v_cndmask_b32_e64 v203, 0, v203, s[50:51]
	v_cvt_pk_bf16_f32 v64, v188, v189
	v_cvt_pk_bf16_f32 v65, v190, v191
	v_cvt_pk_bf16_f32 v66, v192, v193
	v_cvt_pk_bf16_f32 v67, v194, v195
	v_cvt_pk_bf16_f32 v68, v196, v197
	v_cvt_pk_bf16_f32 v69, v198, v199
	v_cvt_pk_bf16_f32 v70, v200, v201
	v_cvt_pk_bf16_f32 v71, v202, v203
	v_pk_add_f32 v[232:233], v[232:233], v[188:189]
	v_pk_add_f32 v[232:233], v[232:233], v[190:191]
	v_pk_add_f32 v[232:233], v[232:233], v[192:193]
	v_pk_add_f32 v[232:233], v[232:233], v[194:195]
	v_pk_add_f32 v[232:233], v[232:233], v[196:197]
	v_pk_add_f32 v[232:233], v[232:233], v[198:199]
	v_pk_add_f32 v[232:233], v[232:233], v[200:201]
	v_pk_add_f32 v[232:233], v[232:233], v[202:203]
	ds_read2_b32 v[188:189], v115 offset0:170 offset1:171
	ds_read2_b32 v[190:191], v115 offset0:172 offset1:173
	ds_read2_b32 v[192:193], v115 offset0:178 offset1:179
	ds_read2_b32 v[194:195], v115 offset0:180 offset1:181
	ds_read2_b32 v[196:197], v115 offset0:187 offset1:188
	ds_read2_b32 v[198:199], v115 offset0:189 offset1:190
	ds_read2_b32 v[200:201], v115 offset0:195 offset1:196
	ds_read2_b32 v[202:203], v115 offset0:197 offset1:198
	v_mfma_f32_32x32x16_bf16 v[0:15], v[64:67], v[72:75], v[0:15]
	v_mfma_f32_32x32x16_bf16 v[16:31], v[64:67], v[76:79], v[16:31]
	v_mfma_f32_32x32x16_bf16 v[0:15], v[68:71], v[220:223], v[0:15]
	v_mfma_f32_32x32x16_bf16 v[16:31], v[68:71], v[224:227], v[16:31]
	s_add_i32 s90, s76, -256
	v_add_u32_e32 v80, s90, v239
	v_add_u32_e32 v83, s90, v240
	v_add_u32_e32 v99, s90, v241
	v_add_u32_e32 v253, s90, v242
	v_add_u32_e32 v254, s90, v101
	v_add_u32_e32 v255, s90, v150
	v_med3_i32 v80, v80, 0, s99
	v_med3_i32 v83, v83, 0, s99
	v_med3_i32 v99, v99, 0, s99
	v_med3_i32 v253, v253, 0, s99
	v_med3_i32 v254, v254, 0, s99
	v_med3_i32 v255, v255, 0, s99
	v_mad_u32_u24 v80, v80, s100, v252
	v_mad_u32_u24 v83, v83, s100, v252
	v_mad_u32_u24 v99, v99, s100, v252
	v_mad_u32_u24 v253, v253, s100, v252
	v_mad_u32_u24 v254, v254, s100, v153
	v_mad_u32_u24 v255, v255, s100, v153
	global_load_dwordx4 v[116:119], v80, s[82:83]
	global_load_dwordx4 v[120:123], v83, s[82:83]
	global_load_dwordx4 v[124:127], v99, s[82:83]
	global_load_dwordx4 v[128:131], v253, s[82:83]
	global_load_dwordx4 v[132:135], v254, s[82:83] offset:768
	global_load_dwordx4 v[136:139], v255, s[82:83] offset:768
	global_load_dwordx4 v[140:143], v254, s[82:83] offset:832
	global_load_dwordx4 v[144:147], v255, s[82:83] offset:832
	ds_read_b64_tr_b16 v[72:73], v231
	ds_read_b64_tr_b16 v[74:75], v231 offset:512
	ds_read_b64_tr_b16 v[76:77], v231 offset:2048
	ds_read_b64_tr_b16 v[78:79], v231 offset:2560
	ds_read_b64_tr_b16 v[220:221], v231 offset:1024
	ds_read_b64_tr_b16 v[222:223], v231 offset:1536
	ds_read_b64_tr_b16 v[224:225], v231 offset:3072
	ds_read_b64_tr_b16 v[226:227], v231 offset:3584
	v_exp_f32_e32 v32, v32
	v_exp_f32_e32 v33, v33
	v_exp_f32_e32 v34, v34
	v_exp_f32_e32 v35, v35
	s_waitcnt vmcnt(8)
	ds_write_b128 v247, v[156:159]
	ds_write_b128 v247, v[160:163] offset:1024
	ds_write_b128 v247, v[164:167] offset:2048
	ds_write_b128 v247, v[168:171] offset:3072
	ds_read_b128 v[156:159], v248
	ds_read_b128 v[160:163], v249
	ds_read_b128 v[164:167], v250
	ds_read_b128 v[168:171], v251
	ds_write_b128 v112, v[172:175]
	ds_write_b128 v112, v[176:179] offset:1024
	ds_write_b128 v112, v[180:183] offset:2048
	ds_write_b128 v112, v[184:187] offset:3072
	v_exp_f32_e32 v36, v36
	v_exp_f32_e32 v37, v37
	v_exp_f32_e32 v38, v38
	v_exp_f32_e32 v39, v39
	s_waitcnt lgkmcnt(4)
	v_mfma_f32_32x32x16_bf16 v[188:203], v[156:159], v[48:51], v[188:203]
	v_exp_f32_e32 v40, v40
	v_exp_f32_e32 v41, v41
	v_mfma_f32_32x32x16_bf16 v[188:203], v[160:163], v[52:55], v[188:203]
	v_exp_f32_e32 v42, v42
	v_exp_f32_e32 v43, v43
	v_mfma_f32_32x32x16_bf16 v[188:203], v[164:167], v[56:59], v[188:203]
	v_exp_f32_e32 v44, v44
	v_exp_f32_e32 v45, v45
	v_mfma_f32_32x32x16_bf16 v[188:203], v[168:171], v[60:63], v[188:203]
	v_exp_f32_e32 v46, v46
	v_exp_f32_e32 v47, v47
	s_add_i32 s90, s76, 512
	v_add_u32_e32 v84, s90, v107
	v_add_u32_e32 v85, 0, v84
	v_add_u32_e32 v86, 1, v84
	v_add_u32_e32 v87, 2, v84
	v_add_u32_e32 v88, 3, v84
	v_cmp_gt_u32_e64 s[30:31], s98, v85
	v_cmp_gt_u32_e64 s[36:37], s98, v86
	v_cmp_gt_u32_e64 s[78:79], s98, v87
	v_cmp_gt_u32_e64 s[50:51], s98, v88
	v_cndmask_b32_e64 v32, 0, v32, s[30:31]
	v_add_u32_e32 v85, 8, v84
	v_cmp_gt_u32_e64 s[30:31], s98, v85
	v_cndmask_b32_e64 v33, 0, v33, s[36:37]
	v_add_u32_e32 v86, 9, v84
	v_cmp_gt_u32_e64 s[36:37], s98, v86
	v_cndmask_b32_e64 v34, 0, v34, s[78:79]
	v_add_u32_e32 v87, 10, v84
	v_cmp_gt_u32_e64 s[78:79], s98, v87
	v_cndmask_b32_e64 v35, 0, v35, s[50:51]
	v_add_u32_e32 v88, 11, v84
	v_cmp_gt_u32_e64 s[50:51], s98, v88
	v_cndmask_b32_e64 v36, 0, v36, s[30:31]
	v_add_u32_e32 v85, 16, v84
	v_cmp_gt_u32_e64 s[30:31], s98, v85
	v_cndmask_b32_e64 v37, 0, v37, s[36:37]
	v_add_u32_e32 v86, 17, v84
	v_cmp_gt_u32_e64 s[36:37], s98, v86
	v_cndmask_b32_e64 v38, 0, v38, s[78:79]
	v_add_u32_e32 v87, 18, v84
	v_cmp_gt_u32_e64 s[78:79], s98, v87
	v_cndmask_b32_e64 v39, 0, v39, s[50:51]
	v_add_u32_e32 v88, 19, v84
	v_cmp_gt_u32_e64 s[50:51], s98, v88
	v_cndmask_b32_e64 v40, 0, v40, s[30:31]
	v_add_u32_e32 v85, 24, v84
	v_cmp_gt_u32_e64 s[30:31], s98, v85
	v_cndmask_b32_e64 v41, 0, v41, s[36:37]
	v_add_u32_e32 v86, 25, v84
	v_cmp_gt_u32_e64 s[36:37], s98, v86
	v_cndmask_b32_e64 v42, 0, v42, s[78:79]
	v_add_u32_e32 v87, 26, v84
	v_cmp_gt_u32_e64 s[78:79], s98, v87
	v_cndmask_b32_e64 v43, 0, v43, s[50:51]
	v_add_u32_e32 v88, 27, v84
	v_cmp_gt_u32_e64 s[50:51], s98, v88
	v_nop
	v_cndmask_b32_e64 v44, 0, v44, s[30:31]
	v_cndmask_b32_e64 v45, 0, v45, s[36:37]
	v_cndmask_b32_e64 v46, 0, v46, s[78:79]
	v_cndmask_b32_e64 v47, 0, v47, s[50:51]
	v_cvt_pk_bf16_f32 v64, v32, v33
	v_cvt_pk_bf16_f32 v65, v34, v35
	v_cvt_pk_bf16_f32 v66, v36, v37
	v_cvt_pk_bf16_f32 v67, v38, v39
	v_cvt_pk_bf16_f32 v68, v40, v41
	v_cvt_pk_bf16_f32 v69, v42, v43
	v_cvt_pk_bf16_f32 v70, v44, v45
	v_cvt_pk_bf16_f32 v71, v46, v47
	v_pk_add_f32 v[232:233], v[232:233], v[32:33]
	v_pk_add_f32 v[232:233], v[232:233], v[34:35]
	v_pk_add_f32 v[232:233], v[232:233], v[36:37]
	v_pk_add_f32 v[232:233], v[232:233], v[38:39]
	v_pk_add_f32 v[232:233], v[232:233], v[40:41]
	v_pk_add_f32 v[232:233], v[232:233], v[42:43]
	v_pk_add_f32 v[232:233], v[232:233], v[44:45]
	v_pk_add_f32 v[232:233], v[232:233], v[46:47]
	v_mov_b32_e32 v115, v229
	ds_read2_b32 v[32:33], v115 offset0:0 offset1:1
	ds_read2_b32 v[34:35], v115 offset0:2 offset1:3
	ds_read2_b32 v[36:37], v115 offset0:8 offset1:9
	ds_read2_b32 v[38:39], v115 offset0:10 offset1:11
	ds_read2_b32 v[40:41], v115 offset0:16 offset1:17
	ds_read2_b32 v[42:43], v115 offset0:18 offset1:19
	ds_read2_b32 v[44:45], v115 offset0:24 offset1:25
	ds_read2_b32 v[46:47], v115 offset0:26 offset1:27
	v_mfma_f32_32x32x16_bf16 v[0:15], v[64:67], v[72:75], v[0:15]
	v_mfma_f32_32x32x16_bf16 v[16:31], v[64:67], v[76:79], v[16:31]
	v_mfma_f32_32x32x16_bf16 v[0:15], v[68:71], v[220:223], v[0:15]
	v_mfma_f32_32x32x16_bf16 v[16:31], v[68:71], v[224:227], v[16:31]
	s_add_i32 s90, s76, -128
	v_add_u32_e32 v80, s90, v239
	v_add_u32_e32 v83, s90, v240
	v_add_u32_e32 v99, s90, v241
	v_add_u32_e32 v253, s90, v242
	v_add_u32_e32 v254, s90, v101
	v_add_u32_e32 v255, s90, v150
	v_med3_i32 v80, v80, 0, s99
	v_med3_i32 v83, v83, 0, s99
	v_med3_i32 v99, v99, 0, s99
	v_med3_i32 v253, v253, 0, s99
	v_med3_i32 v254, v254, 0, s99
	v_med3_i32 v255, v255, 0, s99
	v_mad_u32_u24 v80, v80, s100, v252
	v_mad_u32_u24 v83, v83, s100, v252
	v_mad_u32_u24 v99, v99, s100, v252
	v_mad_u32_u24 v253, v253, s100, v252
	v_mad_u32_u24 v254, v254, s100, v153
	v_mad_u32_u24 v255, v255, s100, v153
	global_load_dwordx4 v[156:159], v80, s[82:83]
	global_load_dwordx4 v[160:163], v83, s[82:83]
	global_load_dwordx4 v[164:167], v99, s[82:83]
	global_load_dwordx4 v[168:171], v253, s[82:83]
	global_load_dwordx4 v[172:175], v254, s[82:83] offset:768
	global_load_dwordx4 v[176:179], v255, s[82:83] offset:768
	global_load_dwordx4 v[180:183], v254, s[82:83] offset:832
	global_load_dwordx4 v[184:187], v255, s[82:83] offset:832
	ds_read_b64_tr_b16 v[72:73], v231
	ds_read_b64_tr_b16 v[74:75], v231 offset:512
	ds_read_b64_tr_b16 v[76:77], v231 offset:2048
	ds_read_b64_tr_b16 v[78:79], v231 offset:2560
	ds_read_b64_tr_b16 v[220:221], v231 offset:1024
	ds_read_b64_tr_b16 v[222:223], v231 offset:1536
	ds_read_b64_tr_b16 v[224:225], v231 offset:3072
	ds_read_b64_tr_b16 v[226:227], v231 offset:3584
	v_exp_f32_e32 v188, v188
	v_exp_f32_e32 v189, v189
	v_exp_f32_e32 v190, v190
	v_exp_f32_e32 v191, v191
	s_waitcnt vmcnt(8)
	ds_write_b128 v247, v[116:119]
	ds_write_b128 v247, v[120:123] offset:1024
	ds_write_b128 v247, v[124:127] offset:2048
	ds_write_b128 v247, v[128:131] offset:3072
	ds_read_b128 v[116:119], v248
	ds_read_b128 v[120:123], v249
	ds_read_b128 v[124:127], v250
	ds_read_b128 v[128:131], v251
	ds_write_b128 v112, v[132:135]
	ds_write_b128 v112, v[136:139] offset:1024
	ds_write_b128 v112, v[140:143] offset:2048
	ds_write_b128 v112, v[144:147] offset:3072
	v_exp_f32_e32 v192, v192
	v_exp_f32_e32 v193, v193
	v_exp_f32_e32 v194, v194
	v_exp_f32_e32 v195, v195
	s_waitcnt lgkmcnt(4)
	v_mfma_f32_32x32x16_bf16 v[32:47], v[116:119], v[48:51], v[32:47]
	v_exp_f32_e32 v196, v196
	v_exp_f32_e32 v197, v197
	v_mfma_f32_32x32x16_bf16 v[32:47], v[120:123], v[52:55], v[32:47]
	v_exp_f32_e32 v198, v198
	v_exp_f32_e32 v199, v199
	v_mfma_f32_32x32x16_bf16 v[32:47], v[124:127], v[56:59], v[32:47]
	v_exp_f32_e32 v200, v200
	v_exp_f32_e32 v201, v201
	v_mfma_f32_32x32x16_bf16 v[32:47], v[128:131], v[60:63], v[32:47]
	v_exp_f32_e32 v202, v202
	v_exp_f32_e32 v203, v203
	s_add_i32 s90, s76, 544
	v_add_u32_e32 v84, s90, v107
	v_add_u32_e32 v85, 0, v84
	v_add_u32_e32 v86, 1, v84
	v_add_u32_e32 v87, 2, v84
	v_add_u32_e32 v88, 3, v84
	v_cmp_gt_u32_e64 s[30:31], s98, v85
	v_cmp_gt_u32_e64 s[36:37], s98, v86
	v_cmp_gt_u32_e64 s[78:79], s98, v87
	v_cmp_gt_u32_e64 s[50:51], s98, v88
	v_cndmask_b32_e64 v188, 0, v188, s[30:31]
	v_add_u32_e32 v85, 8, v84
	v_cmp_gt_u32_e64 s[30:31], s98, v85
	v_cndmask_b32_e64 v189, 0, v189, s[36:37]
	v_add_u32_e32 v86, 9, v84
	v_cmp_gt_u32_e64 s[36:37], s98, v86
	v_cndmask_b32_e64 v190, 0, v190, s[78:79]
	v_add_u32_e32 v87, 10, v84
	v_cmp_gt_u32_e64 s[78:79], s98, v87
	v_cndmask_b32_e64 v191, 0, v191, s[50:51]
	v_add_u32_e32 v88, 11, v84
	v_cmp_gt_u32_e64 s[50:51], s98, v88
	v_cndmask_b32_e64 v192, 0, v192, s[30:31]
	v_add_u32_e32 v85, 16, v84
	v_cmp_gt_u32_e64 s[30:31], s98, v85
	v_cndmask_b32_e64 v193, 0, v193, s[36:37]
	v_add_u32_e32 v86, 17, v84
	v_cmp_gt_u32_e64 s[36:37], s98, v86
	v_cndmask_b32_e64 v194, 0, v194, s[78:79]
	v_add_u32_e32 v87, 18, v84
	v_cmp_gt_u32_e64 s[78:79], s98, v87
	v_cndmask_b32_e64 v195, 0, v195, s[50:51]
	v_add_u32_e32 v88, 19, v84
	v_cmp_gt_u32_e64 s[50:51], s98, v88
	v_cndmask_b32_e64 v196, 0, v196, s[30:31]
	v_add_u32_e32 v85, 24, v84
	v_cmp_gt_u32_e64 s[30:31], s98, v85
	v_cndmask_b32_e64 v197, 0, v197, s[36:37]
	v_add_u32_e32 v86, 25, v84
	v_cmp_gt_u32_e64 s[36:37], s98, v86
	v_cndmask_b32_e64 v198, 0, v198, s[78:79]
	v_add_u32_e32 v87, 26, v84
	v_cmp_gt_u32_e64 s[78:79], s98, v87
	v_cndmask_b32_e64 v199, 0, v199, s[50:51]
	v_add_u32_e32 v88, 27, v84
	v_cmp_gt_u32_e64 s[50:51], s98, v88
	v_nop
	v_cndmask_b32_e64 v200, 0, v200, s[30:31]
	v_cndmask_b32_e64 v201, 0, v201, s[36:37]
	v_cndmask_b32_e64 v202, 0, v202, s[78:79]
	v_cndmask_b32_e64 v203, 0, v203, s[50:51]
	v_cvt_pk_bf16_f32 v64, v188, v189
	v_cvt_pk_bf16_f32 v65, v190, v191
	v_cvt_pk_bf16_f32 v66, v192, v193
	v_cvt_pk_bf16_f32 v67, v194, v195
	v_cvt_pk_bf16_f32 v68, v196, v197
	v_cvt_pk_bf16_f32 v69, v198, v199
	v_cvt_pk_bf16_f32 v70, v200, v201
	v_cvt_pk_bf16_f32 v71, v202, v203
	v_pk_add_f32 v[232:233], v[232:233], v[188:189]
	v_pk_add_f32 v[232:233], v[232:233], v[190:191]
	v_pk_add_f32 v[232:233], v[232:233], v[192:193]
	v_pk_add_f32 v[232:233], v[232:233], v[194:195]
	v_pk_add_f32 v[232:233], v[232:233], v[196:197]
	v_pk_add_f32 v[232:233], v[232:233], v[198:199]
	v_pk_add_f32 v[232:233], v[232:233], v[200:201]
	v_pk_add_f32 v[232:233], v[232:233], v[202:203]
	ds_read2_b32 v[188:189], v115 offset0:32 offset1:33
	ds_read2_b32 v[190:191], v115 offset0:34 offset1:35
	ds_read2_b32 v[192:193], v115 offset0:40 offset1:41
	ds_read2_b32 v[194:195], v115 offset0:42 offset1:43
	ds_read2_b32 v[196:197], v115 offset0:48 offset1:49
	ds_read2_b32 v[198:199], v115 offset0:50 offset1:51
	ds_read2_b32 v[200:201], v115 offset0:56 offset1:57
	ds_read2_b32 v[202:203], v115 offset0:58 offset1:59
	v_mfma_f32_32x32x16_bf16 v[0:15], v[64:67], v[72:75], v[0:15]
	v_mfma_f32_32x32x16_bf16 v[16:31], v[64:67], v[76:79], v[16:31]
	v_mfma_f32_32x32x16_bf16 v[0:15], v[68:71], v[220:223], v[0:15]
	v_mfma_f32_32x32x16_bf16 v[16:31], v[68:71], v[224:227], v[16:31]
	s_add_i32 s90, s76, 0
	v_add_u32_e32 v80, s90, v239
	v_add_u32_e32 v83, s90, v240
	v_add_u32_e32 v99, s90, v241
	v_add_u32_e32 v253, s90, v242
	v_add_u32_e32 v254, s90, v101
	v_add_u32_e32 v255, s90, v150
	v_med3_i32 v80, v80, 0, s99
	v_med3_i32 v83, v83, 0, s99
	v_med3_i32 v99, v99, 0, s99
	v_med3_i32 v253, v253, 0, s99
	v_med3_i32 v254, v254, 0, s99
	v_med3_i32 v255, v255, 0, s99
	v_mad_u32_u24 v80, v80, s100, v252
	v_mad_u32_u24 v83, v83, s100, v252
	v_mad_u32_u24 v99, v99, s100, v252
	v_mad_u32_u24 v253, v253, s100, v252
	v_mad_u32_u24 v254, v254, s100, v153
	v_mad_u32_u24 v255, v255, s100, v153
	global_load_dwordx4 v[116:119], v80, s[82:83]
	global_load_dwordx4 v[120:123], v83, s[82:83]
	global_load_dwordx4 v[124:127], v99, s[82:83]
	global_load_dwordx4 v[128:131], v253, s[82:83]
	global_load_dwordx4 v[132:135], v254, s[82:83] offset:768
	global_load_dwordx4 v[136:139], v255, s[82:83] offset:768
	global_load_dwordx4 v[140:143], v254, s[82:83] offset:832
	global_load_dwordx4 v[144:147], v255, s[82:83] offset:832
	ds_read_b64_tr_b16 v[72:73], v231
	ds_read_b64_tr_b16 v[74:75], v231 offset:512
	ds_read_b64_tr_b16 v[76:77], v231 offset:2048
	ds_read_b64_tr_b16 v[78:79], v231 offset:2560
	ds_read_b64_tr_b16 v[220:221], v231 offset:1024
	ds_read_b64_tr_b16 v[222:223], v231 offset:1536
	ds_read_b64_tr_b16 v[224:225], v231 offset:3072
	ds_read_b64_tr_b16 v[226:227], v231 offset:3584
	v_exp_f32_e32 v32, v32
	v_exp_f32_e32 v33, v33
	v_exp_f32_e32 v34, v34
	v_exp_f32_e32 v35, v35
	s_waitcnt vmcnt(8)
	ds_write_b128 v247, v[156:159]
	ds_write_b128 v247, v[160:163] offset:1024
	ds_write_b128 v247, v[164:167] offset:2048
	ds_write_b128 v247, v[168:171] offset:3072
	ds_read_b128 v[156:159], v248
	ds_read_b128 v[160:163], v249
	ds_read_b128 v[164:167], v250
	ds_read_b128 v[168:171], v251
	ds_write_b128 v112, v[172:175]
	ds_write_b128 v112, v[176:179] offset:1024
	ds_write_b128 v112, v[180:183] offset:2048
	ds_write_b128 v112, v[184:187] offset:3072
	v_exp_f32_e32 v36, v36
	v_exp_f32_e32 v37, v37
	v_exp_f32_e32 v38, v38
	v_exp_f32_e32 v39, v39
	s_waitcnt lgkmcnt(4)
	v_mfma_f32_32x32x16_bf16 v[188:203], v[156:159], v[48:51], v[188:203]
	v_exp_f32_e32 v40, v40
	v_exp_f32_e32 v41, v41
	v_mfma_f32_32x32x16_bf16 v[188:203], v[160:163], v[52:55], v[188:203]
	v_exp_f32_e32 v42, v42
	v_exp_f32_e32 v43, v43
	v_mfma_f32_32x32x16_bf16 v[188:203], v[164:167], v[56:59], v[188:203]
	v_exp_f32_e32 v44, v44
	v_exp_f32_e32 v45, v45
	v_mfma_f32_32x32x16_bf16 v[188:203], v[168:171], v[60:63], v[188:203]
	v_exp_f32_e32 v46, v46
	v_exp_f32_e32 v47, v47
	s_add_i32 s90, s76, -256
	v_lshlrev_b32_e32 v84, 2, v107
	v_add_u32_e32 v84, s90, v84
	v_add_u32_e32 v85, 0, v84
	v_add_u32_e32 v86, 4, v84
	v_add_u32_e32 v87, 8, v84
	v_add_u32_e32 v88, 12, v84
	v_cmp_gt_u32_e64 s[30:31], s98, v85
	v_cmp_gt_u32_e64 s[36:37], s98, v86
	v_cmp_gt_u32_e64 s[78:79], s98, v87
	v_cmp_gt_u32_e64 s[50:51], s98, v88
	v_cndmask_b32_e64 v32, 0, v32, s[30:31]
	v_add_u32_e32 v85, 32, v84
	v_cmp_gt_u32_e64 s[30:31], s98, v85
	v_cndmask_b32_e64 v33, 0, v33, s[36:37]
	v_add_u32_e32 v86, 36, v84
	v_cmp_gt_u32_e64 s[36:37], s98, v86
	v_cndmask_b32_e64 v34, 0, v34, s[78:79]
	v_add_u32_e32 v87, 40, v84
	v_cmp_gt_u32_e64 s[78:79], s98, v87
	v_cndmask_b32_e64 v35, 0, v35, s[50:51]
	v_add_u32_e32 v88, 44, v84
	v_cmp_gt_u32_e64 s[50:51], s98, v88
	v_cndmask_b32_e64 v36, 0, v36, s[30:31]
	v_add_u32_e32 v85, 64, v84
	v_cmp_gt_u32_e64 s[30:31], s98, v85
	v_cndmask_b32_e64 v37, 0, v37, s[36:37]
	v_add_u32_e32 v86, 68, v84
	v_cmp_gt_u32_e64 s[36:37], s98, v86
	v_cndmask_b32_e64 v38, 0, v38, s[78:79]
	v_add_u32_e32 v87, 72, v84
	v_cmp_gt_u32_e64 s[78:79], s98, v87
	v_cndmask_b32_e64 v39, 0, v39, s[50:51]
	v_add_u32_e32 v88, 76, v84
	v_cmp_gt_u32_e64 s[50:51], s98, v88
	v_cndmask_b32_e64 v40, 0, v40, s[30:31]
	v_add_u32_e32 v85, 96, v84
	v_cmp_gt_u32_e64 s[30:31], s98, v85
	v_cndmask_b32_e64 v41, 0, v41, s[36:37]
	v_add_u32_e32 v86, 100, v84
	v_cmp_gt_u32_e64 s[36:37], s98, v86
	v_cndmask_b32_e64 v42, 0, v42, s[78:79]
	v_add_u32_e32 v87, 104, v84
	v_cmp_gt_u32_e64 s[78:79], s98, v87
	v_cndmask_b32_e64 v43, 0, v43, s[50:51]
	v_add_u32_e32 v88, 108, v84
	v_cmp_gt_u32_e64 s[50:51], s98, v88
	v_nop
	v_cndmask_b32_e64 v44, 0, v44, s[30:31]
	v_cndmask_b32_e64 v45, 0, v45, s[36:37]
	v_cndmask_b32_e64 v46, 0, v46, s[78:79]
	v_cndmask_b32_e64 v47, 0, v47, s[50:51]
	v_cvt_pk_bf16_f32 v64, v32, v33
	v_cvt_pk_bf16_f32 v65, v34, v35
	v_cvt_pk_bf16_f32 v66, v36, v37
	v_cvt_pk_bf16_f32 v67, v38, v39
	v_cvt_pk_bf16_f32 v68, v40, v41
	v_cvt_pk_bf16_f32 v69, v42, v43
	v_cvt_pk_bf16_f32 v70, v44, v45
	v_cvt_pk_bf16_f32 v71, v46, v47
	v_pk_add_f32 v[232:233], v[232:233], v[32:33]
	v_pk_add_f32 v[232:233], v[232:233], v[34:35]
	v_pk_add_f32 v[232:233], v[232:233], v[36:37]
	v_pk_add_f32 v[232:233], v[232:233], v[38:39]
	v_pk_add_f32 v[232:233], v[232:233], v[40:41]
	v_pk_add_f32 v[232:233], v[232:233], v[42:43]
	v_pk_add_f32 v[232:233], v[232:233], v[44:45]
	v_pk_add_f32 v[232:233], v[232:233], v[46:47]
	ds_read2_b32 v[32:33], v115 offset0:64 offset1:65
	ds_read2_b32 v[34:35], v115 offset0:66 offset1:67
	ds_read2_b32 v[36:37], v115 offset0:72 offset1:73
	ds_read2_b32 v[38:39], v115 offset0:74 offset1:75
	ds_read2_b32 v[40:41], v115 offset0:80 offset1:81
	ds_read2_b32 v[42:43], v115 offset0:82 offset1:83
	ds_read2_b32 v[44:45], v115 offset0:88 offset1:89
	ds_read2_b32 v[46:47], v115 offset0:90 offset1:91
	v_mfma_f32_32x32x16_bf16 v[0:15], v[64:67], v[72:75], v[0:15]
	v_mfma_f32_32x32x16_bf16 v[16:31], v[64:67], v[76:79], v[16:31]
	v_mfma_f32_32x32x16_bf16 v[0:15], v[68:71], v[220:223], v[0:15]
	v_mfma_f32_32x32x16_bf16 v[16:31], v[68:71], v[224:227], v[16:31]
	s_add_i32 s90, s76, 128
	v_add_u32_e32 v80, s90, v239
	v_add_u32_e32 v83, s90, v240
	v_add_u32_e32 v99, s90, v241
	v_add_u32_e32 v253, s90, v242
	v_add_u32_e32 v254, s90, v101
	v_add_u32_e32 v255, s90, v150
	v_med3_i32 v80, v80, 0, s99
	v_med3_i32 v83, v83, 0, s99
	v_med3_i32 v99, v99, 0, s99
	v_med3_i32 v253, v253, 0, s99
	v_med3_i32 v254, v254, 0, s99
	v_med3_i32 v255, v255, 0, s99
	v_mad_u32_u24 v80, v80, s100, v252
	v_mad_u32_u24 v83, v83, s100, v252
	v_mad_u32_u24 v99, v99, s100, v252
	v_mad_u32_u24 v253, v253, s100, v252
	v_mad_u32_u24 v254, v254, s100, v153
	v_mad_u32_u24 v255, v255, s100, v153
	global_load_dwordx4 v[156:159], v80, s[82:83]
	global_load_dwordx4 v[160:163], v83, s[82:83]
	global_load_dwordx4 v[164:167], v99, s[82:83]
	global_load_dwordx4 v[168:171], v253, s[82:83]
	global_load_dwordx4 v[172:175], v254, s[82:83] offset:768
	global_load_dwordx4 v[176:179], v255, s[82:83] offset:768
	global_load_dwordx4 v[180:183], v254, s[82:83] offset:832
	global_load_dwordx4 v[184:187], v255, s[82:83] offset:832
	ds_read_b64_tr_b16 v[72:73], v231
	ds_read_b64_tr_b16 v[74:75], v231 offset:512
	ds_read_b64_tr_b16 v[76:77], v231 offset:2048
	ds_read_b64_tr_b16 v[78:79], v231 offset:2560
	ds_read_b64_tr_b16 v[220:221], v231 offset:1024
	ds_read_b64_tr_b16 v[222:223], v231 offset:1536
	ds_read_b64_tr_b16 v[224:225], v231 offset:3072
	ds_read_b64_tr_b16 v[226:227], v231 offset:3584
	v_exp_f32_e32 v188, v188
	v_exp_f32_e32 v189, v189
	v_exp_f32_e32 v190, v190
	v_exp_f32_e32 v191, v191
	s_waitcnt vmcnt(8)
	ds_write_b128 v247, v[116:119]
	ds_write_b128 v247, v[120:123] offset:1024
	ds_write_b128 v247, v[124:127] offset:2048
	ds_write_b128 v247, v[128:131] offset:3072
	ds_read_b128 v[116:119], v248
	ds_read_b128 v[120:123], v249
	ds_read_b128 v[124:127], v250
	ds_read_b128 v[128:131], v251
	ds_write_b128 v112, v[132:135]
	ds_write_b128 v112, v[136:139] offset:1024
	ds_write_b128 v112, v[140:143] offset:2048
	ds_write_b128 v112, v[144:147] offset:3072
	v_exp_f32_e32 v192, v192
	v_exp_f32_e32 v193, v193
	v_exp_f32_e32 v194, v194
	v_exp_f32_e32 v195, v195
	s_waitcnt lgkmcnt(4)
	v_mfma_f32_32x32x16_bf16 v[32:47], v[116:119], v[48:51], v[32:47]
	v_exp_f32_e32 v196, v196
	v_exp_f32_e32 v197, v197
	v_mfma_f32_32x32x16_bf16 v[32:47], v[120:123], v[52:55], v[32:47]
	v_exp_f32_e32 v198, v198
	v_exp_f32_e32 v199, v199
	v_mfma_f32_32x32x16_bf16 v[32:47], v[124:127], v[56:59], v[32:47]
	v_exp_f32_e32 v200, v200
	v_exp_f32_e32 v201, v201
	v_mfma_f32_32x32x16_bf16 v[32:47], v[128:131], v[60:63], v[32:47]
	v_exp_f32_e32 v202, v202
	v_exp_f32_e32 v203, v203
	s_add_i32 s90, s76, -128
	v_lshlrev_b32_e32 v84, 2, v107
	v_add_u32_e32 v84, s90, v84
	v_add_u32_e32 v85, 0, v84
	v_add_u32_e32 v86, 4, v84
	v_add_u32_e32 v87, 8, v84
	v_add_u32_e32 v88, 12, v84
	v_cmp_gt_u32_e64 s[30:31], s98, v85
	v_cmp_gt_u32_e64 s[36:37], s98, v86
	v_cmp_gt_u32_e64 s[78:79], s98, v87
	v_cmp_gt_u32_e64 s[50:51], s98, v88
	v_cndmask_b32_e64 v188, 0, v188, s[30:31]
	v_add_u32_e32 v85, 32, v84
	v_cmp_gt_u32_e64 s[30:31], s98, v85
	v_cndmask_b32_e64 v189, 0, v189, s[36:37]
	v_add_u32_e32 v86, 36, v84
	v_cmp_gt_u32_e64 s[36:37], s98, v86
	v_cndmask_b32_e64 v190, 0, v190, s[78:79]
	v_add_u32_e32 v87, 40, v84
	v_cmp_gt_u32_e64 s[78:79], s98, v87
	v_cndmask_b32_e64 v191, 0, v191, s[50:51]
	v_add_u32_e32 v88, 44, v84
	v_cmp_gt_u32_e64 s[50:51], s98, v88
	v_cndmask_b32_e64 v192, 0, v192, s[30:31]
	v_add_u32_e32 v85, 64, v84
	v_cmp_gt_u32_e64 s[30:31], s98, v85
	v_cndmask_b32_e64 v193, 0, v193, s[36:37]
	v_add_u32_e32 v86, 68, v84
	v_cmp_gt_u32_e64 s[36:37], s98, v86
	v_cndmask_b32_e64 v194, 0, v194, s[78:79]
	v_add_u32_e32 v87, 72, v84
	v_cmp_gt_u32_e64 s[78:79], s98, v87
	v_cndmask_b32_e64 v195, 0, v195, s[50:51]
	v_add_u32_e32 v88, 76, v84
	v_cmp_gt_u32_e64 s[50:51], s98, v88
	v_cndmask_b32_e64 v196, 0, v196, s[30:31]
	v_add_u32_e32 v85, 96, v84
	v_cmp_gt_u32_e64 s[30:31], s98, v85
	v_cndmask_b32_e64 v197, 0, v197, s[36:37]
	v_add_u32_e32 v86, 100, v84
	v_cmp_gt_u32_e64 s[36:37], s98, v86
	v_cndmask_b32_e64 v198, 0, v198, s[78:79]
	v_add_u32_e32 v87, 104, v84
	v_cmp_gt_u32_e64 s[78:79], s98, v87
	v_cndmask_b32_e64 v199, 0, v199, s[50:51]
	v_add_u32_e32 v88, 108, v84
	v_cmp_gt_u32_e64 s[50:51], s98, v88
	v_nop
	v_cndmask_b32_e64 v200, 0, v200, s[30:31]
	v_cndmask_b32_e64 v201, 0, v201, s[36:37]
	v_cndmask_b32_e64 v202, 0, v202, s[78:79]
	v_cndmask_b32_e64 v203, 0, v203, s[50:51]
	v_cvt_pk_bf16_f32 v64, v188, v189
	v_cvt_pk_bf16_f32 v65, v190, v191
	v_cvt_pk_bf16_f32 v66, v192, v193
	v_cvt_pk_bf16_f32 v67, v194, v195
	v_cvt_pk_bf16_f32 v68, v196, v197
	v_cvt_pk_bf16_f32 v69, v198, v199
	v_cvt_pk_bf16_f32 v70, v200, v201
	v_cvt_pk_bf16_f32 v71, v202, v203
	v_pk_add_f32 v[232:233], v[232:233], v[188:189]
	v_pk_add_f32 v[232:233], v[232:233], v[190:191]
	v_pk_add_f32 v[232:233], v[232:233], v[192:193]
	v_pk_add_f32 v[232:233], v[232:233], v[194:195]
	v_pk_add_f32 v[232:233], v[232:233], v[196:197]
	v_pk_add_f32 v[232:233], v[232:233], v[198:199]
	v_pk_add_f32 v[232:233], v[232:233], v[200:201]
	v_pk_add_f32 v[232:233], v[232:233], v[202:203]
	ds_read2_b32 v[188:189], v115 offset0:96 offset1:97
	ds_read2_b32 v[190:191], v115 offset0:98 offset1:99
	ds_read2_b32 v[192:193], v115 offset0:104 offset1:105
	ds_read2_b32 v[194:195], v115 offset0:106 offset1:107
	ds_read2_b32 v[196:197], v115 offset0:112 offset1:113
	ds_read2_b32 v[198:199], v115 offset0:114 offset1:115
	ds_read2_b32 v[200:201], v115 offset0:120 offset1:121
	ds_read2_b32 v[202:203], v115 offset0:122 offset1:123
	v_mfma_f32_32x32x16_bf16 v[0:15], v[64:67], v[72:75], v[0:15]
	v_mfma_f32_32x32x16_bf16 v[16:31], v[64:67], v[76:79], v[16:31]
	v_mfma_f32_32x32x16_bf16 v[0:15], v[68:71], v[220:223], v[0:15]
	v_mfma_f32_32x32x16_bf16 v[16:31], v[68:71], v[224:227], v[16:31]
	s_add_i32 s90, s76, 256
	v_add_u32_e32 v80, s90, v239
	v_add_u32_e32 v83, s90, v240
	v_add_u32_e32 v99, s90, v241
	v_add_u32_e32 v253, s90, v242
	v_add_u32_e32 v254, s90, v101
	v_add_u32_e32 v255, s90, v150
	v_med3_i32 v80, v80, 0, s99
	v_med3_i32 v83, v83, 0, s99
	v_med3_i32 v99, v99, 0, s99
	v_med3_i32 v253, v253, 0, s99
	v_med3_i32 v254, v254, 0, s99
	v_med3_i32 v255, v255, 0, s99
	v_mad_u32_u24 v80, v80, s100, v252
	v_mad_u32_u24 v83, v83, s100, v252
	v_mad_u32_u24 v99, v99, s100, v252
	v_mad_u32_u24 v253, v253, s100, v252
	v_mad_u32_u24 v254, v254, s100, v153
	v_mad_u32_u24 v255, v255, s100, v153
	global_load_dwordx4 v[116:119], v80, s[82:83]
	global_load_dwordx4 v[120:123], v83, s[82:83]
	global_load_dwordx4 v[124:127], v99, s[82:83]
	global_load_dwordx4 v[128:131], v253, s[82:83]
	global_load_dwordx4 v[132:135], v254, s[82:83] offset:768
	global_load_dwordx4 v[136:139], v255, s[82:83] offset:768
	global_load_dwordx4 v[140:143], v254, s[82:83] offset:832
	global_load_dwordx4 v[144:147], v255, s[82:83] offset:832
	ds_read_b64_tr_b16 v[72:73], v231
	ds_read_b64_tr_b16 v[74:75], v231 offset:512
	ds_read_b64_tr_b16 v[76:77], v231 offset:2048
	ds_read_b64_tr_b16 v[78:79], v231 offset:2560
	ds_read_b64_tr_b16 v[220:221], v231 offset:1024
	ds_read_b64_tr_b16 v[222:223], v231 offset:1536
	ds_read_b64_tr_b16 v[224:225], v231 offset:3072
	ds_read_b64_tr_b16 v[226:227], v231 offset:3584
	v_exp_f32_e32 v32, v32
	v_exp_f32_e32 v33, v33
	v_exp_f32_e32 v34, v34
	v_exp_f32_e32 v35, v35
	s_waitcnt vmcnt(8)
	ds_write_b128 v247, v[156:159]
	ds_write_b128 v247, v[160:163] offset:1024
	ds_write_b128 v247, v[164:167] offset:2048
	ds_write_b128 v247, v[168:171] offset:3072
	ds_read_b128 v[156:159], v248
	ds_read_b128 v[160:163], v249
	ds_read_b128 v[164:167], v250
	ds_read_b128 v[168:171], v251
	ds_write_b128 v112, v[172:175]
	ds_write_b128 v112, v[176:179] offset:1024
	ds_write_b128 v112, v[180:183] offset:2048
	ds_write_b128 v112, v[184:187] offset:3072
	v_exp_f32_e32 v36, v36
	v_exp_f32_e32 v37, v37
	v_exp_f32_e32 v38, v38
	v_exp_f32_e32 v39, v39
	s_waitcnt lgkmcnt(4)
	v_mfma_f32_32x32x16_bf16 v[188:203], v[156:159], v[48:51], v[188:203]
	v_exp_f32_e32 v40, v40
	v_exp_f32_e32 v41, v41
	v_mfma_f32_32x32x16_bf16 v[188:203], v[160:163], v[52:55], v[188:203]
	v_exp_f32_e32 v42, v42
	v_exp_f32_e32 v43, v43
	v_mfma_f32_32x32x16_bf16 v[188:203], v[164:167], v[56:59], v[188:203]
	v_exp_f32_e32 v44, v44
	v_exp_f32_e32 v45, v45
	v_mfma_f32_32x32x16_bf16 v[188:203], v[168:171], v[60:63], v[188:203]
	v_exp_f32_e32 v46, v46
	v_exp_f32_e32 v47, v47
	s_add_i32 s90, s76, 0
	v_lshlrev_b32_e32 v84, 2, v107
	v_add_u32_e32 v84, s90, v84
	v_add_u32_e32 v85, 0, v84
	v_add_u32_e32 v86, 4, v84
	v_add_u32_e32 v87, 8, v84
	v_add_u32_e32 v88, 12, v84
	v_cmp_gt_u32_e64 s[30:31], s98, v85
	v_cmp_gt_u32_e64 s[36:37], s98, v86
	v_cmp_gt_u32_e64 s[78:79], s98, v87
	v_cmp_gt_u32_e64 s[50:51], s98, v88
	v_cndmask_b32_e64 v32, 0, v32, s[30:31]
	v_add_u32_e32 v85, 32, v84
	v_cmp_gt_u32_e64 s[30:31], s98, v85
	v_cndmask_b32_e64 v33, 0, v33, s[36:37]
	v_add_u32_e32 v86, 36, v84
	v_cmp_gt_u32_e64 s[36:37], s98, v86
	v_cndmask_b32_e64 v34, 0, v34, s[78:79]
	v_add_u32_e32 v87, 40, v84
	v_cmp_gt_u32_e64 s[78:79], s98, v87
	v_cndmask_b32_e64 v35, 0, v35, s[50:51]
	v_add_u32_e32 v88, 44, v84
	v_cmp_gt_u32_e64 s[50:51], s98, v88
	v_cndmask_b32_e64 v36, 0, v36, s[30:31]
	v_add_u32_e32 v85, 64, v84
	v_cmp_gt_u32_e64 s[30:31], s98, v85
	v_cndmask_b32_e64 v37, 0, v37, s[36:37]
	v_add_u32_e32 v86, 68, v84
	v_cmp_gt_u32_e64 s[36:37], s98, v86
	v_cndmask_b32_e64 v38, 0, v38, s[78:79]
	v_add_u32_e32 v87, 72, v84
	v_cmp_gt_u32_e64 s[78:79], s98, v87
	v_cndmask_b32_e64 v39, 0, v39, s[50:51]
	v_add_u32_e32 v88, 76, v84
	v_cmp_gt_u32_e64 s[50:51], s98, v88
	v_cndmask_b32_e64 v40, 0, v40, s[30:31]
	v_add_u32_e32 v85, 96, v84
	v_cmp_gt_u32_e64 s[30:31], s98, v85
	v_cndmask_b32_e64 v41, 0, v41, s[36:37]
	v_add_u32_e32 v86, 100, v84
	v_cmp_gt_u32_e64 s[36:37], s98, v86
	v_cndmask_b32_e64 v42, 0, v42, s[78:79]
	v_add_u32_e32 v87, 104, v84
	v_cmp_gt_u32_e64 s[78:79], s98, v87
	v_cndmask_b32_e64 v43, 0, v43, s[50:51]
	v_add_u32_e32 v88, 108, v84
	v_cmp_gt_u32_e64 s[50:51], s98, v88
	v_nop
	v_cndmask_b32_e64 v44, 0, v44, s[30:31]
	v_cndmask_b32_e64 v45, 0, v45, s[36:37]
	v_cndmask_b32_e64 v46, 0, v46, s[78:79]
	v_cndmask_b32_e64 v47, 0, v47, s[50:51]
	v_cvt_pk_bf16_f32 v64, v32, v33
	v_cvt_pk_bf16_f32 v65, v34, v35
	v_cvt_pk_bf16_f32 v66, v36, v37
	v_cvt_pk_bf16_f32 v67, v38, v39
	v_cvt_pk_bf16_f32 v68, v40, v41
	v_cvt_pk_bf16_f32 v69, v42, v43
	v_cvt_pk_bf16_f32 v70, v44, v45
	v_cvt_pk_bf16_f32 v71, v46, v47
	v_pk_add_f32 v[232:233], v[232:233], v[32:33]
	v_pk_add_f32 v[232:233], v[232:233], v[34:35]
	v_pk_add_f32 v[232:233], v[232:233], v[36:37]
	v_pk_add_f32 v[232:233], v[232:233], v[38:39]
	v_pk_add_f32 v[232:233], v[232:233], v[40:41]
	v_pk_add_f32 v[232:233], v[232:233], v[42:43]
	v_pk_add_f32 v[232:233], v[232:233], v[44:45]
	v_pk_add_f32 v[232:233], v[232:233], v[46:47]
	ds_read2_b32 v[32:33], v115 offset0:128 offset1:129
	ds_read2_b32 v[34:35], v115 offset0:130 offset1:131
	ds_read2_b32 v[36:37], v115 offset0:136 offset1:137
	ds_read2_b32 v[38:39], v115 offset0:138 offset1:139
	ds_read2_b32 v[40:41], v115 offset0:144 offset1:145
	ds_read2_b32 v[42:43], v115 offset0:146 offset1:147
	ds_read2_b32 v[44:45], v115 offset0:152 offset1:153
	ds_read2_b32 v[46:47], v115 offset0:154 offset1:155
	v_mfma_f32_32x32x16_bf16 v[0:15], v[64:67], v[72:75], v[0:15]
	v_mfma_f32_32x32x16_bf16 v[16:31], v[64:67], v[76:79], v[16:31]
	v_mfma_f32_32x32x16_bf16 v[0:15], v[68:71], v[220:223], v[0:15]
	v_mfma_f32_32x32x16_bf16 v[16:31], v[68:71], v[224:227], v[16:31]
	s_add_i32 s90, s76, 384
	v_add_u32_e32 v80, s90, v239
	v_add_u32_e32 v83, s90, v240
	v_add_u32_e32 v99, s90, v241
	v_add_u32_e32 v253, s90, v242
	v_add_u32_e32 v254, s90, v101
	v_add_u32_e32 v255, s90, v150
	v_med3_i32 v80, v80, 0, s99
	v_med3_i32 v83, v83, 0, s99
	v_med3_i32 v99, v99, 0, s99
	v_med3_i32 v253, v253, 0, s99
	v_med3_i32 v254, v254, 0, s99
	v_med3_i32 v255, v255, 0, s99
	v_mad_u32_u24 v80, v80, s100, v252
	v_mad_u32_u24 v83, v83, s100, v252
	v_mad_u32_u24 v99, v99, s100, v252
	v_mad_u32_u24 v253, v253, s100, v252
	v_mad_u32_u24 v254, v254, s100, v153
	v_mad_u32_u24 v255, v255, s100, v153
	global_load_dwordx4 v[156:159], v80, s[82:83]
	global_load_dwordx4 v[160:163], v83, s[82:83]
	global_load_dwordx4 v[164:167], v99, s[82:83]
	global_load_dwordx4 v[168:171], v253, s[82:83]
	global_load_dwordx4 v[172:175], v254, s[82:83] offset:768
	global_load_dwordx4 v[176:179], v255, s[82:83] offset:768
	global_load_dwordx4 v[180:183], v254, s[82:83] offset:832
	global_load_dwordx4 v[184:187], v255, s[82:83] offset:832
	ds_read_b64_tr_b16 v[72:73], v231
	ds_read_b64_tr_b16 v[74:75], v231 offset:512
	ds_read_b64_tr_b16 v[76:77], v231 offset:2048
	ds_read_b64_tr_b16 v[78:79], v231 offset:2560
	ds_read_b64_tr_b16 v[220:221], v231 offset:1024
	ds_read_b64_tr_b16 v[222:223], v231 offset:1536
	ds_read_b64_tr_b16 v[224:225], v231 offset:3072
	ds_read_b64_tr_b16 v[226:227], v231 offset:3584
	v_exp_f32_e32 v188, v188
	v_exp_f32_e32 v189, v189
	v_exp_f32_e32 v190, v190
	v_exp_f32_e32 v191, v191
	s_waitcnt vmcnt(8)
	ds_write_b128 v247, v[116:119]
	ds_write_b128 v247, v[120:123] offset:1024
	ds_write_b128 v247, v[124:127] offset:2048
	ds_write_b128 v247, v[128:131] offset:3072
	ds_read_b128 v[116:119], v248
	ds_read_b128 v[120:123], v249
	ds_read_b128 v[124:127], v250
	ds_read_b128 v[128:131], v251
	ds_write_b128 v112, v[132:135]
	ds_write_b128 v112, v[136:139] offset:1024
	ds_write_b128 v112, v[140:143] offset:2048
	ds_write_b128 v112, v[144:147] offset:3072
	v_exp_f32_e32 v192, v192
	v_exp_f32_e32 v193, v193
	v_exp_f32_e32 v194, v194
	v_exp_f32_e32 v195, v195
	s_waitcnt lgkmcnt(4)
	v_mfma_f32_32x32x16_bf16 v[32:47], v[116:119], v[48:51], v[32:47]
	v_exp_f32_e32 v196, v196
	v_exp_f32_e32 v197, v197
	v_mfma_f32_32x32x16_bf16 v[32:47], v[120:123], v[52:55], v[32:47]
	v_exp_f32_e32 v198, v198
	v_exp_f32_e32 v199, v199
	v_mfma_f32_32x32x16_bf16 v[32:47], v[124:127], v[56:59], v[32:47]
	v_exp_f32_e32 v200, v200
	v_exp_f32_e32 v201, v201
	v_mfma_f32_32x32x16_bf16 v[32:47], v[128:131], v[60:63], v[32:47]
	v_exp_f32_e32 v202, v202
	v_exp_f32_e32 v203, v203
	s_add_i32 s90, s76, 128
	v_lshlrev_b32_e32 v84, 2, v107
	v_add_u32_e32 v84, s90, v84
	v_add_u32_e32 v85, 0, v84
	v_add_u32_e32 v86, 4, v84
	v_add_u32_e32 v87, 8, v84
	v_add_u32_e32 v88, 12, v84
	v_cmp_gt_u32_e64 s[30:31], s98, v85
	v_cmp_gt_u32_e64 s[36:37], s98, v86
	v_cmp_gt_u32_e64 s[78:79], s98, v87
	v_cmp_gt_u32_e64 s[50:51], s98, v88
	v_cndmask_b32_e64 v188, 0, v188, s[30:31]
	v_add_u32_e32 v85, 32, v84
	v_cmp_gt_u32_e64 s[30:31], s98, v85
	v_cndmask_b32_e64 v189, 0, v189, s[36:37]
	v_add_u32_e32 v86, 36, v84
	v_cmp_gt_u32_e64 s[36:37], s98, v86
	v_cndmask_b32_e64 v190, 0, v190, s[78:79]
	v_add_u32_e32 v87, 40, v84
	v_cmp_gt_u32_e64 s[78:79], s98, v87
	v_cndmask_b32_e64 v191, 0, v191, s[50:51]
	v_add_u32_e32 v88, 44, v84
	v_cmp_gt_u32_e64 s[50:51], s98, v88
	v_cndmask_b32_e64 v192, 0, v192, s[30:31]
	v_add_u32_e32 v85, 64, v84
	v_cmp_gt_u32_e64 s[30:31], s98, v85
	v_cndmask_b32_e64 v193, 0, v193, s[36:37]
	v_add_u32_e32 v86, 68, v84
	v_cmp_gt_u32_e64 s[36:37], s98, v86
	v_cndmask_b32_e64 v194, 0, v194, s[78:79]
	v_add_u32_e32 v87, 72, v84
	v_cmp_gt_u32_e64 s[78:79], s98, v87
	v_cndmask_b32_e64 v195, 0, v195, s[50:51]
	v_add_u32_e32 v88, 76, v84
	v_cmp_gt_u32_e64 s[50:51], s98, v88
	v_cndmask_b32_e64 v196, 0, v196, s[30:31]
	v_add_u32_e32 v85, 96, v84
	v_cmp_gt_u32_e64 s[30:31], s98, v85
	v_cndmask_b32_e64 v197, 0, v197, s[36:37]
	v_add_u32_e32 v86, 100, v84
	v_cmp_gt_u32_e64 s[36:37], s98, v86
	v_cndmask_b32_e64 v198, 0, v198, s[78:79]
	v_add_u32_e32 v87, 104, v84
	v_cmp_gt_u32_e64 s[78:79], s98, v87
	v_cndmask_b32_e64 v199, 0, v199, s[50:51]
	v_add_u32_e32 v88, 108, v84
	v_cmp_gt_u32_e64 s[50:51], s98, v88
	v_nop
	v_cndmask_b32_e64 v200, 0, v200, s[30:31]
	v_cndmask_b32_e64 v201, 0, v201, s[36:37]
	v_cndmask_b32_e64 v202, 0, v202, s[78:79]
	v_cndmask_b32_e64 v203, 0, v203, s[50:51]
	v_cvt_pk_bf16_f32 v64, v188, v189
	v_cvt_pk_bf16_f32 v65, v190, v191
	v_cvt_pk_bf16_f32 v66, v192, v193
	v_cvt_pk_bf16_f32 v67, v194, v195
	v_cvt_pk_bf16_f32 v68, v196, v197
	v_cvt_pk_bf16_f32 v69, v198, v199
	v_cvt_pk_bf16_f32 v70, v200, v201
	v_cvt_pk_bf16_f32 v71, v202, v203
	v_pk_add_f32 v[232:233], v[232:233], v[188:189]
	v_pk_add_f32 v[232:233], v[232:233], v[190:191]
	v_pk_add_f32 v[232:233], v[232:233], v[192:193]
	v_pk_add_f32 v[232:233], v[232:233], v[194:195]
	v_pk_add_f32 v[232:233], v[232:233], v[196:197]
	v_pk_add_f32 v[232:233], v[232:233], v[198:199]
	v_pk_add_f32 v[232:233], v[232:233], v[200:201]
	v_pk_add_f32 v[232:233], v[232:233], v[202:203]
	ds_read2_b32 v[188:189], v115 offset0:160 offset1:161
	ds_read2_b32 v[190:191], v115 offset0:162 offset1:163
	ds_read2_b32 v[192:193], v115 offset0:168 offset1:169
	ds_read2_b32 v[194:195], v115 offset0:170 offset1:171
	ds_read2_b32 v[196:197], v115 offset0:176 offset1:177
	ds_read2_b32 v[198:199], v115 offset0:178 offset1:179
	ds_read2_b32 v[200:201], v115 offset0:184 offset1:185
	ds_read2_b32 v[202:203], v115 offset0:186 offset1:187
	v_mfma_f32_32x32x16_bf16 v[0:15], v[64:67], v[72:75], v[0:15]
	v_mfma_f32_32x32x16_bf16 v[16:31], v[64:67], v[76:79], v[16:31]
	v_mfma_f32_32x32x16_bf16 v[0:15], v[68:71], v[220:223], v[0:15]
	v_mfma_f32_32x32x16_bf16 v[16:31], v[68:71], v[224:227], v[16:31]
	s_add_i32 s90, s76, 512
	v_add_u32_e32 v80, s90, v239
	v_add_u32_e32 v83, s90, v240
	v_add_u32_e32 v99, s90, v241
	v_add_u32_e32 v253, s90, v242
	v_add_u32_e32 v254, s90, v101
	v_add_u32_e32 v255, s90, v150
	v_med3_i32 v80, v80, 0, s99
	v_med3_i32 v83, v83, 0, s99
	v_med3_i32 v99, v99, 0, s99
	v_med3_i32 v253, v253, 0, s99
	v_med3_i32 v254, v254, 0, s99
	v_med3_i32 v255, v255, 0, s99
	v_mad_u32_u24 v80, v80, s100, v252
	v_mad_u32_u24 v83, v83, s100, v252
	v_mad_u32_u24 v99, v99, s100, v252
	v_mad_u32_u24 v253, v253, s100, v252
	v_mad_u32_u24 v254, v254, s100, v153
	v_mad_u32_u24 v255, v255, s100, v153
	global_load_dwordx4 v[116:119], v80, s[82:83]
	global_load_dwordx4 v[120:123], v83, s[82:83]
	global_load_dwordx4 v[124:127], v99, s[82:83]
	global_load_dwordx4 v[128:131], v253, s[82:83]
	global_load_dwordx4 v[132:135], v254, s[82:83] offset:768
	global_load_dwordx4 v[136:139], v255, s[82:83] offset:768
	global_load_dwordx4 v[140:143], v254, s[82:83] offset:832
	global_load_dwordx4 v[144:147], v255, s[82:83] offset:832
	ds_read_b64_tr_b16 v[72:73], v231
	ds_read_b64_tr_b16 v[74:75], v231 offset:512
	ds_read_b64_tr_b16 v[76:77], v231 offset:2048
	ds_read_b64_tr_b16 v[78:79], v231 offset:2560
	ds_read_b64_tr_b16 v[220:221], v231 offset:1024
	ds_read_b64_tr_b16 v[222:223], v231 offset:1536
	ds_read_b64_tr_b16 v[224:225], v231 offset:3072
	ds_read_b64_tr_b16 v[226:227], v231 offset:3584
	v_exp_f32_e32 v32, v32
	v_exp_f32_e32 v33, v33
	v_exp_f32_e32 v34, v34
	v_exp_f32_e32 v35, v35
	s_waitcnt vmcnt(8)
	ds_write_b128 v247, v[156:159]
	ds_write_b128 v247, v[160:163] offset:1024
	ds_write_b128 v247, v[164:167] offset:2048
	ds_write_b128 v247, v[168:171] offset:3072
	ds_read_b128 v[156:159], v248
	ds_read_b128 v[160:163], v249
	ds_read_b128 v[164:167], v250
	ds_read_b128 v[168:171], v251
	ds_write_b128 v112, v[172:175]
	ds_write_b128 v112, v[176:179] offset:1024
	ds_write_b128 v112, v[180:183] offset:2048
	ds_write_b128 v112, v[184:187] offset:3072
	v_exp_f32_e32 v36, v36
	v_exp_f32_e32 v37, v37
	v_exp_f32_e32 v38, v38
	v_exp_f32_e32 v39, v39
	s_waitcnt lgkmcnt(4)
	v_mfma_f32_32x32x16_bf16 v[188:203], v[156:159], v[48:51], v[188:203]
	v_exp_f32_e32 v40, v40
	v_exp_f32_e32 v41, v41
	v_mfma_f32_32x32x16_bf16 v[188:203], v[160:163], v[52:55], v[188:203]
	v_exp_f32_e32 v42, v42
	v_exp_f32_e32 v43, v43
	v_mfma_f32_32x32x16_bf16 v[188:203], v[164:167], v[56:59], v[188:203]
	v_exp_f32_e32 v44, v44
	v_exp_f32_e32 v45, v45
	v_mfma_f32_32x32x16_bf16 v[188:203], v[168:171], v[60:63], v[188:203]
	v_exp_f32_e32 v46, v46
	v_exp_f32_e32 v47, v47
	s_add_i32 s90, s76, 256
	v_lshlrev_b32_e32 v84, 2, v107
	v_add_u32_e32 v84, s90, v84
	v_add_u32_e32 v85, 0, v84
	v_add_u32_e32 v86, 4, v84
	v_add_u32_e32 v87, 8, v84
	v_add_u32_e32 v88, 12, v84
	v_cmp_gt_u32_e64 s[30:31], s98, v85
	v_cmp_gt_u32_e64 s[36:37], s98, v86
	v_cmp_gt_u32_e64 s[78:79], s98, v87
	v_cmp_gt_u32_e64 s[50:51], s98, v88
	v_cndmask_b32_e64 v32, 0, v32, s[30:31]
	v_add_u32_e32 v85, 32, v84
	v_cmp_gt_u32_e64 s[30:31], s98, v85
	v_cndmask_b32_e64 v33, 0, v33, s[36:37]
	v_add_u32_e32 v86, 36, v84
	v_cmp_gt_u32_e64 s[36:37], s98, v86
	v_cndmask_b32_e64 v34, 0, v34, s[78:79]
	v_add_u32_e32 v87, 40, v84
	v_cmp_gt_u32_e64 s[78:79], s98, v87
	v_cndmask_b32_e64 v35, 0, v35, s[50:51]
	v_add_u32_e32 v88, 44, v84
	v_cmp_gt_u32_e64 s[50:51], s98, v88
	v_cndmask_b32_e64 v36, 0, v36, s[30:31]
	v_add_u32_e32 v85, 64, v84
	v_cmp_gt_u32_e64 s[30:31], s98, v85
	v_cndmask_b32_e64 v37, 0, v37, s[36:37]
	v_add_u32_e32 v86, 68, v84
	v_cmp_gt_u32_e64 s[36:37], s98, v86
	v_cndmask_b32_e64 v38, 0, v38, s[78:79]
	v_add_u32_e32 v87, 72, v84
	v_cmp_gt_u32_e64 s[78:79], s98, v87
	v_cndmask_b32_e64 v39, 0, v39, s[50:51]
	v_add_u32_e32 v88, 76, v84
	v_cmp_gt_u32_e64 s[50:51], s98, v88
	v_cndmask_b32_e64 v40, 0, v40, s[30:31]
	v_add_u32_e32 v85, 96, v84
	v_cmp_gt_u32_e64 s[30:31], s98, v85
	v_cndmask_b32_e64 v41, 0, v41, s[36:37]
	v_add_u32_e32 v86, 100, v84
	v_cmp_gt_u32_e64 s[36:37], s98, v86
	v_cndmask_b32_e64 v42, 0, v42, s[78:79]
	v_add_u32_e32 v87, 104, v84
	v_cmp_gt_u32_e64 s[78:79], s98, v87
	v_cndmask_b32_e64 v43, 0, v43, s[50:51]
	v_add_u32_e32 v88, 108, v84
	v_cmp_gt_u32_e64 s[50:51], s98, v88
	v_nop
	v_cndmask_b32_e64 v44, 0, v44, s[30:31]
	v_cndmask_b32_e64 v45, 0, v45, s[36:37]
	v_cndmask_b32_e64 v46, 0, v46, s[78:79]
	v_cndmask_b32_e64 v47, 0, v47, s[50:51]
	v_cvt_pk_bf16_f32 v64, v32, v33
	v_cvt_pk_bf16_f32 v65, v34, v35
	v_cvt_pk_bf16_f32 v66, v36, v37
	v_cvt_pk_bf16_f32 v67, v38, v39
	v_cvt_pk_bf16_f32 v68, v40, v41
	v_cvt_pk_bf16_f32 v69, v42, v43
	v_cvt_pk_bf16_f32 v70, v44, v45
	v_cvt_pk_bf16_f32 v71, v46, v47
	v_pk_add_f32 v[232:233], v[232:233], v[32:33]
	v_pk_add_f32 v[232:233], v[232:233], v[34:35]
	v_pk_add_f32 v[232:233], v[232:233], v[36:37]
	v_pk_add_f32 v[232:233], v[232:233], v[38:39]
	v_pk_add_f32 v[232:233], v[232:233], v[40:41]
	v_pk_add_f32 v[232:233], v[232:233], v[42:43]
	v_pk_add_f32 v[232:233], v[232:233], v[44:45]
	v_pk_add_f32 v[232:233], v[232:233], v[46:47]
	ds_read2_b32 v[32:33], v115 offset0:192 offset1:193
	ds_read2_b32 v[34:35], v115 offset0:194 offset1:195
	ds_read2_b32 v[36:37], v115 offset0:200 offset1:201
	ds_read2_b32 v[38:39], v115 offset0:202 offset1:203
	ds_read2_b32 v[40:41], v115 offset0:208 offset1:209
	ds_read2_b32 v[42:43], v115 offset0:210 offset1:211
	ds_read2_b32 v[44:45], v115 offset0:216 offset1:217
	ds_read2_b32 v[46:47], v115 offset0:218 offset1:219
	v_mfma_f32_32x32x16_bf16 v[0:15], v[64:67], v[72:75], v[0:15]
	v_mfma_f32_32x32x16_bf16 v[16:31], v[64:67], v[76:79], v[16:31]
	v_mfma_f32_32x32x16_bf16 v[0:15], v[68:71], v[220:223], v[0:15]
	v_mfma_f32_32x32x16_bf16 v[16:31], v[68:71], v[224:227], v[16:31]
	s_add_i32 s90, s76, 640
	v_add_u32_e32 v80, s90, v239
	v_add_u32_e32 v83, s90, v240
	v_add_u32_e32 v99, s90, v241
	v_add_u32_e32 v253, s90, v242
	v_add_u32_e32 v254, s90, v101
	v_add_u32_e32 v255, s90, v150
	v_med3_i32 v80, v80, 0, s99
	v_med3_i32 v83, v83, 0, s99
	v_med3_i32 v99, v99, 0, s99
	v_med3_i32 v253, v253, 0, s99
	v_med3_i32 v254, v254, 0, s99
	v_med3_i32 v255, v255, 0, s99
	v_mad_u32_u24 v80, v80, s100, v252
	v_mad_u32_u24 v83, v83, s100, v252
	v_mad_u32_u24 v99, v99, s100, v252
	v_mad_u32_u24 v253, v253, s100, v252
	v_mad_u32_u24 v254, v254, s100, v153
	v_mad_u32_u24 v255, v255, s100, v153
	global_load_dwordx4 v[156:159], v80, s[82:83]
	global_load_dwordx4 v[160:163], v83, s[82:83]
	global_load_dwordx4 v[164:167], v99, s[82:83]
	global_load_dwordx4 v[168:171], v253, s[82:83]
	global_load_dwordx4 v[172:175], v254, s[82:83] offset:768
	global_load_dwordx4 v[176:179], v255, s[82:83] offset:768
	global_load_dwordx4 v[180:183], v254, s[82:83] offset:832
	global_load_dwordx4 v[184:187], v255, s[82:83] offset:832
	ds_read_b64_tr_b16 v[72:73], v231
	ds_read_b64_tr_b16 v[74:75], v231 offset:512
	ds_read_b64_tr_b16 v[76:77], v231 offset:2048
	ds_read_b64_tr_b16 v[78:79], v231 offset:2560
	ds_read_b64_tr_b16 v[220:221], v231 offset:1024
	ds_read_b64_tr_b16 v[222:223], v231 offset:1536
	ds_read_b64_tr_b16 v[224:225], v231 offset:3072
	ds_read_b64_tr_b16 v[226:227], v231 offset:3584
	v_exp_f32_e32 v188, v188
	v_exp_f32_e32 v189, v189
	v_exp_f32_e32 v190, v190
	v_exp_f32_e32 v191, v191
	s_waitcnt vmcnt(8)
	ds_write_b128 v247, v[116:119]
	ds_write_b128 v247, v[120:123] offset:1024
	ds_write_b128 v247, v[124:127] offset:2048
	ds_write_b128 v247, v[128:131] offset:3072
	ds_read_b128 v[116:119], v248
	ds_read_b128 v[120:123], v249
	ds_read_b128 v[124:127], v250
	ds_read_b128 v[128:131], v251
	ds_write_b128 v112, v[132:135]
	ds_write_b128 v112, v[136:139] offset:1024
	ds_write_b128 v112, v[140:143] offset:2048
	ds_write_b128 v112, v[144:147] offset:3072
	v_exp_f32_e32 v192, v192
	v_exp_f32_e32 v193, v193
	v_exp_f32_e32 v194, v194
	v_exp_f32_e32 v195, v195
	s_waitcnt lgkmcnt(4)
	v_mfma_f32_32x32x16_bf16 v[32:47], v[116:119], v[48:51], v[32:47]
	v_exp_f32_e32 v196, v196
	v_exp_f32_e32 v197, v197
	v_mfma_f32_32x32x16_bf16 v[32:47], v[120:123], v[52:55], v[32:47]
	v_exp_f32_e32 v198, v198
	v_exp_f32_e32 v199, v199
	v_mfma_f32_32x32x16_bf16 v[32:47], v[124:127], v[56:59], v[32:47]
	v_exp_f32_e32 v200, v200
	v_exp_f32_e32 v201, v201
	v_mfma_f32_32x32x16_bf16 v[32:47], v[128:131], v[60:63], v[32:47]
	v_exp_f32_e32 v202, v202
	v_exp_f32_e32 v203, v203
	s_add_i32 s90, s76, 384
	v_lshlrev_b32_e32 v84, 2, v107
	v_add_u32_e32 v84, s90, v84
	v_add_u32_e32 v85, 0, v84
	v_add_u32_e32 v86, 4, v84
	v_add_u32_e32 v87, 8, v84
	v_add_u32_e32 v88, 12, v84
	v_cmp_gt_u32_e64 s[30:31], s98, v85
	v_cmp_gt_u32_e64 s[36:37], s98, v86
	v_cmp_gt_u32_e64 s[78:79], s98, v87
	v_cmp_gt_u32_e64 s[50:51], s98, v88
	v_cndmask_b32_e64 v188, 0, v188, s[30:31]
	v_add_u32_e32 v85, 32, v84
	v_cmp_gt_u32_e64 s[30:31], s98, v85
	v_cndmask_b32_e64 v189, 0, v189, s[36:37]
	v_add_u32_e32 v86, 36, v84
	v_cmp_gt_u32_e64 s[36:37], s98, v86
	v_cndmask_b32_e64 v190, 0, v190, s[78:79]
	v_add_u32_e32 v87, 40, v84
	v_cmp_gt_u32_e64 s[78:79], s98, v87
	v_cndmask_b32_e64 v191, 0, v191, s[50:51]
	v_add_u32_e32 v88, 44, v84
	v_cmp_gt_u32_e64 s[50:51], s98, v88
	v_cndmask_b32_e64 v192, 0, v192, s[30:31]
	v_add_u32_e32 v85, 64, v84
	v_cmp_gt_u32_e64 s[30:31], s98, v85
	v_cndmask_b32_e64 v193, 0, v193, s[36:37]
	v_add_u32_e32 v86, 68, v84
	v_cmp_gt_u32_e64 s[36:37], s98, v86
	v_cndmask_b32_e64 v194, 0, v194, s[78:79]
	v_add_u32_e32 v87, 72, v84
	v_cmp_gt_u32_e64 s[78:79], s98, v87
	v_cndmask_b32_e64 v195, 0, v195, s[50:51]
	v_add_u32_e32 v88, 76, v84
	v_cmp_gt_u32_e64 s[50:51], s98, v88
	v_cndmask_b32_e64 v196, 0, v196, s[30:31]
	v_add_u32_e32 v85, 96, v84
	v_cmp_gt_u32_e64 s[30:31], s98, v85
	v_cndmask_b32_e64 v197, 0, v197, s[36:37]
	v_add_u32_e32 v86, 100, v84
	v_cmp_gt_u32_e64 s[36:37], s98, v86
	v_cndmask_b32_e64 v198, 0, v198, s[78:79]
	v_add_u32_e32 v87, 104, v84
	v_cmp_gt_u32_e64 s[78:79], s98, v87
	v_cndmask_b32_e64 v199, 0, v199, s[50:51]
	v_add_u32_e32 v88, 108, v84
	v_cmp_gt_u32_e64 s[50:51], s98, v88
	v_nop
	v_cndmask_b32_e64 v200, 0, v200, s[30:31]
	v_cndmask_b32_e64 v201, 0, v201, s[36:37]
	v_cndmask_b32_e64 v202, 0, v202, s[78:79]
	v_cndmask_b32_e64 v203, 0, v203, s[50:51]
	v_cvt_pk_bf16_f32 v64, v188, v189
	v_cvt_pk_bf16_f32 v65, v190, v191
	v_cvt_pk_bf16_f32 v66, v192, v193
	v_cvt_pk_bf16_f32 v67, v194, v195
	v_cvt_pk_bf16_f32 v68, v196, v197
	v_cvt_pk_bf16_f32 v69, v198, v199
	v_cvt_pk_bf16_f32 v70, v200, v201
	v_cvt_pk_bf16_f32 v71, v202, v203
	v_pk_add_f32 v[232:233], v[232:233], v[188:189]
	v_pk_add_f32 v[232:233], v[232:233], v[190:191]
	v_pk_add_f32 v[232:233], v[232:233], v[192:193]
	v_pk_add_f32 v[232:233], v[232:233], v[194:195]
	v_pk_add_f32 v[232:233], v[232:233], v[196:197]
	v_pk_add_f32 v[232:233], v[232:233], v[198:199]
	v_pk_add_f32 v[232:233], v[232:233], v[200:201]
	v_pk_add_f32 v[232:233], v[232:233], v[202:203]
	ds_read2_b32 v[188:189], v115 offset0:224 offset1:225
	ds_read2_b32 v[190:191], v115 offset0:226 offset1:227
	ds_read2_b32 v[192:193], v115 offset0:232 offset1:233
	ds_read2_b32 v[194:195], v115 offset0:234 offset1:235
	ds_read2_b32 v[196:197], v115 offset0:240 offset1:241
	ds_read2_b32 v[198:199], v115 offset0:242 offset1:243
	ds_read2_b32 v[200:201], v115 offset0:248 offset1:249
	ds_read2_b32 v[202:203], v115 offset0:250 offset1:251
	v_mfma_f32_32x32x16_bf16 v[0:15], v[64:67], v[72:75], v[0:15]
	v_mfma_f32_32x32x16_bf16 v[16:31], v[64:67], v[76:79], v[16:31]
	v_mfma_f32_32x32x16_bf16 v[0:15], v[68:71], v[220:223], v[0:15]
	v_mfma_f32_32x32x16_bf16 v[16:31], v[68:71], v[224:227], v[16:31]
	s_add_i32 s90, s76, -1024
	v_add_u32_e32 v80, s90, v243
	v_add_u32_e32 v83, s90, v244
	v_add_u32_e32 v99, s90, v245
	v_add_u32_e32 v253, s90, v246
	v_add_u32_e32 v254, s90, v148
	v_add_u32_e32 v255, s90, v151
	v_med3_i32 v80, v80, 0, s99
	v_med3_i32 v83, v83, 0, s99
	v_med3_i32 v99, v99, 0, s99
	v_med3_i32 v253, v253, 0, s99
	v_med3_i32 v254, v254, 0, s99
	v_med3_i32 v255, v255, 0, s99
	v_mad_u32_u24 v80, v80, s100, v252
	v_mad_u32_u24 v83, v83, s100, v252
	v_mad_u32_u24 v99, v99, s100, v252
	v_mad_u32_u24 v253, v253, s100, v252
	v_mad_u32_u24 v254, v254, s100, v153
	v_mad_u32_u24 v255, v255, s100, v153
	global_load_dwordx4 v[116:119], v80, s[82:83]
	global_load_dwordx4 v[120:123], v83, s[82:83]
	global_load_dwordx4 v[124:127], v99, s[82:83]
	global_load_dwordx4 v[128:131], v253, s[82:83]
	global_load_dwordx4 v[132:135], v254, s[82:83] offset:768
	global_load_dwordx4 v[136:139], v255, s[82:83] offset:768
	global_load_dwordx4 v[140:143], v254, s[82:83] offset:832
	global_load_dwordx4 v[144:147], v255, s[82:83] offset:832
	ds_read_b64_tr_b16 v[72:73], v231
	ds_read_b64_tr_b16 v[74:75], v231 offset:512
	ds_read_b64_tr_b16 v[76:77], v231 offset:2048
	ds_read_b64_tr_b16 v[78:79], v231 offset:2560
	ds_read_b64_tr_b16 v[220:221], v231 offset:1024
	ds_read_b64_tr_b16 v[222:223], v231 offset:1536
	ds_read_b64_tr_b16 v[224:225], v231 offset:3072
	ds_read_b64_tr_b16 v[226:227], v231 offset:3584
	v_exp_f32_e32 v32, v32
	v_exp_f32_e32 v33, v33
	v_exp_f32_e32 v34, v34
	v_exp_f32_e32 v35, v35
	s_waitcnt vmcnt(8)
	ds_write_b128 v247, v[156:159]
	ds_write_b128 v247, v[160:163] offset:1024
	ds_write_b128 v247, v[164:167] offset:2048
	ds_write_b128 v247, v[168:171] offset:3072
	ds_read_b128 v[156:159], v248
	ds_read_b128 v[160:163], v249
	ds_read_b128 v[164:167], v250
	ds_read_b128 v[168:171], v251
	ds_write_b128 v112, v[172:175]
	ds_write_b128 v112, v[176:179] offset:1024
	ds_write_b128 v112, v[180:183] offset:2048
	ds_write_b128 v112, v[184:187] offset:3072
	v_exp_f32_e32 v36, v36
	v_exp_f32_e32 v37, v37
	v_exp_f32_e32 v38, v38
	v_exp_f32_e32 v39, v39
	s_waitcnt lgkmcnt(4)
	v_mfma_f32_32x32x16_bf16 v[188:203], v[156:159], v[48:51], v[188:203]
	v_exp_f32_e32 v40, v40
	v_exp_f32_e32 v41, v41
	v_mfma_f32_32x32x16_bf16 v[188:203], v[160:163], v[52:55], v[188:203]
	v_exp_f32_e32 v42, v42
	v_exp_f32_e32 v43, v43
	v_mfma_f32_32x32x16_bf16 v[188:203], v[164:167], v[56:59], v[188:203]
	v_exp_f32_e32 v44, v44
	v_exp_f32_e32 v45, v45
	v_mfma_f32_32x32x16_bf16 v[188:203], v[168:171], v[60:63], v[188:203]
	v_exp_f32_e32 v46, v46
	v_exp_f32_e32 v47, v47
	s_add_i32 s90, s76, 512
	v_lshlrev_b32_e32 v84, 2, v107
	v_add_u32_e32 v84, s90, v84
	v_add_u32_e32 v85, 0, v84
	v_add_u32_e32 v86, 4, v84
	v_add_u32_e32 v87, 8, v84
	v_add_u32_e32 v88, 12, v84
	v_cmp_gt_u32_e64 s[30:31], s98, v85
	v_cmp_gt_u32_e64 s[36:37], s98, v86
	v_cmp_gt_u32_e64 s[78:79], s98, v87
	v_cmp_gt_u32_e64 s[50:51], s98, v88
	v_cndmask_b32_e64 v32, 0, v32, s[30:31]
	v_add_u32_e32 v85, 32, v84
	v_cmp_gt_u32_e64 s[30:31], s98, v85
	v_cndmask_b32_e64 v33, 0, v33, s[36:37]
	v_add_u32_e32 v86, 36, v84
	v_cmp_gt_u32_e64 s[36:37], s98, v86
	v_cndmask_b32_e64 v34, 0, v34, s[78:79]
	v_add_u32_e32 v87, 40, v84
	v_cmp_gt_u32_e64 s[78:79], s98, v87
	v_cndmask_b32_e64 v35, 0, v35, s[50:51]
	v_add_u32_e32 v88, 44, v84
	v_cmp_gt_u32_e64 s[50:51], s98, v88
	v_cndmask_b32_e64 v36, 0, v36, s[30:31]
	v_add_u32_e32 v85, 64, v84
	v_cmp_gt_u32_e64 s[30:31], s98, v85
	v_cndmask_b32_e64 v37, 0, v37, s[36:37]
	v_add_u32_e32 v86, 68, v84
	v_cmp_gt_u32_e64 s[36:37], s98, v86
	v_cndmask_b32_e64 v38, 0, v38, s[78:79]
	v_add_u32_e32 v87, 72, v84
	v_cmp_gt_u32_e64 s[78:79], s98, v87
	v_cndmask_b32_e64 v39, 0, v39, s[50:51]
	v_add_u32_e32 v88, 76, v84
	v_cmp_gt_u32_e64 s[50:51], s98, v88
	v_cndmask_b32_e64 v40, 0, v40, s[30:31]
	v_add_u32_e32 v85, 96, v84
	v_cmp_gt_u32_e64 s[30:31], s98, v85
	v_cndmask_b32_e64 v41, 0, v41, s[36:37]
	v_add_u32_e32 v86, 100, v84
	v_cmp_gt_u32_e64 s[36:37], s98, v86
	v_cndmask_b32_e64 v42, 0, v42, s[78:79]
	v_add_u32_e32 v87, 104, v84
	v_cmp_gt_u32_e64 s[78:79], s98, v87
	v_cndmask_b32_e64 v43, 0, v43, s[50:51]
	v_add_u32_e32 v88, 108, v84
	v_cmp_gt_u32_e64 s[50:51], s98, v88
	v_nop
	v_cndmask_b32_e64 v44, 0, v44, s[30:31]
	v_cndmask_b32_e64 v45, 0, v45, s[36:37]
	v_cndmask_b32_e64 v46, 0, v46, s[78:79]
	v_cndmask_b32_e64 v47, 0, v47, s[50:51]
	v_cvt_pk_bf16_f32 v64, v32, v33
	v_cvt_pk_bf16_f32 v65, v34, v35
	v_cvt_pk_bf16_f32 v66, v36, v37
	v_cvt_pk_bf16_f32 v67, v38, v39
	v_cvt_pk_bf16_f32 v68, v40, v41
	v_cvt_pk_bf16_f32 v69, v42, v43
	v_cvt_pk_bf16_f32 v70, v44, v45
	v_cvt_pk_bf16_f32 v71, v46, v47
	v_pk_add_f32 v[232:233], v[232:233], v[32:33]
	v_pk_add_f32 v[232:233], v[232:233], v[34:35]
	v_pk_add_f32 v[232:233], v[232:233], v[36:37]
	v_pk_add_f32 v[232:233], v[232:233], v[38:39]
	v_pk_add_f32 v[232:233], v[232:233], v[40:41]
	v_pk_add_f32 v[232:233], v[232:233], v[42:43]
	v_pk_add_f32 v[232:233], v[232:233], v[44:45]
	v_pk_add_f32 v[232:233], v[232:233], v[46:47]
	v_mov_b32_e32 v115, v230
	ds_read2_b32 v[32:33], v115 offset0:0 offset1:1
	ds_read2_b32 v[34:35], v115 offset0:2 offset1:3
	ds_read2_b32 v[36:37], v115 offset0:8 offset1:9
	ds_read2_b32 v[38:39], v115 offset0:10 offset1:11
	ds_read2_b32 v[40:41], v115 offset0:16 offset1:17
	ds_read2_b32 v[42:43], v115 offset0:18 offset1:19
	ds_read2_b32 v[44:45], v115 offset0:24 offset1:25
	ds_read2_b32 v[46:47], v115 offset0:26 offset1:27
	v_mfma_f32_32x32x16_bf16 v[0:15], v[64:67], v[72:75], v[0:15]
	v_mfma_f32_32x32x16_bf16 v[16:31], v[64:67], v[76:79], v[16:31]
	v_mfma_f32_32x32x16_bf16 v[0:15], v[68:71], v[220:223], v[0:15]
	v_mfma_f32_32x32x16_bf16 v[16:31], v[68:71], v[224:227], v[16:31]
	s_add_i32 s90, s76, -512
	v_add_u32_e32 v80, s90, v243
	v_add_u32_e32 v83, s90, v244
	v_add_u32_e32 v99, s90, v245
	v_add_u32_e32 v253, s90, v246
	v_add_u32_e32 v254, s90, v148
	v_add_u32_e32 v255, s90, v151
	v_med3_i32 v80, v80, 0, s99
	v_med3_i32 v83, v83, 0, s99
	v_med3_i32 v99, v99, 0, s99
	v_med3_i32 v253, v253, 0, s99
	v_med3_i32 v254, v254, 0, s99
	v_med3_i32 v255, v255, 0, s99
	v_mad_u32_u24 v80, v80, s100, v252
	v_mad_u32_u24 v83, v83, s100, v252
	v_mad_u32_u24 v99, v99, s100, v252
	v_mad_u32_u24 v253, v253, s100, v252
	v_mad_u32_u24 v254, v254, s100, v153
	v_mad_u32_u24 v255, v255, s100, v153
	global_load_dwordx4 v[156:159], v80, s[82:83]
	global_load_dwordx4 v[160:163], v83, s[82:83]
	global_load_dwordx4 v[164:167], v99, s[82:83]
	global_load_dwordx4 v[168:171], v253, s[82:83]
	global_load_dwordx4 v[172:175], v254, s[82:83] offset:768
	global_load_dwordx4 v[176:179], v255, s[82:83] offset:768
	global_load_dwordx4 v[180:183], v254, s[82:83] offset:832
	global_load_dwordx4 v[184:187], v255, s[82:83] offset:832
	ds_read_b64_tr_b16 v[72:73], v231
	ds_read_b64_tr_b16 v[74:75], v231 offset:512
	ds_read_b64_tr_b16 v[76:77], v231 offset:2048
	ds_read_b64_tr_b16 v[78:79], v231 offset:2560
	ds_read_b64_tr_b16 v[220:221], v231 offset:1024
	ds_read_b64_tr_b16 v[222:223], v231 offset:1536
	ds_read_b64_tr_b16 v[224:225], v231 offset:3072
	ds_read_b64_tr_b16 v[226:227], v231 offset:3584
	v_exp_f32_e32 v188, v188
	v_exp_f32_e32 v189, v189
	v_exp_f32_e32 v190, v190
	v_exp_f32_e32 v191, v191
	s_waitcnt vmcnt(8)
	ds_write_b128 v247, v[116:119]
	ds_write_b128 v247, v[120:123] offset:1024
	ds_write_b128 v247, v[124:127] offset:2048
	ds_write_b128 v247, v[128:131] offset:3072
	ds_read_b128 v[116:119], v248
	ds_read_b128 v[120:123], v249
	ds_read_b128 v[124:127], v250
	ds_read_b128 v[128:131], v251
	ds_write_b128 v112, v[132:135]
	ds_write_b128 v112, v[136:139] offset:1024
	ds_write_b128 v112, v[140:143] offset:2048
	ds_write_b128 v112, v[144:147] offset:3072
	v_exp_f32_e32 v192, v192
	v_exp_f32_e32 v193, v193
	v_exp_f32_e32 v194, v194
	v_exp_f32_e32 v195, v195
	s_waitcnt lgkmcnt(4)
	v_mfma_f32_32x32x16_bf16 v[32:47], v[116:119], v[48:51], v[32:47]
	v_exp_f32_e32 v196, v196
	v_exp_f32_e32 v197, v197
	v_mfma_f32_32x32x16_bf16 v[32:47], v[120:123], v[52:55], v[32:47]
	v_exp_f32_e32 v198, v198
	v_exp_f32_e32 v199, v199
	v_mfma_f32_32x32x16_bf16 v[32:47], v[124:127], v[56:59], v[32:47]
	v_exp_f32_e32 v200, v200
	v_exp_f32_e32 v201, v201
	v_mfma_f32_32x32x16_bf16 v[32:47], v[128:131], v[60:63], v[32:47]
	v_exp_f32_e32 v202, v202
	v_exp_f32_e32 v203, v203
	s_add_i32 s90, s76, 640
	v_lshlrev_b32_e32 v84, 2, v107
	v_add_u32_e32 v84, s90, v84
	v_add_u32_e32 v85, 0, v84
	v_add_u32_e32 v86, 4, v84
	v_add_u32_e32 v87, 8, v84
	v_add_u32_e32 v88, 12, v84
	v_cmp_gt_u32_e64 s[30:31], s98, v85
	v_cmp_gt_u32_e64 s[36:37], s98, v86
	v_cmp_gt_u32_e64 s[78:79], s98, v87
	v_cmp_gt_u32_e64 s[50:51], s98, v88
	v_cndmask_b32_e64 v188, 0, v188, s[30:31]
	v_add_u32_e32 v85, 32, v84
	v_cmp_gt_u32_e64 s[30:31], s98, v85
	v_cndmask_b32_e64 v189, 0, v189, s[36:37]
	v_add_u32_e32 v86, 36, v84
	v_cmp_gt_u32_e64 s[36:37], s98, v86
	v_cndmask_b32_e64 v190, 0, v190, s[78:79]
	v_add_u32_e32 v87, 40, v84
	v_cmp_gt_u32_e64 s[78:79], s98, v87
	v_cndmask_b32_e64 v191, 0, v191, s[50:51]
	v_add_u32_e32 v88, 44, v84
	v_cmp_gt_u32_e64 s[50:51], s98, v88
	v_cndmask_b32_e64 v192, 0, v192, s[30:31]
	v_add_u32_e32 v85, 64, v84
	v_cmp_gt_u32_e64 s[30:31], s98, v85
	v_cndmask_b32_e64 v193, 0, v193, s[36:37]
	v_add_u32_e32 v86, 68, v84
	v_cmp_gt_u32_e64 s[36:37], s98, v86
	v_cndmask_b32_e64 v194, 0, v194, s[78:79]
	v_add_u32_e32 v87, 72, v84
	v_cmp_gt_u32_e64 s[78:79], s98, v87
	v_cndmask_b32_e64 v195, 0, v195, s[50:51]
	v_add_u32_e32 v88, 76, v84
	v_cmp_gt_u32_e64 s[50:51], s98, v88
	v_cndmask_b32_e64 v196, 0, v196, s[30:31]
	v_add_u32_e32 v85, 96, v84
	v_cmp_gt_u32_e64 s[30:31], s98, v85
	v_cndmask_b32_e64 v197, 0, v197, s[36:37]
	v_add_u32_e32 v86, 100, v84
	v_cmp_gt_u32_e64 s[36:37], s98, v86
	v_cndmask_b32_e64 v198, 0, v198, s[78:79]
	v_add_u32_e32 v87, 104, v84
	v_cmp_gt_u32_e64 s[78:79], s98, v87
	v_cndmask_b32_e64 v199, 0, v199, s[50:51]
	v_add_u32_e32 v88, 108, v84
	v_cmp_gt_u32_e64 s[50:51], s98, v88
	v_nop
	v_cndmask_b32_e64 v200, 0, v200, s[30:31]
	v_cndmask_b32_e64 v201, 0, v201, s[36:37]
	v_cndmask_b32_e64 v202, 0, v202, s[78:79]
	v_cndmask_b32_e64 v203, 0, v203, s[50:51]
	v_cvt_pk_bf16_f32 v64, v188, v189
	v_cvt_pk_bf16_f32 v65, v190, v191
	v_cvt_pk_bf16_f32 v66, v192, v193
	v_cvt_pk_bf16_f32 v67, v194, v195
	v_cvt_pk_bf16_f32 v68, v196, v197
	v_cvt_pk_bf16_f32 v69, v198, v199
	v_cvt_pk_bf16_f32 v70, v200, v201
	v_cvt_pk_bf16_f32 v71, v202, v203
	v_pk_add_f32 v[232:233], v[232:233], v[188:189]
	v_pk_add_f32 v[232:233], v[232:233], v[190:191]
	v_pk_add_f32 v[232:233], v[232:233], v[192:193]
	v_pk_add_f32 v[232:233], v[232:233], v[194:195]
	v_pk_add_f32 v[232:233], v[232:233], v[196:197]
	v_pk_add_f32 v[232:233], v[232:233], v[198:199]
	v_pk_add_f32 v[232:233], v[232:233], v[200:201]
	v_pk_add_f32 v[232:233], v[232:233], v[202:203]
	ds_read2_b32 v[188:189], v115 offset0:32 offset1:33
	ds_read2_b32 v[190:191], v115 offset0:34 offset1:35
	ds_read2_b32 v[192:193], v115 offset0:40 offset1:41
	ds_read2_b32 v[194:195], v115 offset0:42 offset1:43
	ds_read2_b32 v[196:197], v115 offset0:48 offset1:49
	ds_read2_b32 v[198:199], v115 offset0:50 offset1:51
	ds_read2_b32 v[200:201], v115 offset0:56 offset1:57
	ds_read2_b32 v[202:203], v115 offset0:58 offset1:59
	v_mfma_f32_32x32x16_bf16 v[0:15], v[64:67], v[72:75], v[0:15]
	v_mfma_f32_32x32x16_bf16 v[16:31], v[64:67], v[76:79], v[16:31]
	v_mfma_f32_32x32x16_bf16 v[0:15], v[68:71], v[220:223], v[0:15]
	v_mfma_f32_32x32x16_bf16 v[16:31], v[68:71], v[224:227], v[16:31]
	s_add_i32 s90, s76, 0
	v_add_u32_e32 v80, s90, v243
	v_add_u32_e32 v83, s90, v244
	v_add_u32_e32 v99, s90, v245
	v_add_u32_e32 v253, s90, v246
	v_add_u32_e32 v254, s90, v148
	v_add_u32_e32 v255, s90, v151
	v_med3_i32 v80, v80, 0, s99
	v_med3_i32 v83, v83, 0, s99
	v_med3_i32 v99, v99, 0, s99
	v_med3_i32 v253, v253, 0, s99
	v_med3_i32 v254, v254, 0, s99
	v_med3_i32 v255, v255, 0, s99
	v_mad_u32_u24 v80, v80, s100, v252
	v_mad_u32_u24 v83, v83, s100, v252
	v_mad_u32_u24 v99, v99, s100, v252
	v_mad_u32_u24 v253, v253, s100, v252
	v_mad_u32_u24 v254, v254, s100, v153
	v_mad_u32_u24 v255, v255, s100, v153
	global_load_dwordx4 v[116:119], v80, s[82:83]
	global_load_dwordx4 v[120:123], v83, s[82:83]
	global_load_dwordx4 v[124:127], v99, s[82:83]
	global_load_dwordx4 v[128:131], v253, s[82:83]
	global_load_dwordx4 v[132:135], v254, s[82:83] offset:768
	global_load_dwordx4 v[136:139], v255, s[82:83] offset:768
	global_load_dwordx4 v[140:143], v254, s[82:83] offset:832
	global_load_dwordx4 v[144:147], v255, s[82:83] offset:832
	ds_read_b64_tr_b16 v[72:73], v231
	ds_read_b64_tr_b16 v[74:75], v231 offset:512
	ds_read_b64_tr_b16 v[76:77], v231 offset:2048
	ds_read_b64_tr_b16 v[78:79], v231 offset:2560
	ds_read_b64_tr_b16 v[220:221], v231 offset:1024
	ds_read_b64_tr_b16 v[222:223], v231 offset:1536
	ds_read_b64_tr_b16 v[224:225], v231 offset:3072
	ds_read_b64_tr_b16 v[226:227], v231 offset:3584
	v_exp_f32_e32 v32, v32
	v_exp_f32_e32 v33, v33
	v_exp_f32_e32 v34, v34
	v_exp_f32_e32 v35, v35
	s_waitcnt vmcnt(8)
	ds_write_b128 v247, v[156:159]
	ds_write_b128 v247, v[160:163] offset:1024
	ds_write_b128 v247, v[164:167] offset:2048
	ds_write_b128 v247, v[168:171] offset:3072
	ds_read_b128 v[156:159], v248
	ds_read_b128 v[160:163], v249
	ds_read_b128 v[164:167], v250
	ds_read_b128 v[168:171], v251
	ds_write_b128 v112, v[172:175]
	ds_write_b128 v112, v[176:179] offset:1024
	ds_write_b128 v112, v[180:183] offset:2048
	ds_write_b128 v112, v[184:187] offset:3072
	v_exp_f32_e32 v36, v36
	v_exp_f32_e32 v37, v37
	v_exp_f32_e32 v38, v38
	v_exp_f32_e32 v39, v39
	s_waitcnt lgkmcnt(4)
	v_mfma_f32_32x32x16_bf16 v[188:203], v[156:159], v[48:51], v[188:203]
	v_exp_f32_e32 v40, v40
	v_exp_f32_e32 v41, v41
	v_mfma_f32_32x32x16_bf16 v[188:203], v[160:163], v[52:55], v[188:203]
	v_exp_f32_e32 v42, v42
	v_exp_f32_e32 v43, v43
	v_mfma_f32_32x32x16_bf16 v[188:203], v[164:167], v[56:59], v[188:203]
	v_exp_f32_e32 v44, v44
	v_exp_f32_e32 v45, v45
	v_mfma_f32_32x32x16_bf16 v[188:203], v[168:171], v[60:63], v[188:203]
	v_exp_f32_e32 v46, v46
	v_exp_f32_e32 v47, v47
	s_add_i32 s90, s76, -1024
	v_lshlrev_b32_e32 v84, 4, v107
	v_add_u32_e32 v84, s90, v84
	v_add_u32_e32 v85, 0, v84
	v_add_u32_e32 v86, 16, v84
	v_add_u32_e32 v87, 32, v84
	v_add_u32_e32 v88, 48, v84
	v_cmp_gt_u32_e64 s[30:31], s98, v85
	v_cmp_gt_u32_e64 s[36:37], s98, v86
	v_cmp_gt_u32_e64 s[78:79], s98, v87
	v_cmp_gt_u32_e64 s[50:51], s98, v88
	v_cndmask_b32_e64 v32, 0, v32, s[30:31]
	v_add_u32_e32 v85, 128, v84
	v_cmp_gt_u32_e64 s[30:31], s98, v85
	v_cndmask_b32_e64 v33, 0, v33, s[36:37]
	v_add_u32_e32 v86, 144, v84
	v_cmp_gt_u32_e64 s[36:37], s98, v86
	v_cndmask_b32_e64 v34, 0, v34, s[78:79]
	v_add_u32_e32 v87, 160, v84
	v_cmp_gt_u32_e64 s[78:79], s98, v87
	v_cndmask_b32_e64 v35, 0, v35, s[50:51]
	v_add_u32_e32 v88, 176, v84
	v_cmp_gt_u32_e64 s[50:51], s98, v88
	v_cndmask_b32_e64 v36, 0, v36, s[30:31]
	v_add_u32_e32 v85, 256, v84
	v_cmp_gt_u32_e64 s[30:31], s98, v85
	v_cndmask_b32_e64 v37, 0, v37, s[36:37]
	v_add_u32_e32 v86, 272, v84
	v_cmp_gt_u32_e64 s[36:37], s98, v86
	v_cndmask_b32_e64 v38, 0, v38, s[78:79]
	v_add_u32_e32 v87, 288, v84
	v_cmp_gt_u32_e64 s[78:79], s98, v87
	v_cndmask_b32_e64 v39, 0, v39, s[50:51]
	v_add_u32_e32 v88, 304, v84
	v_cmp_gt_u32_e64 s[50:51], s98, v88
	v_cndmask_b32_e64 v40, 0, v40, s[30:31]
	v_add_u32_e32 v85, 384, v84
	v_cmp_gt_u32_e64 s[30:31], s98, v85
	v_cndmask_b32_e64 v41, 0, v41, s[36:37]
	v_add_u32_e32 v86, 400, v84
	v_cmp_gt_u32_e64 s[36:37], s98, v86
	v_cndmask_b32_e64 v42, 0, v42, s[78:79]
	v_add_u32_e32 v87, 416, v84
	v_cmp_gt_u32_e64 s[78:79], s98, v87
	v_cndmask_b32_e64 v43, 0, v43, s[50:51]
	v_add_u32_e32 v88, 432, v84
	v_cmp_gt_u32_e64 s[50:51], s98, v88
	v_nop
	v_cndmask_b32_e64 v44, 0, v44, s[30:31]
	v_cndmask_b32_e64 v45, 0, v45, s[36:37]
	v_cndmask_b32_e64 v46, 0, v46, s[78:79]
	v_cndmask_b32_e64 v47, 0, v47, s[50:51]
	v_cvt_pk_bf16_f32 v64, v32, v33
	v_cvt_pk_bf16_f32 v65, v34, v35
	v_cvt_pk_bf16_f32 v66, v36, v37
	v_cvt_pk_bf16_f32 v67, v38, v39
	v_cvt_pk_bf16_f32 v68, v40, v41
	v_cvt_pk_bf16_f32 v69, v42, v43
	v_cvt_pk_bf16_f32 v70, v44, v45
	v_cvt_pk_bf16_f32 v71, v46, v47
	v_pk_add_f32 v[232:233], v[232:233], v[32:33]
	v_pk_add_f32 v[232:233], v[232:233], v[34:35]
	v_pk_add_f32 v[232:233], v[232:233], v[36:37]
	v_pk_add_f32 v[232:233], v[232:233], v[38:39]
	v_pk_add_f32 v[232:233], v[232:233], v[40:41]
	v_pk_add_f32 v[232:233], v[232:233], v[42:43]
	v_pk_add_f32 v[232:233], v[232:233], v[44:45]
	v_pk_add_f32 v[232:233], v[232:233], v[46:47]
	ds_read2_b32 v[32:33], v115 offset0:64 offset1:65
	ds_read2_b32 v[34:35], v115 offset0:66 offset1:67
	ds_read2_b32 v[36:37], v115 offset0:72 offset1:73
	ds_read2_b32 v[38:39], v115 offset0:74 offset1:75
	ds_read2_b32 v[40:41], v115 offset0:80 offset1:81
	ds_read2_b32 v[42:43], v115 offset0:82 offset1:83
	ds_read2_b32 v[44:45], v115 offset0:88 offset1:89
	ds_read2_b32 v[46:47], v115 offset0:90 offset1:91
	v_mfma_f32_32x32x16_bf16 v[0:15], v[64:67], v[72:75], v[0:15]
	v_mfma_f32_32x32x16_bf16 v[16:31], v[64:67], v[76:79], v[16:31]
	v_mfma_f32_32x32x16_bf16 v[0:15], v[68:71], v[220:223], v[0:15]
	v_mfma_f32_32x32x16_bf16 v[16:31], v[68:71], v[224:227], v[16:31]
	s_add_i32 s90, s76, 512
	v_add_u32_e32 v80, s90, v243
	v_add_u32_e32 v83, s90, v244
	v_add_u32_e32 v99, s90, v245
	v_add_u32_e32 v253, s90, v246
	v_add_u32_e32 v254, s90, v148
	v_add_u32_e32 v255, s90, v151
	v_med3_i32 v80, v80, 0, s99
	v_med3_i32 v83, v83, 0, s99
	v_med3_i32 v99, v99, 0, s99
	v_med3_i32 v253, v253, 0, s99
	v_med3_i32 v254, v254, 0, s99
	v_med3_i32 v255, v255, 0, s99
	v_mad_u32_u24 v80, v80, s100, v252
	v_mad_u32_u24 v83, v83, s100, v252
	v_mad_u32_u24 v99, v99, s100, v252
	v_mad_u32_u24 v253, v253, s100, v252
	v_mad_u32_u24 v254, v254, s100, v153
	v_mad_u32_u24 v255, v255, s100, v153
	global_load_dwordx4 v[156:159], v80, s[82:83]
	global_load_dwordx4 v[160:163], v83, s[82:83]
	global_load_dwordx4 v[164:167], v99, s[82:83]
	global_load_dwordx4 v[168:171], v253, s[82:83]
	global_load_dwordx4 v[172:175], v254, s[82:83] offset:768
	global_load_dwordx4 v[176:179], v255, s[82:83] offset:768
	global_load_dwordx4 v[180:183], v254, s[82:83] offset:832
	global_load_dwordx4 v[184:187], v255, s[82:83] offset:832
	ds_read_b64_tr_b16 v[72:73], v231
	ds_read_b64_tr_b16 v[74:75], v231 offset:512
	ds_read_b64_tr_b16 v[76:77], v231 offset:2048
	ds_read_b64_tr_b16 v[78:79], v231 offset:2560
	ds_read_b64_tr_b16 v[220:221], v231 offset:1024
	ds_read_b64_tr_b16 v[222:223], v231 offset:1536
	ds_read_b64_tr_b16 v[224:225], v231 offset:3072
	ds_read_b64_tr_b16 v[226:227], v231 offset:3584
	v_exp_f32_e32 v188, v188
	v_exp_f32_e32 v189, v189
	v_exp_f32_e32 v190, v190
	v_exp_f32_e32 v191, v191
	s_waitcnt vmcnt(8)
	ds_write_b128 v247, v[116:119]
	ds_write_b128 v247, v[120:123] offset:1024
	ds_write_b128 v247, v[124:127] offset:2048
	ds_write_b128 v247, v[128:131] offset:3072
	ds_read_b128 v[116:119], v248
	ds_read_b128 v[120:123], v249
	ds_read_b128 v[124:127], v250
	ds_read_b128 v[128:131], v251
	ds_write_b128 v112, v[132:135]
	ds_write_b128 v112, v[136:139] offset:1024
	ds_write_b128 v112, v[140:143] offset:2048
	ds_write_b128 v112, v[144:147] offset:3072
	v_exp_f32_e32 v192, v192
	v_exp_f32_e32 v193, v193
	v_exp_f32_e32 v194, v194
	v_exp_f32_e32 v195, v195
	s_waitcnt lgkmcnt(4)
	v_mfma_f32_32x32x16_bf16 v[32:47], v[116:119], v[48:51], v[32:47]
	v_exp_f32_e32 v196, v196
	v_exp_f32_e32 v197, v197
	v_mfma_f32_32x32x16_bf16 v[32:47], v[120:123], v[52:55], v[32:47]
	v_exp_f32_e32 v198, v198
	v_exp_f32_e32 v199, v199
	v_mfma_f32_32x32x16_bf16 v[32:47], v[124:127], v[56:59], v[32:47]
	v_exp_f32_e32 v200, v200
	v_exp_f32_e32 v201, v201
	v_mfma_f32_32x32x16_bf16 v[32:47], v[128:131], v[60:63], v[32:47]
	v_exp_f32_e32 v202, v202
	v_exp_f32_e32 v203, v203
	s_add_i32 s90, s76, -512
	v_lshlrev_b32_e32 v84, 4, v107
	v_add_u32_e32 v84, s90, v84
	v_add_u32_e32 v85, 0, v84
	v_add_u32_e32 v86, 16, v84
	v_add_u32_e32 v87, 32, v84
	v_add_u32_e32 v88, 48, v84
	v_cmp_gt_u32_e64 s[30:31], s98, v85
	v_cmp_gt_u32_e64 s[36:37], s98, v86
	v_cmp_gt_u32_e64 s[78:79], s98, v87
	v_cmp_gt_u32_e64 s[50:51], s98, v88
	v_cndmask_b32_e64 v188, 0, v188, s[30:31]
	v_add_u32_e32 v85, 128, v84
	v_cmp_gt_u32_e64 s[30:31], s98, v85
	v_cndmask_b32_e64 v189, 0, v189, s[36:37]
	v_add_u32_e32 v86, 144, v84
	v_cmp_gt_u32_e64 s[36:37], s98, v86
	v_cndmask_b32_e64 v190, 0, v190, s[78:79]
	v_add_u32_e32 v87, 160, v84
	v_cmp_gt_u32_e64 s[78:79], s98, v87
	v_cndmask_b32_e64 v191, 0, v191, s[50:51]
	v_add_u32_e32 v88, 176, v84
	v_cmp_gt_u32_e64 s[50:51], s98, v88
	v_cndmask_b32_e64 v192, 0, v192, s[30:31]
	v_add_u32_e32 v85, 256, v84
	v_cmp_gt_u32_e64 s[30:31], s98, v85
	v_cndmask_b32_e64 v193, 0, v193, s[36:37]
	v_add_u32_e32 v86, 272, v84
	v_cmp_gt_u32_e64 s[36:37], s98, v86
	v_cndmask_b32_e64 v194, 0, v194, s[78:79]
	v_add_u32_e32 v87, 288, v84
	v_cmp_gt_u32_e64 s[78:79], s98, v87
	v_cndmask_b32_e64 v195, 0, v195, s[50:51]
	v_add_u32_e32 v88, 304, v84
	v_cmp_gt_u32_e64 s[50:51], s98, v88
	v_cndmask_b32_e64 v196, 0, v196, s[30:31]
	v_add_u32_e32 v85, 384, v84
	v_cmp_gt_u32_e64 s[30:31], s98, v85
	v_cndmask_b32_e64 v197, 0, v197, s[36:37]
	v_add_u32_e32 v86, 400, v84
	v_cmp_gt_u32_e64 s[36:37], s98, v86
	v_cndmask_b32_e64 v198, 0, v198, s[78:79]
	v_add_u32_e32 v87, 416, v84
	v_cmp_gt_u32_e64 s[78:79], s98, v87
	v_cndmask_b32_e64 v199, 0, v199, s[50:51]
	v_add_u32_e32 v88, 432, v84
	v_cmp_gt_u32_e64 s[50:51], s98, v88
	v_nop
	v_cndmask_b32_e64 v200, 0, v200, s[30:31]
	v_cndmask_b32_e64 v201, 0, v201, s[36:37]
	v_cndmask_b32_e64 v202, 0, v202, s[78:79]
	v_cndmask_b32_e64 v203, 0, v203, s[50:51]
	v_cvt_pk_bf16_f32 v64, v188, v189
	v_cvt_pk_bf16_f32 v65, v190, v191
	v_cvt_pk_bf16_f32 v66, v192, v193
	v_cvt_pk_bf16_f32 v67, v194, v195
	v_cvt_pk_bf16_f32 v68, v196, v197
	v_cvt_pk_bf16_f32 v69, v198, v199
	v_cvt_pk_bf16_f32 v70, v200, v201
	v_cvt_pk_bf16_f32 v71, v202, v203
	v_pk_add_f32 v[232:233], v[232:233], v[188:189]
	v_pk_add_f32 v[232:233], v[232:233], v[190:191]
	v_pk_add_f32 v[232:233], v[232:233], v[192:193]
	v_pk_add_f32 v[232:233], v[232:233], v[194:195]
	v_pk_add_f32 v[232:233], v[232:233], v[196:197]
	v_pk_add_f32 v[232:233], v[232:233], v[198:199]
	v_pk_add_f32 v[232:233], v[232:233], v[200:201]
	v_pk_add_f32 v[232:233], v[232:233], v[202:203]
	ds_read2_b32 v[188:189], v115 offset0:96 offset1:97
	ds_read2_b32 v[190:191], v115 offset0:98 offset1:99
	ds_read2_b32 v[192:193], v115 offset0:104 offset1:105
	ds_read2_b32 v[194:195], v115 offset0:106 offset1:107
	ds_read2_b32 v[196:197], v115 offset0:112 offset1:113
	ds_read2_b32 v[198:199], v115 offset0:114 offset1:115
	ds_read2_b32 v[200:201], v115 offset0:120 offset1:121
	ds_read2_b32 v[202:203], v115 offset0:122 offset1:123
	v_mfma_f32_32x32x16_bf16 v[0:15], v[64:67], v[72:75], v[0:15]
	v_mfma_f32_32x32x16_bf16 v[16:31], v[64:67], v[76:79], v[16:31]
	v_mfma_f32_32x32x16_bf16 v[0:15], v[68:71], v[220:223], v[0:15]
	v_mfma_f32_32x32x16_bf16 v[16:31], v[68:71], v[224:227], v[16:31]
	s_add_i32 s90, s76, 1024
	v_add_u32_e32 v80, s90, v243
	v_add_u32_e32 v83, s90, v244
	v_add_u32_e32 v99, s90, v245
	v_add_u32_e32 v253, s90, v246
	v_add_u32_e32 v254, s90, v148
	v_add_u32_e32 v255, s90, v151
	v_med3_i32 v80, v80, 0, s99
	v_med3_i32 v83, v83, 0, s99
	v_med3_i32 v99, v99, 0, s99
	v_med3_i32 v253, v253, 0, s99
	v_med3_i32 v254, v254, 0, s99
	v_med3_i32 v255, v255, 0, s99
	v_mad_u32_u24 v80, v80, s100, v252
	v_mad_u32_u24 v83, v83, s100, v252
	v_mad_u32_u24 v99, v99, s100, v252
	v_mad_u32_u24 v253, v253, s100, v252
	v_mad_u32_u24 v254, v254, s100, v153
	v_mad_u32_u24 v255, v255, s100, v153
	global_load_dwordx4 v[116:119], v80, s[82:83]
	global_load_dwordx4 v[120:123], v83, s[82:83]
	global_load_dwordx4 v[124:127], v99, s[82:83]
	global_load_dwordx4 v[128:131], v253, s[82:83]
	global_load_dwordx4 v[132:135], v254, s[82:83] offset:768
	global_load_dwordx4 v[136:139], v255, s[82:83] offset:768
	global_load_dwordx4 v[140:143], v254, s[82:83] offset:832
	global_load_dwordx4 v[144:147], v255, s[82:83] offset:832
	ds_read_b64_tr_b16 v[72:73], v231
	ds_read_b64_tr_b16 v[74:75], v231 offset:512
	ds_read_b64_tr_b16 v[76:77], v231 offset:2048
	ds_read_b64_tr_b16 v[78:79], v231 offset:2560
	ds_read_b64_tr_b16 v[220:221], v231 offset:1024
	ds_read_b64_tr_b16 v[222:223], v231 offset:1536
	ds_read_b64_tr_b16 v[224:225], v231 offset:3072
	ds_read_b64_tr_b16 v[226:227], v231 offset:3584
	v_exp_f32_e32 v32, v32
	v_exp_f32_e32 v33, v33
	v_exp_f32_e32 v34, v34
	v_exp_f32_e32 v35, v35
	s_waitcnt vmcnt(8)
	ds_write_b128 v247, v[156:159]
	ds_write_b128 v247, v[160:163] offset:1024
	ds_write_b128 v247, v[164:167] offset:2048
	ds_write_b128 v247, v[168:171] offset:3072
	ds_read_b128 v[156:159], v248
	ds_read_b128 v[160:163], v249
	ds_read_b128 v[164:167], v250
	ds_read_b128 v[168:171], v251
	ds_write_b128 v112, v[172:175]
	ds_write_b128 v112, v[176:179] offset:1024
	ds_write_b128 v112, v[180:183] offset:2048
	ds_write_b128 v112, v[184:187] offset:3072
	v_exp_f32_e32 v36, v36
	v_exp_f32_e32 v37, v37
	v_exp_f32_e32 v38, v38
	v_exp_f32_e32 v39, v39
	s_waitcnt lgkmcnt(4)
	v_mfma_f32_32x32x16_bf16 v[188:203], v[156:159], v[48:51], v[188:203]
	v_exp_f32_e32 v40, v40
	v_exp_f32_e32 v41, v41
	v_mfma_f32_32x32x16_bf16 v[188:203], v[160:163], v[52:55], v[188:203]
	v_exp_f32_e32 v42, v42
	v_exp_f32_e32 v43, v43
	v_mfma_f32_32x32x16_bf16 v[188:203], v[164:167], v[56:59], v[188:203]
	v_exp_f32_e32 v44, v44
	v_exp_f32_e32 v45, v45
	v_mfma_f32_32x32x16_bf16 v[188:203], v[168:171], v[60:63], v[188:203]
	v_exp_f32_e32 v46, v46
	v_exp_f32_e32 v47, v47
	s_add_i32 s90, s76, 0
	v_lshlrev_b32_e32 v84, 4, v107
	v_add_u32_e32 v84, s90, v84
	v_add_u32_e32 v85, 0, v84
	v_add_u32_e32 v86, 16, v84
	v_add_u32_e32 v87, 32, v84
	v_add_u32_e32 v88, 48, v84
	v_cmp_gt_u32_e64 s[30:31], s98, v85
	v_cmp_gt_u32_e64 s[36:37], s98, v86
	v_cmp_gt_u32_e64 s[78:79], s98, v87
	v_cmp_gt_u32_e64 s[50:51], s98, v88
	v_cndmask_b32_e64 v32, 0, v32, s[30:31]
	v_add_u32_e32 v85, 128, v84
	v_cmp_gt_u32_e64 s[30:31], s98, v85
	v_cndmask_b32_e64 v33, 0, v33, s[36:37]
	v_add_u32_e32 v86, 144, v84
	v_cmp_gt_u32_e64 s[36:37], s98, v86
	v_cndmask_b32_e64 v34, 0, v34, s[78:79]
	v_add_u32_e32 v87, 160, v84
	v_cmp_gt_u32_e64 s[78:79], s98, v87
	v_cndmask_b32_e64 v35, 0, v35, s[50:51]
	v_add_u32_e32 v88, 176, v84
	v_cmp_gt_u32_e64 s[50:51], s98, v88
	v_cndmask_b32_e64 v36, 0, v36, s[30:31]
	v_add_u32_e32 v85, 256, v84
	v_cmp_gt_u32_e64 s[30:31], s98, v85
	v_cndmask_b32_e64 v37, 0, v37, s[36:37]
	v_add_u32_e32 v86, 272, v84
	v_cmp_gt_u32_e64 s[36:37], s98, v86
	v_cndmask_b32_e64 v38, 0, v38, s[78:79]
	v_add_u32_e32 v87, 288, v84
	v_cmp_gt_u32_e64 s[78:79], s98, v87
	v_cndmask_b32_e64 v39, 0, v39, s[50:51]
	v_add_u32_e32 v88, 304, v84
	v_cmp_gt_u32_e64 s[50:51], s98, v88
	v_cndmask_b32_e64 v40, 0, v40, s[30:31]
	v_add_u32_e32 v85, 384, v84
	v_cmp_gt_u32_e64 s[30:31], s98, v85
	v_cndmask_b32_e64 v41, 0, v41, s[36:37]
	v_add_u32_e32 v86, 400, v84
	v_cmp_gt_u32_e64 s[36:37], s98, v86
	v_cndmask_b32_e64 v42, 0, v42, s[78:79]
	v_add_u32_e32 v87, 416, v84
	v_cmp_gt_u32_e64 s[78:79], s98, v87
	v_cndmask_b32_e64 v43, 0, v43, s[50:51]
	v_add_u32_e32 v88, 432, v84
	v_cmp_gt_u32_e64 s[50:51], s98, v88
	v_nop
	v_cndmask_b32_e64 v44, 0, v44, s[30:31]
	v_cndmask_b32_e64 v45, 0, v45, s[36:37]
	v_cndmask_b32_e64 v46, 0, v46, s[78:79]
	v_cndmask_b32_e64 v47, 0, v47, s[50:51]
	v_cvt_pk_bf16_f32 v64, v32, v33
	v_cvt_pk_bf16_f32 v65, v34, v35
	v_cvt_pk_bf16_f32 v66, v36, v37
	v_cvt_pk_bf16_f32 v67, v38, v39
	v_cvt_pk_bf16_f32 v68, v40, v41
	v_cvt_pk_bf16_f32 v69, v42, v43
	v_cvt_pk_bf16_f32 v70, v44, v45
	v_cvt_pk_bf16_f32 v71, v46, v47
	v_pk_add_f32 v[232:233], v[232:233], v[32:33]
	v_pk_add_f32 v[232:233], v[232:233], v[34:35]
	v_pk_add_f32 v[232:233], v[232:233], v[36:37]
	v_pk_add_f32 v[232:233], v[232:233], v[38:39]
	v_pk_add_f32 v[232:233], v[232:233], v[40:41]
	v_pk_add_f32 v[232:233], v[232:233], v[42:43]
	v_pk_add_f32 v[232:233], v[232:233], v[44:45]
	v_pk_add_f32 v[232:233], v[232:233], v[46:47]
	ds_read2_b32 v[32:33], v115 offset0:128 offset1:129
	ds_read2_b32 v[34:35], v115 offset0:130 offset1:131
	ds_read2_b32 v[36:37], v115 offset0:136 offset1:137
	ds_read2_b32 v[38:39], v115 offset0:138 offset1:139
	ds_read2_b32 v[40:41], v115 offset0:144 offset1:145
	ds_read2_b32 v[42:43], v115 offset0:146 offset1:147
	ds_read2_b32 v[44:45], v115 offset0:152 offset1:153
	ds_read2_b32 v[46:47], v115 offset0:154 offset1:155
	v_mfma_f32_32x32x16_bf16 v[0:15], v[64:67], v[72:75], v[0:15]
	v_mfma_f32_32x32x16_bf16 v[16:31], v[64:67], v[76:79], v[16:31]
	v_mfma_f32_32x32x16_bf16 v[0:15], v[68:71], v[220:223], v[0:15]
	v_mfma_f32_32x32x16_bf16 v[16:31], v[68:71], v[224:227], v[16:31]
	ds_read_b64_tr_b16 v[72:73], v231
	ds_read_b64_tr_b16 v[74:75], v231 offset:512
	ds_read_b64_tr_b16 v[76:77], v231 offset:2048
	ds_read_b64_tr_b16 v[78:79], v231 offset:2560
	ds_read_b64_tr_b16 v[220:221], v231 offset:1024
	ds_read_b64_tr_b16 v[222:223], v231 offset:1536
	ds_read_b64_tr_b16 v[224:225], v231 offset:3072
	ds_read_b64_tr_b16 v[226:227], v231 offset:3584
	v_exp_f32_e32 v188, v188
	v_exp_f32_e32 v189, v189
	v_exp_f32_e32 v190, v190
	v_exp_f32_e32 v191, v191
	s_waitcnt vmcnt(0)
	ds_write_b128 v247, v[116:119]
	ds_write_b128 v247, v[120:123] offset:1024
	ds_write_b128 v247, v[124:127] offset:2048
	ds_write_b128 v247, v[128:131] offset:3072
	ds_read_b128 v[116:119], v248
	ds_read_b128 v[120:123], v249
	ds_read_b128 v[124:127], v250
	ds_read_b128 v[128:131], v251
	ds_write_b128 v112, v[132:135]
	ds_write_b128 v112, v[136:139] offset:1024
	ds_write_b128 v112, v[140:143] offset:2048
	ds_write_b128 v112, v[144:147] offset:3072
	v_exp_f32_e32 v192, v192
	v_exp_f32_e32 v193, v193
	v_exp_f32_e32 v194, v194
	v_exp_f32_e32 v195, v195
	s_waitcnt lgkmcnt(4)
	v_mfma_f32_32x32x16_bf16 v[32:47], v[116:119], v[48:51], v[32:47]
	v_exp_f32_e32 v196, v196
	v_exp_f32_e32 v197, v197
	v_mfma_f32_32x32x16_bf16 v[32:47], v[120:123], v[52:55], v[32:47]
	v_exp_f32_e32 v198, v198
	v_exp_f32_e32 v199, v199
	v_mfma_f32_32x32x16_bf16 v[32:47], v[124:127], v[56:59], v[32:47]
	v_exp_f32_e32 v200, v200
	v_exp_f32_e32 v201, v201
	v_mfma_f32_32x32x16_bf16 v[32:47], v[128:131], v[60:63], v[32:47]
	v_exp_f32_e32 v202, v202
	v_exp_f32_e32 v203, v203
	s_add_i32 s90, s76, 512
	v_lshlrev_b32_e32 v84, 4, v107
	v_add_u32_e32 v84, s90, v84
	v_add_u32_e32 v85, 0, v84
	v_add_u32_e32 v86, 16, v84
	v_add_u32_e32 v87, 32, v84
	v_add_u32_e32 v88, 48, v84
	v_cmp_gt_u32_e64 s[30:31], s98, v85
	v_cmp_gt_u32_e64 s[36:37], s98, v86
	v_cmp_gt_u32_e64 s[78:79], s98, v87
	v_cmp_gt_u32_e64 s[50:51], s98, v88
	v_cndmask_b32_e64 v188, 0, v188, s[30:31]
	v_add_u32_e32 v85, 128, v84
	v_cmp_gt_u32_e64 s[30:31], s98, v85
	v_cndmask_b32_e64 v189, 0, v189, s[36:37]
	v_add_u32_e32 v86, 144, v84
	v_cmp_gt_u32_e64 s[36:37], s98, v86
	v_cndmask_b32_e64 v190, 0, v190, s[78:79]
	v_add_u32_e32 v87, 160, v84
	v_cmp_gt_u32_e64 s[78:79], s98, v87
	v_cndmask_b32_e64 v191, 0, v191, s[50:51]
	v_add_u32_e32 v88, 176, v84
	v_cmp_gt_u32_e64 s[50:51], s98, v88
	v_cndmask_b32_e64 v192, 0, v192, s[30:31]
	v_add_u32_e32 v85, 256, v84
	v_cmp_gt_u32_e64 s[30:31], s98, v85
	v_cndmask_b32_e64 v193, 0, v193, s[36:37]
	v_add_u32_e32 v86, 272, v84
	v_cmp_gt_u32_e64 s[36:37], s98, v86
	v_cndmask_b32_e64 v194, 0, v194, s[78:79]
	v_add_u32_e32 v87, 288, v84
	v_cmp_gt_u32_e64 s[78:79], s98, v87
	v_cndmask_b32_e64 v195, 0, v195, s[50:51]
	v_add_u32_e32 v88, 304, v84
	v_cmp_gt_u32_e64 s[50:51], s98, v88
	v_cndmask_b32_e64 v196, 0, v196, s[30:31]
	v_add_u32_e32 v85, 384, v84
	v_cmp_gt_u32_e64 s[30:31], s98, v85
	v_cndmask_b32_e64 v197, 0, v197, s[36:37]
	v_add_u32_e32 v86, 400, v84
	v_cmp_gt_u32_e64 s[36:37], s98, v86
	v_cndmask_b32_e64 v198, 0, v198, s[78:79]
	v_add_u32_e32 v87, 416, v84
	v_cmp_gt_u32_e64 s[78:79], s98, v87
	v_cndmask_b32_e64 v199, 0, v199, s[50:51]
	v_add_u32_e32 v88, 432, v84
	v_cmp_gt_u32_e64 s[50:51], s98, v88
	v_nop
	v_cndmask_b32_e64 v200, 0, v200, s[30:31]
	v_cndmask_b32_e64 v201, 0, v201, s[36:37]
	v_cndmask_b32_e64 v202, 0, v202, s[78:79]
	v_cndmask_b32_e64 v203, 0, v203, s[50:51]
	v_cvt_pk_bf16_f32 v64, v188, v189
	v_cvt_pk_bf16_f32 v65, v190, v191
	v_cvt_pk_bf16_f32 v66, v192, v193
	v_cvt_pk_bf16_f32 v67, v194, v195
	v_cvt_pk_bf16_f32 v68, v196, v197
	v_cvt_pk_bf16_f32 v69, v198, v199
	v_cvt_pk_bf16_f32 v70, v200, v201
	v_cvt_pk_bf16_f32 v71, v202, v203
	v_pk_add_f32 v[232:233], v[232:233], v[188:189]
	v_pk_add_f32 v[232:233], v[232:233], v[190:191]
	v_pk_add_f32 v[232:233], v[232:233], v[192:193]
	v_pk_add_f32 v[232:233], v[232:233], v[194:195]
	v_pk_add_f32 v[232:233], v[232:233], v[196:197]
	v_pk_add_f32 v[232:233], v[232:233], v[198:199]
	v_pk_add_f32 v[232:233], v[232:233], v[200:201]
	v_pk_add_f32 v[232:233], v[232:233], v[202:203]
	v_mfma_f32_32x32x16_bf16 v[0:15], v[64:67], v[72:75], v[0:15]
	v_mfma_f32_32x32x16_bf16 v[16:31], v[64:67], v[76:79], v[16:31]
	v_mfma_f32_32x32x16_bf16 v[0:15], v[68:71], v[220:223], v[0:15]
	v_mfma_f32_32x32x16_bf16 v[16:31], v[68:71], v[224:227], v[16:31]
	ds_read_b64_tr_b16 v[72:73], v231
	ds_read_b64_tr_b16 v[74:75], v231 offset:512
	ds_read_b64_tr_b16 v[76:77], v231 offset:2048
	ds_read_b64_tr_b16 v[78:79], v231 offset:2560
	ds_read_b64_tr_b16 v[220:221], v231 offset:1024
	ds_read_b64_tr_b16 v[222:223], v231 offset:1536
	ds_read_b64_tr_b16 v[224:225], v231 offset:3072
	ds_read_b64_tr_b16 v[226:227], v231 offset:3584
	s_waitcnt lgkmcnt(0)
; __device__ __forceinline__ int crow(int r, int hi) { return (r & 3) + 8 * (r >> 2) + 4 * hi; }
; __device__ __forceinline__ void dil_unit(LAS unsigned char* lds, bf16_t* proj, int seq, int hd, int T0, int rho) {
;     ...
;     l += __shfl_xor(l, 32);
; #pragma unroll
;     for (int rr = 0; rr < 16; ++rr) {
;         const int j = crow(rr, hi);
;         const float il = __builtin_amdgcn_rcpf(__shfl(l, j));
	v_exp_f32_e32 v32, v32
	v_exp_f32_e32 v33, v33
	v_exp_f32_e32 v34, v34
	v_exp_f32_e32 v35, v35
	v_exp_f32_e32 v36, v36
	v_exp_f32_e32 v37, v37
	v_exp_f32_e32 v38, v38
	v_exp_f32_e32 v39, v39
	v_exp_f32_e32 v40, v40
	v_exp_f32_e32 v41, v41
	v_exp_f32_e32 v42, v42
	v_exp_f32_e32 v43, v43
	v_exp_f32_e32 v44, v44
	v_exp_f32_e32 v45, v45
	v_exp_f32_e32 v46, v46
	v_exp_f32_e32 v47, v47
	s_add_i32 s90, s76, 1024
	v_lshlrev_b32_e32 v84, 4, v107
	v_add_u32_e32 v84, s90, v84
	v_add_u32_e32 v85, 0, v84
	v_add_u32_e32 v86, 16, v84
	v_add_u32_e32 v87, 32, v84
	v_add_u32_e32 v88, 48, v84
	v_cmp_gt_u32_e64 s[30:31], s98, v85
	v_cmp_gt_u32_e64 s[36:37], s98, v86
	v_cmp_gt_u32_e64 s[78:79], s98, v87
	v_cmp_gt_u32_e64 s[50:51], s98, v88
	v_cndmask_b32_e64 v32, 0, v32, s[30:31]
	v_add_u32_e32 v85, 128, v84
	v_cmp_gt_u32_e64 s[30:31], s98, v85
	v_cndmask_b32_e64 v33, 0, v33, s[36:37]
	v_add_u32_e32 v86, 144, v84
	v_cmp_gt_u32_e64 s[36:37], s98, v86
	v_cndmask_b32_e64 v34, 0, v34, s[78:79]
	v_add_u32_e32 v87, 160, v84
	v_cmp_gt_u32_e64 s[78:79], s98, v87
	v_cndmask_b32_e64 v35, 0, v35, s[50:51]
	v_add_u32_e32 v88, 176, v84
	v_cmp_gt_u32_e64 s[50:51], s98, v88
	v_cndmask_b32_e64 v36, 0, v36, s[30:31]
	v_add_u32_e32 v85, 256, v84
	v_cmp_gt_u32_e64 s[30:31], s98, v85
	v_cndmask_b32_e64 v37, 0, v37, s[36:37]
	v_add_u32_e32 v86, 272, v84
	v_cmp_gt_u32_e64 s[36:37], s98, v86
	v_cndmask_b32_e64 v38, 0, v38, s[78:79]
	v_add_u32_e32 v87, 288, v84
	v_cmp_gt_u32_e64 s[78:79], s98, v87
	v_cndmask_b32_e64 v39, 0, v39, s[50:51]
	v_add_u32_e32 v88, 304, v84
	v_cmp_gt_u32_e64 s[50:51], s98, v88
	v_cndmask_b32_e64 v40, 0, v40, s[30:31]
	v_add_u32_e32 v85, 384, v84
	v_cmp_gt_u32_e64 s[30:31], s98, v85
	v_cndmask_b32_e64 v41, 0, v41, s[36:37]
	v_add_u32_e32 v86, 400, v84
	v_cmp_gt_u32_e64 s[36:37], s98, v86
	v_cndmask_b32_e64 v42, 0, v42, s[78:79]
	v_add_u32_e32 v87, 416, v84
	v_cmp_gt_u32_e64 s[78:79], s98, v87
	v_cndmask_b32_e64 v43, 0, v43, s[50:51]
	v_add_u32_e32 v88, 432, v84
	v_cmp_gt_u32_e64 s[50:51], s98, v88
	v_nop
	v_cndmask_b32_e64 v44, 0, v44, s[30:31]
	v_cndmask_b32_e64 v45, 0, v45, s[36:37]
	v_cndmask_b32_e64 v46, 0, v46, s[78:79]
	v_cndmask_b32_e64 v47, 0, v47, s[50:51]
	v_cvt_pk_bf16_f32 v64, v32, v33
	v_cvt_pk_bf16_f32 v65, v34, v35
	v_cvt_pk_bf16_f32 v66, v36, v37
	v_cvt_pk_bf16_f32 v67, v38, v39
	v_cvt_pk_bf16_f32 v68, v40, v41
	v_cvt_pk_bf16_f32 v69, v42, v43
	v_cvt_pk_bf16_f32 v70, v44, v45
	v_cvt_pk_bf16_f32 v71, v46, v47
	v_pk_add_f32 v[232:233], v[232:233], v[32:33]
	v_pk_add_f32 v[232:233], v[232:233], v[34:35]
	v_pk_add_f32 v[232:233], v[232:233], v[36:37]
	v_pk_add_f32 v[232:233], v[232:233], v[38:39]
	v_pk_add_f32 v[232:233], v[232:233], v[40:41]
	v_pk_add_f32 v[232:233], v[232:233], v[42:43]
	v_pk_add_f32 v[232:233], v[232:233], v[44:45]
	v_pk_add_f32 v[232:233], v[232:233], v[46:47]
	v_mfma_f32_32x32x16_bf16 v[0:15], v[64:67], v[72:75], v[0:15]
	v_mfma_f32_32x32x16_bf16 v[16:31], v[64:67], v[76:79], v[16:31]
	v_mfma_f32_32x32x16_bf16 v[0:15], v[68:71], v[220:223], v[0:15]
	v_mfma_f32_32x32x16_bf16 v[16:31], v[68:71], v[224:227], v[16:31]
	v_add_f32_e32 v113, v232, v233
	v_or_b32_e32 v114, 1, v107
	v_or_b32_e32 v97, 2, v107
	v_or_b32_e32 v96, 3, v107
	v_or_b32_e32 v95, 8, v107
	v_or_b32_e32 v94, 9, v107
	v_or_b32_e32 v93, 10, v107
	v_or_b32_e32 v92, 11, v107
	v_or_b32_e32 v91, 16, v107
	v_or_b32_e32 v90, 17, v107
	v_or_b32_e32 v89, 18, v107
	v_or_b32_e32 v88, 19, v107
	v_or_b32_e32 v87, 24, v107
	v_or_b32_e32 v86, 25, v107
	v_or_b32_e32 v85, 26, v107
	v_or_b32_e32 v84, 27, v107
	s_nop 11
	s_branch .LBB0_553

; #define LAS __attribute__((address_space(3)))
; #define GAS __attribute__((address_space(1)))
; __device__ __forceinline__ void dil_unit(LAS unsigned char* lds, bf16_t* proj, int seq, int hd, int T0, int rho) {
;     int tid_ = threadIdx.x; asm volatile("" : "+v"(tid_));
;     const int tid = tid_, lane = tid & 63, r32 = lane & 31, hi = lane >> 5, wid = __builtin_amdgcn_readfirstlane(tid >> 6);
;     bf16_t* base = proj + (size_t)seq * SEQ * NIN;
;     LAS unsigned char* wbuf = lds + wid * 4096;
;     const LAS unsigned char* vp = wbuf + ((lane >> 4) & 1) * 32 + (lane & 3) * 8 + (4 * hi + ((lane & 15) >> 2)) * 64;
;     const int P0 = T0 + rho;
;     bf16x8 qr[4];
; #pragma unroll
;     for (int ks = 0; ks < 4; ++ks) qr[ks] = *(const GAS bf16x8*)(base + (size_t)(P0 + 16 * r32) * NIN + PC_LQ + hd * 64 + 16 * ks + 8 * hi);
;     f32x16 o0 = {}, o1 = {}; float l = 0.f;
;     const bool bound = (T0 < 1024) || (T0 >= 15360);
.LBB0_1266:
	s_lshr_b32 s82, s60, 8
	s_mul_i32 s82, s82, 13
	s_add_i32 s82, s82, s60
	s_ashr_i32 s4, s60, 6
	s_mul_hi_i32 s9, s4, 0x2aaaaaab
	s_lshl_b32 s5, s82, 8
	s_lshr_b32 s10, s9, 31
	s_and_b32 s8, s5, 0x3e00
	s_lshl_b32 s5, s82, 3
	s_add_i32 s9, s9, s10
	s_and_b32 s5, s5, 8
	s_mul_i32 s10, s9, 6
	s_add_i32 s5, s5, s61
	s_sub_i32 s10, s4, s10
	s_mul_hi_i32 s4, s9, 0x6000000
	s_mul_i32 s9, s9, 0x6000000
	v_mov_b32_e32 v2, v154
	s_add_u32 s52, s44, s9
	s_addc_u32 s53, s45, s4
	v_and_b32_e32 v105, 31, v2
	s_add_i32 s67, s5, s8
	v_lshl_add_u32 v3, v105, 4, s67
	v_mov_b64_e32 v[0:1], s[52:53]
	s_lshl_b32 s54, s10, 6
	v_bfe_u32 v106, v2, 5, 1
	v_mad_u64_u32 v[0:1], s[4:5], v3, s62, v[0:1]
	s_ashr_i32 s55, s54, 31
	v_lshl_add_u64 v[0:1], s[54:55], 1, v[0:1]
	v_lshlrev_b32_e32 v80, 4, v106
	v_lshl_add_u64 v[0:1], v[0:1], 0, v[80:81]
	global_load_dwordx4 v[48:51], v[0:1], off offset:1280
	global_load_dwordx4 v[52:55], v[0:1], off offset:1312
	global_load_dwordx4 v[56:59], v[0:1], off offset:1344
	global_load_dwordx4 v[60:63], v[0:1], off offset:1376
	v_readfirstlane_b32 s4, v2
	s_lshl_b32 s4, s4, 6
	s_and_b32 s4, s4, 0xfffff000
	v_lshlrev_b32_e32 v0, 1, v2
	v_lshlrev_b32_e32 v104, 3, v2
	v_lshlrev_b32_e32 v107, 2, v106
	v_lshrrev_b32_e32 v1, 2, v2
	v_and_b32_e32 v103, 63, v2
	v_and_b32_e32 v0, 32, v0
	v_and_b32_e32 v98, 24, v104
	v_and_or_b32 v1, v1, 3, v107
	s_add_i32 s69, s4, 0
	v_lshlrev_b32_e32 v108, 6, v1
	v_lshlrev_b32_e32 v1, 3, v106
	v_add3_u32 v109, s69, v0, v98
	s_addk_i32 s8, 0xc400
	v_lshrrev_b32_e32 v110, 2, v103
	v_lshlrev_b32_e32 v0, 4, v103
	s_mov_b64 s[4:5], -1
	s_cmp_gt_u32 s8, 0xffffc7ff
	v_lshlrev_b32_e32 v100, 1, v98
	s_mul_i32 s8, s10, 0x1c00
	v_lshlrev_b32_e32 v82, 1, v1
	v_or_b32_e32 v111, 16, v110
	v_add_u32_e32 v112, s69, v0
	s_cbranch_scc0 .LBB0_1270
	s_movk_i32 s100, 0x1800
	s_add_i32 s101, s8, 0x15c00
	s_lshl_b32 s90, s54, 1
	s_add_u32 s82, s52, s90
	s_addc_u32 s83, s53, 0
	s_add_u32 s82, s82, 0x1200
	s_addc_u32 s83, s83, 0
	s_sub_i32 s90, s67, 64
	s_mul_i32 s90, s90, 0x1800
	s_add_u32 s84, s82, s90
	s_addc_u32 s85, s83, 0
	s_sub_i32 s90, s67, 256
	s_mul_i32 s90, s90, 0x1800
	s_add_u32 s86, s82, s90
	s_addc_u32 s87, s83, 0
	s_sub_i32 s90, s67, 1024
	s_mul_i32 s90, s90, 0x1800
	s_add_u32 s88, s82, s90
	s_addc_u32 s89, s83, 0
	v_lshlrev_b32_e32 v153, 1, v98
	v_mad_u32_u24 v80, v105, s100, v82
	v_mad_u32_u24 v100, v110, s100, v153
	v_add_u32_e32 v149, 0x18000, v100
	v_lshlrev_b32_e32 v83, 2, v105
	v_mad_u32_u24 v83, v83, s100, v82
	v_lshlrev_b32_e32 v101, 2, v110
	v_mad_u32_u24 v101, v101, s100, v153
	v_add_u32_e32 v150, 0x60000, v101
	v_lshlrev_b32_e32 v99, 4, v105
	v_mad_u32_u24 v99, v99, s100, v82
	v_lshlrev_b32_e32 v148, 4, v110
	v_mad_u32_u24 v148, v148, s100, v153
	v_add_u32_e32 v151, 0x180000, v148
	v_lshrrev_b32_e32 v249, 3, v103
	v_and_b32_e32 v250, 7, v103
	v_lshlrev_b32_e32 v250, 4, v250
	v_add_u32_e32 v235, 0, v249
	v_mad_u32_u24 v235, v235, s100, v250
	v_add_u32_e32 v236, 8, v249
	v_mad_u32_u24 v236, v236, s100, v250
	v_add_u32_e32 v237, 16, v249
	v_mad_u32_u24 v237, v237, s100, v250
	v_add_u32_e32 v238, 24, v249
	v_mad_u32_u24 v238, v238, s100, v250
	v_add_u32_e32 v239, 0, v249
	v_lshlrev_b32_e32 v239, 2, v239
	v_mad_u32_u24 v239, v239, s100, v250
	v_add_u32_e32 v240, 8, v249
	v_lshlrev_b32_e32 v240, 2, v240
	v_mad_u32_u24 v240, v240, s100, v250
	v_add_u32_e32 v241, 16, v249
	v_lshlrev_b32_e32 v241, 2, v241
	v_mad_u32_u24 v241, v241, s100, v250
	v_add_u32_e32 v242, 24, v249
	v_lshlrev_b32_e32 v242, 2, v242
	v_mad_u32_u24 v242, v242, s100, v250
	v_add_u32_e32 v243, 0, v249
	v_lshlrev_b32_e32 v243, 4, v243
	v_mad_u32_u24 v243, v243, s100, v250
	v_add_u32_e32 v244, 8, v249
	v_lshlrev_b32_e32 v244, 4, v244
	v_mad_u32_u24 v244, v244, s100, v250
	v_add_u32_e32 v245, 16, v249
	v_lshlrev_b32_e32 v245, 4, v245
	v_mad_u32_u24 v245, v245, s100, v250
	v_add_u32_e32 v246, 24, v249
	v_lshlrev_b32_e32 v246, 4, v246
	v_mad_u32_u24 v246, v246, s100, v250
	v_and_b32_e32 v247, 7, v249
	v_lshlrev_b32_e32 v247, 4, v247
	v_xor_b32_e32 v247, v247, v112
	v_and_b32_e32 v153, 7, v105
	v_or_b32_e32 v248, 0, v106
	v_xor_b32_e32 v248, v248, v153
	v_lshlrev_b32_e32 v248, 4, v248
	v_lshl_add_u32 v248, v105, 7, v248
	v_add_u32_e32 v248, s69, v248
	v_or_b32_e32 v249, 2, v106
	v_xor_b32_e32 v249, v249, v153
	v_lshlrev_b32_e32 v249, 4, v249
	v_lshl_add_u32 v249, v105, 7, v249
	v_add_u32_e32 v249, s69, v249
	v_or_b32_e32 v250, 4, v106
	v_xor_b32_e32 v250, v250, v153
	v_lshlrev_b32_e32 v250, 4, v250
	v_lshl_add_u32 v250, v105, 7, v250
	v_add_u32_e32 v250, s69, v250
	v_or_b32_e32 v251, 6, v106
	v_xor_b32_e32 v251, v251, v153
	v_lshlrev_b32_e32 v251, 4, v251
	v_lshl_add_u32 v251, v105, 7, v251
	v_add_u32_e32 v251, s69, v251
	v_lshlrev_b32_e32 v153, 1, v98
	v_mul_u32_u24_e32 v228, 17, v105
	v_sub_u32_e32 v228, v107, v228
	s_mul_i32 s90, s54, 153
	s_lshr_b32 s90, s90, 1
	s_add_i32 s90, s90, 34876
	v_lshl_add_u32 v228, v228, 2, s90
	v_lshlrev_b32_e32 v229, 2, v105
	v_sub_u32_e32 v229, v107, v229
	s_add_i32 s90, s101, 5104
	v_lshl_add_u32 v229, v229, 2, s90
	v_sub_u32_e32 v230, v107, v105
	s_add_i32 s90, s101, 6364
	v_lshl_add_u32 v230, v230, 2, s90
	v_add_u32_e32 v231, v109, v108
	v_mov_b64_e32 v[232:233], 0
	v_mov_b64_e32 v[0:1], 0
	v_mov_b64_e32 v[2:3], 0
	v_mov_b64_e32 v[4:5], 0
	v_mov_b64_e32 v[6:7], 0
	v_mov_b64_e32 v[8:9], 0
	v_mov_b64_e32 v[10:11], 0
	v_mov_b64_e32 v[12:13], 0
	v_mov_b64_e32 v[14:15], 0
	v_mov_b64_e32 v[16:17], 0
	v_mov_b64_e32 v[18:19], 0
	v_mov_b64_e32 v[20:21], 0
	v_mov_b64_e32 v[22:23], 0
	v_mov_b64_e32 v[24:25], 0
	v_mov_b64_e32 v[26:27], 0
	v_mov_b64_e32 v[28:29], 0
	v_mov_b64_e32 v[30:31], 0
	global_load_dwordx4 v[116:119], v235, s[84:85]
	global_load_dwordx4 v[120:123], v236, s[84:85]
	global_load_dwordx4 v[124:127], v237, s[84:85]
	global_load_dwordx4 v[128:131], v238, s[84:85]
	global_load_dwordx4 v[132:135], v100, s[84:85] offset:768
	global_load_dwordx4 v[136:139], v149, s[84:85] offset:768
	global_load_dwordx4 v[140:143], v100, s[84:85] offset:832
	global_load_dwordx4 v[144:147], v149, s[84:85] offset:832
	s_add_u32 s84, s84, 0x30000
	s_addc_u32 s85, s85, 0
	global_load_dwordx4 v[156:159], v235, s[84:85]
	global_load_dwordx4 v[160:163], v236, s[84:85]
	global_load_dwordx4 v[164:167], v237, s[84:85]
	global_load_dwordx4 v[168:171], v238, s[84:85]
	global_load_dwordx4 v[172:175], v100, s[84:85] offset:768
	global_load_dwordx4 v[176:179], v149, s[84:85] offset:768
	global_load_dwordx4 v[180:183], v100, s[84:85] offset:832
	global_load_dwordx4 v[184:187], v149, s[84:85] offset:832
	s_add_u32 s84, s84, 0x30000
	s_addc_u32 s85, s85, 0
	v_mov_b32_e32 v115, v228
	ds_read2_b32 v[32:33], v115 offset0:0 offset1:1
	ds_read2_b32 v[34:35], v115 offset0:2 offset1:3
	ds_read2_b32 v[36:37], v115 offset0:8 offset1:9
	ds_read2_b32 v[38:39], v115 offset0:10 offset1:11
	ds_read2_b32 v[40:41], v115 offset0:17 offset1:18
	ds_read2_b32 v[42:43], v115 offset0:19 offset1:20
	ds_read2_b32 v[44:45], v115 offset0:25 offset1:26
	ds_read2_b32 v[46:47], v115 offset0:27 offset1:28
	s_waitcnt vmcnt(8)
	ds_write_b128 v247, v[116:119]
	ds_write_b128 v247, v[120:123] offset:1024
	ds_write_b128 v247, v[124:127] offset:2048
	ds_write_b128 v247, v[128:131] offset:3072
	ds_read_b128 v[116:119], v248
	ds_read_b128 v[120:123], v249
	ds_read_b128 v[124:127], v250
	ds_read_b128 v[128:131], v251
	ds_write_b128 v112, v[132:135]
	ds_write_b128 v112, v[136:139] offset:1024
	ds_write_b128 v112, v[140:143] offset:2048
	ds_write_b128 v112, v[144:147] offset:3072
	s_waitcnt lgkmcnt(4)
	v_mfma_f32_32x32x16_bf16 v[32:47], v[116:119], v[48:51], v[32:47]
	v_mfma_f32_32x32x16_bf16 v[32:47], v[120:123], v[52:55], v[32:47]
	v_mfma_f32_32x32x16_bf16 v[32:47], v[124:127], v[56:59], v[32:47]
	v_mfma_f32_32x32x16_bf16 v[32:47], v[128:131], v[60:63], v[32:47]
	ds_read2_b32 v[188:189], v115 offset0:34 offset1:35
	ds_read2_b32 v[190:191], v115 offset0:36 offset1:37
	ds_read2_b32 v[192:193], v115 offset0:42 offset1:43
	ds_read2_b32 v[194:195], v115 offset0:44 offset1:45
	ds_read2_b32 v[196:197], v115 offset0:51 offset1:52
	ds_read2_b32 v[198:199], v115 offset0:53 offset1:54
	ds_read2_b32 v[200:201], v115 offset0:59 offset1:60
	ds_read2_b32 v[202:203], v115 offset0:61 offset1:62
	global_load_dwordx4 v[116:119], v235, s[84:85]
	global_load_dwordx4 v[120:123], v236, s[84:85]
	global_load_dwordx4 v[124:127], v237, s[84:85]
	global_load_dwordx4 v[128:131], v238, s[84:85]
	global_load_dwordx4 v[132:135], v100, s[84:85] offset:768
	global_load_dwordx4 v[136:139], v149, s[84:85] offset:768
	global_load_dwordx4 v[140:143], v100, s[84:85] offset:832
	global_load_dwordx4 v[144:147], v149, s[84:85] offset:832
	s_add_u32 s84, s84, 0x30000
	s_addc_u32 s85, s85, 0
	ds_read_b64_tr_b16 v[72:73], v231
	ds_read_b64_tr_b16 v[74:75], v231 offset:512
	ds_read_b64_tr_b16 v[76:77], v231 offset:2048
	ds_read_b64_tr_b16 v[78:79], v231 offset:2560
	ds_read_b64_tr_b16 v[220:221], v231 offset:1024
	ds_read_b64_tr_b16 v[222:223], v231 offset:1536
	ds_read_b64_tr_b16 v[224:225], v231 offset:3072
	ds_read_b64_tr_b16 v[226:227], v231 offset:3584
	v_exp_f32_e32 v32, v32
	v_exp_f32_e32 v33, v33
	v_exp_f32_e32 v34, v34
	v_exp_f32_e32 v35, v35
	s_waitcnt vmcnt(8)
	ds_write_b128 v247, v[156:159]
	ds_write_b128 v247, v[160:163] offset:1024
	ds_write_b128 v247, v[164:167] offset:2048
	ds_write_b128 v247, v[168:171] offset:3072
	ds_read_b128 v[156:159], v248
	ds_read_b128 v[160:163], v249
	ds_read_b128 v[164:167], v250
	ds_read_b128 v[168:171], v251
	ds_write_b128 v112, v[172:175]
	ds_write_b128 v112, v[176:179] offset:1024
	ds_write_b128 v112, v[180:183] offset:2048
	ds_write_b128 v112, v[184:187] offset:3072
	v_exp_f32_e32 v36, v36
	v_exp_f32_e32 v37, v37
	v_exp_f32_e32 v38, v38
	v_exp_f32_e32 v39, v39
	s_waitcnt lgkmcnt(4)
	v_mfma_f32_32x32x16_bf16 v[188:203], v[156:159], v[48:51], v[188:203]
	v_exp_f32_e32 v40, v40
	v_exp_f32_e32 v41, v41
	v_mfma_f32_32x32x16_bf16 v[188:203], v[160:163], v[52:55], v[188:203]
	v_exp_f32_e32 v42, v42
	v_exp_f32_e32 v43, v43
	v_mfma_f32_32x32x16_bf16 v[188:203], v[164:167], v[56:59], v[188:203]
	v_exp_f32_e32 v44, v44
	v_exp_f32_e32 v45, v45
	v_mfma_f32_32x32x16_bf16 v[188:203], v[168:171], v[60:63], v[188:203]
	v_exp_f32_e32 v46, v46
	v_exp_f32_e32 v47, v47
	v_cvt_pk_bf16_f32 v64, v32, v33
	v_cvt_pk_bf16_f32 v65, v34, v35
	v_cvt_pk_bf16_f32 v66, v36, v37
	v_cvt_pk_bf16_f32 v67, v38, v39
	v_cvt_pk_bf16_f32 v68, v40, v41
	v_cvt_pk_bf16_f32 v69, v42, v43
	v_cvt_pk_bf16_f32 v70, v44, v45
	v_cvt_pk_bf16_f32 v71, v46, v47
	v_pk_add_f32 v[232:233], v[232:233], v[32:33]
	v_pk_add_f32 v[232:233], v[232:233], v[34:35]
	v_pk_add_f32 v[232:233], v[232:233], v[36:37]
	v_pk_add_f32 v[232:233], v[232:233], v[38:39]
	v_pk_add_f32 v[232:233], v[232:233], v[40:41]
	v_pk_add_f32 v[232:233], v[232:233], v[42:43]
	v_pk_add_f32 v[232:233], v[232:233], v[44:45]
	v_pk_add_f32 v[232:233], v[232:233], v[46:47]
	ds_read2_b32 v[32:33], v115 offset0:68 offset1:69
	ds_read2_b32 v[34:35], v115 offset0:70 offset1:71
	ds_read2_b32 v[36:37], v115 offset0:76 offset1:77
	ds_read2_b32 v[38:39], v115 offset0:78 offset1:79
	ds_read2_b32 v[40:41], v115 offset0:85 offset1:86
	ds_read2_b32 v[42:43], v115 offset0:87 offset1:88
	ds_read2_b32 v[44:45], v115 offset0:93 offset1:94
	ds_read2_b32 v[46:47], v115 offset0:95 offset1:96
	v_mfma_f32_32x32x16_bf16 v[0:15], v[64:67], v[72:75], v[0:15]
	v_mfma_f32_32x32x16_bf16 v[16:31], v[64:67], v[76:79], v[16:31]
	v_mfma_f32_32x32x16_bf16 v[0:15], v[68:71], v[220:223], v[0:15]
	v_mfma_f32_32x32x16_bf16 v[16:31], v[68:71], v[224:227], v[16:31]
	global_load_dwordx4 v[156:159], v235, s[84:85]
	global_load_dwordx4 v[160:163], v236, s[84:85]
	global_load_dwordx4 v[164:167], v237, s[84:85]
	global_load_dwordx4 v[168:171], v238, s[84:85]
	global_load_dwordx4 v[172:175], v100, s[84:85] offset:768
	global_load_dwordx4 v[176:179], v149, s[84:85] offset:768
	global_load_dwordx4 v[180:183], v100, s[84:85] offset:832
	global_load_dwordx4 v[184:187], v149, s[84:85] offset:832
	s_add_u32 s84, s84, 0x30000
	s_addc_u32 s85, s85, 0
	ds_read_b64_tr_b16 v[72:73], v231
	ds_read_b64_tr_b16 v[74:75], v231 offset:512
	ds_read_b64_tr_b16 v[76:77], v231 offset:2048
	ds_read_b64_tr_b16 v[78:79], v231 offset:2560
	ds_read_b64_tr_b16 v[220:221], v231 offset:1024
	ds_read_b64_tr_b16 v[222:223], v231 offset:1536
	ds_read_b64_tr_b16 v[224:225], v231 offset:3072
	ds_read_b64_tr_b16 v[226:227], v231 offset:3584
	v_exp_f32_e32 v188, v188
	v_exp_f32_e32 v189, v189
	v_exp_f32_e32 v190, v190
	v_exp_f32_e32 v191, v191
	s_waitcnt vmcnt(8)
	ds_write_b128 v247, v[116:119]
	ds_write_b128 v247, v[120:123] offset:1024
	ds_write_b128 v247, v[124:127] offset:2048
	ds_write_b128 v247, v[128:131] offset:3072
	ds_read_b128 v[116:119], v248
	ds_read_b128 v[120:123], v249
	ds_read_b128 v[124:127], v250
	ds_read_b128 v[128:131], v251
	ds_write_b128 v112, v[132:135]
	ds_write_b128 v112, v[136:139] offset:1024
	ds_write_b128 v112, v[140:143] offset:2048
	ds_write_b128 v112, v[144:147] offset:3072
	v_exp_f32_e32 v192, v192
	v_exp_f32_e32 v193, v193
	v_exp_f32_e32 v194, v194
	v_exp_f32_e32 v195, v195
	s_waitcnt lgkmcnt(4)
	v_mfma_f32_32x32x16_bf16 v[32:47], v[116:119], v[48:51], v[32:47]
	v_exp_f32_e32 v196, v196
	v_exp_f32_e32 v197, v197
	v_mfma_f32_32x32x16_bf16 v[32:47], v[120:123], v[52:55], v[32:47]
	v_exp_f32_e32 v198, v198
	v_exp_f32_e32 v199, v199
	v_mfma_f32_32x32x16_bf16 v[32:47], v[124:127], v[56:59], v[32:47]
	v_exp_f32_e32 v200, v200
	v_exp_f32_e32 v201, v201
	v_mfma_f32_32x32x16_bf16 v[32:47], v[128:131], v[60:63], v[32:47]
	v_exp_f32_e32 v202, v202
	v_exp_f32_e32 v203, v203
	v_cvt_pk_bf16_f32 v64, v188, v189
	v_cvt_pk_bf16_f32 v65, v190, v191
	v_cvt_pk_bf16_f32 v66, v192, v193
	v_cvt_pk_bf16_f32 v67, v194, v195
	v_cvt_pk_bf16_f32 v68, v196, v197
	v_cvt_pk_bf16_f32 v69, v198, v199
	v_cvt_pk_bf16_f32 v70, v200, v201
	v_cvt_pk_bf16_f32 v71, v202, v203
	v_pk_add_f32 v[232:233], v[232:233], v[188:189]
	v_pk_add_f32 v[232:233], v[232:233], v[190:191]
	v_pk_add_f32 v[232:233], v[232:233], v[192:193]
	v_pk_add_f32 v[232:233], v[232:233], v[194:195]
	v_pk_add_f32 v[232:233], v[232:233], v[196:197]
	v_pk_add_f32 v[232:233], v[232:233], v[198:199]
	v_pk_add_f32 v[232:233], v[232:233], v[200:201]
	v_pk_add_f32 v[232:233], v[232:233], v[202:203]
	ds_read2_b32 v[188:189], v115 offset0:102 offset1:103
	ds_read2_b32 v[190:191], v115 offset0:104 offset1:105
	ds_read2_b32 v[192:193], v115 offset0:110 offset1:111
	ds_read2_b32 v[194:195], v115 offset0:112 offset1:113
	ds_read2_b32 v[196:197], v115 offset0:119 offset1:120
	ds_read2_b32 v[198:199], v115 offset0:121 offset1:122
	ds_read2_b32 v[200:201], v115 offset0:127 offset1:128
	ds_read2_b32 v[202:203], v115 offset0:129 offset1:130
	v_mfma_f32_32x32x16_bf16 v[0:15], v[64:67], v[72:75], v[0:15]
	v_mfma_f32_32x32x16_bf16 v[16:31], v[64:67], v[76:79], v[16:31]
	v_mfma_f32_32x32x16_bf16 v[0:15], v[68:71], v[220:223], v[0:15]
	v_mfma_f32_32x32x16_bf16 v[16:31], v[68:71], v[224:227], v[16:31]
	global_load_dwordx4 v[116:119], v235, s[84:85]
	global_load_dwordx4 v[120:123], v236, s[84:85]
	global_load_dwordx4 v[124:127], v237, s[84:85]
	global_load_dwordx4 v[128:131], v238, s[84:85]
	global_load_dwordx4 v[132:135], v100, s[84:85] offset:768
	global_load_dwordx4 v[136:139], v149, s[84:85] offset:768
	global_load_dwordx4 v[140:143], v100, s[84:85] offset:832
	global_load_dwordx4 v[144:147], v149, s[84:85] offset:832
	s_add_u32 s84, s84, 0x30000
	s_addc_u32 s85, s85, 0
	ds_read_b64_tr_b16 v[72:73], v231
	ds_read_b64_tr_b16 v[74:75], v231 offset:512
	ds_read_b64_tr_b16 v[76:77], v231 offset:2048
	ds_read_b64_tr_b16 v[78:79], v231 offset:2560
	ds_read_b64_tr_b16 v[220:221], v231 offset:1024
	ds_read_b64_tr_b16 v[222:223], v231 offset:1536
	ds_read_b64_tr_b16 v[224:225], v231 offset:3072
	ds_read_b64_tr_b16 v[226:227], v231 offset:3584
	v_exp_f32_e32 v32, v32
	v_exp_f32_e32 v33, v33
	v_exp_f32_e32 v34, v34
	v_exp_f32_e32 v35, v35
	s_waitcnt vmcnt(8)
	ds_write_b128 v247, v[156:159]
	ds_write_b128 v247, v[160:163] offset:1024
	ds_write_b128 v247, v[164:167] offset:2048
	ds_write_b128 v247, v[168:171] offset:3072
	ds_read_b128 v[156:159], v248
	ds_read_b128 v[160:163], v249
	ds_read_b128 v[164:167], v250
	ds_read_b128 v[168:171], v251
	ds_write_b128 v112, v[172:175]
	ds_write_b128 v112, v[176:179] offset:1024
	ds_write_b128 v112, v[180:183] offset:2048
	ds_write_b128 v112, v[184:187] offset:3072
	v_exp_f32_e32 v36, v36
	v_exp_f32_e32 v37, v37
	v_exp_f32_e32 v38, v38
	v_exp_f32_e32 v39, v39
	s_waitcnt lgkmcnt(4)
	v_mfma_f32_32x32x16_bf16 v[188:203], v[156:159], v[48:51], v[188:203]
	v_exp_f32_e32 v40, v40
	v_exp_f32_e32 v41, v41
	v_mfma_f32_32x32x16_bf16 v[188:203], v[160:163], v[52:55], v[188:203]
	v_exp_f32_e32 v42, v42
	v_exp_f32_e32 v43, v43
	v_mfma_f32_32x32x16_bf16 v[188:203], v[164:167], v[56:59], v[188:203]
	v_exp_f32_e32 v44, v44
	v_exp_f32_e32 v45, v45
	v_mfma_f32_32x32x16_bf16 v[188:203], v[168:171], v[60:63], v[188:203]
	v_exp_f32_e32 v46, v46
	v_exp_f32_e32 v47, v47
	v_cvt_pk_bf16_f32 v64, v32, v33
	v_cvt_pk_bf16_f32 v65, v34, v35
	v_cvt_pk_bf16_f32 v66, v36, v37
	v_cvt_pk_bf16_f32 v67, v38, v39
	v_cvt_pk_bf16_f32 v68, v40, v41
	v_cvt_pk_bf16_f32 v69, v42, v43
	v_cvt_pk_bf16_f32 v70, v44, v45
	v_cvt_pk_bf16_f32 v71, v46, v47
	v_pk_add_f32 v[232:233], v[232:233], v[32:33]
	v_pk_add_f32 v[232:233], v[232:233], v[34:35]
	v_pk_add_f32 v[232:233], v[232:233], v[36:37]
	v_pk_add_f32 v[232:233], v[232:233], v[38:39]
	v_pk_add_f32 v[232:233], v[232:233], v[40:41]
	v_pk_add_f32 v[232:233], v[232:233], v[42:43]
	v_pk_add_f32 v[232:233], v[232:233], v[44:45]
	v_pk_add_f32 v[232:233], v[232:233], v[46:47]
	ds_read2_b32 v[32:33], v115 offset0:136 offset1:137
	ds_read2_b32 v[34:35], v115 offset0:138 offset1:139
	ds_read2_b32 v[36:37], v115 offset0:144 offset1:145
	ds_read2_b32 v[38:39], v115 offset0:146 offset1:147
	ds_read2_b32 v[40:41], v115 offset0:153 offset1:154
	ds_read2_b32 v[42:43], v115 offset0:155 offset1:156
	ds_read2_b32 v[44:45], v115 offset0:161 offset1:162
	ds_read2_b32 v[46:47], v115 offset0:163 offset1:164
	v_mfma_f32_32x32x16_bf16 v[0:15], v[64:67], v[72:75], v[0:15]
	v_mfma_f32_32x32x16_bf16 v[16:31], v[64:67], v[76:79], v[16:31]
	v_mfma_f32_32x32x16_bf16 v[0:15], v[68:71], v[220:223], v[0:15]
	v_mfma_f32_32x32x16_bf16 v[16:31], v[68:71], v[224:227], v[16:31]
	global_load_dwordx4 v[156:159], v235, s[84:85]
	global_load_dwordx4 v[160:163], v236, s[84:85]
	global_load_dwordx4 v[164:167], v237, s[84:85]
	global_load_dwordx4 v[168:171], v238, s[84:85]
	global_load_dwordx4 v[172:175], v100, s[84:85] offset:768
	global_load_dwordx4 v[176:179], v149, s[84:85] offset:768
	global_load_dwordx4 v[180:183], v100, s[84:85] offset:832
	global_load_dwordx4 v[184:187], v149, s[84:85] offset:832
	s_add_u32 s84, s84, 0x30000
	s_addc_u32 s85, s85, 0
	ds_read_b64_tr_b16 v[72:73], v231
	ds_read_b64_tr_b16 v[74:75], v231 offset:512
	ds_read_b64_tr_b16 v[76:77], v231 offset:2048
	ds_read_b64_tr_b16 v[78:79], v231 offset:2560
	ds_read_b64_tr_b16 v[220:221], v231 offset:1024
	ds_read_b64_tr_b16 v[222:223], v231 offset:1536
	ds_read_b64_tr_b16 v[224:225], v231 offset:3072
	ds_read_b64_tr_b16 v[226:227], v231 offset:3584
	v_exp_f32_e32 v188, v188
	v_exp_f32_e32 v189, v189
	v_exp_f32_e32 v190, v190
	v_exp_f32_e32 v191, v191
	s_waitcnt vmcnt(8)
	ds_write_b128 v247, v[116:119]
	ds_write_b128 v247, v[120:123] offset:1024
	ds_write_b128 v247, v[124:127] offset:2048
	ds_write_b128 v247, v[128:131] offset:3072
	ds_read_b128 v[116:119], v248
	ds_read_b128 v[120:123], v249
	ds_read_b128 v[124:127], v250
	ds_read_b128 v[128:131], v251
	ds_write_b128 v112, v[132:135]
	ds_write_b128 v112, v[136:139] offset:1024
	ds_write_b128 v112, v[140:143] offset:2048
	ds_write_b128 v112, v[144:147] offset:3072
	v_exp_f32_e32 v192, v192
	v_exp_f32_e32 v193, v193
	v_exp_f32_e32 v194, v194
	v_exp_f32_e32 v195, v195
	s_waitcnt lgkmcnt(4)
	v_mfma_f32_32x32x16_bf16 v[32:47], v[116:119], v[48:51], v[32:47]
	v_exp_f32_e32 v196, v196
	v_exp_f32_e32 v197, v197
	v_mfma_f32_32x32x16_bf16 v[32:47], v[120:123], v[52:55], v[32:47]
	v_exp_f32_e32 v198, v198
	v_exp_f32_e32 v199, v199
	v_mfma_f32_32x32x16_bf16 v[32:47], v[124:127], v[56:59], v[32:47]
	v_exp_f32_e32 v200, v200
	v_exp_f32_e32 v201, v201
	v_mfma_f32_32x32x16_bf16 v[32:47], v[128:131], v[60:63], v[32:47]
	v_exp_f32_e32 v202, v202
	v_exp_f32_e32 v203, v203
	v_cvt_pk_bf16_f32 v64, v188, v189
	v_cvt_pk_bf16_f32 v65, v190, v191
	v_cvt_pk_bf16_f32 v66, v192, v193
	v_cvt_pk_bf16_f32 v67, v194, v195
	v_cvt_pk_bf16_f32 v68, v196, v197
	v_cvt_pk_bf16_f32 v69, v198, v199
	v_cvt_pk_bf16_f32 v70, v200, v201
	v_cvt_pk_bf16_f32 v71, v202, v203
	v_pk_add_f32 v[232:233], v[232:233], v[188:189]
	v_pk_add_f32 v[232:233], v[232:233], v[190:191]
	v_pk_add_f32 v[232:233], v[232:233], v[192:193]
	v_pk_add_f32 v[232:233], v[232:233], v[194:195]
	v_pk_add_f32 v[232:233], v[232:233], v[196:197]
	v_pk_add_f32 v[232:233], v[232:233], v[198:199]
	v_pk_add_f32 v[232:233], v[232:233], v[200:201]
	v_pk_add_f32 v[232:233], v[232:233], v[202:203]
	ds_read2_b32 v[188:189], v115 offset0:170 offset1:171
	ds_read2_b32 v[190:191], v115 offset0:172 offset1:173
	ds_read2_b32 v[192:193], v115 offset0:178 offset1:179
	ds_read2_b32 v[194:195], v115 offset0:180 offset1:181
	ds_read2_b32 v[196:197], v115 offset0:187 offset1:188
	ds_read2_b32 v[198:199], v115 offset0:189 offset1:190
	ds_read2_b32 v[200:201], v115 offset0:195 offset1:196
	ds_read2_b32 v[202:203], v115 offset0:197 offset1:198
	v_mfma_f32_32x32x16_bf16 v[0:15], v[64:67], v[72:75], v[0:15]
	v_mfma_f32_32x32x16_bf16 v[16:31], v[64:67], v[76:79], v[16:31]
	v_mfma_f32_32x32x16_bf16 v[0:15], v[68:71], v[220:223], v[0:15]
	v_mfma_f32_32x32x16_bf16 v[16:31], v[68:71], v[224:227], v[16:31]
	global_load_dwordx4 v[116:119], v235, s[84:85]
	global_load_dwordx4 v[120:123], v236, s[84:85]
	global_load_dwordx4 v[124:127], v237, s[84:85]
	global_load_dwordx4 v[128:131], v238, s[84:85]
	global_load_dwordx4 v[132:135], v100, s[84:85] offset:768
	global_load_dwordx4 v[136:139], v149, s[84:85] offset:768
	global_load_dwordx4 v[140:143], v100, s[84:85] offset:832
	global_load_dwordx4 v[144:147], v149, s[84:85] offset:832
	s_add_u32 s84, s84, 0x30000
	s_addc_u32 s85, s85, 0
	ds_read_b64_tr_b16 v[72:73], v231
	ds_read_b64_tr_b16 v[74:75], v231 offset:512
	ds_read_b64_tr_b16 v[76:77], v231 offset:2048
	ds_read_b64_tr_b16 v[78:79], v231 offset:2560
	ds_read_b64_tr_b16 v[220:221], v231 offset:1024
	ds_read_b64_tr_b16 v[222:223], v231 offset:1536
	ds_read_b64_tr_b16 v[224:225], v231 offset:3072
	ds_read_b64_tr_b16 v[226:227], v231 offset:3584
	v_exp_f32_e32 v32, v32
	v_exp_f32_e32 v33, v33
	v_exp_f32_e32 v34, v34
	v_exp_f32_e32 v35, v35
	s_waitcnt vmcnt(8)
	ds_write_b128 v247, v[156:159]
	ds_write_b128 v247, v[160:163] offset:1024
	ds_write_b128 v247, v[164:167] offset:2048
	ds_write_b128 v247, v[168:171] offset:3072
	ds_read_b128 v[156:159], v248
	ds_read_b128 v[160:163], v249
	ds_read_b128 v[164:167], v250
	ds_read_b128 v[168:171], v251
	ds_write_b128 v112, v[172:175]
	ds_write_b128 v112, v[176:179] offset:1024
	ds_write_b128 v112, v[180:183] offset:2048
	ds_write_b128 v112, v[184:187] offset:3072
	v_exp_f32_e32 v36, v36
	v_exp_f32_e32 v37, v37
	v_exp_f32_e32 v38, v38
	v_exp_f32_e32 v39, v39
	s_waitcnt lgkmcnt(4)
	v_mfma_f32_32x32x16_bf16 v[188:203], v[156:159], v[48:51], v[188:203]
	v_exp_f32_e32 v40, v40
	v_exp_f32_e32 v41, v41
	v_mfma_f32_32x32x16_bf16 v[188:203], v[160:163], v[52:55], v[188:203]
	v_exp_f32_e32 v42, v42
	v_exp_f32_e32 v43, v43
	v_mfma_f32_32x32x16_bf16 v[188:203], v[164:167], v[56:59], v[188:203]
	v_exp_f32_e32 v44, v44
	v_exp_f32_e32 v45, v45
	v_mfma_f32_32x32x16_bf16 v[188:203], v[168:171], v[60:63], v[188:203]
	v_exp_f32_e32 v46, v46
	v_exp_f32_e32 v47, v47
	v_cvt_pk_bf16_f32 v64, v32, v33
	v_cvt_pk_bf16_f32 v65, v34, v35
	v_cvt_pk_bf16_f32 v66, v36, v37
	v_cvt_pk_bf16_f32 v67, v38, v39
	v_cvt_pk_bf16_f32 v68, v40, v41
	v_cvt_pk_bf16_f32 v69, v42, v43
	v_cvt_pk_bf16_f32 v70, v44, v45
	v_cvt_pk_bf16_f32 v71, v46, v47
	v_pk_add_f32 v[232:233], v[232:233], v[32:33]
	v_pk_add_f32 v[232:233], v[232:233], v[34:35]
	v_pk_add_f32 v[232:233], v[232:233], v[36:37]
	v_pk_add_f32 v[232:233], v[232:233], v[38:39]
	v_pk_add_f32 v[232:233], v[232:233], v[40:41]
	v_pk_add_f32 v[232:233], v[232:233], v[42:43]
	v_pk_add_f32 v[232:233], v[232:233], v[44:45]
	v_pk_add_f32 v[232:233], v[232:233], v[46:47]
	ds_read2_b32 v[32:33], v115 offset0:204 offset1:205
	ds_read2_b32 v[34:35], v115 offset0:206 offset1:207
	ds_read2_b32 v[36:37], v115 offset0:212 offset1:213
	ds_read2_b32 v[38:39], v115 offset0:214 offset1:215
	ds_read2_b32 v[40:41], v115 offset0:221 offset1:222
	ds_read2_b32 v[42:43], v115 offset0:223 offset1:224
	ds_read2_b32 v[44:45], v115 offset0:229 offset1:230
	ds_read2_b32 v[46:47], v115 offset0:231 offset1:232
	v_mfma_f32_32x32x16_bf16 v[0:15], v[64:67], v[72:75], v[0:15]
	v_mfma_f32_32x32x16_bf16 v[16:31], v[64:67], v[76:79], v[16:31]
	v_mfma_f32_32x32x16_bf16 v[0:15], v[68:71], v[220:223], v[0:15]
	v_mfma_f32_32x32x16_bf16 v[16:31], v[68:71], v[224:227], v[16:31]
	global_load_dwordx4 v[156:159], v235, s[84:85]
	global_load_dwordx4 v[160:163], v236, s[84:85]
	global_load_dwordx4 v[164:167], v237, s[84:85]
	global_load_dwordx4 v[168:171], v238, s[84:85]
	global_load_dwordx4 v[172:175], v100, s[84:85] offset:768
	global_load_dwordx4 v[176:179], v149, s[84:85] offset:768
	global_load_dwordx4 v[180:183], v100, s[84:85] offset:832
	global_load_dwordx4 v[184:187], v149, s[84:85] offset:832
	s_add_u32 s84, s84, 0x30000
	s_addc_u32 s85, s85, 0
	ds_read_b64_tr_b16 v[72:73], v231
	ds_read_b64_tr_b16 v[74:75], v231 offset:512
	ds_read_b64_tr_b16 v[76:77], v231 offset:2048
	ds_read_b64_tr_b16 v[78:79], v231 offset:2560
	ds_read_b64_tr_b16 v[220:221], v231 offset:1024
	ds_read_b64_tr_b16 v[222:223], v231 offset:1536
	ds_read_b64_tr_b16 v[224:225], v231 offset:3072
	ds_read_b64_tr_b16 v[226:227], v231 offset:3584
	v_exp_f32_e32 v188, v188
	v_exp_f32_e32 v189, v189
	v_exp_f32_e32 v190, v190
	v_exp_f32_e32 v191, v191
	s_waitcnt vmcnt(8)
	ds_write_b128 v247, v[116:119]
	ds_write_b128 v247, v[120:123] offset:1024
	ds_write_b128 v247, v[124:127] offset:2048
	ds_write_b128 v247, v[128:131] offset:3072
	ds_read_b128 v[116:119], v248
	ds_read_b128 v[120:123], v249
	ds_read_b128 v[124:127], v250
	ds_read_b128 v[128:131], v251
	ds_write_b128 v112, v[132:135]
	ds_write_b128 v112, v[136:139] offset:1024
	ds_write_b128 v112, v[140:143] offset:2048
	ds_write_b128 v112, v[144:147] offset:3072
	v_exp_f32_e32 v192, v192
	v_exp_f32_e32 v193, v193
	v_exp_f32_e32 v194, v194
	v_exp_f32_e32 v195, v195
	s_waitcnt lgkmcnt(4)
	v_mfma_f32_32x32x16_bf16 v[32:47], v[116:119], v[48:51], v[32:47]
	v_exp_f32_e32 v196, v196
	v_exp_f32_e32 v197, v197
	v_mfma_f32_32x32x16_bf16 v[32:47], v[120:123], v[52:55], v[32:47]
	v_exp_f32_e32 v198, v198
	v_exp_f32_e32 v199, v199
	v_mfma_f32_32x32x16_bf16 v[32:47], v[124:127], v[56:59], v[32:47]
	v_exp_f32_e32 v200, v200
	v_exp_f32_e32 v201, v201
	v_mfma_f32_32x32x16_bf16 v[32:47], v[128:131], v[60:63], v[32:47]
	v_exp_f32_e32 v202, v202
	v_exp_f32_e32 v203, v203
	v_cvt_pk_bf16_f32 v64, v188, v189
	v_cvt_pk_bf16_f32 v65, v190, v191
	v_cvt_pk_bf16_f32 v66, v192, v193
	v_cvt_pk_bf16_f32 v67, v194, v195
	v_cvt_pk_bf16_f32 v68, v196, v197
	v_cvt_pk_bf16_f32 v69, v198, v199
	v_cvt_pk_bf16_f32 v70, v200, v201
	v_cvt_pk_bf16_f32 v71, v202, v203
	v_pk_add_f32 v[232:233], v[232:233], v[188:189]
	v_pk_add_f32 v[232:233], v[232:233], v[190:191]
	v_pk_add_f32 v[232:233], v[232:233], v[192:193]
	v_pk_add_f32 v[232:233], v[232:233], v[194:195]
	v_pk_add_f32 v[232:233], v[232:233], v[196:197]
	v_pk_add_f32 v[232:233], v[232:233], v[198:199]
	v_pk_add_f32 v[232:233], v[232:233], v[200:201]
	v_pk_add_f32 v[232:233], v[232:233], v[202:203]
	v_add_u32_e32 v115, 952, v115
	ds_read2_b32 v[188:189], v115 offset0:0 offset1:1
	ds_read2_b32 v[190:191], v115 offset0:2 offset1:3
	ds_read2_b32 v[192:193], v115 offset0:8 offset1:9
	ds_read2_b32 v[194:195], v115 offset0:10 offset1:11
	ds_read2_b32 v[196:197], v115 offset0:17 offset1:18
	ds_read2_b32 v[198:199], v115 offset0:19 offset1:20
	ds_read2_b32 v[200:201], v115 offset0:25 offset1:26
	ds_read2_b32 v[202:203], v115 offset0:27 offset1:28
	v_mfma_f32_32x32x16_bf16 v[0:15], v[64:67], v[72:75], v[0:15]
	v_mfma_f32_32x32x16_bf16 v[16:31], v[64:67], v[76:79], v[16:31]
	v_mfma_f32_32x32x16_bf16 v[0:15], v[68:71], v[220:223], v[0:15]
	v_mfma_f32_32x32x16_bf16 v[16:31], v[68:71], v[224:227], v[16:31]
	global_load_dwordx4 v[116:119], v235, s[84:85]
	global_load_dwordx4 v[120:123], v236, s[84:85]
	global_load_dwordx4 v[124:127], v237, s[84:85]
	global_load_dwordx4 v[128:131], v238, s[84:85]
	global_load_dwordx4 v[132:135], v100, s[84:85] offset:768
	global_load_dwordx4 v[136:139], v149, s[84:85] offset:768
	global_load_dwordx4 v[140:143], v100, s[84:85] offset:832
	global_load_dwordx4 v[144:147], v149, s[84:85] offset:832
	s_add_u32 s84, s84, 0x30000
	s_addc_u32 s85, s85, 0
	ds_read_b64_tr_b16 v[72:73], v231
	ds_read_b64_tr_b16 v[74:75], v231 offset:512
	ds_read_b64_tr_b16 v[76:77], v231 offset:2048
	ds_read_b64_tr_b16 v[78:79], v231 offset:2560
	ds_read_b64_tr_b16 v[220:221], v231 offset:1024
	ds_read_b64_tr_b16 v[222:223], v231 offset:1536
	ds_read_b64_tr_b16 v[224:225], v231 offset:3072
	ds_read_b64_tr_b16 v[226:227], v231 offset:3584
	v_exp_f32_e32 v32, v32
	v_exp_f32_e32 v33, v33
	v_exp_f32_e32 v34, v34
	v_exp_f32_e32 v35, v35
	s_waitcnt vmcnt(8)
	ds_write_b128 v247, v[156:159]
	ds_write_b128 v247, v[160:163] offset:1024
	ds_write_b128 v247, v[164:167] offset:2048
	ds_write_b128 v247, v[168:171] offset:3072
	ds_read_b128 v[156:159], v248
	ds_read_b128 v[160:163], v249
	ds_read_b128 v[164:167], v250
	ds_read_b128 v[168:171], v251
	ds_write_b128 v112, v[172:175]
	ds_write_b128 v112, v[176:179] offset:1024
	ds_write_b128 v112, v[180:183] offset:2048
	ds_write_b128 v112, v[184:187] offset:3072
	v_exp_f32_e32 v36, v36
	v_exp_f32_e32 v37, v37
	v_exp_f32_e32 v38, v38
	v_exp_f32_e32 v39, v39
	s_waitcnt lgkmcnt(4)
	v_mfma_f32_32x32x16_bf16 v[188:203], v[156:159], v[48:51], v[188:203]
	v_exp_f32_e32 v40, v40
	v_exp_f32_e32 v41, v41
	v_mfma_f32_32x32x16_bf16 v[188:203], v[160:163], v[52:55], v[188:203]
	v_exp_f32_e32 v42, v42
	v_exp_f32_e32 v43, v43
	v_mfma_f32_32x32x16_bf16 v[188:203], v[164:167], v[56:59], v[188:203]
	v_exp_f32_e32 v44, v44
	v_exp_f32_e32 v45, v45
	v_mfma_f32_32x32x16_bf16 v[188:203], v[168:171], v[60:63], v[188:203]
	v_exp_f32_e32 v46, v46
	v_exp_f32_e32 v47, v47
	v_cvt_pk_bf16_f32 v64, v32, v33
	v_cvt_pk_bf16_f32 v65, v34, v35
	v_cvt_pk_bf16_f32 v66, v36, v37
	v_cvt_pk_bf16_f32 v67, v38, v39
	v_cvt_pk_bf16_f32 v68, v40, v41
	v_cvt_pk_bf16_f32 v69, v42, v43
	v_cvt_pk_bf16_f32 v70, v44, v45
	v_cvt_pk_bf16_f32 v71, v46, v47
	v_pk_add_f32 v[232:233], v[232:233], v[32:33]
	v_pk_add_f32 v[232:233], v[232:233], v[34:35]
	v_pk_add_f32 v[232:233], v[232:233], v[36:37]
	v_pk_add_f32 v[232:233], v[232:233], v[38:39]
	v_pk_add_f32 v[232:233], v[232:233], v[40:41]
	v_pk_add_f32 v[232:233], v[232:233], v[42:43]
	v_pk_add_f32 v[232:233], v[232:233], v[44:45]
	v_pk_add_f32 v[232:233], v[232:233], v[46:47]
	ds_read2_b32 v[32:33], v115 offset0:34 offset1:35
	ds_read2_b32 v[34:35], v115 offset0:36 offset1:37
	ds_read2_b32 v[36:37], v115 offset0:42 offset1:43
	ds_read2_b32 v[38:39], v115 offset0:44 offset1:45
	ds_read2_b32 v[40:41], v115 offset0:51 offset1:52
	ds_read2_b32 v[42:43], v115 offset0:53 offset1:54
	ds_read2_b32 v[44:45], v115 offset0:59 offset1:60
	ds_read2_b32 v[46:47], v115 offset0:61 offset1:62
	v_mfma_f32_32x32x16_bf16 v[0:15], v[64:67], v[72:75], v[0:15]
	v_mfma_f32_32x32x16_bf16 v[16:31], v[64:67], v[76:79], v[16:31]
	v_mfma_f32_32x32x16_bf16 v[0:15], v[68:71], v[220:223], v[0:15]
	v_mfma_f32_32x32x16_bf16 v[16:31], v[68:71], v[224:227], v[16:31]
	global_load_dwordx4 v[156:159], v235, s[84:85]
	global_load_dwordx4 v[160:163], v236, s[84:85]
	global_load_dwordx4 v[164:167], v237, s[84:85]
	global_load_dwordx4 v[168:171], v238, s[84:85]
	global_load_dwordx4 v[172:175], v100, s[84:85] offset:768
	global_load_dwordx4 v[176:179], v149, s[84:85] offset:768
	global_load_dwordx4 v[180:183], v100, s[84:85] offset:832
	global_load_dwordx4 v[184:187], v149, s[84:85] offset:832
	s_add_u32 s84, s84, 0x30000
	s_addc_u32 s85, s85, 0
	ds_read_b64_tr_b16 v[72:73], v231
	ds_read_b64_tr_b16 v[74:75], v231 offset:512
	ds_read_b64_tr_b16 v[76:77], v231 offset:2048
	ds_read_b64_tr_b16 v[78:79], v231 offset:2560
	ds_read_b64_tr_b16 v[220:221], v231 offset:1024
	ds_read_b64_tr_b16 v[222:223], v231 offset:1536
	ds_read_b64_tr_b16 v[224:225], v231 offset:3072
	ds_read_b64_tr_b16 v[226:227], v231 offset:3584
	v_exp_f32_e32 v188, v188
	v_exp_f32_e32 v189, v189
	v_exp_f32_e32 v190, v190
	v_exp_f32_e32 v191, v191
	s_waitcnt vmcnt(8)
	ds_write_b128 v247, v[116:119]
	ds_write_b128 v247, v[120:123] offset:1024
	ds_write_b128 v247, v[124:127] offset:2048
	ds_write_b128 v247, v[128:131] offset:3072
	ds_read_b128 v[116:119], v248
	ds_read_b128 v[120:123], v249
	ds_read_b128 v[124:127], v250
	ds_read_b128 v[128:131], v251
	ds_write_b128 v112, v[132:135]
	ds_write_b128 v112, v[136:139] offset:1024
	ds_write_b128 v112, v[140:143] offset:2048
	ds_write_b128 v112, v[144:147] offset:3072
	v_exp_f32_e32 v192, v192
	v_exp_f32_e32 v193, v193
	v_exp_f32_e32 v194, v194
	v_exp_f32_e32 v195, v195
	s_waitcnt lgkmcnt(4)
	v_mfma_f32_32x32x16_bf16 v[32:47], v[116:119], v[48:51], v[32:47]
	v_exp_f32_e32 v196, v196
	v_exp_f32_e32 v197, v197
	v_mfma_f32_32x32x16_bf16 v[32:47], v[120:123], v[52:55], v[32:47]
	v_exp_f32_e32 v198, v198
	v_exp_f32_e32 v199, v199
	v_mfma_f32_32x32x16_bf16 v[32:47], v[124:127], v[56:59], v[32:47]
	v_exp_f32_e32 v200, v200
	v_exp_f32_e32 v201, v201
	v_mfma_f32_32x32x16_bf16 v[32:47], v[128:131], v[60:63], v[32:47]
	v_exp_f32_e32 v202, v202
	v_exp_f32_e32 v203, v203
	v_cvt_pk_bf16_f32 v64, v188, v189
	v_cvt_pk_bf16_f32 v65, v190, v191
	v_cvt_pk_bf16_f32 v66, v192, v193
	v_cvt_pk_bf16_f32 v67, v194, v195
	v_cvt_pk_bf16_f32 v68, v196, v197
	v_cvt_pk_bf16_f32 v69, v198, v199
	v_cvt_pk_bf16_f32 v70, v200, v201
	v_cvt_pk_bf16_f32 v71, v202, v203
	v_pk_add_f32 v[232:233], v[232:233], v[188:189]
	v_pk_add_f32 v[232:233], v[232:233], v[190:191]
	v_pk_add_f32 v[232:233], v[232:233], v[192:193]
	v_pk_add_f32 v[232:233], v[232:233], v[194:195]
	v_pk_add_f32 v[232:233], v[232:233], v[196:197]
	v_pk_add_f32 v[232:233], v[232:233], v[198:199]
	v_pk_add_f32 v[232:233], v[232:233], v[200:201]
	v_pk_add_f32 v[232:233], v[232:233], v[202:203]
	ds_read2_b32 v[188:189], v115 offset0:68 offset1:69
	ds_read2_b32 v[190:191], v115 offset0:70 offset1:71
	ds_read2_b32 v[192:193], v115 offset0:76 offset1:77
	ds_read2_b32 v[194:195], v115 offset0:78 offset1:79
	ds_read2_b32 v[196:197], v115 offset0:85 offset1:86
	ds_read2_b32 v[198:199], v115 offset0:87 offset1:88
	ds_read2_b32 v[200:201], v115 offset0:93 offset1:94
	ds_read2_b32 v[202:203], v115 offset0:95 offset1:96
	v_mfma_f32_32x32x16_bf16 v[0:15], v[64:67], v[72:75], v[0:15]
	v_mfma_f32_32x32x16_bf16 v[16:31], v[64:67], v[76:79], v[16:31]
	v_mfma_f32_32x32x16_bf16 v[0:15], v[68:71], v[220:223], v[0:15]
	v_mfma_f32_32x32x16_bf16 v[16:31], v[68:71], v[224:227], v[16:31]
	global_load_dwordx4 v[116:119], v235, s[84:85]
	global_load_dwordx4 v[120:123], v236, s[84:85]
	global_load_dwordx4 v[124:127], v237, s[84:85]
	global_load_dwordx4 v[128:131], v238, s[84:85]
	global_load_dwordx4 v[132:135], v100, s[84:85] offset:768
	global_load_dwordx4 v[136:139], v149, s[84:85] offset:768
	global_load_dwordx4 v[140:143], v100, s[84:85] offset:832
	global_load_dwordx4 v[144:147], v149, s[84:85] offset:832
	s_add_u32 s84, s84, 0x30000
	s_addc_u32 s85, s85, 0
	ds_read_b64_tr_b16 v[72:73], v231
	ds_read_b64_tr_b16 v[74:75], v231 offset:512
	ds_read_b64_tr_b16 v[76:77], v231 offset:2048
	ds_read_b64_tr_b16 v[78:79], v231 offset:2560
	ds_read_b64_tr_b16 v[220:221], v231 offset:1024
	ds_read_b64_tr_b16 v[222:223], v231 offset:1536
	ds_read_b64_tr_b16 v[224:225], v231 offset:3072
	ds_read_b64_tr_b16 v[226:227], v231 offset:3584
	v_exp_f32_e32 v32, v32
	v_exp_f32_e32 v33, v33
	v_exp_f32_e32 v34, v34
	v_exp_f32_e32 v35, v35
	s_waitcnt vmcnt(8)
	ds_write_b128 v247, v[156:159]
	ds_write_b128 v247, v[160:163] offset:1024
	ds_write_b128 v247, v[164:167] offset:2048
	ds_write_b128 v247, v[168:171] offset:3072
	ds_read_b128 v[156:159], v248
	ds_read_b128 v[160:163], v249
	ds_read_b128 v[164:167], v250
	ds_read_b128 v[168:171], v251
	ds_write_b128 v112, v[172:175]
	ds_write_b128 v112, v[176:179] offset:1024
	ds_write_b128 v112, v[180:183] offset:2048
	ds_write_b128 v112, v[184:187] offset:3072
	v_exp_f32_e32 v36, v36
	v_exp_f32_e32 v37, v37
	v_exp_f32_e32 v38, v38
	v_exp_f32_e32 v39, v39
	s_waitcnt lgkmcnt(4)
	v_mfma_f32_32x32x16_bf16 v[188:203], v[156:159], v[48:51], v[188:203]
	v_exp_f32_e32 v40, v40
	v_exp_f32_e32 v41, v41
	v_mfma_f32_32x32x16_bf16 v[188:203], v[160:163], v[52:55], v[188:203]
	v_exp_f32_e32 v42, v42
	v_exp_f32_e32 v43, v43
	v_mfma_f32_32x32x16_bf16 v[188:203], v[164:167], v[56:59], v[188:203]
	v_exp_f32_e32 v44, v44
	v_exp_f32_e32 v45, v45
	v_mfma_f32_32x32x16_bf16 v[188:203], v[168:171], v[60:63], v[188:203]
	v_exp_f32_e32 v46, v46
	v_exp_f32_e32 v47, v47
	v_cvt_pk_bf16_f32 v64, v32, v33
	v_cvt_pk_bf16_f32 v65, v34, v35
	v_cvt_pk_bf16_f32 v66, v36, v37
	v_cvt_pk_bf16_f32 v67, v38, v39
	v_cvt_pk_bf16_f32 v68, v40, v41
	v_cvt_pk_bf16_f32 v69, v42, v43
	v_cvt_pk_bf16_f32 v70, v44, v45
	v_cvt_pk_bf16_f32 v71, v46, v47
	v_pk_add_f32 v[232:233], v[232:233], v[32:33]
	v_pk_add_f32 v[232:233], v[232:233], v[34:35]
	v_pk_add_f32 v[232:233], v[232:233], v[36:37]
	v_pk_add_f32 v[232:233], v[232:233], v[38:39]
	v_pk_add_f32 v[232:233], v[232:233], v[40:41]
	v_pk_add_f32 v[232:233], v[232:233], v[42:43]
	v_pk_add_f32 v[232:233], v[232:233], v[44:45]
	v_pk_add_f32 v[232:233], v[232:233], v[46:47]
	ds_read2_b32 v[32:33], v115 offset0:102 offset1:103
	ds_read2_b32 v[34:35], v115 offset0:104 offset1:105
	ds_read2_b32 v[36:37], v115 offset0:110 offset1:111
	ds_read2_b32 v[38:39], v115 offset0:112 offset1:113
	ds_read2_b32 v[40:41], v115 offset0:119 offset1:120
	ds_read2_b32 v[42:43], v115 offset0:121 offset1:122
	ds_read2_b32 v[44:45], v115 offset0:127 offset1:128
	ds_read2_b32 v[46:47], v115 offset0:129 offset1:130
	v_mfma_f32_32x32x16_bf16 v[0:15], v[64:67], v[72:75], v[0:15]
	v_mfma_f32_32x32x16_bf16 v[16:31], v[64:67], v[76:79], v[16:31]
	v_mfma_f32_32x32x16_bf16 v[0:15], v[68:71], v[220:223], v[0:15]
	v_mfma_f32_32x32x16_bf16 v[16:31], v[68:71], v[224:227], v[16:31]
	global_load_dwordx4 v[156:159], v235, s[84:85]
	global_load_dwordx4 v[160:163], v236, s[84:85]
	global_load_dwordx4 v[164:167], v237, s[84:85]
	global_load_dwordx4 v[168:171], v238, s[84:85]
	global_load_dwordx4 v[172:175], v100, s[84:85] offset:768
	global_load_dwordx4 v[176:179], v149, s[84:85] offset:768
	global_load_dwordx4 v[180:183], v100, s[84:85] offset:832
	global_load_dwordx4 v[184:187], v149, s[84:85] offset:832
	s_add_u32 s84, s84, 0x30000
	s_addc_u32 s85, s85, 0
	ds_read_b64_tr_b16 v[72:73], v231
	ds_read_b64_tr_b16 v[74:75], v231 offset:512
	ds_read_b64_tr_b16 v[76:77], v231 offset:2048
	ds_read_b64_tr_b16 v[78:79], v231 offset:2560
	ds_read_b64_tr_b16 v[220:221], v231 offset:1024
	ds_read_b64_tr_b16 v[222:223], v231 offset:1536
	ds_read_b64_tr_b16 v[224:225], v231 offset:3072
	ds_read_b64_tr_b16 v[226:227], v231 offset:3584
	v_exp_f32_e32 v188, v188
	v_exp_f32_e32 v189, v189
	v_exp_f32_e32 v190, v190
	v_exp_f32_e32 v191, v191
	s_waitcnt vmcnt(8)
	ds_write_b128 v247, v[116:119]
	ds_write_b128 v247, v[120:123] offset:1024
	ds_write_b128 v247, v[124:127] offset:2048
	ds_write_b128 v247, v[128:131] offset:3072
	ds_read_b128 v[116:119], v248
	ds_read_b128 v[120:123], v249
	ds_read_b128 v[124:127], v250
	ds_read_b128 v[128:131], v251
	ds_write_b128 v112, v[132:135]
	ds_write_b128 v112, v[136:139] offset:1024
	ds_write_b128 v112, v[140:143] offset:2048
	ds_write_b128 v112, v[144:147] offset:3072
	v_exp_f32_e32 v192, v192
	v_exp_f32_e32 v193, v193
	v_exp_f32_e32 v194, v194
	v_exp_f32_e32 v195, v195
	s_waitcnt lgkmcnt(4)
	v_mfma_f32_32x32x16_bf16 v[32:47], v[116:119], v[48:51], v[32:47]
	v_exp_f32_e32 v196, v196
	v_exp_f32_e32 v197, v197
	v_mfma_f32_32x32x16_bf16 v[32:47], v[120:123], v[52:55], v[32:47]
	v_exp_f32_e32 v198, v198
	v_exp_f32_e32 v199, v199
	v_mfma_f32_32x32x16_bf16 v[32:47], v[124:127], v[56:59], v[32:47]
	v_exp_f32_e32 v200, v200
	v_exp_f32_e32 v201, v201
	v_mfma_f32_32x32x16_bf16 v[32:47], v[128:131], v[60:63], v[32:47]
	v_exp_f32_e32 v202, v202
	v_exp_f32_e32 v203, v203
	v_cvt_pk_bf16_f32 v64, v188, v189
	v_cvt_pk_bf16_f32 v65, v190, v191
	v_cvt_pk_bf16_f32 v66, v192, v193
	v_cvt_pk_bf16_f32 v67, v194, v195
	v_cvt_pk_bf16_f32 v68, v196, v197
	v_cvt_pk_bf16_f32 v69, v198, v199
	v_cvt_pk_bf16_f32 v70, v200, v201
	v_cvt_pk_bf16_f32 v71, v202, v203
	v_pk_add_f32 v[232:233], v[232:233], v[188:189]
	v_pk_add_f32 v[232:233], v[232:233], v[190:191]
	v_pk_add_f32 v[232:233], v[232:233], v[192:193]
	v_pk_add_f32 v[232:233], v[232:233], v[194:195]
	v_pk_add_f32 v[232:233], v[232:233], v[196:197]
	v_pk_add_f32 v[232:233], v[232:233], v[198:199]
	v_pk_add_f32 v[232:233], v[232:233], v[200:201]
	v_pk_add_f32 v[232:233], v[232:233], v[202:203]
	ds_read2_b32 v[188:189], v115 offset0:136 offset1:137
	ds_read2_b32 v[190:191], v115 offset0:138 offset1:139
	ds_read2_b32 v[192:193], v115 offset0:144 offset1:145
	ds_read2_b32 v[194:195], v115 offset0:146 offset1:147
	ds_read2_b32 v[196:197], v115 offset0:153 offset1:154
	ds_read2_b32 v[198:199], v115 offset0:155 offset1:156
	ds_read2_b32 v[200:201], v115 offset0:161 offset1:162
	ds_read2_b32 v[202:203], v115 offset0:163 offset1:164
	v_mfma_f32_32x32x16_bf16 v[0:15], v[64:67], v[72:75], v[0:15]
	v_mfma_f32_32x32x16_bf16 v[16:31], v[64:67], v[76:79], v[16:31]
	v_mfma_f32_32x32x16_bf16 v[0:15], v[68:71], v[220:223], v[0:15]
	v_mfma_f32_32x32x16_bf16 v[16:31], v[68:71], v[224:227], v[16:31]
	global_load_dwordx4 v[116:119], v235, s[84:85]
	global_load_dwordx4 v[120:123], v236, s[84:85]
	global_load_dwordx4 v[124:127], v237, s[84:85]
	global_load_dwordx4 v[128:131], v238, s[84:85]
	global_load_dwordx4 v[132:135], v100, s[84:85] offset:768
	global_load_dwordx4 v[136:139], v149, s[84:85] offset:768
	global_load_dwordx4 v[140:143], v100, s[84:85] offset:832
	global_load_dwordx4 v[144:147], v149, s[84:85] offset:832
	s_add_u32 s84, s84, 0x30000
	s_addc_u32 s85, s85, 0
	ds_read_b64_tr_b16 v[72:73], v231
	ds_read_b64_tr_b16 v[74:75], v231 offset:512
	ds_read_b64_tr_b16 v[76:77], v231 offset:2048
	ds_read_b64_tr_b16 v[78:79], v231 offset:2560
	ds_read_b64_tr_b16 v[220:221], v231 offset:1024
	ds_read_b64_tr_b16 v[222:223], v231 offset:1536
	ds_read_b64_tr_b16 v[224:225], v231 offset:3072
	ds_read_b64_tr_b16 v[226:227], v231 offset:3584
	v_exp_f32_e32 v32, v32
	v_exp_f32_e32 v33, v33
	v_exp_f32_e32 v34, v34
	v_exp_f32_e32 v35, v35
	s_waitcnt vmcnt(8)
	ds_write_b128 v247, v[156:159]
	ds_write_b128 v247, v[160:163] offset:1024
	ds_write_b128 v247, v[164:167] offset:2048
	ds_write_b128 v247, v[168:171] offset:3072
	ds_read_b128 v[156:159], v248
	ds_read_b128 v[160:163], v249
	ds_read_b128 v[164:167], v250
	ds_read_b128 v[168:171], v251
	ds_write_b128 v112, v[172:175]
	ds_write_b128 v112, v[176:179] offset:1024
	ds_write_b128 v112, v[180:183] offset:2048
	ds_write_b128 v112, v[184:187] offset:3072
	v_exp_f32_e32 v36, v36
	v_exp_f32_e32 v37, v37
	v_exp_f32_e32 v38, v38
	v_exp_f32_e32 v39, v39
	s_waitcnt lgkmcnt(4)
	v_mfma_f32_32x32x16_bf16 v[188:203], v[156:159], v[48:51], v[188:203]
	v_exp_f32_e32 v40, v40
	v_exp_f32_e32 v41, v41
	v_mfma_f32_32x32x16_bf16 v[188:203], v[160:163], v[52:55], v[188:203]
	v_exp_f32_e32 v42, v42
	v_exp_f32_e32 v43, v43
	v_mfma_f32_32x32x16_bf16 v[188:203], v[164:167], v[56:59], v[188:203]
	v_exp_f32_e32 v44, v44
	v_exp_f32_e32 v45, v45
	v_mfma_f32_32x32x16_bf16 v[188:203], v[168:171], v[60:63], v[188:203]
	v_exp_f32_e32 v46, v46
	v_exp_f32_e32 v47, v47
	v_cvt_pk_bf16_f32 v64, v32, v33
	v_cvt_pk_bf16_f32 v65, v34, v35
	v_cvt_pk_bf16_f32 v66, v36, v37
	v_cvt_pk_bf16_f32 v67, v38, v39
	v_cvt_pk_bf16_f32 v68, v40, v41
	v_cvt_pk_bf16_f32 v69, v42, v43
	v_cvt_pk_bf16_f32 v70, v44, v45
	v_cvt_pk_bf16_f32 v71, v46, v47
	v_pk_add_f32 v[232:233], v[232:233], v[32:33]
	v_pk_add_f32 v[232:233], v[232:233], v[34:35]
	v_pk_add_f32 v[232:233], v[232:233], v[36:37]
	v_pk_add_f32 v[232:233], v[232:233], v[38:39]
	v_pk_add_f32 v[232:233], v[232:233], v[40:41]
	v_pk_add_f32 v[232:233], v[232:233], v[42:43]
	v_pk_add_f32 v[232:233], v[232:233], v[44:45]
	v_pk_add_f32 v[232:233], v[232:233], v[46:47]
	ds_read2_b32 v[32:33], v115 offset0:170 offset1:171
	ds_read2_b32 v[34:35], v115 offset0:172 offset1:173
	ds_read2_b32 v[36:37], v115 offset0:178 offset1:179
	ds_read2_b32 v[38:39], v115 offset0:180 offset1:181
	ds_read2_b32 v[40:41], v115 offset0:187 offset1:188
	ds_read2_b32 v[42:43], v115 offset0:189 offset1:190
	ds_read2_b32 v[44:45], v115 offset0:195 offset1:196
	ds_read2_b32 v[46:47], v115 offset0:197 offset1:198
	v_mfma_f32_32x32x16_bf16 v[0:15], v[64:67], v[72:75], v[0:15]
	v_mfma_f32_32x32x16_bf16 v[16:31], v[64:67], v[76:79], v[16:31]
	v_mfma_f32_32x32x16_bf16 v[0:15], v[68:71], v[220:223], v[0:15]
	v_mfma_f32_32x32x16_bf16 v[16:31], v[68:71], v[224:227], v[16:31]
	global_load_dwordx4 v[156:159], v235, s[84:85]
	global_load_dwordx4 v[160:163], v236, s[84:85]
	global_load_dwordx4 v[164:167], v237, s[84:85]
	global_load_dwordx4 v[168:171], v238, s[84:85]
	global_load_dwordx4 v[172:175], v100, s[84:85] offset:768
	global_load_dwordx4 v[176:179], v149, s[84:85] offset:768
	global_load_dwordx4 v[180:183], v100, s[84:85] offset:832
	global_load_dwordx4 v[184:187], v149, s[84:85] offset:832
	s_add_u32 s84, s84, 0x30000
	s_addc_u32 s85, s85, 0
	ds_read_b64_tr_b16 v[72:73], v231
	ds_read_b64_tr_b16 v[74:75], v231 offset:512
	ds_read_b64_tr_b16 v[76:77], v231 offset:2048
	ds_read_b64_tr_b16 v[78:79], v231 offset:2560
	ds_read_b64_tr_b16 v[220:221], v231 offset:1024
	ds_read_b64_tr_b16 v[222:223], v231 offset:1536
	ds_read_b64_tr_b16 v[224:225], v231 offset:3072
	ds_read_b64_tr_b16 v[226:227], v231 offset:3584
	v_exp_f32_e32 v188, v188
	v_exp_f32_e32 v189, v189
	v_exp_f32_e32 v190, v190
	v_exp_f32_e32 v191, v191
	s_waitcnt vmcnt(8)
	ds_write_b128 v247, v[116:119]
	ds_write_b128 v247, v[120:123] offset:1024
	ds_write_b128 v247, v[124:127] offset:2048
	ds_write_b128 v247, v[128:131] offset:3072
	ds_read_b128 v[116:119], v248
	ds_read_b128 v[120:123], v249
	ds_read_b128 v[124:127], v250
	ds_read_b128 v[128:131], v251
	ds_write_b128 v112, v[132:135]
	ds_write_b128 v112, v[136:139] offset:1024
	ds_write_b128 v112, v[140:143] offset:2048
	ds_write_b128 v112, v[144:147] offset:3072
	v_exp_f32_e32 v192, v192
	v_exp_f32_e32 v193, v193
	v_exp_f32_e32 v194, v194
	v_exp_f32_e32 v195, v195
	s_waitcnt lgkmcnt(4)
	v_mfma_f32_32x32x16_bf16 v[32:47], v[116:119], v[48:51], v[32:47]
	v_exp_f32_e32 v196, v196
	v_exp_f32_e32 v197, v197
	v_mfma_f32_32x32x16_bf16 v[32:47], v[120:123], v[52:55], v[32:47]
	v_exp_f32_e32 v198, v198
	v_exp_f32_e32 v199, v199
	v_mfma_f32_32x32x16_bf16 v[32:47], v[124:127], v[56:59], v[32:47]
	v_exp_f32_e32 v200, v200
	v_exp_f32_e32 v201, v201
	v_mfma_f32_32x32x16_bf16 v[32:47], v[128:131], v[60:63], v[32:47]
	v_exp_f32_e32 v202, v202
	v_exp_f32_e32 v203, v203
	v_cvt_pk_bf16_f32 v64, v188, v189
	v_cvt_pk_bf16_f32 v65, v190, v191
	v_cvt_pk_bf16_f32 v66, v192, v193
	v_cvt_pk_bf16_f32 v67, v194, v195
	v_cvt_pk_bf16_f32 v68, v196, v197
	v_cvt_pk_bf16_f32 v69, v198, v199
	v_cvt_pk_bf16_f32 v70, v200, v201
	v_cvt_pk_bf16_f32 v71, v202, v203
	v_pk_add_f32 v[232:233], v[232:233], v[188:189]
	v_pk_add_f32 v[232:233], v[232:233], v[190:191]
	v_pk_add_f32 v[232:233], v[232:233], v[192:193]
	v_pk_add_f32 v[232:233], v[232:233], v[194:195]
	v_pk_add_f32 v[232:233], v[232:233], v[196:197]
	v_pk_add_f32 v[232:233], v[232:233], v[198:199]
	v_pk_add_f32 v[232:233], v[232:233], v[200:201]
	v_pk_add_f32 v[232:233], v[232:233], v[202:203]
	ds_read2_b32 v[188:189], v115 offset0:204 offset1:205
	ds_read2_b32 v[190:191], v115 offset0:206 offset1:207
	ds_read2_b32 v[192:193], v115 offset0:212 offset1:213
	ds_read2_b32 v[194:195], v115 offset0:214 offset1:215
	ds_read2_b32 v[196:197], v115 offset0:221 offset1:222
	ds_read2_b32 v[198:199], v115 offset0:223 offset1:224
	ds_read2_b32 v[200:201], v115 offset0:229 offset1:230
	ds_read2_b32 v[202:203], v115 offset0:231 offset1:232
	v_mfma_f32_32x32x16_bf16 v[0:15], v[64:67], v[72:75], v[0:15]
	v_mfma_f32_32x32x16_bf16 v[16:31], v[64:67], v[76:79], v[16:31]
	v_mfma_f32_32x32x16_bf16 v[0:15], v[68:71], v[220:223], v[0:15]
	v_mfma_f32_32x32x16_bf16 v[16:31], v[68:71], v[224:227], v[16:31]
	global_load_dwordx4 v[116:119], v235, s[84:85]
	global_load_dwordx4 v[120:123], v236, s[84:85]
	global_load_dwordx4 v[124:127], v237, s[84:85]
	global_load_dwordx4 v[128:131], v238, s[84:85]
	global_load_dwordx4 v[132:135], v100, s[84:85] offset:768
	global_load_dwordx4 v[136:139], v149, s[84:85] offset:768
	global_load_dwordx4 v[140:143], v100, s[84:85] offset:832
	global_load_dwordx4 v[144:147], v149, s[84:85] offset:832
	s_add_u32 s84, s84, 0x30000
	s_addc_u32 s85, s85, 0
	ds_read_b64_tr_b16 v[72:73], v231
	ds_read_b64_tr_b16 v[74:75], v231 offset:512
	ds_read_b64_tr_b16 v[76:77], v231 offset:2048
	ds_read_b64_tr_b16 v[78:79], v231 offset:2560
	ds_read_b64_tr_b16 v[220:221], v231 offset:1024
	ds_read_b64_tr_b16 v[222:223], v231 offset:1536
	ds_read_b64_tr_b16 v[224:225], v231 offset:3072
	ds_read_b64_tr_b16 v[226:227], v231 offset:3584
	v_exp_f32_e32 v32, v32
	v_exp_f32_e32 v33, v33
	v_exp_f32_e32 v34, v34
	v_exp_f32_e32 v35, v35
	s_waitcnt vmcnt(8)
	ds_write_b128 v247, v[156:159]
	ds_write_b128 v247, v[160:163] offset:1024
	ds_write_b128 v247, v[164:167] offset:2048
	ds_write_b128 v247, v[168:171] offset:3072
	ds_read_b128 v[156:159], v248
	ds_read_b128 v[160:163], v249
	ds_read_b128 v[164:167], v250
	ds_read_b128 v[168:171], v251
	ds_write_b128 v112, v[172:175]
	ds_write_b128 v112, v[176:179] offset:1024
	ds_write_b128 v112, v[180:183] offset:2048
	ds_write_b128 v112, v[184:187] offset:3072
	v_exp_f32_e32 v36, v36
	v_exp_f32_e32 v37, v37
	v_exp_f32_e32 v38, v38
	v_exp_f32_e32 v39, v39
	s_waitcnt lgkmcnt(4)
	v_mfma_f32_32x32x16_bf16 v[188:203], v[156:159], v[48:51], v[188:203]
	v_exp_f32_e32 v40, v40
	v_exp_f32_e32 v41, v41
	v_mfma_f32_32x32x16_bf16 v[188:203], v[160:163], v[52:55], v[188:203]
	v_exp_f32_e32 v42, v42
	v_exp_f32_e32 v43, v43
	v_mfma_f32_32x32x16_bf16 v[188:203], v[164:167], v[56:59], v[188:203]
	v_exp_f32_e32 v44, v44
	v_exp_f32_e32 v45, v45
	v_mfma_f32_32x32x16_bf16 v[188:203], v[168:171], v[60:63], v[188:203]
	v_exp_f32_e32 v46, v46
	v_exp_f32_e32 v47, v47
	v_cvt_pk_bf16_f32 v64, v32, v33
	v_cvt_pk_bf16_f32 v65, v34, v35
	v_cvt_pk_bf16_f32 v66, v36, v37
	v_cvt_pk_bf16_f32 v67, v38, v39
	v_cvt_pk_bf16_f32 v68, v40, v41
	v_cvt_pk_bf16_f32 v69, v42, v43
	v_cvt_pk_bf16_f32 v70, v44, v45
	v_cvt_pk_bf16_f32 v71, v46, v47
	v_pk_add_f32 v[232:233], v[232:233], v[32:33]
	v_pk_add_f32 v[232:233], v[232:233], v[34:35]
	v_pk_add_f32 v[232:233], v[232:233], v[36:37]
	v_pk_add_f32 v[232:233], v[232:233], v[38:39]
	v_pk_add_f32 v[232:233], v[232:233], v[40:41]
	v_pk_add_f32 v[232:233], v[232:233], v[42:43]
	v_pk_add_f32 v[232:233], v[232:233], v[44:45]
	v_pk_add_f32 v[232:233], v[232:233], v[46:47]
	v_add_u32_e32 v115, 952, v115
	ds_read2_b32 v[32:33], v115 offset0:0 offset1:1
	ds_read2_b32 v[34:35], v115 offset0:2 offset1:3
	ds_read2_b32 v[36:37], v115 offset0:8 offset1:9
	ds_read2_b32 v[38:39], v115 offset0:10 offset1:11
	ds_read2_b32 v[40:41], v115 offset0:17 offset1:18
	ds_read2_b32 v[42:43], v115 offset0:19 offset1:20
	ds_read2_b32 v[44:45], v115 offset0:25 offset1:26
	ds_read2_b32 v[46:47], v115 offset0:27 offset1:28
	v_mfma_f32_32x32x16_bf16 v[0:15], v[64:67], v[72:75], v[0:15]
	v_mfma_f32_32x32x16_bf16 v[16:31], v[64:67], v[76:79], v[16:31]
	v_mfma_f32_32x32x16_bf16 v[0:15], v[68:71], v[220:223], v[0:15]
	v_mfma_f32_32x32x16_bf16 v[16:31], v[68:71], v[224:227], v[16:31]
	global_load_dwordx4 v[156:159], v235, s[84:85]
	global_load_dwordx4 v[160:163], v236, s[84:85]
	global_load_dwordx4 v[164:167], v237, s[84:85]
	global_load_dwordx4 v[168:171], v238, s[84:85]
	global_load_dwordx4 v[172:175], v100, s[84:85] offset:768
	global_load_dwordx4 v[176:179], v149, s[84:85] offset:768
	global_load_dwordx4 v[180:183], v100, s[84:85] offset:832
	global_load_dwordx4 v[184:187], v149, s[84:85] offset:832
	s_add_u32 s84, s84, 0x30000
	s_addc_u32 s85, s85, 0
	ds_read_b64_tr_b16 v[72:73], v231
	ds_read_b64_tr_b16 v[74:75], v231 offset:512
	ds_read_b64_tr_b16 v[76:77], v231 offset:2048
	ds_read_b64_tr_b16 v[78:79], v231 offset:2560
	ds_read_b64_tr_b16 v[220:221], v231 offset:1024
	ds_read_b64_tr_b16 v[222:223], v231 offset:1536
	ds_read_b64_tr_b16 v[224:225], v231 offset:3072
	ds_read_b64_tr_b16 v[226:227], v231 offset:3584
	v_exp_f32_e32 v188, v188
	v_exp_f32_e32 v189, v189
	v_exp_f32_e32 v190, v190
	v_exp_f32_e32 v191, v191
	s_waitcnt vmcnt(8)
	ds_write_b128 v247, v[116:119]
	ds_write_b128 v247, v[120:123] offset:1024
	ds_write_b128 v247, v[124:127] offset:2048
	ds_write_b128 v247, v[128:131] offset:3072
	ds_read_b128 v[116:119], v248
	ds_read_b128 v[120:123], v249
	ds_read_b128 v[124:127], v250
	ds_read_b128 v[128:131], v251
	ds_write_b128 v112, v[132:135]
	ds_write_b128 v112, v[136:139] offset:1024
	ds_write_b128 v112, v[140:143] offset:2048
	ds_write_b128 v112, v[144:147] offset:3072
	v_exp_f32_e32 v192, v192
	v_exp_f32_e32 v193, v193
	v_exp_f32_e32 v194, v194
	v_exp_f32_e32 v195, v195
	s_waitcnt lgkmcnt(4)
	v_mfma_f32_32x32x16_bf16 v[32:47], v[116:119], v[48:51], v[32:47]
	v_exp_f32_e32 v196, v196
	v_exp_f32_e32 v197, v197
	v_mfma_f32_32x32x16_bf16 v[32:47], v[120:123], v[52:55], v[32:47]
	v_exp_f32_e32 v198, v198
	v_exp_f32_e32 v199, v199
	v_mfma_f32_32x32x16_bf16 v[32:47], v[124:127], v[56:59], v[32:47]
	v_exp_f32_e32 v200, v200
	v_exp_f32_e32 v201, v201
	v_mfma_f32_32x32x16_bf16 v[32:47], v[128:131], v[60:63], v[32:47]
	v_exp_f32_e32 v202, v202
	v_exp_f32_e32 v203, v203
	v_cvt_pk_bf16_f32 v64, v188, v189
	v_cvt_pk_bf16_f32 v65, v190, v191
	v_cvt_pk_bf16_f32 v66, v192, v193
	v_cvt_pk_bf16_f32 v67, v194, v195
	v_cvt_pk_bf16_f32 v68, v196, v197
	v_cvt_pk_bf16_f32 v69, v198, v199
	v_cvt_pk_bf16_f32 v70, v200, v201
	v_cvt_pk_bf16_f32 v71, v202, v203
	v_pk_add_f32 v[232:233], v[232:233], v[188:189]
	v_pk_add_f32 v[232:233], v[232:233], v[190:191]
	v_pk_add_f32 v[232:233], v[232:233], v[192:193]
	v_pk_add_f32 v[232:233], v[232:233], v[194:195]
	v_pk_add_f32 v[232:233], v[232:233], v[196:197]
	v_pk_add_f32 v[232:233], v[232:233], v[198:199]
	v_pk_add_f32 v[232:233], v[232:233], v[200:201]
	v_pk_add_f32 v[232:233], v[232:233], v[202:203]
	ds_read2_b32 v[188:189], v115 offset0:34 offset1:35
	ds_read2_b32 v[190:191], v115 offset0:36 offset1:37
	ds_read2_b32 v[192:193], v115 offset0:42 offset1:43
	ds_read2_b32 v[194:195], v115 offset0:44 offset1:45
	ds_read2_b32 v[196:197], v115 offset0:51 offset1:52
	ds_read2_b32 v[198:199], v115 offset0:53 offset1:54
	ds_read2_b32 v[200:201], v115 offset0:59 offset1:60
	ds_read2_b32 v[202:203], v115 offset0:61 offset1:62
	v_mfma_f32_32x32x16_bf16 v[0:15], v[64:67], v[72:75], v[0:15]
	v_mfma_f32_32x32x16_bf16 v[16:31], v[64:67], v[76:79], v[16:31]
	v_mfma_f32_32x32x16_bf16 v[0:15], v[68:71], v[220:223], v[0:15]
	v_mfma_f32_32x32x16_bf16 v[16:31], v[68:71], v[224:227], v[16:31]
	global_load_dwordx4 v[116:119], v235, s[84:85]
	global_load_dwordx4 v[120:123], v236, s[84:85]
	global_load_dwordx4 v[124:127], v237, s[84:85]
	global_load_dwordx4 v[128:131], v238, s[84:85]
	global_load_dwordx4 v[132:135], v100, s[84:85] offset:768
	global_load_dwordx4 v[136:139], v149, s[84:85] offset:768
	global_load_dwordx4 v[140:143], v100, s[84:85] offset:832
	global_load_dwordx4 v[144:147], v149, s[84:85] offset:832
	s_add_u32 s84, s84, 0x30000
	s_addc_u32 s85, s85, 0
	ds_read_b64_tr_b16 v[72:73], v231
	ds_read_b64_tr_b16 v[74:75], v231 offset:512
	ds_read_b64_tr_b16 v[76:77], v231 offset:2048
	ds_read_b64_tr_b16 v[78:79], v231 offset:2560
	ds_read_b64_tr_b16 v[220:221], v231 offset:1024
	ds_read_b64_tr_b16 v[222:223], v231 offset:1536
	ds_read_b64_tr_b16 v[224:225], v231 offset:3072
	ds_read_b64_tr_b16 v[226:227], v231 offset:3584
	v_exp_f32_e32 v32, v32
	v_exp_f32_e32 v33, v33
	v_exp_f32_e32 v34, v34
	v_exp_f32_e32 v35, v35
	s_waitcnt vmcnt(8)
	ds_write_b128 v247, v[156:159]
	ds_write_b128 v247, v[160:163] offset:1024
	ds_write_b128 v247, v[164:167] offset:2048
	ds_write_b128 v247, v[168:171] offset:3072
	ds_read_b128 v[156:159], v248
	ds_read_b128 v[160:163], v249
	ds_read_b128 v[164:167], v250
	ds_read_b128 v[168:171], v251
	ds_write_b128 v112, v[172:175]
	ds_write_b128 v112, v[176:179] offset:1024
	ds_write_b128 v112, v[180:183] offset:2048
	ds_write_b128 v112, v[184:187] offset:3072
	v_exp_f32_e32 v36, v36
	v_exp_f32_e32 v37, v37
	v_exp_f32_e32 v38, v38
	v_exp_f32_e32 v39, v39
	s_waitcnt lgkmcnt(4)
	v_mfma_f32_32x32x16_bf16 v[188:203], v[156:159], v[48:51], v[188:203]
	v_exp_f32_e32 v40, v40
	v_exp_f32_e32 v41, v41
	v_mfma_f32_32x32x16_bf16 v[188:203], v[160:163], v[52:55], v[188:203]
	v_exp_f32_e32 v42, v42
	v_exp_f32_e32 v43, v43
	v_mfma_f32_32x32x16_bf16 v[188:203], v[164:167], v[56:59], v[188:203]
	v_exp_f32_e32 v44, v44
	v_exp_f32_e32 v45, v45
	v_mfma_f32_32x32x16_bf16 v[188:203], v[168:171], v[60:63], v[188:203]
	v_exp_f32_e32 v46, v46
	v_exp_f32_e32 v47, v47
	v_cvt_pk_bf16_f32 v64, v32, v33
	v_cvt_pk_bf16_f32 v65, v34, v35
	v_cvt_pk_bf16_f32 v66, v36, v37
	v_cvt_pk_bf16_f32 v67, v38, v39
	v_cvt_pk_bf16_f32 v68, v40, v41
	v_cvt_pk_bf16_f32 v69, v42, v43
	v_cvt_pk_bf16_f32 v70, v44, v45
	v_cvt_pk_bf16_f32 v71, v46, v47
	v_pk_add_f32 v[232:233], v[232:233], v[32:33]
	v_pk_add_f32 v[232:233], v[232:233], v[34:35]
	v_pk_add_f32 v[232:233], v[232:233], v[36:37]
	v_pk_add_f32 v[232:233], v[232:233], v[38:39]
	v_pk_add_f32 v[232:233], v[232:233], v[40:41]
	v_pk_add_f32 v[232:233], v[232:233], v[42:43]
	v_pk_add_f32 v[232:233], v[232:233], v[44:45]
	v_pk_add_f32 v[232:233], v[232:233], v[46:47]
	ds_read2_b32 v[32:33], v115 offset0:68 offset1:69
	ds_read2_b32 v[34:35], v115 offset0:70 offset1:71
	ds_read2_b32 v[36:37], v115 offset0:76 offset1:77
	ds_read2_b32 v[38:39], v115 offset0:78 offset1:79
	ds_read2_b32 v[40:41], v115 offset0:85 offset1:86
	ds_read2_b32 v[42:43], v115 offset0:87 offset1:88
	ds_read2_b32 v[44:45], v115 offset0:93 offset1:94
	ds_read2_b32 v[46:47], v115 offset0:95 offset1:96
	v_mfma_f32_32x32x16_bf16 v[0:15], v[64:67], v[72:75], v[0:15]
	v_mfma_f32_32x32x16_bf16 v[16:31], v[64:67], v[76:79], v[16:31]
	v_mfma_f32_32x32x16_bf16 v[0:15], v[68:71], v[220:223], v[0:15]
	v_mfma_f32_32x32x16_bf16 v[16:31], v[68:71], v[224:227], v[16:31]
	global_load_dwordx4 v[156:159], v235, s[84:85]
	global_load_dwordx4 v[160:163], v236, s[84:85]
	global_load_dwordx4 v[164:167], v237, s[84:85]
	global_load_dwordx4 v[168:171], v238, s[84:85]
	global_load_dwordx4 v[172:175], v100, s[84:85] offset:768
	global_load_dwordx4 v[176:179], v149, s[84:85] offset:768
	global_load_dwordx4 v[180:183], v100, s[84:85] offset:832
	global_load_dwordx4 v[184:187], v149, s[84:85] offset:832
	s_add_u32 s84, s84, 0x30000
	s_addc_u32 s85, s85, 0
	ds_read_b64_tr_b16 v[72:73], v231
	ds_read_b64_tr_b16 v[74:75], v231 offset:512
	ds_read_b64_tr_b16 v[76:77], v231 offset:2048
	ds_read_b64_tr_b16 v[78:79], v231 offset:2560
	ds_read_b64_tr_b16 v[220:221], v231 offset:1024
	ds_read_b64_tr_b16 v[222:223], v231 offset:1536
	ds_read_b64_tr_b16 v[224:225], v231 offset:3072
	ds_read_b64_tr_b16 v[226:227], v231 offset:3584
	v_exp_f32_e32 v188, v188
	v_exp_f32_e32 v189, v189
	v_exp_f32_e32 v190, v190
	v_exp_f32_e32 v191, v191
	s_waitcnt vmcnt(8)
	ds_write_b128 v247, v[116:119]
	ds_write_b128 v247, v[120:123] offset:1024
	ds_write_b128 v247, v[124:127] offset:2048
	ds_write_b128 v247, v[128:131] offset:3072
	ds_read_b128 v[116:119], v248
	ds_read_b128 v[120:123], v249
	ds_read_b128 v[124:127], v250
	ds_read_b128 v[128:131], v251
	ds_write_b128 v112, v[132:135]
	ds_write_b128 v112, v[136:139] offset:1024
	ds_write_b128 v112, v[140:143] offset:2048
	ds_write_b128 v112, v[144:147] offset:3072
	v_exp_f32_e32 v192, v192
	v_exp_f32_e32 v193, v193
	v_exp_f32_e32 v194, v194
	v_exp_f32_e32 v195, v195
	s_waitcnt lgkmcnt(4)
	v_mfma_f32_32x32x16_bf16 v[32:47], v[116:119], v[48:51], v[32:47]
	v_exp_f32_e32 v196, v196
	v_exp_f32_e32 v197, v197
	v_mfma_f32_32x32x16_bf16 v[32:47], v[120:123], v[52:55], v[32:47]
	v_exp_f32_e32 v198, v198
	v_exp_f32_e32 v199, v199
	v_mfma_f32_32x32x16_bf16 v[32:47], v[124:127], v[56:59], v[32:47]
	v_exp_f32_e32 v200, v200
	v_exp_f32_e32 v201, v201
	v_mfma_f32_32x32x16_bf16 v[32:47], v[128:131], v[60:63], v[32:47]
	v_exp_f32_e32 v202, v202
	v_exp_f32_e32 v203, v203
	v_cvt_pk_bf16_f32 v64, v188, v189
	v_cvt_pk_bf16_f32 v65, v190, v191
	v_cvt_pk_bf16_f32 v66, v192, v193
	v_cvt_pk_bf16_f32 v67, v194, v195
	v_cvt_pk_bf16_f32 v68, v196, v197
	v_cvt_pk_bf16_f32 v69, v198, v199
	v_cvt_pk_bf16_f32 v70, v200, v201
	v_cvt_pk_bf16_f32 v71, v202, v203
	v_pk_add_f32 v[232:233], v[232:233], v[188:189]
	v_pk_add_f32 v[232:233], v[232:233], v[190:191]
	v_pk_add_f32 v[232:233], v[232:233], v[192:193]
	v_pk_add_f32 v[232:233], v[232:233], v[194:195]
	v_pk_add_f32 v[232:233], v[232:233], v[196:197]
	v_pk_add_f32 v[232:233], v[232:233], v[198:199]
	v_pk_add_f32 v[232:233], v[232:233], v[200:201]
	v_pk_add_f32 v[232:233], v[232:233], v[202:203]
	ds_read2_b32 v[188:189], v115 offset0:102 offset1:103
	ds_read2_b32 v[190:191], v115 offset0:104 offset1:105
	ds_read2_b32 v[192:193], v115 offset0:110 offset1:111
	ds_read2_b32 v[194:195], v115 offset0:112 offset1:113
	ds_read2_b32 v[196:197], v115 offset0:119 offset1:120
	ds_read2_b32 v[198:199], v115 offset0:121 offset1:122
	ds_read2_b32 v[200:201], v115 offset0:127 offset1:128
	ds_read2_b32 v[202:203], v115 offset0:129 offset1:130
	v_mfma_f32_32x32x16_bf16 v[0:15], v[64:67], v[72:75], v[0:15]
	v_mfma_f32_32x32x16_bf16 v[16:31], v[64:67], v[76:79], v[16:31]
	v_mfma_f32_32x32x16_bf16 v[0:15], v[68:71], v[220:223], v[0:15]
	v_mfma_f32_32x32x16_bf16 v[16:31], v[68:71], v[224:227], v[16:31]
	global_load_dwordx4 v[116:119], v235, s[84:85]
	global_load_dwordx4 v[120:123], v236, s[84:85]
	global_load_dwordx4 v[124:127], v237, s[84:85]
	global_load_dwordx4 v[128:131], v238, s[84:85]
	global_load_dwordx4 v[132:135], v100, s[84:85] offset:768
	global_load_dwordx4 v[136:139], v149, s[84:85] offset:768
	global_load_dwordx4 v[140:143], v100, s[84:85] offset:832
	global_load_dwordx4 v[144:147], v149, s[84:85] offset:832
	s_add_u32 s84, s84, 0x30000
	s_addc_u32 s85, s85, 0
	ds_read_b64_tr_b16 v[72:73], v231
	ds_read_b64_tr_b16 v[74:75], v231 offset:512
	ds_read_b64_tr_b16 v[76:77], v231 offset:2048
	ds_read_b64_tr_b16 v[78:79], v231 offset:2560
	ds_read_b64_tr_b16 v[220:221], v231 offset:1024
	ds_read_b64_tr_b16 v[222:223], v231 offset:1536
	ds_read_b64_tr_b16 v[224:225], v231 offset:3072
	ds_read_b64_tr_b16 v[226:227], v231 offset:3584
	v_exp_f32_e32 v32, v32
	v_exp_f32_e32 v33, v33
	v_exp_f32_e32 v34, v34
	v_exp_f32_e32 v35, v35
	s_waitcnt vmcnt(8)
	ds_write_b128 v247, v[156:159]
	ds_write_b128 v247, v[160:163] offset:1024
	ds_write_b128 v247, v[164:167] offset:2048
	ds_write_b128 v247, v[168:171] offset:3072
	ds_read_b128 v[156:159], v248
	ds_read_b128 v[160:163], v249
	ds_read_b128 v[164:167], v250
	ds_read_b128 v[168:171], v251
	ds_write_b128 v112, v[172:175]
	ds_write_b128 v112, v[176:179] offset:1024
	ds_write_b128 v112, v[180:183] offset:2048
	ds_write_b128 v112, v[184:187] offset:3072
	v_exp_f32_e32 v36, v36
	v_exp_f32_e32 v37, v37
	v_exp_f32_e32 v38, v38
	v_exp_f32_e32 v39, v39
	s_waitcnt lgkmcnt(4)
	v_mfma_f32_32x32x16_bf16 v[188:203], v[156:159], v[48:51], v[188:203]
	v_exp_f32_e32 v40, v40
	v_exp_f32_e32 v41, v41
	v_mfma_f32_32x32x16_bf16 v[188:203], v[160:163], v[52:55], v[188:203]
	v_exp_f32_e32 v42, v42
	v_exp_f32_e32 v43, v43
	v_mfma_f32_32x32x16_bf16 v[188:203], v[164:167], v[56:59], v[188:203]
	v_exp_f32_e32 v44, v44
	v_exp_f32_e32 v45, v45
	v_mfma_f32_32x32x16_bf16 v[188:203], v[168:171], v[60:63], v[188:203]
	v_exp_f32_e32 v46, v46
	v_exp_f32_e32 v47, v47
	v_cvt_pk_bf16_f32 v64, v32, v33
	v_cvt_pk_bf16_f32 v65, v34, v35
	v_cvt_pk_bf16_f32 v66, v36, v37
	v_cvt_pk_bf16_f32 v67, v38, v39
	v_cvt_pk_bf16_f32 v68, v40, v41
	v_cvt_pk_bf16_f32 v69, v42, v43
	v_cvt_pk_bf16_f32 v70, v44, v45
	v_cvt_pk_bf16_f32 v71, v46, v47
	v_pk_add_f32 v[232:233], v[232:233], v[32:33]
	v_pk_add_f32 v[232:233], v[232:233], v[34:35]
	v_pk_add_f32 v[232:233], v[232:233], v[36:37]
	v_pk_add_f32 v[232:233], v[232:233], v[38:39]
	v_pk_add_f32 v[232:233], v[232:233], v[40:41]
	v_pk_add_f32 v[232:233], v[232:233], v[42:43]
	v_pk_add_f32 v[232:233], v[232:233], v[44:45]
	v_pk_add_f32 v[232:233], v[232:233], v[46:47]
	ds_read2_b32 v[32:33], v115 offset0:136 offset1:137
	ds_read2_b32 v[34:35], v115 offset0:138 offset1:139
	ds_read2_b32 v[36:37], v115 offset0:144 offset1:145
	ds_read2_b32 v[38:39], v115 offset0:146 offset1:147
	ds_read2_b32 v[40:41], v115 offset0:153 offset1:154
	ds_read2_b32 v[42:43], v115 offset0:155 offset1:156
	ds_read2_b32 v[44:45], v115 offset0:161 offset1:162
	ds_read2_b32 v[46:47], v115 offset0:163 offset1:164
	v_mfma_f32_32x32x16_bf16 v[0:15], v[64:67], v[72:75], v[0:15]
	v_mfma_f32_32x32x16_bf16 v[16:31], v[64:67], v[76:79], v[16:31]
	v_mfma_f32_32x32x16_bf16 v[0:15], v[68:71], v[220:223], v[0:15]
	v_mfma_f32_32x32x16_bf16 v[16:31], v[68:71], v[224:227], v[16:31]
	global_load_dwordx4 v[156:159], v235, s[84:85]
	global_load_dwordx4 v[160:163], v236, s[84:85]
	global_load_dwordx4 v[164:167], v237, s[84:85]
	global_load_dwordx4 v[168:171], v238, s[84:85]
	global_load_dwordx4 v[172:175], v100, s[84:85] offset:768
	global_load_dwordx4 v[176:179], v149, s[84:85] offset:768
	global_load_dwordx4 v[180:183], v100, s[84:85] offset:832
	global_load_dwordx4 v[184:187], v149, s[84:85] offset:832
	ds_read_b64_tr_b16 v[72:73], v231
	ds_read_b64_tr_b16 v[74:75], v231 offset:512
	ds_read_b64_tr_b16 v[76:77], v231 offset:2048
	ds_read_b64_tr_b16 v[78:79], v231 offset:2560
	ds_read_b64_tr_b16 v[220:221], v231 offset:1024
	ds_read_b64_tr_b16 v[222:223], v231 offset:1536
	ds_read_b64_tr_b16 v[224:225], v231 offset:3072
	ds_read_b64_tr_b16 v[226:227], v231 offset:3584
	v_exp_f32_e32 v188, v188
	v_exp_f32_e32 v189, v189
	v_exp_f32_e32 v190, v190
	v_exp_f32_e32 v191, v191
	s_waitcnt vmcnt(8)
	ds_write_b128 v247, v[116:119]
	ds_write_b128 v247, v[120:123] offset:1024
	ds_write_b128 v247, v[124:127] offset:2048
	ds_write_b128 v247, v[128:131] offset:3072
	ds_read_b128 v[116:119], v248
	ds_read_b128 v[120:123], v249
	ds_read_b128 v[124:127], v250
	ds_read_b128 v[128:131], v251
	ds_write_b128 v112, v[132:135]
	ds_write_b128 v112, v[136:139] offset:1024
	ds_write_b128 v112, v[140:143] offset:2048
	ds_write_b128 v112, v[144:147] offset:3072
	v_exp_f32_e32 v192, v192
	v_exp_f32_e32 v193, v193
	v_exp_f32_e32 v194, v194
	v_exp_f32_e32 v195, v195
	s_waitcnt lgkmcnt(4)
	v_mfma_f32_32x32x16_bf16 v[32:47], v[116:119], v[48:51], v[32:47]
	v_exp_f32_e32 v196, v196
	v_exp_f32_e32 v197, v197
	v_mfma_f32_32x32x16_bf16 v[32:47], v[120:123], v[52:55], v[32:47]
	v_exp_f32_e32 v198, v198
	v_exp_f32_e32 v199, v199
	v_mfma_f32_32x32x16_bf16 v[32:47], v[124:127], v[56:59], v[32:47]
	v_exp_f32_e32 v200, v200
	v_exp_f32_e32 v201, v201
	v_mfma_f32_32x32x16_bf16 v[32:47], v[128:131], v[60:63], v[32:47]
	v_exp_f32_e32 v202, v202
	v_exp_f32_e32 v203, v203
	v_cvt_pk_bf16_f32 v64, v188, v189
	v_cvt_pk_bf16_f32 v65, v190, v191
	v_cvt_pk_bf16_f32 v66, v192, v193
	v_cvt_pk_bf16_f32 v67, v194, v195
	v_cvt_pk_bf16_f32 v68, v196, v197
	v_cvt_pk_bf16_f32 v69, v198, v199
	v_cvt_pk_bf16_f32 v70, v200, v201
	v_cvt_pk_bf16_f32 v71, v202, v203
	v_pk_add_f32 v[232:233], v[232:233], v[188:189]
	v_pk_add_f32 v[232:233], v[232:233], v[190:191]
	v_pk_add_f32 v[232:233], v[232:233], v[192:193]
	v_pk_add_f32 v[232:233], v[232:233], v[194:195]
	v_pk_add_f32 v[232:233], v[232:233], v[196:197]
	v_pk_add_f32 v[232:233], v[232:233], v[198:199]
	v_pk_add_f32 v[232:233], v[232:233], v[200:201]
	v_pk_add_f32 v[232:233], v[232:233], v[202:203]
	ds_read2_b32 v[188:189], v115 offset0:170 offset1:171
	ds_read2_b32 v[190:191], v115 offset0:172 offset1:173
	ds_read2_b32 v[192:193], v115 offset0:178 offset1:179
	ds_read2_b32 v[194:195], v115 offset0:180 offset1:181
	ds_read2_b32 v[196:197], v115 offset0:187 offset1:188
	ds_read2_b32 v[198:199], v115 offset0:189 offset1:190
	ds_read2_b32 v[200:201], v115 offset0:195 offset1:196
	ds_read2_b32 v[202:203], v115 offset0:197 offset1:198
	v_mfma_f32_32x32x16_bf16 v[0:15], v[64:67], v[72:75], v[0:15]
	v_mfma_f32_32x32x16_bf16 v[16:31], v[64:67], v[76:79], v[16:31]
	v_mfma_f32_32x32x16_bf16 v[0:15], v[68:71], v[220:223], v[0:15]
	v_mfma_f32_32x32x16_bf16 v[16:31], v[68:71], v[224:227], v[16:31]
	global_load_dwordx4 v[116:119], v239, s[86:87]
	global_load_dwordx4 v[120:123], v240, s[86:87]
	global_load_dwordx4 v[124:127], v241, s[86:87]
	global_load_dwordx4 v[128:131], v242, s[86:87]
	global_load_dwordx4 v[132:135], v101, s[86:87] offset:768
	global_load_dwordx4 v[136:139], v150, s[86:87] offset:768
	global_load_dwordx4 v[140:143], v101, s[86:87] offset:832
	global_load_dwordx4 v[144:147], v150, s[86:87] offset:832
	s_add_u32 s86, s86, 0xc0000
	s_addc_u32 s87, s87, 0
	ds_read_b64_tr_b16 v[72:73], v231
	ds_read_b64_tr_b16 v[74:75], v231 offset:512
	ds_read_b64_tr_b16 v[76:77], v231 offset:2048
	ds_read_b64_tr_b16 v[78:79], v231 offset:2560
	ds_read_b64_tr_b16 v[220:221], v231 offset:1024
	ds_read_b64_tr_b16 v[222:223], v231 offset:1536
	ds_read_b64_tr_b16 v[224:225], v231 offset:3072
	ds_read_b64_tr_b16 v[226:227], v231 offset:3584
	v_exp_f32_e32 v32, v32
	v_exp_f32_e32 v33, v33
	v_exp_f32_e32 v34, v34
	v_exp_f32_e32 v35, v35
	s_waitcnt vmcnt(8)
	ds_write_b128 v247, v[156:159]
	ds_write_b128 v247, v[160:163] offset:1024
	ds_write_b128 v247, v[164:167] offset:2048
	ds_write_b128 v247, v[168:171] offset:3072
	ds_read_b128 v[156:159], v248
	ds_read_b128 v[160:163], v249
	ds_read_b128 v[164:167], v250
	ds_read_b128 v[168:171], v251
	ds_write_b128 v112, v[172:175]
	ds_write_b128 v112, v[176:179] offset:1024
	ds_write_b128 v112, v[180:183] offset:2048
	ds_write_b128 v112, v[184:187] offset:3072
	v_exp_f32_e32 v36, v36
	v_exp_f32_e32 v37, v37
	v_exp_f32_e32 v38, v38
	v_exp_f32_e32 v39, v39
	s_waitcnt lgkmcnt(4)
	v_mfma_f32_32x32x16_bf16 v[188:203], v[156:159], v[48:51], v[188:203]
	v_exp_f32_e32 v40, v40
	v_exp_f32_e32 v41, v41
	v_mfma_f32_32x32x16_bf16 v[188:203], v[160:163], v[52:55], v[188:203]
	v_exp_f32_e32 v42, v42
	v_exp_f32_e32 v43, v43
	v_mfma_f32_32x32x16_bf16 v[188:203], v[164:167], v[56:59], v[188:203]
	v_exp_f32_e32 v44, v44
	v_exp_f32_e32 v45, v45
	v_mfma_f32_32x32x16_bf16 v[188:203], v[168:171], v[60:63], v[188:203]
	v_exp_f32_e32 v46, v46
	v_exp_f32_e32 v47, v47
	v_cvt_pk_bf16_f32 v64, v32, v33
	v_cvt_pk_bf16_f32 v65, v34, v35
	v_cvt_pk_bf16_f32 v66, v36, v37
	v_cvt_pk_bf16_f32 v67, v38, v39
	v_cvt_pk_bf16_f32 v68, v40, v41
	v_cvt_pk_bf16_f32 v69, v42, v43
	v_cvt_pk_bf16_f32 v70, v44, v45
	v_cvt_pk_bf16_f32 v71, v46, v47
	v_pk_add_f32 v[232:233], v[232:233], v[32:33]
	v_pk_add_f32 v[232:233], v[232:233], v[34:35]
	v_pk_add_f32 v[232:233], v[232:233], v[36:37]
	v_pk_add_f32 v[232:233], v[232:233], v[38:39]
	v_pk_add_f32 v[232:233], v[232:233], v[40:41]
	v_pk_add_f32 v[232:233], v[232:233], v[42:43]
	v_pk_add_f32 v[232:233], v[232:233], v[44:45]
	v_pk_add_f32 v[232:233], v[232:233], v[46:47]
	v_mov_b32_e32 v115, v229
	ds_read2_b32 v[32:33], v115 offset0:0 offset1:1
	ds_read2_b32 v[34:35], v115 offset0:2 offset1:3
	ds_read2_b32 v[36:37], v115 offset0:8 offset1:9
	ds_read2_b32 v[38:39], v115 offset0:10 offset1:11
	ds_read2_b32 v[40:41], v115 offset0:16 offset1:17
	ds_read2_b32 v[42:43], v115 offset0:18 offset1:19
	ds_read2_b32 v[44:45], v115 offset0:24 offset1:25
	ds_read2_b32 v[46:47], v115 offset0:26 offset1:27
	v_mfma_f32_32x32x16_bf16 v[0:15], v[64:67], v[72:75], v[0:15]
	v_mfma_f32_32x32x16_bf16 v[16:31], v[64:67], v[76:79], v[16:31]
	v_mfma_f32_32x32x16_bf16 v[0:15], v[68:71], v[220:223], v[0:15]
	v_mfma_f32_32x32x16_bf16 v[16:31], v[68:71], v[224:227], v[16:31]
	global_load_dwordx4 v[156:159], v239, s[86:87]
	global_load_dwordx4 v[160:163], v240, s[86:87]
	global_load_dwordx4 v[164:167], v241, s[86:87]
	global_load_dwordx4 v[168:171], v242, s[86:87]
	global_load_dwordx4 v[172:175], v101, s[86:87] offset:768
	global_load_dwordx4 v[176:179], v150, s[86:87] offset:768
	global_load_dwordx4 v[180:183], v101, s[86:87] offset:832
	global_load_dwordx4 v[184:187], v150, s[86:87] offset:832
	s_add_u32 s86, s86, 0xc0000
	s_addc_u32 s87, s87, 0
	ds_read_b64_tr_b16 v[72:73], v231
	ds_read_b64_tr_b16 v[74:75], v231 offset:512
	ds_read_b64_tr_b16 v[76:77], v231 offset:2048
	ds_read_b64_tr_b16 v[78:79], v231 offset:2560
	ds_read_b64_tr_b16 v[220:221], v231 offset:1024
	ds_read_b64_tr_b16 v[222:223], v231 offset:1536
	ds_read_b64_tr_b16 v[224:225], v231 offset:3072
	ds_read_b64_tr_b16 v[226:227], v231 offset:3584
	v_exp_f32_e32 v188, v188
	v_exp_f32_e32 v189, v189
	v_exp_f32_e32 v190, v190
	v_exp_f32_e32 v191, v191
	s_waitcnt vmcnt(8)
	ds_write_b128 v247, v[116:119]
	ds_write_b128 v247, v[120:123] offset:1024
	ds_write_b128 v247, v[124:127] offset:2048
	ds_write_b128 v247, v[128:131] offset:3072
	ds_read_b128 v[116:119], v248
	ds_read_b128 v[120:123], v249
	ds_read_b128 v[124:127], v250
	ds_read_b128 v[128:131], v251
	ds_write_b128 v112, v[132:135]
	ds_write_b128 v112, v[136:139] offset:1024
	ds_write_b128 v112, v[140:143] offset:2048
	ds_write_b128 v112, v[144:147] offset:3072
	v_exp_f32_e32 v192, v192
	v_exp_f32_e32 v193, v193
	v_exp_f32_e32 v194, v194
	v_exp_f32_e32 v195, v195
	s_waitcnt lgkmcnt(4)
	v_mfma_f32_32x32x16_bf16 v[32:47], v[116:119], v[48:51], v[32:47]
	v_exp_f32_e32 v196, v196
	v_exp_f32_e32 v197, v197
	v_mfma_f32_32x32x16_bf16 v[32:47], v[120:123], v[52:55], v[32:47]
	v_exp_f32_e32 v198, v198
	v_exp_f32_e32 v199, v199
	v_mfma_f32_32x32x16_bf16 v[32:47], v[124:127], v[56:59], v[32:47]
	v_exp_f32_e32 v200, v200
	v_exp_f32_e32 v201, v201
	v_mfma_f32_32x32x16_bf16 v[32:47], v[128:131], v[60:63], v[32:47]
	v_exp_f32_e32 v202, v202
	v_exp_f32_e32 v203, v203
	v_cvt_pk_bf16_f32 v64, v188, v189
	v_cvt_pk_bf16_f32 v65, v190, v191
	v_cvt_pk_bf16_f32 v66, v192, v193
	v_cvt_pk_bf16_f32 v67, v194, v195
	v_cvt_pk_bf16_f32 v68, v196, v197
	v_cvt_pk_bf16_f32 v69, v198, v199
	v_cvt_pk_bf16_f32 v70, v200, v201
	v_cvt_pk_bf16_f32 v71, v202, v203
	v_pk_add_f32 v[232:233], v[232:233], v[188:189]
	v_pk_add_f32 v[232:233], v[232:233], v[190:191]
	v_pk_add_f32 v[232:233], v[232:233], v[192:193]
	v_pk_add_f32 v[232:233], v[232:233], v[194:195]
	v_pk_add_f32 v[232:233], v[232:233], v[196:197]
	v_pk_add_f32 v[232:233], v[232:233], v[198:199]
	v_pk_add_f32 v[232:233], v[232:233], v[200:201]
	v_pk_add_f32 v[232:233], v[232:233], v[202:203]
	ds_read2_b32 v[188:189], v115 offset0:32 offset1:33
	ds_read2_b32 v[190:191], v115 offset0:34 offset1:35
	ds_read2_b32 v[192:193], v115 offset0:40 offset1:41
	ds_read2_b32 v[194:195], v115 offset0:42 offset1:43
	ds_read2_b32 v[196:197], v115 offset0:48 offset1:49
	ds_read2_b32 v[198:199], v115 offset0:50 offset1:51
	ds_read2_b32 v[200:201], v115 offset0:56 offset1:57
	ds_read2_b32 v[202:203], v115 offset0:58 offset1:59
	v_mfma_f32_32x32x16_bf16 v[0:15], v[64:67], v[72:75], v[0:15]
	v_mfma_f32_32x32x16_bf16 v[16:31], v[64:67], v[76:79], v[16:31]
	v_mfma_f32_32x32x16_bf16 v[0:15], v[68:71], v[220:223], v[0:15]
	v_mfma_f32_32x32x16_bf16 v[16:31], v[68:71], v[224:227], v[16:31]
	global_load_dwordx4 v[116:119], v239, s[86:87]
	global_load_dwordx4 v[120:123], v240, s[86:87]
	global_load_dwordx4 v[124:127], v241, s[86:87]
	global_load_dwordx4 v[128:131], v242, s[86:87]
	global_load_dwordx4 v[132:135], v101, s[86:87] offset:768
	global_load_dwordx4 v[136:139], v150, s[86:87] offset:768
	global_load_dwordx4 v[140:143], v101, s[86:87] offset:832
	global_load_dwordx4 v[144:147], v150, s[86:87] offset:832
	s_add_u32 s86, s86, 0xc0000
	s_addc_u32 s87, s87, 0
	ds_read_b64_tr_b16 v[72:73], v231
	ds_read_b64_tr_b16 v[74:75], v231 offset:512
	ds_read_b64_tr_b16 v[76:77], v231 offset:2048
	ds_read_b64_tr_b16 v[78:79], v231 offset:2560
	ds_read_b64_tr_b16 v[220:221], v231 offset:1024
	ds_read_b64_tr_b16 v[222:223], v231 offset:1536
	ds_read_b64_tr_b16 v[224:225], v231 offset:3072
	ds_read_b64_tr_b16 v[226:227], v231 offset:3584
	v_exp_f32_e32 v32, v32
	v_exp_f32_e32 v33, v33
	v_exp_f32_e32 v34, v34
	v_exp_f32_e32 v35, v35
	s_waitcnt vmcnt(8)
	ds_write_b128 v247, v[156:159]
	ds_write_b128 v247, v[160:163] offset:1024
	ds_write_b128 v247, v[164:167] offset:2048
	ds_write_b128 v247, v[168:171] offset:3072
	ds_read_b128 v[156:159], v248
	ds_read_b128 v[160:163], v249
	ds_read_b128 v[164:167], v250
	ds_read_b128 v[168:171], v251
	ds_write_b128 v112, v[172:175]
	ds_write_b128 v112, v[176:179] offset:1024
	ds_write_b128 v112, v[180:183] offset:2048
	ds_write_b128 v112, v[184:187] offset:3072
	v_exp_f32_e32 v36, v36
	v_exp_f32_e32 v37, v37
	v_exp_f32_e32 v38, v38
	v_exp_f32_e32 v39, v39
	s_waitcnt lgkmcnt(4)
	v_mfma_f32_32x32x16_bf16 v[188:203], v[156:159], v[48:51], v[188:203]
	v_exp_f32_e32 v40, v40
	v_exp_f32_e32 v41, v41
	v_mfma_f32_32x32x16_bf16 v[188:203], v[160:163], v[52:55], v[188:203]
	v_exp_f32_e32 v42, v42
	v_exp_f32_e32 v43, v43
	v_mfma_f32_32x32x16_bf16 v[188:203], v[164:167], v[56:59], v[188:203]
	v_exp_f32_e32 v44, v44
	v_exp_f32_e32 v45, v45
	v_mfma_f32_32x32x16_bf16 v[188:203], v[168:171], v[60:63], v[188:203]
	v_exp_f32_e32 v46, v46
	v_exp_f32_e32 v47, v47
	v_cvt_pk_bf16_f32 v64, v32, v33
	v_cvt_pk_bf16_f32 v65, v34, v35
	v_cvt_pk_bf16_f32 v66, v36, v37
	v_cvt_pk_bf16_f32 v67, v38, v39
	v_cvt_pk_bf16_f32 v68, v40, v41
	v_cvt_pk_bf16_f32 v69, v42, v43
	v_cvt_pk_bf16_f32 v70, v44, v45
	v_cvt_pk_bf16_f32 v71, v46, v47
	v_pk_add_f32 v[232:233], v[232:233], v[32:33]
	v_pk_add_f32 v[232:233], v[232:233], v[34:35]
	v_pk_add_f32 v[232:233], v[232:233], v[36:37]
	v_pk_add_f32 v[232:233], v[232:233], v[38:39]
	v_pk_add_f32 v[232:233], v[232:233], v[40:41]
	v_pk_add_f32 v[232:233], v[232:233], v[42:43]
	v_pk_add_f32 v[232:233], v[232:233], v[44:45]
	v_pk_add_f32 v[232:233], v[232:233], v[46:47]
	ds_read2_b32 v[32:33], v115 offset0:64 offset1:65
	ds_read2_b32 v[34:35], v115 offset0:66 offset1:67
	ds_read2_b32 v[36:37], v115 offset0:72 offset1:73
	ds_read2_b32 v[38:39], v115 offset0:74 offset1:75
	ds_read2_b32 v[40:41], v115 offset0:80 offset1:81
	ds_read2_b32 v[42:43], v115 offset0:82 offset1:83
	ds_read2_b32 v[44:45], v115 offset0:88 offset1:89
	ds_read2_b32 v[46:47], v115 offset0:90 offset1:91
	v_mfma_f32_32x32x16_bf16 v[0:15], v[64:67], v[72:75], v[0:15]
	v_mfma_f32_32x32x16_bf16 v[16:31], v[64:67], v[76:79], v[16:31]
	v_mfma_f32_32x32x16_bf16 v[0:15], v[68:71], v[220:223], v[0:15]
	v_mfma_f32_32x32x16_bf16 v[16:31], v[68:71], v[224:227], v[16:31]
	global_load_dwordx4 v[156:159], v239, s[86:87]
	global_load_dwordx4 v[160:163], v240, s[86:87]
	global_load_dwordx4 v[164:167], v241, s[86:87]
	global_load_dwordx4 v[168:171], v242, s[86:87]
	global_load_dwordx4 v[172:175], v101, s[86:87] offset:768
	global_load_dwordx4 v[176:179], v150, s[86:87] offset:768
	global_load_dwordx4 v[180:183], v101, s[86:87] offset:832
	global_load_dwordx4 v[184:187], v150, s[86:87] offset:832
	s_add_u32 s86, s86, 0xc0000
	s_addc_u32 s87, s87, 0
	ds_read_b64_tr_b16 v[72:73], v231
	ds_read_b64_tr_b16 v[74:75], v231 offset:512
	ds_read_b64_tr_b16 v[76:77], v231 offset:2048
	ds_read_b64_tr_b16 v[78:79], v231 offset:2560
	ds_read_b64_tr_b16 v[220:221], v231 offset:1024
	ds_read_b64_tr_b16 v[222:223], v231 offset:1536
	ds_read_b64_tr_b16 v[224:225], v231 offset:3072
	ds_read_b64_tr_b16 v[226:227], v231 offset:3584
	v_exp_f32_e32 v188, v188
	v_exp_f32_e32 v189, v189
	v_exp_f32_e32 v190, v190
	v_exp_f32_e32 v191, v191
	s_waitcnt vmcnt(8)
	ds_write_b128 v247, v[116:119]
	ds_write_b128 v247, v[120:123] offset:1024
	ds_write_b128 v247, v[124:127] offset:2048
	ds_write_b128 v247, v[128:131] offset:3072
	ds_read_b128 v[116:119], v248
	ds_read_b128 v[120:123], v249
	ds_read_b128 v[124:127], v250
	ds_read_b128 v[128:131], v251
	ds_write_b128 v112, v[132:135]
	ds_write_b128 v112, v[136:139] offset:1024
	ds_write_b128 v112, v[140:143] offset:2048
	ds_write_b128 v112, v[144:147] offset:3072
	v_exp_f32_e32 v192, v192
	v_exp_f32_e32 v193, v193
	v_exp_f32_e32 v194, v194
	v_exp_f32_e32 v195, v195
	s_waitcnt lgkmcnt(4)
	v_mfma_f32_32x32x16_bf16 v[32:47], v[116:119], v[48:51], v[32:47]
	v_exp_f32_e32 v196, v196
	v_exp_f32_e32 v197, v197
	v_mfma_f32_32x32x16_bf16 v[32:47], v[120:123], v[52:55], v[32:47]
	v_exp_f32_e32 v198, v198
	v_exp_f32_e32 v199, v199
	v_mfma_f32_32x32x16_bf16 v[32:47], v[124:127], v[56:59], v[32:47]
	v_exp_f32_e32 v200, v200
	v_exp_f32_e32 v201, v201
	v_mfma_f32_32x32x16_bf16 v[32:47], v[128:131], v[60:63], v[32:47]
	v_exp_f32_e32 v202, v202
	v_exp_f32_e32 v203, v203
	v_cvt_pk_bf16_f32 v64, v188, v189
	v_cvt_pk_bf16_f32 v65, v190, v191
	v_cvt_pk_bf16_f32 v66, v192, v193
	v_cvt_pk_bf16_f32 v67, v194, v195
	v_cvt_pk_bf16_f32 v68, v196, v197
	v_cvt_pk_bf16_f32 v69, v198, v199
	v_cvt_pk_bf16_f32 v70, v200, v201
	v_cvt_pk_bf16_f32 v71, v202, v203
	v_pk_add_f32 v[232:233], v[232:233], v[188:189]
	v_pk_add_f32 v[232:233], v[232:233], v[190:191]
	v_pk_add_f32 v[232:233], v[232:233], v[192:193]
	v_pk_add_f32 v[232:233], v[232:233], v[194:195]
	v_pk_add_f32 v[232:233], v[232:233], v[196:197]
	v_pk_add_f32 v[232:233], v[232:233], v[198:199]
	v_pk_add_f32 v[232:233], v[232:233], v[200:201]
	v_pk_add_f32 v[232:233], v[232:233], v[202:203]
	ds_read2_b32 v[188:189], v115 offset0:96 offset1:97
	ds_read2_b32 v[190:191], v115 offset0:98 offset1:99
	ds_read2_b32 v[192:193], v115 offset0:104 offset1:105
	ds_read2_b32 v[194:195], v115 offset0:106 offset1:107
	ds_read2_b32 v[196:197], v115 offset0:112 offset1:113
	ds_read2_b32 v[198:199], v115 offset0:114 offset1:115
	ds_read2_b32 v[200:201], v115 offset0:120 offset1:121
	ds_read2_b32 v[202:203], v115 offset0:122 offset1:123
	v_mfma_f32_32x32x16_bf16 v[0:15], v[64:67], v[72:75], v[0:15]
	v_mfma_f32_32x32x16_bf16 v[16:31], v[64:67], v[76:79], v[16:31]
	v_mfma_f32_32x32x16_bf16 v[0:15], v[68:71], v[220:223], v[0:15]
	v_mfma_f32_32x32x16_bf16 v[16:31], v[68:71], v[224:227], v[16:31]
	global_load_dwordx4 v[116:119], v239, s[86:87]
	global_load_dwordx4 v[120:123], v240, s[86:87]
	global_load_dwordx4 v[124:127], v241, s[86:87]
	global_load_dwordx4 v[128:131], v242, s[86:87]
	global_load_dwordx4 v[132:135], v101, s[86:87] offset:768
	global_load_dwordx4 v[136:139], v150, s[86:87] offset:768
	global_load_dwordx4 v[140:143], v101, s[86:87] offset:832
	global_load_dwordx4 v[144:147], v150, s[86:87] offset:832
	s_add_u32 s86, s86, 0xc0000
	s_addc_u32 s87, s87, 0
	ds_read_b64_tr_b16 v[72:73], v231
	ds_read_b64_tr_b16 v[74:75], v231 offset:512
	ds_read_b64_tr_b16 v[76:77], v231 offset:2048
	ds_read_b64_tr_b16 v[78:79], v231 offset:2560
	ds_read_b64_tr_b16 v[220:221], v231 offset:1024
	ds_read_b64_tr_b16 v[222:223], v231 offset:1536
	ds_read_b64_tr_b16 v[224:225], v231 offset:3072
	ds_read_b64_tr_b16 v[226:227], v231 offset:3584
	v_exp_f32_e32 v32, v32
	v_exp_f32_e32 v33, v33
	v_exp_f32_e32 v34, v34
	v_exp_f32_e32 v35, v35
	s_waitcnt vmcnt(8)
	ds_write_b128 v247, v[156:159]
	ds_write_b128 v247, v[160:163] offset:1024
	ds_write_b128 v247, v[164:167] offset:2048
	ds_write_b128 v247, v[168:171] offset:3072
	ds_read_b128 v[156:159], v248
	ds_read_b128 v[160:163], v249
	ds_read_b128 v[164:167], v250
	ds_read_b128 v[168:171], v251
	ds_write_b128 v112, v[172:175]
	ds_write_b128 v112, v[176:179] offset:1024
	ds_write_b128 v112, v[180:183] offset:2048
	ds_write_b128 v112, v[184:187] offset:3072
	v_exp_f32_e32 v36, v36
	v_exp_f32_e32 v37, v37
	v_exp_f32_e32 v38, v38
	v_exp_f32_e32 v39, v39
	s_waitcnt lgkmcnt(4)
	v_mfma_f32_32x32x16_bf16 v[188:203], v[156:159], v[48:51], v[188:203]
	v_exp_f32_e32 v40, v40
	v_exp_f32_e32 v41, v41
	v_mfma_f32_32x32x16_bf16 v[188:203], v[160:163], v[52:55], v[188:203]
	v_exp_f32_e32 v42, v42
	v_exp_f32_e32 v43, v43
	v_mfma_f32_32x32x16_bf16 v[188:203], v[164:167], v[56:59], v[188:203]
	v_exp_f32_e32 v44, v44
	v_exp_f32_e32 v45, v45
	v_mfma_f32_32x32x16_bf16 v[188:203], v[168:171], v[60:63], v[188:203]
	v_exp_f32_e32 v46, v46
	v_exp_f32_e32 v47, v47
	v_cvt_pk_bf16_f32 v64, v32, v33
	v_cvt_pk_bf16_f32 v65, v34, v35
	v_cvt_pk_bf16_f32 v66, v36, v37
	v_cvt_pk_bf16_f32 v67, v38, v39
	v_cvt_pk_bf16_f32 v68, v40, v41
	v_cvt_pk_bf16_f32 v69, v42, v43
	v_cvt_pk_bf16_f32 v70, v44, v45
	v_cvt_pk_bf16_f32 v71, v46, v47
	v_pk_add_f32 v[232:233], v[232:233], v[32:33]
	v_pk_add_f32 v[232:233], v[232:233], v[34:35]
	v_pk_add_f32 v[232:233], v[232:233], v[36:37]
	v_pk_add_f32 v[232:233], v[232:233], v[38:39]
	v_pk_add_f32 v[232:233], v[232:233], v[40:41]
	v_pk_add_f32 v[232:233], v[232:233], v[42:43]
	v_pk_add_f32 v[232:233], v[232:233], v[44:45]
	v_pk_add_f32 v[232:233], v[232:233], v[46:47]
	ds_read2_b32 v[32:33], v115 offset0:128 offset1:129
	ds_read2_b32 v[34:35], v115 offset0:130 offset1:131
	ds_read2_b32 v[36:37], v115 offset0:136 offset1:137
	ds_read2_b32 v[38:39], v115 offset0:138 offset1:139
	ds_read2_b32 v[40:41], v115 offset0:144 offset1:145
	ds_read2_b32 v[42:43], v115 offset0:146 offset1:147
	ds_read2_b32 v[44:45], v115 offset0:152 offset1:153
	ds_read2_b32 v[46:47], v115 offset0:154 offset1:155
	v_mfma_f32_32x32x16_bf16 v[0:15], v[64:67], v[72:75], v[0:15]
	v_mfma_f32_32x32x16_bf16 v[16:31], v[64:67], v[76:79], v[16:31]
	v_mfma_f32_32x32x16_bf16 v[0:15], v[68:71], v[220:223], v[0:15]
	v_mfma_f32_32x32x16_bf16 v[16:31], v[68:71], v[224:227], v[16:31]
	global_load_dwordx4 v[156:159], v239, s[86:87]
	global_load_dwordx4 v[160:163], v240, s[86:87]
	global_load_dwordx4 v[164:167], v241, s[86:87]
	global_load_dwordx4 v[168:171], v242, s[86:87]
	global_load_dwordx4 v[172:175], v101, s[86:87] offset:768
	global_load_dwordx4 v[176:179], v150, s[86:87] offset:768
	global_load_dwordx4 v[180:183], v101, s[86:87] offset:832
	global_load_dwordx4 v[184:187], v150, s[86:87] offset:832
	s_add_u32 s86, s86, 0xc0000
	s_addc_u32 s87, s87, 0
	ds_read_b64_tr_b16 v[72:73], v231
	ds_read_b64_tr_b16 v[74:75], v231 offset:512
	ds_read_b64_tr_b16 v[76:77], v231 offset:2048
	ds_read_b64_tr_b16 v[78:79], v231 offset:2560
	ds_read_b64_tr_b16 v[220:221], v231 offset:1024
	ds_read_b64_tr_b16 v[222:223], v231 offset:1536
	ds_read_b64_tr_b16 v[224:225], v231 offset:3072
	ds_read_b64_tr_b16 v[226:227], v231 offset:3584
	v_exp_f32_e32 v188, v188
	v_exp_f32_e32 v189, v189
	v_exp_f32_e32 v190, v190
	v_exp_f32_e32 v191, v191
	s_waitcnt vmcnt(8)
	ds_write_b128 v247, v[116:119]
	ds_write_b128 v247, v[120:123] offset:1024
	ds_write_b128 v247, v[124:127] offset:2048
	ds_write_b128 v247, v[128:131] offset:3072
	ds_read_b128 v[116:119], v248
	ds_read_b128 v[120:123], v249
	ds_read_b128 v[124:127], v250
	ds_read_b128 v[128:131], v251
	ds_write_b128 v112, v[132:135]
	ds_write_b128 v112, v[136:139] offset:1024
	ds_write_b128 v112, v[140:143] offset:2048
	ds_write_b128 v112, v[144:147] offset:3072
	v_exp_f32_e32 v192, v192
	v_exp_f32_e32 v193, v193
	v_exp_f32_e32 v194, v194
	v_exp_f32_e32 v195, v195
	s_waitcnt lgkmcnt(4)
	v_mfma_f32_32x32x16_bf16 v[32:47], v[116:119], v[48:51], v[32:47]
	v_exp_f32_e32 v196, v196
	v_exp_f32_e32 v197, v197
	v_mfma_f32_32x32x16_bf16 v[32:47], v[120:123], v[52:55], v[32:47]
	v_exp_f32_e32 v198, v198
	v_exp_f32_e32 v199, v199
	v_mfma_f32_32x32x16_bf16 v[32:47], v[124:127], v[56:59], v[32:47]
	v_exp_f32_e32 v200, v200
	v_exp_f32_e32 v201, v201
	v_mfma_f32_32x32x16_bf16 v[32:47], v[128:131], v[60:63], v[32:47]
	v_exp_f32_e32 v202, v202
	v_exp_f32_e32 v203, v203
	v_cvt_pk_bf16_f32 v64, v188, v189
	v_cvt_pk_bf16_f32 v65, v190, v191
	v_cvt_pk_bf16_f32 v66, v192, v193
	v_cvt_pk_bf16_f32 v67, v194, v195
	v_cvt_pk_bf16_f32 v68, v196, v197
	v_cvt_pk_bf16_f32 v69, v198, v199
	v_cvt_pk_bf16_f32 v70, v200, v201
	v_cvt_pk_bf16_f32 v71, v202, v203
	v_pk_add_f32 v[232:233], v[232:233], v[188:189]
	v_pk_add_f32 v[232:233], v[232:233], v[190:191]
	v_pk_add_f32 v[232:233], v[232:233], v[192:193]
	v_pk_add_f32 v[232:233], v[232:233], v[194:195]
	v_pk_add_f32 v[232:233], v[232:233], v[196:197]
	v_pk_add_f32 v[232:233], v[232:233], v[198:199]
	v_pk_add_f32 v[232:233], v[232:233], v[200:201]
	v_pk_add_f32 v[232:233], v[232:233], v[202:203]
	ds_read2_b32 v[188:189], v115 offset0:160 offset1:161
	ds_read2_b32 v[190:191], v115 offset0:162 offset1:163
	ds_read2_b32 v[192:193], v115 offset0:168 offset1:169
	ds_read2_b32 v[194:195], v115 offset0:170 offset1:171
	ds_read2_b32 v[196:197], v115 offset0:176 offset1:177
	ds_read2_b32 v[198:199], v115 offset0:178 offset1:179
	ds_read2_b32 v[200:201], v115 offset0:184 offset1:185
	ds_read2_b32 v[202:203], v115 offset0:186 offset1:187
	v_mfma_f32_32x32x16_bf16 v[0:15], v[64:67], v[72:75], v[0:15]
	v_mfma_f32_32x32x16_bf16 v[16:31], v[64:67], v[76:79], v[16:31]
	v_mfma_f32_32x32x16_bf16 v[0:15], v[68:71], v[220:223], v[0:15]
	v_mfma_f32_32x32x16_bf16 v[16:31], v[68:71], v[224:227], v[16:31]
	global_load_dwordx4 v[116:119], v239, s[86:87]
	global_load_dwordx4 v[120:123], v240, s[86:87]
	global_load_dwordx4 v[124:127], v241, s[86:87]
	global_load_dwordx4 v[128:131], v242, s[86:87]
	global_load_dwordx4 v[132:135], v101, s[86:87] offset:768
	global_load_dwordx4 v[136:139], v150, s[86:87] offset:768
	global_load_dwordx4 v[140:143], v101, s[86:87] offset:832
	global_load_dwordx4 v[144:147], v150, s[86:87] offset:832
	s_add_u32 s86, s86, 0xc0000
	s_addc_u32 s87, s87, 0
	ds_read_b64_tr_b16 v[72:73], v231
	ds_read_b64_tr_b16 v[74:75], v231 offset:512
	ds_read_b64_tr_b16 v[76:77], v231 offset:2048
	ds_read_b64_tr_b16 v[78:79], v231 offset:2560
	ds_read_b64_tr_b16 v[220:221], v231 offset:1024
	ds_read_b64_tr_b16 v[222:223], v231 offset:1536
	ds_read_b64_tr_b16 v[224:225], v231 offset:3072
	ds_read_b64_tr_b16 v[226:227], v231 offset:3584
	v_exp_f32_e32 v32, v32
	v_exp_f32_e32 v33, v33
	v_exp_f32_e32 v34, v34
	v_exp_f32_e32 v35, v35
	s_waitcnt vmcnt(8)
	ds_write_b128 v247, v[156:159]
	ds_write_b128 v247, v[160:163] offset:1024
	ds_write_b128 v247, v[164:167] offset:2048
	ds_write_b128 v247, v[168:171] offset:3072
	ds_read_b128 v[156:159], v248
	ds_read_b128 v[160:163], v249
	ds_read_b128 v[164:167], v250
	ds_read_b128 v[168:171], v251
	ds_write_b128 v112, v[172:175]
	ds_write_b128 v112, v[176:179] offset:1024
	ds_write_b128 v112, v[180:183] offset:2048
	ds_write_b128 v112, v[184:187] offset:3072
	v_exp_f32_e32 v36, v36
	v_exp_f32_e32 v37, v37
	v_exp_f32_e32 v38, v38
	v_exp_f32_e32 v39, v39
	s_waitcnt lgkmcnt(4)
	v_mfma_f32_32x32x16_bf16 v[188:203], v[156:159], v[48:51], v[188:203]
	v_exp_f32_e32 v40, v40
	v_exp_f32_e32 v41, v41
	v_mfma_f32_32x32x16_bf16 v[188:203], v[160:163], v[52:55], v[188:203]
	v_exp_f32_e32 v42, v42
	v_exp_f32_e32 v43, v43
	v_mfma_f32_32x32x16_bf16 v[188:203], v[164:167], v[56:59], v[188:203]
	v_exp_f32_e32 v44, v44
	v_exp_f32_e32 v45, v45
	v_mfma_f32_32x32x16_bf16 v[188:203], v[168:171], v[60:63], v[188:203]
	v_exp_f32_e32 v46, v46
	v_exp_f32_e32 v47, v47
	v_cvt_pk_bf16_f32 v64, v32, v33
	v_cvt_pk_bf16_f32 v65, v34, v35
	v_cvt_pk_bf16_f32 v66, v36, v37
	v_cvt_pk_bf16_f32 v67, v38, v39
	v_cvt_pk_bf16_f32 v68, v40, v41
	v_cvt_pk_bf16_f32 v69, v42, v43
	v_cvt_pk_bf16_f32 v70, v44, v45
	v_cvt_pk_bf16_f32 v71, v46, v47
	v_pk_add_f32 v[232:233], v[232:233], v[32:33]
	v_pk_add_f32 v[232:233], v[232:233], v[34:35]
	v_pk_add_f32 v[232:233], v[232:233], v[36:37]
	v_pk_add_f32 v[232:233], v[232:233], v[38:39]
	v_pk_add_f32 v[232:233], v[232:233], v[40:41]
	v_pk_add_f32 v[232:233], v[232:233], v[42:43]
	v_pk_add_f32 v[232:233], v[232:233], v[44:45]
	v_pk_add_f32 v[232:233], v[232:233], v[46:47]
	ds_read2_b32 v[32:33], v115 offset0:192 offset1:193
	ds_read2_b32 v[34:35], v115 offset0:194 offset1:195
	ds_read2_b32 v[36:37], v115 offset0:200 offset1:201
	ds_read2_b32 v[38:39], v115 offset0:202 offset1:203
	ds_read2_b32 v[40:41], v115 offset0:208 offset1:209
	ds_read2_b32 v[42:43], v115 offset0:210 offset1:211
	ds_read2_b32 v[44:45], v115 offset0:216 offset1:217
	ds_read2_b32 v[46:47], v115 offset0:218 offset1:219
	v_mfma_f32_32x32x16_bf16 v[0:15], v[64:67], v[72:75], v[0:15]
	v_mfma_f32_32x32x16_bf16 v[16:31], v[64:67], v[76:79], v[16:31]
	v_mfma_f32_32x32x16_bf16 v[0:15], v[68:71], v[220:223], v[0:15]
	v_mfma_f32_32x32x16_bf16 v[16:31], v[68:71], v[224:227], v[16:31]
	global_load_dwordx4 v[156:159], v239, s[86:87]
	global_load_dwordx4 v[160:163], v240, s[86:87]
	global_load_dwordx4 v[164:167], v241, s[86:87]
	global_load_dwordx4 v[168:171], v242, s[86:87]
	global_load_dwordx4 v[172:175], v101, s[86:87] offset:768
	global_load_dwordx4 v[176:179], v150, s[86:87] offset:768
	global_load_dwordx4 v[180:183], v101, s[86:87] offset:832
	global_load_dwordx4 v[184:187], v150, s[86:87] offset:832
	ds_read_b64_tr_b16 v[72:73], v231
	ds_read_b64_tr_b16 v[74:75], v231 offset:512
	ds_read_b64_tr_b16 v[76:77], v231 offset:2048
	ds_read_b64_tr_b16 v[78:79], v231 offset:2560
	ds_read_b64_tr_b16 v[220:221], v231 offset:1024
	ds_read_b64_tr_b16 v[222:223], v231 offset:1536
	ds_read_b64_tr_b16 v[224:225], v231 offset:3072
	ds_read_b64_tr_b16 v[226:227], v231 offset:3584
	v_exp_f32_e32 v188, v188
	v_exp_f32_e32 v189, v189
	v_exp_f32_e32 v190, v190
	v_exp_f32_e32 v191, v191
	s_waitcnt vmcnt(8)
	ds_write_b128 v247, v[116:119]
	ds_write_b128 v247, v[120:123] offset:1024
	ds_write_b128 v247, v[124:127] offset:2048
	ds_write_b128 v247, v[128:131] offset:3072
	ds_read_b128 v[116:119], v248
	ds_read_b128 v[120:123], v249
	ds_read_b128 v[124:127], v250
	ds_read_b128 v[128:131], v251
	ds_write_b128 v112, v[132:135]
	ds_write_b128 v112, v[136:139] offset:1024
	ds_write_b128 v112, v[140:143] offset:2048
	ds_write_b128 v112, v[144:147] offset:3072
	v_exp_f32_e32 v192, v192
	v_exp_f32_e32 v193, v193
	v_exp_f32_e32 v194, v194
	v_exp_f32_e32 v195, v195
	s_waitcnt lgkmcnt(4)
	v_mfma_f32_32x32x16_bf16 v[32:47], v[116:119], v[48:51], v[32:47]
	v_exp_f32_e32 v196, v196
	v_exp_f32_e32 v197, v197
	v_mfma_f32_32x32x16_bf16 v[32:47], v[120:123], v[52:55], v[32:47]
	v_exp_f32_e32 v198, v198
	v_exp_f32_e32 v199, v199
	v_mfma_f32_32x32x16_bf16 v[32:47], v[124:127], v[56:59], v[32:47]
	v_exp_f32_e32 v200, v200
	v_exp_f32_e32 v201, v201
	v_mfma_f32_32x32x16_bf16 v[32:47], v[128:131], v[60:63], v[32:47]
	v_exp_f32_e32 v202, v202
	v_exp_f32_e32 v203, v203
	v_cvt_pk_bf16_f32 v64, v188, v189
	v_cvt_pk_bf16_f32 v65, v190, v191
	v_cvt_pk_bf16_f32 v66, v192, v193
	v_cvt_pk_bf16_f32 v67, v194, v195
	v_cvt_pk_bf16_f32 v68, v196, v197
	v_cvt_pk_bf16_f32 v69, v198, v199
	v_cvt_pk_bf16_f32 v70, v200, v201
	v_cvt_pk_bf16_f32 v71, v202, v203
	v_pk_add_f32 v[232:233], v[232:233], v[188:189]
	v_pk_add_f32 v[232:233], v[232:233], v[190:191]
	v_pk_add_f32 v[232:233], v[232:233], v[192:193]
	v_pk_add_f32 v[232:233], v[232:233], v[194:195]
	v_pk_add_f32 v[232:233], v[232:233], v[196:197]
	v_pk_add_f32 v[232:233], v[232:233], v[198:199]
	v_pk_add_f32 v[232:233], v[232:233], v[200:201]
	v_pk_add_f32 v[232:233], v[232:233], v[202:203]
	ds_read2_b32 v[188:189], v115 offset0:224 offset1:225
	ds_read2_b32 v[190:191], v115 offset0:226 offset1:227
	ds_read2_b32 v[192:193], v115 offset0:232 offset1:233
	ds_read2_b32 v[194:195], v115 offset0:234 offset1:235
	ds_read2_b32 v[196:197], v115 offset0:240 offset1:241
	ds_read2_b32 v[198:199], v115 offset0:242 offset1:243
	ds_read2_b32 v[200:201], v115 offset0:248 offset1:249
	ds_read2_b32 v[202:203], v115 offset0:250 offset1:251
	v_mfma_f32_32x32x16_bf16 v[0:15], v[64:67], v[72:75], v[0:15]
	v_mfma_f32_32x32x16_bf16 v[16:31], v[64:67], v[76:79], v[16:31]
	v_mfma_f32_32x32x16_bf16 v[0:15], v[68:71], v[220:223], v[0:15]
	v_mfma_f32_32x32x16_bf16 v[16:31], v[68:71], v[224:227], v[16:31]
	global_load_dwordx4 v[116:119], v243, s[88:89]
	global_load_dwordx4 v[120:123], v244, s[88:89]
	global_load_dwordx4 v[124:127], v245, s[88:89]
	global_load_dwordx4 v[128:131], v246, s[88:89]
	global_load_dwordx4 v[132:135], v148, s[88:89] offset:768
	global_load_dwordx4 v[136:139], v151, s[88:89] offset:768
	global_load_dwordx4 v[140:143], v148, s[88:89] offset:832
	global_load_dwordx4 v[144:147], v151, s[88:89] offset:832
	s_add_u32 s88, s88, 0x300000
	s_addc_u32 s89, s89, 0
	ds_read_b64_tr_b16 v[72:73], v231
	ds_read_b64_tr_b16 v[74:75], v231 offset:512
	ds_read_b64_tr_b16 v[76:77], v231 offset:2048
	ds_read_b64_tr_b16 v[78:79], v231 offset:2560
	ds_read_b64_tr_b16 v[220:221], v231 offset:1024
	ds_read_b64_tr_b16 v[222:223], v231 offset:1536
	ds_read_b64_tr_b16 v[224:225], v231 offset:3072
	ds_read_b64_tr_b16 v[226:227], v231 offset:3584
	v_exp_f32_e32 v32, v32
	v_exp_f32_e32 v33, v33
	v_exp_f32_e32 v34, v34
	v_exp_f32_e32 v35, v35
	s_waitcnt vmcnt(8)
	ds_write_b128 v247, v[156:159]
	ds_write_b128 v247, v[160:163] offset:1024
	ds_write_b128 v247, v[164:167] offset:2048
	ds_write_b128 v247, v[168:171] offset:3072
	ds_read_b128 v[156:159], v248
	ds_read_b128 v[160:163], v249
	ds_read_b128 v[164:167], v250
	ds_read_b128 v[168:171], v251
	ds_write_b128 v112, v[172:175]
	ds_write_b128 v112, v[176:179] offset:1024
	ds_write_b128 v112, v[180:183] offset:2048
	ds_write_b128 v112, v[184:187] offset:3072
	v_exp_f32_e32 v36, v36
	v_exp_f32_e32 v37, v37
	v_exp_f32_e32 v38, v38
	v_exp_f32_e32 v39, v39
	s_waitcnt lgkmcnt(4)
	v_mfma_f32_32x32x16_bf16 v[188:203], v[156:159], v[48:51], v[188:203]
	v_exp_f32_e32 v40, v40
	v_exp_f32_e32 v41, v41
	v_mfma_f32_32x32x16_bf16 v[188:203], v[160:163], v[52:55], v[188:203]
	v_exp_f32_e32 v42, v42
	v_exp_f32_e32 v43, v43
	v_mfma_f32_32x32x16_bf16 v[188:203], v[164:167], v[56:59], v[188:203]
	v_exp_f32_e32 v44, v44
	v_exp_f32_e32 v45, v45
	v_mfma_f32_32x32x16_bf16 v[188:203], v[168:171], v[60:63], v[188:203]
	v_exp_f32_e32 v46, v46
	v_exp_f32_e32 v47, v47
	v_cvt_pk_bf16_f32 v64, v32, v33
	v_cvt_pk_bf16_f32 v65, v34, v35
	v_cvt_pk_bf16_f32 v66, v36, v37
	v_cvt_pk_bf16_f32 v67, v38, v39
	v_cvt_pk_bf16_f32 v68, v40, v41
	v_cvt_pk_bf16_f32 v69, v42, v43
	v_cvt_pk_bf16_f32 v70, v44, v45
	v_cvt_pk_bf16_f32 v71, v46, v47
	v_pk_add_f32 v[232:233], v[232:233], v[32:33]
	v_pk_add_f32 v[232:233], v[232:233], v[34:35]
	v_pk_add_f32 v[232:233], v[232:233], v[36:37]
	v_pk_add_f32 v[232:233], v[232:233], v[38:39]
	v_pk_add_f32 v[232:233], v[232:233], v[40:41]
	v_pk_add_f32 v[232:233], v[232:233], v[42:43]
	v_pk_add_f32 v[232:233], v[232:233], v[44:45]
	v_pk_add_f32 v[232:233], v[232:233], v[46:47]
	v_mov_b32_e32 v115, v230
	ds_read2_b32 v[32:33], v115 offset0:0 offset1:1
	ds_read2_b32 v[34:35], v115 offset0:2 offset1:3
	ds_read2_b32 v[36:37], v115 offset0:8 offset1:9
	ds_read2_b32 v[38:39], v115 offset0:10 offset1:11
	ds_read2_b32 v[40:41], v115 offset0:16 offset1:17
	ds_read2_b32 v[42:43], v115 offset0:18 offset1:19
	ds_read2_b32 v[44:45], v115 offset0:24 offset1:25
	ds_read2_b32 v[46:47], v115 offset0:26 offset1:27
	v_mfma_f32_32x32x16_bf16 v[0:15], v[64:67], v[72:75], v[0:15]
	v_mfma_f32_32x32x16_bf16 v[16:31], v[64:67], v[76:79], v[16:31]
	v_mfma_f32_32x32x16_bf16 v[0:15], v[68:71], v[220:223], v[0:15]
	v_mfma_f32_32x32x16_bf16 v[16:31], v[68:71], v[224:227], v[16:31]
	global_load_dwordx4 v[156:159], v243, s[88:89]
	global_load_dwordx4 v[160:163], v244, s[88:89]
	global_load_dwordx4 v[164:167], v245, s[88:89]
	global_load_dwordx4 v[168:171], v246, s[88:89]
	global_load_dwordx4 v[172:175], v148, s[88:89] offset:768
	global_load_dwordx4 v[176:179], v151, s[88:89] offset:768
	global_load_dwordx4 v[180:183], v148, s[88:89] offset:832
	global_load_dwordx4 v[184:187], v151, s[88:89] offset:832
	s_add_u32 s88, s88, 0x300000
	s_addc_u32 s89, s89, 0
	ds_read_b64_tr_b16 v[72:73], v231
	ds_read_b64_tr_b16 v[74:75], v231 offset:512
	ds_read_b64_tr_b16 v[76:77], v231 offset:2048
	ds_read_b64_tr_b16 v[78:79], v231 offset:2560
	ds_read_b64_tr_b16 v[220:221], v231 offset:1024
	ds_read_b64_tr_b16 v[222:223], v231 offset:1536
	ds_read_b64_tr_b16 v[224:225], v231 offset:3072
	ds_read_b64_tr_b16 v[226:227], v231 offset:3584
	v_exp_f32_e32 v188, v188
	v_exp_f32_e32 v189, v189
	v_exp_f32_e32 v190, v190
	v_exp_f32_e32 v191, v191
	s_waitcnt vmcnt(8)
	ds_write_b128 v247, v[116:119]
	ds_write_b128 v247, v[120:123] offset:1024
	ds_write_b128 v247, v[124:127] offset:2048
	ds_write_b128 v247, v[128:131] offset:3072
	ds_read_b128 v[116:119], v248
	ds_read_b128 v[120:123], v249
	ds_read_b128 v[124:127], v250
	ds_read_b128 v[128:131], v251
	ds_write_b128 v112, v[132:135]
	ds_write_b128 v112, v[136:139] offset:1024
	ds_write_b128 v112, v[140:143] offset:2048
	ds_write_b128 v112, v[144:147] offset:3072
	v_exp_f32_e32 v192, v192
	v_exp_f32_e32 v193, v193
	v_exp_f32_e32 v194, v194
	v_exp_f32_e32 v195, v195
	s_waitcnt lgkmcnt(4)
	v_mfma_f32_32x32x16_bf16 v[32:47], v[116:119], v[48:51], v[32:47]
	v_exp_f32_e32 v196, v196
	v_exp_f32_e32 v197, v197
	v_mfma_f32_32x32x16_bf16 v[32:47], v[120:123], v[52:55], v[32:47]
	v_exp_f32_e32 v198, v198
	v_exp_f32_e32 v199, v199
	v_mfma_f32_32x32x16_bf16 v[32:47], v[124:127], v[56:59], v[32:47]
	v_exp_f32_e32 v200, v200
	v_exp_f32_e32 v201, v201
	v_mfma_f32_32x32x16_bf16 v[32:47], v[128:131], v[60:63], v[32:47]
	v_exp_f32_e32 v202, v202
	v_exp_f32_e32 v203, v203
	v_cvt_pk_bf16_f32 v64, v188, v189
	v_cvt_pk_bf16_f32 v65, v190, v191
	v_cvt_pk_bf16_f32 v66, v192, v193
	v_cvt_pk_bf16_f32 v67, v194, v195
	v_cvt_pk_bf16_f32 v68, v196, v197
	v_cvt_pk_bf16_f32 v69, v198, v199
	v_cvt_pk_bf16_f32 v70, v200, v201
	v_cvt_pk_bf16_f32 v71, v202, v203
	v_pk_add_f32 v[232:233], v[232:233], v[188:189]
	v_pk_add_f32 v[232:233], v[232:233], v[190:191]
	v_pk_add_f32 v[232:233], v[232:233], v[192:193]
	v_pk_add_f32 v[232:233], v[232:233], v[194:195]
	v_pk_add_f32 v[232:233], v[232:233], v[196:197]
	v_pk_add_f32 v[232:233], v[232:233], v[198:199]
	v_pk_add_f32 v[232:233], v[232:233], v[200:201]
	v_pk_add_f32 v[232:233], v[232:233], v[202:203]
	ds_read2_b32 v[188:189], v115 offset0:32 offset1:33
	ds_read2_b32 v[190:191], v115 offset0:34 offset1:35
	ds_read2_b32 v[192:193], v115 offset0:40 offset1:41
	ds_read2_b32 v[194:195], v115 offset0:42 offset1:43
	ds_read2_b32 v[196:197], v115 offset0:48 offset1:49
	ds_read2_b32 v[198:199], v115 offset0:50 offset1:51
	ds_read2_b32 v[200:201], v115 offset0:56 offset1:57
	ds_read2_b32 v[202:203], v115 offset0:58 offset1:59
	v_mfma_f32_32x32x16_bf16 v[0:15], v[64:67], v[72:75], v[0:15]
	v_mfma_f32_32x32x16_bf16 v[16:31], v[64:67], v[76:79], v[16:31]
	v_mfma_f32_32x32x16_bf16 v[0:15], v[68:71], v[220:223], v[0:15]
	v_mfma_f32_32x32x16_bf16 v[16:31], v[68:71], v[224:227], v[16:31]
	global_load_dwordx4 v[116:119], v243, s[88:89]
	global_load_dwordx4 v[120:123], v244, s[88:89]
	global_load_dwordx4 v[124:127], v245, s[88:89]
	global_load_dwordx4 v[128:131], v246, s[88:89]
	global_load_dwordx4 v[132:135], v148, s[88:89] offset:768
	global_load_dwordx4 v[136:139], v151, s[88:89] offset:768
	global_load_dwordx4 v[140:143], v148, s[88:89] offset:832
	global_load_dwordx4 v[144:147], v151, s[88:89] offset:832
	s_add_u32 s88, s88, 0x300000
	s_addc_u32 s89, s89, 0
	ds_read_b64_tr_b16 v[72:73], v231
	ds_read_b64_tr_b16 v[74:75], v231 offset:512
	ds_read_b64_tr_b16 v[76:77], v231 offset:2048
	ds_read_b64_tr_b16 v[78:79], v231 offset:2560
	ds_read_b64_tr_b16 v[220:221], v231 offset:1024
	ds_read_b64_tr_b16 v[222:223], v231 offset:1536
	ds_read_b64_tr_b16 v[224:225], v231 offset:3072
	ds_read_b64_tr_b16 v[226:227], v231 offset:3584
	v_exp_f32_e32 v32, v32
	v_exp_f32_e32 v33, v33
	v_exp_f32_e32 v34, v34
	v_exp_f32_e32 v35, v35
	s_waitcnt vmcnt(8)
	ds_write_b128 v247, v[156:159]
	ds_write_b128 v247, v[160:163] offset:1024
	ds_write_b128 v247, v[164:167] offset:2048
	ds_write_b128 v247, v[168:171] offset:3072
	ds_read_b128 v[156:159], v248
	ds_read_b128 v[160:163], v249
	ds_read_b128 v[164:167], v250
	ds_read_b128 v[168:171], v251
	ds_write_b128 v112, v[172:175]
	ds_write_b128 v112, v[176:179] offset:1024
	ds_write_b128 v112, v[180:183] offset:2048
	ds_write_b128 v112, v[184:187] offset:3072
	v_exp_f32_e32 v36, v36
	v_exp_f32_e32 v37, v37
	v_exp_f32_e32 v38, v38
	v_exp_f32_e32 v39, v39
	s_waitcnt lgkmcnt(4)
	v_mfma_f32_32x32x16_bf16 v[188:203], v[156:159], v[48:51], v[188:203]
	v_exp_f32_e32 v40, v40
	v_exp_f32_e32 v41, v41
	v_mfma_f32_32x32x16_bf16 v[188:203], v[160:163], v[52:55], v[188:203]
	v_exp_f32_e32 v42, v42
	v_exp_f32_e32 v43, v43
	v_mfma_f32_32x32x16_bf16 v[188:203], v[164:167], v[56:59], v[188:203]
	v_exp_f32_e32 v44, v44
	v_exp_f32_e32 v45, v45
	v_mfma_f32_32x32x16_bf16 v[188:203], v[168:171], v[60:63], v[188:203]
	v_exp_f32_e32 v46, v46
	v_exp_f32_e32 v47, v47
	v_cvt_pk_bf16_f32 v64, v32, v33
	v_cvt_pk_bf16_f32 v65, v34, v35
	v_cvt_pk_bf16_f32 v66, v36, v37
	v_cvt_pk_bf16_f32 v67, v38, v39
	v_cvt_pk_bf16_f32 v68, v40, v41
	v_cvt_pk_bf16_f32 v69, v42, v43
	v_cvt_pk_bf16_f32 v70, v44, v45
	v_cvt_pk_bf16_f32 v71, v46, v47
	v_pk_add_f32 v[232:233], v[232:233], v[32:33]
	v_pk_add_f32 v[232:233], v[232:233], v[34:35]
	v_pk_add_f32 v[232:233], v[232:233], v[36:37]
	v_pk_add_f32 v[232:233], v[232:233], v[38:39]
	v_pk_add_f32 v[232:233], v[232:233], v[40:41]
	v_pk_add_f32 v[232:233], v[232:233], v[42:43]
	v_pk_add_f32 v[232:233], v[232:233], v[44:45]
	v_pk_add_f32 v[232:233], v[232:233], v[46:47]
	ds_read2_b32 v[32:33], v115 offset0:64 offset1:65
	ds_read2_b32 v[34:35], v115 offset0:66 offset1:67
	ds_read2_b32 v[36:37], v115 offset0:72 offset1:73
	ds_read2_b32 v[38:39], v115 offset0:74 offset1:75
	ds_read2_b32 v[40:41], v115 offset0:80 offset1:81
	ds_read2_b32 v[42:43], v115 offset0:82 offset1:83
	ds_read2_b32 v[44:45], v115 offset0:88 offset1:89
	ds_read2_b32 v[46:47], v115 offset0:90 offset1:91
	v_mfma_f32_32x32x16_bf16 v[0:15], v[64:67], v[72:75], v[0:15]
	v_mfma_f32_32x32x16_bf16 v[16:31], v[64:67], v[76:79], v[16:31]
	v_mfma_f32_32x32x16_bf16 v[0:15], v[68:71], v[220:223], v[0:15]
	v_mfma_f32_32x32x16_bf16 v[16:31], v[68:71], v[224:227], v[16:31]
	global_load_dwordx4 v[156:159], v243, s[88:89]
	global_load_dwordx4 v[160:163], v244, s[88:89]
	global_load_dwordx4 v[164:167], v245, s[88:89]
	global_load_dwordx4 v[168:171], v246, s[88:89]
	global_load_dwordx4 v[172:175], v148, s[88:89] offset:768
	global_load_dwordx4 v[176:179], v151, s[88:89] offset:768
	global_load_dwordx4 v[180:183], v148, s[88:89] offset:832
	global_load_dwordx4 v[184:187], v151, s[88:89] offset:832
	s_add_u32 s88, s88, 0x300000
	s_addc_u32 s89, s89, 0
	ds_read_b64_tr_b16 v[72:73], v231
	ds_read_b64_tr_b16 v[74:75], v231 offset:512
	ds_read_b64_tr_b16 v[76:77], v231 offset:2048
	ds_read_b64_tr_b16 v[78:79], v231 offset:2560
	ds_read_b64_tr_b16 v[220:221], v231 offset:1024
	ds_read_b64_tr_b16 v[222:223], v231 offset:1536
	ds_read_b64_tr_b16 v[224:225], v231 offset:3072
	ds_read_b64_tr_b16 v[226:227], v231 offset:3584
	v_exp_f32_e32 v188, v188
	v_exp_f32_e32 v189, v189
	v_exp_f32_e32 v190, v190
	v_exp_f32_e32 v191, v191
	s_waitcnt vmcnt(8)
	ds_write_b128 v247, v[116:119]
	ds_write_b128 v247, v[120:123] offset:1024
	ds_write_b128 v247, v[124:127] offset:2048
	ds_write_b128 v247, v[128:131] offset:3072
	ds_read_b128 v[116:119], v248
	ds_read_b128 v[120:123], v249
	ds_read_b128 v[124:127], v250
	ds_read_b128 v[128:131], v251
	ds_write_b128 v112, v[132:135]
	ds_write_b128 v112, v[136:139] offset:1024
	ds_write_b128 v112, v[140:143] offset:2048
	ds_write_b128 v112, v[144:147] offset:3072
	v_exp_f32_e32 v192, v192
	v_exp_f32_e32 v193, v193
	v_exp_f32_e32 v194, v194
	v_exp_f32_e32 v195, v195
	s_waitcnt lgkmcnt(4)
	v_mfma_f32_32x32x16_bf16 v[32:47], v[116:119], v[48:51], v[32:47]
	v_exp_f32_e32 v196, v196
	v_exp_f32_e32 v197, v197
	v_mfma_f32_32x32x16_bf16 v[32:47], v[120:123], v[52:55], v[32:47]
	v_exp_f32_e32 v198, v198
	v_exp_f32_e32 v199, v199
	v_mfma_f32_32x32x16_bf16 v[32:47], v[124:127], v[56:59], v[32:47]
	v_exp_f32_e32 v200, v200
	v_exp_f32_e32 v201, v201
	v_mfma_f32_32x32x16_bf16 v[32:47], v[128:131], v[60:63], v[32:47]
	v_exp_f32_e32 v202, v202
	v_exp_f32_e32 v203, v203
	v_cvt_pk_bf16_f32 v64, v188, v189
	v_cvt_pk_bf16_f32 v65, v190, v191
	v_cvt_pk_bf16_f32 v66, v192, v193
	v_cvt_pk_bf16_f32 v67, v194, v195
	v_cvt_pk_bf16_f32 v68, v196, v197
	v_cvt_pk_bf16_f32 v69, v198, v199
	v_cvt_pk_bf16_f32 v70, v200, v201
	v_cvt_pk_bf16_f32 v71, v202, v203
	v_pk_add_f32 v[232:233], v[232:233], v[188:189]
	v_pk_add_f32 v[232:233], v[232:233], v[190:191]
	v_pk_add_f32 v[232:233], v[232:233], v[192:193]
	v_pk_add_f32 v[232:233], v[232:233], v[194:195]
	v_pk_add_f32 v[232:233], v[232:233], v[196:197]
	v_pk_add_f32 v[232:233], v[232:233], v[198:199]
	v_pk_add_f32 v[232:233], v[232:233], v[200:201]
	v_pk_add_f32 v[232:233], v[232:233], v[202:203]
	ds_read2_b32 v[188:189], v115 offset0:96 offset1:97
	ds_read2_b32 v[190:191], v115 offset0:98 offset1:99
	ds_read2_b32 v[192:193], v115 offset0:104 offset1:105
	ds_read2_b32 v[194:195], v115 offset0:106 offset1:107
	ds_read2_b32 v[196:197], v115 offset0:112 offset1:113
	ds_read2_b32 v[198:199], v115 offset0:114 offset1:115
	ds_read2_b32 v[200:201], v115 offset0:120 offset1:121
	ds_read2_b32 v[202:203], v115 offset0:122 offset1:123
	v_mfma_f32_32x32x16_bf16 v[0:15], v[64:67], v[72:75], v[0:15]
	v_mfma_f32_32x32x16_bf16 v[16:31], v[64:67], v[76:79], v[16:31]
	v_mfma_f32_32x32x16_bf16 v[0:15], v[68:71], v[220:223], v[0:15]
	v_mfma_f32_32x32x16_bf16 v[16:31], v[68:71], v[224:227], v[16:31]
	global_load_dwordx4 v[116:119], v243, s[88:89]
	global_load_dwordx4 v[120:123], v244, s[88:89]
	global_load_dwordx4 v[124:127], v245, s[88:89]
	global_load_dwordx4 v[128:131], v246, s[88:89]
	global_load_dwordx4 v[132:135], v148, s[88:89] offset:768
	global_load_dwordx4 v[136:139], v151, s[88:89] offset:768
	global_load_dwordx4 v[140:143], v148, s[88:89] offset:832
	global_load_dwordx4 v[144:147], v151, s[88:89] offset:832
	ds_read_b64_tr_b16 v[72:73], v231
	ds_read_b64_tr_b16 v[74:75], v231 offset:512
	ds_read_b64_tr_b16 v[76:77], v231 offset:2048
	ds_read_b64_tr_b16 v[78:79], v231 offset:2560
	ds_read_b64_tr_b16 v[220:221], v231 offset:1024
	ds_read_b64_tr_b16 v[222:223], v231 offset:1536
	ds_read_b64_tr_b16 v[224:225], v231 offset:3072
	ds_read_b64_tr_b16 v[226:227], v231 offset:3584
	v_exp_f32_e32 v32, v32
	v_exp_f32_e32 v33, v33
	v_exp_f32_e32 v34, v34
	v_exp_f32_e32 v35, v35
	s_waitcnt vmcnt(8)
	ds_write_b128 v247, v[156:159]
	ds_write_b128 v247, v[160:163] offset:1024
	ds_write_b128 v247, v[164:167] offset:2048
	ds_write_b128 v247, v[168:171] offset:3072
	ds_read_b128 v[156:159], v248
	ds_read_b128 v[160:163], v249
	ds_read_b128 v[164:167], v250
	ds_read_b128 v[168:171], v251
	ds_write_b128 v112, v[172:175]
	ds_write_b128 v112, v[176:179] offset:1024
	ds_write_b128 v112, v[180:183] offset:2048
	ds_write_b128 v112, v[184:187] offset:3072
	v_exp_f32_e32 v36, v36
	v_exp_f32_e32 v37, v37
	v_exp_f32_e32 v38, v38
	v_exp_f32_e32 v39, v39
	s_waitcnt lgkmcnt(4)
	v_mfma_f32_32x32x16_bf16 v[188:203], v[156:159], v[48:51], v[188:203]
	v_exp_f32_e32 v40, v40
	v_exp_f32_e32 v41, v41
	v_mfma_f32_32x32x16_bf16 v[188:203], v[160:163], v[52:55], v[188:203]
	v_exp_f32_e32 v42, v42
	v_exp_f32_e32 v43, v43
	v_mfma_f32_32x32x16_bf16 v[188:203], v[164:167], v[56:59], v[188:203]
	v_exp_f32_e32 v44, v44
	v_exp_f32_e32 v45, v45
	v_mfma_f32_32x32x16_bf16 v[188:203], v[168:171], v[60:63], v[188:203]
	v_exp_f32_e32 v46, v46
	v_exp_f32_e32 v47, v47
	v_cvt_pk_bf16_f32 v64, v32, v33
	v_cvt_pk_bf16_f32 v65, v34, v35
	v_cvt_pk_bf16_f32 v66, v36, v37
	v_cvt_pk_bf16_f32 v67, v38, v39
	v_cvt_pk_bf16_f32 v68, v40, v41
	v_cvt_pk_bf16_f32 v69, v42, v43
	v_cvt_pk_bf16_f32 v70, v44, v45
	v_cvt_pk_bf16_f32 v71, v46, v47
	v_pk_add_f32 v[232:233], v[232:233], v[32:33]
	v_pk_add_f32 v[232:233], v[232:233], v[34:35]
	v_pk_add_f32 v[232:233], v[232:233], v[36:37]
	v_pk_add_f32 v[232:233], v[232:233], v[38:39]
	v_pk_add_f32 v[232:233], v[232:233], v[40:41]
	v_pk_add_f32 v[232:233], v[232:233], v[42:43]
	v_pk_add_f32 v[232:233], v[232:233], v[44:45]
	v_pk_add_f32 v[232:233], v[232:233], v[46:47]
	ds_read2_b32 v[32:33], v115 offset0:128 offset1:129
	ds_read2_b32 v[34:35], v115 offset0:130 offset1:131
	ds_read2_b32 v[36:37], v115 offset0:136 offset1:137
	ds_read2_b32 v[38:39], v115 offset0:138 offset1:139
	ds_read2_b32 v[40:41], v115 offset0:144 offset1:145
	ds_read2_b32 v[42:43], v115 offset0:146 offset1:147
	ds_read2_b32 v[44:45], v115 offset0:152 offset1:153
	ds_read2_b32 v[46:47], v115 offset0:154 offset1:155
	v_mfma_f32_32x32x16_bf16 v[0:15], v[64:67], v[72:75], v[0:15]
	v_mfma_f32_32x32x16_bf16 v[16:31], v[64:67], v[76:79], v[16:31]
	v_mfma_f32_32x32x16_bf16 v[0:15], v[68:71], v[220:223], v[0:15]
	v_mfma_f32_32x32x16_bf16 v[16:31], v[68:71], v[224:227], v[16:31]
	ds_read_b64_tr_b16 v[72:73], v231
	ds_read_b64_tr_b16 v[74:75], v231 offset:512
	ds_read_b64_tr_b16 v[76:77], v231 offset:2048
	ds_read_b64_tr_b16 v[78:79], v231 offset:2560
	ds_read_b64_tr_b16 v[220:221], v231 offset:1024
	ds_read_b64_tr_b16 v[222:223], v231 offset:1536
	ds_read_b64_tr_b16 v[224:225], v231 offset:3072
	ds_read_b64_tr_b16 v[226:227], v231 offset:3584
	v_exp_f32_e32 v188, v188
	v_exp_f32_e32 v189, v189
	v_exp_f32_e32 v190, v190
	v_exp_f32_e32 v191, v191
	s_waitcnt vmcnt(0)
; __device__ __forceinline__ int crow(int r, int hi) { return (r & 3) + 8 * (r >> 2) + 4 * hi; }
; __device__ __forceinline__ void dil_unit(LAS unsigned char* lds, bf16_t* proj, int seq, int hd, int T0, int rho) {
;     ...
;     l += __shfl_xor(l, 32);
; #pragma unroll
;     for (int rr = 0; rr < 16; ++rr) {
;         const int j = crow(rr, hi);
;         const float il = __builtin_amdgcn_rcpf(__shfl(l, j));
	ds_write_b128 v247, v[116:119]
	ds_write_b128 v247, v[120:123] offset:1024
	ds_write_b128 v247, v[124:127] offset:2048
	ds_write_b128 v247, v[128:131] offset:3072
	ds_read_b128 v[116:119], v248
	ds_read_b128 v[120:123], v249
	ds_read_b128 v[124:127], v250
	ds_read_b128 v[128:131], v251
	ds_write_b128 v112, v[132:135]
	ds_write_b128 v112, v[136:139] offset:1024
	ds_write_b128 v112, v[140:143] offset:2048
	ds_write_b128 v112, v[144:147] offset:3072
	v_exp_f32_e32 v192, v192
	v_exp_f32_e32 v193, v193
	v_exp_f32_e32 v194, v194
	v_exp_f32_e32 v195, v195
	s_waitcnt lgkmcnt(4)
	v_mfma_f32_32x32x16_bf16 v[32:47], v[116:119], v[48:51], v[32:47]
	v_exp_f32_e32 v196, v196
	v_exp_f32_e32 v197, v197
	v_mfma_f32_32x32x16_bf16 v[32:47], v[120:123], v[52:55], v[32:47]
	v_exp_f32_e32 v198, v198
	v_exp_f32_e32 v199, v199
	v_mfma_f32_32x32x16_bf16 v[32:47], v[124:127], v[56:59], v[32:47]
	v_exp_f32_e32 v200, v200
	v_exp_f32_e32 v201, v201
	v_mfma_f32_32x32x16_bf16 v[32:47], v[128:131], v[60:63], v[32:47]
	v_exp_f32_e32 v202, v202
	v_exp_f32_e32 v203, v203
	v_cvt_pk_bf16_f32 v64, v188, v189
	v_cvt_pk_bf16_f32 v65, v190, v191
	v_cvt_pk_bf16_f32 v66, v192, v193
	v_cvt_pk_bf16_f32 v67, v194, v195
	v_cvt_pk_bf16_f32 v68, v196, v197
	v_cvt_pk_bf16_f32 v69, v198, v199
	v_cvt_pk_bf16_f32 v70, v200, v201
	v_cvt_pk_bf16_f32 v71, v202, v203
	v_pk_add_f32 v[232:233], v[232:233], v[188:189]
	v_pk_add_f32 v[232:233], v[232:233], v[190:191]
	v_pk_add_f32 v[232:233], v[232:233], v[192:193]
	v_pk_add_f32 v[232:233], v[232:233], v[194:195]
	v_pk_add_f32 v[232:233], v[232:233], v[196:197]
	v_pk_add_f32 v[232:233], v[232:233], v[198:199]
	v_pk_add_f32 v[232:233], v[232:233], v[200:201]
	v_pk_add_f32 v[232:233], v[232:233], v[202:203]
	v_mfma_f32_32x32x16_bf16 v[0:15], v[64:67], v[72:75], v[0:15]
	v_mfma_f32_32x32x16_bf16 v[16:31], v[64:67], v[76:79], v[16:31]
	v_mfma_f32_32x32x16_bf16 v[0:15], v[68:71], v[220:223], v[0:15]
	v_mfma_f32_32x32x16_bf16 v[16:31], v[68:71], v[224:227], v[16:31]
	ds_read_b64_tr_b16 v[72:73], v231
	ds_read_b64_tr_b16 v[74:75], v231 offset:512
	ds_read_b64_tr_b16 v[76:77], v231 offset:2048
	ds_read_b64_tr_b16 v[78:79], v231 offset:2560
	ds_read_b64_tr_b16 v[220:221], v231 offset:1024
	ds_read_b64_tr_b16 v[222:223], v231 offset:1536
	ds_read_b64_tr_b16 v[224:225], v231 offset:3072
	ds_read_b64_tr_b16 v[226:227], v231 offset:3584
	s_waitcnt lgkmcnt(0)
	v_exp_f32_e32 v32, v32
	v_exp_f32_e32 v33, v33
	v_exp_f32_e32 v34, v34
	v_exp_f32_e32 v35, v35
	v_exp_f32_e32 v36, v36
	v_exp_f32_e32 v37, v37
	v_exp_f32_e32 v38, v38
	v_exp_f32_e32 v39, v39
	v_exp_f32_e32 v40, v40
	v_exp_f32_e32 v41, v41
	v_exp_f32_e32 v42, v42
	v_exp_f32_e32 v43, v43
	v_exp_f32_e32 v44, v44
	v_exp_f32_e32 v45, v45
	v_exp_f32_e32 v46, v46
	v_exp_f32_e32 v47, v47
	v_cvt_pk_bf16_f32 v64, v32, v33
	v_cvt_pk_bf16_f32 v65, v34, v35
	v_cvt_pk_bf16_f32 v66, v36, v37
	v_cvt_pk_bf16_f32 v67, v38, v39
	v_cvt_pk_bf16_f32 v68, v40, v41
	v_cvt_pk_bf16_f32 v69, v42, v43
	v_cvt_pk_bf16_f32 v70, v44, v45
	v_cvt_pk_bf16_f32 v71, v46, v47
	v_pk_add_f32 v[232:233], v[232:233], v[32:33]
	v_pk_add_f32 v[232:233], v[232:233], v[34:35]
	v_pk_add_f32 v[232:233], v[232:233], v[36:37]
	v_pk_add_f32 v[232:233], v[232:233], v[38:39]
	v_pk_add_f32 v[232:233], v[232:233], v[40:41]
	v_pk_add_f32 v[232:233], v[232:233], v[42:43]
	v_pk_add_f32 v[232:233], v[232:233], v[44:45]
	v_pk_add_f32 v[232:233], v[232:233], v[46:47]
	v_mfma_f32_32x32x16_bf16 v[0:15], v[64:67], v[72:75], v[0:15]
	v_mfma_f32_32x32x16_bf16 v[16:31], v[64:67], v[76:79], v[16:31]
	v_mfma_f32_32x32x16_bf16 v[0:15], v[68:71], v[220:223], v[0:15]
	v_mfma_f32_32x32x16_bf16 v[16:31], v[68:71], v[224:227], v[16:31]
	v_add_f32_e32 v113, v232, v233
	v_or_b32_e32 v114, 1, v107
	v_or_b32_e32 v97, 2, v107
	v_or_b32_e32 v96, 3, v107
	v_or_b32_e32 v95, 8, v107
	v_or_b32_e32 v94, 9, v107
	v_or_b32_e32 v93, 10, v107
	v_or_b32_e32 v92, 11, v107
	v_or_b32_e32 v91, 16, v107
	v_or_b32_e32 v90, 17, v107
	v_or_b32_e32 v89, 18, v107
	v_or_b32_e32 v88, 19, v107
	v_or_b32_e32 v87, 24, v107
	v_or_b32_e32 v86, 25, v107
	v_or_b32_e32 v85, 26, v107
	v_or_b32_e32 v84, 27, v107
	s_nop 11
	s_branch .LBB0_1265
.LBB0_1270:
	s_movk_i32 s100, 0x1800
	s_add_i32 s101, s8, 0x15c00
	s_lshl_b32 s90, s54, 1
	s_add_u32 s82, s52, s90
	s_addc_u32 s83, s53, 0
	s_add_u32 s82, s82, 0x1200
	s_addc_u32 s83, s83, 0
	s_sub_i32 s90, s67, 64
	s_mul_i32 s90, s90, 0x1800
	s_add_u32 s84, s82, s90
	s_addc_u32 s85, s83, 0
	s_sub_i32 s90, s67, 256
	s_mul_i32 s90, s90, 0x1800
	s_add_u32 s86, s82, s90
	s_addc_u32 s87, s83, 0
	s_sub_i32 s90, s67, 1024
	s_mul_i32 s90, s90, 0x1800
	s_add_u32 s88, s82, s90
	s_addc_u32 s89, s83, 0
	v_lshlrev_b32_e32 v153, 1, v98
	v_mad_u32_u24 v80, v105, s100, v82
	v_mad_u32_u24 v100, v110, s100, v153
	v_add_u32_e32 v149, 0x18000, v100
	v_lshlrev_b32_e32 v83, 2, v105
	v_mad_u32_u24 v83, v83, s100, v82
	v_lshlrev_b32_e32 v101, 2, v110
	v_mad_u32_u24 v101, v101, s100, v153
	v_add_u32_e32 v150, 0x60000, v101
	v_lshlrev_b32_e32 v99, 4, v105
	v_mad_u32_u24 v99, v99, s100, v82
	v_lshlrev_b32_e32 v148, 4, v110
	v_mad_u32_u24 v148, v148, s100, v153
	v_add_u32_e32 v151, 0x180000, v148
	v_lshrrev_b32_e32 v249, 3, v103
	v_and_b32_e32 v250, 7, v103
	v_lshlrev_b32_e32 v250, 4, v250
	v_add_u32_e32 v235, 0, v249
	v_add_u32_e32 v236, 8, v249
	v_add_u32_e32 v237, 16, v249
	v_add_u32_e32 v238, 24, v249
	v_add_u32_e32 v239, 0, v249
	v_lshlrev_b32_e32 v239, 2, v239
	v_add_u32_e32 v240, 8, v249
	v_lshlrev_b32_e32 v240, 2, v240
	v_add_u32_e32 v241, 16, v249
	v_lshlrev_b32_e32 v241, 2, v241
	v_add_u32_e32 v242, 24, v249
	v_lshlrev_b32_e32 v242, 2, v242
	v_add_u32_e32 v243, 0, v249
	v_lshlrev_b32_e32 v243, 4, v243
; #define LAS __attribute__((address_space(3)))
; #define GAS __attribute__((address_space(1)))
; __device__ __forceinline__ void dil_unit(LAS unsigned char* lds, bf16_t* proj, int seq, int hd, int T0, int rho) {
;     ...
;     LAS unsigned char* wbuf = lds + wid * 4096;
;     const LAS unsigned char* vp = wbuf + ((lane >> 4) & 1) * 32 + (lane & 3) * 8 + (4 * hi + ((lane & 15) >> 2)) * 64;
;     const int P0 = T0 + rho;
;     bf16x8 qr[4];
; #pragma unroll
;     for (int ks = 0; ks < 4; ++ks) qr[ks] = *(const GAS bf16x8*)(base + (size_t)(P0 + 16 * r32) * NIN + PC_LQ + hd * 64 + 16 * ks + 8 * hi);
;     f32x16 o0 = {}, o1 = {}; float l = 0.f;
;     const bool bound = (T0 < 1024) || (T0 >= 15360);
	v_add_u32_e32 v244, 8, v249
	v_lshlrev_b32_e32 v244, 4, v244
	v_add_u32_e32 v245, 16, v249
	v_lshlrev_b32_e32 v245, 4, v245
	v_add_u32_e32 v246, 24, v249
	v_lshlrev_b32_e32 v246, 4, v246
	v_mov_b32_e32 v252, v250
	v_mov_b32_e32 v100, v110
	v_add_u32_e32 v149, 16, v100
	v_lshlrev_b32_e32 v101, 2, v110
	v_add_u32_e32 v150, 64, v101
	v_lshlrev_b32_e32 v148, 4, v110
	v_add_u32_e32 v151, 256, v148
	s_mov_b32 s98, 0x4000
	s_mov_b32 s99, 0x3fff
	v_and_b32_e32 v247, 7, v249
	v_lshlrev_b32_e32 v247, 4, v247
	v_xor_b32_e32 v247, v247, v112
	v_and_b32_e32 v153, 7, v105
	v_or_b32_e32 v248, 0, v106
	v_xor_b32_e32 v248, v248, v153
	v_lshlrev_b32_e32 v248, 4, v248
	v_lshl_add_u32 v248, v105, 7, v248
	v_add_u32_e32 v248, s69, v248
	v_or_b32_e32 v249, 2, v106
	v_xor_b32_e32 v249, v249, v153
	v_lshlrev_b32_e32 v249, 4, v249
	v_lshl_add_u32 v249, v105, 7, v249
	v_add_u32_e32 v249, s69, v249
	v_or_b32_e32 v250, 4, v106
	v_xor_b32_e32 v250, v250, v153
	v_lshlrev_b32_e32 v250, 4, v250
	v_lshl_add_u32 v250, v105, 7, v250
	v_add_u32_e32 v250, s69, v250
	v_or_b32_e32 v251, 6, v106
	v_xor_b32_e32 v251, v251, v153
	v_lshlrev_b32_e32 v251, 4, v251
	v_lshl_add_u32 v251, v105, 7, v251
	v_add_u32_e32 v251, s69, v251
	v_lshlrev_b32_e32 v153, 1, v98
	v_mul_u32_u24_e32 v228, 17, v105
	v_sub_u32_e32 v228, v107, v228
	s_mul_i32 s90, s54, 153
	s_lshr_b32 s90, s90, 1
	s_add_i32 s90, s90, 34876
	v_lshl_add_u32 v228, v228, 2, s90
	v_lshlrev_b32_e32 v229, 2, v105
	v_sub_u32_e32 v229, v107, v229
	s_add_i32 s90, s101, 5104
	v_lshl_add_u32 v229, v229, 2, s90
	v_sub_u32_e32 v230, v107, v105
	s_add_i32 s90, s101, 6364
	v_lshl_add_u32 v230, v230, 2, s90
	v_add_u32_e32 v231, v109, v108
	v_mov_b64_e32 v[232:233], 0
	v_mov_b64_e32 v[0:1], 0
	v_mov_b64_e32 v[2:3], 0
	v_mov_b64_e32 v[4:5], 0
	v_mov_b64_e32 v[6:7], 0
	v_mov_b64_e32 v[8:9], 0
	v_mov_b64_e32 v[10:11], 0
	v_mov_b64_e32 v[12:13], 0
	v_mov_b64_e32 v[14:15], 0
	v_mov_b64_e32 v[16:17], 0
	v_mov_b64_e32 v[18:19], 0
	v_mov_b64_e32 v[20:21], 0
	v_mov_b64_e32 v[22:23], 0
	v_mov_b64_e32 v[24:25], 0
	v_mov_b64_e32 v[26:27], 0
	v_mov_b64_e32 v[28:29], 0
	v_mov_b64_e32 v[30:31], 0
	s_add_i32 s90, s67, -64
	v_add_u32_e32 v80, s90, v235
	v_add_u32_e32 v83, s90, v236
	v_add_u32_e32 v99, s90, v237
	v_add_u32_e32 v253, s90, v238
	v_add_u32_e32 v254, s90, v100
	v_add_u32_e32 v255, s90, v149
	v_med3_i32 v80, v80, 0, s99
	v_med3_i32 v83, v83, 0, s99
	v_med3_i32 v99, v99, 0, s99
	v_med3_i32 v253, v253, 0, s99
	v_med3_i32 v254, v254, 0, s99
	v_med3_i32 v255, v255, 0, s99
	v_mad_u32_u24 v80, v80, s100, v252
	v_mad_u32_u24 v83, v83, s100, v252
	v_mad_u32_u24 v99, v99, s100, v252
	v_mad_u32_u24 v253, v253, s100, v252
	v_mad_u32_u24 v254, v254, s100, v153
	v_mad_u32_u24 v255, v255, s100, v153
	global_load_dwordx4 v[116:119], v80, s[82:83]
	global_load_dwordx4 v[120:123], v83, s[82:83]
	global_load_dwordx4 v[124:127], v99, s[82:83]
	global_load_dwordx4 v[128:131], v253, s[82:83]
	global_load_dwordx4 v[132:135], v254, s[82:83] offset:768
	global_load_dwordx4 v[136:139], v255, s[82:83] offset:768
	global_load_dwordx4 v[140:143], v254, s[82:83] offset:832
	global_load_dwordx4 v[144:147], v255, s[82:83] offset:832
	s_add_i32 s90, s67, -32
	v_add_u32_e32 v80, s90, v235
	v_add_u32_e32 v83, s90, v236
	v_add_u32_e32 v99, s90, v237
	v_add_u32_e32 v253, s90, v238
	v_add_u32_e32 v254, s90, v100
	v_add_u32_e32 v255, s90, v149
	v_med3_i32 v80, v80, 0, s99
	v_med3_i32 v83, v83, 0, s99
	v_med3_i32 v99, v99, 0, s99
	v_med3_i32 v253, v253, 0, s99
	v_med3_i32 v254, v254, 0, s99
	v_med3_i32 v255, v255, 0, s99
	v_mad_u32_u24 v80, v80, s100, v252
	v_mad_u32_u24 v83, v83, s100, v252
	v_mad_u32_u24 v99, v99, s100, v252
	v_mad_u32_u24 v253, v253, s100, v252
	v_mad_u32_u24 v254, v254, s100, v153
	v_mad_u32_u24 v255, v255, s100, v153
	global_load_dwordx4 v[156:159], v80, s[82:83]
	global_load_dwordx4 v[160:163], v83, s[82:83]
	global_load_dwordx4 v[164:167], v99, s[82:83]
	global_load_dwordx4 v[168:171], v253, s[82:83]
	global_load_dwordx4 v[172:175], v254, s[82:83] offset:768
	global_load_dwordx4 v[176:179], v255, s[82:83] offset:768
	global_load_dwordx4 v[180:183], v254, s[82:83] offset:832
	global_load_dwordx4 v[184:187], v255, s[82:83] offset:832
	v_mov_b32_e32 v115, v228
	ds_read2_b32 v[32:33], v115 offset0:0 offset1:1
	ds_read2_b32 v[34:35], v115 offset0:2 offset1:3
	ds_read2_b32 v[36:37], v115 offset0:8 offset1:9
	ds_read2_b32 v[38:39], v115 offset0:10 offset1:11
	ds_read2_b32 v[40:41], v115 offset0:17 offset1:18
	ds_read2_b32 v[42:43], v115 offset0:19 offset1:20
	ds_read2_b32 v[44:45], v115 offset0:25 offset1:26
	ds_read2_b32 v[46:47], v115 offset0:27 offset1:28
	s_waitcnt vmcnt(8)
	ds_write_b128 v247, v[116:119]
	ds_write_b128 v247, v[120:123] offset:1024
	ds_write_b128 v247, v[124:127] offset:2048
	ds_write_b128 v247, v[128:131] offset:3072
	ds_read_b128 v[116:119], v248
	ds_read_b128 v[120:123], v249
	ds_read_b128 v[124:127], v250
	ds_read_b128 v[128:131], v251
	ds_write_b128 v112, v[132:135]
	ds_write_b128 v112, v[136:139] offset:1024
	ds_write_b128 v112, v[140:143] offset:2048
	ds_write_b128 v112, v[144:147] offset:3072
	s_waitcnt lgkmcnt(4)
	v_mfma_f32_32x32x16_bf16 v[32:47], v[116:119], v[48:51], v[32:47]
	v_mfma_f32_32x32x16_bf16 v[32:47], v[120:123], v[52:55], v[32:47]
	v_mfma_f32_32x32x16_bf16 v[32:47], v[124:127], v[56:59], v[32:47]
	v_mfma_f32_32x32x16_bf16 v[32:47], v[128:131], v[60:63], v[32:47]
	ds_read2_b32 v[188:189], v115 offset0:34 offset1:35
	ds_read2_b32 v[190:191], v115 offset0:36 offset1:37
	ds_read2_b32 v[192:193], v115 offset0:42 offset1:43
	ds_read2_b32 v[194:195], v115 offset0:44 offset1:45
	ds_read2_b32 v[196:197], v115 offset0:51 offset1:52
	ds_read2_b32 v[198:199], v115 offset0:53 offset1:54
	ds_read2_b32 v[200:201], v115 offset0:59 offset1:60
	ds_read2_b32 v[202:203], v115 offset0:61 offset1:62
	s_add_i32 s90, s67, 0
	v_add_u32_e32 v80, s90, v235
	v_add_u32_e32 v83, s90, v236
	v_add_u32_e32 v99, s90, v237
	v_add_u32_e32 v253, s90, v238
	v_add_u32_e32 v254, s90, v100
	v_add_u32_e32 v255, s90, v149
	v_med3_i32 v80, v80, 0, s99
	v_med3_i32 v83, v83, 0, s99
	v_med3_i32 v99, v99, 0, s99
	v_med3_i32 v253, v253, 0, s99
	v_med3_i32 v254, v254, 0, s99
	v_med3_i32 v255, v255, 0, s99
	v_mad_u32_u24 v80, v80, s100, v252
	v_mad_u32_u24 v83, v83, s100, v252
	v_mad_u32_u24 v99, v99, s100, v252
	v_mad_u32_u24 v253, v253, s100, v252
	v_mad_u32_u24 v254, v254, s100, v153
	v_mad_u32_u24 v255, v255, s100, v153
	global_load_dwordx4 v[116:119], v80, s[82:83]
	global_load_dwordx4 v[120:123], v83, s[82:83]
	global_load_dwordx4 v[124:127], v99, s[82:83]
	global_load_dwordx4 v[128:131], v253, s[82:83]
	global_load_dwordx4 v[132:135], v254, s[82:83] offset:768
	global_load_dwordx4 v[136:139], v255, s[82:83] offset:768
	global_load_dwordx4 v[140:143], v254, s[82:83] offset:832
	global_load_dwordx4 v[144:147], v255, s[82:83] offset:832
	ds_read_b64_tr_b16 v[72:73], v231
	ds_read_b64_tr_b16 v[74:75], v231 offset:512
	ds_read_b64_tr_b16 v[76:77], v231 offset:2048
	ds_read_b64_tr_b16 v[78:79], v231 offset:2560
	ds_read_b64_tr_b16 v[220:221], v231 offset:1024
	ds_read_b64_tr_b16 v[222:223], v231 offset:1536
	ds_read_b64_tr_b16 v[224:225], v231 offset:3072
	ds_read_b64_tr_b16 v[226:227], v231 offset:3584
	v_exp_f32_e32 v32, v32
	v_exp_f32_e32 v33, v33
	v_exp_f32_e32 v34, v34
	v_exp_f32_e32 v35, v35
	s_waitcnt vmcnt(8)
	ds_write_b128 v247, v[156:159]
	ds_write_b128 v247, v[160:163] offset:1024
	ds_write_b128 v247, v[164:167] offset:2048
	ds_write_b128 v247, v[168:171] offset:3072
	ds_read_b128 v[156:159], v248
	ds_read_b128 v[160:163], v249
	ds_read_b128 v[164:167], v250
	ds_read_b128 v[168:171], v251
	ds_write_b128 v112, v[172:175]
	ds_write_b128 v112, v[176:179] offset:1024
	ds_write_b128 v112, v[180:183] offset:2048
	ds_write_b128 v112, v[184:187] offset:3072
	v_exp_f32_e32 v36, v36
	v_exp_f32_e32 v37, v37
	v_exp_f32_e32 v38, v38
	v_exp_f32_e32 v39, v39
	s_waitcnt lgkmcnt(4)
	v_mfma_f32_32x32x16_bf16 v[188:203], v[156:159], v[48:51], v[188:203]
	v_exp_f32_e32 v40, v40
	v_exp_f32_e32 v41, v41
	v_mfma_f32_32x32x16_bf16 v[188:203], v[160:163], v[52:55], v[188:203]
	v_exp_f32_e32 v42, v42
	v_exp_f32_e32 v43, v43
	v_mfma_f32_32x32x16_bf16 v[188:203], v[164:167], v[56:59], v[188:203]
	v_exp_f32_e32 v44, v44
	v_exp_f32_e32 v45, v45
	v_mfma_f32_32x32x16_bf16 v[188:203], v[168:171], v[60:63], v[188:203]
	v_exp_f32_e32 v46, v46
	v_exp_f32_e32 v47, v47
	s_add_i32 s90, s67, -64
	v_add_u32_e32 v84, s90, v107
	v_add_u32_e32 v85, 0, v84
	v_add_u32_e32 v86, 1, v84
	v_add_u32_e32 v87, 2, v84
	v_add_u32_e32 v88, 3, v84
	v_cmp_gt_u32_e64 s[30:31], s98, v85
	v_cmp_gt_u32_e64 s[36:37], s98, v86
	v_cmp_gt_u32_e64 s[78:79], s98, v87
	v_cmp_gt_u32_e64 s[50:51], s98, v88
	v_cndmask_b32_e64 v32, 0, v32, s[30:31]
	v_add_u32_e32 v85, 8, v84
	v_cmp_gt_u32_e64 s[30:31], s98, v85
	v_cndmask_b32_e64 v33, 0, v33, s[36:37]
	v_add_u32_e32 v86, 9, v84
	v_cmp_gt_u32_e64 s[36:37], s98, v86
	v_cndmask_b32_e64 v34, 0, v34, s[78:79]
	v_add_u32_e32 v87, 10, v84
	v_cmp_gt_u32_e64 s[78:79], s98, v87
	v_cndmask_b32_e64 v35, 0, v35, s[50:51]
	v_add_u32_e32 v88, 11, v84
	v_cmp_gt_u32_e64 s[50:51], s98, v88
	v_cndmask_b32_e64 v36, 0, v36, s[30:31]
	v_add_u32_e32 v85, 16, v84
	v_cmp_gt_u32_e64 s[30:31], s98, v85
	v_cndmask_b32_e64 v37, 0, v37, s[36:37]
	v_add_u32_e32 v86, 17, v84
	v_cmp_gt_u32_e64 s[36:37], s98, v86
	v_cndmask_b32_e64 v38, 0, v38, s[78:79]
	v_add_u32_e32 v87, 18, v84
	v_cmp_gt_u32_e64 s[78:79], s98, v87
	v_cndmask_b32_e64 v39, 0, v39, s[50:51]
	v_add_u32_e32 v88, 19, v84
	v_cmp_gt_u32_e64 s[50:51], s98, v88
	v_cndmask_b32_e64 v40, 0, v40, s[30:31]
	v_add_u32_e32 v85, 24, v84
	v_cmp_gt_u32_e64 s[30:31], s98, v85
	v_cndmask_b32_e64 v41, 0, v41, s[36:37]
	v_add_u32_e32 v86, 25, v84
	v_cmp_gt_u32_e64 s[36:37], s98, v86
	v_cndmask_b32_e64 v42, 0, v42, s[78:79]
	v_add_u32_e32 v87, 26, v84
	v_cmp_gt_u32_e64 s[78:79], s98, v87
	v_cndmask_b32_e64 v43, 0, v43, s[50:51]
	v_add_u32_e32 v88, 27, v84
	v_cmp_gt_u32_e64 s[50:51], s98, v88
	v_nop
	v_cndmask_b32_e64 v44, 0, v44, s[30:31]
	v_cndmask_b32_e64 v45, 0, v45, s[36:37]
	v_cndmask_b32_e64 v46, 0, v46, s[78:79]
	v_cndmask_b32_e64 v47, 0, v47, s[50:51]
	v_cvt_pk_bf16_f32 v64, v32, v33
	v_cvt_pk_bf16_f32 v65, v34, v35
	v_cvt_pk_bf16_f32 v66, v36, v37
	v_cvt_pk_bf16_f32 v67, v38, v39
	v_cvt_pk_bf16_f32 v68, v40, v41
	v_cvt_pk_bf16_f32 v69, v42, v43
	v_cvt_pk_bf16_f32 v70, v44, v45
	v_cvt_pk_bf16_f32 v71, v46, v47
	v_pk_add_f32 v[232:233], v[232:233], v[32:33]
	v_pk_add_f32 v[232:233], v[232:233], v[34:35]
	v_pk_add_f32 v[232:233], v[232:233], v[36:37]
	v_pk_add_f32 v[232:233], v[232:233], v[38:39]
	v_pk_add_f32 v[232:233], v[232:233], v[40:41]
	v_pk_add_f32 v[232:233], v[232:233], v[42:43]
	v_pk_add_f32 v[232:233], v[232:233], v[44:45]
	v_pk_add_f32 v[232:233], v[232:233], v[46:47]
	ds_read2_b32 v[32:33], v115 offset0:68 offset1:69
	ds_read2_b32 v[34:35], v115 offset0:70 offset1:71
	ds_read2_b32 v[36:37], v115 offset0:76 offset1:77
	ds_read2_b32 v[38:39], v115 offset0:78 offset1:79
	ds_read2_b32 v[40:41], v115 offset0:85 offset1:86
	ds_read2_b32 v[42:43], v115 offset0:87 offset1:88
	ds_read2_b32 v[44:45], v115 offset0:93 offset1:94
	ds_read2_b32 v[46:47], v115 offset0:95 offset1:96
	v_mfma_f32_32x32x16_bf16 v[0:15], v[64:67], v[72:75], v[0:15]
	v_mfma_f32_32x32x16_bf16 v[16:31], v[64:67], v[76:79], v[16:31]
	v_mfma_f32_32x32x16_bf16 v[0:15], v[68:71], v[220:223], v[0:15]
	v_mfma_f32_32x32x16_bf16 v[16:31], v[68:71], v[224:227], v[16:31]
	s_add_i32 s90, s67, 32
	v_add_u32_e32 v80, s90, v235
	v_add_u32_e32 v83, s90, v236
	v_add_u32_e32 v99, s90, v237
	v_add_u32_e32 v253, s90, v238
	v_add_u32_e32 v254, s90, v100
	v_add_u32_e32 v255, s90, v149
	v_med3_i32 v80, v80, 0, s99
	v_med3_i32 v83, v83, 0, s99
	v_med3_i32 v99, v99, 0, s99
	v_med3_i32 v253, v253, 0, s99
	v_med3_i32 v254, v254, 0, s99
	v_med3_i32 v255, v255, 0, s99
	v_mad_u32_u24 v80, v80, s100, v252
	v_mad_u32_u24 v83, v83, s100, v252
	v_mad_u32_u24 v99, v99, s100, v252
	v_mad_u32_u24 v253, v253, s100, v252
	v_mad_u32_u24 v254, v254, s100, v153
	v_mad_u32_u24 v255, v255, s100, v153
	global_load_dwordx4 v[156:159], v80, s[82:83]
	global_load_dwordx4 v[160:163], v83, s[82:83]
	global_load_dwordx4 v[164:167], v99, s[82:83]
	global_load_dwordx4 v[168:171], v253, s[82:83]
	global_load_dwordx4 v[172:175], v254, s[82:83] offset:768
	global_load_dwordx4 v[176:179], v255, s[82:83] offset:768
	global_load_dwordx4 v[180:183], v254, s[82:83] offset:832
	global_load_dwordx4 v[184:187], v255, s[82:83] offset:832
	ds_read_b64_tr_b16 v[72:73], v231
	ds_read_b64_tr_b16 v[74:75], v231 offset:512
	ds_read_b64_tr_b16 v[76:77], v231 offset:2048
	ds_read_b64_tr_b16 v[78:79], v231 offset:2560
	ds_read_b64_tr_b16 v[220:221], v231 offset:1024
	ds_read_b64_tr_b16 v[222:223], v231 offset:1536
	ds_read_b64_tr_b16 v[224:225], v231 offset:3072
	ds_read_b64_tr_b16 v[226:227], v231 offset:3584
	v_exp_f32_e32 v188, v188
	v_exp_f32_e32 v189, v189
	v_exp_f32_e32 v190, v190
	v_exp_f32_e32 v191, v191
	s_waitcnt vmcnt(8)
	ds_write_b128 v247, v[116:119]
	ds_write_b128 v247, v[120:123] offset:1024
	ds_write_b128 v247, v[124:127] offset:2048
	ds_write_b128 v247, v[128:131] offset:3072
	ds_read_b128 v[116:119], v248
	ds_read_b128 v[120:123], v249
	ds_read_b128 v[124:127], v250
	ds_read_b128 v[128:131], v251
	ds_write_b128 v112, v[132:135]
	ds_write_b128 v112, v[136:139] offset:1024
	ds_write_b128 v112, v[140:143] offset:2048
	ds_write_b128 v112, v[144:147] offset:3072
	v_exp_f32_e32 v192, v192
	v_exp_f32_e32 v193, v193
	v_exp_f32_e32 v194, v194
	v_exp_f32_e32 v195, v195
	s_waitcnt lgkmcnt(4)
	v_mfma_f32_32x32x16_bf16 v[32:47], v[116:119], v[48:51], v[32:47]
	v_exp_f32_e32 v196, v196
	v_exp_f32_e32 v197, v197
	v_mfma_f32_32x32x16_bf16 v[32:47], v[120:123], v[52:55], v[32:47]
	v_exp_f32_e32 v198, v198
	v_exp_f32_e32 v199, v199
	v_mfma_f32_32x32x16_bf16 v[32:47], v[124:127], v[56:59], v[32:47]
	v_exp_f32_e32 v200, v200
	v_exp_f32_e32 v201, v201
	v_mfma_f32_32x32x16_bf16 v[32:47], v[128:131], v[60:63], v[32:47]
	v_exp_f32_e32 v202, v202
	v_exp_f32_e32 v203, v203
	s_add_i32 s90, s67, -32
	v_add_u32_e32 v84, s90, v107
	v_add_u32_e32 v85, 0, v84
	v_add_u32_e32 v86, 1, v84
	v_add_u32_e32 v87, 2, v84
	v_add_u32_e32 v88, 3, v84
	v_cmp_gt_u32_e64 s[30:31], s98, v85
	v_cmp_gt_u32_e64 s[36:37], s98, v86
	v_cmp_gt_u32_e64 s[78:79], s98, v87
	v_cmp_gt_u32_e64 s[50:51], s98, v88
	v_cndmask_b32_e64 v188, 0, v188, s[30:31]
	v_add_u32_e32 v85, 8, v84
	v_cmp_gt_u32_e64 s[30:31], s98, v85
	v_cndmask_b32_e64 v189, 0, v189, s[36:37]
	v_add_u32_e32 v86, 9, v84
	v_cmp_gt_u32_e64 s[36:37], s98, v86
	v_cndmask_b32_e64 v190, 0, v190, s[78:79]
	v_add_u32_e32 v87, 10, v84
	v_cmp_gt_u32_e64 s[78:79], s98, v87
	v_cndmask_b32_e64 v191, 0, v191, s[50:51]
	v_add_u32_e32 v88, 11, v84
	v_cmp_gt_u32_e64 s[50:51], s98, v88
	v_cndmask_b32_e64 v192, 0, v192, s[30:31]
	v_add_u32_e32 v85, 16, v84
	v_cmp_gt_u32_e64 s[30:31], s98, v85
	v_cndmask_b32_e64 v193, 0, v193, s[36:37]
	v_add_u32_e32 v86, 17, v84
	v_cmp_gt_u32_e64 s[36:37], s98, v86
	v_cndmask_b32_e64 v194, 0, v194, s[78:79]
	v_add_u32_e32 v87, 18, v84
	v_cmp_gt_u32_e64 s[78:79], s98, v87
	v_cndmask_b32_e64 v195, 0, v195, s[50:51]
	v_add_u32_e32 v88, 19, v84
	v_cmp_gt_u32_e64 s[50:51], s98, v88
	v_cndmask_b32_e64 v196, 0, v196, s[30:31]
	v_add_u32_e32 v85, 24, v84
	v_cmp_gt_u32_e64 s[30:31], s98, v85
	v_cndmask_b32_e64 v197, 0, v197, s[36:37]
	v_add_u32_e32 v86, 25, v84
	v_cmp_gt_u32_e64 s[36:37], s98, v86
	v_cndmask_b32_e64 v198, 0, v198, s[78:79]
	v_add_u32_e32 v87, 26, v84
	v_cmp_gt_u32_e64 s[78:79], s98, v87
	v_cndmask_b32_e64 v199, 0, v199, s[50:51]
	v_add_u32_e32 v88, 27, v84
	v_cmp_gt_u32_e64 s[50:51], s98, v88
	v_nop
	v_cndmask_b32_e64 v200, 0, v200, s[30:31]
	v_cndmask_b32_e64 v201, 0, v201, s[36:37]
	v_cndmask_b32_e64 v202, 0, v202, s[78:79]
	v_cndmask_b32_e64 v203, 0, v203, s[50:51]
	v_cvt_pk_bf16_f32 v64, v188, v189
	v_cvt_pk_bf16_f32 v65, v190, v191
	v_cvt_pk_bf16_f32 v66, v192, v193
	v_cvt_pk_bf16_f32 v67, v194, v195
	v_cvt_pk_bf16_f32 v68, v196, v197
	v_cvt_pk_bf16_f32 v69, v198, v199
	v_cvt_pk_bf16_f32 v70, v200, v201
	v_cvt_pk_bf16_f32 v71, v202, v203
	v_pk_add_f32 v[232:233], v[232:233], v[188:189]
	v_pk_add_f32 v[232:233], v[232:233], v[190:191]
	v_pk_add_f32 v[232:233], v[232:233], v[192:193]
	v_pk_add_f32 v[232:233], v[232:233], v[194:195]
	v_pk_add_f32 v[232:233], v[232:233], v[196:197]
	v_pk_add_f32 v[232:233], v[232:233], v[198:199]
	v_pk_add_f32 v[232:233], v[232:233], v[200:201]
	v_pk_add_f32 v[232:233], v[232:233], v[202:203]
	ds_read2_b32 v[188:189], v115 offset0:102 offset1:103
	ds_read2_b32 v[190:191], v115 offset0:104 offset1:105
	ds_read2_b32 v[192:193], v115 offset0:110 offset1:111
	ds_read2_b32 v[194:195], v115 offset0:112 offset1:113
	ds_read2_b32 v[196:197], v115 offset0:119 offset1:120
	ds_read2_b32 v[198:199], v115 offset0:121 offset1:122
	ds_read2_b32 v[200:201], v115 offset0:127 offset1:128
	ds_read2_b32 v[202:203], v115 offset0:129 offset1:130
	v_mfma_f32_32x32x16_bf16 v[0:15], v[64:67], v[72:75], v[0:15]
	v_mfma_f32_32x32x16_bf16 v[16:31], v[64:67], v[76:79], v[16:31]
	v_mfma_f32_32x32x16_bf16 v[0:15], v[68:71], v[220:223], v[0:15]
	v_mfma_f32_32x32x16_bf16 v[16:31], v[68:71], v[224:227], v[16:31]
	s_add_i32 s90, s67, 64
	v_add_u32_e32 v80, s90, v235
	v_add_u32_e32 v83, s90, v236
	v_add_u32_e32 v99, s90, v237
	v_add_u32_e32 v253, s90, v238
	v_add_u32_e32 v254, s90, v100
	v_add_u32_e32 v255, s90, v149
	v_med3_i32 v80, v80, 0, s99
	v_med3_i32 v83, v83, 0, s99
	v_med3_i32 v99, v99, 0, s99
	v_med3_i32 v253, v253, 0, s99
	v_med3_i32 v254, v254, 0, s99
	v_med3_i32 v255, v255, 0, s99
	v_mad_u32_u24 v80, v80, s100, v252
	v_mad_u32_u24 v83, v83, s100, v252
	v_mad_u32_u24 v99, v99, s100, v252
	v_mad_u32_u24 v253, v253, s100, v252
	v_mad_u32_u24 v254, v254, s100, v153
	v_mad_u32_u24 v255, v255, s100, v153
	global_load_dwordx4 v[116:119], v80, s[82:83]
	global_load_dwordx4 v[120:123], v83, s[82:83]
	global_load_dwordx4 v[124:127], v99, s[82:83]
	global_load_dwordx4 v[128:131], v253, s[82:83]
	global_load_dwordx4 v[132:135], v254, s[82:83] offset:768
	global_load_dwordx4 v[136:139], v255, s[82:83] offset:768
	global_load_dwordx4 v[140:143], v254, s[82:83] offset:832
	global_load_dwordx4 v[144:147], v255, s[82:83] offset:832
	ds_read_b64_tr_b16 v[72:73], v231
	ds_read_b64_tr_b16 v[74:75], v231 offset:512
	ds_read_b64_tr_b16 v[76:77], v231 offset:2048
	ds_read_b64_tr_b16 v[78:79], v231 offset:2560
	ds_read_b64_tr_b16 v[220:221], v231 offset:1024
	ds_read_b64_tr_b16 v[222:223], v231 offset:1536
	ds_read_b64_tr_b16 v[224:225], v231 offset:3072
	ds_read_b64_tr_b16 v[226:227], v231 offset:3584
	v_exp_f32_e32 v32, v32
	v_exp_f32_e32 v33, v33
	v_exp_f32_e32 v34, v34
	v_exp_f32_e32 v35, v35
	s_waitcnt vmcnt(8)
	ds_write_b128 v247, v[156:159]
	ds_write_b128 v247, v[160:163] offset:1024
	ds_write_b128 v247, v[164:167] offset:2048
	ds_write_b128 v247, v[168:171] offset:3072
	ds_read_b128 v[156:159], v248
	ds_read_b128 v[160:163], v249
	ds_read_b128 v[164:167], v250
	ds_read_b128 v[168:171], v251
	ds_write_b128 v112, v[172:175]
	ds_write_b128 v112, v[176:179] offset:1024
	ds_write_b128 v112, v[180:183] offset:2048
	ds_write_b128 v112, v[184:187] offset:3072
	v_exp_f32_e32 v36, v36
	v_exp_f32_e32 v37, v37
	v_exp_f32_e32 v38, v38
	v_exp_f32_e32 v39, v39
	s_waitcnt lgkmcnt(4)
	v_mfma_f32_32x32x16_bf16 v[188:203], v[156:159], v[48:51], v[188:203]
	v_exp_f32_e32 v40, v40
	v_exp_f32_e32 v41, v41
	v_mfma_f32_32x32x16_bf16 v[188:203], v[160:163], v[52:55], v[188:203]
	v_exp_f32_e32 v42, v42
	v_exp_f32_e32 v43, v43
	v_mfma_f32_32x32x16_bf16 v[188:203], v[164:167], v[56:59], v[188:203]
	v_exp_f32_e32 v44, v44
	v_exp_f32_e32 v45, v45
	v_mfma_f32_32x32x16_bf16 v[188:203], v[168:171], v[60:63], v[188:203]
	v_exp_f32_e32 v46, v46
	v_exp_f32_e32 v47, v47
	s_add_i32 s90, s67, 0
	v_add_u32_e32 v84, s90, v107
	v_add_u32_e32 v85, 0, v84
	v_add_u32_e32 v86, 1, v84
	v_add_u32_e32 v87, 2, v84
	v_add_u32_e32 v88, 3, v84
	v_cmp_gt_u32_e64 s[30:31], s98, v85
	v_cmp_gt_u32_e64 s[36:37], s98, v86
	v_cmp_gt_u32_e64 s[78:79], s98, v87
	v_cmp_gt_u32_e64 s[50:51], s98, v88
	v_cndmask_b32_e64 v32, 0, v32, s[30:31]
	v_add_u32_e32 v85, 8, v84
	v_cmp_gt_u32_e64 s[30:31], s98, v85
	v_cndmask_b32_e64 v33, 0, v33, s[36:37]
	v_add_u32_e32 v86, 9, v84
	v_cmp_gt_u32_e64 s[36:37], s98, v86
	v_cndmask_b32_e64 v34, 0, v34, s[78:79]
	v_add_u32_e32 v87, 10, v84
	v_cmp_gt_u32_e64 s[78:79], s98, v87
	v_cndmask_b32_e64 v35, 0, v35, s[50:51]
	v_add_u32_e32 v88, 11, v84
	v_cmp_gt_u32_e64 s[50:51], s98, v88
	v_cndmask_b32_e64 v36, 0, v36, s[30:31]
	v_add_u32_e32 v85, 16, v84
	v_cmp_gt_u32_e64 s[30:31], s98, v85
	v_cndmask_b32_e64 v37, 0, v37, s[36:37]
	v_add_u32_e32 v86, 17, v84
	v_cmp_gt_u32_e64 s[36:37], s98, v86
	v_cndmask_b32_e64 v38, 0, v38, s[78:79]
	v_add_u32_e32 v87, 18, v84
	v_cmp_gt_u32_e64 s[78:79], s98, v87
	v_cndmask_b32_e64 v39, 0, v39, s[50:51]
	v_add_u32_e32 v88, 19, v84
	v_cmp_gt_u32_e64 s[50:51], s98, v88
	v_cndmask_b32_e64 v40, 0, v40, s[30:31]
	v_add_u32_e32 v85, 24, v84
	v_cmp_gt_u32_e64 s[30:31], s98, v85
	v_cndmask_b32_e64 v41, 0, v41, s[36:37]
	v_add_u32_e32 v86, 25, v84
	v_cmp_gt_u32_e64 s[36:37], s98, v86
	v_cndmask_b32_e64 v42, 0, v42, s[78:79]
	v_add_u32_e32 v87, 26, v84
	v_cmp_gt_u32_e64 s[78:79], s98, v87
	v_cndmask_b32_e64 v43, 0, v43, s[50:51]
	v_add_u32_e32 v88, 27, v84
	v_cmp_gt_u32_e64 s[50:51], s98, v88
	v_nop
	v_cndmask_b32_e64 v44, 0, v44, s[30:31]
	v_cndmask_b32_e64 v45, 0, v45, s[36:37]
	v_cndmask_b32_e64 v46, 0, v46, s[78:79]
	v_cndmask_b32_e64 v47, 0, v47, s[50:51]
	v_cvt_pk_bf16_f32 v64, v32, v33
	v_cvt_pk_bf16_f32 v65, v34, v35
	v_cvt_pk_bf16_f32 v66, v36, v37
	v_cvt_pk_bf16_f32 v67, v38, v39
	v_cvt_pk_bf16_f32 v68, v40, v41
	v_cvt_pk_bf16_f32 v69, v42, v43
	v_cvt_pk_bf16_f32 v70, v44, v45
	v_cvt_pk_bf16_f32 v71, v46, v47
	v_pk_add_f32 v[232:233], v[232:233], v[32:33]
	v_pk_add_f32 v[232:233], v[232:233], v[34:35]
	v_pk_add_f32 v[232:233], v[232:233], v[36:37]
	v_pk_add_f32 v[232:233], v[232:233], v[38:39]
	v_pk_add_f32 v[232:233], v[232:233], v[40:41]
	v_pk_add_f32 v[232:233], v[232:233], v[42:43]
	v_pk_add_f32 v[232:233], v[232:233], v[44:45]
	v_pk_add_f32 v[232:233], v[232:233], v[46:47]
	ds_read2_b32 v[32:33], v115 offset0:136 offset1:137
	ds_read2_b32 v[34:35], v115 offset0:138 offset1:139
	ds_read2_b32 v[36:37], v115 offset0:144 offset1:145
	ds_read2_b32 v[38:39], v115 offset0:146 offset1:147
	ds_read2_b32 v[40:41], v115 offset0:153 offset1:154
	ds_read2_b32 v[42:43], v115 offset0:155 offset1:156
	ds_read2_b32 v[44:45], v115 offset0:161 offset1:162
	ds_read2_b32 v[46:47], v115 offset0:163 offset1:164
	v_mfma_f32_32x32x16_bf16 v[0:15], v[64:67], v[72:75], v[0:15]
	v_mfma_f32_32x32x16_bf16 v[16:31], v[64:67], v[76:79], v[16:31]
	v_mfma_f32_32x32x16_bf16 v[0:15], v[68:71], v[220:223], v[0:15]
	v_mfma_f32_32x32x16_bf16 v[16:31], v[68:71], v[224:227], v[16:31]
	s_add_i32 s90, s67, 96
	v_add_u32_e32 v80, s90, v235
	v_add_u32_e32 v83, s90, v236
	v_add_u32_e32 v99, s90, v237
	v_add_u32_e32 v253, s90, v238
	v_add_u32_e32 v254, s90, v100
	v_add_u32_e32 v255, s90, v149
	v_med3_i32 v80, v80, 0, s99
	v_med3_i32 v83, v83, 0, s99
	v_med3_i32 v99, v99, 0, s99
	v_med3_i32 v253, v253, 0, s99
	v_med3_i32 v254, v254, 0, s99
	v_med3_i32 v255, v255, 0, s99
	v_mad_u32_u24 v80, v80, s100, v252
	v_mad_u32_u24 v83, v83, s100, v252
	v_mad_u32_u24 v99, v99, s100, v252
	v_mad_u32_u24 v253, v253, s100, v252
	v_mad_u32_u24 v254, v254, s100, v153
	v_mad_u32_u24 v255, v255, s100, v153
	global_load_dwordx4 v[156:159], v80, s[82:83]
	global_load_dwordx4 v[160:163], v83, s[82:83]
	global_load_dwordx4 v[164:167], v99, s[82:83]
	global_load_dwordx4 v[168:171], v253, s[82:83]
	global_load_dwordx4 v[172:175], v254, s[82:83] offset:768
	global_load_dwordx4 v[176:179], v255, s[82:83] offset:768
	global_load_dwordx4 v[180:183], v254, s[82:83] offset:832
	global_load_dwordx4 v[184:187], v255, s[82:83] offset:832
	ds_read_b64_tr_b16 v[72:73], v231
	ds_read_b64_tr_b16 v[74:75], v231 offset:512
	ds_read_b64_tr_b16 v[76:77], v231 offset:2048
	ds_read_b64_tr_b16 v[78:79], v231 offset:2560
	ds_read_b64_tr_b16 v[220:221], v231 offset:1024
	ds_read_b64_tr_b16 v[222:223], v231 offset:1536
	ds_read_b64_tr_b16 v[224:225], v231 offset:3072
	ds_read_b64_tr_b16 v[226:227], v231 offset:3584
	v_exp_f32_e32 v188, v188
	v_exp_f32_e32 v189, v189
	v_exp_f32_e32 v190, v190
	v_exp_f32_e32 v191, v191
	s_waitcnt vmcnt(8)
	ds_write_b128 v247, v[116:119]
	ds_write_b128 v247, v[120:123] offset:1024
	ds_write_b128 v247, v[124:127] offset:2048
	ds_write_b128 v247, v[128:131] offset:3072
	ds_read_b128 v[116:119], v248
	ds_read_b128 v[120:123], v249
	ds_read_b128 v[124:127], v250
	ds_read_b128 v[128:131], v251
	ds_write_b128 v112, v[132:135]
	ds_write_b128 v112, v[136:139] offset:1024
	ds_write_b128 v112, v[140:143] offset:2048
	ds_write_b128 v112, v[144:147] offset:3072
	v_exp_f32_e32 v192, v192
	v_exp_f32_e32 v193, v193
	v_exp_f32_e32 v194, v194
	v_exp_f32_e32 v195, v195
	s_waitcnt lgkmcnt(4)
	v_mfma_f32_32x32x16_bf16 v[32:47], v[116:119], v[48:51], v[32:47]
	v_exp_f32_e32 v196, v196
	v_exp_f32_e32 v197, v197
	v_mfma_f32_32x32x16_bf16 v[32:47], v[120:123], v[52:55], v[32:47]
	v_exp_f32_e32 v198, v198
	v_exp_f32_e32 v199, v199
	v_mfma_f32_32x32x16_bf16 v[32:47], v[124:127], v[56:59], v[32:47]
	v_exp_f32_e32 v200, v200
	v_exp_f32_e32 v201, v201
	v_mfma_f32_32x32x16_bf16 v[32:47], v[128:131], v[60:63], v[32:47]
	v_exp_f32_e32 v202, v202
	v_exp_f32_e32 v203, v203
	s_add_i32 s90, s67, 32
	v_add_u32_e32 v84, s90, v107
	v_add_u32_e32 v85, 0, v84
	v_add_u32_e32 v86, 1, v84
	v_add_u32_e32 v87, 2, v84
	v_add_u32_e32 v88, 3, v84
	v_cmp_gt_u32_e64 s[30:31], s98, v85
	v_cmp_gt_u32_e64 s[36:37], s98, v86
	v_cmp_gt_u32_e64 s[78:79], s98, v87
	v_cmp_gt_u32_e64 s[50:51], s98, v88
	v_cndmask_b32_e64 v188, 0, v188, s[30:31]
	v_add_u32_e32 v85, 8, v84
	v_cmp_gt_u32_e64 s[30:31], s98, v85
	v_cndmask_b32_e64 v189, 0, v189, s[36:37]
	v_add_u32_e32 v86, 9, v84
	v_cmp_gt_u32_e64 s[36:37], s98, v86
	v_cndmask_b32_e64 v190, 0, v190, s[78:79]
	v_add_u32_e32 v87, 10, v84
	v_cmp_gt_u32_e64 s[78:79], s98, v87
	v_cndmask_b32_e64 v191, 0, v191, s[50:51]
	v_add_u32_e32 v88, 11, v84
	v_cmp_gt_u32_e64 s[50:51], s98, v88
	v_cndmask_b32_e64 v192, 0, v192, s[30:31]
	v_add_u32_e32 v85, 16, v84
	v_cmp_gt_u32_e64 s[30:31], s98, v85
	v_cndmask_b32_e64 v193, 0, v193, s[36:37]
	v_add_u32_e32 v86, 17, v84
	v_cmp_gt_u32_e64 s[36:37], s98, v86
	v_cndmask_b32_e64 v194, 0, v194, s[78:79]
	v_add_u32_e32 v87, 18, v84
	v_cmp_gt_u32_e64 s[78:79], s98, v87
	v_cndmask_b32_e64 v195, 0, v195, s[50:51]
	v_add_u32_e32 v88, 19, v84
	v_cmp_gt_u32_e64 s[50:51], s98, v88
	v_cndmask_b32_e64 v196, 0, v196, s[30:31]
	v_add_u32_e32 v85, 24, v84
	v_cmp_gt_u32_e64 s[30:31], s98, v85
	v_cndmask_b32_e64 v197, 0, v197, s[36:37]
	v_add_u32_e32 v86, 25, v84
	v_cmp_gt_u32_e64 s[36:37], s98, v86
	v_cndmask_b32_e64 v198, 0, v198, s[78:79]
	v_add_u32_e32 v87, 26, v84
	v_cmp_gt_u32_e64 s[78:79], s98, v87
	v_cndmask_b32_e64 v199, 0, v199, s[50:51]
	v_add_u32_e32 v88, 27, v84
	v_cmp_gt_u32_e64 s[50:51], s98, v88
	v_nop
	v_cndmask_b32_e64 v200, 0, v200, s[30:31]
	v_cndmask_b32_e64 v201, 0, v201, s[36:37]
	v_cndmask_b32_e64 v202, 0, v202, s[78:79]
	v_cndmask_b32_e64 v203, 0, v203, s[50:51]
	v_cvt_pk_bf16_f32 v64, v188, v189
	v_cvt_pk_bf16_f32 v65, v190, v191
	v_cvt_pk_bf16_f32 v66, v192, v193
	v_cvt_pk_bf16_f32 v67, v194, v195
	v_cvt_pk_bf16_f32 v68, v196, v197
	v_cvt_pk_bf16_f32 v69, v198, v199
	v_cvt_pk_bf16_f32 v70, v200, v201
	v_cvt_pk_bf16_f32 v71, v202, v203
	v_pk_add_f32 v[232:233], v[232:233], v[188:189]
	v_pk_add_f32 v[232:233], v[232:233], v[190:191]
	v_pk_add_f32 v[232:233], v[232:233], v[192:193]
	v_pk_add_f32 v[232:233], v[232:233], v[194:195]
	v_pk_add_f32 v[232:233], v[232:233], v[196:197]
	v_pk_add_f32 v[232:233], v[232:233], v[198:199]
	v_pk_add_f32 v[232:233], v[232:233], v[200:201]
	v_pk_add_f32 v[232:233], v[232:233], v[202:203]
	ds_read2_b32 v[188:189], v115 offset0:170 offset1:171
	ds_read2_b32 v[190:191], v115 offset0:172 offset1:173
	ds_read2_b32 v[192:193], v115 offset0:178 offset1:179
	ds_read2_b32 v[194:195], v115 offset0:180 offset1:181
	ds_read2_b32 v[196:197], v115 offset0:187 offset1:188
	ds_read2_b32 v[198:199], v115 offset0:189 offset1:190
	ds_read2_b32 v[200:201], v115 offset0:195 offset1:196
	ds_read2_b32 v[202:203], v115 offset0:197 offset1:198
	v_mfma_f32_32x32x16_bf16 v[0:15], v[64:67], v[72:75], v[0:15]
	v_mfma_f32_32x32x16_bf16 v[16:31], v[64:67], v[76:79], v[16:31]
	v_mfma_f32_32x32x16_bf16 v[0:15], v[68:71], v[220:223], v[0:15]
	v_mfma_f32_32x32x16_bf16 v[16:31], v[68:71], v[224:227], v[16:31]
	s_add_i32 s90, s67, 128
	v_add_u32_e32 v80, s90, v235
	v_add_u32_e32 v83, s90, v236
	v_add_u32_e32 v99, s90, v237
	v_add_u32_e32 v253, s90, v238
	v_add_u32_e32 v254, s90, v100
	v_add_u32_e32 v255, s90, v149
	v_med3_i32 v80, v80, 0, s99
	v_med3_i32 v83, v83, 0, s99
	v_med3_i32 v99, v99, 0, s99
	v_med3_i32 v253, v253, 0, s99
	v_med3_i32 v254, v254, 0, s99
	v_med3_i32 v255, v255, 0, s99
	v_mad_u32_u24 v80, v80, s100, v252
	v_mad_u32_u24 v83, v83, s100, v252
	v_mad_u32_u24 v99, v99, s100, v252
	v_mad_u32_u24 v253, v253, s100, v252
	v_mad_u32_u24 v254, v254, s100, v153
	v_mad_u32_u24 v255, v255, s100, v153
	global_load_dwordx4 v[116:119], v80, s[82:83]
	global_load_dwordx4 v[120:123], v83, s[82:83]
	global_load_dwordx4 v[124:127], v99, s[82:83]
	global_load_dwordx4 v[128:131], v253, s[82:83]
	global_load_dwordx4 v[132:135], v254, s[82:83] offset:768
	global_load_dwordx4 v[136:139], v255, s[82:83] offset:768
	global_load_dwordx4 v[140:143], v254, s[82:83] offset:832
	global_load_dwordx4 v[144:147], v255, s[82:83] offset:832
	ds_read_b64_tr_b16 v[72:73], v231
	ds_read_b64_tr_b16 v[74:75], v231 offset:512
	ds_read_b64_tr_b16 v[76:77], v231 offset:2048
	ds_read_b64_tr_b16 v[78:79], v231 offset:2560
	ds_read_b64_tr_b16 v[220:221], v231 offset:1024
	ds_read_b64_tr_b16 v[222:223], v231 offset:1536
	ds_read_b64_tr_b16 v[224:225], v231 offset:3072
	ds_read_b64_tr_b16 v[226:227], v231 offset:3584
	v_exp_f32_e32 v32, v32
	v_exp_f32_e32 v33, v33
	v_exp_f32_e32 v34, v34
	v_exp_f32_e32 v35, v35
	s_waitcnt vmcnt(8)
	ds_write_b128 v247, v[156:159]
	ds_write_b128 v247, v[160:163] offset:1024
	ds_write_b128 v247, v[164:167] offset:2048
	ds_write_b128 v247, v[168:171] offset:3072
	ds_read_b128 v[156:159], v248
	ds_read_b128 v[160:163], v249
	ds_read_b128 v[164:167], v250
	ds_read_b128 v[168:171], v251
	ds_write_b128 v112, v[172:175]
	ds_write_b128 v112, v[176:179] offset:1024
	ds_write_b128 v112, v[180:183] offset:2048
	ds_write_b128 v112, v[184:187] offset:3072
	v_exp_f32_e32 v36, v36
	v_exp_f32_e32 v37, v37
	v_exp_f32_e32 v38, v38
	v_exp_f32_e32 v39, v39
	s_waitcnt lgkmcnt(4)
	v_mfma_f32_32x32x16_bf16 v[188:203], v[156:159], v[48:51], v[188:203]
	v_exp_f32_e32 v40, v40
	v_exp_f32_e32 v41, v41
	v_mfma_f32_32x32x16_bf16 v[188:203], v[160:163], v[52:55], v[188:203]
	v_exp_f32_e32 v42, v42
	v_exp_f32_e32 v43, v43
	v_mfma_f32_32x32x16_bf16 v[188:203], v[164:167], v[56:59], v[188:203]
	v_exp_f32_e32 v44, v44
	v_exp_f32_e32 v45, v45
	v_mfma_f32_32x32x16_bf16 v[188:203], v[168:171], v[60:63], v[188:203]
	v_exp_f32_e32 v46, v46
	v_exp_f32_e32 v47, v47
	s_add_i32 s90, s67, 64
	v_add_u32_e32 v84, s90, v107
	v_add_u32_e32 v85, 0, v84
	v_add_u32_e32 v86, 1, v84
	v_add_u32_e32 v87, 2, v84
	v_add_u32_e32 v88, 3, v84
	v_cmp_gt_u32_e64 s[30:31], s98, v85
	v_cmp_gt_u32_e64 s[36:37], s98, v86
	v_cmp_gt_u32_e64 s[78:79], s98, v87
	v_cmp_gt_u32_e64 s[50:51], s98, v88
	v_cndmask_b32_e64 v32, 0, v32, s[30:31]
	v_add_u32_e32 v85, 8, v84
	v_cmp_gt_u32_e64 s[30:31], s98, v85
	v_cndmask_b32_e64 v33, 0, v33, s[36:37]
	v_add_u32_e32 v86, 9, v84
	v_cmp_gt_u32_e64 s[36:37], s98, v86
	v_cndmask_b32_e64 v34, 0, v34, s[78:79]
	v_add_u32_e32 v87, 10, v84
	v_cmp_gt_u32_e64 s[78:79], s98, v87
	v_cndmask_b32_e64 v35, 0, v35, s[50:51]
	v_add_u32_e32 v88, 11, v84
	v_cmp_gt_u32_e64 s[50:51], s98, v88
	v_cndmask_b32_e64 v36, 0, v36, s[30:31]
	v_add_u32_e32 v85, 16, v84
	v_cmp_gt_u32_e64 s[30:31], s98, v85
	v_cndmask_b32_e64 v37, 0, v37, s[36:37]
	v_add_u32_e32 v86, 17, v84
	v_cmp_gt_u32_e64 s[36:37], s98, v86
	v_cndmask_b32_e64 v38, 0, v38, s[78:79]
	v_add_u32_e32 v87, 18, v84
	v_cmp_gt_u32_e64 s[78:79], s98, v87
	v_cndmask_b32_e64 v39, 0, v39, s[50:51]
	v_add_u32_e32 v88, 19, v84
	v_cmp_gt_u32_e64 s[50:51], s98, v88
	v_cndmask_b32_e64 v40, 0, v40, s[30:31]
	v_add_u32_e32 v85, 24, v84
	v_cmp_gt_u32_e64 s[30:31], s98, v85
	v_cndmask_b32_e64 v41, 0, v41, s[36:37]
	v_add_u32_e32 v86, 25, v84
	v_cmp_gt_u32_e64 s[36:37], s98, v86
	v_cndmask_b32_e64 v42, 0, v42, s[78:79]
	v_add_u32_e32 v87, 26, v84
	v_cmp_gt_u32_e64 s[78:79], s98, v87
	v_cndmask_b32_e64 v43, 0, v43, s[50:51]
	v_add_u32_e32 v88, 27, v84
	v_cmp_gt_u32_e64 s[50:51], s98, v88
	v_nop
	v_cndmask_b32_e64 v44, 0, v44, s[30:31]
	v_cndmask_b32_e64 v45, 0, v45, s[36:37]
	v_cndmask_b32_e64 v46, 0, v46, s[78:79]
	v_cndmask_b32_e64 v47, 0, v47, s[50:51]
	v_cvt_pk_bf16_f32 v64, v32, v33
	v_cvt_pk_bf16_f32 v65, v34, v35
	v_cvt_pk_bf16_f32 v66, v36, v37
	v_cvt_pk_bf16_f32 v67, v38, v39
	v_cvt_pk_bf16_f32 v68, v40, v41
	v_cvt_pk_bf16_f32 v69, v42, v43
	v_cvt_pk_bf16_f32 v70, v44, v45
	v_cvt_pk_bf16_f32 v71, v46, v47
	v_pk_add_f32 v[232:233], v[232:233], v[32:33]
	v_pk_add_f32 v[232:233], v[232:233], v[34:35]
	v_pk_add_f32 v[232:233], v[232:233], v[36:37]
	v_pk_add_f32 v[232:233], v[232:233], v[38:39]
	v_pk_add_f32 v[232:233], v[232:233], v[40:41]
	v_pk_add_f32 v[232:233], v[232:233], v[42:43]
	v_pk_add_f32 v[232:233], v[232:233], v[44:45]
	v_pk_add_f32 v[232:233], v[232:233], v[46:47]
	ds_read2_b32 v[32:33], v115 offset0:204 offset1:205
	ds_read2_b32 v[34:35], v115 offset0:206 offset1:207
	ds_read2_b32 v[36:37], v115 offset0:212 offset1:213
	ds_read2_b32 v[38:39], v115 offset0:214 offset1:215
	ds_read2_b32 v[40:41], v115 offset0:221 offset1:222
	ds_read2_b32 v[42:43], v115 offset0:223 offset1:224
	ds_read2_b32 v[44:45], v115 offset0:229 offset1:230
	ds_read2_b32 v[46:47], v115 offset0:231 offset1:232
	v_mfma_f32_32x32x16_bf16 v[0:15], v[64:67], v[72:75], v[0:15]
	v_mfma_f32_32x32x16_bf16 v[16:31], v[64:67], v[76:79], v[16:31]
	v_mfma_f32_32x32x16_bf16 v[0:15], v[68:71], v[220:223], v[0:15]
	v_mfma_f32_32x32x16_bf16 v[16:31], v[68:71], v[224:227], v[16:31]
	s_add_i32 s90, s67, 160
	v_add_u32_e32 v80, s90, v235
	v_add_u32_e32 v83, s90, v236
	v_add_u32_e32 v99, s90, v237
	v_add_u32_e32 v253, s90, v238
	v_add_u32_e32 v254, s90, v100
	v_add_u32_e32 v255, s90, v149
	v_med3_i32 v80, v80, 0, s99
	v_med3_i32 v83, v83, 0, s99
	v_med3_i32 v99, v99, 0, s99
	v_med3_i32 v253, v253, 0, s99
	v_med3_i32 v254, v254, 0, s99
	v_med3_i32 v255, v255, 0, s99
	v_mad_u32_u24 v80, v80, s100, v252
	v_mad_u32_u24 v83, v83, s100, v252
	v_mad_u32_u24 v99, v99, s100, v252
	v_mad_u32_u24 v253, v253, s100, v252
	v_mad_u32_u24 v254, v254, s100, v153
	v_mad_u32_u24 v255, v255, s100, v153
	global_load_dwordx4 v[156:159], v80, s[82:83]
	global_load_dwordx4 v[160:163], v83, s[82:83]
	global_load_dwordx4 v[164:167], v99, s[82:83]
	global_load_dwordx4 v[168:171], v253, s[82:83]
	global_load_dwordx4 v[172:175], v254, s[82:83] offset:768
	global_load_dwordx4 v[176:179], v255, s[82:83] offset:768
	global_load_dwordx4 v[180:183], v254, s[82:83] offset:832
	global_load_dwordx4 v[184:187], v255, s[82:83] offset:832
	ds_read_b64_tr_b16 v[72:73], v231
	ds_read_b64_tr_b16 v[74:75], v231 offset:512
	ds_read_b64_tr_b16 v[76:77], v231 offset:2048
	ds_read_b64_tr_b16 v[78:79], v231 offset:2560
	ds_read_b64_tr_b16 v[220:221], v231 offset:1024
	ds_read_b64_tr_b16 v[222:223], v231 offset:1536
	ds_read_b64_tr_b16 v[224:225], v231 offset:3072
	ds_read_b64_tr_b16 v[226:227], v231 offset:3584
	v_exp_f32_e32 v188, v188
	v_exp_f32_e32 v189, v189
	v_exp_f32_e32 v190, v190
	v_exp_f32_e32 v191, v191
	s_waitcnt vmcnt(8)
	ds_write_b128 v247, v[116:119]
	ds_write_b128 v247, v[120:123] offset:1024
	ds_write_b128 v247, v[124:127] offset:2048
	ds_write_b128 v247, v[128:131] offset:3072
	ds_read_b128 v[116:119], v248
	ds_read_b128 v[120:123], v249
	ds_read_b128 v[124:127], v250
	ds_read_b128 v[128:131], v251
	ds_write_b128 v112, v[132:135]
	ds_write_b128 v112, v[136:139] offset:1024
	ds_write_b128 v112, v[140:143] offset:2048
	ds_write_b128 v112, v[144:147] offset:3072
	v_exp_f32_e32 v192, v192
	v_exp_f32_e32 v193, v193
	v_exp_f32_e32 v194, v194
	v_exp_f32_e32 v195, v195
	s_waitcnt lgkmcnt(4)
	v_mfma_f32_32x32x16_bf16 v[32:47], v[116:119], v[48:51], v[32:47]
	v_exp_f32_e32 v196, v196
	v_exp_f32_e32 v197, v197
	v_mfma_f32_32x32x16_bf16 v[32:47], v[120:123], v[52:55], v[32:47]
	v_exp_f32_e32 v198, v198
	v_exp_f32_e32 v199, v199
	v_mfma_f32_32x32x16_bf16 v[32:47], v[124:127], v[56:59], v[32:47]
	v_exp_f32_e32 v200, v200
	v_exp_f32_e32 v201, v201
	v_mfma_f32_32x32x16_bf16 v[32:47], v[128:131], v[60:63], v[32:47]
	v_exp_f32_e32 v202, v202
	v_exp_f32_e32 v203, v203
	s_add_i32 s90, s67, 96
	v_add_u32_e32 v84, s90, v107
	v_add_u32_e32 v85, 0, v84
	v_add_u32_e32 v86, 1, v84
	v_add_u32_e32 v87, 2, v84
	v_add_u32_e32 v88, 3, v84
	v_cmp_gt_u32_e64 s[30:31], s98, v85
	v_cmp_gt_u32_e64 s[36:37], s98, v86
	v_cmp_gt_u32_e64 s[78:79], s98, v87
	v_cmp_gt_u32_e64 s[50:51], s98, v88
	v_cndmask_b32_e64 v188, 0, v188, s[30:31]
	v_add_u32_e32 v85, 8, v84
	v_cmp_gt_u32_e64 s[30:31], s98, v85
	v_cndmask_b32_e64 v189, 0, v189, s[36:37]
	v_add_u32_e32 v86, 9, v84
	v_cmp_gt_u32_e64 s[36:37], s98, v86
	v_cndmask_b32_e64 v190, 0, v190, s[78:79]
	v_add_u32_e32 v87, 10, v84
	v_cmp_gt_u32_e64 s[78:79], s98, v87
	v_cndmask_b32_e64 v191, 0, v191, s[50:51]
	v_add_u32_e32 v88, 11, v84
	v_cmp_gt_u32_e64 s[50:51], s98, v88
	v_cndmask_b32_e64 v192, 0, v192, s[30:31]
	v_add_u32_e32 v85, 16, v84
	v_cmp_gt_u32_e64 s[30:31], s98, v85
	v_cndmask_b32_e64 v193, 0, v193, s[36:37]
	v_add_u32_e32 v86, 17, v84
	v_cmp_gt_u32_e64 s[36:37], s98, v86
	v_cndmask_b32_e64 v194, 0, v194, s[78:79]
	v_add_u32_e32 v87, 18, v84
	v_cmp_gt_u32_e64 s[78:79], s98, v87
	v_cndmask_b32_e64 v195, 0, v195, s[50:51]
	v_add_u32_e32 v88, 19, v84
	v_cmp_gt_u32_e64 s[50:51], s98, v88
	v_cndmask_b32_e64 v196, 0, v196, s[30:31]
	v_add_u32_e32 v85, 24, v84
	v_cmp_gt_u32_e64 s[30:31], s98, v85
	v_cndmask_b32_e64 v197, 0, v197, s[36:37]
	v_add_u32_e32 v86, 25, v84
	v_cmp_gt_u32_e64 s[36:37], s98, v86
	v_cndmask_b32_e64 v198, 0, v198, s[78:79]
	v_add_u32_e32 v87, 26, v84
	v_cmp_gt_u32_e64 s[78:79], s98, v87
	v_cndmask_b32_e64 v199, 0, v199, s[50:51]
	v_add_u32_e32 v88, 27, v84
	v_cmp_gt_u32_e64 s[50:51], s98, v88
	v_nop
	v_cndmask_b32_e64 v200, 0, v200, s[30:31]
	v_cndmask_b32_e64 v201, 0, v201, s[36:37]
	v_cndmask_b32_e64 v202, 0, v202, s[78:79]
	v_cndmask_b32_e64 v203, 0, v203, s[50:51]
	v_cvt_pk_bf16_f32 v64, v188, v189
	v_cvt_pk_bf16_f32 v65, v190, v191
	v_cvt_pk_bf16_f32 v66, v192, v193
	v_cvt_pk_bf16_f32 v67, v194, v195
	v_cvt_pk_bf16_f32 v68, v196, v197
	v_cvt_pk_bf16_f32 v69, v198, v199
	v_cvt_pk_bf16_f32 v70, v200, v201
	v_cvt_pk_bf16_f32 v71, v202, v203
	v_pk_add_f32 v[232:233], v[232:233], v[188:189]
	v_pk_add_f32 v[232:233], v[232:233], v[190:191]
	v_pk_add_f32 v[232:233], v[232:233], v[192:193]
	v_pk_add_f32 v[232:233], v[232:233], v[194:195]
	v_pk_add_f32 v[232:233], v[232:233], v[196:197]
	v_pk_add_f32 v[232:233], v[232:233], v[198:199]
	v_pk_add_f32 v[232:233], v[232:233], v[200:201]
	v_pk_add_f32 v[232:233], v[232:233], v[202:203]
	v_add_u32_e32 v115, 952, v115
	ds_read2_b32 v[188:189], v115 offset0:0 offset1:1
	ds_read2_b32 v[190:191], v115 offset0:2 offset1:3
	ds_read2_b32 v[192:193], v115 offset0:8 offset1:9
	ds_read2_b32 v[194:195], v115 offset0:10 offset1:11
	ds_read2_b32 v[196:197], v115 offset0:17 offset1:18
	ds_read2_b32 v[198:199], v115 offset0:19 offset1:20
	ds_read2_b32 v[200:201], v115 offset0:25 offset1:26
	ds_read2_b32 v[202:203], v115 offset0:27 offset1:28
	v_mfma_f32_32x32x16_bf16 v[0:15], v[64:67], v[72:75], v[0:15]
	v_mfma_f32_32x32x16_bf16 v[16:31], v[64:67], v[76:79], v[16:31]
	v_mfma_f32_32x32x16_bf16 v[0:15], v[68:71], v[220:223], v[0:15]
	v_mfma_f32_32x32x16_bf16 v[16:31], v[68:71], v[224:227], v[16:31]
	s_add_i32 s90, s67, 192
	v_add_u32_e32 v80, s90, v235
	v_add_u32_e32 v83, s90, v236
	v_add_u32_e32 v99, s90, v237
	v_add_u32_e32 v253, s90, v238
	v_add_u32_e32 v254, s90, v100
	v_add_u32_e32 v255, s90, v149
	v_med3_i32 v80, v80, 0, s99
	v_med3_i32 v83, v83, 0, s99
	v_med3_i32 v99, v99, 0, s99
	v_med3_i32 v253, v253, 0, s99
	v_med3_i32 v254, v254, 0, s99
	v_med3_i32 v255, v255, 0, s99
	v_mad_u32_u24 v80, v80, s100, v252
	v_mad_u32_u24 v83, v83, s100, v252
	v_mad_u32_u24 v99, v99, s100, v252
	v_mad_u32_u24 v253, v253, s100, v252
	v_mad_u32_u24 v254, v254, s100, v153
	v_mad_u32_u24 v255, v255, s100, v153
	global_load_dwordx4 v[116:119], v80, s[82:83]
	global_load_dwordx4 v[120:123], v83, s[82:83]
	global_load_dwordx4 v[124:127], v99, s[82:83]
	global_load_dwordx4 v[128:131], v253, s[82:83]
	global_load_dwordx4 v[132:135], v254, s[82:83] offset:768
	global_load_dwordx4 v[136:139], v255, s[82:83] offset:768
	global_load_dwordx4 v[140:143], v254, s[82:83] offset:832
	global_load_dwordx4 v[144:147], v255, s[82:83] offset:832
	ds_read_b64_tr_b16 v[72:73], v231
	ds_read_b64_tr_b16 v[74:75], v231 offset:512
	ds_read_b64_tr_b16 v[76:77], v231 offset:2048
	ds_read_b64_tr_b16 v[78:79], v231 offset:2560
	ds_read_b64_tr_b16 v[220:221], v231 offset:1024
	ds_read_b64_tr_b16 v[222:223], v231 offset:1536
	ds_read_b64_tr_b16 v[224:225], v231 offset:3072
	ds_read_b64_tr_b16 v[226:227], v231 offset:3584
	v_exp_f32_e32 v32, v32
	v_exp_f32_e32 v33, v33
	v_exp_f32_e32 v34, v34
	v_exp_f32_e32 v35, v35
	s_waitcnt vmcnt(8)
	ds_write_b128 v247, v[156:159]
	ds_write_b128 v247, v[160:163] offset:1024
	ds_write_b128 v247, v[164:167] offset:2048
	ds_write_b128 v247, v[168:171] offset:3072
	ds_read_b128 v[156:159], v248
	ds_read_b128 v[160:163], v249
	ds_read_b128 v[164:167], v250
	ds_read_b128 v[168:171], v251
	ds_write_b128 v112, v[172:175]
	ds_write_b128 v112, v[176:179] offset:1024
	ds_write_b128 v112, v[180:183] offset:2048
	ds_write_b128 v112, v[184:187] offset:3072
	v_exp_f32_e32 v36, v36
	v_exp_f32_e32 v37, v37
	v_exp_f32_e32 v38, v38
	v_exp_f32_e32 v39, v39
	s_waitcnt lgkmcnt(4)
	v_mfma_f32_32x32x16_bf16 v[188:203], v[156:159], v[48:51], v[188:203]
	v_exp_f32_e32 v40, v40
	v_exp_f32_e32 v41, v41
	v_mfma_f32_32x32x16_bf16 v[188:203], v[160:163], v[52:55], v[188:203]
	v_exp_f32_e32 v42, v42
	v_exp_f32_e32 v43, v43
	v_mfma_f32_32x32x16_bf16 v[188:203], v[164:167], v[56:59], v[188:203]
	v_exp_f32_e32 v44, v44
	v_exp_f32_e32 v45, v45
	v_mfma_f32_32x32x16_bf16 v[188:203], v[168:171], v[60:63], v[188:203]
	v_exp_f32_e32 v46, v46
	v_exp_f32_e32 v47, v47
	s_add_i32 s90, s67, 128
	v_add_u32_e32 v84, s90, v107
	v_add_u32_e32 v85, 0, v84
	v_add_u32_e32 v86, 1, v84
	v_add_u32_e32 v87, 2, v84
	v_add_u32_e32 v88, 3, v84
	v_cmp_gt_u32_e64 s[30:31], s98, v85
	v_cmp_gt_u32_e64 s[36:37], s98, v86
	v_cmp_gt_u32_e64 s[78:79], s98, v87
	v_cmp_gt_u32_e64 s[50:51], s98, v88
	v_cndmask_b32_e64 v32, 0, v32, s[30:31]
	v_add_u32_e32 v85, 8, v84
	v_cmp_gt_u32_e64 s[30:31], s98, v85
	v_cndmask_b32_e64 v33, 0, v33, s[36:37]
	v_add_u32_e32 v86, 9, v84
	v_cmp_gt_u32_e64 s[36:37], s98, v86
	v_cndmask_b32_e64 v34, 0, v34, s[78:79]
	v_add_u32_e32 v87, 10, v84
	v_cmp_gt_u32_e64 s[78:79], s98, v87
	v_cndmask_b32_e64 v35, 0, v35, s[50:51]
	v_add_u32_e32 v88, 11, v84
	v_cmp_gt_u32_e64 s[50:51], s98, v88
	v_cndmask_b32_e64 v36, 0, v36, s[30:31]
	v_add_u32_e32 v85, 16, v84
	v_cmp_gt_u32_e64 s[30:31], s98, v85
	v_cndmask_b32_e64 v37, 0, v37, s[36:37]
	v_add_u32_e32 v86, 17, v84
	v_cmp_gt_u32_e64 s[36:37], s98, v86
	v_cndmask_b32_e64 v38, 0, v38, s[78:79]
	v_add_u32_e32 v87, 18, v84
	v_cmp_gt_u32_e64 s[78:79], s98, v87
	v_cndmask_b32_e64 v39, 0, v39, s[50:51]
	v_add_u32_e32 v88, 19, v84
	v_cmp_gt_u32_e64 s[50:51], s98, v88
	v_cndmask_b32_e64 v40, 0, v40, s[30:31]
	v_add_u32_e32 v85, 24, v84
	v_cmp_gt_u32_e64 s[30:31], s98, v85
	v_cndmask_b32_e64 v41, 0, v41, s[36:37]
	v_add_u32_e32 v86, 25, v84
	v_cmp_gt_u32_e64 s[36:37], s98, v86
	v_cndmask_b32_e64 v42, 0, v42, s[78:79]
	v_add_u32_e32 v87, 26, v84
	v_cmp_gt_u32_e64 s[78:79], s98, v87
	v_cndmask_b32_e64 v43, 0, v43, s[50:51]
	v_add_u32_e32 v88, 27, v84
	v_cmp_gt_u32_e64 s[50:51], s98, v88
	v_nop
	v_cndmask_b32_e64 v44, 0, v44, s[30:31]
	v_cndmask_b32_e64 v45, 0, v45, s[36:37]
	v_cndmask_b32_e64 v46, 0, v46, s[78:79]
	v_cndmask_b32_e64 v47, 0, v47, s[50:51]
	v_cvt_pk_bf16_f32 v64, v32, v33
	v_cvt_pk_bf16_f32 v65, v34, v35
	v_cvt_pk_bf16_f32 v66, v36, v37
	v_cvt_pk_bf16_f32 v67, v38, v39
	v_cvt_pk_bf16_f32 v68, v40, v41
	v_cvt_pk_bf16_f32 v69, v42, v43
	v_cvt_pk_bf16_f32 v70, v44, v45
	v_cvt_pk_bf16_f32 v71, v46, v47
	v_pk_add_f32 v[232:233], v[232:233], v[32:33]
	v_pk_add_f32 v[232:233], v[232:233], v[34:35]
	v_pk_add_f32 v[232:233], v[232:233], v[36:37]
	v_pk_add_f32 v[232:233], v[232:233], v[38:39]
	v_pk_add_f32 v[232:233], v[232:233], v[40:41]
	v_pk_add_f32 v[232:233], v[232:233], v[42:43]
	v_pk_add_f32 v[232:233], v[232:233], v[44:45]
	v_pk_add_f32 v[232:233], v[232:233], v[46:47]
	ds_read2_b32 v[32:33], v115 offset0:34 offset1:35
	ds_read2_b32 v[34:35], v115 offset0:36 offset1:37
	ds_read2_b32 v[36:37], v115 offset0:42 offset1:43
	ds_read2_b32 v[38:39], v115 offset0:44 offset1:45
	ds_read2_b32 v[40:41], v115 offset0:51 offset1:52
	ds_read2_b32 v[42:43], v115 offset0:53 offset1:54
	ds_read2_b32 v[44:45], v115 offset0:59 offset1:60
	ds_read2_b32 v[46:47], v115 offset0:61 offset1:62
	v_mfma_f32_32x32x16_bf16 v[0:15], v[64:67], v[72:75], v[0:15]
	v_mfma_f32_32x32x16_bf16 v[16:31], v[64:67], v[76:79], v[16:31]
	v_mfma_f32_32x32x16_bf16 v[0:15], v[68:71], v[220:223], v[0:15]
	v_mfma_f32_32x32x16_bf16 v[16:31], v[68:71], v[224:227], v[16:31]
	s_add_i32 s90, s67, 224
	v_add_u32_e32 v80, s90, v235
	v_add_u32_e32 v83, s90, v236
	v_add_u32_e32 v99, s90, v237
	v_add_u32_e32 v253, s90, v238
	v_add_u32_e32 v254, s90, v100
	v_add_u32_e32 v255, s90, v149
	v_med3_i32 v80, v80, 0, s99
	v_med3_i32 v83, v83, 0, s99
	v_med3_i32 v99, v99, 0, s99
	v_med3_i32 v253, v253, 0, s99
	v_med3_i32 v254, v254, 0, s99
	v_med3_i32 v255, v255, 0, s99
	v_mad_u32_u24 v80, v80, s100, v252
	v_mad_u32_u24 v83, v83, s100, v252
	v_mad_u32_u24 v99, v99, s100, v252
	v_mad_u32_u24 v253, v253, s100, v252
	v_mad_u32_u24 v254, v254, s100, v153
	v_mad_u32_u24 v255, v255, s100, v153
	global_load_dwordx4 v[156:159], v80, s[82:83]
	global_load_dwordx4 v[160:163], v83, s[82:83]
	global_load_dwordx4 v[164:167], v99, s[82:83]
	global_load_dwordx4 v[168:171], v253, s[82:83]
	global_load_dwordx4 v[172:175], v254, s[82:83] offset:768
	global_load_dwordx4 v[176:179], v255, s[82:83] offset:768
	global_load_dwordx4 v[180:183], v254, s[82:83] offset:832
	global_load_dwordx4 v[184:187], v255, s[82:83] offset:832
	ds_read_b64_tr_b16 v[72:73], v231
	ds_read_b64_tr_b16 v[74:75], v231 offset:512
	ds_read_b64_tr_b16 v[76:77], v231 offset:2048
	ds_read_b64_tr_b16 v[78:79], v231 offset:2560
	ds_read_b64_tr_b16 v[220:221], v231 offset:1024
	ds_read_b64_tr_b16 v[222:223], v231 offset:1536
	ds_read_b64_tr_b16 v[224:225], v231 offset:3072
	ds_read_b64_tr_b16 v[226:227], v231 offset:3584
	v_exp_f32_e32 v188, v188
	v_exp_f32_e32 v189, v189
	v_exp_f32_e32 v190, v190
	v_exp_f32_e32 v191, v191
	s_waitcnt vmcnt(8)
	ds_write_b128 v247, v[116:119]
	ds_write_b128 v247, v[120:123] offset:1024
	ds_write_b128 v247, v[124:127] offset:2048
	ds_write_b128 v247, v[128:131] offset:3072
	ds_read_b128 v[116:119], v248
	ds_read_b128 v[120:123], v249
	ds_read_b128 v[124:127], v250
	ds_read_b128 v[128:131], v251
	ds_write_b128 v112, v[132:135]
	ds_write_b128 v112, v[136:139] offset:1024
	ds_write_b128 v112, v[140:143] offset:2048
	ds_write_b128 v112, v[144:147] offset:3072
	v_exp_f32_e32 v192, v192
	v_exp_f32_e32 v193, v193
	v_exp_f32_e32 v194, v194
	v_exp_f32_e32 v195, v195
	s_waitcnt lgkmcnt(4)
	v_mfma_f32_32x32x16_bf16 v[32:47], v[116:119], v[48:51], v[32:47]
	v_exp_f32_e32 v196, v196
	v_exp_f32_e32 v197, v197
	v_mfma_f32_32x32x16_bf16 v[32:47], v[120:123], v[52:55], v[32:47]
	v_exp_f32_e32 v198, v198
	v_exp_f32_e32 v199, v199
	v_mfma_f32_32x32x16_bf16 v[32:47], v[124:127], v[56:59], v[32:47]
	v_exp_f32_e32 v200, v200
	v_exp_f32_e32 v201, v201
	v_mfma_f32_32x32x16_bf16 v[32:47], v[128:131], v[60:63], v[32:47]
	v_exp_f32_e32 v202, v202
	v_exp_f32_e32 v203, v203
	s_add_i32 s90, s67, 160
	v_add_u32_e32 v84, s90, v107
	v_add_u32_e32 v85, 0, v84
	v_add_u32_e32 v86, 1, v84
	v_add_u32_e32 v87, 2, v84
	v_add_u32_e32 v88, 3, v84
	v_cmp_gt_u32_e64 s[30:31], s98, v85
	v_cmp_gt_u32_e64 s[36:37], s98, v86
	v_cmp_gt_u32_e64 s[78:79], s98, v87
	v_cmp_gt_u32_e64 s[50:51], s98, v88
	v_cndmask_b32_e64 v188, 0, v188, s[30:31]
	v_add_u32_e32 v85, 8, v84
	v_cmp_gt_u32_e64 s[30:31], s98, v85
	v_cndmask_b32_e64 v189, 0, v189, s[36:37]
	v_add_u32_e32 v86, 9, v84
	v_cmp_gt_u32_e64 s[36:37], s98, v86
	v_cndmask_b32_e64 v190, 0, v190, s[78:79]
	v_add_u32_e32 v87, 10, v84
	v_cmp_gt_u32_e64 s[78:79], s98, v87
	v_cndmask_b32_e64 v191, 0, v191, s[50:51]
	v_add_u32_e32 v88, 11, v84
	v_cmp_gt_u32_e64 s[50:51], s98, v88
	v_cndmask_b32_e64 v192, 0, v192, s[30:31]
	v_add_u32_e32 v85, 16, v84
	v_cmp_gt_u32_e64 s[30:31], s98, v85
	v_cndmask_b32_e64 v193, 0, v193, s[36:37]
	v_add_u32_e32 v86, 17, v84
	v_cmp_gt_u32_e64 s[36:37], s98, v86
	v_cndmask_b32_e64 v194, 0, v194, s[78:79]
	v_add_u32_e32 v87, 18, v84
	v_cmp_gt_u32_e64 s[78:79], s98, v87
	v_cndmask_b32_e64 v195, 0, v195, s[50:51]
	v_add_u32_e32 v88, 19, v84
	v_cmp_gt_u32_e64 s[50:51], s98, v88
	v_cndmask_b32_e64 v196, 0, v196, s[30:31]
	v_add_u32_e32 v85, 24, v84
	v_cmp_gt_u32_e64 s[30:31], s98, v85
	v_cndmask_b32_e64 v197, 0, v197, s[36:37]
	v_add_u32_e32 v86, 25, v84
	v_cmp_gt_u32_e64 s[36:37], s98, v86
	v_cndmask_b32_e64 v198, 0, v198, s[78:79]
	v_add_u32_e32 v87, 26, v84
	v_cmp_gt_u32_e64 s[78:79], s98, v87
	v_cndmask_b32_e64 v199, 0, v199, s[50:51]
	v_add_u32_e32 v88, 27, v84
	v_cmp_gt_u32_e64 s[50:51], s98, v88
	v_nop
	v_cndmask_b32_e64 v200, 0, v200, s[30:31]
	v_cndmask_b32_e64 v201, 0, v201, s[36:37]
	v_cndmask_b32_e64 v202, 0, v202, s[78:79]
	v_cndmask_b32_e64 v203, 0, v203, s[50:51]
	v_cvt_pk_bf16_f32 v64, v188, v189
	v_cvt_pk_bf16_f32 v65, v190, v191
	v_cvt_pk_bf16_f32 v66, v192, v193
	v_cvt_pk_bf16_f32 v67, v194, v195
	v_cvt_pk_bf16_f32 v68, v196, v197
	v_cvt_pk_bf16_f32 v69, v198, v199
	v_cvt_pk_bf16_f32 v70, v200, v201
	v_cvt_pk_bf16_f32 v71, v202, v203
	v_pk_add_f32 v[232:233], v[232:233], v[188:189]
	v_pk_add_f32 v[232:233], v[232:233], v[190:191]
	v_pk_add_f32 v[232:233], v[232:233], v[192:193]
	v_pk_add_f32 v[232:233], v[232:233], v[194:195]
	v_pk_add_f32 v[232:233], v[232:233], v[196:197]
	v_pk_add_f32 v[232:233], v[232:233], v[198:199]
	v_pk_add_f32 v[232:233], v[232:233], v[200:201]
	v_pk_add_f32 v[232:233], v[232:233], v[202:203]
	ds_read2_b32 v[188:189], v115 offset0:68 offset1:69
	ds_read2_b32 v[190:191], v115 offset0:70 offset1:71
	ds_read2_b32 v[192:193], v115 offset0:76 offset1:77
	ds_read2_b32 v[194:195], v115 offset0:78 offset1:79
	ds_read2_b32 v[196:197], v115 offset0:85 offset1:86
	ds_read2_b32 v[198:199], v115 offset0:87 offset1:88
	ds_read2_b32 v[200:201], v115 offset0:93 offset1:94
	ds_read2_b32 v[202:203], v115 offset0:95 offset1:96
	v_mfma_f32_32x32x16_bf16 v[0:15], v[64:67], v[72:75], v[0:15]
	v_mfma_f32_32x32x16_bf16 v[16:31], v[64:67], v[76:79], v[16:31]
	v_mfma_f32_32x32x16_bf16 v[0:15], v[68:71], v[220:223], v[0:15]
	v_mfma_f32_32x32x16_bf16 v[16:31], v[68:71], v[224:227], v[16:31]
	s_add_i32 s90, s67, 256
	v_add_u32_e32 v80, s90, v235
	v_add_u32_e32 v83, s90, v236
	v_add_u32_e32 v99, s90, v237
	v_add_u32_e32 v253, s90, v238
	v_add_u32_e32 v254, s90, v100
	v_add_u32_e32 v255, s90, v149
	v_med3_i32 v80, v80, 0, s99
	v_med3_i32 v83, v83, 0, s99
	v_med3_i32 v99, v99, 0, s99
	v_med3_i32 v253, v253, 0, s99
	v_med3_i32 v254, v254, 0, s99
	v_med3_i32 v255, v255, 0, s99
	v_mad_u32_u24 v80, v80, s100, v252
	v_mad_u32_u24 v83, v83, s100, v252
	v_mad_u32_u24 v99, v99, s100, v252
	v_mad_u32_u24 v253, v253, s100, v252
	v_mad_u32_u24 v254, v254, s100, v153
	v_mad_u32_u24 v255, v255, s100, v153
	global_load_dwordx4 v[116:119], v80, s[82:83]
	global_load_dwordx4 v[120:123], v83, s[82:83]
	global_load_dwordx4 v[124:127], v99, s[82:83]
	global_load_dwordx4 v[128:131], v253, s[82:83]
	global_load_dwordx4 v[132:135], v254, s[82:83] offset:768
	global_load_dwordx4 v[136:139], v255, s[82:83] offset:768
	global_load_dwordx4 v[140:143], v254, s[82:83] offset:832
	global_load_dwordx4 v[144:147], v255, s[82:83] offset:832
	ds_read_b64_tr_b16 v[72:73], v231
	ds_read_b64_tr_b16 v[74:75], v231 offset:512
	ds_read_b64_tr_b16 v[76:77], v231 offset:2048
	ds_read_b64_tr_b16 v[78:79], v231 offset:2560
	ds_read_b64_tr_b16 v[220:221], v231 offset:1024
	ds_read_b64_tr_b16 v[222:223], v231 offset:1536
	ds_read_b64_tr_b16 v[224:225], v231 offset:3072
	ds_read_b64_tr_b16 v[226:227], v231 offset:3584
	v_exp_f32_e32 v32, v32
	v_exp_f32_e32 v33, v33
	v_exp_f32_e32 v34, v34
	v_exp_f32_e32 v35, v35
	s_waitcnt vmcnt(8)
	ds_write_b128 v247, v[156:159]
	ds_write_b128 v247, v[160:163] offset:1024
	ds_write_b128 v247, v[164:167] offset:2048
	ds_write_b128 v247, v[168:171] offset:3072
	ds_read_b128 v[156:159], v248
	ds_read_b128 v[160:163], v249
	ds_read_b128 v[164:167], v250
	ds_read_b128 v[168:171], v251
	ds_write_b128 v112, v[172:175]
	ds_write_b128 v112, v[176:179] offset:1024
	ds_write_b128 v112, v[180:183] offset:2048
	ds_write_b128 v112, v[184:187] offset:3072
	v_exp_f32_e32 v36, v36
	v_exp_f32_e32 v37, v37
	v_exp_f32_e32 v38, v38
	v_exp_f32_e32 v39, v39
	s_waitcnt lgkmcnt(4)
	v_mfma_f32_32x32x16_bf16 v[188:203], v[156:159], v[48:51], v[188:203]
	v_exp_f32_e32 v40, v40
	v_exp_f32_e32 v41, v41
	v_mfma_f32_32x32x16_bf16 v[188:203], v[160:163], v[52:55], v[188:203]
	v_exp_f32_e32 v42, v42
	v_exp_f32_e32 v43, v43
	v_mfma_f32_32x32x16_bf16 v[188:203], v[164:167], v[56:59], v[188:203]
	v_exp_f32_e32 v44, v44
	v_exp_f32_e32 v45, v45
	v_mfma_f32_32x32x16_bf16 v[188:203], v[168:171], v[60:63], v[188:203]
	v_exp_f32_e32 v46, v46
	v_exp_f32_e32 v47, v47
	s_add_i32 s90, s67, 192
	v_add_u32_e32 v84, s90, v107
	v_add_u32_e32 v85, 0, v84
	v_add_u32_e32 v86, 1, v84
	v_add_u32_e32 v87, 2, v84
	v_add_u32_e32 v88, 3, v84
	v_cmp_gt_u32_e64 s[30:31], s98, v85
	v_cmp_gt_u32_e64 s[36:37], s98, v86
	v_cmp_gt_u32_e64 s[78:79], s98, v87
	v_cmp_gt_u32_e64 s[50:51], s98, v88
	v_cndmask_b32_e64 v32, 0, v32, s[30:31]
	v_add_u32_e32 v85, 8, v84
	v_cmp_gt_u32_e64 s[30:31], s98, v85
	v_cndmask_b32_e64 v33, 0, v33, s[36:37]
	v_add_u32_e32 v86, 9, v84
	v_cmp_gt_u32_e64 s[36:37], s98, v86
	v_cndmask_b32_e64 v34, 0, v34, s[78:79]
	v_add_u32_e32 v87, 10, v84
	v_cmp_gt_u32_e64 s[78:79], s98, v87
	v_cndmask_b32_e64 v35, 0, v35, s[50:51]
	v_add_u32_e32 v88, 11, v84
	v_cmp_gt_u32_e64 s[50:51], s98, v88
	v_cndmask_b32_e64 v36, 0, v36, s[30:31]
	v_add_u32_e32 v85, 16, v84
	v_cmp_gt_u32_e64 s[30:31], s98, v85
	v_cndmask_b32_e64 v37, 0, v37, s[36:37]
	v_add_u32_e32 v86, 17, v84
	v_cmp_gt_u32_e64 s[36:37], s98, v86
	v_cndmask_b32_e64 v38, 0, v38, s[78:79]
	v_add_u32_e32 v87, 18, v84
	v_cmp_gt_u32_e64 s[78:79], s98, v87
	v_cndmask_b32_e64 v39, 0, v39, s[50:51]
	v_add_u32_e32 v88, 19, v84
	v_cmp_gt_u32_e64 s[50:51], s98, v88
	v_cndmask_b32_e64 v40, 0, v40, s[30:31]
	v_add_u32_e32 v85, 24, v84
	v_cmp_gt_u32_e64 s[30:31], s98, v85
	v_cndmask_b32_e64 v41, 0, v41, s[36:37]
	v_add_u32_e32 v86, 25, v84
	v_cmp_gt_u32_e64 s[36:37], s98, v86
	v_cndmask_b32_e64 v42, 0, v42, s[78:79]
	v_add_u32_e32 v87, 26, v84
	v_cmp_gt_u32_e64 s[78:79], s98, v87
	v_cndmask_b32_e64 v43, 0, v43, s[50:51]
	v_add_u32_e32 v88, 27, v84
	v_cmp_gt_u32_e64 s[50:51], s98, v88
	v_nop
	v_cndmask_b32_e64 v44, 0, v44, s[30:31]
	v_cndmask_b32_e64 v45, 0, v45, s[36:37]
	v_cndmask_b32_e64 v46, 0, v46, s[78:79]
	v_cndmask_b32_e64 v47, 0, v47, s[50:51]
	v_cvt_pk_bf16_f32 v64, v32, v33
	v_cvt_pk_bf16_f32 v65, v34, v35
	v_cvt_pk_bf16_f32 v66, v36, v37
	v_cvt_pk_bf16_f32 v67, v38, v39
	v_cvt_pk_bf16_f32 v68, v40, v41
	v_cvt_pk_bf16_f32 v69, v42, v43
	v_cvt_pk_bf16_f32 v70, v44, v45
	v_cvt_pk_bf16_f32 v71, v46, v47
	v_pk_add_f32 v[232:233], v[232:233], v[32:33]
	v_pk_add_f32 v[232:233], v[232:233], v[34:35]
	v_pk_add_f32 v[232:233], v[232:233], v[36:37]
	v_pk_add_f32 v[232:233], v[232:233], v[38:39]
	v_pk_add_f32 v[232:233], v[232:233], v[40:41]
	v_pk_add_f32 v[232:233], v[232:233], v[42:43]
	v_pk_add_f32 v[232:233], v[232:233], v[44:45]
	v_pk_add_f32 v[232:233], v[232:233], v[46:47]
	ds_read2_b32 v[32:33], v115 offset0:102 offset1:103
	ds_read2_b32 v[34:35], v115 offset0:104 offset1:105
	ds_read2_b32 v[36:37], v115 offset0:110 offset1:111
	ds_read2_b32 v[38:39], v115 offset0:112 offset1:113
	ds_read2_b32 v[40:41], v115 offset0:119 offset1:120
	ds_read2_b32 v[42:43], v115 offset0:121 offset1:122
	ds_read2_b32 v[44:45], v115 offset0:127 offset1:128
	ds_read2_b32 v[46:47], v115 offset0:129 offset1:130
	v_mfma_f32_32x32x16_bf16 v[0:15], v[64:67], v[72:75], v[0:15]
	v_mfma_f32_32x32x16_bf16 v[16:31], v[64:67], v[76:79], v[16:31]
	v_mfma_f32_32x32x16_bf16 v[0:15], v[68:71], v[220:223], v[0:15]
	v_mfma_f32_32x32x16_bf16 v[16:31], v[68:71], v[224:227], v[16:31]
	s_add_i32 s90, s67, 288
	v_add_u32_e32 v80, s90, v235
	v_add_u32_e32 v83, s90, v236
	v_add_u32_e32 v99, s90, v237
	v_add_u32_e32 v253, s90, v238
	v_add_u32_e32 v254, s90, v100
	v_add_u32_e32 v255, s90, v149
	v_med3_i32 v80, v80, 0, s99
	v_med3_i32 v83, v83, 0, s99
	v_med3_i32 v99, v99, 0, s99
	v_med3_i32 v253, v253, 0, s99
	v_med3_i32 v254, v254, 0, s99
	v_med3_i32 v255, v255, 0, s99
	v_mad_u32_u24 v80, v80, s100, v252
	v_mad_u32_u24 v83, v83, s100, v252
	v_mad_u32_u24 v99, v99, s100, v252
	v_mad_u32_u24 v253, v253, s100, v252
	v_mad_u32_u24 v254, v254, s100, v153
	v_mad_u32_u24 v255, v255, s100, v153
	global_load_dwordx4 v[156:159], v80, s[82:83]
	global_load_dwordx4 v[160:163], v83, s[82:83]
	global_load_dwordx4 v[164:167], v99, s[82:83]
	global_load_dwordx4 v[168:171], v253, s[82:83]
	global_load_dwordx4 v[172:175], v254, s[82:83] offset:768
	global_load_dwordx4 v[176:179], v255, s[82:83] offset:768
	global_load_dwordx4 v[180:183], v254, s[82:83] offset:832
	global_load_dwordx4 v[184:187], v255, s[82:83] offset:832
	ds_read_b64_tr_b16 v[72:73], v231
	ds_read_b64_tr_b16 v[74:75], v231 offset:512
	ds_read_b64_tr_b16 v[76:77], v231 offset:2048
	ds_read_b64_tr_b16 v[78:79], v231 offset:2560
	ds_read_b64_tr_b16 v[220:221], v231 offset:1024
	ds_read_b64_tr_b16 v[222:223], v231 offset:1536
	ds_read_b64_tr_b16 v[224:225], v231 offset:3072
	ds_read_b64_tr_b16 v[226:227], v231 offset:3584
	v_exp_f32_e32 v188, v188
	v_exp_f32_e32 v189, v189
	v_exp_f32_e32 v190, v190
	v_exp_f32_e32 v191, v191
	s_waitcnt vmcnt(8)
	ds_write_b128 v247, v[116:119]
	ds_write_b128 v247, v[120:123] offset:1024
	ds_write_b128 v247, v[124:127] offset:2048
	ds_write_b128 v247, v[128:131] offset:3072
	ds_read_b128 v[116:119], v248
	ds_read_b128 v[120:123], v249
	ds_read_b128 v[124:127], v250
	ds_read_b128 v[128:131], v251
	ds_write_b128 v112, v[132:135]
	ds_write_b128 v112, v[136:139] offset:1024
	ds_write_b128 v112, v[140:143] offset:2048
	ds_write_b128 v112, v[144:147] offset:3072
	v_exp_f32_e32 v192, v192
	v_exp_f32_e32 v193, v193
	v_exp_f32_e32 v194, v194
	v_exp_f32_e32 v195, v195
	s_waitcnt lgkmcnt(4)
	v_mfma_f32_32x32x16_bf16 v[32:47], v[116:119], v[48:51], v[32:47]
	v_exp_f32_e32 v196, v196
	v_exp_f32_e32 v197, v197
	v_mfma_f32_32x32x16_bf16 v[32:47], v[120:123], v[52:55], v[32:47]
	v_exp_f32_e32 v198, v198
	v_exp_f32_e32 v199, v199
	v_mfma_f32_32x32x16_bf16 v[32:47], v[124:127], v[56:59], v[32:47]
	v_exp_f32_e32 v200, v200
	v_exp_f32_e32 v201, v201
	v_mfma_f32_32x32x16_bf16 v[32:47], v[128:131], v[60:63], v[32:47]
	v_exp_f32_e32 v202, v202
	v_exp_f32_e32 v203, v203
	s_add_i32 s90, s67, 224
	v_add_u32_e32 v84, s90, v107
	v_add_u32_e32 v85, 0, v84
	v_add_u32_e32 v86, 1, v84
	v_add_u32_e32 v87, 2, v84
	v_add_u32_e32 v88, 3, v84
	v_cmp_gt_u32_e64 s[30:31], s98, v85
	v_cmp_gt_u32_e64 s[36:37], s98, v86
	v_cmp_gt_u32_e64 s[78:79], s98, v87
	v_cmp_gt_u32_e64 s[50:51], s98, v88
	v_cndmask_b32_e64 v188, 0, v188, s[30:31]
	v_add_u32_e32 v85, 8, v84
	v_cmp_gt_u32_e64 s[30:31], s98, v85
	v_cndmask_b32_e64 v189, 0, v189, s[36:37]
	v_add_u32_e32 v86, 9, v84
	v_cmp_gt_u32_e64 s[36:37], s98, v86
	v_cndmask_b32_e64 v190, 0, v190, s[78:79]
	v_add_u32_e32 v87, 10, v84
	v_cmp_gt_u32_e64 s[78:79], s98, v87
	v_cndmask_b32_e64 v191, 0, v191, s[50:51]
	v_add_u32_e32 v88, 11, v84
	v_cmp_gt_u32_e64 s[50:51], s98, v88
	v_cndmask_b32_e64 v192, 0, v192, s[30:31]
	v_add_u32_e32 v85, 16, v84
	v_cmp_gt_u32_e64 s[30:31], s98, v85
	v_cndmask_b32_e64 v193, 0, v193, s[36:37]
	v_add_u32_e32 v86, 17, v84
	v_cmp_gt_u32_e64 s[36:37], s98, v86
	v_cndmask_b32_e64 v194, 0, v194, s[78:79]
	v_add_u32_e32 v87, 18, v84
	v_cmp_gt_u32_e64 s[78:79], s98, v87
	v_cndmask_b32_e64 v195, 0, v195, s[50:51]
	v_add_u32_e32 v88, 19, v84
	v_cmp_gt_u32_e64 s[50:51], s98, v88
	v_cndmask_b32_e64 v196, 0, v196, s[30:31]
	v_add_u32_e32 v85, 24, v84
	v_cmp_gt_u32_e64 s[30:31], s98, v85
	v_cndmask_b32_e64 v197, 0, v197, s[36:37]
	v_add_u32_e32 v86, 25, v84
	v_cmp_gt_u32_e64 s[36:37], s98, v86
	v_cndmask_b32_e64 v198, 0, v198, s[78:79]
	v_add_u32_e32 v87, 26, v84
	v_cmp_gt_u32_e64 s[78:79], s98, v87
	v_cndmask_b32_e64 v199, 0, v199, s[50:51]
	v_add_u32_e32 v88, 27, v84
	v_cmp_gt_u32_e64 s[50:51], s98, v88
	v_nop
	v_cndmask_b32_e64 v200, 0, v200, s[30:31]
	v_cndmask_b32_e64 v201, 0, v201, s[36:37]
	v_cndmask_b32_e64 v202, 0, v202, s[78:79]
	v_cndmask_b32_e64 v203, 0, v203, s[50:51]
	v_cvt_pk_bf16_f32 v64, v188, v189
	v_cvt_pk_bf16_f32 v65, v190, v191
	v_cvt_pk_bf16_f32 v66, v192, v193
	v_cvt_pk_bf16_f32 v67, v194, v195
	v_cvt_pk_bf16_f32 v68, v196, v197
	v_cvt_pk_bf16_f32 v69, v198, v199
	v_cvt_pk_bf16_f32 v70, v200, v201
	v_cvt_pk_bf16_f32 v71, v202, v203
	v_pk_add_f32 v[232:233], v[232:233], v[188:189]
	v_pk_add_f32 v[232:233], v[232:233], v[190:191]
	v_pk_add_f32 v[232:233], v[232:233], v[192:193]
	v_pk_add_f32 v[232:233], v[232:233], v[194:195]
	v_pk_add_f32 v[232:233], v[232:233], v[196:197]
	v_pk_add_f32 v[232:233], v[232:233], v[198:199]
	v_pk_add_f32 v[232:233], v[232:233], v[200:201]
	v_pk_add_f32 v[232:233], v[232:233], v[202:203]
	ds_read2_b32 v[188:189], v115 offset0:136 offset1:137
	ds_read2_b32 v[190:191], v115 offset0:138 offset1:139
	ds_read2_b32 v[192:193], v115 offset0:144 offset1:145
	ds_read2_b32 v[194:195], v115 offset0:146 offset1:147
	ds_read2_b32 v[196:197], v115 offset0:153 offset1:154
	ds_read2_b32 v[198:199], v115 offset0:155 offset1:156
	ds_read2_b32 v[200:201], v115 offset0:161 offset1:162
	ds_read2_b32 v[202:203], v115 offset0:163 offset1:164
	v_mfma_f32_32x32x16_bf16 v[0:15], v[64:67], v[72:75], v[0:15]
	v_mfma_f32_32x32x16_bf16 v[16:31], v[64:67], v[76:79], v[16:31]
	v_mfma_f32_32x32x16_bf16 v[0:15], v[68:71], v[220:223], v[0:15]
	v_mfma_f32_32x32x16_bf16 v[16:31], v[68:71], v[224:227], v[16:31]
	s_add_i32 s90, s67, 320
	v_add_u32_e32 v80, s90, v235
	v_add_u32_e32 v83, s90, v236
	v_add_u32_e32 v99, s90, v237
	v_add_u32_e32 v253, s90, v238
	v_add_u32_e32 v254, s90, v100
	v_add_u32_e32 v255, s90, v149
	v_med3_i32 v80, v80, 0, s99
	v_med3_i32 v83, v83, 0, s99
	v_med3_i32 v99, v99, 0, s99
	v_med3_i32 v253, v253, 0, s99
	v_med3_i32 v254, v254, 0, s99
	v_med3_i32 v255, v255, 0, s99
	v_mad_u32_u24 v80, v80, s100, v252
	v_mad_u32_u24 v83, v83, s100, v252
	v_mad_u32_u24 v99, v99, s100, v252
	v_mad_u32_u24 v253, v253, s100, v252
	v_mad_u32_u24 v254, v254, s100, v153
	v_mad_u32_u24 v255, v255, s100, v153
	global_load_dwordx4 v[116:119], v80, s[82:83]
	global_load_dwordx4 v[120:123], v83, s[82:83]
	global_load_dwordx4 v[124:127], v99, s[82:83]
	global_load_dwordx4 v[128:131], v253, s[82:83]
	global_load_dwordx4 v[132:135], v254, s[82:83] offset:768
	global_load_dwordx4 v[136:139], v255, s[82:83] offset:768
	global_load_dwordx4 v[140:143], v254, s[82:83] offset:832
	global_load_dwordx4 v[144:147], v255, s[82:83] offset:832
	ds_read_b64_tr_b16 v[72:73], v231
	ds_read_b64_tr_b16 v[74:75], v231 offset:512
	ds_read_b64_tr_b16 v[76:77], v231 offset:2048
	ds_read_b64_tr_b16 v[78:79], v231 offset:2560
	ds_read_b64_tr_b16 v[220:221], v231 offset:1024
	ds_read_b64_tr_b16 v[222:223], v231 offset:1536
	ds_read_b64_tr_b16 v[224:225], v231 offset:3072
	ds_read_b64_tr_b16 v[226:227], v231 offset:3584
	v_exp_f32_e32 v32, v32
	v_exp_f32_e32 v33, v33
	v_exp_f32_e32 v34, v34
	v_exp_f32_e32 v35, v35
	s_waitcnt vmcnt(8)
	ds_write_b128 v247, v[156:159]
	ds_write_b128 v247, v[160:163] offset:1024
	ds_write_b128 v247, v[164:167] offset:2048
	ds_write_b128 v247, v[168:171] offset:3072
	ds_read_b128 v[156:159], v248
	ds_read_b128 v[160:163], v249
	ds_read_b128 v[164:167], v250
	ds_read_b128 v[168:171], v251
	ds_write_b128 v112, v[172:175]
	ds_write_b128 v112, v[176:179] offset:1024
	ds_write_b128 v112, v[180:183] offset:2048
	ds_write_b128 v112, v[184:187] offset:3072
	v_exp_f32_e32 v36, v36
	v_exp_f32_e32 v37, v37
	v_exp_f32_e32 v38, v38
	v_exp_f32_e32 v39, v39
	s_waitcnt lgkmcnt(4)
	v_mfma_f32_32x32x16_bf16 v[188:203], v[156:159], v[48:51], v[188:203]
	v_exp_f32_e32 v40, v40
	v_exp_f32_e32 v41, v41
	v_mfma_f32_32x32x16_bf16 v[188:203], v[160:163], v[52:55], v[188:203]
	v_exp_f32_e32 v42, v42
	v_exp_f32_e32 v43, v43
	v_mfma_f32_32x32x16_bf16 v[188:203], v[164:167], v[56:59], v[188:203]
	v_exp_f32_e32 v44, v44
	v_exp_f32_e32 v45, v45
	v_mfma_f32_32x32x16_bf16 v[188:203], v[168:171], v[60:63], v[188:203]
	v_exp_f32_e32 v46, v46
	v_exp_f32_e32 v47, v47
	s_add_i32 s90, s67, 256
	v_add_u32_e32 v84, s90, v107
	v_add_u32_e32 v85, 0, v84
	v_add_u32_e32 v86, 1, v84
	v_add_u32_e32 v87, 2, v84
	v_add_u32_e32 v88, 3, v84
	v_cmp_gt_u32_e64 s[30:31], s98, v85
	v_cmp_gt_u32_e64 s[36:37], s98, v86
	v_cmp_gt_u32_e64 s[78:79], s98, v87
	v_cmp_gt_u32_e64 s[50:51], s98, v88
	v_cndmask_b32_e64 v32, 0, v32, s[30:31]
	v_add_u32_e32 v85, 8, v84
	v_cmp_gt_u32_e64 s[30:31], s98, v85
	v_cndmask_b32_e64 v33, 0, v33, s[36:37]
	v_add_u32_e32 v86, 9, v84
	v_cmp_gt_u32_e64 s[36:37], s98, v86
	v_cndmask_b32_e64 v34, 0, v34, s[78:79]
	v_add_u32_e32 v87, 10, v84
	v_cmp_gt_u32_e64 s[78:79], s98, v87
	v_cndmask_b32_e64 v35, 0, v35, s[50:51]
	v_add_u32_e32 v88, 11, v84
	v_cmp_gt_u32_e64 s[50:51], s98, v88
	v_cndmask_b32_e64 v36, 0, v36, s[30:31]
	v_add_u32_e32 v85, 16, v84
	v_cmp_gt_u32_e64 s[30:31], s98, v85
	v_cndmask_b32_e64 v37, 0, v37, s[36:37]
	v_add_u32_e32 v86, 17, v84
	v_cmp_gt_u32_e64 s[36:37], s98, v86
	v_cndmask_b32_e64 v38, 0, v38, s[78:79]
	v_add_u32_e32 v87, 18, v84
	v_cmp_gt_u32_e64 s[78:79], s98, v87
	v_cndmask_b32_e64 v39, 0, v39, s[50:51]
	v_add_u32_e32 v88, 19, v84
	v_cmp_gt_u32_e64 s[50:51], s98, v88
	v_cndmask_b32_e64 v40, 0, v40, s[30:31]
	v_add_u32_e32 v85, 24, v84
	v_cmp_gt_u32_e64 s[30:31], s98, v85
	v_cndmask_b32_e64 v41, 0, v41, s[36:37]
	v_add_u32_e32 v86, 25, v84
	v_cmp_gt_u32_e64 s[36:37], s98, v86
	v_cndmask_b32_e64 v42, 0, v42, s[78:79]
	v_add_u32_e32 v87, 26, v84
	v_cmp_gt_u32_e64 s[78:79], s98, v87
	v_cndmask_b32_e64 v43, 0, v43, s[50:51]
	v_add_u32_e32 v88, 27, v84
	v_cmp_gt_u32_e64 s[50:51], s98, v88
	v_nop
	v_cndmask_b32_e64 v44, 0, v44, s[30:31]
	v_cndmask_b32_e64 v45, 0, v45, s[36:37]
	v_cndmask_b32_e64 v46, 0, v46, s[78:79]
	v_cndmask_b32_e64 v47, 0, v47, s[50:51]
	v_cvt_pk_bf16_f32 v64, v32, v33
	v_cvt_pk_bf16_f32 v65, v34, v35
	v_cvt_pk_bf16_f32 v66, v36, v37
	v_cvt_pk_bf16_f32 v67, v38, v39
	v_cvt_pk_bf16_f32 v68, v40, v41
	v_cvt_pk_bf16_f32 v69, v42, v43
	v_cvt_pk_bf16_f32 v70, v44, v45
	v_cvt_pk_bf16_f32 v71, v46, v47
	v_pk_add_f32 v[232:233], v[232:233], v[32:33]
	v_pk_add_f32 v[232:233], v[232:233], v[34:35]
	v_pk_add_f32 v[232:233], v[232:233], v[36:37]
	v_pk_add_f32 v[232:233], v[232:233], v[38:39]
	v_pk_add_f32 v[232:233], v[232:233], v[40:41]
	v_pk_add_f32 v[232:233], v[232:233], v[42:43]
	v_pk_add_f32 v[232:233], v[232:233], v[44:45]
	v_pk_add_f32 v[232:233], v[232:233], v[46:47]
	ds_read2_b32 v[32:33], v115 offset0:170 offset1:171
	ds_read2_b32 v[34:35], v115 offset0:172 offset1:173
	ds_read2_b32 v[36:37], v115 offset0:178 offset1:179
	ds_read2_b32 v[38:39], v115 offset0:180 offset1:181
	ds_read2_b32 v[40:41], v115 offset0:187 offset1:188
	ds_read2_b32 v[42:43], v115 offset0:189 offset1:190
	ds_read2_b32 v[44:45], v115 offset0:195 offset1:196
	ds_read2_b32 v[46:47], v115 offset0:197 offset1:198
	v_mfma_f32_32x32x16_bf16 v[0:15], v[64:67], v[72:75], v[0:15]
	v_mfma_f32_32x32x16_bf16 v[16:31], v[64:67], v[76:79], v[16:31]
	v_mfma_f32_32x32x16_bf16 v[0:15], v[68:71], v[220:223], v[0:15]
	v_mfma_f32_32x32x16_bf16 v[16:31], v[68:71], v[224:227], v[16:31]
	s_add_i32 s90, s67, 352
	v_add_u32_e32 v80, s90, v235
	v_add_u32_e32 v83, s90, v236
	v_add_u32_e32 v99, s90, v237
	v_add_u32_e32 v253, s90, v238
	v_add_u32_e32 v254, s90, v100
	v_add_u32_e32 v255, s90, v149
	v_med3_i32 v80, v80, 0, s99
	v_med3_i32 v83, v83, 0, s99
	v_med3_i32 v99, v99, 0, s99
	v_med3_i32 v253, v253, 0, s99
	v_med3_i32 v254, v254, 0, s99
	v_med3_i32 v255, v255, 0, s99
	v_mad_u32_u24 v80, v80, s100, v252
	v_mad_u32_u24 v83, v83, s100, v252
	v_mad_u32_u24 v99, v99, s100, v252
	v_mad_u32_u24 v253, v253, s100, v252
	v_mad_u32_u24 v254, v254, s100, v153
	v_mad_u32_u24 v255, v255, s100, v153
	global_load_dwordx4 v[156:159], v80, s[82:83]
	global_load_dwordx4 v[160:163], v83, s[82:83]
	global_load_dwordx4 v[164:167], v99, s[82:83]
	global_load_dwordx4 v[168:171], v253, s[82:83]
	global_load_dwordx4 v[172:175], v254, s[82:83] offset:768
	global_load_dwordx4 v[176:179], v255, s[82:83] offset:768
	global_load_dwordx4 v[180:183], v254, s[82:83] offset:832
	global_load_dwordx4 v[184:187], v255, s[82:83] offset:832
	ds_read_b64_tr_b16 v[72:73], v231
	ds_read_b64_tr_b16 v[74:75], v231 offset:512
	ds_read_b64_tr_b16 v[76:77], v231 offset:2048
	ds_read_b64_tr_b16 v[78:79], v231 offset:2560
	ds_read_b64_tr_b16 v[220:221], v231 offset:1024
	ds_read_b64_tr_b16 v[222:223], v231 offset:1536
	ds_read_b64_tr_b16 v[224:225], v231 offset:3072
	ds_read_b64_tr_b16 v[226:227], v231 offset:3584
	v_exp_f32_e32 v188, v188
	v_exp_f32_e32 v189, v189
	v_exp_f32_e32 v190, v190
	v_exp_f32_e32 v191, v191
	s_waitcnt vmcnt(8)
	ds_write_b128 v247, v[116:119]
	ds_write_b128 v247, v[120:123] offset:1024
	ds_write_b128 v247, v[124:127] offset:2048
	ds_write_b128 v247, v[128:131] offset:3072
	ds_read_b128 v[116:119], v248
	ds_read_b128 v[120:123], v249
	ds_read_b128 v[124:127], v250
	ds_read_b128 v[128:131], v251
	ds_write_b128 v112, v[132:135]
	ds_write_b128 v112, v[136:139] offset:1024
	ds_write_b128 v112, v[140:143] offset:2048
	ds_write_b128 v112, v[144:147] offset:3072
	v_exp_f32_e32 v192, v192
	v_exp_f32_e32 v193, v193
	v_exp_f32_e32 v194, v194
	v_exp_f32_e32 v195, v195
	s_waitcnt lgkmcnt(4)
	v_mfma_f32_32x32x16_bf16 v[32:47], v[116:119], v[48:51], v[32:47]
	v_exp_f32_e32 v196, v196
	v_exp_f32_e32 v197, v197
	v_mfma_f32_32x32x16_bf16 v[32:47], v[120:123], v[52:55], v[32:47]
	v_exp_f32_e32 v198, v198
	v_exp_f32_e32 v199, v199
	v_mfma_f32_32x32x16_bf16 v[32:47], v[124:127], v[56:59], v[32:47]
	v_exp_f32_e32 v200, v200
	v_exp_f32_e32 v201, v201
	v_mfma_f32_32x32x16_bf16 v[32:47], v[128:131], v[60:63], v[32:47]
	v_exp_f32_e32 v202, v202
	v_exp_f32_e32 v203, v203
	s_add_i32 s90, s67, 288
	v_add_u32_e32 v84, s90, v107
	v_add_u32_e32 v85, 0, v84
	v_add_u32_e32 v86, 1, v84
	v_add_u32_e32 v87, 2, v84
	v_add_u32_e32 v88, 3, v84
	v_cmp_gt_u32_e64 s[30:31], s98, v85
	v_cmp_gt_u32_e64 s[36:37], s98, v86
	v_cmp_gt_u32_e64 s[78:79], s98, v87
	v_cmp_gt_u32_e64 s[50:51], s98, v88
	v_cndmask_b32_e64 v188, 0, v188, s[30:31]
	v_add_u32_e32 v85, 8, v84
	v_cmp_gt_u32_e64 s[30:31], s98, v85
	v_cndmask_b32_e64 v189, 0, v189, s[36:37]
	v_add_u32_e32 v86, 9, v84
	v_cmp_gt_u32_e64 s[36:37], s98, v86
	v_cndmask_b32_e64 v190, 0, v190, s[78:79]
	v_add_u32_e32 v87, 10, v84
	v_cmp_gt_u32_e64 s[78:79], s98, v87
	v_cndmask_b32_e64 v191, 0, v191, s[50:51]
	v_add_u32_e32 v88, 11, v84
	v_cmp_gt_u32_e64 s[50:51], s98, v88
	v_cndmask_b32_e64 v192, 0, v192, s[30:31]
	v_add_u32_e32 v85, 16, v84
	v_cmp_gt_u32_e64 s[30:31], s98, v85
	v_cndmask_b32_e64 v193, 0, v193, s[36:37]
	v_add_u32_e32 v86, 17, v84
	v_cmp_gt_u32_e64 s[36:37], s98, v86
	v_cndmask_b32_e64 v194, 0, v194, s[78:79]
	v_add_u32_e32 v87, 18, v84
	v_cmp_gt_u32_e64 s[78:79], s98, v87
	v_cndmask_b32_e64 v195, 0, v195, s[50:51]
	v_add_u32_e32 v88, 19, v84
	v_cmp_gt_u32_e64 s[50:51], s98, v88
	v_cndmask_b32_e64 v196, 0, v196, s[30:31]
	v_add_u32_e32 v85, 24, v84
	v_cmp_gt_u32_e64 s[30:31], s98, v85
	v_cndmask_b32_e64 v197, 0, v197, s[36:37]
	v_add_u32_e32 v86, 25, v84
	v_cmp_gt_u32_e64 s[36:37], s98, v86
	v_cndmask_b32_e64 v198, 0, v198, s[78:79]
	v_add_u32_e32 v87, 26, v84
	v_cmp_gt_u32_e64 s[78:79], s98, v87
	v_cndmask_b32_e64 v199, 0, v199, s[50:51]
	v_add_u32_e32 v88, 27, v84
	v_cmp_gt_u32_e64 s[50:51], s98, v88
	v_nop
	v_cndmask_b32_e64 v200, 0, v200, s[30:31]
	v_cndmask_b32_e64 v201, 0, v201, s[36:37]
	v_cndmask_b32_e64 v202, 0, v202, s[78:79]
	v_cndmask_b32_e64 v203, 0, v203, s[50:51]
	v_cvt_pk_bf16_f32 v64, v188, v189
	v_cvt_pk_bf16_f32 v65, v190, v191
	v_cvt_pk_bf16_f32 v66, v192, v193
	v_cvt_pk_bf16_f32 v67, v194, v195
	v_cvt_pk_bf16_f32 v68, v196, v197
	v_cvt_pk_bf16_f32 v69, v198, v199
	v_cvt_pk_bf16_f32 v70, v200, v201
	v_cvt_pk_bf16_f32 v71, v202, v203
	v_pk_add_f32 v[232:233], v[232:233], v[188:189]
	v_pk_add_f32 v[232:233], v[232:233], v[190:191]
	v_pk_add_f32 v[232:233], v[232:233], v[192:193]
	v_pk_add_f32 v[232:233], v[232:233], v[194:195]
	v_pk_add_f32 v[232:233], v[232:233], v[196:197]
	v_pk_add_f32 v[232:233], v[232:233], v[198:199]
	v_pk_add_f32 v[232:233], v[232:233], v[200:201]
	v_pk_add_f32 v[232:233], v[232:233], v[202:203]
	ds_read2_b32 v[188:189], v115 offset0:204 offset1:205
	ds_read2_b32 v[190:191], v115 offset0:206 offset1:207
	ds_read2_b32 v[192:193], v115 offset0:212 offset1:213
	ds_read2_b32 v[194:195], v115 offset0:214 offset1:215
	ds_read2_b32 v[196:197], v115 offset0:221 offset1:222
	ds_read2_b32 v[198:199], v115 offset0:223 offset1:224
	ds_read2_b32 v[200:201], v115 offset0:229 offset1:230
	ds_read2_b32 v[202:203], v115 offset0:231 offset1:232
	v_mfma_f32_32x32x16_bf16 v[0:15], v[64:67], v[72:75], v[0:15]
	v_mfma_f32_32x32x16_bf16 v[16:31], v[64:67], v[76:79], v[16:31]
	v_mfma_f32_32x32x16_bf16 v[0:15], v[68:71], v[220:223], v[0:15]
	v_mfma_f32_32x32x16_bf16 v[16:31], v[68:71], v[224:227], v[16:31]
	s_add_i32 s90, s67, 384
	v_add_u32_e32 v80, s90, v235
	v_add_u32_e32 v83, s90, v236
	v_add_u32_e32 v99, s90, v237
	v_add_u32_e32 v253, s90, v238
	v_add_u32_e32 v254, s90, v100
	v_add_u32_e32 v255, s90, v149
	v_med3_i32 v80, v80, 0, s99
	v_med3_i32 v83, v83, 0, s99
	v_med3_i32 v99, v99, 0, s99
	v_med3_i32 v253, v253, 0, s99
	v_med3_i32 v254, v254, 0, s99
	v_med3_i32 v255, v255, 0, s99
	v_mad_u32_u24 v80, v80, s100, v252
	v_mad_u32_u24 v83, v83, s100, v252
	v_mad_u32_u24 v99, v99, s100, v252
	v_mad_u32_u24 v253, v253, s100, v252
	v_mad_u32_u24 v254, v254, s100, v153
	v_mad_u32_u24 v255, v255, s100, v153
	global_load_dwordx4 v[116:119], v80, s[82:83]
	global_load_dwordx4 v[120:123], v83, s[82:83]
	global_load_dwordx4 v[124:127], v99, s[82:83]
	global_load_dwordx4 v[128:131], v253, s[82:83]
	global_load_dwordx4 v[132:135], v254, s[82:83] offset:768
	global_load_dwordx4 v[136:139], v255, s[82:83] offset:768
	global_load_dwordx4 v[140:143], v254, s[82:83] offset:832
	global_load_dwordx4 v[144:147], v255, s[82:83] offset:832
	ds_read_b64_tr_b16 v[72:73], v231
	ds_read_b64_tr_b16 v[74:75], v231 offset:512
	ds_read_b64_tr_b16 v[76:77], v231 offset:2048
	ds_read_b64_tr_b16 v[78:79], v231 offset:2560
	ds_read_b64_tr_b16 v[220:221], v231 offset:1024
	ds_read_b64_tr_b16 v[222:223], v231 offset:1536
	ds_read_b64_tr_b16 v[224:225], v231 offset:3072
	ds_read_b64_tr_b16 v[226:227], v231 offset:3584
	v_exp_f32_e32 v32, v32
	v_exp_f32_e32 v33, v33
	v_exp_f32_e32 v34, v34
	v_exp_f32_e32 v35, v35
	s_waitcnt vmcnt(8)
	ds_write_b128 v247, v[156:159]
	ds_write_b128 v247, v[160:163] offset:1024
	ds_write_b128 v247, v[164:167] offset:2048
	ds_write_b128 v247, v[168:171] offset:3072
	ds_read_b128 v[156:159], v248
	ds_read_b128 v[160:163], v249
	ds_read_b128 v[164:167], v250
	ds_read_b128 v[168:171], v251
	ds_write_b128 v112, v[172:175]
	ds_write_b128 v112, v[176:179] offset:1024
	ds_write_b128 v112, v[180:183] offset:2048
	ds_write_b128 v112, v[184:187] offset:3072
	v_exp_f32_e32 v36, v36
	v_exp_f32_e32 v37, v37
	v_exp_f32_e32 v38, v38
	v_exp_f32_e32 v39, v39
	s_waitcnt lgkmcnt(4)
	v_mfma_f32_32x32x16_bf16 v[188:203], v[156:159], v[48:51], v[188:203]
	v_exp_f32_e32 v40, v40
	v_exp_f32_e32 v41, v41
	v_mfma_f32_32x32x16_bf16 v[188:203], v[160:163], v[52:55], v[188:203]
	v_exp_f32_e32 v42, v42
	v_exp_f32_e32 v43, v43
	v_mfma_f32_32x32x16_bf16 v[188:203], v[164:167], v[56:59], v[188:203]
	v_exp_f32_e32 v44, v44
	v_exp_f32_e32 v45, v45
	v_mfma_f32_32x32x16_bf16 v[188:203], v[168:171], v[60:63], v[188:203]
	v_exp_f32_e32 v46, v46
	v_exp_f32_e32 v47, v47
	s_add_i32 s90, s67, 320
	v_add_u32_e32 v84, s90, v107
	v_add_u32_e32 v85, 0, v84
	v_add_u32_e32 v86, 1, v84
	v_add_u32_e32 v87, 2, v84
	v_add_u32_e32 v88, 3, v84
	v_cmp_gt_u32_e64 s[30:31], s98, v85
	v_cmp_gt_u32_e64 s[36:37], s98, v86
	v_cmp_gt_u32_e64 s[78:79], s98, v87
	v_cmp_gt_u32_e64 s[50:51], s98, v88
	v_cndmask_b32_e64 v32, 0, v32, s[30:31]
	v_add_u32_e32 v85, 8, v84
	v_cmp_gt_u32_e64 s[30:31], s98, v85
	v_cndmask_b32_e64 v33, 0, v33, s[36:37]
	v_add_u32_e32 v86, 9, v84
	v_cmp_gt_u32_e64 s[36:37], s98, v86
	v_cndmask_b32_e64 v34, 0, v34, s[78:79]
	v_add_u32_e32 v87, 10, v84
	v_cmp_gt_u32_e64 s[78:79], s98, v87
	v_cndmask_b32_e64 v35, 0, v35, s[50:51]
	v_add_u32_e32 v88, 11, v84
	v_cmp_gt_u32_e64 s[50:51], s98, v88
	v_cndmask_b32_e64 v36, 0, v36, s[30:31]
	v_add_u32_e32 v85, 16, v84
	v_cmp_gt_u32_e64 s[30:31], s98, v85
	v_cndmask_b32_e64 v37, 0, v37, s[36:37]
	v_add_u32_e32 v86, 17, v84
	v_cmp_gt_u32_e64 s[36:37], s98, v86
	v_cndmask_b32_e64 v38, 0, v38, s[78:79]
	v_add_u32_e32 v87, 18, v84
	v_cmp_gt_u32_e64 s[78:79], s98, v87
	v_cndmask_b32_e64 v39, 0, v39, s[50:51]
	v_add_u32_e32 v88, 19, v84
	v_cmp_gt_u32_e64 s[50:51], s98, v88
	v_cndmask_b32_e64 v40, 0, v40, s[30:31]
	v_add_u32_e32 v85, 24, v84
	v_cmp_gt_u32_e64 s[30:31], s98, v85
	v_cndmask_b32_e64 v41, 0, v41, s[36:37]
	v_add_u32_e32 v86, 25, v84
	v_cmp_gt_u32_e64 s[36:37], s98, v86
	v_cndmask_b32_e64 v42, 0, v42, s[78:79]
	v_add_u32_e32 v87, 26, v84
	v_cmp_gt_u32_e64 s[78:79], s98, v87
	v_cndmask_b32_e64 v43, 0, v43, s[50:51]
	v_add_u32_e32 v88, 27, v84
	v_cmp_gt_u32_e64 s[50:51], s98, v88
	v_nop
	v_cndmask_b32_e64 v44, 0, v44, s[30:31]
	v_cndmask_b32_e64 v45, 0, v45, s[36:37]
	v_cndmask_b32_e64 v46, 0, v46, s[78:79]
	v_cndmask_b32_e64 v47, 0, v47, s[50:51]
	v_cvt_pk_bf16_f32 v64, v32, v33
	v_cvt_pk_bf16_f32 v65, v34, v35
	v_cvt_pk_bf16_f32 v66, v36, v37
	v_cvt_pk_bf16_f32 v67, v38, v39
	v_cvt_pk_bf16_f32 v68, v40, v41
	v_cvt_pk_bf16_f32 v69, v42, v43
	v_cvt_pk_bf16_f32 v70, v44, v45
	v_cvt_pk_bf16_f32 v71, v46, v47
	v_pk_add_f32 v[232:233], v[232:233], v[32:33]
	v_pk_add_f32 v[232:233], v[232:233], v[34:35]
	v_pk_add_f32 v[232:233], v[232:233], v[36:37]
	v_pk_add_f32 v[232:233], v[232:233], v[38:39]
	v_pk_add_f32 v[232:233], v[232:233], v[40:41]
	v_pk_add_f32 v[232:233], v[232:233], v[42:43]
	v_pk_add_f32 v[232:233], v[232:233], v[44:45]
	v_pk_add_f32 v[232:233], v[232:233], v[46:47]
	v_add_u32_e32 v115, 952, v115
	ds_read2_b32 v[32:33], v115 offset0:0 offset1:1
	ds_read2_b32 v[34:35], v115 offset0:2 offset1:3
	ds_read2_b32 v[36:37], v115 offset0:8 offset1:9
	ds_read2_b32 v[38:39], v115 offset0:10 offset1:11
	ds_read2_b32 v[40:41], v115 offset0:17 offset1:18
	ds_read2_b32 v[42:43], v115 offset0:19 offset1:20
	ds_read2_b32 v[44:45], v115 offset0:25 offset1:26
	ds_read2_b32 v[46:47], v115 offset0:27 offset1:28
	v_mfma_f32_32x32x16_bf16 v[0:15], v[64:67], v[72:75], v[0:15]
	v_mfma_f32_32x32x16_bf16 v[16:31], v[64:67], v[76:79], v[16:31]
	v_mfma_f32_32x32x16_bf16 v[0:15], v[68:71], v[220:223], v[0:15]
	v_mfma_f32_32x32x16_bf16 v[16:31], v[68:71], v[224:227], v[16:31]
	s_add_i32 s90, s67, 416
	v_add_u32_e32 v80, s90, v235
	v_add_u32_e32 v83, s90, v236
	v_add_u32_e32 v99, s90, v237
	v_add_u32_e32 v253, s90, v238
	v_add_u32_e32 v254, s90, v100
	v_add_u32_e32 v255, s90, v149
	v_med3_i32 v80, v80, 0, s99
	v_med3_i32 v83, v83, 0, s99
	v_med3_i32 v99, v99, 0, s99
	v_med3_i32 v253, v253, 0, s99
	v_med3_i32 v254, v254, 0, s99
	v_med3_i32 v255, v255, 0, s99
	v_mad_u32_u24 v80, v80, s100, v252
	v_mad_u32_u24 v83, v83, s100, v252
	v_mad_u32_u24 v99, v99, s100, v252
	v_mad_u32_u24 v253, v253, s100, v252
	v_mad_u32_u24 v254, v254, s100, v153
	v_mad_u32_u24 v255, v255, s100, v153
	global_load_dwordx4 v[156:159], v80, s[82:83]
	global_load_dwordx4 v[160:163], v83, s[82:83]
	global_load_dwordx4 v[164:167], v99, s[82:83]
	global_load_dwordx4 v[168:171], v253, s[82:83]
	global_load_dwordx4 v[172:175], v254, s[82:83] offset:768
	global_load_dwordx4 v[176:179], v255, s[82:83] offset:768
	global_load_dwordx4 v[180:183], v254, s[82:83] offset:832
	global_load_dwordx4 v[184:187], v255, s[82:83] offset:832
	ds_read_b64_tr_b16 v[72:73], v231
	ds_read_b64_tr_b16 v[74:75], v231 offset:512
	ds_read_b64_tr_b16 v[76:77], v231 offset:2048
	ds_read_b64_tr_b16 v[78:79], v231 offset:2560
	ds_read_b64_tr_b16 v[220:221], v231 offset:1024
	ds_read_b64_tr_b16 v[222:223], v231 offset:1536
	ds_read_b64_tr_b16 v[224:225], v231 offset:3072
	ds_read_b64_tr_b16 v[226:227], v231 offset:3584
	v_exp_f32_e32 v188, v188
	v_exp_f32_e32 v189, v189
	v_exp_f32_e32 v190, v190
	v_exp_f32_e32 v191, v191
	s_waitcnt vmcnt(8)
	ds_write_b128 v247, v[116:119]
	ds_write_b128 v247, v[120:123] offset:1024
	ds_write_b128 v247, v[124:127] offset:2048
	ds_write_b128 v247, v[128:131] offset:3072
	ds_read_b128 v[116:119], v248
	ds_read_b128 v[120:123], v249
	ds_read_b128 v[124:127], v250
	ds_read_b128 v[128:131], v251
	ds_write_b128 v112, v[132:135]
	ds_write_b128 v112, v[136:139] offset:1024
	ds_write_b128 v112, v[140:143] offset:2048
	ds_write_b128 v112, v[144:147] offset:3072
	v_exp_f32_e32 v192, v192
	v_exp_f32_e32 v193, v193
	v_exp_f32_e32 v194, v194
	v_exp_f32_e32 v195, v195
	s_waitcnt lgkmcnt(4)
	v_mfma_f32_32x32x16_bf16 v[32:47], v[116:119], v[48:51], v[32:47]
	v_exp_f32_e32 v196, v196
	v_exp_f32_e32 v197, v197
	v_mfma_f32_32x32x16_bf16 v[32:47], v[120:123], v[52:55], v[32:47]
	v_exp_f32_e32 v198, v198
	v_exp_f32_e32 v199, v199
	v_mfma_f32_32x32x16_bf16 v[32:47], v[124:127], v[56:59], v[32:47]
	v_exp_f32_e32 v200, v200
	v_exp_f32_e32 v201, v201
	v_mfma_f32_32x32x16_bf16 v[32:47], v[128:131], v[60:63], v[32:47]
	v_exp_f32_e32 v202, v202
	v_exp_f32_e32 v203, v203
	s_add_i32 s90, s67, 352
	v_add_u32_e32 v84, s90, v107
	v_add_u32_e32 v85, 0, v84
	v_add_u32_e32 v86, 1, v84
	v_add_u32_e32 v87, 2, v84
	v_add_u32_e32 v88, 3, v84
	v_cmp_gt_u32_e64 s[30:31], s98, v85
	v_cmp_gt_u32_e64 s[36:37], s98, v86
	v_cmp_gt_u32_e64 s[78:79], s98, v87
	v_cmp_gt_u32_e64 s[50:51], s98, v88
	v_cndmask_b32_e64 v188, 0, v188, s[30:31]
	v_add_u32_e32 v85, 8, v84
	v_cmp_gt_u32_e64 s[30:31], s98, v85
	v_cndmask_b32_e64 v189, 0, v189, s[36:37]
	v_add_u32_e32 v86, 9, v84
	v_cmp_gt_u32_e64 s[36:37], s98, v86
	v_cndmask_b32_e64 v190, 0, v190, s[78:79]
	v_add_u32_e32 v87, 10, v84
	v_cmp_gt_u32_e64 s[78:79], s98, v87
	v_cndmask_b32_e64 v191, 0, v191, s[50:51]
	v_add_u32_e32 v88, 11, v84
	v_cmp_gt_u32_e64 s[50:51], s98, v88
	v_cndmask_b32_e64 v192, 0, v192, s[30:31]
	v_add_u32_e32 v85, 16, v84
	v_cmp_gt_u32_e64 s[30:31], s98, v85
	v_cndmask_b32_e64 v193, 0, v193, s[36:37]
	v_add_u32_e32 v86, 17, v84
	v_cmp_gt_u32_e64 s[36:37], s98, v86
	v_cndmask_b32_e64 v194, 0, v194, s[78:79]
	v_add_u32_e32 v87, 18, v84
	v_cmp_gt_u32_e64 s[78:79], s98, v87
	v_cndmask_b32_e64 v195, 0, v195, s[50:51]
	v_add_u32_e32 v88, 19, v84
	v_cmp_gt_u32_e64 s[50:51], s98, v88
	v_cndmask_b32_e64 v196, 0, v196, s[30:31]
	v_add_u32_e32 v85, 24, v84
	v_cmp_gt_u32_e64 s[30:31], s98, v85
	v_cndmask_b32_e64 v197, 0, v197, s[36:37]
	v_add_u32_e32 v86, 25, v84
	v_cmp_gt_u32_e64 s[36:37], s98, v86
	v_cndmask_b32_e64 v198, 0, v198, s[78:79]
	v_add_u32_e32 v87, 26, v84
	v_cmp_gt_u32_e64 s[78:79], s98, v87
	v_cndmask_b32_e64 v199, 0, v199, s[50:51]
	v_add_u32_e32 v88, 27, v84
	v_cmp_gt_u32_e64 s[50:51], s98, v88
	v_nop
	v_cndmask_b32_e64 v200, 0, v200, s[30:31]
	v_cndmask_b32_e64 v201, 0, v201, s[36:37]
	v_cndmask_b32_e64 v202, 0, v202, s[78:79]
	v_cndmask_b32_e64 v203, 0, v203, s[50:51]
	v_cvt_pk_bf16_f32 v64, v188, v189
	v_cvt_pk_bf16_f32 v65, v190, v191
	v_cvt_pk_bf16_f32 v66, v192, v193
	v_cvt_pk_bf16_f32 v67, v194, v195
	v_cvt_pk_bf16_f32 v68, v196, v197
	v_cvt_pk_bf16_f32 v69, v198, v199
	v_cvt_pk_bf16_f32 v70, v200, v201
	v_cvt_pk_bf16_f32 v71, v202, v203
	v_pk_add_f32 v[232:233], v[232:233], v[188:189]
	v_pk_add_f32 v[232:233], v[232:233], v[190:191]
	v_pk_add_f32 v[232:233], v[232:233], v[192:193]
	v_pk_add_f32 v[232:233], v[232:233], v[194:195]
	v_pk_add_f32 v[232:233], v[232:233], v[196:197]
	v_pk_add_f32 v[232:233], v[232:233], v[198:199]
	v_pk_add_f32 v[232:233], v[232:233], v[200:201]
	v_pk_add_f32 v[232:233], v[232:233], v[202:203]
	ds_read2_b32 v[188:189], v115 offset0:34 offset1:35
	ds_read2_b32 v[190:191], v115 offset0:36 offset1:37
	ds_read2_b32 v[192:193], v115 offset0:42 offset1:43
	ds_read2_b32 v[194:195], v115 offset0:44 offset1:45
	ds_read2_b32 v[196:197], v115 offset0:51 offset1:52
	ds_read2_b32 v[198:199], v115 offset0:53 offset1:54
	ds_read2_b32 v[200:201], v115 offset0:59 offset1:60
	ds_read2_b32 v[202:203], v115 offset0:61 offset1:62
	v_mfma_f32_32x32x16_bf16 v[0:15], v[64:67], v[72:75], v[0:15]
	v_mfma_f32_32x32x16_bf16 v[16:31], v[64:67], v[76:79], v[16:31]
	v_mfma_f32_32x32x16_bf16 v[0:15], v[68:71], v[220:223], v[0:15]
	v_mfma_f32_32x32x16_bf16 v[16:31], v[68:71], v[224:227], v[16:31]
	s_add_i32 s90, s67, 448
	v_add_u32_e32 v80, s90, v235
	v_add_u32_e32 v83, s90, v236
	v_add_u32_e32 v99, s90, v237
	v_add_u32_e32 v253, s90, v238
	v_add_u32_e32 v254, s90, v100
	v_add_u32_e32 v255, s90, v149
	v_med3_i32 v80, v80, 0, s99
	v_med3_i32 v83, v83, 0, s99
	v_med3_i32 v99, v99, 0, s99
	v_med3_i32 v253, v253, 0, s99
	v_med3_i32 v254, v254, 0, s99
	v_med3_i32 v255, v255, 0, s99
	v_mad_u32_u24 v80, v80, s100, v252
	v_mad_u32_u24 v83, v83, s100, v252
	v_mad_u32_u24 v99, v99, s100, v252
	v_mad_u32_u24 v253, v253, s100, v252
	v_mad_u32_u24 v254, v254, s100, v153
	v_mad_u32_u24 v255, v255, s100, v153
	global_load_dwordx4 v[116:119], v80, s[82:83]
	global_load_dwordx4 v[120:123], v83, s[82:83]
	global_load_dwordx4 v[124:127], v99, s[82:83]
	global_load_dwordx4 v[128:131], v253, s[82:83]
	global_load_dwordx4 v[132:135], v254, s[82:83] offset:768
	global_load_dwordx4 v[136:139], v255, s[82:83] offset:768
	global_load_dwordx4 v[140:143], v254, s[82:83] offset:832
	global_load_dwordx4 v[144:147], v255, s[82:83] offset:832
	ds_read_b64_tr_b16 v[72:73], v231
	ds_read_b64_tr_b16 v[74:75], v231 offset:512
	ds_read_b64_tr_b16 v[76:77], v231 offset:2048
	ds_read_b64_tr_b16 v[78:79], v231 offset:2560
	ds_read_b64_tr_b16 v[220:221], v231 offset:1024
	ds_read_b64_tr_b16 v[222:223], v231 offset:1536
	ds_read_b64_tr_b16 v[224:225], v231 offset:3072
	ds_read_b64_tr_b16 v[226:227], v231 offset:3584
	v_exp_f32_e32 v32, v32
	v_exp_f32_e32 v33, v33
	v_exp_f32_e32 v34, v34
	v_exp_f32_e32 v35, v35
	s_waitcnt vmcnt(8)
	ds_write_b128 v247, v[156:159]
	ds_write_b128 v247, v[160:163] offset:1024
	ds_write_b128 v247, v[164:167] offset:2048
	ds_write_b128 v247, v[168:171] offset:3072
	ds_read_b128 v[156:159], v248
	ds_read_b128 v[160:163], v249
	ds_read_b128 v[164:167], v250
	ds_read_b128 v[168:171], v251
	ds_write_b128 v112, v[172:175]
	ds_write_b128 v112, v[176:179] offset:1024
	ds_write_b128 v112, v[180:183] offset:2048
	ds_write_b128 v112, v[184:187] offset:3072
	v_exp_f32_e32 v36, v36
	v_exp_f32_e32 v37, v37
	v_exp_f32_e32 v38, v38
	v_exp_f32_e32 v39, v39
	s_waitcnt lgkmcnt(4)
	v_mfma_f32_32x32x16_bf16 v[188:203], v[156:159], v[48:51], v[188:203]
	v_exp_f32_e32 v40, v40
	v_exp_f32_e32 v41, v41
	v_mfma_f32_32x32x16_bf16 v[188:203], v[160:163], v[52:55], v[188:203]
	v_exp_f32_e32 v42, v42
	v_exp_f32_e32 v43, v43
	v_mfma_f32_32x32x16_bf16 v[188:203], v[164:167], v[56:59], v[188:203]
	v_exp_f32_e32 v44, v44
	v_exp_f32_e32 v45, v45
	v_mfma_f32_32x32x16_bf16 v[188:203], v[168:171], v[60:63], v[188:203]
	v_exp_f32_e32 v46, v46
	v_exp_f32_e32 v47, v47
	s_add_i32 s90, s67, 384
	v_add_u32_e32 v84, s90, v107
	v_add_u32_e32 v85, 0, v84
	v_add_u32_e32 v86, 1, v84
	v_add_u32_e32 v87, 2, v84
	v_add_u32_e32 v88, 3, v84
	v_cmp_gt_u32_e64 s[30:31], s98, v85
	v_cmp_gt_u32_e64 s[36:37], s98, v86
	v_cmp_gt_u32_e64 s[78:79], s98, v87
	v_cmp_gt_u32_e64 s[50:51], s98, v88
	v_cndmask_b32_e64 v32, 0, v32, s[30:31]
	v_add_u32_e32 v85, 8, v84
	v_cmp_gt_u32_e64 s[30:31], s98, v85
	v_cndmask_b32_e64 v33, 0, v33, s[36:37]
	v_add_u32_e32 v86, 9, v84
	v_cmp_gt_u32_e64 s[36:37], s98, v86
	v_cndmask_b32_e64 v34, 0, v34, s[78:79]
	v_add_u32_e32 v87, 10, v84
	v_cmp_gt_u32_e64 s[78:79], s98, v87
	v_cndmask_b32_e64 v35, 0, v35, s[50:51]
	v_add_u32_e32 v88, 11, v84
	v_cmp_gt_u32_e64 s[50:51], s98, v88
	v_cndmask_b32_e64 v36, 0, v36, s[30:31]
	v_add_u32_e32 v85, 16, v84
	v_cmp_gt_u32_e64 s[30:31], s98, v85
	v_cndmask_b32_e64 v37, 0, v37, s[36:37]
	v_add_u32_e32 v86, 17, v84
	v_cmp_gt_u32_e64 s[36:37], s98, v86
	v_cndmask_b32_e64 v38, 0, v38, s[78:79]
	v_add_u32_e32 v87, 18, v84
	v_cmp_gt_u32_e64 s[78:79], s98, v87
	v_cndmask_b32_e64 v39, 0, v39, s[50:51]
	v_add_u32_e32 v88, 19, v84
	v_cmp_gt_u32_e64 s[50:51], s98, v88
	v_cndmask_b32_e64 v40, 0, v40, s[30:31]
	v_add_u32_e32 v85, 24, v84
	v_cmp_gt_u32_e64 s[30:31], s98, v85
	v_cndmask_b32_e64 v41, 0, v41, s[36:37]
	v_add_u32_e32 v86, 25, v84
	v_cmp_gt_u32_e64 s[36:37], s98, v86
	v_cndmask_b32_e64 v42, 0, v42, s[78:79]
	v_add_u32_e32 v87, 26, v84
	v_cmp_gt_u32_e64 s[78:79], s98, v87
	v_cndmask_b32_e64 v43, 0, v43, s[50:51]
	v_add_u32_e32 v88, 27, v84
	v_cmp_gt_u32_e64 s[50:51], s98, v88
	v_nop
	v_cndmask_b32_e64 v44, 0, v44, s[30:31]
	v_cndmask_b32_e64 v45, 0, v45, s[36:37]
	v_cndmask_b32_e64 v46, 0, v46, s[78:79]
	v_cndmask_b32_e64 v47, 0, v47, s[50:51]
	v_cvt_pk_bf16_f32 v64, v32, v33
	v_cvt_pk_bf16_f32 v65, v34, v35
	v_cvt_pk_bf16_f32 v66, v36, v37
	v_cvt_pk_bf16_f32 v67, v38, v39
	v_cvt_pk_bf16_f32 v68, v40, v41
	v_cvt_pk_bf16_f32 v69, v42, v43
	v_cvt_pk_bf16_f32 v70, v44, v45
	v_cvt_pk_bf16_f32 v71, v46, v47
	v_pk_add_f32 v[232:233], v[232:233], v[32:33]
	v_pk_add_f32 v[232:233], v[232:233], v[34:35]
	v_pk_add_f32 v[232:233], v[232:233], v[36:37]
	v_pk_add_f32 v[232:233], v[232:233], v[38:39]
	v_pk_add_f32 v[232:233], v[232:233], v[40:41]
	v_pk_add_f32 v[232:233], v[232:233], v[42:43]
	v_pk_add_f32 v[232:233], v[232:233], v[44:45]
	v_pk_add_f32 v[232:233], v[232:233], v[46:47]
	ds_read2_b32 v[32:33], v115 offset0:68 offset1:69
	ds_read2_b32 v[34:35], v115 offset0:70 offset1:71
	ds_read2_b32 v[36:37], v115 offset0:76 offset1:77
	ds_read2_b32 v[38:39], v115 offset0:78 offset1:79
	ds_read2_b32 v[40:41], v115 offset0:85 offset1:86
	ds_read2_b32 v[42:43], v115 offset0:87 offset1:88
	ds_read2_b32 v[44:45], v115 offset0:93 offset1:94
	ds_read2_b32 v[46:47], v115 offset0:95 offset1:96
	v_mfma_f32_32x32x16_bf16 v[0:15], v[64:67], v[72:75], v[0:15]
	v_mfma_f32_32x32x16_bf16 v[16:31], v[64:67], v[76:79], v[16:31]
	v_mfma_f32_32x32x16_bf16 v[0:15], v[68:71], v[220:223], v[0:15]
	v_mfma_f32_32x32x16_bf16 v[16:31], v[68:71], v[224:227], v[16:31]
	s_add_i32 s90, s67, 480
	v_add_u32_e32 v80, s90, v235
	v_add_u32_e32 v83, s90, v236
	v_add_u32_e32 v99, s90, v237
	v_add_u32_e32 v253, s90, v238
	v_add_u32_e32 v254, s90, v100
	v_add_u32_e32 v255, s90, v149
	v_med3_i32 v80, v80, 0, s99
	v_med3_i32 v83, v83, 0, s99
	v_med3_i32 v99, v99, 0, s99
	v_med3_i32 v253, v253, 0, s99
	v_med3_i32 v254, v254, 0, s99
	v_med3_i32 v255, v255, 0, s99
	v_mad_u32_u24 v80, v80, s100, v252
	v_mad_u32_u24 v83, v83, s100, v252
	v_mad_u32_u24 v99, v99, s100, v252
	v_mad_u32_u24 v253, v253, s100, v252
	v_mad_u32_u24 v254, v254, s100, v153
	v_mad_u32_u24 v255, v255, s100, v153
	global_load_dwordx4 v[156:159], v80, s[82:83]
	global_load_dwordx4 v[160:163], v83, s[82:83]
	global_load_dwordx4 v[164:167], v99, s[82:83]
	global_load_dwordx4 v[168:171], v253, s[82:83]
	global_load_dwordx4 v[172:175], v254, s[82:83] offset:768
	global_load_dwordx4 v[176:179], v255, s[82:83] offset:768
	global_load_dwordx4 v[180:183], v254, s[82:83] offset:832
	global_load_dwordx4 v[184:187], v255, s[82:83] offset:832
	ds_read_b64_tr_b16 v[72:73], v231
	ds_read_b64_tr_b16 v[74:75], v231 offset:512
	ds_read_b64_tr_b16 v[76:77], v231 offset:2048
	ds_read_b64_tr_b16 v[78:79], v231 offset:2560
	ds_read_b64_tr_b16 v[220:221], v231 offset:1024
	ds_read_b64_tr_b16 v[222:223], v231 offset:1536
	ds_read_b64_tr_b16 v[224:225], v231 offset:3072
	ds_read_b64_tr_b16 v[226:227], v231 offset:3584
	v_exp_f32_e32 v188, v188
	v_exp_f32_e32 v189, v189
	v_exp_f32_e32 v190, v190
	v_exp_f32_e32 v191, v191
	s_waitcnt vmcnt(8)
	ds_write_b128 v247, v[116:119]
	ds_write_b128 v247, v[120:123] offset:1024
	ds_write_b128 v247, v[124:127] offset:2048
	ds_write_b128 v247, v[128:131] offset:3072
	ds_read_b128 v[116:119], v248
	ds_read_b128 v[120:123], v249
	ds_read_b128 v[124:127], v250
	ds_read_b128 v[128:131], v251
	ds_write_b128 v112, v[132:135]
	ds_write_b128 v112, v[136:139] offset:1024
	ds_write_b128 v112, v[140:143] offset:2048
	ds_write_b128 v112, v[144:147] offset:3072
	v_exp_f32_e32 v192, v192
	v_exp_f32_e32 v193, v193
	v_exp_f32_e32 v194, v194
	v_exp_f32_e32 v195, v195
	s_waitcnt lgkmcnt(4)
	v_mfma_f32_32x32x16_bf16 v[32:47], v[116:119], v[48:51], v[32:47]
	v_exp_f32_e32 v196, v196
	v_exp_f32_e32 v197, v197
	v_mfma_f32_32x32x16_bf16 v[32:47], v[120:123], v[52:55], v[32:47]
	v_exp_f32_e32 v198, v198
	v_exp_f32_e32 v199, v199
	v_mfma_f32_32x32x16_bf16 v[32:47], v[124:127], v[56:59], v[32:47]
	v_exp_f32_e32 v200, v200
	v_exp_f32_e32 v201, v201
	v_mfma_f32_32x32x16_bf16 v[32:47], v[128:131], v[60:63], v[32:47]
	v_exp_f32_e32 v202, v202
	v_exp_f32_e32 v203, v203
	s_add_i32 s90, s67, 416
	v_add_u32_e32 v84, s90, v107
	v_add_u32_e32 v85, 0, v84
	v_add_u32_e32 v86, 1, v84
	v_add_u32_e32 v87, 2, v84
	v_add_u32_e32 v88, 3, v84
	v_cmp_gt_u32_e64 s[30:31], s98, v85
	v_cmp_gt_u32_e64 s[36:37], s98, v86
	v_cmp_gt_u32_e64 s[78:79], s98, v87
	v_cmp_gt_u32_e64 s[50:51], s98, v88
	v_cndmask_b32_e64 v188, 0, v188, s[30:31]
	v_add_u32_e32 v85, 8, v84
	v_cmp_gt_u32_e64 s[30:31], s98, v85
	v_cndmask_b32_e64 v189, 0, v189, s[36:37]
	v_add_u32_e32 v86, 9, v84
	v_cmp_gt_u32_e64 s[36:37], s98, v86
	v_cndmask_b32_e64 v190, 0, v190, s[78:79]
	v_add_u32_e32 v87, 10, v84
	v_cmp_gt_u32_e64 s[78:79], s98, v87
	v_cndmask_b32_e64 v191, 0, v191, s[50:51]
	v_add_u32_e32 v88, 11, v84
	v_cmp_gt_u32_e64 s[50:51], s98, v88
	v_cndmask_b32_e64 v192, 0, v192, s[30:31]
	v_add_u32_e32 v85, 16, v84
	v_cmp_gt_u32_e64 s[30:31], s98, v85
	v_cndmask_b32_e64 v193, 0, v193, s[36:37]
	v_add_u32_e32 v86, 17, v84
	v_cmp_gt_u32_e64 s[36:37], s98, v86
	v_cndmask_b32_e64 v194, 0, v194, s[78:79]
	v_add_u32_e32 v87, 18, v84
	v_cmp_gt_u32_e64 s[78:79], s98, v87
	v_cndmask_b32_e64 v195, 0, v195, s[50:51]
	v_add_u32_e32 v88, 19, v84
	v_cmp_gt_u32_e64 s[50:51], s98, v88
	v_cndmask_b32_e64 v196, 0, v196, s[30:31]
	v_add_u32_e32 v85, 24, v84
	v_cmp_gt_u32_e64 s[30:31], s98, v85
	v_cndmask_b32_e64 v197, 0, v197, s[36:37]
	v_add_u32_e32 v86, 25, v84
	v_cmp_gt_u32_e64 s[36:37], s98, v86
	v_cndmask_b32_e64 v198, 0, v198, s[78:79]
	v_add_u32_e32 v87, 26, v84
	v_cmp_gt_u32_e64 s[78:79], s98, v87
	v_cndmask_b32_e64 v199, 0, v199, s[50:51]
	v_add_u32_e32 v88, 27, v84
	v_cmp_gt_u32_e64 s[50:51], s98, v88
	v_nop
	v_cndmask_b32_e64 v200, 0, v200, s[30:31]
	v_cndmask_b32_e64 v201, 0, v201, s[36:37]
	v_cndmask_b32_e64 v202, 0, v202, s[78:79]
	v_cndmask_b32_e64 v203, 0, v203, s[50:51]
	v_cvt_pk_bf16_f32 v64, v188, v189
	v_cvt_pk_bf16_f32 v65, v190, v191
	v_cvt_pk_bf16_f32 v66, v192, v193
	v_cvt_pk_bf16_f32 v67, v194, v195
	v_cvt_pk_bf16_f32 v68, v196, v197
	v_cvt_pk_bf16_f32 v69, v198, v199
	v_cvt_pk_bf16_f32 v70, v200, v201
	v_cvt_pk_bf16_f32 v71, v202, v203
	v_pk_add_f32 v[232:233], v[232:233], v[188:189]
	v_pk_add_f32 v[232:233], v[232:233], v[190:191]
	v_pk_add_f32 v[232:233], v[232:233], v[192:193]
	v_pk_add_f32 v[232:233], v[232:233], v[194:195]
	v_pk_add_f32 v[232:233], v[232:233], v[196:197]
	v_pk_add_f32 v[232:233], v[232:233], v[198:199]
	v_pk_add_f32 v[232:233], v[232:233], v[200:201]
	v_pk_add_f32 v[232:233], v[232:233], v[202:203]
	ds_read2_b32 v[188:189], v115 offset0:102 offset1:103
	ds_read2_b32 v[190:191], v115 offset0:104 offset1:105
	ds_read2_b32 v[192:193], v115 offset0:110 offset1:111
	ds_read2_b32 v[194:195], v115 offset0:112 offset1:113
	ds_read2_b32 v[196:197], v115 offset0:119 offset1:120
	ds_read2_b32 v[198:199], v115 offset0:121 offset1:122
	ds_read2_b32 v[200:201], v115 offset0:127 offset1:128
	ds_read2_b32 v[202:203], v115 offset0:129 offset1:130
	v_mfma_f32_32x32x16_bf16 v[0:15], v[64:67], v[72:75], v[0:15]
	v_mfma_f32_32x32x16_bf16 v[16:31], v[64:67], v[76:79], v[16:31]
	v_mfma_f32_32x32x16_bf16 v[0:15], v[68:71], v[220:223], v[0:15]
	v_mfma_f32_32x32x16_bf16 v[16:31], v[68:71], v[224:227], v[16:31]
	s_add_i32 s90, s67, 512
	v_add_u32_e32 v80, s90, v235
	v_add_u32_e32 v83, s90, v236
	v_add_u32_e32 v99, s90, v237
	v_add_u32_e32 v253, s90, v238
	v_add_u32_e32 v254, s90, v100
	v_add_u32_e32 v255, s90, v149
	v_med3_i32 v80, v80, 0, s99
	v_med3_i32 v83, v83, 0, s99
	v_med3_i32 v99, v99, 0, s99
	v_med3_i32 v253, v253, 0, s99
	v_med3_i32 v254, v254, 0, s99
	v_med3_i32 v255, v255, 0, s99
	v_mad_u32_u24 v80, v80, s100, v252
	v_mad_u32_u24 v83, v83, s100, v252
	v_mad_u32_u24 v99, v99, s100, v252
	v_mad_u32_u24 v253, v253, s100, v252
	v_mad_u32_u24 v254, v254, s100, v153
	v_mad_u32_u24 v255, v255, s100, v153
	global_load_dwordx4 v[116:119], v80, s[82:83]
	global_load_dwordx4 v[120:123], v83, s[82:83]
	global_load_dwordx4 v[124:127], v99, s[82:83]
	global_load_dwordx4 v[128:131], v253, s[82:83]
	global_load_dwordx4 v[132:135], v254, s[82:83] offset:768
	global_load_dwordx4 v[136:139], v255, s[82:83] offset:768
	global_load_dwordx4 v[140:143], v254, s[82:83] offset:832
	global_load_dwordx4 v[144:147], v255, s[82:83] offset:832
	ds_read_b64_tr_b16 v[72:73], v231
	ds_read_b64_tr_b16 v[74:75], v231 offset:512
	ds_read_b64_tr_b16 v[76:77], v231 offset:2048
	ds_read_b64_tr_b16 v[78:79], v231 offset:2560
	ds_read_b64_tr_b16 v[220:221], v231 offset:1024
	ds_read_b64_tr_b16 v[222:223], v231 offset:1536
	ds_read_b64_tr_b16 v[224:225], v231 offset:3072
	ds_read_b64_tr_b16 v[226:227], v231 offset:3584
	v_exp_f32_e32 v32, v32
	v_exp_f32_e32 v33, v33
	v_exp_f32_e32 v34, v34
	v_exp_f32_e32 v35, v35
	s_waitcnt vmcnt(8)
	ds_write_b128 v247, v[156:159]
	ds_write_b128 v247, v[160:163] offset:1024
	ds_write_b128 v247, v[164:167] offset:2048
	ds_write_b128 v247, v[168:171] offset:3072
	ds_read_b128 v[156:159], v248
	ds_read_b128 v[160:163], v249
	ds_read_b128 v[164:167], v250
	ds_read_b128 v[168:171], v251
	ds_write_b128 v112, v[172:175]
	ds_write_b128 v112, v[176:179] offset:1024
	ds_write_b128 v112, v[180:183] offset:2048
	ds_write_b128 v112, v[184:187] offset:3072
	v_exp_f32_e32 v36, v36
	v_exp_f32_e32 v37, v37
	v_exp_f32_e32 v38, v38
	v_exp_f32_e32 v39, v39
	s_waitcnt lgkmcnt(4)
	v_mfma_f32_32x32x16_bf16 v[188:203], v[156:159], v[48:51], v[188:203]
	v_exp_f32_e32 v40, v40
	v_exp_f32_e32 v41, v41
	v_mfma_f32_32x32x16_bf16 v[188:203], v[160:163], v[52:55], v[188:203]
	v_exp_f32_e32 v42, v42
	v_exp_f32_e32 v43, v43
	v_mfma_f32_32x32x16_bf16 v[188:203], v[164:167], v[56:59], v[188:203]
	v_exp_f32_e32 v44, v44
	v_exp_f32_e32 v45, v45
	v_mfma_f32_32x32x16_bf16 v[188:203], v[168:171], v[60:63], v[188:203]
	v_exp_f32_e32 v46, v46
	v_exp_f32_e32 v47, v47
	s_add_i32 s90, s67, 448
	v_add_u32_e32 v84, s90, v107
	v_add_u32_e32 v85, 0, v84
	v_add_u32_e32 v86, 1, v84
	v_add_u32_e32 v87, 2, v84
	v_add_u32_e32 v88, 3, v84
	v_cmp_gt_u32_e64 s[30:31], s98, v85
	v_cmp_gt_u32_e64 s[36:37], s98, v86
	v_cmp_gt_u32_e64 s[78:79], s98, v87
	v_cmp_gt_u32_e64 s[50:51], s98, v88
	v_cndmask_b32_e64 v32, 0, v32, s[30:31]
	v_add_u32_e32 v85, 8, v84
	v_cmp_gt_u32_e64 s[30:31], s98, v85
	v_cndmask_b32_e64 v33, 0, v33, s[36:37]
	v_add_u32_e32 v86, 9, v84
	v_cmp_gt_u32_e64 s[36:37], s98, v86
	v_cndmask_b32_e64 v34, 0, v34, s[78:79]
	v_add_u32_e32 v87, 10, v84
	v_cmp_gt_u32_e64 s[78:79], s98, v87
	v_cndmask_b32_e64 v35, 0, v35, s[50:51]
	v_add_u32_e32 v88, 11, v84
	v_cmp_gt_u32_e64 s[50:51], s98, v88
	v_cndmask_b32_e64 v36, 0, v36, s[30:31]
	v_add_u32_e32 v85, 16, v84
	v_cmp_gt_u32_e64 s[30:31], s98, v85
	v_cndmask_b32_e64 v37, 0, v37, s[36:37]
	v_add_u32_e32 v86, 17, v84
	v_cmp_gt_u32_e64 s[36:37], s98, v86
	v_cndmask_b32_e64 v38, 0, v38, s[78:79]
	v_add_u32_e32 v87, 18, v84
	v_cmp_gt_u32_e64 s[78:79], s98, v87
	v_cndmask_b32_e64 v39, 0, v39, s[50:51]
	v_add_u32_e32 v88, 19, v84
	v_cmp_gt_u32_e64 s[50:51], s98, v88
	v_cndmask_b32_e64 v40, 0, v40, s[30:31]
	v_add_u32_e32 v85, 24, v84
	v_cmp_gt_u32_e64 s[30:31], s98, v85
	v_cndmask_b32_e64 v41, 0, v41, s[36:37]
	v_add_u32_e32 v86, 25, v84
	v_cmp_gt_u32_e64 s[36:37], s98, v86
	v_cndmask_b32_e64 v42, 0, v42, s[78:79]
	v_add_u32_e32 v87, 26, v84
	v_cmp_gt_u32_e64 s[78:79], s98, v87
	v_cndmask_b32_e64 v43, 0, v43, s[50:51]
	v_add_u32_e32 v88, 27, v84
	v_cmp_gt_u32_e64 s[50:51], s98, v88
	v_nop
	v_cndmask_b32_e64 v44, 0, v44, s[30:31]
	v_cndmask_b32_e64 v45, 0, v45, s[36:37]
	v_cndmask_b32_e64 v46, 0, v46, s[78:79]
	v_cndmask_b32_e64 v47, 0, v47, s[50:51]
	v_cvt_pk_bf16_f32 v64, v32, v33
	v_cvt_pk_bf16_f32 v65, v34, v35
	v_cvt_pk_bf16_f32 v66, v36, v37
	v_cvt_pk_bf16_f32 v67, v38, v39
	v_cvt_pk_bf16_f32 v68, v40, v41
	v_cvt_pk_bf16_f32 v69, v42, v43
	v_cvt_pk_bf16_f32 v70, v44, v45
	v_cvt_pk_bf16_f32 v71, v46, v47
	v_pk_add_f32 v[232:233], v[232:233], v[32:33]
	v_pk_add_f32 v[232:233], v[232:233], v[34:35]
	v_pk_add_f32 v[232:233], v[232:233], v[36:37]
	v_pk_add_f32 v[232:233], v[232:233], v[38:39]
	v_pk_add_f32 v[232:233], v[232:233], v[40:41]
	v_pk_add_f32 v[232:233], v[232:233], v[42:43]
	v_pk_add_f32 v[232:233], v[232:233], v[44:45]
	v_pk_add_f32 v[232:233], v[232:233], v[46:47]
	ds_read2_b32 v[32:33], v115 offset0:136 offset1:137
	ds_read2_b32 v[34:35], v115 offset0:138 offset1:139
	ds_read2_b32 v[36:37], v115 offset0:144 offset1:145
	ds_read2_b32 v[38:39], v115 offset0:146 offset1:147
	ds_read2_b32 v[40:41], v115 offset0:153 offset1:154
	ds_read2_b32 v[42:43], v115 offset0:155 offset1:156
	ds_read2_b32 v[44:45], v115 offset0:161 offset1:162
	ds_read2_b32 v[46:47], v115 offset0:163 offset1:164
	v_mfma_f32_32x32x16_bf16 v[0:15], v[64:67], v[72:75], v[0:15]
	v_mfma_f32_32x32x16_bf16 v[16:31], v[64:67], v[76:79], v[16:31]
	v_mfma_f32_32x32x16_bf16 v[0:15], v[68:71], v[220:223], v[0:15]
	v_mfma_f32_32x32x16_bf16 v[16:31], v[68:71], v[224:227], v[16:31]
	s_add_i32 s90, s67, 544
	v_add_u32_e32 v80, s90, v235
	v_add_u32_e32 v83, s90, v236
	v_add_u32_e32 v99, s90, v237
	v_add_u32_e32 v253, s90, v238
	v_add_u32_e32 v254, s90, v100
	v_add_u32_e32 v255, s90, v149
	v_med3_i32 v80, v80, 0, s99
	v_med3_i32 v83, v83, 0, s99
	v_med3_i32 v99, v99, 0, s99
	v_med3_i32 v253, v253, 0, s99
	v_med3_i32 v254, v254, 0, s99
	v_med3_i32 v255, v255, 0, s99
	v_mad_u32_u24 v80, v80, s100, v252
	v_mad_u32_u24 v83, v83, s100, v252
	v_mad_u32_u24 v99, v99, s100, v252
	v_mad_u32_u24 v253, v253, s100, v252
	v_mad_u32_u24 v254, v254, s100, v153
	v_mad_u32_u24 v255, v255, s100, v153
	global_load_dwordx4 v[156:159], v80, s[82:83]
	global_load_dwordx4 v[160:163], v83, s[82:83]
	global_load_dwordx4 v[164:167], v99, s[82:83]
	global_load_dwordx4 v[168:171], v253, s[82:83]
	global_load_dwordx4 v[172:175], v254, s[82:83] offset:768
	global_load_dwordx4 v[176:179], v255, s[82:83] offset:768
	global_load_dwordx4 v[180:183], v254, s[82:83] offset:832
	global_load_dwordx4 v[184:187], v255, s[82:83] offset:832
	ds_read_b64_tr_b16 v[72:73], v231
	ds_read_b64_tr_b16 v[74:75], v231 offset:512
	ds_read_b64_tr_b16 v[76:77], v231 offset:2048
	ds_read_b64_tr_b16 v[78:79], v231 offset:2560
	ds_read_b64_tr_b16 v[220:221], v231 offset:1024
	ds_read_b64_tr_b16 v[222:223], v231 offset:1536
	ds_read_b64_tr_b16 v[224:225], v231 offset:3072
	ds_read_b64_tr_b16 v[226:227], v231 offset:3584
	v_exp_f32_e32 v188, v188
	v_exp_f32_e32 v189, v189
	v_exp_f32_e32 v190, v190
	v_exp_f32_e32 v191, v191
	s_waitcnt vmcnt(8)
	ds_write_b128 v247, v[116:119]
	ds_write_b128 v247, v[120:123] offset:1024
	ds_write_b128 v247, v[124:127] offset:2048
	ds_write_b128 v247, v[128:131] offset:3072
	ds_read_b128 v[116:119], v248
	ds_read_b128 v[120:123], v249
	ds_read_b128 v[124:127], v250
	ds_read_b128 v[128:131], v251
	ds_write_b128 v112, v[132:135]
	ds_write_b128 v112, v[136:139] offset:1024
	ds_write_b128 v112, v[140:143] offset:2048
	ds_write_b128 v112, v[144:147] offset:3072
	v_exp_f32_e32 v192, v192
	v_exp_f32_e32 v193, v193
	v_exp_f32_e32 v194, v194
	v_exp_f32_e32 v195, v195
	s_waitcnt lgkmcnt(4)
	v_mfma_f32_32x32x16_bf16 v[32:47], v[116:119], v[48:51], v[32:47]
	v_exp_f32_e32 v196, v196
	v_exp_f32_e32 v197, v197
	v_mfma_f32_32x32x16_bf16 v[32:47], v[120:123], v[52:55], v[32:47]
	v_exp_f32_e32 v198, v198
	v_exp_f32_e32 v199, v199
	v_mfma_f32_32x32x16_bf16 v[32:47], v[124:127], v[56:59], v[32:47]
	v_exp_f32_e32 v200, v200
	v_exp_f32_e32 v201, v201
	v_mfma_f32_32x32x16_bf16 v[32:47], v[128:131], v[60:63], v[32:47]
	v_exp_f32_e32 v202, v202
	v_exp_f32_e32 v203, v203
	s_add_i32 s90, s67, 480
	v_add_u32_e32 v84, s90, v107
	v_add_u32_e32 v85, 0, v84
	v_add_u32_e32 v86, 1, v84
	v_add_u32_e32 v87, 2, v84
	v_add_u32_e32 v88, 3, v84
	v_cmp_gt_u32_e64 s[30:31], s98, v85
	v_cmp_gt_u32_e64 s[36:37], s98, v86
	v_cmp_gt_u32_e64 s[78:79], s98, v87
	v_cmp_gt_u32_e64 s[50:51], s98, v88
	v_cndmask_b32_e64 v188, 0, v188, s[30:31]
	v_add_u32_e32 v85, 8, v84
	v_cmp_gt_u32_e64 s[30:31], s98, v85
	v_cndmask_b32_e64 v189, 0, v189, s[36:37]
	v_add_u32_e32 v86, 9, v84
	v_cmp_gt_u32_e64 s[36:37], s98, v86
	v_cndmask_b32_e64 v190, 0, v190, s[78:79]
	v_add_u32_e32 v87, 10, v84
	v_cmp_gt_u32_e64 s[78:79], s98, v87
	v_cndmask_b32_e64 v191, 0, v191, s[50:51]
	v_add_u32_e32 v88, 11, v84
	v_cmp_gt_u32_e64 s[50:51], s98, v88
	v_cndmask_b32_e64 v192, 0, v192, s[30:31]
	v_add_u32_e32 v85, 16, v84
	v_cmp_gt_u32_e64 s[30:31], s98, v85
	v_cndmask_b32_e64 v193, 0, v193, s[36:37]
	v_add_u32_e32 v86, 17, v84
	v_cmp_gt_u32_e64 s[36:37], s98, v86
	v_cndmask_b32_e64 v194, 0, v194, s[78:79]
	v_add_u32_e32 v87, 18, v84
	v_cmp_gt_u32_e64 s[78:79], s98, v87
	v_cndmask_b32_e64 v195, 0, v195, s[50:51]
	v_add_u32_e32 v88, 19, v84
	v_cmp_gt_u32_e64 s[50:51], s98, v88
	v_cndmask_b32_e64 v196, 0, v196, s[30:31]
	v_add_u32_e32 v85, 24, v84
	v_cmp_gt_u32_e64 s[30:31], s98, v85
	v_cndmask_b32_e64 v197, 0, v197, s[36:37]
	v_add_u32_e32 v86, 25, v84
	v_cmp_gt_u32_e64 s[36:37], s98, v86
	v_cndmask_b32_e64 v198, 0, v198, s[78:79]
	v_add_u32_e32 v87, 26, v84
	v_cmp_gt_u32_e64 s[78:79], s98, v87
	v_cndmask_b32_e64 v199, 0, v199, s[50:51]
	v_add_u32_e32 v88, 27, v84
	v_cmp_gt_u32_e64 s[50:51], s98, v88
	v_nop
	v_cndmask_b32_e64 v200, 0, v200, s[30:31]
	v_cndmask_b32_e64 v201, 0, v201, s[36:37]
	v_cndmask_b32_e64 v202, 0, v202, s[78:79]
	v_cndmask_b32_e64 v203, 0, v203, s[50:51]
	v_cvt_pk_bf16_f32 v64, v188, v189
	v_cvt_pk_bf16_f32 v65, v190, v191
	v_cvt_pk_bf16_f32 v66, v192, v193
	v_cvt_pk_bf16_f32 v67, v194, v195
	v_cvt_pk_bf16_f32 v68, v196, v197
	v_cvt_pk_bf16_f32 v69, v198, v199
	v_cvt_pk_bf16_f32 v70, v200, v201
	v_cvt_pk_bf16_f32 v71, v202, v203
	v_pk_add_f32 v[232:233], v[232:233], v[188:189]
	v_pk_add_f32 v[232:233], v[232:233], v[190:191]
	v_pk_add_f32 v[232:233], v[232:233], v[192:193]
	v_pk_add_f32 v[232:233], v[232:233], v[194:195]
	v_pk_add_f32 v[232:233], v[232:233], v[196:197]
	v_pk_add_f32 v[232:233], v[232:233], v[198:199]
	v_pk_add_f32 v[232:233], v[232:233], v[200:201]
	v_pk_add_f32 v[232:233], v[232:233], v[202:203]
	ds_read2_b32 v[188:189], v115 offset0:170 offset1:171
	ds_read2_b32 v[190:191], v115 offset0:172 offset1:173
	ds_read2_b32 v[192:193], v115 offset0:178 offset1:179
	ds_read2_b32 v[194:195], v115 offset0:180 offset1:181
	ds_read2_b32 v[196:197], v115 offset0:187 offset1:188
	ds_read2_b32 v[198:199], v115 offset0:189 offset1:190
	ds_read2_b32 v[200:201], v115 offset0:195 offset1:196
	ds_read2_b32 v[202:203], v115 offset0:197 offset1:198
	v_mfma_f32_32x32x16_bf16 v[0:15], v[64:67], v[72:75], v[0:15]
	v_mfma_f32_32x32x16_bf16 v[16:31], v[64:67], v[76:79], v[16:31]
	v_mfma_f32_32x32x16_bf16 v[0:15], v[68:71], v[220:223], v[0:15]
	v_mfma_f32_32x32x16_bf16 v[16:31], v[68:71], v[224:227], v[16:31]
	s_add_i32 s90, s67, -256
	v_add_u32_e32 v80, s90, v239
	v_add_u32_e32 v83, s90, v240
	v_add_u32_e32 v99, s90, v241
	v_add_u32_e32 v253, s90, v242
	v_add_u32_e32 v254, s90, v101
	v_add_u32_e32 v255, s90, v150
	v_med3_i32 v80, v80, 0, s99
	v_med3_i32 v83, v83, 0, s99
	v_med3_i32 v99, v99, 0, s99
	v_med3_i32 v253, v253, 0, s99
	v_med3_i32 v254, v254, 0, s99
	v_med3_i32 v255, v255, 0, s99
	v_mad_u32_u24 v80, v80, s100, v252
	v_mad_u32_u24 v83, v83, s100, v252
	v_mad_u32_u24 v99, v99, s100, v252
	v_mad_u32_u24 v253, v253, s100, v252
	v_mad_u32_u24 v254, v254, s100, v153
	v_mad_u32_u24 v255, v255, s100, v153
	global_load_dwordx4 v[116:119], v80, s[82:83]
	global_load_dwordx4 v[120:123], v83, s[82:83]
	global_load_dwordx4 v[124:127], v99, s[82:83]
	global_load_dwordx4 v[128:131], v253, s[82:83]
	global_load_dwordx4 v[132:135], v254, s[82:83] offset:768
	global_load_dwordx4 v[136:139], v255, s[82:83] offset:768
	global_load_dwordx4 v[140:143], v254, s[82:83] offset:832
	global_load_dwordx4 v[144:147], v255, s[82:83] offset:832
	ds_read_b64_tr_b16 v[72:73], v231
	ds_read_b64_tr_b16 v[74:75], v231 offset:512
	ds_read_b64_tr_b16 v[76:77], v231 offset:2048
	ds_read_b64_tr_b16 v[78:79], v231 offset:2560
	ds_read_b64_tr_b16 v[220:221], v231 offset:1024
	ds_read_b64_tr_b16 v[222:223], v231 offset:1536
	ds_read_b64_tr_b16 v[224:225], v231 offset:3072
	ds_read_b64_tr_b16 v[226:227], v231 offset:3584
	v_exp_f32_e32 v32, v32
	v_exp_f32_e32 v33, v33
	v_exp_f32_e32 v34, v34
	v_exp_f32_e32 v35, v35
	s_waitcnt vmcnt(8)
	ds_write_b128 v247, v[156:159]
	ds_write_b128 v247, v[160:163] offset:1024
	ds_write_b128 v247, v[164:167] offset:2048
	ds_write_b128 v247, v[168:171] offset:3072
	ds_read_b128 v[156:159], v248
	ds_read_b128 v[160:163], v249
	ds_read_b128 v[164:167], v250
	ds_read_b128 v[168:171], v251
	ds_write_b128 v112, v[172:175]
	ds_write_b128 v112, v[176:179] offset:1024
	ds_write_b128 v112, v[180:183] offset:2048
	ds_write_b128 v112, v[184:187] offset:3072
	v_exp_f32_e32 v36, v36
	v_exp_f32_e32 v37, v37
	v_exp_f32_e32 v38, v38
	v_exp_f32_e32 v39, v39
	s_waitcnt lgkmcnt(4)
	v_mfma_f32_32x32x16_bf16 v[188:203], v[156:159], v[48:51], v[188:203]
	v_exp_f32_e32 v40, v40
	v_exp_f32_e32 v41, v41
	v_mfma_f32_32x32x16_bf16 v[188:203], v[160:163], v[52:55], v[188:203]
	v_exp_f32_e32 v42, v42
	v_exp_f32_e32 v43, v43
	v_mfma_f32_32x32x16_bf16 v[188:203], v[164:167], v[56:59], v[188:203]
	v_exp_f32_e32 v44, v44
	v_exp_f32_e32 v45, v45
	v_mfma_f32_32x32x16_bf16 v[188:203], v[168:171], v[60:63], v[188:203]
	v_exp_f32_e32 v46, v46
	v_exp_f32_e32 v47, v47
	s_add_i32 s90, s67, 512
	v_add_u32_e32 v84, s90, v107
	v_add_u32_e32 v85, 0, v84
	v_add_u32_e32 v86, 1, v84
	v_add_u32_e32 v87, 2, v84
	v_add_u32_e32 v88, 3, v84
	v_cmp_gt_u32_e64 s[30:31], s98, v85
	v_cmp_gt_u32_e64 s[36:37], s98, v86
	v_cmp_gt_u32_e64 s[78:79], s98, v87
	v_cmp_gt_u32_e64 s[50:51], s98, v88
	v_cndmask_b32_e64 v32, 0, v32, s[30:31]
	v_add_u32_e32 v85, 8, v84
	v_cmp_gt_u32_e64 s[30:31], s98, v85
	v_cndmask_b32_e64 v33, 0, v33, s[36:37]
	v_add_u32_e32 v86, 9, v84
	v_cmp_gt_u32_e64 s[36:37], s98, v86
	v_cndmask_b32_e64 v34, 0, v34, s[78:79]
	v_add_u32_e32 v87, 10, v84
	v_cmp_gt_u32_e64 s[78:79], s98, v87
	v_cndmask_b32_e64 v35, 0, v35, s[50:51]
	v_add_u32_e32 v88, 11, v84
	v_cmp_gt_u32_e64 s[50:51], s98, v88
	v_cndmask_b32_e64 v36, 0, v36, s[30:31]
	v_add_u32_e32 v85, 16, v84
	v_cmp_gt_u32_e64 s[30:31], s98, v85
	v_cndmask_b32_e64 v37, 0, v37, s[36:37]
	v_add_u32_e32 v86, 17, v84
	v_cmp_gt_u32_e64 s[36:37], s98, v86
	v_cndmask_b32_e64 v38, 0, v38, s[78:79]
	v_add_u32_e32 v87, 18, v84
	v_cmp_gt_u32_e64 s[78:79], s98, v87
	v_cndmask_b32_e64 v39, 0, v39, s[50:51]
	v_add_u32_e32 v88, 19, v84
	v_cmp_gt_u32_e64 s[50:51], s98, v88
	v_cndmask_b32_e64 v40, 0, v40, s[30:31]
	v_add_u32_e32 v85, 24, v84
	v_cmp_gt_u32_e64 s[30:31], s98, v85
	v_cndmask_b32_e64 v41, 0, v41, s[36:37]
	v_add_u32_e32 v86, 25, v84
	v_cmp_gt_u32_e64 s[36:37], s98, v86
	v_cndmask_b32_e64 v42, 0, v42, s[78:79]
	v_add_u32_e32 v87, 26, v84
	v_cmp_gt_u32_e64 s[78:79], s98, v87
	v_cndmask_b32_e64 v43, 0, v43, s[50:51]
	v_add_u32_e32 v88, 27, v84
	v_cmp_gt_u32_e64 s[50:51], s98, v88
	v_nop
	v_cndmask_b32_e64 v44, 0, v44, s[30:31]
	v_cndmask_b32_e64 v45, 0, v45, s[36:37]
	v_cndmask_b32_e64 v46, 0, v46, s[78:79]
	v_cndmask_b32_e64 v47, 0, v47, s[50:51]
	v_cvt_pk_bf16_f32 v64, v32, v33
	v_cvt_pk_bf16_f32 v65, v34, v35
	v_cvt_pk_bf16_f32 v66, v36, v37
	v_cvt_pk_bf16_f32 v67, v38, v39
	v_cvt_pk_bf16_f32 v68, v40, v41
	v_cvt_pk_bf16_f32 v69, v42, v43
	v_cvt_pk_bf16_f32 v70, v44, v45
	v_cvt_pk_bf16_f32 v71, v46, v47
	v_pk_add_f32 v[232:233], v[232:233], v[32:33]
	v_pk_add_f32 v[232:233], v[232:233], v[34:35]
	v_pk_add_f32 v[232:233], v[232:233], v[36:37]
	v_pk_add_f32 v[232:233], v[232:233], v[38:39]
	v_pk_add_f32 v[232:233], v[232:233], v[40:41]
	v_pk_add_f32 v[232:233], v[232:233], v[42:43]
	v_pk_add_f32 v[232:233], v[232:233], v[44:45]
	v_pk_add_f32 v[232:233], v[232:233], v[46:47]
	v_mov_b32_e32 v115, v229
	ds_read2_b32 v[32:33], v115 offset0:0 offset1:1
	ds_read2_b32 v[34:35], v115 offset0:2 offset1:3
	ds_read2_b32 v[36:37], v115 offset0:8 offset1:9
	ds_read2_b32 v[38:39], v115 offset0:10 offset1:11
	ds_read2_b32 v[40:41], v115 offset0:16 offset1:17
	ds_read2_b32 v[42:43], v115 offset0:18 offset1:19
	ds_read2_b32 v[44:45], v115 offset0:24 offset1:25
	ds_read2_b32 v[46:47], v115 offset0:26 offset1:27
	v_mfma_f32_32x32x16_bf16 v[0:15], v[64:67], v[72:75], v[0:15]
	v_mfma_f32_32x32x16_bf16 v[16:31], v[64:67], v[76:79], v[16:31]
	v_mfma_f32_32x32x16_bf16 v[0:15], v[68:71], v[220:223], v[0:15]
	v_mfma_f32_32x32x16_bf16 v[16:31], v[68:71], v[224:227], v[16:31]
	s_add_i32 s90, s67, -128
	v_add_u32_e32 v80, s90, v239
	v_add_u32_e32 v83, s90, v240
	v_add_u32_e32 v99, s90, v241
	v_add_u32_e32 v253, s90, v242
	v_add_u32_e32 v254, s90, v101
	v_add_u32_e32 v255, s90, v150
	v_med3_i32 v80, v80, 0, s99
	v_med3_i32 v83, v83, 0, s99
	v_med3_i32 v99, v99, 0, s99
	v_med3_i32 v253, v253, 0, s99
	v_med3_i32 v254, v254, 0, s99
	v_med3_i32 v255, v255, 0, s99
	v_mad_u32_u24 v80, v80, s100, v252
	v_mad_u32_u24 v83, v83, s100, v252
	v_mad_u32_u24 v99, v99, s100, v252
	v_mad_u32_u24 v253, v253, s100, v252
	v_mad_u32_u24 v254, v254, s100, v153
	v_mad_u32_u24 v255, v255, s100, v153
	global_load_dwordx4 v[156:159], v80, s[82:83]
	global_load_dwordx4 v[160:163], v83, s[82:83]
	global_load_dwordx4 v[164:167], v99, s[82:83]
	global_load_dwordx4 v[168:171], v253, s[82:83]
	global_load_dwordx4 v[172:175], v254, s[82:83] offset:768
	global_load_dwordx4 v[176:179], v255, s[82:83] offset:768
	global_load_dwordx4 v[180:183], v254, s[82:83] offset:832
	global_load_dwordx4 v[184:187], v255, s[82:83] offset:832
	ds_read_b64_tr_b16 v[72:73], v231
	ds_read_b64_tr_b16 v[74:75], v231 offset:512
	ds_read_b64_tr_b16 v[76:77], v231 offset:2048
	ds_read_b64_tr_b16 v[78:79], v231 offset:2560
	ds_read_b64_tr_b16 v[220:221], v231 offset:1024
	ds_read_b64_tr_b16 v[222:223], v231 offset:1536
	ds_read_b64_tr_b16 v[224:225], v231 offset:3072
	ds_read_b64_tr_b16 v[226:227], v231 offset:3584
	v_exp_f32_e32 v188, v188
	v_exp_f32_e32 v189, v189
	v_exp_f32_e32 v190, v190
	v_exp_f32_e32 v191, v191
	s_waitcnt vmcnt(8)
	ds_write_b128 v247, v[116:119]
	ds_write_b128 v247, v[120:123] offset:1024
	ds_write_b128 v247, v[124:127] offset:2048
	ds_write_b128 v247, v[128:131] offset:3072
	ds_read_b128 v[116:119], v248
	ds_read_b128 v[120:123], v249
	ds_read_b128 v[124:127], v250
	ds_read_b128 v[128:131], v251
	ds_write_b128 v112, v[132:135]
	ds_write_b128 v112, v[136:139] offset:1024
	ds_write_b128 v112, v[140:143] offset:2048
	ds_write_b128 v112, v[144:147] offset:3072
	v_exp_f32_e32 v192, v192
	v_exp_f32_e32 v193, v193
	v_exp_f32_e32 v194, v194
	v_exp_f32_e32 v195, v195
	s_waitcnt lgkmcnt(4)
	v_mfma_f32_32x32x16_bf16 v[32:47], v[116:119], v[48:51], v[32:47]
	v_exp_f32_e32 v196, v196
	v_exp_f32_e32 v197, v197
	v_mfma_f32_32x32x16_bf16 v[32:47], v[120:123], v[52:55], v[32:47]
	v_exp_f32_e32 v198, v198
	v_exp_f32_e32 v199, v199
	v_mfma_f32_32x32x16_bf16 v[32:47], v[124:127], v[56:59], v[32:47]
	v_exp_f32_e32 v200, v200
	v_exp_f32_e32 v201, v201
	v_mfma_f32_32x32x16_bf16 v[32:47], v[128:131], v[60:63], v[32:47]
	v_exp_f32_e32 v202, v202
	v_exp_f32_e32 v203, v203
	s_add_i32 s90, s67, 544
	v_add_u32_e32 v84, s90, v107
	v_add_u32_e32 v85, 0, v84
	v_add_u32_e32 v86, 1, v84
	v_add_u32_e32 v87, 2, v84
	v_add_u32_e32 v88, 3, v84
	v_cmp_gt_u32_e64 s[30:31], s98, v85
	v_cmp_gt_u32_e64 s[36:37], s98, v86
	v_cmp_gt_u32_e64 s[78:79], s98, v87
	v_cmp_gt_u32_e64 s[50:51], s98, v88
	v_cndmask_b32_e64 v188, 0, v188, s[30:31]
	v_add_u32_e32 v85, 8, v84
	v_cmp_gt_u32_e64 s[30:31], s98, v85
	v_cndmask_b32_e64 v189, 0, v189, s[36:37]
	v_add_u32_e32 v86, 9, v84
	v_cmp_gt_u32_e64 s[36:37], s98, v86
	v_cndmask_b32_e64 v190, 0, v190, s[78:79]
	v_add_u32_e32 v87, 10, v84
	v_cmp_gt_u32_e64 s[78:79], s98, v87
	v_cndmask_b32_e64 v191, 0, v191, s[50:51]
	v_add_u32_e32 v88, 11, v84
	v_cmp_gt_u32_e64 s[50:51], s98, v88
	v_cndmask_b32_e64 v192, 0, v192, s[30:31]
	v_add_u32_e32 v85, 16, v84
	v_cmp_gt_u32_e64 s[30:31], s98, v85
	v_cndmask_b32_e64 v193, 0, v193, s[36:37]
	v_add_u32_e32 v86, 17, v84
	v_cmp_gt_u32_e64 s[36:37], s98, v86
	v_cndmask_b32_e64 v194, 0, v194, s[78:79]
	v_add_u32_e32 v87, 18, v84
	v_cmp_gt_u32_e64 s[78:79], s98, v87
	v_cndmask_b32_e64 v195, 0, v195, s[50:51]
	v_add_u32_e32 v88, 19, v84
	v_cmp_gt_u32_e64 s[50:51], s98, v88
	v_cndmask_b32_e64 v196, 0, v196, s[30:31]
	v_add_u32_e32 v85, 24, v84
	v_cmp_gt_u32_e64 s[30:31], s98, v85
	v_cndmask_b32_e64 v197, 0, v197, s[36:37]
	v_add_u32_e32 v86, 25, v84
	v_cmp_gt_u32_e64 s[36:37], s98, v86
	v_cndmask_b32_e64 v198, 0, v198, s[78:79]
	v_add_u32_e32 v87, 26, v84
	v_cmp_gt_u32_e64 s[78:79], s98, v87
	v_cndmask_b32_e64 v199, 0, v199, s[50:51]
	v_add_u32_e32 v88, 27, v84
	v_cmp_gt_u32_e64 s[50:51], s98, v88
	v_nop
	v_cndmask_b32_e64 v200, 0, v200, s[30:31]
	v_cndmask_b32_e64 v201, 0, v201, s[36:37]
	v_cndmask_b32_e64 v202, 0, v202, s[78:79]
	v_cndmask_b32_e64 v203, 0, v203, s[50:51]
	v_cvt_pk_bf16_f32 v64, v188, v189
	v_cvt_pk_bf16_f32 v65, v190, v191
	v_cvt_pk_bf16_f32 v66, v192, v193
	v_cvt_pk_bf16_f32 v67, v194, v195
	v_cvt_pk_bf16_f32 v68, v196, v197
	v_cvt_pk_bf16_f32 v69, v198, v199
	v_cvt_pk_bf16_f32 v70, v200, v201
	v_cvt_pk_bf16_f32 v71, v202, v203
	v_pk_add_f32 v[232:233], v[232:233], v[188:189]
	v_pk_add_f32 v[232:233], v[232:233], v[190:191]
	v_pk_add_f32 v[232:233], v[232:233], v[192:193]
	v_pk_add_f32 v[232:233], v[232:233], v[194:195]
	v_pk_add_f32 v[232:233], v[232:233], v[196:197]
	v_pk_add_f32 v[232:233], v[232:233], v[198:199]
	v_pk_add_f32 v[232:233], v[232:233], v[200:201]
	v_pk_add_f32 v[232:233], v[232:233], v[202:203]
	ds_read2_b32 v[188:189], v115 offset0:32 offset1:33
	ds_read2_b32 v[190:191], v115 offset0:34 offset1:35
	ds_read2_b32 v[192:193], v115 offset0:40 offset1:41
	ds_read2_b32 v[194:195], v115 offset0:42 offset1:43
	ds_read2_b32 v[196:197], v115 offset0:48 offset1:49
	ds_read2_b32 v[198:199], v115 offset0:50 offset1:51
	ds_read2_b32 v[200:201], v115 offset0:56 offset1:57
	ds_read2_b32 v[202:203], v115 offset0:58 offset1:59
	v_mfma_f32_32x32x16_bf16 v[0:15], v[64:67], v[72:75], v[0:15]
	v_mfma_f32_32x32x16_bf16 v[16:31], v[64:67], v[76:79], v[16:31]
	v_mfma_f32_32x32x16_bf16 v[0:15], v[68:71], v[220:223], v[0:15]
	v_mfma_f32_32x32x16_bf16 v[16:31], v[68:71], v[224:227], v[16:31]
	s_add_i32 s90, s67, 0
	v_add_u32_e32 v80, s90, v239
	v_add_u32_e32 v83, s90, v240
	v_add_u32_e32 v99, s90, v241
	v_add_u32_e32 v253, s90, v242
	v_add_u32_e32 v254, s90, v101
	v_add_u32_e32 v255, s90, v150
	v_med3_i32 v80, v80, 0, s99
	v_med3_i32 v83, v83, 0, s99
	v_med3_i32 v99, v99, 0, s99
	v_med3_i32 v253, v253, 0, s99
	v_med3_i32 v254, v254, 0, s99
	v_med3_i32 v255, v255, 0, s99
	v_mad_u32_u24 v80, v80, s100, v252
	v_mad_u32_u24 v83, v83, s100, v252
	v_mad_u32_u24 v99, v99, s100, v252
	v_mad_u32_u24 v253, v253, s100, v252
	v_mad_u32_u24 v254, v254, s100, v153
	v_mad_u32_u24 v255, v255, s100, v153
	global_load_dwordx4 v[116:119], v80, s[82:83]
	global_load_dwordx4 v[120:123], v83, s[82:83]
	global_load_dwordx4 v[124:127], v99, s[82:83]
	global_load_dwordx4 v[128:131], v253, s[82:83]
	global_load_dwordx4 v[132:135], v254, s[82:83] offset:768
	global_load_dwordx4 v[136:139], v255, s[82:83] offset:768
	global_load_dwordx4 v[140:143], v254, s[82:83] offset:832
	global_load_dwordx4 v[144:147], v255, s[82:83] offset:832
	ds_read_b64_tr_b16 v[72:73], v231
	ds_read_b64_tr_b16 v[74:75], v231 offset:512
	ds_read_b64_tr_b16 v[76:77], v231 offset:2048
	ds_read_b64_tr_b16 v[78:79], v231 offset:2560
	ds_read_b64_tr_b16 v[220:221], v231 offset:1024
	ds_read_b64_tr_b16 v[222:223], v231 offset:1536
	ds_read_b64_tr_b16 v[224:225], v231 offset:3072
	ds_read_b64_tr_b16 v[226:227], v231 offset:3584
	v_exp_f32_e32 v32, v32
	v_exp_f32_e32 v33, v33
	v_exp_f32_e32 v34, v34
	v_exp_f32_e32 v35, v35
	s_waitcnt vmcnt(8)
	ds_write_b128 v247, v[156:159]
	ds_write_b128 v247, v[160:163] offset:1024
	ds_write_b128 v247, v[164:167] offset:2048
	ds_write_b128 v247, v[168:171] offset:3072
	ds_read_b128 v[156:159], v248
	ds_read_b128 v[160:163], v249
	ds_read_b128 v[164:167], v250
	ds_read_b128 v[168:171], v251
	ds_write_b128 v112, v[172:175]
	ds_write_b128 v112, v[176:179] offset:1024
	ds_write_b128 v112, v[180:183] offset:2048
	ds_write_b128 v112, v[184:187] offset:3072
	v_exp_f32_e32 v36, v36
	v_exp_f32_e32 v37, v37
	v_exp_f32_e32 v38, v38
	v_exp_f32_e32 v39, v39
	s_waitcnt lgkmcnt(4)
	v_mfma_f32_32x32x16_bf16 v[188:203], v[156:159], v[48:51], v[188:203]
	v_exp_f32_e32 v40, v40
	v_exp_f32_e32 v41, v41
	v_mfma_f32_32x32x16_bf16 v[188:203], v[160:163], v[52:55], v[188:203]
	v_exp_f32_e32 v42, v42
	v_exp_f32_e32 v43, v43
	v_mfma_f32_32x32x16_bf16 v[188:203], v[164:167], v[56:59], v[188:203]
	v_exp_f32_e32 v44, v44
	v_exp_f32_e32 v45, v45
	v_mfma_f32_32x32x16_bf16 v[188:203], v[168:171], v[60:63], v[188:203]
	v_exp_f32_e32 v46, v46
	v_exp_f32_e32 v47, v47
	s_add_i32 s90, s67, -256
	v_lshlrev_b32_e32 v84, 2, v107
	v_add_u32_e32 v84, s90, v84
	v_add_u32_e32 v85, 0, v84
	v_add_u32_e32 v86, 4, v84
	v_add_u32_e32 v87, 8, v84
	v_add_u32_e32 v88, 12, v84
	v_cmp_gt_u32_e64 s[30:31], s98, v85
	v_cmp_gt_u32_e64 s[36:37], s98, v86
	v_cmp_gt_u32_e64 s[78:79], s98, v87
	v_cmp_gt_u32_e64 s[50:51], s98, v88
	v_cndmask_b32_e64 v32, 0, v32, s[30:31]
	v_add_u32_e32 v85, 32, v84
	v_cmp_gt_u32_e64 s[30:31], s98, v85
	v_cndmask_b32_e64 v33, 0, v33, s[36:37]
	v_add_u32_e32 v86, 36, v84
	v_cmp_gt_u32_e64 s[36:37], s98, v86
	v_cndmask_b32_e64 v34, 0, v34, s[78:79]
	v_add_u32_e32 v87, 40, v84
	v_cmp_gt_u32_e64 s[78:79], s98, v87
	v_cndmask_b32_e64 v35, 0, v35, s[50:51]
	v_add_u32_e32 v88, 44, v84
	v_cmp_gt_u32_e64 s[50:51], s98, v88
	v_cndmask_b32_e64 v36, 0, v36, s[30:31]
	v_add_u32_e32 v85, 64, v84
	v_cmp_gt_u32_e64 s[30:31], s98, v85
	v_cndmask_b32_e64 v37, 0, v37, s[36:37]
	v_add_u32_e32 v86, 68, v84
	v_cmp_gt_u32_e64 s[36:37], s98, v86
	v_cndmask_b32_e64 v38, 0, v38, s[78:79]
	v_add_u32_e32 v87, 72, v84
	v_cmp_gt_u32_e64 s[78:79], s98, v87
	v_cndmask_b32_e64 v39, 0, v39, s[50:51]
	v_add_u32_e32 v88, 76, v84
	v_cmp_gt_u32_e64 s[50:51], s98, v88
	v_cndmask_b32_e64 v40, 0, v40, s[30:31]
	v_add_u32_e32 v85, 96, v84
	v_cmp_gt_u32_e64 s[30:31], s98, v85
	v_cndmask_b32_e64 v41, 0, v41, s[36:37]
	v_add_u32_e32 v86, 100, v84
	v_cmp_gt_u32_e64 s[36:37], s98, v86
	v_cndmask_b32_e64 v42, 0, v42, s[78:79]
	v_add_u32_e32 v87, 104, v84
	v_cmp_gt_u32_e64 s[78:79], s98, v87
	v_cndmask_b32_e64 v43, 0, v43, s[50:51]
	v_add_u32_e32 v88, 108, v84
	v_cmp_gt_u32_e64 s[50:51], s98, v88
	v_nop
	v_cndmask_b32_e64 v44, 0, v44, s[30:31]
	v_cndmask_b32_e64 v45, 0, v45, s[36:37]
	v_cndmask_b32_e64 v46, 0, v46, s[78:79]
	v_cndmask_b32_e64 v47, 0, v47, s[50:51]
	v_cvt_pk_bf16_f32 v64, v32, v33
	v_cvt_pk_bf16_f32 v65, v34, v35
	v_cvt_pk_bf16_f32 v66, v36, v37
	v_cvt_pk_bf16_f32 v67, v38, v39
	v_cvt_pk_bf16_f32 v68, v40, v41
	v_cvt_pk_bf16_f32 v69, v42, v43
	v_cvt_pk_bf16_f32 v70, v44, v45
	v_cvt_pk_bf16_f32 v71, v46, v47
	v_pk_add_f32 v[232:233], v[232:233], v[32:33]
	v_pk_add_f32 v[232:233], v[232:233], v[34:35]
	v_pk_add_f32 v[232:233], v[232:233], v[36:37]
	v_pk_add_f32 v[232:233], v[232:233], v[38:39]
	v_pk_add_f32 v[232:233], v[232:233], v[40:41]
	v_pk_add_f32 v[232:233], v[232:233], v[42:43]
	v_pk_add_f32 v[232:233], v[232:233], v[44:45]
	v_pk_add_f32 v[232:233], v[232:233], v[46:47]
	ds_read2_b32 v[32:33], v115 offset0:64 offset1:65
	ds_read2_b32 v[34:35], v115 offset0:66 offset1:67
	ds_read2_b32 v[36:37], v115 offset0:72 offset1:73
	ds_read2_b32 v[38:39], v115 offset0:74 offset1:75
	ds_read2_b32 v[40:41], v115 offset0:80 offset1:81
	ds_read2_b32 v[42:43], v115 offset0:82 offset1:83
	ds_read2_b32 v[44:45], v115 offset0:88 offset1:89
	ds_read2_b32 v[46:47], v115 offset0:90 offset1:91
	v_mfma_f32_32x32x16_bf16 v[0:15], v[64:67], v[72:75], v[0:15]
	v_mfma_f32_32x32x16_bf16 v[16:31], v[64:67], v[76:79], v[16:31]
	v_mfma_f32_32x32x16_bf16 v[0:15], v[68:71], v[220:223], v[0:15]
	v_mfma_f32_32x32x16_bf16 v[16:31], v[68:71], v[224:227], v[16:31]
	s_add_i32 s90, s67, 128
	v_add_u32_e32 v80, s90, v239
	v_add_u32_e32 v83, s90, v240
	v_add_u32_e32 v99, s90, v241
	v_add_u32_e32 v253, s90, v242
	v_add_u32_e32 v254, s90, v101
	v_add_u32_e32 v255, s90, v150
	v_med3_i32 v80, v80, 0, s99
	v_med3_i32 v83, v83, 0, s99
	v_med3_i32 v99, v99, 0, s99
	v_med3_i32 v253, v253, 0, s99
	v_med3_i32 v254, v254, 0, s99
	v_med3_i32 v255, v255, 0, s99
	v_mad_u32_u24 v80, v80, s100, v252
	v_mad_u32_u24 v83, v83, s100, v252
	v_mad_u32_u24 v99, v99, s100, v252
	v_mad_u32_u24 v253, v253, s100, v252
	v_mad_u32_u24 v254, v254, s100, v153
	v_mad_u32_u24 v255, v255, s100, v153
	global_load_dwordx4 v[156:159], v80, s[82:83]
	global_load_dwordx4 v[160:163], v83, s[82:83]
	global_load_dwordx4 v[164:167], v99, s[82:83]
	global_load_dwordx4 v[168:171], v253, s[82:83]
	global_load_dwordx4 v[172:175], v254, s[82:83] offset:768
	global_load_dwordx4 v[176:179], v255, s[82:83] offset:768
	global_load_dwordx4 v[180:183], v254, s[82:83] offset:832
	global_load_dwordx4 v[184:187], v255, s[82:83] offset:832
	ds_read_b64_tr_b16 v[72:73], v231
	ds_read_b64_tr_b16 v[74:75], v231 offset:512
	ds_read_b64_tr_b16 v[76:77], v231 offset:2048
	ds_read_b64_tr_b16 v[78:79], v231 offset:2560
	ds_read_b64_tr_b16 v[220:221], v231 offset:1024
	ds_read_b64_tr_b16 v[222:223], v231 offset:1536
	ds_read_b64_tr_b16 v[224:225], v231 offset:3072
	ds_read_b64_tr_b16 v[226:227], v231 offset:3584
	v_exp_f32_e32 v188, v188
	v_exp_f32_e32 v189, v189
	v_exp_f32_e32 v190, v190
	v_exp_f32_e32 v191, v191
	s_waitcnt vmcnt(8)
	ds_write_b128 v247, v[116:119]
	ds_write_b128 v247, v[120:123] offset:1024
	ds_write_b128 v247, v[124:127] offset:2048
	ds_write_b128 v247, v[128:131] offset:3072
	ds_read_b128 v[116:119], v248
	ds_read_b128 v[120:123], v249
	ds_read_b128 v[124:127], v250
	ds_read_b128 v[128:131], v251
	ds_write_b128 v112, v[132:135]
	ds_write_b128 v112, v[136:139] offset:1024
	ds_write_b128 v112, v[140:143] offset:2048
	ds_write_b128 v112, v[144:147] offset:3072
	v_exp_f32_e32 v192, v192
	v_exp_f32_e32 v193, v193
	v_exp_f32_e32 v194, v194
	v_exp_f32_e32 v195, v195
	s_waitcnt lgkmcnt(4)
	v_mfma_f32_32x32x16_bf16 v[32:47], v[116:119], v[48:51], v[32:47]
	v_exp_f32_e32 v196, v196
	v_exp_f32_e32 v197, v197
	v_mfma_f32_32x32x16_bf16 v[32:47], v[120:123], v[52:55], v[32:47]
	v_exp_f32_e32 v198, v198
	v_exp_f32_e32 v199, v199
	v_mfma_f32_32x32x16_bf16 v[32:47], v[124:127], v[56:59], v[32:47]
	v_exp_f32_e32 v200, v200
	v_exp_f32_e32 v201, v201
	v_mfma_f32_32x32x16_bf16 v[32:47], v[128:131], v[60:63], v[32:47]
	v_exp_f32_e32 v202, v202
	v_exp_f32_e32 v203, v203
	s_add_i32 s90, s67, -128
	v_lshlrev_b32_e32 v84, 2, v107
	v_add_u32_e32 v84, s90, v84
	v_add_u32_e32 v85, 0, v84
	v_add_u32_e32 v86, 4, v84
	v_add_u32_e32 v87, 8, v84
	v_add_u32_e32 v88, 12, v84
	v_cmp_gt_u32_e64 s[30:31], s98, v85
	v_cmp_gt_u32_e64 s[36:37], s98, v86
	v_cmp_gt_u32_e64 s[78:79], s98, v87
	v_cmp_gt_u32_e64 s[50:51], s98, v88
	v_cndmask_b32_e64 v188, 0, v188, s[30:31]
	v_add_u32_e32 v85, 32, v84
	v_cmp_gt_u32_e64 s[30:31], s98, v85
	v_cndmask_b32_e64 v189, 0, v189, s[36:37]
	v_add_u32_e32 v86, 36, v84
	v_cmp_gt_u32_e64 s[36:37], s98, v86
	v_cndmask_b32_e64 v190, 0, v190, s[78:79]
	v_add_u32_e32 v87, 40, v84
	v_cmp_gt_u32_e64 s[78:79], s98, v87
	v_cndmask_b32_e64 v191, 0, v191, s[50:51]
	v_add_u32_e32 v88, 44, v84
	v_cmp_gt_u32_e64 s[50:51], s98, v88
	v_cndmask_b32_e64 v192, 0, v192, s[30:31]
	v_add_u32_e32 v85, 64, v84
	v_cmp_gt_u32_e64 s[30:31], s98, v85
	v_cndmask_b32_e64 v193, 0, v193, s[36:37]
	v_add_u32_e32 v86, 68, v84
	v_cmp_gt_u32_e64 s[36:37], s98, v86
	v_cndmask_b32_e64 v194, 0, v194, s[78:79]
	v_add_u32_e32 v87, 72, v84
	v_cmp_gt_u32_e64 s[78:79], s98, v87
	v_cndmask_b32_e64 v195, 0, v195, s[50:51]
	v_add_u32_e32 v88, 76, v84
	v_cmp_gt_u32_e64 s[50:51], s98, v88
	v_cndmask_b32_e64 v196, 0, v196, s[30:31]
	v_add_u32_e32 v85, 96, v84
	v_cmp_gt_u32_e64 s[30:31], s98, v85
	v_cndmask_b32_e64 v197, 0, v197, s[36:37]
	v_add_u32_e32 v86, 100, v84
	v_cmp_gt_u32_e64 s[36:37], s98, v86
	v_cndmask_b32_e64 v198, 0, v198, s[78:79]
	v_add_u32_e32 v87, 104, v84
	v_cmp_gt_u32_e64 s[78:79], s98, v87
	v_cndmask_b32_e64 v199, 0, v199, s[50:51]
	v_add_u32_e32 v88, 108, v84
	v_cmp_gt_u32_e64 s[50:51], s98, v88
	v_nop
	v_cndmask_b32_e64 v200, 0, v200, s[30:31]
	v_cndmask_b32_e64 v201, 0, v201, s[36:37]
	v_cndmask_b32_e64 v202, 0, v202, s[78:79]
	v_cndmask_b32_e64 v203, 0, v203, s[50:51]
	v_cvt_pk_bf16_f32 v64, v188, v189
	v_cvt_pk_bf16_f32 v65, v190, v191
	v_cvt_pk_bf16_f32 v66, v192, v193
	v_cvt_pk_bf16_f32 v67, v194, v195
	v_cvt_pk_bf16_f32 v68, v196, v197
	v_cvt_pk_bf16_f32 v69, v198, v199
	v_cvt_pk_bf16_f32 v70, v200, v201
	v_cvt_pk_bf16_f32 v71, v202, v203
	v_pk_add_f32 v[232:233], v[232:233], v[188:189]
	v_pk_add_f32 v[232:233], v[232:233], v[190:191]
	v_pk_add_f32 v[232:233], v[232:233], v[192:193]
	v_pk_add_f32 v[232:233], v[232:233], v[194:195]
	v_pk_add_f32 v[232:233], v[232:233], v[196:197]
	v_pk_add_f32 v[232:233], v[232:233], v[198:199]
	v_pk_add_f32 v[232:233], v[232:233], v[200:201]
	v_pk_add_f32 v[232:233], v[232:233], v[202:203]
	ds_read2_b32 v[188:189], v115 offset0:96 offset1:97
	ds_read2_b32 v[190:191], v115 offset0:98 offset1:99
	ds_read2_b32 v[192:193], v115 offset0:104 offset1:105
	ds_read2_b32 v[194:195], v115 offset0:106 offset1:107
	ds_read2_b32 v[196:197], v115 offset0:112 offset1:113
	ds_read2_b32 v[198:199], v115 offset0:114 offset1:115
	ds_read2_b32 v[200:201], v115 offset0:120 offset1:121
	ds_read2_b32 v[202:203], v115 offset0:122 offset1:123
	v_mfma_f32_32x32x16_bf16 v[0:15], v[64:67], v[72:75], v[0:15]
	v_mfma_f32_32x32x16_bf16 v[16:31], v[64:67], v[76:79], v[16:31]
	v_mfma_f32_32x32x16_bf16 v[0:15], v[68:71], v[220:223], v[0:15]
	v_mfma_f32_32x32x16_bf16 v[16:31], v[68:71], v[224:227], v[16:31]
	s_add_i32 s90, s67, 256
	v_add_u32_e32 v80, s90, v239
	v_add_u32_e32 v83, s90, v240
	v_add_u32_e32 v99, s90, v241
	v_add_u32_e32 v253, s90, v242
	v_add_u32_e32 v254, s90, v101
	v_add_u32_e32 v255, s90, v150
	v_med3_i32 v80, v80, 0, s99
	v_med3_i32 v83, v83, 0, s99
	v_med3_i32 v99, v99, 0, s99
	v_med3_i32 v253, v253, 0, s99
	v_med3_i32 v254, v254, 0, s99
	v_med3_i32 v255, v255, 0, s99
	v_mad_u32_u24 v80, v80, s100, v252
	v_mad_u32_u24 v83, v83, s100, v252
	v_mad_u32_u24 v99, v99, s100, v252
	v_mad_u32_u24 v253, v253, s100, v252
	v_mad_u32_u24 v254, v254, s100, v153
	v_mad_u32_u24 v255, v255, s100, v153
	global_load_dwordx4 v[116:119], v80, s[82:83]
	global_load_dwordx4 v[120:123], v83, s[82:83]
	global_load_dwordx4 v[124:127], v99, s[82:83]
	global_load_dwordx4 v[128:131], v253, s[82:83]
	global_load_dwordx4 v[132:135], v254, s[82:83] offset:768
	global_load_dwordx4 v[136:139], v255, s[82:83] offset:768
	global_load_dwordx4 v[140:143], v254, s[82:83] offset:832
	global_load_dwordx4 v[144:147], v255, s[82:83] offset:832
	ds_read_b64_tr_b16 v[72:73], v231
	ds_read_b64_tr_b16 v[74:75], v231 offset:512
	ds_read_b64_tr_b16 v[76:77], v231 offset:2048
	ds_read_b64_tr_b16 v[78:79], v231 offset:2560
	ds_read_b64_tr_b16 v[220:221], v231 offset:1024
	ds_read_b64_tr_b16 v[222:223], v231 offset:1536
	ds_read_b64_tr_b16 v[224:225], v231 offset:3072
	ds_read_b64_tr_b16 v[226:227], v231 offset:3584
	v_exp_f32_e32 v32, v32
	v_exp_f32_e32 v33, v33
	v_exp_f32_e32 v34, v34
	v_exp_f32_e32 v35, v35
	s_waitcnt vmcnt(8)
	ds_write_b128 v247, v[156:159]
	ds_write_b128 v247, v[160:163] offset:1024
	ds_write_b128 v247, v[164:167] offset:2048
	ds_write_b128 v247, v[168:171] offset:3072
	ds_read_b128 v[156:159], v248
	ds_read_b128 v[160:163], v249
	ds_read_b128 v[164:167], v250
	ds_read_b128 v[168:171], v251
	ds_write_b128 v112, v[172:175]
	ds_write_b128 v112, v[176:179] offset:1024
	ds_write_b128 v112, v[180:183] offset:2048
	ds_write_b128 v112, v[184:187] offset:3072
	v_exp_f32_e32 v36, v36
	v_exp_f32_e32 v37, v37
	v_exp_f32_e32 v38, v38
	v_exp_f32_e32 v39, v39
	s_waitcnt lgkmcnt(4)
	v_mfma_f32_32x32x16_bf16 v[188:203], v[156:159], v[48:51], v[188:203]
	v_exp_f32_e32 v40, v40
	v_exp_f32_e32 v41, v41
	v_mfma_f32_32x32x16_bf16 v[188:203], v[160:163], v[52:55], v[188:203]
	v_exp_f32_e32 v42, v42
	v_exp_f32_e32 v43, v43
	v_mfma_f32_32x32x16_bf16 v[188:203], v[164:167], v[56:59], v[188:203]
	v_exp_f32_e32 v44, v44
	v_exp_f32_e32 v45, v45
	v_mfma_f32_32x32x16_bf16 v[188:203], v[168:171], v[60:63], v[188:203]
	v_exp_f32_e32 v46, v46
	v_exp_f32_e32 v47, v47
	s_add_i32 s90, s67, 0
	v_lshlrev_b32_e32 v84, 2, v107
	v_add_u32_e32 v84, s90, v84
	v_add_u32_e32 v85, 0, v84
	v_add_u32_e32 v86, 4, v84
	v_add_u32_e32 v87, 8, v84
	v_add_u32_e32 v88, 12, v84
	v_cmp_gt_u32_e64 s[30:31], s98, v85
	v_cmp_gt_u32_e64 s[36:37], s98, v86
	v_cmp_gt_u32_e64 s[78:79], s98, v87
	v_cmp_gt_u32_e64 s[50:51], s98, v88
	v_cndmask_b32_e64 v32, 0, v32, s[30:31]
	v_add_u32_e32 v85, 32, v84
	v_cmp_gt_u32_e64 s[30:31], s98, v85
	v_cndmask_b32_e64 v33, 0, v33, s[36:37]
	v_add_u32_e32 v86, 36, v84
	v_cmp_gt_u32_e64 s[36:37], s98, v86
	v_cndmask_b32_e64 v34, 0, v34, s[78:79]
	v_add_u32_e32 v87, 40, v84
	v_cmp_gt_u32_e64 s[78:79], s98, v87
	v_cndmask_b32_e64 v35, 0, v35, s[50:51]
	v_add_u32_e32 v88, 44, v84
	v_cmp_gt_u32_e64 s[50:51], s98, v88
	v_cndmask_b32_e64 v36, 0, v36, s[30:31]
	v_add_u32_e32 v85, 64, v84
	v_cmp_gt_u32_e64 s[30:31], s98, v85
	v_cndmask_b32_e64 v37, 0, v37, s[36:37]
	v_add_u32_e32 v86, 68, v84
	v_cmp_gt_u32_e64 s[36:37], s98, v86
	v_cndmask_b32_e64 v38, 0, v38, s[78:79]
	v_add_u32_e32 v87, 72, v84
	v_cmp_gt_u32_e64 s[78:79], s98, v87
	v_cndmask_b32_e64 v39, 0, v39, s[50:51]
	v_add_u32_e32 v88, 76, v84
	v_cmp_gt_u32_e64 s[50:51], s98, v88
	v_cndmask_b32_e64 v40, 0, v40, s[30:31]
	v_add_u32_e32 v85, 96, v84
	v_cmp_gt_u32_e64 s[30:31], s98, v85
	v_cndmask_b32_e64 v41, 0, v41, s[36:37]
	v_add_u32_e32 v86, 100, v84
	v_cmp_gt_u32_e64 s[36:37], s98, v86
	v_cndmask_b32_e64 v42, 0, v42, s[78:79]
	v_add_u32_e32 v87, 104, v84
	v_cmp_gt_u32_e64 s[78:79], s98, v87
	v_cndmask_b32_e64 v43, 0, v43, s[50:51]
	v_add_u32_e32 v88, 108, v84
	v_cmp_gt_u32_e64 s[50:51], s98, v88
	v_nop
	v_cndmask_b32_e64 v44, 0, v44, s[30:31]
	v_cndmask_b32_e64 v45, 0, v45, s[36:37]
	v_cndmask_b32_e64 v46, 0, v46, s[78:79]
	v_cndmask_b32_e64 v47, 0, v47, s[50:51]
	v_cvt_pk_bf16_f32 v64, v32, v33
	v_cvt_pk_bf16_f32 v65, v34, v35
	v_cvt_pk_bf16_f32 v66, v36, v37
	v_cvt_pk_bf16_f32 v67, v38, v39
	v_cvt_pk_bf16_f32 v68, v40, v41
	v_cvt_pk_bf16_f32 v69, v42, v43
	v_cvt_pk_bf16_f32 v70, v44, v45
	v_cvt_pk_bf16_f32 v71, v46, v47
	v_pk_add_f32 v[232:233], v[232:233], v[32:33]
	v_pk_add_f32 v[232:233], v[232:233], v[34:35]
	v_pk_add_f32 v[232:233], v[232:233], v[36:37]
	v_pk_add_f32 v[232:233], v[232:233], v[38:39]
	v_pk_add_f32 v[232:233], v[232:233], v[40:41]
	v_pk_add_f32 v[232:233], v[232:233], v[42:43]
	v_pk_add_f32 v[232:233], v[232:233], v[44:45]
	v_pk_add_f32 v[232:233], v[232:233], v[46:47]
	ds_read2_b32 v[32:33], v115 offset0:128 offset1:129
	ds_read2_b32 v[34:35], v115 offset0:130 offset1:131
	ds_read2_b32 v[36:37], v115 offset0:136 offset1:137
	ds_read2_b32 v[38:39], v115 offset0:138 offset1:139
	ds_read2_b32 v[40:41], v115 offset0:144 offset1:145
	ds_read2_b32 v[42:43], v115 offset0:146 offset1:147
	ds_read2_b32 v[44:45], v115 offset0:152 offset1:153
	ds_read2_b32 v[46:47], v115 offset0:154 offset1:155
	v_mfma_f32_32x32x16_bf16 v[0:15], v[64:67], v[72:75], v[0:15]
	v_mfma_f32_32x32x16_bf16 v[16:31], v[64:67], v[76:79], v[16:31]
	v_mfma_f32_32x32x16_bf16 v[0:15], v[68:71], v[220:223], v[0:15]
	v_mfma_f32_32x32x16_bf16 v[16:31], v[68:71], v[224:227], v[16:31]
	s_add_i32 s90, s67, 384
	v_add_u32_e32 v80, s90, v239
	v_add_u32_e32 v83, s90, v240
	v_add_u32_e32 v99, s90, v241
	v_add_u32_e32 v253, s90, v242
	v_add_u32_e32 v254, s90, v101
	v_add_u32_e32 v255, s90, v150
	v_med3_i32 v80, v80, 0, s99
	v_med3_i32 v83, v83, 0, s99
	v_med3_i32 v99, v99, 0, s99
	v_med3_i32 v253, v253, 0, s99
	v_med3_i32 v254, v254, 0, s99
	v_med3_i32 v255, v255, 0, s99
	v_mad_u32_u24 v80, v80, s100, v252
	v_mad_u32_u24 v83, v83, s100, v252
	v_mad_u32_u24 v99, v99, s100, v252
	v_mad_u32_u24 v253, v253, s100, v252
	v_mad_u32_u24 v254, v254, s100, v153
	v_mad_u32_u24 v255, v255, s100, v153
	global_load_dwordx4 v[156:159], v80, s[82:83]
	global_load_dwordx4 v[160:163], v83, s[82:83]
	global_load_dwordx4 v[164:167], v99, s[82:83]
	global_load_dwordx4 v[168:171], v253, s[82:83]
	global_load_dwordx4 v[172:175], v254, s[82:83] offset:768
	global_load_dwordx4 v[176:179], v255, s[82:83] offset:768
	global_load_dwordx4 v[180:183], v254, s[82:83] offset:832
	global_load_dwordx4 v[184:187], v255, s[82:83] offset:832
	ds_read_b64_tr_b16 v[72:73], v231
	ds_read_b64_tr_b16 v[74:75], v231 offset:512
	ds_read_b64_tr_b16 v[76:77], v231 offset:2048
	ds_read_b64_tr_b16 v[78:79], v231 offset:2560
	ds_read_b64_tr_b16 v[220:221], v231 offset:1024
	ds_read_b64_tr_b16 v[222:223], v231 offset:1536
	ds_read_b64_tr_b16 v[224:225], v231 offset:3072
	ds_read_b64_tr_b16 v[226:227], v231 offset:3584
	v_exp_f32_e32 v188, v188
	v_exp_f32_e32 v189, v189
	v_exp_f32_e32 v190, v190
	v_exp_f32_e32 v191, v191
	s_waitcnt vmcnt(8)
	ds_write_b128 v247, v[116:119]
	ds_write_b128 v247, v[120:123] offset:1024
	ds_write_b128 v247, v[124:127] offset:2048
	ds_write_b128 v247, v[128:131] offset:3072
	ds_read_b128 v[116:119], v248
	ds_read_b128 v[120:123], v249
	ds_read_b128 v[124:127], v250
	ds_read_b128 v[128:131], v251
	ds_write_b128 v112, v[132:135]
	ds_write_b128 v112, v[136:139] offset:1024
	ds_write_b128 v112, v[140:143] offset:2048
	ds_write_b128 v112, v[144:147] offset:3072
	v_exp_f32_e32 v192, v192
	v_exp_f32_e32 v193, v193
	v_exp_f32_e32 v194, v194
	v_exp_f32_e32 v195, v195
	s_waitcnt lgkmcnt(4)
	v_mfma_f32_32x32x16_bf16 v[32:47], v[116:119], v[48:51], v[32:47]
	v_exp_f32_e32 v196, v196
	v_exp_f32_e32 v197, v197
	v_mfma_f32_32x32x16_bf16 v[32:47], v[120:123], v[52:55], v[32:47]
	v_exp_f32_e32 v198, v198
	v_exp_f32_e32 v199, v199
	v_mfma_f32_32x32x16_bf16 v[32:47], v[124:127], v[56:59], v[32:47]
	v_exp_f32_e32 v200, v200
	v_exp_f32_e32 v201, v201
	v_mfma_f32_32x32x16_bf16 v[32:47], v[128:131], v[60:63], v[32:47]
	v_exp_f32_e32 v202, v202
	v_exp_f32_e32 v203, v203
	s_add_i32 s90, s67, 128
	v_lshlrev_b32_e32 v84, 2, v107
	v_add_u32_e32 v84, s90, v84
	v_add_u32_e32 v85, 0, v84
	v_add_u32_e32 v86, 4, v84
	v_add_u32_e32 v87, 8, v84
	v_add_u32_e32 v88, 12, v84
	v_cmp_gt_u32_e64 s[30:31], s98, v85
	v_cmp_gt_u32_e64 s[36:37], s98, v86
	v_cmp_gt_u32_e64 s[78:79], s98, v87
	v_cmp_gt_u32_e64 s[50:51], s98, v88
	v_cndmask_b32_e64 v188, 0, v188, s[30:31]
	v_add_u32_e32 v85, 32, v84
	v_cmp_gt_u32_e64 s[30:31], s98, v85
	v_cndmask_b32_e64 v189, 0, v189, s[36:37]
	v_add_u32_e32 v86, 36, v84
	v_cmp_gt_u32_e64 s[36:37], s98, v86
	v_cndmask_b32_e64 v190, 0, v190, s[78:79]
	v_add_u32_e32 v87, 40, v84
	v_cmp_gt_u32_e64 s[78:79], s98, v87
	v_cndmask_b32_e64 v191, 0, v191, s[50:51]
	v_add_u32_e32 v88, 44, v84
	v_cmp_gt_u32_e64 s[50:51], s98, v88
	v_cndmask_b32_e64 v192, 0, v192, s[30:31]
	v_add_u32_e32 v85, 64, v84
	v_cmp_gt_u32_e64 s[30:31], s98, v85
	v_cndmask_b32_e64 v193, 0, v193, s[36:37]
	v_add_u32_e32 v86, 68, v84
	v_cmp_gt_u32_e64 s[36:37], s98, v86
	v_cndmask_b32_e64 v194, 0, v194, s[78:79]
	v_add_u32_e32 v87, 72, v84
	v_cmp_gt_u32_e64 s[78:79], s98, v87
	v_cndmask_b32_e64 v195, 0, v195, s[50:51]
	v_add_u32_e32 v88, 76, v84
	v_cmp_gt_u32_e64 s[50:51], s98, v88
	v_cndmask_b32_e64 v196, 0, v196, s[30:31]
	v_add_u32_e32 v85, 96, v84
	v_cmp_gt_u32_e64 s[30:31], s98, v85
	v_cndmask_b32_e64 v197, 0, v197, s[36:37]
	v_add_u32_e32 v86, 100, v84
	v_cmp_gt_u32_e64 s[36:37], s98, v86
	v_cndmask_b32_e64 v198, 0, v198, s[78:79]
	v_add_u32_e32 v87, 104, v84
	v_cmp_gt_u32_e64 s[78:79], s98, v87
	v_cndmask_b32_e64 v199, 0, v199, s[50:51]
	v_add_u32_e32 v88, 108, v84
	v_cmp_gt_u32_e64 s[50:51], s98, v88
	v_nop
	v_cndmask_b32_e64 v200, 0, v200, s[30:31]
	v_cndmask_b32_e64 v201, 0, v201, s[36:37]
	v_cndmask_b32_e64 v202, 0, v202, s[78:79]
	v_cndmask_b32_e64 v203, 0, v203, s[50:51]
	v_cvt_pk_bf16_f32 v64, v188, v189
	v_cvt_pk_bf16_f32 v65, v190, v191
	v_cvt_pk_bf16_f32 v66, v192, v193
	v_cvt_pk_bf16_f32 v67, v194, v195
	v_cvt_pk_bf16_f32 v68, v196, v197
	v_cvt_pk_bf16_f32 v69, v198, v199
	v_cvt_pk_bf16_f32 v70, v200, v201
	v_cvt_pk_bf16_f32 v71, v202, v203
	v_pk_add_f32 v[232:233], v[232:233], v[188:189]
	v_pk_add_f32 v[232:233], v[232:233], v[190:191]
	v_pk_add_f32 v[232:233], v[232:233], v[192:193]
	v_pk_add_f32 v[232:233], v[232:233], v[194:195]
	v_pk_add_f32 v[232:233], v[232:233], v[196:197]
	v_pk_add_f32 v[232:233], v[232:233], v[198:199]
	v_pk_add_f32 v[232:233], v[232:233], v[200:201]
	v_pk_add_f32 v[232:233], v[232:233], v[202:203]
	ds_read2_b32 v[188:189], v115 offset0:160 offset1:161
	ds_read2_b32 v[190:191], v115 offset0:162 offset1:163
	ds_read2_b32 v[192:193], v115 offset0:168 offset1:169
	ds_read2_b32 v[194:195], v115 offset0:170 offset1:171
	ds_read2_b32 v[196:197], v115 offset0:176 offset1:177
	ds_read2_b32 v[198:199], v115 offset0:178 offset1:179
	ds_read2_b32 v[200:201], v115 offset0:184 offset1:185
	ds_read2_b32 v[202:203], v115 offset0:186 offset1:187
	v_mfma_f32_32x32x16_bf16 v[0:15], v[64:67], v[72:75], v[0:15]
	v_mfma_f32_32x32x16_bf16 v[16:31], v[64:67], v[76:79], v[16:31]
	v_mfma_f32_32x32x16_bf16 v[0:15], v[68:71], v[220:223], v[0:15]
	v_mfma_f32_32x32x16_bf16 v[16:31], v[68:71], v[224:227], v[16:31]
	s_add_i32 s90, s67, 512
	v_add_u32_e32 v80, s90, v239
	v_add_u32_e32 v83, s90, v240
	v_add_u32_e32 v99, s90, v241
	v_add_u32_e32 v253, s90, v242
	v_add_u32_e32 v254, s90, v101
	v_add_u32_e32 v255, s90, v150
	v_med3_i32 v80, v80, 0, s99
	v_med3_i32 v83, v83, 0, s99
	v_med3_i32 v99, v99, 0, s99
	v_med3_i32 v253, v253, 0, s99
	v_med3_i32 v254, v254, 0, s99
	v_med3_i32 v255, v255, 0, s99
	v_mad_u32_u24 v80, v80, s100, v252
	v_mad_u32_u24 v83, v83, s100, v252
	v_mad_u32_u24 v99, v99, s100, v252
	v_mad_u32_u24 v253, v253, s100, v252
	v_mad_u32_u24 v254, v254, s100, v153
	v_mad_u32_u24 v255, v255, s100, v153
	global_load_dwordx4 v[116:119], v80, s[82:83]
	global_load_dwordx4 v[120:123], v83, s[82:83]
	global_load_dwordx4 v[124:127], v99, s[82:83]
	global_load_dwordx4 v[128:131], v253, s[82:83]
	global_load_dwordx4 v[132:135], v254, s[82:83] offset:768
	global_load_dwordx4 v[136:139], v255, s[82:83] offset:768
	global_load_dwordx4 v[140:143], v254, s[82:83] offset:832
	global_load_dwordx4 v[144:147], v255, s[82:83] offset:832
	ds_read_b64_tr_b16 v[72:73], v231
	ds_read_b64_tr_b16 v[74:75], v231 offset:512
	ds_read_b64_tr_b16 v[76:77], v231 offset:2048
	ds_read_b64_tr_b16 v[78:79], v231 offset:2560
	ds_read_b64_tr_b16 v[220:221], v231 offset:1024
	ds_read_b64_tr_b16 v[222:223], v231 offset:1536
	ds_read_b64_tr_b16 v[224:225], v231 offset:3072
	ds_read_b64_tr_b16 v[226:227], v231 offset:3584
	v_exp_f32_e32 v32, v32
	v_exp_f32_e32 v33, v33
	v_exp_f32_e32 v34, v34
	v_exp_f32_e32 v35, v35
	s_waitcnt vmcnt(8)
	ds_write_b128 v247, v[156:159]
	ds_write_b128 v247, v[160:163] offset:1024
	ds_write_b128 v247, v[164:167] offset:2048
	ds_write_b128 v247, v[168:171] offset:3072
	ds_read_b128 v[156:159], v248
	ds_read_b128 v[160:163], v249
	ds_read_b128 v[164:167], v250
	ds_read_b128 v[168:171], v251
	ds_write_b128 v112, v[172:175]
	ds_write_b128 v112, v[176:179] offset:1024
	ds_write_b128 v112, v[180:183] offset:2048
	ds_write_b128 v112, v[184:187] offset:3072
	v_exp_f32_e32 v36, v36
	v_exp_f32_e32 v37, v37
	v_exp_f32_e32 v38, v38
	v_exp_f32_e32 v39, v39
	s_waitcnt lgkmcnt(4)
	v_mfma_f32_32x32x16_bf16 v[188:203], v[156:159], v[48:51], v[188:203]
	v_exp_f32_e32 v40, v40
	v_exp_f32_e32 v41, v41
	v_mfma_f32_32x32x16_bf16 v[188:203], v[160:163], v[52:55], v[188:203]
	v_exp_f32_e32 v42, v42
	v_exp_f32_e32 v43, v43
	v_mfma_f32_32x32x16_bf16 v[188:203], v[164:167], v[56:59], v[188:203]
	v_exp_f32_e32 v44, v44
	v_exp_f32_e32 v45, v45
	v_mfma_f32_32x32x16_bf16 v[188:203], v[168:171], v[60:63], v[188:203]
	v_exp_f32_e32 v46, v46
	v_exp_f32_e32 v47, v47
	s_add_i32 s90, s67, 256
	v_lshlrev_b32_e32 v84, 2, v107
	v_add_u32_e32 v84, s90, v84
	v_add_u32_e32 v85, 0, v84
	v_add_u32_e32 v86, 4, v84
	v_add_u32_e32 v87, 8, v84
	v_add_u32_e32 v88, 12, v84
	v_cmp_gt_u32_e64 s[30:31], s98, v85
	v_cmp_gt_u32_e64 s[36:37], s98, v86
	v_cmp_gt_u32_e64 s[78:79], s98, v87
	v_cmp_gt_u32_e64 s[50:51], s98, v88
	v_cndmask_b32_e64 v32, 0, v32, s[30:31]
	v_add_u32_e32 v85, 32, v84
	v_cmp_gt_u32_e64 s[30:31], s98, v85
	v_cndmask_b32_e64 v33, 0, v33, s[36:37]
	v_add_u32_e32 v86, 36, v84
	v_cmp_gt_u32_e64 s[36:37], s98, v86
	v_cndmask_b32_e64 v34, 0, v34, s[78:79]
	v_add_u32_e32 v87, 40, v84
	v_cmp_gt_u32_e64 s[78:79], s98, v87
	v_cndmask_b32_e64 v35, 0, v35, s[50:51]
	v_add_u32_e32 v88, 44, v84
	v_cmp_gt_u32_e64 s[50:51], s98, v88
	v_cndmask_b32_e64 v36, 0, v36, s[30:31]
	v_add_u32_e32 v85, 64, v84
	v_cmp_gt_u32_e64 s[30:31], s98, v85
	v_cndmask_b32_e64 v37, 0, v37, s[36:37]
	v_add_u32_e32 v86, 68, v84
	v_cmp_gt_u32_e64 s[36:37], s98, v86
	v_cndmask_b32_e64 v38, 0, v38, s[78:79]
	v_add_u32_e32 v87, 72, v84
	v_cmp_gt_u32_e64 s[78:79], s98, v87
	v_cndmask_b32_e64 v39, 0, v39, s[50:51]
	v_add_u32_e32 v88, 76, v84
	v_cmp_gt_u32_e64 s[50:51], s98, v88
	v_cndmask_b32_e64 v40, 0, v40, s[30:31]
	v_add_u32_e32 v85, 96, v84
	v_cmp_gt_u32_e64 s[30:31], s98, v85
	v_cndmask_b32_e64 v41, 0, v41, s[36:37]
	v_add_u32_e32 v86, 100, v84
	v_cmp_gt_u32_e64 s[36:37], s98, v86
	v_cndmask_b32_e64 v42, 0, v42, s[78:79]
	v_add_u32_e32 v87, 104, v84
	v_cmp_gt_u32_e64 s[78:79], s98, v87
	v_cndmask_b32_e64 v43, 0, v43, s[50:51]
	v_add_u32_e32 v88, 108, v84
	v_cmp_gt_u32_e64 s[50:51], s98, v88
	v_nop
	v_cndmask_b32_e64 v44, 0, v44, s[30:31]
	v_cndmask_b32_e64 v45, 0, v45, s[36:37]
	v_cndmask_b32_e64 v46, 0, v46, s[78:79]
	v_cndmask_b32_e64 v47, 0, v47, s[50:51]
	v_cvt_pk_bf16_f32 v64, v32, v33
	v_cvt_pk_bf16_f32 v65, v34, v35
	v_cvt_pk_bf16_f32 v66, v36, v37
	v_cvt_pk_bf16_f32 v67, v38, v39
	v_cvt_pk_bf16_f32 v68, v40, v41
	v_cvt_pk_bf16_f32 v69, v42, v43
	v_cvt_pk_bf16_f32 v70, v44, v45
	v_cvt_pk_bf16_f32 v71, v46, v47
	v_pk_add_f32 v[232:233], v[232:233], v[32:33]
	v_pk_add_f32 v[232:233], v[232:233], v[34:35]
	v_pk_add_f32 v[232:233], v[232:233], v[36:37]
	v_pk_add_f32 v[232:233], v[232:233], v[38:39]
	v_pk_add_f32 v[232:233], v[232:233], v[40:41]
	v_pk_add_f32 v[232:233], v[232:233], v[42:43]
	v_pk_add_f32 v[232:233], v[232:233], v[44:45]
	v_pk_add_f32 v[232:233], v[232:233], v[46:47]
	ds_read2_b32 v[32:33], v115 offset0:192 offset1:193
	ds_read2_b32 v[34:35], v115 offset0:194 offset1:195
	ds_read2_b32 v[36:37], v115 offset0:200 offset1:201
	ds_read2_b32 v[38:39], v115 offset0:202 offset1:203
	ds_read2_b32 v[40:41], v115 offset0:208 offset1:209
	ds_read2_b32 v[42:43], v115 offset0:210 offset1:211
	ds_read2_b32 v[44:45], v115 offset0:216 offset1:217
	ds_read2_b32 v[46:47], v115 offset0:218 offset1:219
	v_mfma_f32_32x32x16_bf16 v[0:15], v[64:67], v[72:75], v[0:15]
	v_mfma_f32_32x32x16_bf16 v[16:31], v[64:67], v[76:79], v[16:31]
	v_mfma_f32_32x32x16_bf16 v[0:15], v[68:71], v[220:223], v[0:15]
	v_mfma_f32_32x32x16_bf16 v[16:31], v[68:71], v[224:227], v[16:31]
	s_add_i32 s90, s67, 640
	v_add_u32_e32 v80, s90, v239
	v_add_u32_e32 v83, s90, v240
	v_add_u32_e32 v99, s90, v241
	v_add_u32_e32 v253, s90, v242
	v_add_u32_e32 v254, s90, v101
	v_add_u32_e32 v255, s90, v150
	v_med3_i32 v80, v80, 0, s99
	v_med3_i32 v83, v83, 0, s99
	v_med3_i32 v99, v99, 0, s99
	v_med3_i32 v253, v253, 0, s99
	v_med3_i32 v254, v254, 0, s99
	v_med3_i32 v255, v255, 0, s99
	v_mad_u32_u24 v80, v80, s100, v252
	v_mad_u32_u24 v83, v83, s100, v252
	v_mad_u32_u24 v99, v99, s100, v252
	v_mad_u32_u24 v253, v253, s100, v252
	v_mad_u32_u24 v254, v254, s100, v153
	v_mad_u32_u24 v255, v255, s100, v153
	global_load_dwordx4 v[156:159], v80, s[82:83]
	global_load_dwordx4 v[160:163], v83, s[82:83]
	global_load_dwordx4 v[164:167], v99, s[82:83]
	global_load_dwordx4 v[168:171], v253, s[82:83]
	global_load_dwordx4 v[172:175], v254, s[82:83] offset:768
	global_load_dwordx4 v[176:179], v255, s[82:83] offset:768
	global_load_dwordx4 v[180:183], v254, s[82:83] offset:832
	global_load_dwordx4 v[184:187], v255, s[82:83] offset:832
	ds_read_b64_tr_b16 v[72:73], v231
	ds_read_b64_tr_b16 v[74:75], v231 offset:512
	ds_read_b64_tr_b16 v[76:77], v231 offset:2048
	ds_read_b64_tr_b16 v[78:79], v231 offset:2560
	ds_read_b64_tr_b16 v[220:221], v231 offset:1024
	ds_read_b64_tr_b16 v[222:223], v231 offset:1536
	ds_read_b64_tr_b16 v[224:225], v231 offset:3072
	ds_read_b64_tr_b16 v[226:227], v231 offset:3584
	v_exp_f32_e32 v188, v188
	v_exp_f32_e32 v189, v189
	v_exp_f32_e32 v190, v190
	v_exp_f32_e32 v191, v191
	s_waitcnt vmcnt(8)
	ds_write_b128 v247, v[116:119]
	ds_write_b128 v247, v[120:123] offset:1024
	ds_write_b128 v247, v[124:127] offset:2048
	ds_write_b128 v247, v[128:131] offset:3072
	ds_read_b128 v[116:119], v248
	ds_read_b128 v[120:123], v249
	ds_read_b128 v[124:127], v250
	ds_read_b128 v[128:131], v251
	ds_write_b128 v112, v[132:135]
	ds_write_b128 v112, v[136:139] offset:1024
	ds_write_b128 v112, v[140:143] offset:2048
	ds_write_b128 v112, v[144:147] offset:3072
	v_exp_f32_e32 v192, v192
	v_exp_f32_e32 v193, v193
	v_exp_f32_e32 v194, v194
	v_exp_f32_e32 v195, v195
	s_waitcnt lgkmcnt(4)
	v_mfma_f32_32x32x16_bf16 v[32:47], v[116:119], v[48:51], v[32:47]
	v_exp_f32_e32 v196, v196
	v_exp_f32_e32 v197, v197
	v_mfma_f32_32x32x16_bf16 v[32:47], v[120:123], v[52:55], v[32:47]
	v_exp_f32_e32 v198, v198
	v_exp_f32_e32 v199, v199
	v_mfma_f32_32x32x16_bf16 v[32:47], v[124:127], v[56:59], v[32:47]
	v_exp_f32_e32 v200, v200
	v_exp_f32_e32 v201, v201
	v_mfma_f32_32x32x16_bf16 v[32:47], v[128:131], v[60:63], v[32:47]
	v_exp_f32_e32 v202, v202
	v_exp_f32_e32 v203, v203
	s_add_i32 s90, s67, 384
	v_lshlrev_b32_e32 v84, 2, v107
	v_add_u32_e32 v84, s90, v84
	v_add_u32_e32 v85, 0, v84
	v_add_u32_e32 v86, 4, v84
	v_add_u32_e32 v87, 8, v84
	v_add_u32_e32 v88, 12, v84
	v_cmp_gt_u32_e64 s[30:31], s98, v85
	v_cmp_gt_u32_e64 s[36:37], s98, v86
	v_cmp_gt_u32_e64 s[78:79], s98, v87
	v_cmp_gt_u32_e64 s[50:51], s98, v88
	v_cndmask_b32_e64 v188, 0, v188, s[30:31]
	v_add_u32_e32 v85, 32, v84
	v_cmp_gt_u32_e64 s[30:31], s98, v85
	v_cndmask_b32_e64 v189, 0, v189, s[36:37]
	v_add_u32_e32 v86, 36, v84
	v_cmp_gt_u32_e64 s[36:37], s98, v86
	v_cndmask_b32_e64 v190, 0, v190, s[78:79]
	v_add_u32_e32 v87, 40, v84
	v_cmp_gt_u32_e64 s[78:79], s98, v87
	v_cndmask_b32_e64 v191, 0, v191, s[50:51]
	v_add_u32_e32 v88, 44, v84
	v_cmp_gt_u32_e64 s[50:51], s98, v88
	v_cndmask_b32_e64 v192, 0, v192, s[30:31]
	v_add_u32_e32 v85, 64, v84
	v_cmp_gt_u32_e64 s[30:31], s98, v85
	v_cndmask_b32_e64 v193, 0, v193, s[36:37]
	v_add_u32_e32 v86, 68, v84
	v_cmp_gt_u32_e64 s[36:37], s98, v86
	v_cndmask_b32_e64 v194, 0, v194, s[78:79]
	v_add_u32_e32 v87, 72, v84
	v_cmp_gt_u32_e64 s[78:79], s98, v87
	v_cndmask_b32_e64 v195, 0, v195, s[50:51]
	v_add_u32_e32 v88, 76, v84
	v_cmp_gt_u32_e64 s[50:51], s98, v88
	v_cndmask_b32_e64 v196, 0, v196, s[30:31]
	v_add_u32_e32 v85, 96, v84
	v_cmp_gt_u32_e64 s[30:31], s98, v85
	v_cndmask_b32_e64 v197, 0, v197, s[36:37]
	v_add_u32_e32 v86, 100, v84
	v_cmp_gt_u32_e64 s[36:37], s98, v86
	v_cndmask_b32_e64 v198, 0, v198, s[78:79]
	v_add_u32_e32 v87, 104, v84
	v_cmp_gt_u32_e64 s[78:79], s98, v87
	v_cndmask_b32_e64 v199, 0, v199, s[50:51]
	v_add_u32_e32 v88, 108, v84
	v_cmp_gt_u32_e64 s[50:51], s98, v88
	v_nop
	v_cndmask_b32_e64 v200, 0, v200, s[30:31]
	v_cndmask_b32_e64 v201, 0, v201, s[36:37]
	v_cndmask_b32_e64 v202, 0, v202, s[78:79]
	v_cndmask_b32_e64 v203, 0, v203, s[50:51]
	v_cvt_pk_bf16_f32 v64, v188, v189
	v_cvt_pk_bf16_f32 v65, v190, v191
	v_cvt_pk_bf16_f32 v66, v192, v193
	v_cvt_pk_bf16_f32 v67, v194, v195
	v_cvt_pk_bf16_f32 v68, v196, v197
	v_cvt_pk_bf16_f32 v69, v198, v199
	v_cvt_pk_bf16_f32 v70, v200, v201
	v_cvt_pk_bf16_f32 v71, v202, v203
	v_pk_add_f32 v[232:233], v[232:233], v[188:189]
	v_pk_add_f32 v[232:233], v[232:233], v[190:191]
	v_pk_add_f32 v[232:233], v[232:233], v[192:193]
	v_pk_add_f32 v[232:233], v[232:233], v[194:195]
	v_pk_add_f32 v[232:233], v[232:233], v[196:197]
	v_pk_add_f32 v[232:233], v[232:233], v[198:199]
	v_pk_add_f32 v[232:233], v[232:233], v[200:201]
	v_pk_add_f32 v[232:233], v[232:233], v[202:203]
	ds_read2_b32 v[188:189], v115 offset0:224 offset1:225
	ds_read2_b32 v[190:191], v115 offset0:226 offset1:227
	ds_read2_b32 v[192:193], v115 offset0:232 offset1:233
	ds_read2_b32 v[194:195], v115 offset0:234 offset1:235
	ds_read2_b32 v[196:197], v115 offset0:240 offset1:241
	ds_read2_b32 v[198:199], v115 offset0:242 offset1:243
	ds_read2_b32 v[200:201], v115 offset0:248 offset1:249
	ds_read2_b32 v[202:203], v115 offset0:250 offset1:251
	v_mfma_f32_32x32x16_bf16 v[0:15], v[64:67], v[72:75], v[0:15]
	v_mfma_f32_32x32x16_bf16 v[16:31], v[64:67], v[76:79], v[16:31]
	v_mfma_f32_32x32x16_bf16 v[0:15], v[68:71], v[220:223], v[0:15]
	v_mfma_f32_32x32x16_bf16 v[16:31], v[68:71], v[224:227], v[16:31]
	s_add_i32 s90, s67, -1024
	v_add_u32_e32 v80, s90, v243
	v_add_u32_e32 v83, s90, v244
	v_add_u32_e32 v99, s90, v245
	v_add_u32_e32 v253, s90, v246
	v_add_u32_e32 v254, s90, v148
	v_add_u32_e32 v255, s90, v151
	v_med3_i32 v80, v80, 0, s99
	v_med3_i32 v83, v83, 0, s99
	v_med3_i32 v99, v99, 0, s99
	v_med3_i32 v253, v253, 0, s99
	v_med3_i32 v254, v254, 0, s99
	v_med3_i32 v255, v255, 0, s99
	v_mad_u32_u24 v80, v80, s100, v252
	v_mad_u32_u24 v83, v83, s100, v252
	v_mad_u32_u24 v99, v99, s100, v252
	v_mad_u32_u24 v253, v253, s100, v252
	v_mad_u32_u24 v254, v254, s100, v153
	v_mad_u32_u24 v255, v255, s100, v153
	global_load_dwordx4 v[116:119], v80, s[82:83]
	global_load_dwordx4 v[120:123], v83, s[82:83]
	global_load_dwordx4 v[124:127], v99, s[82:83]
	global_load_dwordx4 v[128:131], v253, s[82:83]
	global_load_dwordx4 v[132:135], v254, s[82:83] offset:768
	global_load_dwordx4 v[136:139], v255, s[82:83] offset:768
	global_load_dwordx4 v[140:143], v254, s[82:83] offset:832
	global_load_dwordx4 v[144:147], v255, s[82:83] offset:832
	ds_read_b64_tr_b16 v[72:73], v231
	ds_read_b64_tr_b16 v[74:75], v231 offset:512
	ds_read_b64_tr_b16 v[76:77], v231 offset:2048
	ds_read_b64_tr_b16 v[78:79], v231 offset:2560
	ds_read_b64_tr_b16 v[220:221], v231 offset:1024
	ds_read_b64_tr_b16 v[222:223], v231 offset:1536
	ds_read_b64_tr_b16 v[224:225], v231 offset:3072
	ds_read_b64_tr_b16 v[226:227], v231 offset:3584
	v_exp_f32_e32 v32, v32
	v_exp_f32_e32 v33, v33
	v_exp_f32_e32 v34, v34
	v_exp_f32_e32 v35, v35
	s_waitcnt vmcnt(8)
	ds_write_b128 v247, v[156:159]
	ds_write_b128 v247, v[160:163] offset:1024
	ds_write_b128 v247, v[164:167] offset:2048
	ds_write_b128 v247, v[168:171] offset:3072
	ds_read_b128 v[156:159], v248
	ds_read_b128 v[160:163], v249
	ds_read_b128 v[164:167], v250
	ds_read_b128 v[168:171], v251
	ds_write_b128 v112, v[172:175]
	ds_write_b128 v112, v[176:179] offset:1024
	ds_write_b128 v112, v[180:183] offset:2048
	ds_write_b128 v112, v[184:187] offset:3072
	v_exp_f32_e32 v36, v36
	v_exp_f32_e32 v37, v37
	v_exp_f32_e32 v38, v38
	v_exp_f32_e32 v39, v39
	s_waitcnt lgkmcnt(4)
	v_mfma_f32_32x32x16_bf16 v[188:203], v[156:159], v[48:51], v[188:203]
	v_exp_f32_e32 v40, v40
	v_exp_f32_e32 v41, v41
	v_mfma_f32_32x32x16_bf16 v[188:203], v[160:163], v[52:55], v[188:203]
	v_exp_f32_e32 v42, v42
	v_exp_f32_e32 v43, v43
	v_mfma_f32_32x32x16_bf16 v[188:203], v[164:167], v[56:59], v[188:203]
	v_exp_f32_e32 v44, v44
	v_exp_f32_e32 v45, v45
	v_mfma_f32_32x32x16_bf16 v[188:203], v[168:171], v[60:63], v[188:203]
	v_exp_f32_e32 v46, v46
	v_exp_f32_e32 v47, v47
	s_add_i32 s90, s67, 512
	v_lshlrev_b32_e32 v84, 2, v107
	v_add_u32_e32 v84, s90, v84
	v_add_u32_e32 v85, 0, v84
	v_add_u32_e32 v86, 4, v84
	v_add_u32_e32 v87, 8, v84
	v_add_u32_e32 v88, 12, v84
	v_cmp_gt_u32_e64 s[30:31], s98, v85
	v_cmp_gt_u32_e64 s[36:37], s98, v86
	v_cmp_gt_u32_e64 s[78:79], s98, v87
	v_cmp_gt_u32_e64 s[50:51], s98, v88
	v_cndmask_b32_e64 v32, 0, v32, s[30:31]
	v_add_u32_e32 v85, 32, v84
	v_cmp_gt_u32_e64 s[30:31], s98, v85
	v_cndmask_b32_e64 v33, 0, v33, s[36:37]
	v_add_u32_e32 v86, 36, v84
	v_cmp_gt_u32_e64 s[36:37], s98, v86
	v_cndmask_b32_e64 v34, 0, v34, s[78:79]
	v_add_u32_e32 v87, 40, v84
	v_cmp_gt_u32_e64 s[78:79], s98, v87
	v_cndmask_b32_e64 v35, 0, v35, s[50:51]
	v_add_u32_e32 v88, 44, v84
	v_cmp_gt_u32_e64 s[50:51], s98, v88
	v_cndmask_b32_e64 v36, 0, v36, s[30:31]
	v_add_u32_e32 v85, 64, v84
	v_cmp_gt_u32_e64 s[30:31], s98, v85
	v_cndmask_b32_e64 v37, 0, v37, s[36:37]
	v_add_u32_e32 v86, 68, v84
	v_cmp_gt_u32_e64 s[36:37], s98, v86
	v_cndmask_b32_e64 v38, 0, v38, s[78:79]
	v_add_u32_e32 v87, 72, v84
	v_cmp_gt_u32_e64 s[78:79], s98, v87
	v_cndmask_b32_e64 v39, 0, v39, s[50:51]
	v_add_u32_e32 v88, 76, v84
	v_cmp_gt_u32_e64 s[50:51], s98, v88
	v_cndmask_b32_e64 v40, 0, v40, s[30:31]
	v_add_u32_e32 v85, 96, v84
	v_cmp_gt_u32_e64 s[30:31], s98, v85
	v_cndmask_b32_e64 v41, 0, v41, s[36:37]
	v_add_u32_e32 v86, 100, v84
	v_cmp_gt_u32_e64 s[36:37], s98, v86
	v_cndmask_b32_e64 v42, 0, v42, s[78:79]
	v_add_u32_e32 v87, 104, v84
	v_cmp_gt_u32_e64 s[78:79], s98, v87
	v_cndmask_b32_e64 v43, 0, v43, s[50:51]
	v_add_u32_e32 v88, 108, v84
	v_cmp_gt_u32_e64 s[50:51], s98, v88
	v_nop
	v_cndmask_b32_e64 v44, 0, v44, s[30:31]
	v_cndmask_b32_e64 v45, 0, v45, s[36:37]
	v_cndmask_b32_e64 v46, 0, v46, s[78:79]
	v_cndmask_b32_e64 v47, 0, v47, s[50:51]
	v_cvt_pk_bf16_f32 v64, v32, v33
	v_cvt_pk_bf16_f32 v65, v34, v35
	v_cvt_pk_bf16_f32 v66, v36, v37
	v_cvt_pk_bf16_f32 v67, v38, v39
	v_cvt_pk_bf16_f32 v68, v40, v41
	v_cvt_pk_bf16_f32 v69, v42, v43
	v_cvt_pk_bf16_f32 v70, v44, v45
	v_cvt_pk_bf16_f32 v71, v46, v47
	v_pk_add_f32 v[232:233], v[232:233], v[32:33]
	v_pk_add_f32 v[232:233], v[232:233], v[34:35]
	v_pk_add_f32 v[232:233], v[232:233], v[36:37]
	v_pk_add_f32 v[232:233], v[232:233], v[38:39]
	v_pk_add_f32 v[232:233], v[232:233], v[40:41]
	v_pk_add_f32 v[232:233], v[232:233], v[42:43]
	v_pk_add_f32 v[232:233], v[232:233], v[44:45]
	v_pk_add_f32 v[232:233], v[232:233], v[46:47]
	v_mov_b32_e32 v115, v230
	ds_read2_b32 v[32:33], v115 offset0:0 offset1:1
	ds_read2_b32 v[34:35], v115 offset0:2 offset1:3
	ds_read2_b32 v[36:37], v115 offset0:8 offset1:9
	ds_read2_b32 v[38:39], v115 offset0:10 offset1:11
	ds_read2_b32 v[40:41], v115 offset0:16 offset1:17
	ds_read2_b32 v[42:43], v115 offset0:18 offset1:19
	ds_read2_b32 v[44:45], v115 offset0:24 offset1:25
	ds_read2_b32 v[46:47], v115 offset0:26 offset1:27
	v_mfma_f32_32x32x16_bf16 v[0:15], v[64:67], v[72:75], v[0:15]
	v_mfma_f32_32x32x16_bf16 v[16:31], v[64:67], v[76:79], v[16:31]
	v_mfma_f32_32x32x16_bf16 v[0:15], v[68:71], v[220:223], v[0:15]
	v_mfma_f32_32x32x16_bf16 v[16:31], v[68:71], v[224:227], v[16:31]
	s_add_i32 s90, s67, -512
	v_add_u32_e32 v80, s90, v243
	v_add_u32_e32 v83, s90, v244
	v_add_u32_e32 v99, s90, v245
	v_add_u32_e32 v253, s90, v246
	v_add_u32_e32 v254, s90, v148
	v_add_u32_e32 v255, s90, v151
	v_med3_i32 v80, v80, 0, s99
	v_med3_i32 v83, v83, 0, s99
	v_med3_i32 v99, v99, 0, s99
	v_med3_i32 v253, v253, 0, s99
	v_med3_i32 v254, v254, 0, s99
	v_med3_i32 v255, v255, 0, s99
	v_mad_u32_u24 v80, v80, s100, v252
	v_mad_u32_u24 v83, v83, s100, v252
	v_mad_u32_u24 v99, v99, s100, v252
	v_mad_u32_u24 v253, v253, s100, v252
	v_mad_u32_u24 v254, v254, s100, v153
	v_mad_u32_u24 v255, v255, s100, v153
	global_load_dwordx4 v[156:159], v80, s[82:83]
	global_load_dwordx4 v[160:163], v83, s[82:83]
	global_load_dwordx4 v[164:167], v99, s[82:83]
	global_load_dwordx4 v[168:171], v253, s[82:83]
	global_load_dwordx4 v[172:175], v254, s[82:83] offset:768
	global_load_dwordx4 v[176:179], v255, s[82:83] offset:768
	global_load_dwordx4 v[180:183], v254, s[82:83] offset:832
	global_load_dwordx4 v[184:187], v255, s[82:83] offset:832
	ds_read_b64_tr_b16 v[72:73], v231
	ds_read_b64_tr_b16 v[74:75], v231 offset:512
	ds_read_b64_tr_b16 v[76:77], v231 offset:2048
	ds_read_b64_tr_b16 v[78:79], v231 offset:2560
	ds_read_b64_tr_b16 v[220:221], v231 offset:1024
	ds_read_b64_tr_b16 v[222:223], v231 offset:1536
	ds_read_b64_tr_b16 v[224:225], v231 offset:3072
	ds_read_b64_tr_b16 v[226:227], v231 offset:3584
	v_exp_f32_e32 v188, v188
	v_exp_f32_e32 v189, v189
	v_exp_f32_e32 v190, v190
	v_exp_f32_e32 v191, v191
	s_waitcnt vmcnt(8)
	ds_write_b128 v247, v[116:119]
	ds_write_b128 v247, v[120:123] offset:1024
	ds_write_b128 v247, v[124:127] offset:2048
	ds_write_b128 v247, v[128:131] offset:3072
	ds_read_b128 v[116:119], v248
	ds_read_b128 v[120:123], v249
	ds_read_b128 v[124:127], v250
	ds_read_b128 v[128:131], v251
	ds_write_b128 v112, v[132:135]
	ds_write_b128 v112, v[136:139] offset:1024
	ds_write_b128 v112, v[140:143] offset:2048
	ds_write_b128 v112, v[144:147] offset:3072
	v_exp_f32_e32 v192, v192
	v_exp_f32_e32 v193, v193
	v_exp_f32_e32 v194, v194
	v_exp_f32_e32 v195, v195
	s_waitcnt lgkmcnt(4)
	v_mfma_f32_32x32x16_bf16 v[32:47], v[116:119], v[48:51], v[32:47]
	v_exp_f32_e32 v196, v196
	v_exp_f32_e32 v197, v197
	v_mfma_f32_32x32x16_bf16 v[32:47], v[120:123], v[52:55], v[32:47]
	v_exp_f32_e32 v198, v198
	v_exp_f32_e32 v199, v199
	v_mfma_f32_32x32x16_bf16 v[32:47], v[124:127], v[56:59], v[32:47]
	v_exp_f32_e32 v200, v200
	v_exp_f32_e32 v201, v201
	v_mfma_f32_32x32x16_bf16 v[32:47], v[128:131], v[60:63], v[32:47]
	v_exp_f32_e32 v202, v202
	v_exp_f32_e32 v203, v203
	s_add_i32 s90, s67, 640
	v_lshlrev_b32_e32 v84, 2, v107
	v_add_u32_e32 v84, s90, v84
	v_add_u32_e32 v85, 0, v84
	v_add_u32_e32 v86, 4, v84
	v_add_u32_e32 v87, 8, v84
	v_add_u32_e32 v88, 12, v84
	v_cmp_gt_u32_e64 s[30:31], s98, v85
	v_cmp_gt_u32_e64 s[36:37], s98, v86
	v_cmp_gt_u32_e64 s[78:79], s98, v87
	v_cmp_gt_u32_e64 s[50:51], s98, v88
	v_cndmask_b32_e64 v188, 0, v188, s[30:31]
	v_add_u32_e32 v85, 32, v84
	v_cmp_gt_u32_e64 s[30:31], s98, v85
	v_cndmask_b32_e64 v189, 0, v189, s[36:37]
	v_add_u32_e32 v86, 36, v84
	v_cmp_gt_u32_e64 s[36:37], s98, v86
	v_cndmask_b32_e64 v190, 0, v190, s[78:79]
	v_add_u32_e32 v87, 40, v84
	v_cmp_gt_u32_e64 s[78:79], s98, v87
	v_cndmask_b32_e64 v191, 0, v191, s[50:51]
	v_add_u32_e32 v88, 44, v84
	v_cmp_gt_u32_e64 s[50:51], s98, v88
	v_cndmask_b32_e64 v192, 0, v192, s[30:31]
	v_add_u32_e32 v85, 64, v84
	v_cmp_gt_u32_e64 s[30:31], s98, v85
	v_cndmask_b32_e64 v193, 0, v193, s[36:37]
	v_add_u32_e32 v86, 68, v84
	v_cmp_gt_u32_e64 s[36:37], s98, v86
	v_cndmask_b32_e64 v194, 0, v194, s[78:79]
	v_add_u32_e32 v87, 72, v84
	v_cmp_gt_u32_e64 s[78:79], s98, v87
	v_cndmask_b32_e64 v195, 0, v195, s[50:51]
	v_add_u32_e32 v88, 76, v84
	v_cmp_gt_u32_e64 s[50:51], s98, v88
	v_cndmask_b32_e64 v196, 0, v196, s[30:31]
	v_add_u32_e32 v85, 96, v84
	v_cmp_gt_u32_e64 s[30:31], s98, v85
	v_cndmask_b32_e64 v197, 0, v197, s[36:37]
	v_add_u32_e32 v86, 100, v84
	v_cmp_gt_u32_e64 s[36:37], s98, v86
	v_cndmask_b32_e64 v198, 0, v198, s[78:79]
	v_add_u32_e32 v87, 104, v84
	v_cmp_gt_u32_e64 s[78:79], s98, v87
	v_cndmask_b32_e64 v199, 0, v199, s[50:51]
	v_add_u32_e32 v88, 108, v84
	v_cmp_gt_u32_e64 s[50:51], s98, v88
	v_nop
	v_cndmask_b32_e64 v200, 0, v200, s[30:31]
	v_cndmask_b32_e64 v201, 0, v201, s[36:37]
	v_cndmask_b32_e64 v202, 0, v202, s[78:79]
	v_cndmask_b32_e64 v203, 0, v203, s[50:51]
	v_cvt_pk_bf16_f32 v64, v188, v189
	v_cvt_pk_bf16_f32 v65, v190, v191
	v_cvt_pk_bf16_f32 v66, v192, v193
	v_cvt_pk_bf16_f32 v67, v194, v195
	v_cvt_pk_bf16_f32 v68, v196, v197
	v_cvt_pk_bf16_f32 v69, v198, v199
	v_cvt_pk_bf16_f32 v70, v200, v201
	v_cvt_pk_bf16_f32 v71, v202, v203
	v_pk_add_f32 v[232:233], v[232:233], v[188:189]
	v_pk_add_f32 v[232:233], v[232:233], v[190:191]
	v_pk_add_f32 v[232:233], v[232:233], v[192:193]
	v_pk_add_f32 v[232:233], v[232:233], v[194:195]
	v_pk_add_f32 v[232:233], v[232:233], v[196:197]
	v_pk_add_f32 v[232:233], v[232:233], v[198:199]
	v_pk_add_f32 v[232:233], v[232:233], v[200:201]
	v_pk_add_f32 v[232:233], v[232:233], v[202:203]
	ds_read2_b32 v[188:189], v115 offset0:32 offset1:33
	ds_read2_b32 v[190:191], v115 offset0:34 offset1:35
	ds_read2_b32 v[192:193], v115 offset0:40 offset1:41
	ds_read2_b32 v[194:195], v115 offset0:42 offset1:43
	ds_read2_b32 v[196:197], v115 offset0:48 offset1:49
	ds_read2_b32 v[198:199], v115 offset0:50 offset1:51
	ds_read2_b32 v[200:201], v115 offset0:56 offset1:57
	ds_read2_b32 v[202:203], v115 offset0:58 offset1:59
	v_mfma_f32_32x32x16_bf16 v[0:15], v[64:67], v[72:75], v[0:15]
	v_mfma_f32_32x32x16_bf16 v[16:31], v[64:67], v[76:79], v[16:31]
	v_mfma_f32_32x32x16_bf16 v[0:15], v[68:71], v[220:223], v[0:15]
	v_mfma_f32_32x32x16_bf16 v[16:31], v[68:71], v[224:227], v[16:31]
	s_add_i32 s90, s67, 0
	v_add_u32_e32 v80, s90, v243
	v_add_u32_e32 v83, s90, v244
	v_add_u32_e32 v99, s90, v245
	v_add_u32_e32 v253, s90, v246
	v_add_u32_e32 v254, s90, v148
	v_add_u32_e32 v255, s90, v151
	v_med3_i32 v80, v80, 0, s99
	v_med3_i32 v83, v83, 0, s99
	v_med3_i32 v99, v99, 0, s99
	v_med3_i32 v253, v253, 0, s99
	v_med3_i32 v254, v254, 0, s99
	v_med3_i32 v255, v255, 0, s99
	v_mad_u32_u24 v80, v80, s100, v252
	v_mad_u32_u24 v83, v83, s100, v252
	v_mad_u32_u24 v99, v99, s100, v252
	v_mad_u32_u24 v253, v253, s100, v252
	v_mad_u32_u24 v254, v254, s100, v153
	v_mad_u32_u24 v255, v255, s100, v153
	global_load_dwordx4 v[116:119], v80, s[82:83]
	global_load_dwordx4 v[120:123], v83, s[82:83]
	global_load_dwordx4 v[124:127], v99, s[82:83]
	global_load_dwordx4 v[128:131], v253, s[82:83]
	global_load_dwordx4 v[132:135], v254, s[82:83] offset:768
	global_load_dwordx4 v[136:139], v255, s[82:83] offset:768
	global_load_dwordx4 v[140:143], v254, s[82:83] offset:832
	global_load_dwordx4 v[144:147], v255, s[82:83] offset:832
	ds_read_b64_tr_b16 v[72:73], v231
	ds_read_b64_tr_b16 v[74:75], v231 offset:512
	ds_read_b64_tr_b16 v[76:77], v231 offset:2048
	ds_read_b64_tr_b16 v[78:79], v231 offset:2560
	ds_read_b64_tr_b16 v[220:221], v231 offset:1024
	ds_read_b64_tr_b16 v[222:223], v231 offset:1536
	ds_read_b64_tr_b16 v[224:225], v231 offset:3072
	ds_read_b64_tr_b16 v[226:227], v231 offset:3584
	v_exp_f32_e32 v32, v32
	v_exp_f32_e32 v33, v33
	v_exp_f32_e32 v34, v34
	v_exp_f32_e32 v35, v35
	s_waitcnt vmcnt(8)
	ds_write_b128 v247, v[156:159]
	ds_write_b128 v247, v[160:163] offset:1024
	ds_write_b128 v247, v[164:167] offset:2048
	ds_write_b128 v247, v[168:171] offset:3072
	ds_read_b128 v[156:159], v248
	ds_read_b128 v[160:163], v249
	ds_read_b128 v[164:167], v250
	ds_read_b128 v[168:171], v251
	ds_write_b128 v112, v[172:175]
	ds_write_b128 v112, v[176:179] offset:1024
	ds_write_b128 v112, v[180:183] offset:2048
	ds_write_b128 v112, v[184:187] offset:3072
	v_exp_f32_e32 v36, v36
	v_exp_f32_e32 v37, v37
	v_exp_f32_e32 v38, v38
	v_exp_f32_e32 v39, v39
	s_waitcnt lgkmcnt(4)
	v_mfma_f32_32x32x16_bf16 v[188:203], v[156:159], v[48:51], v[188:203]
	v_exp_f32_e32 v40, v40
	v_exp_f32_e32 v41, v41
	v_mfma_f32_32x32x16_bf16 v[188:203], v[160:163], v[52:55], v[188:203]
	v_exp_f32_e32 v42, v42
	v_exp_f32_e32 v43, v43
	v_mfma_f32_32x32x16_bf16 v[188:203], v[164:167], v[56:59], v[188:203]
	v_exp_f32_e32 v44, v44
	v_exp_f32_e32 v45, v45
	v_mfma_f32_32x32x16_bf16 v[188:203], v[168:171], v[60:63], v[188:203]
	v_exp_f32_e32 v46, v46
	v_exp_f32_e32 v47, v47
	s_add_i32 s90, s67, -1024
	v_lshlrev_b32_e32 v84, 4, v107
	v_add_u32_e32 v84, s90, v84
	v_add_u32_e32 v85, 0, v84
	v_add_u32_e32 v86, 16, v84
	v_add_u32_e32 v87, 32, v84
	v_add_u32_e32 v88, 48, v84
	v_cmp_gt_u32_e64 s[30:31], s98, v85
	v_cmp_gt_u32_e64 s[36:37], s98, v86
	v_cmp_gt_u32_e64 s[78:79], s98, v87
	v_cmp_gt_u32_e64 s[50:51], s98, v88
	v_cndmask_b32_e64 v32, 0, v32, s[30:31]
	v_add_u32_e32 v85, 128, v84
	v_cmp_gt_u32_e64 s[30:31], s98, v85
	v_cndmask_b32_e64 v33, 0, v33, s[36:37]
	v_add_u32_e32 v86, 144, v84
	v_cmp_gt_u32_e64 s[36:37], s98, v86
	v_cndmask_b32_e64 v34, 0, v34, s[78:79]
	v_add_u32_e32 v87, 160, v84
	v_cmp_gt_u32_e64 s[78:79], s98, v87
	v_cndmask_b32_e64 v35, 0, v35, s[50:51]
	v_add_u32_e32 v88, 176, v84
	v_cmp_gt_u32_e64 s[50:51], s98, v88
	v_cndmask_b32_e64 v36, 0, v36, s[30:31]
	v_add_u32_e32 v85, 256, v84
	v_cmp_gt_u32_e64 s[30:31], s98, v85
	v_cndmask_b32_e64 v37, 0, v37, s[36:37]
	v_add_u32_e32 v86, 272, v84
	v_cmp_gt_u32_e64 s[36:37], s98, v86
	v_cndmask_b32_e64 v38, 0, v38, s[78:79]
	v_add_u32_e32 v87, 288, v84
	v_cmp_gt_u32_e64 s[78:79], s98, v87
	v_cndmask_b32_e64 v39, 0, v39, s[50:51]
	v_add_u32_e32 v88, 304, v84
	v_cmp_gt_u32_e64 s[50:51], s98, v88
	v_cndmask_b32_e64 v40, 0, v40, s[30:31]
	v_add_u32_e32 v85, 384, v84
	v_cmp_gt_u32_e64 s[30:31], s98, v85
	v_cndmask_b32_e64 v41, 0, v41, s[36:37]
	v_add_u32_e32 v86, 400, v84
	v_cmp_gt_u32_e64 s[36:37], s98, v86
	v_cndmask_b32_e64 v42, 0, v42, s[78:79]
	v_add_u32_e32 v87, 416, v84
	v_cmp_gt_u32_e64 s[78:79], s98, v87
	v_cndmask_b32_e64 v43, 0, v43, s[50:51]
	v_add_u32_e32 v88, 432, v84
	v_cmp_gt_u32_e64 s[50:51], s98, v88
	v_nop
	v_cndmask_b32_e64 v44, 0, v44, s[30:31]
	v_cndmask_b32_e64 v45, 0, v45, s[36:37]
	v_cndmask_b32_e64 v46, 0, v46, s[78:79]
	v_cndmask_b32_e64 v47, 0, v47, s[50:51]
	v_cvt_pk_bf16_f32 v64, v32, v33
	v_cvt_pk_bf16_f32 v65, v34, v35
	v_cvt_pk_bf16_f32 v66, v36, v37
	v_cvt_pk_bf16_f32 v67, v38, v39
	v_cvt_pk_bf16_f32 v68, v40, v41
	v_cvt_pk_bf16_f32 v69, v42, v43
	v_cvt_pk_bf16_f32 v70, v44, v45
	v_cvt_pk_bf16_f32 v71, v46, v47
	v_pk_add_f32 v[232:233], v[232:233], v[32:33]
	v_pk_add_f32 v[232:233], v[232:233], v[34:35]
	v_pk_add_f32 v[232:233], v[232:233], v[36:37]
	v_pk_add_f32 v[232:233], v[232:233], v[38:39]
	v_pk_add_f32 v[232:233], v[232:233], v[40:41]
	v_pk_add_f32 v[232:233], v[232:233], v[42:43]
	v_pk_add_f32 v[232:233], v[232:233], v[44:45]
	v_pk_add_f32 v[232:233], v[232:233], v[46:47]
	ds_read2_b32 v[32:33], v115 offset0:64 offset1:65
	ds_read2_b32 v[34:35], v115 offset0:66 offset1:67
	ds_read2_b32 v[36:37], v115 offset0:72 offset1:73
	ds_read2_b32 v[38:39], v115 offset0:74 offset1:75
	ds_read2_b32 v[40:41], v115 offset0:80 offset1:81
	ds_read2_b32 v[42:43], v115 offset0:82 offset1:83
	ds_read2_b32 v[44:45], v115 offset0:88 offset1:89
	ds_read2_b32 v[46:47], v115 offset0:90 offset1:91
	v_mfma_f32_32x32x16_bf16 v[0:15], v[64:67], v[72:75], v[0:15]
	v_mfma_f32_32x32x16_bf16 v[16:31], v[64:67], v[76:79], v[16:31]
	v_mfma_f32_32x32x16_bf16 v[0:15], v[68:71], v[220:223], v[0:15]
	v_mfma_f32_32x32x16_bf16 v[16:31], v[68:71], v[224:227], v[16:31]
	s_add_i32 s90, s67, 512
	v_add_u32_e32 v80, s90, v243
	v_add_u32_e32 v83, s90, v244
	v_add_u32_e32 v99, s90, v245
	v_add_u32_e32 v253, s90, v246
	v_add_u32_e32 v254, s90, v148
	v_add_u32_e32 v255, s90, v151
	v_med3_i32 v80, v80, 0, s99
	v_med3_i32 v83, v83, 0, s99
	v_med3_i32 v99, v99, 0, s99
	v_med3_i32 v253, v253, 0, s99
	v_med3_i32 v254, v254, 0, s99
	v_med3_i32 v255, v255, 0, s99
	v_mad_u32_u24 v80, v80, s100, v252
	v_mad_u32_u24 v83, v83, s100, v252
	v_mad_u32_u24 v99, v99, s100, v252
	v_mad_u32_u24 v253, v253, s100, v252
	v_mad_u32_u24 v254, v254, s100, v153
	v_mad_u32_u24 v255, v255, s100, v153
	global_load_dwordx4 v[156:159], v80, s[82:83]
	global_load_dwordx4 v[160:163], v83, s[82:83]
	global_load_dwordx4 v[164:167], v99, s[82:83]
	global_load_dwordx4 v[168:171], v253, s[82:83]
	global_load_dwordx4 v[172:175], v254, s[82:83] offset:768
	global_load_dwordx4 v[176:179], v255, s[82:83] offset:768
	global_load_dwordx4 v[180:183], v254, s[82:83] offset:832
	global_load_dwordx4 v[184:187], v255, s[82:83] offset:832
	ds_read_b64_tr_b16 v[72:73], v231
	ds_read_b64_tr_b16 v[74:75], v231 offset:512
	ds_read_b64_tr_b16 v[76:77], v231 offset:2048
	ds_read_b64_tr_b16 v[78:79], v231 offset:2560
	ds_read_b64_tr_b16 v[220:221], v231 offset:1024
	ds_read_b64_tr_b16 v[222:223], v231 offset:1536
	ds_read_b64_tr_b16 v[224:225], v231 offset:3072
	ds_read_b64_tr_b16 v[226:227], v231 offset:3584
	v_exp_f32_e32 v188, v188
	v_exp_f32_e32 v189, v189
	v_exp_f32_e32 v190, v190
	v_exp_f32_e32 v191, v191
	s_waitcnt vmcnt(8)
	ds_write_b128 v247, v[116:119]
	ds_write_b128 v247, v[120:123] offset:1024
	ds_write_b128 v247, v[124:127] offset:2048
	ds_write_b128 v247, v[128:131] offset:3072
	ds_read_b128 v[116:119], v248
	ds_read_b128 v[120:123], v249
	ds_read_b128 v[124:127], v250
	ds_read_b128 v[128:131], v251
	ds_write_b128 v112, v[132:135]
	ds_write_b128 v112, v[136:139] offset:1024
	ds_write_b128 v112, v[140:143] offset:2048
	ds_write_b128 v112, v[144:147] offset:3072
	v_exp_f32_e32 v192, v192
	v_exp_f32_e32 v193, v193
	v_exp_f32_e32 v194, v194
	v_exp_f32_e32 v195, v195
	s_waitcnt lgkmcnt(4)
	v_mfma_f32_32x32x16_bf16 v[32:47], v[116:119], v[48:51], v[32:47]
	v_exp_f32_e32 v196, v196
	v_exp_f32_e32 v197, v197
	v_mfma_f32_32x32x16_bf16 v[32:47], v[120:123], v[52:55], v[32:47]
	v_exp_f32_e32 v198, v198
	v_exp_f32_e32 v199, v199
	v_mfma_f32_32x32x16_bf16 v[32:47], v[124:127], v[56:59], v[32:47]
	v_exp_f32_e32 v200, v200
	v_exp_f32_e32 v201, v201
	v_mfma_f32_32x32x16_bf16 v[32:47], v[128:131], v[60:63], v[32:47]
	v_exp_f32_e32 v202, v202
	v_exp_f32_e32 v203, v203
	s_add_i32 s90, s67, -512
	v_lshlrev_b32_e32 v84, 4, v107
	v_add_u32_e32 v84, s90, v84
	v_add_u32_e32 v85, 0, v84
	v_add_u32_e32 v86, 16, v84
	v_add_u32_e32 v87, 32, v84
	v_add_u32_e32 v88, 48, v84
	v_cmp_gt_u32_e64 s[30:31], s98, v85
	v_cmp_gt_u32_e64 s[36:37], s98, v86
	v_cmp_gt_u32_e64 s[78:79], s98, v87
	v_cmp_gt_u32_e64 s[50:51], s98, v88
	v_cndmask_b32_e64 v188, 0, v188, s[30:31]
	v_add_u32_e32 v85, 128, v84
	v_cmp_gt_u32_e64 s[30:31], s98, v85
	v_cndmask_b32_e64 v189, 0, v189, s[36:37]
	v_add_u32_e32 v86, 144, v84
	v_cmp_gt_u32_e64 s[36:37], s98, v86
	v_cndmask_b32_e64 v190, 0, v190, s[78:79]
	v_add_u32_e32 v87, 160, v84
	v_cmp_gt_u32_e64 s[78:79], s98, v87
	v_cndmask_b32_e64 v191, 0, v191, s[50:51]
	v_add_u32_e32 v88, 176, v84
	v_cmp_gt_u32_e64 s[50:51], s98, v88
	v_cndmask_b32_e64 v192, 0, v192, s[30:31]
	v_add_u32_e32 v85, 256, v84
	v_cmp_gt_u32_e64 s[30:31], s98, v85
	v_cndmask_b32_e64 v193, 0, v193, s[36:37]
	v_add_u32_e32 v86, 272, v84
	v_cmp_gt_u32_e64 s[36:37], s98, v86
	v_cndmask_b32_e64 v194, 0, v194, s[78:79]
	v_add_u32_e32 v87, 288, v84
	v_cmp_gt_u32_e64 s[78:79], s98, v87
	v_cndmask_b32_e64 v195, 0, v195, s[50:51]
	v_add_u32_e32 v88, 304, v84
	v_cmp_gt_u32_e64 s[50:51], s98, v88
	v_cndmask_b32_e64 v196, 0, v196, s[30:31]
	v_add_u32_e32 v85, 384, v84
	v_cmp_gt_u32_e64 s[30:31], s98, v85
	v_cndmask_b32_e64 v197, 0, v197, s[36:37]
	v_add_u32_e32 v86, 400, v84
	v_cmp_gt_u32_e64 s[36:37], s98, v86
	v_cndmask_b32_e64 v198, 0, v198, s[78:79]
	v_add_u32_e32 v87, 416, v84
	v_cmp_gt_u32_e64 s[78:79], s98, v87
	v_cndmask_b32_e64 v199, 0, v199, s[50:51]
	v_add_u32_e32 v88, 432, v84
	v_cmp_gt_u32_e64 s[50:51], s98, v88
	v_nop
	v_cndmask_b32_e64 v200, 0, v200, s[30:31]
	v_cndmask_b32_e64 v201, 0, v201, s[36:37]
	v_cndmask_b32_e64 v202, 0, v202, s[78:79]
	v_cndmask_b32_e64 v203, 0, v203, s[50:51]
	v_cvt_pk_bf16_f32 v64, v188, v189
	v_cvt_pk_bf16_f32 v65, v190, v191
	v_cvt_pk_bf16_f32 v66, v192, v193
	v_cvt_pk_bf16_f32 v67, v194, v195
	v_cvt_pk_bf16_f32 v68, v196, v197
	v_cvt_pk_bf16_f32 v69, v198, v199
	v_cvt_pk_bf16_f32 v70, v200, v201
	v_cvt_pk_bf16_f32 v71, v202, v203
	v_pk_add_f32 v[232:233], v[232:233], v[188:189]
	v_pk_add_f32 v[232:233], v[232:233], v[190:191]
	v_pk_add_f32 v[232:233], v[232:233], v[192:193]
	v_pk_add_f32 v[232:233], v[232:233], v[194:195]
	v_pk_add_f32 v[232:233], v[232:233], v[196:197]
	v_pk_add_f32 v[232:233], v[232:233], v[198:199]
	v_pk_add_f32 v[232:233], v[232:233], v[200:201]
	v_pk_add_f32 v[232:233], v[232:233], v[202:203]
	ds_read2_b32 v[188:189], v115 offset0:96 offset1:97
	ds_read2_b32 v[190:191], v115 offset0:98 offset1:99
	ds_read2_b32 v[192:193], v115 offset0:104 offset1:105
	ds_read2_b32 v[194:195], v115 offset0:106 offset1:107
	ds_read2_b32 v[196:197], v115 offset0:112 offset1:113
	ds_read2_b32 v[198:199], v115 offset0:114 offset1:115
	ds_read2_b32 v[200:201], v115 offset0:120 offset1:121
	ds_read2_b32 v[202:203], v115 offset0:122 offset1:123
	v_mfma_f32_32x32x16_bf16 v[0:15], v[64:67], v[72:75], v[0:15]
	v_mfma_f32_32x32x16_bf16 v[16:31], v[64:67], v[76:79], v[16:31]
	v_mfma_f32_32x32x16_bf16 v[0:15], v[68:71], v[220:223], v[0:15]
	v_mfma_f32_32x32x16_bf16 v[16:31], v[68:71], v[224:227], v[16:31]
	s_add_i32 s90, s67, 1024
	v_add_u32_e32 v80, s90, v243
	v_add_u32_e32 v83, s90, v244
	v_add_u32_e32 v99, s90, v245
	v_add_u32_e32 v253, s90, v246
	v_add_u32_e32 v254, s90, v148
	v_add_u32_e32 v255, s90, v151
	v_med3_i32 v80, v80, 0, s99
	v_med3_i32 v83, v83, 0, s99
	v_med3_i32 v99, v99, 0, s99
	v_med3_i32 v253, v253, 0, s99
	v_med3_i32 v254, v254, 0, s99
	v_med3_i32 v255, v255, 0, s99
	v_mad_u32_u24 v80, v80, s100, v252
	v_mad_u32_u24 v83, v83, s100, v252
	v_mad_u32_u24 v99, v99, s100, v252
	v_mad_u32_u24 v253, v253, s100, v252
	v_mad_u32_u24 v254, v254, s100, v153
	v_mad_u32_u24 v255, v255, s100, v153
	global_load_dwordx4 v[116:119], v80, s[82:83]
	global_load_dwordx4 v[120:123], v83, s[82:83]
	global_load_dwordx4 v[124:127], v99, s[82:83]
	global_load_dwordx4 v[128:131], v253, s[82:83]
	global_load_dwordx4 v[132:135], v254, s[82:83] offset:768
	global_load_dwordx4 v[136:139], v255, s[82:83] offset:768
	global_load_dwordx4 v[140:143], v254, s[82:83] offset:832
	global_load_dwordx4 v[144:147], v255, s[82:83] offset:832
	ds_read_b64_tr_b16 v[72:73], v231
	ds_read_b64_tr_b16 v[74:75], v231 offset:512
	ds_read_b64_tr_b16 v[76:77], v231 offset:2048
	ds_read_b64_tr_b16 v[78:79], v231 offset:2560
	ds_read_b64_tr_b16 v[220:221], v231 offset:1024
	ds_read_b64_tr_b16 v[222:223], v231 offset:1536
	ds_read_b64_tr_b16 v[224:225], v231 offset:3072
	ds_read_b64_tr_b16 v[226:227], v231 offset:3584
	v_exp_f32_e32 v32, v32
	v_exp_f32_e32 v33, v33
	v_exp_f32_e32 v34, v34
	v_exp_f32_e32 v35, v35
	s_waitcnt vmcnt(8)
	ds_write_b128 v247, v[156:159]
	ds_write_b128 v247, v[160:163] offset:1024
	ds_write_b128 v247, v[164:167] offset:2048
	ds_write_b128 v247, v[168:171] offset:3072
	ds_read_b128 v[156:159], v248
	ds_read_b128 v[160:163], v249
	ds_read_b128 v[164:167], v250
	ds_read_b128 v[168:171], v251
	ds_write_b128 v112, v[172:175]
	ds_write_b128 v112, v[176:179] offset:1024
	ds_write_b128 v112, v[180:183] offset:2048
	ds_write_b128 v112, v[184:187] offset:3072
	v_exp_f32_e32 v36, v36
	v_exp_f32_e32 v37, v37
	v_exp_f32_e32 v38, v38
	v_exp_f32_e32 v39, v39
	s_waitcnt lgkmcnt(4)
	v_mfma_f32_32x32x16_bf16 v[188:203], v[156:159], v[48:51], v[188:203]
	v_exp_f32_e32 v40, v40
	v_exp_f32_e32 v41, v41
	v_mfma_f32_32x32x16_bf16 v[188:203], v[160:163], v[52:55], v[188:203]
	v_exp_f32_e32 v42, v42
	v_exp_f32_e32 v43, v43
	v_mfma_f32_32x32x16_bf16 v[188:203], v[164:167], v[56:59], v[188:203]
	v_exp_f32_e32 v44, v44
	v_exp_f32_e32 v45, v45
	v_mfma_f32_32x32x16_bf16 v[188:203], v[168:171], v[60:63], v[188:203]
	v_exp_f32_e32 v46, v46
	v_exp_f32_e32 v47, v47
	s_add_i32 s90, s67, 0
	v_lshlrev_b32_e32 v84, 4, v107
	v_add_u32_e32 v84, s90, v84
	v_add_u32_e32 v85, 0, v84
	v_add_u32_e32 v86, 16, v84
	v_add_u32_e32 v87, 32, v84
	v_add_u32_e32 v88, 48, v84
	v_cmp_gt_u32_e64 s[30:31], s98, v85
	v_cmp_gt_u32_e64 s[36:37], s98, v86
	v_cmp_gt_u32_e64 s[78:79], s98, v87
	v_cmp_gt_u32_e64 s[50:51], s98, v88
	v_cndmask_b32_e64 v32, 0, v32, s[30:31]
	v_add_u32_e32 v85, 128, v84
	v_cmp_gt_u32_e64 s[30:31], s98, v85
	v_cndmask_b32_e64 v33, 0, v33, s[36:37]
	v_add_u32_e32 v86, 144, v84
	v_cmp_gt_u32_e64 s[36:37], s98, v86
	v_cndmask_b32_e64 v34, 0, v34, s[78:79]
	v_add_u32_e32 v87, 160, v84
	v_cmp_gt_u32_e64 s[78:79], s98, v87
	v_cndmask_b32_e64 v35, 0, v35, s[50:51]
	v_add_u32_e32 v88, 176, v84
	v_cmp_gt_u32_e64 s[50:51], s98, v88
	v_cndmask_b32_e64 v36, 0, v36, s[30:31]
	v_add_u32_e32 v85, 256, v84
	v_cmp_gt_u32_e64 s[30:31], s98, v85
	v_cndmask_b32_e64 v37, 0, v37, s[36:37]
	v_add_u32_e32 v86, 272, v84
	v_cmp_gt_u32_e64 s[36:37], s98, v86
	v_cndmask_b32_e64 v38, 0, v38, s[78:79]
	v_add_u32_e32 v87, 288, v84
	v_cmp_gt_u32_e64 s[78:79], s98, v87
	v_cndmask_b32_e64 v39, 0, v39, s[50:51]
	v_add_u32_e32 v88, 304, v84
	v_cmp_gt_u32_e64 s[50:51], s98, v88
	v_cndmask_b32_e64 v40, 0, v40, s[30:31]
	v_add_u32_e32 v85, 384, v84
	v_cmp_gt_u32_e64 s[30:31], s98, v85
	v_cndmask_b32_e64 v41, 0, v41, s[36:37]
	v_add_u32_e32 v86, 400, v84
	v_cmp_gt_u32_e64 s[36:37], s98, v86
	v_cndmask_b32_e64 v42, 0, v42, s[78:79]
	v_add_u32_e32 v87, 416, v84
	v_cmp_gt_u32_e64 s[78:79], s98, v87
	v_cndmask_b32_e64 v43, 0, v43, s[50:51]
	v_add_u32_e32 v88, 432, v84
	v_cmp_gt_u32_e64 s[50:51], s98, v88
	v_nop
	v_cndmask_b32_e64 v44, 0, v44, s[30:31]
	v_cndmask_b32_e64 v45, 0, v45, s[36:37]
	v_cndmask_b32_e64 v46, 0, v46, s[78:79]
	v_cndmask_b32_e64 v47, 0, v47, s[50:51]
	v_cvt_pk_bf16_f32 v64, v32, v33
	v_cvt_pk_bf16_f32 v65, v34, v35
	v_cvt_pk_bf16_f32 v66, v36, v37
	v_cvt_pk_bf16_f32 v67, v38, v39
	v_cvt_pk_bf16_f32 v68, v40, v41
	v_cvt_pk_bf16_f32 v69, v42, v43
	v_cvt_pk_bf16_f32 v70, v44, v45
	v_cvt_pk_bf16_f32 v71, v46, v47
	v_pk_add_f32 v[232:233], v[232:233], v[32:33]
	v_pk_add_f32 v[232:233], v[232:233], v[34:35]
	v_pk_add_f32 v[232:233], v[232:233], v[36:37]
	v_pk_add_f32 v[232:233], v[232:233], v[38:39]
	v_pk_add_f32 v[232:233], v[232:233], v[40:41]
	v_pk_add_f32 v[232:233], v[232:233], v[42:43]
	v_pk_add_f32 v[232:233], v[232:233], v[44:45]
	v_pk_add_f32 v[232:233], v[232:233], v[46:47]
	ds_read2_b32 v[32:33], v115 offset0:128 offset1:129
	ds_read2_b32 v[34:35], v115 offset0:130 offset1:131
	ds_read2_b32 v[36:37], v115 offset0:136 offset1:137
	ds_read2_b32 v[38:39], v115 offset0:138 offset1:139
	ds_read2_b32 v[40:41], v115 offset0:144 offset1:145
	ds_read2_b32 v[42:43], v115 offset0:146 offset1:147
	ds_read2_b32 v[44:45], v115 offset0:152 offset1:153
	ds_read2_b32 v[46:47], v115 offset0:154 offset1:155
	v_mfma_f32_32x32x16_bf16 v[0:15], v[64:67], v[72:75], v[0:15]
	v_mfma_f32_32x32x16_bf16 v[16:31], v[64:67], v[76:79], v[16:31]
	v_mfma_f32_32x32x16_bf16 v[0:15], v[68:71], v[220:223], v[0:15]
	v_mfma_f32_32x32x16_bf16 v[16:31], v[68:71], v[224:227], v[16:31]
	ds_read_b64_tr_b16 v[72:73], v231
	ds_read_b64_tr_b16 v[74:75], v231 offset:512
	ds_read_b64_tr_b16 v[76:77], v231 offset:2048
	ds_read_b64_tr_b16 v[78:79], v231 offset:2560
	ds_read_b64_tr_b16 v[220:221], v231 offset:1024
	ds_read_b64_tr_b16 v[222:223], v231 offset:1536
	ds_read_b64_tr_b16 v[224:225], v231 offset:3072
	ds_read_b64_tr_b16 v[226:227], v231 offset:3584
	v_exp_f32_e32 v188, v188
	v_exp_f32_e32 v189, v189
	v_exp_f32_e32 v190, v190
	v_exp_f32_e32 v191, v191
	s_waitcnt vmcnt(0)
	ds_write_b128 v247, v[116:119]
	ds_write_b128 v247, v[120:123] offset:1024
	ds_write_b128 v247, v[124:127] offset:2048
	ds_write_b128 v247, v[128:131] offset:3072
	ds_read_b128 v[116:119], v248
	ds_read_b128 v[120:123], v249
	ds_read_b128 v[124:127], v250
	ds_read_b128 v[128:131], v251
	ds_write_b128 v112, v[132:135]
	ds_write_b128 v112, v[136:139] offset:1024
	ds_write_b128 v112, v[140:143] offset:2048
	ds_write_b128 v112, v[144:147] offset:3072
	v_exp_f32_e32 v192, v192
	v_exp_f32_e32 v193, v193
	v_exp_f32_e32 v194, v194
	v_exp_f32_e32 v195, v195
	s_waitcnt lgkmcnt(4)
	v_mfma_f32_32x32x16_bf16 v[32:47], v[116:119], v[48:51], v[32:47]
	v_exp_f32_e32 v196, v196
	v_exp_f32_e32 v197, v197
	v_mfma_f32_32x32x16_bf16 v[32:47], v[120:123], v[52:55], v[32:47]
	v_exp_f32_e32 v198, v198
	v_exp_f32_e32 v199, v199
	v_mfma_f32_32x32x16_bf16 v[32:47], v[124:127], v[56:59], v[32:47]
	v_exp_f32_e32 v200, v200
	v_exp_f32_e32 v201, v201
	v_mfma_f32_32x32x16_bf16 v[32:47], v[128:131], v[60:63], v[32:47]
	v_exp_f32_e32 v202, v202
	v_exp_f32_e32 v203, v203
	s_add_i32 s90, s67, 512
	v_lshlrev_b32_e32 v84, 4, v107
	v_add_u32_e32 v84, s90, v84
	v_add_u32_e32 v85, 0, v84
	v_add_u32_e32 v86, 16, v84
	v_add_u32_e32 v87, 32, v84
	v_add_u32_e32 v88, 48, v84
	v_cmp_gt_u32_e64 s[30:31], s98, v85
	v_cmp_gt_u32_e64 s[36:37], s98, v86
	v_cmp_gt_u32_e64 s[78:79], s98, v87
	v_cmp_gt_u32_e64 s[50:51], s98, v88
	v_cndmask_b32_e64 v188, 0, v188, s[30:31]
	v_add_u32_e32 v85, 128, v84
	v_cmp_gt_u32_e64 s[30:31], s98, v85
	v_cndmask_b32_e64 v189, 0, v189, s[36:37]
	v_add_u32_e32 v86, 144, v84
	v_cmp_gt_u32_e64 s[36:37], s98, v86
	v_cndmask_b32_e64 v190, 0, v190, s[78:79]
	v_add_u32_e32 v87, 160, v84
	v_cmp_gt_u32_e64 s[78:79], s98, v87
	v_cndmask_b32_e64 v191, 0, v191, s[50:51]
	v_add_u32_e32 v88, 176, v84
	v_cmp_gt_u32_e64 s[50:51], s98, v88
	v_cndmask_b32_e64 v192, 0, v192, s[30:31]
	v_add_u32_e32 v85, 256, v84
	v_cmp_gt_u32_e64 s[30:31], s98, v85
	v_cndmask_b32_e64 v193, 0, v193, s[36:37]
	v_add_u32_e32 v86, 272, v84
	v_cmp_gt_u32_e64 s[36:37], s98, v86
	v_cndmask_b32_e64 v194, 0, v194, s[78:79]
	v_add_u32_e32 v87, 288, v84
	v_cmp_gt_u32_e64 s[78:79], s98, v87
	v_cndmask_b32_e64 v195, 0, v195, s[50:51]
	v_add_u32_e32 v88, 304, v84
	v_cmp_gt_u32_e64 s[50:51], s98, v88
	v_cndmask_b32_e64 v196, 0, v196, s[30:31]
	v_add_u32_e32 v85, 384, v84
	v_cmp_gt_u32_e64 s[30:31], s98, v85
	v_cndmask_b32_e64 v197, 0, v197, s[36:37]
	v_add_u32_e32 v86, 400, v84
	v_cmp_gt_u32_e64 s[36:37], s98, v86
	v_cndmask_b32_e64 v198, 0, v198, s[78:79]
	v_add_u32_e32 v87, 416, v84
	v_cmp_gt_u32_e64 s[78:79], s98, v87
	v_cndmask_b32_e64 v199, 0, v199, s[50:51]
	v_add_u32_e32 v88, 432, v84
	v_cmp_gt_u32_e64 s[50:51], s98, v88
	v_nop
	v_cndmask_b32_e64 v200, 0, v200, s[30:31]
	v_cndmask_b32_e64 v201, 0, v201, s[36:37]
	v_cndmask_b32_e64 v202, 0, v202, s[78:79]
	v_cndmask_b32_e64 v203, 0, v203, s[50:51]
	v_cvt_pk_bf16_f32 v64, v188, v189
	v_cvt_pk_bf16_f32 v65, v190, v191
	v_cvt_pk_bf16_f32 v66, v192, v193
	v_cvt_pk_bf16_f32 v67, v194, v195
	v_cvt_pk_bf16_f32 v68, v196, v197
	v_cvt_pk_bf16_f32 v69, v198, v199
	v_cvt_pk_bf16_f32 v70, v200, v201
	v_cvt_pk_bf16_f32 v71, v202, v203
	v_pk_add_f32 v[232:233], v[232:233], v[188:189]
	v_pk_add_f32 v[232:233], v[232:233], v[190:191]
	v_pk_add_f32 v[232:233], v[232:233], v[192:193]
	v_pk_add_f32 v[232:233], v[232:233], v[194:195]
	v_pk_add_f32 v[232:233], v[232:233], v[196:197]
	v_pk_add_f32 v[232:233], v[232:233], v[198:199]
	v_pk_add_f32 v[232:233], v[232:233], v[200:201]
	v_pk_add_f32 v[232:233], v[232:233], v[202:203]
	v_mfma_f32_32x32x16_bf16 v[0:15], v[64:67], v[72:75], v[0:15]
	v_mfma_f32_32x32x16_bf16 v[16:31], v[64:67], v[76:79], v[16:31]
	v_mfma_f32_32x32x16_bf16 v[0:15], v[68:71], v[220:223], v[0:15]
	v_mfma_f32_32x32x16_bf16 v[16:31], v[68:71], v[224:227], v[16:31]
	ds_read_b64_tr_b16 v[72:73], v231
	ds_read_b64_tr_b16 v[74:75], v231 offset:512
	ds_read_b64_tr_b16 v[76:77], v231 offset:2048
	ds_read_b64_tr_b16 v[78:79], v231 offset:2560
	ds_read_b64_tr_b16 v[220:221], v231 offset:1024
	ds_read_b64_tr_b16 v[222:223], v231 offset:1536
	ds_read_b64_tr_b16 v[224:225], v231 offset:3072
	ds_read_b64_tr_b16 v[226:227], v231 offset:3584
	s_waitcnt lgkmcnt(0)
; __device__ __forceinline__ int crow(int r, int hi) { return (r & 3) + 8 * (r >> 2) + 4 * hi; }
; __device__ __forceinline__ void dil_unit(LAS unsigned char* lds, bf16_t* proj, int seq, int hd, int T0, int rho) {
;     ...
;     l += __shfl_xor(l, 32);
; #pragma unroll
;     for (int rr = 0; rr < 16; ++rr) {
;         const int j = crow(rr, hi);
;         const float il = __builtin_amdgcn_rcpf(__shfl(l, j));
	v_exp_f32_e32 v32, v32
	v_exp_f32_e32 v33, v33
	v_exp_f32_e32 v34, v34
	v_exp_f32_e32 v35, v35
	v_exp_f32_e32 v36, v36
	v_exp_f32_e32 v37, v37
	v_exp_f32_e32 v38, v38
	v_exp_f32_e32 v39, v39
	v_exp_f32_e32 v40, v40
	v_exp_f32_e32 v41, v41
	v_exp_f32_e32 v42, v42
	v_exp_f32_e32 v43, v43
	v_exp_f32_e32 v44, v44
	v_exp_f32_e32 v45, v45
	v_exp_f32_e32 v46, v46
	v_exp_f32_e32 v47, v47
	s_add_i32 s90, s67, 1024
	v_lshlrev_b32_e32 v84, 4, v107
	v_add_u32_e32 v84, s90, v84
	v_add_u32_e32 v85, 0, v84
	v_add_u32_e32 v86, 16, v84
	v_add_u32_e32 v87, 32, v84
	v_add_u32_e32 v88, 48, v84
	v_cmp_gt_u32_e64 s[30:31], s98, v85
	v_cmp_gt_u32_e64 s[36:37], s98, v86
	v_cmp_gt_u32_e64 s[78:79], s98, v87
	v_cmp_gt_u32_e64 s[50:51], s98, v88
	v_cndmask_b32_e64 v32, 0, v32, s[30:31]
	v_add_u32_e32 v85, 128, v84
	v_cmp_gt_u32_e64 s[30:31], s98, v85
	v_cndmask_b32_e64 v33, 0, v33, s[36:37]
	v_add_u32_e32 v86, 144, v84
	v_cmp_gt_u32_e64 s[36:37], s98, v86
	v_cndmask_b32_e64 v34, 0, v34, s[78:79]
	v_add_u32_e32 v87, 160, v84
	v_cmp_gt_u32_e64 s[78:79], s98, v87
	v_cndmask_b32_e64 v35, 0, v35, s[50:51]
	v_add_u32_e32 v88, 176, v84
	v_cmp_gt_u32_e64 s[50:51], s98, v88
	v_cndmask_b32_e64 v36, 0, v36, s[30:31]
	v_add_u32_e32 v85, 256, v84
	v_cmp_gt_u32_e64 s[30:31], s98, v85
	v_cndmask_b32_e64 v37, 0, v37, s[36:37]
	v_add_u32_e32 v86, 272, v84
	v_cmp_gt_u32_e64 s[36:37], s98, v86
	v_cndmask_b32_e64 v38, 0, v38, s[78:79]
	v_add_u32_e32 v87, 288, v84
	v_cmp_gt_u32_e64 s[78:79], s98, v87
	v_cndmask_b32_e64 v39, 0, v39, s[50:51]
	v_add_u32_e32 v88, 304, v84
	v_cmp_gt_u32_e64 s[50:51], s98, v88
	v_cndmask_b32_e64 v40, 0, v40, s[30:31]
	v_add_u32_e32 v85, 384, v84
	v_cmp_gt_u32_e64 s[30:31], s98, v85
	v_cndmask_b32_e64 v41, 0, v41, s[36:37]
	v_add_u32_e32 v86, 400, v84
	v_cmp_gt_u32_e64 s[36:37], s98, v86
	v_cndmask_b32_e64 v42, 0, v42, s[78:79]
	v_add_u32_e32 v87, 416, v84
	v_cmp_gt_u32_e64 s[78:79], s98, v87
	v_cndmask_b32_e64 v43, 0, v43, s[50:51]
	v_add_u32_e32 v88, 432, v84
	v_cmp_gt_u32_e64 s[50:51], s98, v88
	v_nop
	v_cndmask_b32_e64 v44, 0, v44, s[30:31]
	v_cndmask_b32_e64 v45, 0, v45, s[36:37]
	v_cndmask_b32_e64 v46, 0, v46, s[78:79]
	v_cndmask_b32_e64 v47, 0, v47, s[50:51]
	v_cvt_pk_bf16_f32 v64, v32, v33
	v_cvt_pk_bf16_f32 v65, v34, v35
	v_cvt_pk_bf16_f32 v66, v36, v37
	v_cvt_pk_bf16_f32 v67, v38, v39
	v_cvt_pk_bf16_f32 v68, v40, v41
	v_cvt_pk_bf16_f32 v69, v42, v43
	v_cvt_pk_bf16_f32 v70, v44, v45
	v_cvt_pk_bf16_f32 v71, v46, v47
	v_pk_add_f32 v[232:233], v[232:233], v[32:33]
	v_pk_add_f32 v[232:233], v[232:233], v[34:35]
	v_pk_add_f32 v[232:233], v[232:233], v[36:37]
	v_pk_add_f32 v[232:233], v[232:233], v[38:39]
	v_pk_add_f32 v[232:233], v[232:233], v[40:41]
	v_pk_add_f32 v[232:233], v[232:233], v[42:43]
	v_pk_add_f32 v[232:233], v[232:233], v[44:45]
	v_pk_add_f32 v[232:233], v[232:233], v[46:47]
	v_mfma_f32_32x32x16_bf16 v[0:15], v[64:67], v[72:75], v[0:15]
	v_mfma_f32_32x32x16_bf16 v[16:31], v[64:67], v[76:79], v[16:31]
	v_mfma_f32_32x32x16_bf16 v[0:15], v[68:71], v[220:223], v[0:15]
	v_mfma_f32_32x32x16_bf16 v[16:31], v[68:71], v[224:227], v[16:31]
	v_add_f32_e32 v113, v232, v233
	v_or_b32_e32 v114, 1, v107
	v_or_b32_e32 v97, 2, v107
	v_or_b32_e32 v96, 3, v107
	v_or_b32_e32 v95, 8, v107
	v_or_b32_e32 v94, 9, v107
	v_or_b32_e32 v93, 10, v107
	v_or_b32_e32 v92, 11, v107
	v_or_b32_e32 v91, 16, v107
	v_or_b32_e32 v90, 17, v107
	v_or_b32_e32 v89, 18, v107
	v_or_b32_e32 v88, 19, v107
	v_or_b32_e32 v87, 24, v107
	v_or_b32_e32 v86, 25, v107
	v_or_b32_e32 v85, 26, v107
	v_or_b32_e32 v84, 27, v107
	s_nop 11
	s_branch .LBB0_1265
